# v33: v30 plus removal of back-to-back duplicate lgkmcnt(0) waits in the GEMM slots
# baseline (speedup 1.0000x reference)
.LBB0_278:
	ds_read_b128 v[130:133], v158
	ds_read_b128 v[134:137], v158 offset:1024
	ds_read_b128 v[162:165], v158 offset:2048
	ds_read_b128 v[166:169], v158 offset:3072
	s_add_u32 s0, s30, 0xfffc0080
	s_addc_u32 s1, s31, -1
	s_cmp_eq_u32 s60, 12
	s_cselect_b32 s37, s23, s1
	s_cselect_b32 s36, s56, s0
	s_cselect_b32 s35, s21, s59
	s_cselect_b32 s34, s57, s58
	v_lshl_add_u64 v[154:155], s[30:31], 0, v[148:149]
	s_add_i32 m0, s29, 0xc000
	ds_read_b128 v[170:173], v159
	ds_read_b128 v[174:177], v159 offset:1024
	ds_read_b128 v[178:181], v159 offset:2048
	ds_read_b128 v[182:185], v159 offset:3072
	ds_read_b128 v[186:189], v159 offset:4096
	ds_read_b128 v[190:193], v159 offset:5120
	ds_read_b128 v[194:197], v159 offset:6144
	ds_read_b128 v[198:201], v159 offset:7168
	global_load_lds_dwordx4 v[154:155], off
	v_lshl_add_u64 v[154:155], s[30:31], 0, v[146:147]
	s_add_i32 m0, s29, 0xe000
	s_nop 0
	global_load_lds_dwordx4 v[154:155], off
	s_waitcnt lgkmcnt(8)
	s_waitcnt vmcnt(10)
	s_barrier
	s_waitcnt lgkmcnt(0)
	v_mfma_f32_16x16x32_bf16 v[126:129], v[130:133], v[170:173], v[126:129]
	v_mfma_f32_16x16x32_bf16 v[122:125], v[162:165], v[170:173], v[122:125]
	v_mfma_f32_16x16x32_bf16 v[118:121], v[130:133], v[178:181], v[118:121]
	v_mfma_f32_16x16x32_bf16 v[110:113], v[162:165], v[178:181], v[110:113]
	v_mfma_f32_16x16x32_bf16 v[102:105], v[130:133], v[186:189], v[102:105]
	v_mfma_f32_16x16x32_bf16 v[94:97], v[162:165], v[186:189], v[94:97]
	v_mfma_f32_16x16x32_bf16 v[86:89], v[130:133], v[194:197], v[86:89]
	v_mfma_f32_16x16x32_bf16 v[78:81], v[162:165], v[194:197], v[78:81]
	v_mfma_f32_16x16x32_bf16 v[126:129], v[134:137], v[174:177], v[126:129]
	v_mfma_f32_16x16x32_bf16 v[122:125], v[166:169], v[174:177], v[122:125]
	v_mfma_f32_16x16x32_bf16 v[118:121], v[134:137], v[182:185], v[118:121]
	v_mfma_f32_16x16x32_bf16 v[110:113], v[166:169], v[182:185], v[110:113]
	v_mfma_f32_16x16x32_bf16 v[102:105], v[134:137], v[190:193], v[102:105]
	v_mfma_f32_16x16x32_bf16 v[94:97], v[166:169], v[190:193], v[94:97]
	v_mfma_f32_16x16x32_bf16 v[86:89], v[134:137], v[198:201], v[86:89]
	v_mfma_f32_16x16x32_bf16 v[78:81], v[166:169], v[198:201], v[78:81]
	s_barrier
	s_add_i32 s0, s52, s41
	v_lshl_add_u64 v[154:155], s[34:35], 0, v[142:143]
	s_mov_b32 m0, s0
	ds_read_b128 v[202:205], v160
	ds_read_b128 v[206:209], v160 offset:1024
	ds_read_b128 v[210:213], v160 offset:2048
	ds_read_b128 v[214:217], v160 offset:3072
	global_load_lds_dwordx4 v[154:155], off
	v_lshl_add_u64 v[218:219], s[34:35], 0, v[138:139]
	s_add_i32 m0, s0, 0x2000
	s_nop 0
	global_load_lds_dwordx4 v[218:219], off
	s_waitcnt vmcnt(10)
	s_barrier
	s_waitcnt lgkmcnt(0)
	v_mfma_f32_16x16x32_bf16 v[114:117], v[202:205], v[170:173], v[114:117]
	v_mfma_f32_16x16x32_bf16 v[106:109], v[210:213], v[170:173], v[106:109]
	v_mfma_f32_16x16x32_bf16 v[98:101], v[202:205], v[178:181], v[98:101]
	v_mfma_f32_16x16x32_bf16 v[90:93], v[210:213], v[178:181], v[90:93]
	v_mfma_f32_16x16x32_bf16 v[82:85], v[202:205], v[186:189], v[82:85]
	v_mfma_f32_16x16x32_bf16 v[74:77], v[210:213], v[186:189], v[74:77]
	v_mfma_f32_16x16x32_bf16 v[70:73], v[202:205], v[194:197], v[70:73]
	v_mfma_f32_16x16x32_bf16 v[66:69], v[210:213], v[194:197], v[66:69]
	v_mfma_f32_16x16x32_bf16 v[114:117], v[206:209], v[174:177], v[114:117]
	v_mfma_f32_16x16x32_bf16 v[106:109], v[214:217], v[174:177], v[106:109]
	v_mfma_f32_16x16x32_bf16 v[98:101], v[206:209], v[182:185], v[98:101]
	v_mfma_f32_16x16x32_bf16 v[90:93], v[214:217], v[182:185], v[90:93]
	v_mfma_f32_16x16x32_bf16 v[82:85], v[206:209], v[190:193], v[82:85]
	v_mfma_f32_16x16x32_bf16 v[74:77], v[214:217], v[190:193], v[74:77]
	v_mfma_f32_16x16x32_bf16 v[70:73], v[206:209], v[198:201], v[70:73]
	v_mfma_f32_16x16x32_bf16 v[66:69], v[214:217], v[198:201], v[66:69]
	s_mov_b32 m0, s29
	v_lshl_add_u64 v[220:221], s[36:37], 0, v[144:145]
	s_barrier
	ds_read_b128 v[170:173], v159 offset:16384
	ds_read_b128 v[174:177], v159 offset:17408
	ds_read_b128 v[178:181], v159 offset:18432
	ds_read_b128 v[182:185], v159 offset:19456
	ds_read_b128 v[186:189], v159 offset:20480
	ds_read_b128 v[190:193], v159 offset:21504
	ds_read_b128 v[194:197], v159 offset:22528
	ds_read_b128 v[198:201], v159 offset:23552
	global_load_lds_dwordx4 v[220:221], off
	v_lshl_add_u64 v[222:223], s[36:37], 0, v[140:141]
	s_mov_b32 m0, s43
	s_nop 0
	global_load_lds_dwordx4 v[222:223], off
	s_waitcnt vmcnt(10)
	s_barrier
	s_waitcnt lgkmcnt(0)
	v_mfma_f32_16x16x32_bf16 v[62:65], v[130:133], v[170:173], v[62:65]
	v_mfma_f32_16x16x32_bf16 v[58:61], v[162:165], v[170:173], v[58:61]
	v_mfma_f32_16x16x32_bf16 v[54:57], v[130:133], v[178:181], v[54:57]
	v_mfma_f32_16x16x32_bf16 v[46:49], v[162:165], v[178:181], v[46:49]
	v_mfma_f32_16x16x32_bf16 v[38:41], v[130:133], v[186:189], v[38:41]
	v_mfma_f32_16x16x32_bf16 v[30:33], v[162:165], v[186:189], v[30:33]
	v_mfma_f32_16x16x32_bf16 v[22:25], v[130:133], v[194:197], v[22:25]
	v_mfma_f32_16x16x32_bf16 v[14:17], v[162:165], v[194:197], v[14:17]
	v_mfma_f32_16x16x32_bf16 v[62:65], v[134:137], v[174:177], v[62:65]
	v_mfma_f32_16x16x32_bf16 v[58:61], v[166:169], v[174:177], v[58:61]
	v_mfma_f32_16x16x32_bf16 v[54:57], v[134:137], v[182:185], v[54:57]
	v_mfma_f32_16x16x32_bf16 v[46:49], v[166:169], v[182:185], v[46:49]
	v_mfma_f32_16x16x32_bf16 v[38:41], v[134:137], v[190:193], v[38:41]
	v_mfma_f32_16x16x32_bf16 v[30:33], v[166:169], v[190:193], v[30:33]
	v_mfma_f32_16x16x32_bf16 v[22:25], v[134:137], v[198:201], v[22:25]
	v_mfma_f32_16x16x32_bf16 v[14:17], v[166:169], v[198:201], v[14:17]
	s_barrier
	s_add_u32 s0, s34, 0x40000
	s_addc_u32 s1, s35, 0
	s_add_i32 s61, s53, s41
	v_lshl_add_u64 v[130:131], s[0:1], 0, v[142:143]
	s_mov_b32 m0, s61
	s_nop 0
	global_load_lds_dwordx4 v[130:131], off
	v_lshl_add_u64 v[130:131], s[0:1], 0, v[138:139]
	s_add_i32 m0, s61, 0x2000
	s_nop 0
	global_load_lds_dwordx4 v[130:131], off
	s_waitcnt vmcnt(10)
	s_barrier
	v_mfma_f32_16x16x32_bf16 v[50:53], v[202:205], v[170:173], v[50:53]
	v_mfma_f32_16x16x32_bf16 v[42:45], v[210:213], v[170:173], v[42:45]
	v_mfma_f32_16x16x32_bf16 v[34:37], v[202:205], v[178:181], v[34:37]
	v_mfma_f32_16x16x32_bf16 v[26:29], v[210:213], v[178:181], v[26:29]
	v_mfma_f32_16x16x32_bf16 v[18:21], v[202:205], v[186:189], v[18:21]
	v_mfma_f32_16x16x32_bf16 v[10:13], v[210:213], v[186:189], v[10:13]
	v_mfma_f32_16x16x32_bf16 v[6:9], v[202:205], v[194:197], v[6:9]
	v_mfma_f32_16x16x32_bf16 v[2:5], v[210:213], v[194:197], v[2:5]
	v_mfma_f32_16x16x32_bf16 v[50:53], v[206:209], v[174:177], v[50:53]
	v_mfma_f32_16x16x32_bf16 v[42:45], v[214:217], v[174:177], v[42:45]
	v_mfma_f32_16x16x32_bf16 v[34:37], v[206:209], v[182:185], v[34:37]
	v_mfma_f32_16x16x32_bf16 v[26:29], v[214:217], v[182:185], v[26:29]
	v_mfma_f32_16x16x32_bf16 v[18:21], v[206:209], v[190:193], v[18:21]
	v_mfma_f32_16x16x32_bf16 v[10:13], v[214:217], v[190:193], v[10:13]
	v_mfma_f32_16x16x32_bf16 v[6:9], v[206:209], v[198:201], v[6:9]
	v_mfma_f32_16x16x32_bf16 v[2:5], v[214:217], v[198:201], v[2:5]
	s_add_i32 s61, 0, 0x18000
	v_add_u32_e32 v166, s61, v157
	s_barrier
	ds_read_b128 v[130:133], v166
	ds_read_b128 v[134:137], v166 offset:1024
	ds_read_b128 v[162:165], v166 offset:2048
	ds_read_b128 v[166:169], v166 offset:3072
	s_add_u32 s0, s36, 0x40000
	s_addc_u32 s1, s37, 0
	s_mov_b32 m0, s44
	v_lshl_add_u64 v[202:203], s[0:1], 0, v[144:145]
	ds_read_b128 v[170:173], v159 offset:32768
	ds_read_b128 v[174:177], v159 offset:33792
	ds_read_b128 v[178:181], v159 offset:34816
	ds_read_b128 v[182:185], v159 offset:35840
	ds_read_b128 v[186:189], v159 offset:36864
	ds_read_b128 v[190:193], v159 offset:37888
	ds_read_b128 v[194:197], v159 offset:38912
	ds_read_b128 v[198:201], v159 offset:39936
	global_load_lds_dwordx4 v[202:203], off
	v_lshl_add_u64 v[202:203], s[0:1], 0, v[140:141]
	s_mov_b32 m0, s45
	s_nop 0
	global_load_lds_dwordx4 v[202:203], off
	s_waitcnt lgkmcnt(8)
	s_waitcnt vmcnt(10)
	s_barrier
	s_waitcnt lgkmcnt(0)
	v_mfma_f32_16x16x32_bf16 v[126:129], v[130:133], v[170:173], v[126:129]
	v_mfma_f32_16x16x32_bf16 v[122:125], v[162:165], v[170:173], v[122:125]
	v_mfma_f32_16x16x32_bf16 v[118:121], v[130:133], v[178:181], v[118:121]
	v_mfma_f32_16x16x32_bf16 v[110:113], v[162:165], v[178:181], v[110:113]
	v_mfma_f32_16x16x32_bf16 v[102:105], v[130:133], v[186:189], v[102:105]
	v_mfma_f32_16x16x32_bf16 v[94:97], v[162:165], v[186:189], v[94:97]
	v_mfma_f32_16x16x32_bf16 v[86:89], v[130:133], v[194:197], v[86:89]
	v_mfma_f32_16x16x32_bf16 v[78:81], v[162:165], v[194:197], v[78:81]
	v_mfma_f32_16x16x32_bf16 v[126:129], v[134:137], v[174:177], v[126:129]
	v_mfma_f32_16x16x32_bf16 v[122:125], v[166:169], v[174:177], v[122:125]
	v_mfma_f32_16x16x32_bf16 v[118:121], v[134:137], v[182:185], v[118:121]
	v_mfma_f32_16x16x32_bf16 v[110:113], v[166:169], v[182:185], v[110:113]
	v_mfma_f32_16x16x32_bf16 v[102:105], v[134:137], v[190:193], v[102:105]
	v_mfma_f32_16x16x32_bf16 v[94:97], v[166:169], v[190:193], v[94:97]
	v_mfma_f32_16x16x32_bf16 v[86:89], v[134:137], v[198:201], v[86:89]
	v_mfma_f32_16x16x32_bf16 v[78:81], v[166:169], v[198:201], v[78:81]
	s_barrier
	s_add_i32 s36, 0, 0x1c000
	s_add_i32 s0, s61, s41
	v_add_u32_e32 v214, s36, v157
	v_lshl_add_u64 v[154:155], v[154:155], 0, s[16:17]
	s_mov_b32 m0, s0
	ds_read_b128 v[202:205], v214
	ds_read_b128 v[206:209], v214 offset:1024
	ds_read_b128 v[210:213], v214 offset:2048
	ds_read_b128 v[214:217], v214 offset:3072
	global_load_lds_dwordx4 v[154:155], off
	v_lshl_add_u64 v[154:155], v[218:219], 0, s[16:17]
	s_add_i32 m0, s0, 0x2000
	s_nop 0
	global_load_lds_dwordx4 v[154:155], off
	s_waitcnt vmcnt(10)
	s_barrier
	s_waitcnt lgkmcnt(0)
	v_mfma_f32_16x16x32_bf16 v[114:117], v[202:205], v[170:173], v[114:117]
	v_mfma_f32_16x16x32_bf16 v[106:109], v[210:213], v[170:173], v[106:109]
	v_mfma_f32_16x16x32_bf16 v[98:101], v[202:205], v[178:181], v[98:101]
	v_mfma_f32_16x16x32_bf16 v[90:93], v[210:213], v[178:181], v[90:93]
	v_mfma_f32_16x16x32_bf16 v[82:85], v[202:205], v[186:189], v[82:85]
	v_mfma_f32_16x16x32_bf16 v[74:77], v[210:213], v[186:189], v[74:77]
	v_mfma_f32_16x16x32_bf16 v[70:73], v[202:205], v[194:197], v[70:73]
	v_mfma_f32_16x16x32_bf16 v[66:69], v[210:213], v[194:197], v[66:69]
	v_mfma_f32_16x16x32_bf16 v[114:117], v[206:209], v[174:177], v[114:117]
	v_mfma_f32_16x16x32_bf16 v[106:109], v[214:217], v[174:177], v[106:109]
	v_mfma_f32_16x16x32_bf16 v[98:101], v[206:209], v[182:185], v[98:101]
	v_mfma_f32_16x16x32_bf16 v[90:93], v[214:217], v[182:185], v[90:93]
	v_mfma_f32_16x16x32_bf16 v[82:85], v[206:209], v[190:193], v[82:85]
	v_mfma_f32_16x16x32_bf16 v[74:77], v[214:217], v[190:193], v[74:77]
	v_mfma_f32_16x16x32_bf16 v[70:73], v[206:209], v[198:201], v[70:73]
	v_mfma_f32_16x16x32_bf16 v[66:69], v[214:217], v[198:201], v[66:69]
	s_mov_b32 m0, s49
	v_lshl_add_u64 v[154:155], v[220:221], 0, s[16:17]
	s_barrier
	ds_read_b128 v[170:173], v159 offset:49152
	ds_read_b128 v[174:177], v159 offset:50176
	ds_read_b128 v[178:181], v159 offset:51200
	ds_read_b128 v[182:185], v159 offset:52224
	ds_read_b128 v[186:189], v159 offset:53248
	ds_read_b128 v[190:193], v159 offset:54272
	ds_read_b128 v[194:197], v159 offset:55296
	ds_read_b128 v[198:201], v159 offset:56320
	global_load_lds_dwordx4 v[154:155], off
	v_lshl_add_u64 v[154:155], v[222:223], 0, s[16:17]
	s_mov_b32 m0, s51
	s_nop 0
	global_load_lds_dwordx4 v[154:155], off
	s_waitcnt vmcnt(10)
	s_barrier
	s_waitcnt lgkmcnt(0)
	v_mfma_f32_16x16x32_bf16 v[62:65], v[130:133], v[170:173], v[62:65]
	v_mfma_f32_16x16x32_bf16 v[58:61], v[162:165], v[170:173], v[58:61]
	v_mfma_f32_16x16x32_bf16 v[54:57], v[130:133], v[178:181], v[54:57]
	v_mfma_f32_16x16x32_bf16 v[46:49], v[162:165], v[178:181], v[46:49]
	v_mfma_f32_16x16x32_bf16 v[38:41], v[130:133], v[186:189], v[38:41]
	v_mfma_f32_16x16x32_bf16 v[30:33], v[162:165], v[186:189], v[30:33]
	v_mfma_f32_16x16x32_bf16 v[22:25], v[130:133], v[194:197], v[22:25]
	v_mfma_f32_16x16x32_bf16 v[14:17], v[162:165], v[194:197], v[14:17]
	v_mfma_f32_16x16x32_bf16 v[62:65], v[134:137], v[174:177], v[62:65]
	v_mfma_f32_16x16x32_bf16 v[58:61], v[166:169], v[174:177], v[58:61]
	v_mfma_f32_16x16x32_bf16 v[54:57], v[134:137], v[182:185], v[54:57]
	v_mfma_f32_16x16x32_bf16 v[46:49], v[166:169], v[182:185], v[46:49]
	v_mfma_f32_16x16x32_bf16 v[38:41], v[134:137], v[190:193], v[38:41]
	v_mfma_f32_16x16x32_bf16 v[30:33], v[166:169], v[190:193], v[30:33]
	v_mfma_f32_16x16x32_bf16 v[22:25], v[134:137], v[198:201], v[22:25]
	v_mfma_f32_16x16x32_bf16 v[14:17], v[166:169], v[198:201], v[14:17]
	s_barrier
	s_add_u32 s0, s34, 0x40080
	s_addc_u32 s1, s35, 0
	s_add_i32 s34, s36, s41
	v_lshl_add_u64 v[130:131], s[0:1], 0, v[142:143]
	s_mov_b32 m0, s34
	s_nop 0
	global_load_lds_dwordx4 v[130:131], off
	v_lshl_add_u64 v[130:131], s[0:1], 0, v[138:139]
	s_add_i32 m0, s34, 0x2000
	s_nop 0
	global_load_lds_dwordx4 v[130:131], off
	s_waitcnt vmcnt(10)
	s_barrier
	v_mfma_f32_16x16x32_bf16 v[50:53], v[202:205], v[170:173], v[50:53]
	v_mfma_f32_16x16x32_bf16 v[42:45], v[210:213], v[170:173], v[42:45]
	v_mfma_f32_16x16x32_bf16 v[34:37], v[202:205], v[178:181], v[34:37]
	v_mfma_f32_16x16x32_bf16 v[26:29], v[210:213], v[178:181], v[26:29]
	v_mfma_f32_16x16x32_bf16 v[18:21], v[202:205], v[186:189], v[18:21]
	v_mfma_f32_16x16x32_bf16 v[10:13], v[210:213], v[186:189], v[10:13]
	v_mfma_f32_16x16x32_bf16 v[6:9], v[202:205], v[194:197], v[6:9]
	v_mfma_f32_16x16x32_bf16 v[2:5], v[210:213], v[194:197], v[2:5]
	v_mfma_f32_16x16x32_bf16 v[50:53], v[206:209], v[174:177], v[50:53]
	v_mfma_f32_16x16x32_bf16 v[42:45], v[214:217], v[174:177], v[42:45]
	v_mfma_f32_16x16x32_bf16 v[34:37], v[206:209], v[182:185], v[34:37]
	v_mfma_f32_16x16x32_bf16 v[26:29], v[214:217], v[182:185], v[26:29]
	v_mfma_f32_16x16x32_bf16 v[18:21], v[206:209], v[190:193], v[18:21]
	v_mfma_f32_16x16x32_bf16 v[10:13], v[214:217], v[190:193], v[10:13]
	v_mfma_f32_16x16x32_bf16 v[6:9], v[206:209], v[198:201], v[6:9]
	v_mfma_f32_16x16x32_bf16 v[2:5], v[214:217], v[198:201], v[2:5]
	s_add_i32 s60, s60, 2
	s_add_u32 s58, s58, 0x100
	s_addc_u32 s59, s59, 0
	s_add_u32 s30, s30, 0x100
	s_addc_u32 s31, s31, 0
	s_cmp_gt_u32 s60, 13
	s_barrier
	s_cbranch_scc0 .LBB0_278
	v_mov_b32_e32 v162, v1
	v_mov_b32_e32 v163, v156
	s_cmp_gt_i32 s55, 11
	s_mov_b64 s[30:31], -1
	s_cbranch_scc0 .LBB0_286
	s_cmp_eq_u32 s55, 12
	s_cselect_b64 s[0:1], -1, 0
	s_and_b64 s[0:1], s[0:1], s[18:19]
	v_cmp_gt_i32_e32 vcc, 2, v163
	s_and_b64 s[0:1], s[0:1], vcc
	s_and_saveexec_b64 s[30:31], s[0:1]
	s_cbranch_execz .LBB0_285
	v_lshlrev_b32_e32 v154, 3, v163
	s_andn2_b64 vcc, exec, s[12:13]
	v_ashrrev_i32_e32 v155, 31, v154
	s_cbranch_vccnz .LBB0_283
	v_lshl_add_u64 v[134:135], v[154:155], 2, s[8:9]
	global_load_dwordx4 v[130:133], v[134:135], off
	s_nop 0
	global_load_dwordx4 v[134:137], v[134:135], off offset:16
	s_branch .LBB0_284

.LBB0_434:
	ds_read_b128 v[146:149], v152
	ds_read_b128 v[156:159], v152 offset:1024
	ds_read_b128 v[160:163], v152 offset:2048
	ds_read_b128 v[164:167], v152 offset:3072
	s_add_u32 s0, s36, 0xfffc0080
	s_addc_u32 s1, s37, -1
	s_cmp_eq_u32 s69, 12
	s_cselect_b32 s41, s60, s1
	s_cselect_b32 s40, s61, s0
	s_cselect_b32 s39, s62, s67
	s_cselect_b32 s38, s63, s66
	s_mov_b32 m0, s50
	v_lshl_add_u64 v[200:201], s[36:37], 0, v[144:145]
	ds_read_b128 v[168:171], v153
	ds_read_b128 v[172:175], v153 offset:1024
	ds_read_b128 v[176:179], v153 offset:2048
	ds_read_b128 v[180:183], v153 offset:3072
	ds_read_b128 v[184:187], v153 offset:4096
	ds_read_b128 v[188:191], v153 offset:5120
	ds_read_b128 v[192:195], v153 offset:6144
	ds_read_b128 v[196:199], v153 offset:7168
	global_load_lds_dwordx4 v[200:201], off
	v_lshl_add_u64 v[200:201], s[36:37], 0, v[142:143]
	s_mov_b32 m0, s51
	s_nop 0
	global_load_lds_dwordx4 v[200:201], off
	s_waitcnt lgkmcnt(8)
	s_waitcnt vmcnt(10)
	s_barrier
	s_waitcnt lgkmcnt(0)
	v_mfma_f32_16x16x32_bf16 v[126:129], v[146:149], v[168:171], v[126:129]
	v_mfma_f32_16x16x32_bf16 v[122:125], v[160:163], v[168:171], v[122:125]
	v_mfma_f32_16x16x32_bf16 v[114:117], v[146:149], v[176:179], v[114:117]
	v_mfma_f32_16x16x32_bf16 v[106:109], v[160:163], v[176:179], v[106:109]
	v_mfma_f32_16x16x32_bf16 v[98:101], v[146:149], v[184:187], v[98:101]
	v_mfma_f32_16x16x32_bf16 v[90:93], v[160:163], v[184:187], v[90:93]
	v_mfma_f32_16x16x32_bf16 v[82:85], v[146:149], v[192:195], v[82:85]
	v_mfma_f32_16x16x32_bf16 v[74:77], v[160:163], v[192:195], v[74:77]
	v_mfma_f32_16x16x32_bf16 v[126:129], v[156:159], v[172:175], v[126:129]
	v_mfma_f32_16x16x32_bf16 v[122:125], v[164:167], v[172:175], v[122:125]
	v_mfma_f32_16x16x32_bf16 v[114:117], v[156:159], v[180:183], v[114:117]
	v_mfma_f32_16x16x32_bf16 v[106:109], v[164:167], v[180:183], v[106:109]
	v_mfma_f32_16x16x32_bf16 v[98:101], v[156:159], v[188:191], v[98:101]
	v_mfma_f32_16x16x32_bf16 v[90:93], v[164:167], v[188:191], v[90:93]
	v_mfma_f32_16x16x32_bf16 v[82:85], v[156:159], v[196:199], v[82:85]
	v_mfma_f32_16x16x32_bf16 v[74:77], v[164:167], v[196:199], v[74:77]
	s_barrier
	s_mov_b32 m0, s52
	v_lshl_add_u64 v[216:217], s[38:39], 0, v[138:139]
	ds_read_b128 v[200:203], v154
	ds_read_b128 v[204:207], v154 offset:1024
	ds_read_b128 v[208:211], v154 offset:2048
	ds_read_b128 v[212:215], v154 offset:3072
	global_load_lds_dwordx4 v[216:217], off
	v_lshl_add_u64 v[218:219], s[38:39], 0, v[134:135]
	s_mov_b32 m0, s53
	s_nop 0
	global_load_lds_dwordx4 v[218:219], off
	s_waitcnt vmcnt(10)
	s_barrier
	s_waitcnt lgkmcnt(0)
	v_mfma_f32_16x16x32_bf16 v[118:121], v[200:203], v[168:171], v[118:121]
	v_mfma_f32_16x16x32_bf16 v[110:113], v[208:211], v[168:171], v[110:113]
	v_mfma_f32_16x16x32_bf16 v[102:105], v[200:203], v[176:179], v[102:105]
	v_mfma_f32_16x16x32_bf16 v[94:97], v[208:211], v[176:179], v[94:97]
	v_mfma_f32_16x16x32_bf16 v[86:89], v[200:203], v[184:187], v[86:89]
	v_mfma_f32_16x16x32_bf16 v[78:81], v[208:211], v[184:187], v[78:81]
	v_mfma_f32_16x16x32_bf16 v[70:73], v[200:203], v[192:195], v[70:73]
	v_mfma_f32_16x16x32_bf16 v[66:69], v[208:211], v[192:195], v[66:69]
	v_mfma_f32_16x16x32_bf16 v[118:121], v[204:207], v[172:175], v[118:121]
	v_mfma_f32_16x16x32_bf16 v[110:113], v[212:215], v[172:175], v[110:113]
	v_mfma_f32_16x16x32_bf16 v[102:105], v[204:207], v[180:183], v[102:105]
	v_mfma_f32_16x16x32_bf16 v[94:97], v[212:215], v[180:183], v[94:97]
	v_mfma_f32_16x16x32_bf16 v[86:89], v[204:207], v[188:191], v[86:89]
	v_mfma_f32_16x16x32_bf16 v[78:81], v[212:215], v[188:191], v[78:81]
	v_mfma_f32_16x16x32_bf16 v[70:73], v[204:207], v[196:199], v[70:73]
	v_mfma_f32_16x16x32_bf16 v[66:69], v[212:215], v[196:199], v[66:69]
	s_mov_b32 m0, s6
	v_lshl_add_u64 v[220:221], s[40:41], 0, v[140:141]
	s_barrier
	ds_read_b128 v[168:171], v153 offset:16384
	ds_read_b128 v[172:175], v153 offset:17408
	ds_read_b128 v[176:179], v153 offset:18432
	ds_read_b128 v[180:183], v153 offset:19456
	ds_read_b128 v[184:187], v153 offset:20480
	ds_read_b128 v[188:191], v153 offset:21504
	ds_read_b128 v[192:195], v153 offset:22528
	ds_read_b128 v[196:199], v153 offset:23552
	global_load_lds_dwordx4 v[220:221], off
	v_lshl_add_u64 v[222:223], s[40:41], 0, v[136:137]
	s_mov_b32 m0, s7
	s_nop 0
	global_load_lds_dwordx4 v[222:223], off
	s_waitcnt vmcnt(10)
	s_barrier
	s_waitcnt lgkmcnt(0)
	v_mfma_f32_16x16x32_bf16 v[62:65], v[146:149], v[168:171], v[62:65]
	v_mfma_f32_16x16x32_bf16 v[58:61], v[160:163], v[168:171], v[58:61]
	v_mfma_f32_16x16x32_bf16 v[50:53], v[146:149], v[176:179], v[50:53]
	v_mfma_f32_16x16x32_bf16 v[42:45], v[160:163], v[176:179], v[42:45]
	v_mfma_f32_16x16x32_bf16 v[34:37], v[146:149], v[184:187], v[34:37]
	v_mfma_f32_16x16x32_bf16 v[26:29], v[160:163], v[184:187], v[26:29]
	v_mfma_f32_16x16x32_bf16 v[18:21], v[146:149], v[192:195], v[18:21]
	v_mfma_f32_16x16x32_bf16 v[10:13], v[160:163], v[192:195], v[10:13]
	v_mfma_f32_16x16x32_bf16 v[62:65], v[156:159], v[172:175], v[62:65]
	v_mfma_f32_16x16x32_bf16 v[58:61], v[164:167], v[172:175], v[58:61]
	v_mfma_f32_16x16x32_bf16 v[50:53], v[156:159], v[180:183], v[50:53]
	v_mfma_f32_16x16x32_bf16 v[42:45], v[164:167], v[180:183], v[42:45]
	v_mfma_f32_16x16x32_bf16 v[34:37], v[156:159], v[188:191], v[34:37]
	v_mfma_f32_16x16x32_bf16 v[26:29], v[164:167], v[188:191], v[26:29]
	v_mfma_f32_16x16x32_bf16 v[18:21], v[156:159], v[196:199], v[18:21]
	v_mfma_f32_16x16x32_bf16 v[10:13], v[164:167], v[196:199], v[10:13]
	s_barrier
	s_add_u32 s0, s38, 0x40000
	s_addc_u32 s1, s39, 0
	s_mov_b32 m0, s54
	v_lshl_add_u64 v[146:147], s[0:1], 0, v[138:139]
	global_load_lds_dwordx4 v[146:147], off
	v_lshl_add_u64 v[146:147], s[0:1], 0, v[134:135]
	s_add_i32 m0, s54, 0x2000
	s_nop 0
	global_load_lds_dwordx4 v[146:147], off
	s_waitcnt vmcnt(10)
	s_barrier
	v_mfma_f32_16x16x32_bf16 v[54:57], v[200:203], v[168:171], v[54:57]
	v_mfma_f32_16x16x32_bf16 v[46:49], v[208:211], v[168:171], v[46:49]
	v_mfma_f32_16x16x32_bf16 v[38:41], v[200:203], v[176:179], v[38:41]
	v_mfma_f32_16x16x32_bf16 v[30:33], v[208:211], v[176:179], v[30:33]
	v_mfma_f32_16x16x32_bf16 v[22:25], v[200:203], v[184:187], v[22:25]
	v_mfma_f32_16x16x32_bf16 v[14:17], v[208:211], v[184:187], v[14:17]
	v_mfma_f32_16x16x32_bf16 v[6:9], v[200:203], v[192:195], v[6:9]
	v_mfma_f32_16x16x32_bf16 v[2:5], v[208:211], v[192:195], v[2:5]
	v_mfma_f32_16x16x32_bf16 v[54:57], v[204:207], v[172:175], v[54:57]
	v_mfma_f32_16x16x32_bf16 v[46:49], v[212:215], v[172:175], v[46:49]
	v_mfma_f32_16x16x32_bf16 v[38:41], v[204:207], v[180:183], v[38:41]
	v_mfma_f32_16x16x32_bf16 v[30:33], v[212:215], v[180:183], v[30:33]
	v_mfma_f32_16x16x32_bf16 v[22:25], v[204:207], v[188:191], v[22:25]
	v_mfma_f32_16x16x32_bf16 v[14:17], v[212:215], v[188:191], v[14:17]
	v_mfma_f32_16x16x32_bf16 v[6:9], v[204:207], v[196:199], v[6:9]
	v_mfma_f32_16x16x32_bf16 v[2:5], v[212:215], v[196:199], v[2:5]
	s_add_i32 s70, 0, 0x18000
	v_add_u32_e32 v155, s70, v151
	s_barrier
	ds_read_b128 v[146:149], v155
	ds_read_b128 v[156:159], v155 offset:1024
	ds_read_b128 v[160:163], v155 offset:2048
	ds_read_b128 v[164:167], v155 offset:3072
	s_add_u32 s0, s40, 0x40000
	s_addc_u32 s1, s41, 0
	s_mov_b32 m0, s29
	v_lshl_add_u64 v[200:201], s[0:1], 0, v[140:141]
	ds_read_b128 v[168:171], v153 offset:32768
	ds_read_b128 v[172:175], v153 offset:33792
	ds_read_b128 v[176:179], v153 offset:34816
	ds_read_b128 v[180:183], v153 offset:35840
	ds_read_b128 v[184:187], v153 offset:36864
	ds_read_b128 v[188:191], v153 offset:37888
	ds_read_b128 v[192:195], v153 offset:38912
	ds_read_b128 v[196:199], v153 offset:39936
	global_load_lds_dwordx4 v[200:201], off
	v_lshl_add_u64 v[200:201], s[0:1], 0, v[136:137]
	s_mov_b32 m0, s42
	s_nop 0
	global_load_lds_dwordx4 v[200:201], off
	s_waitcnt lgkmcnt(8)
	s_waitcnt vmcnt(10)
	s_barrier
	s_waitcnt lgkmcnt(0)
	v_mfma_f32_16x16x32_bf16 v[126:129], v[146:149], v[168:171], v[126:129]
	v_mfma_f32_16x16x32_bf16 v[122:125], v[160:163], v[168:171], v[122:125]
	v_mfma_f32_16x16x32_bf16 v[114:117], v[146:149], v[176:179], v[114:117]
	v_mfma_f32_16x16x32_bf16 v[106:109], v[160:163], v[176:179], v[106:109]
	v_mfma_f32_16x16x32_bf16 v[98:101], v[146:149], v[184:187], v[98:101]
	v_mfma_f32_16x16x32_bf16 v[90:93], v[160:163], v[184:187], v[90:93]
	v_mfma_f32_16x16x32_bf16 v[82:85], v[146:149], v[192:195], v[82:85]
	v_mfma_f32_16x16x32_bf16 v[74:77], v[160:163], v[192:195], v[74:77]
	v_mfma_f32_16x16x32_bf16 v[126:129], v[156:159], v[172:175], v[126:129]
	v_mfma_f32_16x16x32_bf16 v[122:125], v[164:167], v[172:175], v[122:125]
	v_mfma_f32_16x16x32_bf16 v[114:117], v[156:159], v[180:183], v[114:117]
	v_mfma_f32_16x16x32_bf16 v[106:109], v[164:167], v[180:183], v[106:109]
	v_mfma_f32_16x16x32_bf16 v[98:101], v[156:159], v[188:191], v[98:101]
	v_mfma_f32_16x16x32_bf16 v[90:93], v[164:167], v[188:191], v[90:93]
	v_mfma_f32_16x16x32_bf16 v[82:85], v[156:159], v[196:199], v[82:85]
	v_mfma_f32_16x16x32_bf16 v[74:77], v[164:167], v[196:199], v[74:77]
	s_barrier
	s_add_i32 s40, 0, 0x1c000
	s_add_i32 s0, s70, s5
	v_add_u32_e32 v155, s40, v151
	v_lshl_add_u64 v[216:217], v[216:217], 0, s[26:27]
	s_mov_b32 m0, s0
	ds_read_b128 v[200:203], v155
	ds_read_b128 v[204:207], v155 offset:1024
	ds_read_b128 v[208:211], v155 offset:2048
	ds_read_b128 v[212:215], v155 offset:3072
	global_load_lds_dwordx4 v[216:217], off
	v_lshl_add_u64 v[216:217], v[218:219], 0, s[26:27]
	s_add_i32 m0, s0, 0x2000
	s_nop 0
	global_load_lds_dwordx4 v[216:217], off
	s_waitcnt vmcnt(10)
	s_barrier
	s_waitcnt lgkmcnt(0)
	v_mfma_f32_16x16x32_bf16 v[118:121], v[200:203], v[168:171], v[118:121]
	v_mfma_f32_16x16x32_bf16 v[110:113], v[208:211], v[168:171], v[110:113]
	v_mfma_f32_16x16x32_bf16 v[102:105], v[200:203], v[176:179], v[102:105]
	v_mfma_f32_16x16x32_bf16 v[94:97], v[208:211], v[176:179], v[94:97]
	v_mfma_f32_16x16x32_bf16 v[86:89], v[200:203], v[184:187], v[86:89]
	v_mfma_f32_16x16x32_bf16 v[78:81], v[208:211], v[184:187], v[78:81]
	v_mfma_f32_16x16x32_bf16 v[70:73], v[200:203], v[192:195], v[70:73]
	v_mfma_f32_16x16x32_bf16 v[66:69], v[208:211], v[192:195], v[66:69]
	v_mfma_f32_16x16x32_bf16 v[118:121], v[204:207], v[172:175], v[118:121]
	v_mfma_f32_16x16x32_bf16 v[110:113], v[212:215], v[172:175], v[110:113]
	v_mfma_f32_16x16x32_bf16 v[102:105], v[204:207], v[180:183], v[102:105]
	v_mfma_f32_16x16x32_bf16 v[94:97], v[212:215], v[180:183], v[94:97]
	v_mfma_f32_16x16x32_bf16 v[86:89], v[204:207], v[188:191], v[86:89]
	v_mfma_f32_16x16x32_bf16 v[78:81], v[212:215], v[188:191], v[78:81]
	v_mfma_f32_16x16x32_bf16 v[70:73], v[204:207], v[196:199], v[70:73]
	v_mfma_f32_16x16x32_bf16 v[66:69], v[212:215], v[196:199], v[66:69]
	s_mov_b32 m0, s46
	v_lshl_add_u64 v[216:217], v[220:221], 0, s[26:27]
	s_barrier
	ds_read_b128 v[168:171], v153 offset:49152
	ds_read_b128 v[172:175], v153 offset:50176
	ds_read_b128 v[176:179], v153 offset:51200
	ds_read_b128 v[180:183], v153 offset:52224
	ds_read_b128 v[184:187], v153 offset:53248
	ds_read_b128 v[188:191], v153 offset:54272
	ds_read_b128 v[192:195], v153 offset:55296
	ds_read_b128 v[196:199], v153 offset:56320
	global_load_lds_dwordx4 v[216:217], off
	v_lshl_add_u64 v[216:217], v[222:223], 0, s[26:27]
	s_mov_b32 m0, s47
	s_nop 0
	global_load_lds_dwordx4 v[216:217], off
	s_waitcnt vmcnt(10)
	s_barrier
	s_waitcnt lgkmcnt(0)
	v_mfma_f32_16x16x32_bf16 v[62:65], v[146:149], v[168:171], v[62:65]
	v_mfma_f32_16x16x32_bf16 v[58:61], v[160:163], v[168:171], v[58:61]
	v_mfma_f32_16x16x32_bf16 v[50:53], v[146:149], v[176:179], v[50:53]
	v_mfma_f32_16x16x32_bf16 v[42:45], v[160:163], v[176:179], v[42:45]
	v_mfma_f32_16x16x32_bf16 v[34:37], v[146:149], v[184:187], v[34:37]
	v_mfma_f32_16x16x32_bf16 v[26:29], v[160:163], v[184:187], v[26:29]
	v_mfma_f32_16x16x32_bf16 v[18:21], v[146:149], v[192:195], v[18:21]
	v_mfma_f32_16x16x32_bf16 v[10:13], v[160:163], v[192:195], v[10:13]
	v_mfma_f32_16x16x32_bf16 v[62:65], v[156:159], v[172:175], v[62:65]
	v_mfma_f32_16x16x32_bf16 v[58:61], v[164:167], v[172:175], v[58:61]
	v_mfma_f32_16x16x32_bf16 v[50:53], v[156:159], v[180:183], v[50:53]
	v_mfma_f32_16x16x32_bf16 v[42:45], v[164:167], v[180:183], v[42:45]
	v_mfma_f32_16x16x32_bf16 v[34:37], v[156:159], v[188:191], v[34:37]
	v_mfma_f32_16x16x32_bf16 v[26:29], v[164:167], v[188:191], v[26:29]
	v_mfma_f32_16x16x32_bf16 v[18:21], v[156:159], v[196:199], v[18:21]
	v_mfma_f32_16x16x32_bf16 v[10:13], v[164:167], v[196:199], v[10:13]
	s_barrier
	s_add_u32 s0, s38, 0x40080
	s_addc_u32 s1, s39, 0
	s_add_i32 s38, s40, s5
	v_lshl_add_u64 v[146:147], s[0:1], 0, v[138:139]
	s_mov_b32 m0, s38
	s_nop 0
	global_load_lds_dwordx4 v[146:147], off
	v_lshl_add_u64 v[146:147], s[0:1], 0, v[134:135]
	s_add_i32 m0, s38, 0x2000
	s_nop 0
	global_load_lds_dwordx4 v[146:147], off
	s_waitcnt vmcnt(10)
	s_barrier
	v_mfma_f32_16x16x32_bf16 v[54:57], v[200:203], v[168:171], v[54:57]
	v_mfma_f32_16x16x32_bf16 v[46:49], v[208:211], v[168:171], v[46:49]
	v_mfma_f32_16x16x32_bf16 v[38:41], v[200:203], v[176:179], v[38:41]
	v_mfma_f32_16x16x32_bf16 v[30:33], v[208:211], v[176:179], v[30:33]
	v_mfma_f32_16x16x32_bf16 v[22:25], v[200:203], v[184:187], v[22:25]
	v_mfma_f32_16x16x32_bf16 v[14:17], v[208:211], v[184:187], v[14:17]
	v_mfma_f32_16x16x32_bf16 v[6:9], v[200:203], v[192:195], v[6:9]
	v_mfma_f32_16x16x32_bf16 v[2:5], v[208:211], v[192:195], v[2:5]
	v_mfma_f32_16x16x32_bf16 v[54:57], v[204:207], v[172:175], v[54:57]
	v_mfma_f32_16x16x32_bf16 v[46:49], v[212:215], v[172:175], v[46:49]
	v_mfma_f32_16x16x32_bf16 v[38:41], v[204:207], v[180:183], v[38:41]
	v_mfma_f32_16x16x32_bf16 v[30:33], v[212:215], v[180:183], v[30:33]
	v_mfma_f32_16x16x32_bf16 v[22:25], v[204:207], v[188:191], v[22:25]
	v_mfma_f32_16x16x32_bf16 v[14:17], v[212:215], v[188:191], v[14:17]
	v_mfma_f32_16x16x32_bf16 v[6:9], v[204:207], v[196:199], v[6:9]
	v_mfma_f32_16x16x32_bf16 v[2:5], v[212:215], v[196:199], v[2:5]
	s_add_i32 s69, s69, 2
	s_add_u32 s66, s66, 0x100
	s_addc_u32 s67, s67, 0
	s_add_u32 s36, s36, 0x100
	s_addc_u32 s37, s37, 0
	s_cmp_gt_u32 s69, 13
	s_barrier
	s_cbranch_scc0 .LBB0_434
	v_mov_b32_e32 v147, v131
	v_mov_b32_e32 v146, v133
	s_lshl_b32 s0, s58, 8
	s_or_b32 s0, s0, s45
	v_lshl_add_u32 v146, v146, 3, s0
	s_lshl_b32 s0, s59, 8
	s_add_i32 s0, s0, s44
	v_add_u32_e32 v155, s0, v147
	v_mov_b32_e32 v148, v155
	v_ashrrev_i32_e32 v147, 31, v146
	v_ashrrev_i32_e32 v149, 31, v148
	v_lshlrev_b64 v[148:149], 10, v[148:149]
	v_lshl_add_u64 v[148:149], v[148:149], 0, v[146:147]
	v_lshlrev_b64 v[148:149], 1, v[148:149]
	v_lshl_add_u64 v[176:177], s[10:11], 0, v[148:149]
	global_load_dwordx4 v[156:159], v[176:177], off
	global_load_dwordx4 v[160:163], v[176:177], off offset:256
	v_add_co_u32_e32 v168, vcc, s49, v176
	v_lshl_add_u64 v[148:149], s[12:13], 0, v[148:149]
	s_nop 0
	v_addc_co_u32_e32 v169, vcc, 0, v177, vcc
	global_load_dwordx4 v[164:167], v[168:169], off
	s_nop 0
	global_load_dwordx4 v[168:171], v[168:169], off offset:256
	v_add_co_u32_e32 v178, vcc, s43, v176
	s_mov_b32 s58, s57
	s_nop 0
	v_addc_co_u32_e32 v179, vcc, 0, v177, vcc
	global_load_dwordx4 v[172:175], v[178:179], off
	v_add_co_u32_e32 v184, vcc, s48, v176
	s_mov_b32 s59, s56
	s_nop 0
	v_addc_co_u32_e32 v185, vcc, 0, v177, vcc
	global_load_dwordx4 v[176:179], v[178:179], off offset:256
	s_nop 0
	global_load_dwordx4 v[180:183], v[184:185], off
	s_nop 0
	global_load_dwordx4 v[184:187], v[184:185], off offset:256
	v_add_co_u32_e32 v188, vcc, s49, v148
	s_waitcnt vmcnt(0) lgkmcnt(0)
	v_lshlrev_b32_e32 v190, 16, v156
	v_and_b32_e32 v191, 0xffff0000, v156
	v_lshlrev_b32_e32 v156, 16, v157
	v_and_b32_e32 v157, 0xffff0000, v157
	v_lshlrev_b32_e32 v192, 16, v158
	v_and_b32_e32 v193, 0xffff0000, v158
	v_lshlrev_b32_e32 v194, 16, v160
	v_and_b32_e32 v195, 0xffff0000, v160
	v_lshlrev_b32_e32 v160, 16, v161
	v_and_b32_e32 v161, 0xffff0000, v161
	v_lshlrev_b32_e32 v196, 16, v162
	v_and_b32_e32 v197, 0xffff0000, v162
	v_lshlrev_b32_e32 v162, 16, v163
	v_and_b32_e32 v163, 0xffff0000, v163
	v_lshlrev_b32_e32 v158, 16, v159
	v_and_b32_e32 v159, 0xffff0000, v159
	v_pk_fma_f32 v[128:129], v[156:157], s[28:29], v[128:129] op_sel_hi:[1,0,1]
	v_pk_fma_f32 v[122:123], v[192:193], s[28:29], v[122:123] op_sel_hi:[1,0,1]
	v_pk_fma_f32 v[120:121], v[160:161], s[28:29], v[120:121] op_sel_hi:[1,0,1]
	v_pk_fma_f32 v[156:157], v[162:163], s[28:29], v[112:113] op_sel_hi:[1,0,1]
	v_lshlrev_b32_e32 v160, 16, v164
	v_and_b32_e32 v161, 0xffff0000, v164
	v_lshlrev_b32_e32 v162, 16, v165
	v_and_b32_e32 v163, 0xffff0000, v165
	v_lshlrev_b32_e32 v164, 16, v166
	v_and_b32_e32 v165, 0xffff0000, v166
	v_lshlrev_b32_e32 v166, 16, v167
	v_and_b32_e32 v167, 0xffff0000, v167
	v_pk_fma_f32 v[126:127], v[190:191], s[28:29], v[126:127] op_sel_hi:[1,0,1]
	v_pk_fma_f32 v[124:125], v[158:159], s[28:29], v[124:125] op_sel_hi:[1,0,1]
	v_cvt_pk_bf16_f32 v112, v122, v123
	v_pk_fma_f32 v[116:117], v[162:163], s[28:29], v[116:117] op_sel_hi:[1,0,1]
	v_pk_fma_f32 v[114:115], v[160:161], s[28:29], v[114:115] op_sel_hi:[1,0,1]
	v_pk_fma_f32 v[122:123], v[166:167], s[28:29], v[108:109] op_sel_hi:[1,0,1]
	v_pk_fma_f32 v[108:109], v[164:165], s[28:29], v[106:107] op_sel_hi:[1,0,1]
	v_addc_co_u32_e32 v189, vcc, 0, v149, vcc
	v_pk_fma_f32 v[118:119], v[194:195], s[28:29], v[118:119] op_sel_hi:[1,0,1]
	v_pk_fma_f32 v[158:159], v[196:197], s[28:29], v[110:111] op_sel_hi:[1,0,1]
	v_cvt_pk_bf16_f32 v110, v126, v127
	v_cvt_pk_bf16_f32 v111, v128, v129
	v_cvt_pk_bf16_f32 v113, v124, v125
	v_cvt_pk_bf16_f32 v106, v114, v115
	v_cvt_pk_bf16_f32 v107, v116, v117
	v_cvt_pk_bf16_f32 v108, v108, v109
	v_cvt_pk_bf16_f32 v109, v122, v123
	v_lshlrev_b32_e32 v190, 16, v168
	v_cvt_pk_bf16_f32 v118, v118, v119
	v_cvt_pk_bf16_f32 v119, v120, v121
	v_cvt_pk_bf16_f32 v120, v158, v159
	v_cvt_pk_bf16_f32 v121, v156, v157
	global_store_dwordx4 v[148:149], v[110:113], off
	global_store_dwordx4 v[148:149], v[118:121], off offset:256
	global_store_dwordx4 v[188:189], v[106:109], off
	v_and_b32_e32 v191, 0xffff0000, v168
	v_lshlrev_b32_e32 v110, 16, v171
	v_lshlrev_b32_e32 v106, 16, v169
	v_and_b32_e32 v107, 0xffff0000, v169
	v_lshlrev_b32_e32 v108, 16, v170
	v_and_b32_e32 v109, 0xffff0000, v170
	v_and_b32_e32 v111, 0xffff0000, v171
	v_pk_fma_f32 v[104:105], v[106:107], s[28:29], v[104:105] op_sel_hi:[1,0,1]
	v_pk_fma_f32 v[102:103], v[190:191], s[28:29], v[102:103] op_sel_hi:[1,0,1]
	v_pk_fma_f32 v[106:107], v[110:111], s[28:29], v[96:97] op_sel_hi:[1,0,1]
	v_pk_fma_f32 v[96:97], v[108:109], s[28:29], v[94:95] op_sel_hi:[1,0,1]
	v_cvt_pk_bf16_f32 v94, v102, v103
	v_cvt_pk_bf16_f32 v95, v104, v105
	v_cvt_pk_bf16_f32 v96, v96, v97
	v_cvt_pk_bf16_f32 v97, v106, v107
	global_store_dwordx4 v[188:189], v[94:97], off offset:256
	v_lshlrev_b32_e32 v102, 16, v174
	v_and_b32_e32 v103, 0xffff0000, v174
	v_lshlrev_b32_e32 v94, 16, v172
	v_and_b32_e32 v95, 0xffff0000, v172
	v_lshlrev_b32_e32 v96, 16, v173
	v_and_b32_e32 v97, 0xffff0000, v173
	v_lshlrev_b32_e32 v104, 16, v175
	v_and_b32_e32 v105, 0xffff0000, v175
	v_pk_fma_f32 v[94:95], v[94:95], s[28:29], v[98:99] op_sel_hi:[1,0,1]
	v_pk_fma_f32 v[96:97], v[96:97], s[28:29], v[100:101] op_sel_hi:[1,0,1]
	v_pk_fma_f32 v[98:99], v[104:105], s[28:29], v[92:93] op_sel_hi:[1,0,1]
	v_pk_fma_f32 v[92:93], v[102:103], s[28:29], v[90:91] op_sel_hi:[1,0,1]
	v_cvt_pk_bf16_f32 v90, v94, v95
	v_add_co_u32_e32 v94, vcc, s43, v148
	v_cvt_pk_bf16_f32 v91, v96, v97
	v_cvt_pk_bf16_f32 v92, v92, v93
	v_cvt_pk_bf16_f32 v93, v98, v99
	v_addc_co_u32_e32 v95, vcc, 0, v149, vcc
	global_store_dwordx4 v[94:95], v[90:93], off
	v_lshlrev_b32_e32 v96, 16, v178
	v_and_b32_e32 v97, 0xffff0000, v178
	v_lshlrev_b32_e32 v90, 16, v176
	v_and_b32_e32 v91, 0xffff0000, v176
	v_lshlrev_b32_e32 v92, 16, v177
	v_and_b32_e32 v93, 0xffff0000, v177
	v_lshlrev_b32_e32 v98, 16, v179
	v_and_b32_e32 v99, 0xffff0000, v179
	v_pk_fma_f32 v[88:89], v[92:93], s[28:29], v[88:89] op_sel_hi:[1,0,1]
	v_pk_fma_f32 v[86:87], v[90:91], s[28:29], v[86:87] op_sel_hi:[1,0,1]
	v_pk_fma_f32 v[90:91], v[98:99], s[28:29], v[80:81] op_sel_hi:[1,0,1]
	v_pk_fma_f32 v[80:81], v[96:97], s[28:29], v[78:79] op_sel_hi:[1,0,1]
	v_cvt_pk_bf16_f32 v78, v86, v87
	v_cvt_pk_bf16_f32 v79, v88, v89
	v_cvt_pk_bf16_f32 v80, v80, v81
	v_cvt_pk_bf16_f32 v81, v90, v91
	global_store_dwordx4 v[94:95], v[78:81], off offset:256
	v_lshlrev_b32_e32 v86, 16, v182
	v_and_b32_e32 v87, 0xffff0000, v182
	v_lshlrev_b32_e32 v78, 16, v180
	v_and_b32_e32 v79, 0xffff0000, v180
	v_lshlrev_b32_e32 v80, 16, v181
	v_and_b32_e32 v81, 0xffff0000, v181
	v_lshlrev_b32_e32 v88, 16, v183
	v_and_b32_e32 v89, 0xffff0000, v183
	v_pk_fma_f32 v[78:79], v[78:79], s[28:29], v[82:83] op_sel_hi:[1,0,1]
	v_pk_fma_f32 v[80:81], v[80:81], s[28:29], v[84:85] op_sel_hi:[1,0,1]
	v_pk_fma_f32 v[82:83], v[88:89], s[28:29], v[76:77] op_sel_hi:[1,0,1]
	v_pk_fma_f32 v[76:77], v[86:87], s[28:29], v[74:75] op_sel_hi:[1,0,1]
	v_cvt_pk_bf16_f32 v74, v78, v79
	v_add_co_u32_e32 v78, vcc, s48, v148
	v_cvt_pk_bf16_f32 v75, v80, v81
	v_cvt_pk_bf16_f32 v76, v76, v77
	v_cvt_pk_bf16_f32 v77, v82, v83
	v_addc_co_u32_e32 v79, vcc, 0, v149, vcc
	global_store_dwordx4 v[78:79], v[74:77], off
	v_lshlrev_b32_e32 v80, 16, v186
	v_and_b32_e32 v81, 0xffff0000, v186
	v_lshlrev_b32_e32 v74, 16, v184
	v_and_b32_e32 v75, 0xffff0000, v184
	v_lshlrev_b32_e32 v76, 16, v185
	v_and_b32_e32 v77, 0xffff0000, v185
	v_lshlrev_b32_e32 v82, 16, v187
	v_and_b32_e32 v83, 0xffff0000, v187
	v_pk_fma_f32 v[72:73], v[76:77], s[28:29], v[72:73] op_sel_hi:[1,0,1]
	v_pk_fma_f32 v[70:71], v[74:75], s[28:29], v[70:71] op_sel_hi:[1,0,1]
	v_pk_fma_f32 v[74:75], v[82:83], s[28:29], v[68:69] op_sel_hi:[1,0,1]
	v_pk_fma_f32 v[68:69], v[80:81], s[28:29], v[66:67] op_sel_hi:[1,0,1]
	v_cvt_pk_bf16_f32 v66, v70, v71
	v_cvt_pk_bf16_f32 v67, v72, v73
	v_cvt_pk_bf16_f32 v68, v68, v69
	v_cvt_pk_bf16_f32 v69, v74, v75
	global_store_dwordx4 v[78:79], v[66:69], off offset:256
	s_nop 1
	v_add_u32_e32 v66, 0x80, v155
	s_nop 0
	v_ashrrev_i32_e32 v67, 31, v66
	v_lshlrev_b64 v[66:67], 10, v[66:67]
	v_lshl_add_u64 v[66:67], v[66:67], 0, v[146:147]
	v_lshlrev_b64 v[98:99], 1, v[66:67]
	v_lshl_add_u64 v[90:91], s[10:11], 0, v[98:99]
	global_load_dwordx4 v[66:69], v[90:91], off
	global_load_dwordx4 v[70:73], v[90:91], off offset:256
	v_add_co_u32_e32 v78, vcc, s49, v90
	s_waitcnt vmcnt(0) lgkmcnt(0)
	v_lshlrev_b32_e32 v100, 16, v66
	v_addc_co_u32_e32 v79, vcc, 0, v91, vcc
	global_load_dwordx4 v[74:77], v[78:79], off
	s_nop 0
	global_load_dwordx4 v[78:81], v[78:79], off offset:256
	v_add_co_u32_e32 v86, vcc, s43, v90
	v_and_b32_e32 v101, 0xffff0000, v66
	s_nop 0
	v_addc_co_u32_e32 v87, vcc, 0, v91, vcc
	global_load_dwordx4 v[82:85], v[86:87], off
	s_nop 0
	global_load_dwordx4 v[86:89], v[86:87], off offset:256
	v_add_co_u32_e32 v94, vcc, s48, v90
	v_lshlrev_b32_e32 v66, 16, v67
	s_nop 0
	v_addc_co_u32_e32 v95, vcc, 0, v91, vcc
	global_load_dwordx4 v[90:93], v[94:95], off
	s_nop 0
	global_load_dwordx4 v[94:97], v[94:95], off offset:256
	v_and_b32_e32 v67, 0xffff0000, v67
	v_lshlrev_b32_e32 v102, 16, v68
	v_and_b32_e32 v103, 0xffff0000, v68
	v_lshlrev_b32_e32 v68, 16, v69
	v_and_b32_e32 v69, 0xffff0000, v69
	v_pk_fma_f32 v[64:65], v[66:67], s[28:29], v[64:65] op_sel_hi:[1,0,1]
	v_pk_fma_f32 v[62:63], v[100:101], s[28:29], v[62:63] op_sel_hi:[1,0,1]
	v_pk_fma_f32 v[66:67], v[68:69], s[28:29], v[60:61] op_sel_hi:[1,0,1]
	v_pk_fma_f32 v[60:61], v[102:103], s[28:29], v[58:59] op_sel_hi:[1,0,1]
	v_cvt_pk_bf16_f32 v58, v62, v63
	v_cvt_pk_bf16_f32 v59, v64, v65
	v_cvt_pk_bf16_f32 v60, v60, v61
	v_cvt_pk_bf16_f32 v61, v66, v67
	v_lshl_add_u64 v[62:63], s[12:13], 0, v[98:99]
	global_store_dwordx4 v[62:63], v[58:61], off
	v_lshlrev_b32_e32 v64, 16, v72
	v_and_b32_e32 v65, 0xffff0000, v72
	v_lshlrev_b32_e32 v58, 16, v70
	v_and_b32_e32 v59, 0xffff0000, v70
	v_lshlrev_b32_e32 v60, 16, v71
	v_and_b32_e32 v61, 0xffff0000, v71
	v_lshlrev_b32_e32 v66, 16, v73
	v_and_b32_e32 v67, 0xffff0000, v73
	v_pk_fma_f32 v[56:57], v[60:61], s[28:29], v[56:57] op_sel_hi:[1,0,1]
	v_pk_fma_f32 v[54:55], v[58:59], s[28:29], v[54:55] op_sel_hi:[1,0,1]
	v_pk_fma_f32 v[58:59], v[66:67], s[28:29], v[48:49] op_sel_hi:[1,0,1]
	v_pk_fma_f32 v[48:49], v[64:65], s[28:29], v[46:47] op_sel_hi:[1,0,1]
	v_cvt_pk_bf16_f32 v46, v54, v55
	v_cvt_pk_bf16_f32 v47, v56, v57
	v_cvt_pk_bf16_f32 v48, v48, v49
	v_cvt_pk_bf16_f32 v49, v58, v59
	global_store_dwordx4 v[62:63], v[46:49], off offset:256
	s_waitcnt vmcnt(0) lgkmcnt(0)
	v_lshlrev_b32_e32 v54, 16, v76
	v_lshlrev_b32_e32 v46, 16, v74
	v_and_b32_e32 v47, 0xffff0000, v74
	v_lshlrev_b32_e32 v48, 16, v75
	v_and_b32_e32 v49, 0xffff0000, v75
	v_and_b32_e32 v55, 0xffff0000, v76
	v_lshlrev_b32_e32 v56, 16, v77
	v_and_b32_e32 v57, 0xffff0000, v77
	v_pk_fma_f32 v[46:47], v[46:47], s[28:29], v[50:51] op_sel_hi:[1,0,1]
	v_pk_fma_f32 v[48:49], v[48:49], s[28:29], v[52:53] op_sel_hi:[1,0,1]
	v_pk_fma_f32 v[50:51], v[56:57], s[28:29], v[44:45] op_sel_hi:[1,0,1]
	v_pk_fma_f32 v[44:45], v[54:55], s[28:29], v[42:43] op_sel_hi:[1,0,1]
	v_cvt_pk_bf16_f32 v42, v46, v47
	v_add_co_u32_e32 v46, vcc, s49, v62
	v_cvt_pk_bf16_f32 v43, v48, v49
	v_cvt_pk_bf16_f32 v44, v44, v45
	v_cvt_pk_bf16_f32 v45, v50, v51
	v_addc_co_u32_e32 v47, vcc, 0, v63, vcc
	global_store_dwordx4 v[46:47], v[42:45], off
	v_lshlrev_b32_e32 v48, 16, v80
	v_and_b32_e32 v49, 0xffff0000, v80
	v_lshlrev_b32_e32 v42, 16, v78
	v_and_b32_e32 v43, 0xffff0000, v78
	v_lshlrev_b32_e32 v44, 16, v79
	v_and_b32_e32 v45, 0xffff0000, v79
	v_lshlrev_b32_e32 v50, 16, v81
	v_and_b32_e32 v51, 0xffff0000, v81
	v_pk_fma_f32 v[40:41], v[44:45], s[28:29], v[40:41] op_sel_hi:[1,0,1]
	v_pk_fma_f32 v[38:39], v[42:43], s[28:29], v[38:39] op_sel_hi:[1,0,1]
	v_pk_fma_f32 v[42:43], v[50:51], s[28:29], v[32:33] op_sel_hi:[1,0,1]
	v_pk_fma_f32 v[32:33], v[48:49], s[28:29], v[30:31] op_sel_hi:[1,0,1]
	v_cvt_pk_bf16_f32 v30, v38, v39
	v_cvt_pk_bf16_f32 v31, v40, v41
	v_cvt_pk_bf16_f32 v32, v32, v33
	v_cvt_pk_bf16_f32 v33, v42, v43
	global_store_dwordx4 v[46:47], v[30:33], off offset:256
	v_lshlrev_b32_e32 v38, 16, v84
	v_and_b32_e32 v39, 0xffff0000, v84
	v_lshlrev_b32_e32 v30, 16, v82
	v_and_b32_e32 v31, 0xffff0000, v82
	v_lshlrev_b32_e32 v32, 16, v83
	v_and_b32_e32 v33, 0xffff0000, v83
	v_lshlrev_b32_e32 v40, 16, v85
	v_and_b32_e32 v41, 0xffff0000, v85
	v_pk_fma_f32 v[30:31], v[30:31], s[28:29], v[34:35] op_sel_hi:[1,0,1]
	v_pk_fma_f32 v[32:33], v[32:33], s[28:29], v[36:37] op_sel_hi:[1,0,1]
	v_pk_fma_f32 v[34:35], v[40:41], s[28:29], v[28:29] op_sel_hi:[1,0,1]
	v_pk_fma_f32 v[28:29], v[38:39], s[28:29], v[26:27] op_sel_hi:[1,0,1]
	v_cvt_pk_bf16_f32 v26, v30, v31
	v_add_co_u32_e32 v30, vcc, s43, v62
	v_cvt_pk_bf16_f32 v27, v32, v33
	v_cvt_pk_bf16_f32 v28, v28, v29
	v_cvt_pk_bf16_f32 v29, v34, v35
	v_addc_co_u32_e32 v31, vcc, 0, v63, vcc
	global_store_dwordx4 v[30:31], v[26:29], off
	v_lshlrev_b32_e32 v32, 16, v88
	v_and_b32_e32 v33, 0xffff0000, v88
	v_lshlrev_b32_e32 v26, 16, v86
	v_and_b32_e32 v27, 0xffff0000, v86
	v_lshlrev_b32_e32 v28, 16, v87
	v_and_b32_e32 v29, 0xffff0000, v87
	v_lshlrev_b32_e32 v34, 16, v89
	v_and_b32_e32 v35, 0xffff0000, v89
	v_pk_fma_f32 v[24:25], v[28:29], s[28:29], v[24:25] op_sel_hi:[1,0,1]
	v_pk_fma_f32 v[22:23], v[26:27], s[28:29], v[22:23] op_sel_hi:[1,0,1]
	v_pk_fma_f32 v[26:27], v[34:35], s[28:29], v[16:17] op_sel_hi:[1,0,1]
	v_pk_fma_f32 v[16:17], v[32:33], s[28:29], v[14:15] op_sel_hi:[1,0,1]
	v_cvt_pk_bf16_f32 v14, v22, v23
	v_cvt_pk_bf16_f32 v15, v24, v25
	v_cvt_pk_bf16_f32 v16, v16, v17
	v_cvt_pk_bf16_f32 v17, v26, v27
	global_store_dwordx4 v[30:31], v[14:17], off offset:256
	v_lshlrev_b32_e32 v22, 16, v92
	v_and_b32_e32 v23, 0xffff0000, v92
	v_lshlrev_b32_e32 v14, 16, v90
	v_and_b32_e32 v15, 0xffff0000, v90
	v_lshlrev_b32_e32 v16, 16, v91
	v_and_b32_e32 v17, 0xffff0000, v91
	v_lshlrev_b32_e32 v24, 16, v93
	v_and_b32_e32 v25, 0xffff0000, v93
	v_pk_fma_f32 v[14:15], v[14:15], s[28:29], v[18:19] op_sel_hi:[1,0,1]
	v_pk_fma_f32 v[16:17], v[16:17], s[28:29], v[20:21] op_sel_hi:[1,0,1]
	v_pk_fma_f32 v[18:19], v[24:25], s[28:29], v[12:13] op_sel_hi:[1,0,1]
	v_pk_fma_f32 v[12:13], v[22:23], s[28:29], v[10:11] op_sel_hi:[1,0,1]
	v_cvt_pk_bf16_f32 v10, v14, v15
	v_add_co_u32_e32 v14, vcc, s48, v62
	v_cvt_pk_bf16_f32 v11, v16, v17
	v_cvt_pk_bf16_f32 v12, v12, v13
	v_cvt_pk_bf16_f32 v13, v18, v19
	v_addc_co_u32_e32 v15, vcc, 0, v63, vcc
	global_store_dwordx4 v[14:15], v[10:13], off
	v_lshlrev_b32_e32 v16, 16, v96
	v_and_b32_e32 v17, 0xffff0000, v96
	v_lshlrev_b32_e32 v10, 16, v94
	v_and_b32_e32 v11, 0xffff0000, v94
	v_lshlrev_b32_e32 v12, 16, v95
	v_and_b32_e32 v13, 0xffff0000, v95
	v_lshlrev_b32_e32 v18, 16, v97
	v_and_b32_e32 v19, 0xffff0000, v97
	v_pk_fma_f32 v[8:9], v[12:13], s[28:29], v[8:9] op_sel_hi:[1,0,1]
	v_pk_fma_f32 v[6:7], v[10:11], s[28:29], v[6:7] op_sel_hi:[1,0,1]
	v_pk_fma_f32 v[10:11], v[18:19], s[28:29], v[4:5] op_sel_hi:[1,0,1]
	v_pk_fma_f32 v[4:5], v[16:17], s[28:29], v[2:3] op_sel_hi:[1,0,1]
	v_cvt_pk_bf16_f32 v2, v6, v7
	v_cvt_pk_bf16_f32 v3, v8, v9
	v_cvt_pk_bf16_f32 v4, v4, v5
	v_cvt_pk_bf16_f32 v5, v10, v11
	s_and_b64 vcc, exec, s[30:31]
	global_store_dwordx4 v[14:15], v[2:5], off offset:256
	s_cbranch_vccz .LBB0_433
	s_waitcnt vmcnt(0)
	s_cmpk_gt_u32 s4, 0xff
	s_cbranch_scc1 .LBB0_438
	s_barrier

.LBB0_688:
	s_add_u32 s10, s34, 0x100
	s_addc_u32 s11, s35, 0
	s_add_u32 s30, s29, s34
	s_addc_u32 s31, s55, s35
	s_cmpk_eq_i32 s34, 0x300
	s_cselect_b64 vcc, -1, 0
	s_and_b64 s[0:1], vcc, exec
	s_cselect_b32 s1, 0, s10
	s_cselect_b32 s0, 0, s11
	s_cselect_b32 s30, s27, s30
	s_cselect_b32 s31, s25, s31
	s_add_u32 s36, s14, s1
	s_addc_u32 s37, s15, s0
	s_add_i32 s1, 0, 0x10000
	v_add_u32_e32 v14, s1, v197
	ds_read_b128 v[2:5], v14
	ds_read_b128 v[6:9], v14 offset:1024
	ds_read_b128 v[10:13], v14 offset:2048
	ds_read_b128 v[14:17], v14 offset:3072
	v_cndmask_b32_e32 v162, v168, v171, vcc
	v_cndmask_b32_e32 v184, v170, v198, vcc
	v_cndmask_b32_e32 v175, v172, v199, vcc
	v_cndmask_b32_e32 v173, v174, v200, vcc
	v_lshl_add_u64 v[18:19], v[178:179], 0, s[34:35]
	s_add_i32 m0, s45, 0xc000
	ds_read_b128 v[202:205], v169
	ds_read_b128 v[206:209], v169 offset:1024
	ds_read_b128 v[210:213], v169 offset:2048
	ds_read_b128 v[214:217], v169 offset:3072
	ds_read_b128 v[218:221], v169 offset:4096
	ds_read_b128 v[222:225], v169 offset:5120
	ds_read_b128 v[226:229], v169 offset:6144
	ds_read_b128 v[230:233], v169 offset:7168
	global_load_lds_dwordx4 v[18:19], off
	v_lshl_add_u64 v[18:19], v[176:177], 0, s[34:35]
	s_add_i32 m0, s45, 0xe000
	s_nop 0
	global_load_lds_dwordx4 v[18:19], off
	s_waitcnt lgkmcnt(8)
	s_waitcnt vmcnt(10)
	s_barrier
	s_waitcnt lgkmcnt(0)
	v_mfma_scale_f32_16x16x128_f8f6f4 v[158:161], v[2:9], v[202:209], v[158:161], v188, v188 op_sel_hi:[0,0,0]
	v_mfma_scale_f32_16x16x128_f8f6f4 v[150:153], v[10:17], v[202:209], v[150:153], v188, v188 op_sel_hi:[0,0,0]
	v_mfma_scale_f32_16x16x128_f8f6f4 v[142:145], v[2:9], v[210:217], v[142:145], v188, v188 op_sel_hi:[0,0,0]
	v_mfma_scale_f32_16x16x128_f8f6f4 v[134:137], v[10:17], v[210:217], v[134:137], v188, v188 op_sel_hi:[0,0,0]
	v_mfma_scale_f32_16x16x128_f8f6f4 v[126:129], v[2:9], v[218:225], v[126:129], v188, v188 op_sel_hi:[0,0,0]
	v_mfma_scale_f32_16x16x128_f8f6f4 v[118:121], v[10:17], v[218:225], v[118:121], v188, v188 op_sel_hi:[0,0,0]
	v_mfma_scale_f32_16x16x128_f8f6f4 v[110:113], v[2:9], v[226:233], v[110:113], v188, v188 op_sel_hi:[0,0,0]
	v_mfma_scale_f32_16x16x128_f8f6f4 v[102:105], v[10:17], v[226:233], v[102:105], v188, v188 op_sel_hi:[0,0,0]
	s_barrier
	s_add_i32 s0, 0, 0x14000
	s_add_i32 s1, s1, s43
	v_add_u32_e32 v30, s0, v197
	v_lshl_add_u64 v[180:181], s[30:31], 0, v[164:165]
	s_mov_b32 m0, s1
	ds_read_b128 v[18:21], v30
	ds_read_b128 v[22:25], v30 offset:1024
	ds_read_b128 v[26:29], v30 offset:2048
	ds_read_b128 v[30:33], v30 offset:3072
	global_load_lds_dwordx4 v[180:181], off
	v_lshl_add_u64 v[182:183], s[30:31], 0, v[166:167]
	s_add_i32 m0, s1, 0x2000
	s_nop 0
	global_load_lds_dwordx4 v[182:183], off
	s_waitcnt vmcnt(10)
	s_barrier
	s_waitcnt lgkmcnt(0)
	v_mfma_scale_f32_16x16x128_f8f6f4 v[154:157], v[18:25], v[202:209], v[154:157], v188, v188 op_sel_hi:[0,0,0]
	v_mfma_scale_f32_16x16x128_f8f6f4 v[146:149], v[26:33], v[202:209], v[146:149], v188, v188 op_sel_hi:[0,0,0]
	v_mfma_scale_f32_16x16x128_f8f6f4 v[138:141], v[18:25], v[210:217], v[138:141], v188, v188 op_sel_hi:[0,0,0]
	v_mfma_scale_f32_16x16x128_f8f6f4 v[130:133], v[26:33], v[210:217], v[130:133], v188, v188 op_sel_hi:[0,0,0]
	v_mfma_scale_f32_16x16x128_f8f6f4 v[122:125], v[18:25], v[218:225], v[122:125], v188, v188 op_sel_hi:[0,0,0]
	v_mfma_scale_f32_16x16x128_f8f6f4 v[114:117], v[26:33], v[218:225], v[114:117], v188, v188 op_sel_hi:[0,0,0]
	v_mfma_scale_f32_16x16x128_f8f6f4 v[106:109], v[18:25], v[226:233], v[106:109], v188, v188 op_sel_hi:[0,0,0]
	v_mfma_scale_f32_16x16x128_f8f6f4 v[98:101], v[26:33], v[226:233], v[98:101], v188, v188 op_sel_hi:[0,0,0]
	s_mov_b32 m0, s45
	s_barrier
	ds_read_b128 v[202:205], v169 offset:16384
	ds_read_b128 v[206:209], v169 offset:17408
	ds_read_b128 v[210:213], v169 offset:18432
	ds_read_b128 v[214:217], v169 offset:19456
	ds_read_b128 v[218:221], v169 offset:20480
	ds_read_b128 v[222:225], v169 offset:21504
	ds_read_b128 v[226:229], v169 offset:22528
	ds_read_b128 v[230:233], v169 offset:23552
	global_load_lds_dwordx4 v162, s[36:37]
	s_mov_b32 m0, s46
	v_mov_b32_e32 v185, v163
	global_load_lds_dwordx4 v184, s[36:37]
	s_waitcnt vmcnt(10)
	s_barrier
	s_waitcnt lgkmcnt(0)
	v_lshl_add_u64 v[186:187], s[36:37], 0, v[162:163]
	v_lshl_add_u64 v[184:185], s[36:37], 0, v[184:185]
	s_waitcnt lgkmcnt(0)
	v_mfma_scale_f32_16x16x128_f8f6f4 v[94:97], v[2:9], v[202:209], v[94:97], v188, v188 op_sel_hi:[0,0,0]
	v_mfma_scale_f32_16x16x128_f8f6f4 v[86:89], v[10:17], v[202:209], v[86:89], v188, v188 op_sel_hi:[0,0,0]
	v_mfma_scale_f32_16x16x128_f8f6f4 v[78:81], v[2:9], v[210:217], v[78:81], v188, v188 op_sel_hi:[0,0,0]
	v_mfma_scale_f32_16x16x128_f8f6f4 v[70:73], v[10:17], v[210:217], v[70:73], v188, v188 op_sel_hi:[0,0,0]
	v_mfma_scale_f32_16x16x128_f8f6f4 v[62:65], v[2:9], v[218:225], v[62:65], v188, v188 op_sel_hi:[0,0,0]
	v_mfma_scale_f32_16x16x128_f8f6f4 v[54:57], v[10:17], v[218:225], v[54:57], v188, v188 op_sel_hi:[0,0,0]
	v_mfma_scale_f32_16x16x128_f8f6f4 v[46:49], v[2:9], v[226:233], v[46:49], v188, v188 op_sel_hi:[0,0,0]
	v_mfma_scale_f32_16x16x128_f8f6f4 v[38:41], v[10:17], v[226:233], v[38:41], v188, v188 op_sel_hi:[0,0,0]
	s_barrier
	s_add_u32 s34, s30, 0x20000
	s_addc_u32 s35, s31, 0
	s_add_i32 s0, s0, s43
	v_lshl_add_u64 v[2:3], s[34:35], 0, v[164:165]
	s_mov_b32 m0, s0
	s_nop 0
	global_load_lds_dwordx4 v[2:3], off
	v_lshl_add_u64 v[2:3], s[34:35], 0, v[166:167]
	s_add_i32 m0, s0, 0x2000
	s_nop 0
	global_load_lds_dwordx4 v[2:3], off
	s_waitcnt vmcnt(10)
	s_barrier
	v_mfma_scale_f32_16x16x128_f8f6f4 v[90:93], v[18:25], v[202:209], v[90:93], v188, v188 op_sel_hi:[0,0,0]
	v_mfma_scale_f32_16x16x128_f8f6f4 v[82:85], v[26:33], v[202:209], v[82:85], v188, v188 op_sel_hi:[0,0,0]
	v_mfma_scale_f32_16x16x128_f8f6f4 v[74:77], v[18:25], v[210:217], v[74:77], v188, v188 op_sel_hi:[0,0,0]
	v_mfma_scale_f32_16x16x128_f8f6f4 v[66:69], v[26:33], v[210:217], v[66:69], v188, v188 op_sel_hi:[0,0,0]
	v_mfma_scale_f32_16x16x128_f8f6f4 v[58:61], v[18:25], v[218:225], v[58:61], v188, v188 op_sel_hi:[0,0,0]
	v_mfma_scale_f32_16x16x128_f8f6f4 v[50:53], v[26:33], v[218:225], v[50:53], v188, v188 op_sel_hi:[0,0,0]
	v_mfma_scale_f32_16x16x128_f8f6f4 v[42:45], v[18:25], v[226:233], v[42:45], v188, v188 op_sel_hi:[0,0,0]
	v_mfma_scale_f32_16x16x128_f8f6f4 v[34:37], v[26:33], v[226:233], v[34:37], v188, v188 op_sel_hi:[0,0,0]
	s_add_i32 s0, 0, 0x18000
	v_add_u32_e32 v14, s0, v197
	s_barrier
	ds_read_b128 v[2:5], v14
	ds_read_b128 v[6:9], v14 offset:1024
	ds_read_b128 v[10:13], v14 offset:2048
	ds_read_b128 v[14:17], v14 offset:3072
	s_mov_b32 m0, s47
	ds_read_b128 v[18:21], v169 offset:32768
	ds_read_b128 v[22:25], v169 offset:33792
	ds_read_b128 v[26:29], v169 offset:34816
	ds_read_b128 v[30:33], v169 offset:35840
	ds_read_b128 v[202:205], v169 offset:36864
	ds_read_b128 v[206:209], v169 offset:37888
	ds_read_b128 v[210:213], v169 offset:38912
	ds_read_b128 v[214:217], v169 offset:39936
	global_load_lds_dwordx4 v175, s[36:37]
	s_mov_b32 m0, s48
	s_nop 0
	global_load_lds_dwordx4 v173, s[36:37]
	s_waitcnt lgkmcnt(8)
	s_waitcnt vmcnt(10)
	s_barrier
	s_waitcnt lgkmcnt(0)
	v_mfma_scale_f32_16x16x128_f8f6f4 v[158:161], v[2:9], v[18:25], v[158:161], v188, v188 op_sel_hi:[0,0,0]
	v_mfma_scale_f32_16x16x128_f8f6f4 v[150:153], v[10:17], v[18:25], v[150:153], v188, v188 op_sel_hi:[0,0,0]
	v_mfma_scale_f32_16x16x128_f8f6f4 v[142:145], v[2:9], v[26:33], v[142:145], v188, v188 op_sel_hi:[0,0,0]
	v_mfma_scale_f32_16x16x128_f8f6f4 v[134:137], v[10:17], v[26:33], v[134:137], v188, v188 op_sel_hi:[0,0,0]
	v_mfma_scale_f32_16x16x128_f8f6f4 v[126:129], v[2:9], v[202:209], v[126:129], v188, v188 op_sel_hi:[0,0,0]
	v_mfma_scale_f32_16x16x128_f8f6f4 v[118:121], v[10:17], v[202:209], v[118:121], v188, v188 op_sel_hi:[0,0,0]
	v_mfma_scale_f32_16x16x128_f8f6f4 v[110:113], v[2:9], v[210:217], v[110:113], v188, v188 op_sel_hi:[0,0,0]
	v_mfma_scale_f32_16x16x128_f8f6f4 v[102:105], v[10:17], v[210:217], v[102:105], v188, v188 op_sel_hi:[0,0,0]
	s_barrier
	s_add_i32 s34, 0, 0x1c000
	s_add_i32 s0, s0, s43
	v_add_u32_e32 v162, s34, v197
	v_lshl_add_u64 v[180:181], v[180:181], 0, s[20:21]
	s_mov_b32 m0, s0
	ds_read_b128 v[218:221], v162
	ds_read_b128 v[222:225], v162 offset:1024
	ds_read_b128 v[226:229], v162 offset:2048
	ds_read_b128 v[230:233], v162 offset:3072
	global_load_lds_dwordx4 v[180:181], off
	v_lshl_add_u64 v[180:181], v[182:183], 0, s[20:21]
	s_add_i32 m0, s0, 0x2000
	s_nop 0
	global_load_lds_dwordx4 v[180:181], off
	s_waitcnt vmcnt(10)
	s_barrier
	s_waitcnt lgkmcnt(0)
	v_mfma_scale_f32_16x16x128_f8f6f4 v[154:157], v[218:225], v[18:25], v[154:157], v188, v188 op_sel_hi:[0,0,0]
	v_mfma_scale_f32_16x16x128_f8f6f4 v[146:149], v[226:233], v[18:25], v[146:149], v188, v188 op_sel_hi:[0,0,0]
	v_mfma_scale_f32_16x16x128_f8f6f4 v[138:141], v[218:225], v[26:33], v[138:141], v188, v188 op_sel_hi:[0,0,0]
	v_mfma_scale_f32_16x16x128_f8f6f4 v[130:133], v[226:233], v[26:33], v[130:133], v188, v188 op_sel_hi:[0,0,0]
	v_mfma_scale_f32_16x16x128_f8f6f4 v[122:125], v[218:225], v[202:209], v[122:125], v188, v188 op_sel_hi:[0,0,0]
	v_mfma_scale_f32_16x16x128_f8f6f4 v[114:117], v[226:233], v[202:209], v[114:117], v188, v188 op_sel_hi:[0,0,0]
	v_mfma_scale_f32_16x16x128_f8f6f4 v[106:109], v[218:225], v[210:217], v[106:109], v188, v188 op_sel_hi:[0,0,0]
	v_mfma_scale_f32_16x16x128_f8f6f4 v[98:101], v[226:233], v[210:217], v[98:101], v188, v188 op_sel_hi:[0,0,0]
	s_mov_b32 m0, s51
	v_lshl_add_u64 v[180:181], v[186:187], 0, s[20:21]
	s_barrier
	ds_read_b128 v[18:21], v169 offset:49152
	ds_read_b128 v[22:25], v169 offset:50176
	ds_read_b128 v[26:29], v169 offset:51200
	ds_read_b128 v[30:33], v169 offset:52224
	ds_read_b128 v[202:205], v169 offset:53248
	ds_read_b128 v[206:209], v169 offset:54272
	ds_read_b128 v[210:213], v169 offset:55296
	ds_read_b128 v[214:217], v169 offset:56320
	global_load_lds_dwordx4 v[180:181], off
	v_lshl_add_u64 v[180:181], v[184:185], 0, s[20:21]
	s_mov_b32 m0, s52
	s_nop 0
	global_load_lds_dwordx4 v[180:181], off
	s_waitcnt vmcnt(10)
	s_barrier
	s_waitcnt lgkmcnt(0)
	v_mfma_scale_f32_16x16x128_f8f6f4 v[94:97], v[2:9], v[18:25], v[94:97], v188, v188 op_sel_hi:[0,0,0]
	v_mfma_scale_f32_16x16x128_f8f6f4 v[86:89], v[10:17], v[18:25], v[86:89], v188, v188 op_sel_hi:[0,0,0]
	v_mfma_scale_f32_16x16x128_f8f6f4 v[78:81], v[2:9], v[26:33], v[78:81], v188, v188 op_sel_hi:[0,0,0]
	v_mfma_scale_f32_16x16x128_f8f6f4 v[70:73], v[10:17], v[26:33], v[70:73], v188, v188 op_sel_hi:[0,0,0]
	v_mfma_scale_f32_16x16x128_f8f6f4 v[62:65], v[2:9], v[202:209], v[62:65], v188, v188 op_sel_hi:[0,0,0]
	v_mfma_scale_f32_16x16x128_f8f6f4 v[54:57], v[10:17], v[202:209], v[54:57], v188, v188 op_sel_hi:[0,0,0]
	v_mfma_scale_f32_16x16x128_f8f6f4 v[46:49], v[2:9], v[210:217], v[46:49], v188, v188 op_sel_hi:[0,0,0]
	v_mfma_scale_f32_16x16x128_f8f6f4 v[38:41], v[10:17], v[210:217], v[38:41], v188, v188 op_sel_hi:[0,0,0]
	s_barrier
	s_add_u32 s0, s30, 0x20080
	s_addc_u32 s1, s31, 0
	s_add_i32 s30, s34, s43
	v_lshl_add_u64 v[2:3], s[0:1], 0, v[164:165]
	s_mov_b32 m0, s30
	s_nop 0
	global_load_lds_dwordx4 v[2:3], off
	v_lshl_add_u64 v[2:3], s[0:1], 0, v[166:167]
	s_add_i32 m0, s30, 0x2000
	s_nop 0
	global_load_lds_dwordx4 v[2:3], off
	s_waitcnt vmcnt(10)
	s_barrier
	v_mfma_scale_f32_16x16x128_f8f6f4 v[90:93], v[218:225], v[18:25], v[90:93], v188, v188 op_sel_hi:[0,0,0]
	v_mfma_scale_f32_16x16x128_f8f6f4 v[82:85], v[226:233], v[18:25], v[82:85], v188, v188 op_sel_hi:[0,0,0]
	v_mfma_scale_f32_16x16x128_f8f6f4 v[74:77], v[218:225], v[26:33], v[74:77], v188, v188 op_sel_hi:[0,0,0]
	v_mfma_scale_f32_16x16x128_f8f6f4 v[66:69], v[226:233], v[26:33], v[66:69], v188, v188 op_sel_hi:[0,0,0]
	v_mfma_scale_f32_16x16x128_f8f6f4 v[58:61], v[218:225], v[202:209], v[58:61], v188, v188 op_sel_hi:[0,0,0]
	v_mfma_scale_f32_16x16x128_f8f6f4 v[50:53], v[226:233], v[202:209], v[50:53], v188, v188 op_sel_hi:[0,0,0]
	v_mfma_scale_f32_16x16x128_f8f6f4 v[42:45], v[218:225], v[210:217], v[42:45], v188, v188 op_sel_hi:[0,0,0]
	v_mfma_scale_f32_16x16x128_f8f6f4 v[34:37], v[226:233], v[210:217], v[34:37], v188, v188 op_sel_hi:[0,0,0]
	s_add_i32 s56, s56, 2
	s_cmp_gt_u32 s56, 5
	s_mov_b64 s[34:35], s[10:11]
	s_barrier
	s_cbranch_scc0 .LBB0_688
	v_mul_f32_e32 v5, 0x3c800000, v158
	v_mul_f32_e32 v6, 0xbfb8aa3b, v5
	v_exp_f32_e32 v6, v6
	s_ashr_i32 s29, s28, 31
	s_ashr_i32 s27, s26, 31
	s_lshl_b64 s[10:11], s[28:29], 18
	v_add_f32_e32 v6, 1.0, v6
	v_rcp_f32_e32 v6, v6
	s_lshl_b64 s[26:27], s[26:27], 15
	v_mov_b32_e32 v3, v195
	s_add_u32 s0, s6, s10
	v_mul_f32_e32 v5, v5, v6
	v_mul_f32_e32 v6, 0x3c800000, v159
	v_mul_f32_e32 v7, 0xbfb8aa3b, v6
	v_exp_f32_e32 v7, v7
	v_mul_f32_e32 v5, v5, v154
	v_mul_f32_e32 v5, 0x3e000000, v5
	v_med3_f32 v5, v5, s40, v190
	v_add_f32_e32 v7, 1.0, v7
	v_rcp_f32_e32 v7, v7
	s_nop 15
	s_nop 15
	v_mov_b32_e32 v2, v196
	v_mul_f32_e32 v6, v6, v7
	v_mul_f32_e32 v7, 0x3c800000, v160
	v_mul_f32_e32 v8, 0xbfb8aa3b, v7
	v_exp_f32_e32 v8, v8
	v_mul_f32_e32 v6, v6, v155
	v_mul_f32_e32 v6, 0x3e000000, v6
	v_add_u32_e32 v4, s49, v3
	v_add_f32_e32 v8, 1.0, v8
	v_rcp_f32_e32 v8, v8
	s_addc_u32 s1, s7, s11
	s_add_u32 s10, s0, s26
	v_mul_f32_e32 v7, v7, v8
	v_mul_f32_e32 v8, 0x3c800000, v161
	v_mul_f32_e32 v9, 0xbfb8aa3b, v8
	v_exp_f32_e32 v9, v9
	v_mul_f32_e32 v7, v7, v156
	v_mul_f32_e32 v7, 0x3e000000, v7
	v_lshl_add_u32 v2, v2, 3, s50
	v_add_f32_e32 v9, 1.0, v9
	v_rcp_f32_e32 v9, v9
	s_addc_u32 s11, s1, s27
	v_ashrrev_i32_e32 v3, 31, v2
	s_and_b64 vcc, exec, s[8:9]
	v_mul_f32_e32 v8, v8, v9
	v_mul_f32_e32 v9, 0x3c800000, v150
	v_mul_f32_e32 v10, 0xbfb8aa3b, v9
	v_exp_f32_e32 v10, v10
	v_mul_f32_e32 v8, v8, v157
	v_mul_f32_e32 v8, 0x3e000000, v8
	v_mov_b32_e32 v174, v200
	v_add_f32_e32 v10, 1.0, v10
	v_rcp_f32_e32 v10, v10
	v_mov_b32_e32 v172, v199
	v_mov_b32_e32 v170, v198
	v_mov_b32_e32 v168, v171
	v_mul_f32_e32 v9, v9, v10
	v_mul_f32_e32 v10, 0x3c800000, v151
	v_mul_f32_e32 v11, 0xbfb8aa3b, v10
	v_exp_f32_e32 v11, v11
	v_mul_f32_e32 v9, v9, v146
	v_mul_f32_e32 v9, 0x3e000000, v9
	s_mov_b32 s26, s24
	v_add_f32_e32 v11, 1.0, v11
	v_rcp_f32_e32 v11, v11
	s_mov_b32 s28, s54
	s_mov_b64 s[30:31], s[12:13]
	v_mul_f32_e32 v10, v10, v11
	v_mul_f32_e32 v11, 0x3c800000, v152
	v_mul_f32_e32 v12, 0xbfb8aa3b, v11
	v_exp_f32_e32 v12, v12
	v_mul_f32_e32 v10, v10, v147
	v_mul_f32_e32 v10, 0x3e000000, v10
	v_add_f32_e32 v12, 1.0, v12
	v_rcp_f32_e32 v12, v12
	s_nop 0
	v_mul_f32_e32 v11, v11, v12
	v_mul_f32_e32 v12, 0x3c800000, v153
	v_mul_f32_e32 v13, 0xbfb8aa3b, v12
	v_exp_f32_e32 v13, v13
	v_mul_f32_e32 v11, v11, v148
	v_mul_f32_e32 v11, 0x3e000000, v11
	v_add_f32_e32 v13, 1.0, v13
	v_rcp_f32_e32 v13, v13
	s_nop 0
	v_mul_f32_e32 v12, v12, v13
	v_med3_f32 v13, v6, s40, v190
	v_mov_b32_e32 v6, v163
	v_cvt_pk_fp8_f32 v6, v5, v13
	v_med3_f32 v5, v7, s40, v190
	v_med3_f32 v7, v8, s40, v190
	v_med3_f32 v8, v10, s40, v190
	v_cvt_pk_fp8_f32 v6, v5, v7 op_sel:[0,0,1]
	v_med3_f32 v5, v9, s40, v190
	v_mov_b32_e32 v7, v163
	v_cvt_pk_fp8_f32 v7, v5, v8
	v_mul_f32_e32 v12, v12, v149
	v_mul_f32_e32 v12, 0x3e000000, v12
	v_med3_f32 v5, v11, s40, v190
	v_med3_f32 v8, v12, s40, v190
	v_cvt_pk_fp8_f32 v7, v5, v8 op_sel:[0,0,1]
	v_ashrrev_i32_e32 v5, 31, v4
	v_lshlrev_b64 v[8:9], 7, v[4:5]
	v_lshl_add_u64 v[8:9], s[10:11], 0, v[8:9]
	v_lshl_add_u64 v[8:9], v[8:9], 0, v[2:3]
	v_mul_f32_e32 v5, 0x3c800000, v142
	global_store_dwordx2 v[8:9], v[6:7], off
	v_mul_f32_e32 v6, 0xbfb8aa3b, v5
	v_exp_f32_e32 v6, v6
	s_nop 0
	v_add_f32_e32 v6, 1.0, v6
	v_rcp_f32_e32 v6, v6
	s_nop 0
	v_mul_f32_e32 v5, v5, v6
	v_mul_f32_e32 v6, 0x3c800000, v143
	v_mul_f32_e32 v7, 0xbfb8aa3b, v6
	v_exp_f32_e32 v7, v7
	v_mul_f32_e32 v5, v5, v138
	v_mul_f32_e32 v5, 0x3e000000, v5
	v_med3_f32 v5, v5, s40, v190
	v_add_f32_e32 v7, 1.0, v7
	v_rcp_f32_e32 v7, v7
	s_nop 0
	v_mul_f32_e32 v6, v6, v7
	v_mul_f32_e32 v6, v6, v139
	v_mul_f32_e32 v7, 0x3e000000, v6
	v_mul_f32_e32 v6, 0x3c800000, v144
	v_mul_f32_e32 v8, 0xbfb8aa3b, v6
	v_exp_f32_e32 v8, v8
	v_med3_f32 v7, v7, s40, v190
	v_add_f32_e32 v8, 1.0, v8
	v_rcp_f32_e32 v8, v8
	s_nop 0
	v_mul_f32_e32 v6, v6, v8
	v_mul_f32_e32 v6, v6, v140
	v_mul_f32_e32 v9, 0x3e000000, v6
	v_mul_f32_e32 v6, 0x3c800000, v145
	v_mul_f32_e32 v8, 0xbfb8aa3b, v6
	v_exp_f32_e32 v8, v8
	s_nop 0
	v_add_f32_e32 v8, 1.0, v8
	v_rcp_f32_e32 v8, v8
	s_nop 0
	v_mul_f32_e32 v6, v6, v8
	v_mul_f32_e32 v6, v6, v141
	v_mul_f32_e32 v10, 0x3e000000, v6
	v_mul_f32_e32 v6, 0x3c800000, v134
	v_mul_f32_e32 v8, 0xbfb8aa3b, v6
	v_exp_f32_e32 v8, v8
	s_nop 0
	v_add_f32_e32 v8, 1.0, v8
	v_rcp_f32_e32 v8, v8
	s_nop 0
	v_mul_f32_e32 v6, v6, v8
	v_mul_f32_e32 v6, v6, v130
	v_mul_f32_e32 v11, 0x3e000000, v6
	v_mul_f32_e32 v6, 0x3c800000, v135
	v_mul_f32_e32 v8, 0xbfb8aa3b, v6
	v_exp_f32_e32 v8, v8
	s_nop 0
	v_add_f32_e32 v8, 1.0, v8
	v_rcp_f32_e32 v8, v8
	s_nop 0
	v_mul_f32_e32 v6, v6, v8
	v_mul_f32_e32 v6, v6, v131
	v_mul_f32_e32 v12, 0x3e000000, v6
	v_mul_f32_e32 v6, 0x3c800000, v136
	v_mul_f32_e32 v8, 0xbfb8aa3b, v6
	v_exp_f32_e32 v8, v8
	s_nop 0
	v_add_f32_e32 v8, 1.0, v8
	v_rcp_f32_e32 v8, v8
	s_nop 0
	v_mul_f32_e32 v6, v6, v8
	v_mul_f32_e32 v6, v6, v132
	v_mul_f32_e32 v13, 0x3e000000, v6
	v_mul_f32_e32 v6, 0x3c800000, v137
	v_mul_f32_e32 v8, 0xbfb8aa3b, v6
	v_exp_f32_e32 v8, v8
	s_nop 0
	v_add_f32_e32 v8, 1.0, v8
	v_rcp_f32_e32 v8, v8
	s_nop 0
	v_mul_f32_e32 v6, v6, v8
	v_mov_b32_e32 v8, v163
	v_cvt_pk_fp8_f32 v8, v5, v7
	v_med3_f32 v5, v9, s40, v190
	v_med3_f32 v7, v10, s40, v190
	v_mov_b32_e32 v9, v163
	v_cvt_pk_fp8_f32 v8, v5, v7 op_sel:[0,0,1]
	v_med3_f32 v5, v11, s40, v190
	v_med3_f32 v7, v12, s40, v190
	v_cvt_pk_fp8_f32 v9, v5, v7
	v_mul_f32_e32 v6, v6, v133
	v_mul_f32_e32 v14, 0x3e000000, v6
	v_add_u32_e32 v6, 16, v4
	v_med3_f32 v5, v13, s40, v190
	v_med3_f32 v7, v14, s40, v190
	v_cvt_pk_fp8_f32 v9, v5, v7 op_sel:[0,0,1]
	v_ashrrev_i32_e32 v7, 31, v6
	v_lshlrev_b64 v[6:7], 7, v[6:7]
	v_lshl_add_u64 v[6:7], s[10:11], 0, v[6:7]
	v_lshl_add_u64 v[6:7], v[6:7], 0, v[2:3]
	v_mul_f32_e32 v5, 0x3c800000, v126
	global_store_dwordx2 v[6:7], v[8:9], off
	v_mul_f32_e32 v6, 0xbfb8aa3b, v5
	v_exp_f32_e32 v6, v6
	s_nop 0
	v_add_f32_e32 v6, 1.0, v6
	v_rcp_f32_e32 v6, v6
	s_nop 0
	v_mul_f32_e32 v5, v5, v6
	v_mul_f32_e32 v6, 0x3c800000, v127
	v_mul_f32_e32 v7, 0xbfb8aa3b, v6
	v_exp_f32_e32 v7, v7
	v_mul_f32_e32 v5, v5, v122
	v_mul_f32_e32 v5, 0x3e000000, v5
	v_med3_f32 v5, v5, s40, v190
	v_add_f32_e32 v7, 1.0, v7
	v_rcp_f32_e32 v7, v7
	s_nop 0
	v_mul_f32_e32 v6, v6, v7
	v_mul_f32_e32 v6, v6, v123
	v_mul_f32_e32 v7, 0x3e000000, v6
	v_mul_f32_e32 v6, 0x3c800000, v128
	v_mul_f32_e32 v8, 0xbfb8aa3b, v6
	v_exp_f32_e32 v8, v8
	v_med3_f32 v7, v7, s40, v190
	v_add_f32_e32 v8, 1.0, v8
	v_rcp_f32_e32 v8, v8
	s_nop 0
	v_mul_f32_e32 v6, v6, v8
	v_mul_f32_e32 v6, v6, v124
	v_mul_f32_e32 v9, 0x3e000000, v6
	v_mul_f32_e32 v6, 0x3c800000, v129
	v_mul_f32_e32 v8, 0xbfb8aa3b, v6
	v_exp_f32_e32 v8, v8
	s_nop 0
	v_add_f32_e32 v8, 1.0, v8
	v_rcp_f32_e32 v8, v8
	s_nop 0
	v_mul_f32_e32 v6, v6, v8
	v_mul_f32_e32 v6, v6, v125
	v_mul_f32_e32 v10, 0x3e000000, v6
	v_mul_f32_e32 v6, 0x3c800000, v118
	v_mul_f32_e32 v8, 0xbfb8aa3b, v6
	v_exp_f32_e32 v8, v8
	s_nop 0
	v_add_f32_e32 v8, 1.0, v8
	v_rcp_f32_e32 v8, v8
	s_nop 0
	v_mul_f32_e32 v6, v6, v8
	v_mul_f32_e32 v6, v6, v114
	v_mul_f32_e32 v11, 0x3e000000, v6
	v_mul_f32_e32 v6, 0x3c800000, v119
	v_mul_f32_e32 v8, 0xbfb8aa3b, v6
	v_exp_f32_e32 v8, v8
	s_nop 0
	v_add_f32_e32 v8, 1.0, v8
	v_rcp_f32_e32 v8, v8
	s_nop 0
	v_mul_f32_e32 v6, v6, v8
	v_mul_f32_e32 v6, v6, v115
	v_mul_f32_e32 v12, 0x3e000000, v6
	v_mul_f32_e32 v6, 0x3c800000, v120
	v_mul_f32_e32 v8, 0xbfb8aa3b, v6
	v_exp_f32_e32 v8, v8
	s_nop 0
	v_add_f32_e32 v8, 1.0, v8
	v_rcp_f32_e32 v8, v8
	s_nop 0
	v_mul_f32_e32 v6, v6, v8
	v_mul_f32_e32 v6, v6, v116
	v_mul_f32_e32 v13, 0x3e000000, v6
	v_mul_f32_e32 v6, 0x3c800000, v121
	v_mul_f32_e32 v8, 0xbfb8aa3b, v6
	v_exp_f32_e32 v8, v8
	s_nop 0
	v_add_f32_e32 v8, 1.0, v8
	v_rcp_f32_e32 v8, v8
	s_nop 0
	v_mul_f32_e32 v6, v6, v8
	v_mov_b32_e32 v8, v163
	v_cvt_pk_fp8_f32 v8, v5, v7
	v_med3_f32 v5, v9, s40, v190
	v_med3_f32 v7, v10, s40, v190
	v_mov_b32_e32 v9, v163
	v_cvt_pk_fp8_f32 v8, v5, v7 op_sel:[0,0,1]
	v_med3_f32 v5, v11, s40, v190
	v_med3_f32 v7, v12, s40, v190
	v_cvt_pk_fp8_f32 v9, v5, v7
	v_mul_f32_e32 v6, v6, v117
	v_mul_f32_e32 v14, 0x3e000000, v6
	v_add_u32_e32 v6, 32, v4
	v_med3_f32 v5, v13, s40, v190
	v_med3_f32 v7, v14, s40, v190
	v_cvt_pk_fp8_f32 v9, v5, v7 op_sel:[0,0,1]
	v_ashrrev_i32_e32 v7, 31, v6
	v_lshlrev_b64 v[6:7], 7, v[6:7]
	v_lshl_add_u64 v[6:7], s[10:11], 0, v[6:7]
	v_lshl_add_u64 v[6:7], v[6:7], 0, v[2:3]
	v_mul_f32_e32 v5, 0x3c800000, v110
	global_store_dwordx2 v[6:7], v[8:9], off
	v_mul_f32_e32 v6, 0xbfb8aa3b, v5
	v_exp_f32_e32 v6, v6
	s_nop 0
	v_add_f32_e32 v6, 1.0, v6
	v_rcp_f32_e32 v6, v6
	s_nop 0
	v_mul_f32_e32 v5, v5, v6
	v_mul_f32_e32 v6, 0x3c800000, v111
	v_mul_f32_e32 v7, 0xbfb8aa3b, v6
	v_exp_f32_e32 v7, v7
	v_mul_f32_e32 v5, v5, v106
	v_mul_f32_e32 v5, 0x3e000000, v5
	v_med3_f32 v5, v5, s40, v190
	v_add_f32_e32 v7, 1.0, v7
	v_rcp_f32_e32 v7, v7
	s_nop 0
	v_mul_f32_e32 v6, v6, v7
	v_mul_f32_e32 v6, v6, v107
	v_mul_f32_e32 v7, 0x3e000000, v6
	v_mul_f32_e32 v6, 0x3c800000, v112
	v_mul_f32_e32 v8, 0xbfb8aa3b, v6
	v_exp_f32_e32 v8, v8
	v_med3_f32 v7, v7, s40, v190
	v_add_f32_e32 v8, 1.0, v8
	v_rcp_f32_e32 v8, v8
	s_nop 0
	v_mul_f32_e32 v6, v6, v8
	v_mul_f32_e32 v6, v6, v108
	v_mul_f32_e32 v9, 0x3e000000, v6
	v_mul_f32_e32 v6, 0x3c800000, v113
	v_mul_f32_e32 v8, 0xbfb8aa3b, v6
	v_exp_f32_e32 v8, v8
	s_nop 0
	v_add_f32_e32 v8, 1.0, v8
	v_rcp_f32_e32 v8, v8
	s_nop 0
	v_mul_f32_e32 v6, v6, v8
	v_mul_f32_e32 v6, v6, v109
	v_mul_f32_e32 v10, 0x3e000000, v6
	v_mul_f32_e32 v6, 0x3c800000, v102
	v_mul_f32_e32 v8, 0xbfb8aa3b, v6
	v_exp_f32_e32 v8, v8
	s_nop 0
	v_add_f32_e32 v8, 1.0, v8
	v_rcp_f32_e32 v8, v8
	s_nop 0
	v_mul_f32_e32 v6, v6, v8
	v_mul_f32_e32 v6, v6, v98
	v_mul_f32_e32 v11, 0x3e000000, v6
	v_mul_f32_e32 v6, 0x3c800000, v103
	v_mul_f32_e32 v8, 0xbfb8aa3b, v6
	v_exp_f32_e32 v8, v8
	s_nop 0
	v_add_f32_e32 v8, 1.0, v8
	v_rcp_f32_e32 v8, v8
	s_nop 0
	v_mul_f32_e32 v6, v6, v8
	v_mul_f32_e32 v6, v6, v99
	v_mul_f32_e32 v12, 0x3e000000, v6
	v_mul_f32_e32 v6, 0x3c800000, v104
	v_mul_f32_e32 v8, 0xbfb8aa3b, v6
	v_exp_f32_e32 v8, v8
	s_nop 0
	v_add_f32_e32 v8, 1.0, v8
	v_rcp_f32_e32 v8, v8
	s_nop 0
	v_mul_f32_e32 v6, v6, v8
	v_mul_f32_e32 v6, v6, v100
	v_mul_f32_e32 v13, 0x3e000000, v6
	v_mul_f32_e32 v6, 0x3c800000, v105
	v_mul_f32_e32 v8, 0xbfb8aa3b, v6
	v_exp_f32_e32 v8, v8
	s_nop 0
	v_add_f32_e32 v8, 1.0, v8
	v_rcp_f32_e32 v8, v8
	s_nop 0
	v_mul_f32_e32 v6, v6, v8
	v_mov_b32_e32 v8, v163
	v_cvt_pk_fp8_f32 v8, v5, v7
	v_med3_f32 v5, v9, s40, v190
	v_med3_f32 v7, v10, s40, v190
	v_mov_b32_e32 v9, v163
	v_cvt_pk_fp8_f32 v8, v5, v7 op_sel:[0,0,1]
	v_med3_f32 v5, v11, s40, v190
	v_med3_f32 v7, v12, s40, v190
	v_cvt_pk_fp8_f32 v9, v5, v7
	v_mul_f32_e32 v6, v6, v101
	v_mul_f32_e32 v14, 0x3e000000, v6
	v_add_u32_e32 v6, 48, v4
	v_med3_f32 v5, v13, s40, v190
	v_med3_f32 v7, v14, s40, v190
	v_cvt_pk_fp8_f32 v9, v5, v7 op_sel:[0,0,1]
	v_ashrrev_i32_e32 v7, 31, v6
	v_lshlrev_b64 v[6:7], 7, v[6:7]
	v_lshl_add_u64 v[6:7], s[10:11], 0, v[6:7]
	v_lshl_add_u64 v[6:7], v[6:7], 0, v[2:3]
	v_mul_f32_e32 v5, 0x3c800000, v94
	global_store_dwordx2 v[6:7], v[8:9], off
	v_mul_f32_e32 v7, 0xbfb8aa3b, v5
	v_exp_f32_e32 v7, v7
	v_add_u32_e32 v6, 0x80, v4
	v_add_f32_e32 v7, 1.0, v7
	v_rcp_f32_e32 v7, v7
	s_nop 0
	v_mul_f32_e32 v5, v5, v7
	v_mul_f32_e32 v7, 0x3c800000, v95
	v_mul_f32_e32 v8, 0xbfb8aa3b, v7
	v_exp_f32_e32 v8, v8
	v_mul_f32_e32 v5, v5, v90
	v_mul_f32_e32 v5, 0x3e000000, v5
	v_med3_f32 v5, v5, s40, v190
	v_add_f32_e32 v8, 1.0, v8
	v_rcp_f32_e32 v8, v8
	s_nop 0
	v_mul_f32_e32 v7, v7, v8
	v_mul_f32_e32 v8, 0x3c800000, v96
	v_mul_f32_e32 v9, 0xbfb8aa3b, v8
	v_exp_f32_e32 v9, v9
	v_mul_f32_e32 v7, v7, v91
	v_mul_f32_e32 v7, 0x3e000000, v7
	v_med3_f32 v7, v7, s40, v190
	v_add_f32_e32 v9, 1.0, v9
	v_rcp_f32_e32 v9, v9
	s_nop 0
	v_mul_f32_e32 v8, v8, v9
	v_mul_f32_e32 v8, v8, v92
	v_mul_f32_e32 v9, 0x3e000000, v8
	v_mul_f32_e32 v8, 0x3c800000, v97
	v_mul_f32_e32 v10, 0xbfb8aa3b, v8
	v_exp_f32_e32 v10, v10
	s_nop 0
	v_add_f32_e32 v10, 1.0, v10
	v_rcp_f32_e32 v10, v10
	s_nop 0
	v_mul_f32_e32 v8, v8, v10
	v_mul_f32_e32 v8, v8, v93
	v_mul_f32_e32 v10, 0x3e000000, v8
	v_mul_f32_e32 v8, 0x3c800000, v86
	v_mul_f32_e32 v11, 0xbfb8aa3b, v8
	v_exp_f32_e32 v11, v11
	s_nop 0
	v_add_f32_e32 v11, 1.0, v11
	v_rcp_f32_e32 v11, v11
	s_nop 0
	v_mul_f32_e32 v8, v8, v11
	v_mul_f32_e32 v8, v8, v82
	v_mul_f32_e32 v11, 0x3e000000, v8
	v_mul_f32_e32 v8, 0x3c800000, v87
	v_mul_f32_e32 v12, 0xbfb8aa3b, v8
	v_exp_f32_e32 v12, v12
	s_nop 0
	v_add_f32_e32 v12, 1.0, v12
	v_rcp_f32_e32 v12, v12
	s_nop 0
	v_mul_f32_e32 v8, v8, v12
	v_mul_f32_e32 v8, v8, v83
	v_mul_f32_e32 v12, 0x3e000000, v8
	v_mul_f32_e32 v8, 0x3c800000, v88
	v_mul_f32_e32 v13, 0xbfb8aa3b, v8
	v_exp_f32_e32 v13, v13
	s_nop 0
	v_add_f32_e32 v13, 1.0, v13
	v_rcp_f32_e32 v13, v13
	s_nop 0
	v_mul_f32_e32 v8, v8, v13
	v_mul_f32_e32 v8, v8, v84
	v_mul_f32_e32 v13, 0x3e000000, v8
	v_mul_f32_e32 v8, 0x3c800000, v89
	v_mul_f32_e32 v14, 0xbfb8aa3b, v8
	v_exp_f32_e32 v14, v14
	s_nop 0
	v_add_f32_e32 v14, 1.0, v14
	v_rcp_f32_e32 v14, v14
	s_nop 0
	v_mul_f32_e32 v8, v8, v14
	v_mul_f32_e32 v8, v8, v85
	v_mul_f32_e32 v14, 0x3e000000, v8
	v_mov_b32_e32 v8, v163
	v_cvt_pk_fp8_f32 v8, v5, v7
	v_med3_f32 v5, v9, s40, v190
	v_med3_f32 v7, v10, s40, v190
	v_mov_b32_e32 v9, v163
	v_cvt_pk_fp8_f32 v8, v5, v7 op_sel:[0,0,1]
	v_med3_f32 v5, v11, s40, v190
	v_med3_f32 v7, v12, s40, v190
	v_cvt_pk_fp8_f32 v9, v5, v7
	v_med3_f32 v5, v13, s40, v190
	v_med3_f32 v7, v14, s40, v190
	v_cvt_pk_fp8_f32 v9, v5, v7 op_sel:[0,0,1]
	v_ashrrev_i32_e32 v7, 31, v6
	v_lshlrev_b64 v[6:7], 7, v[6:7]
	v_lshl_add_u64 v[6:7], s[10:11], 0, v[6:7]
	v_lshl_add_u64 v[6:7], v[6:7], 0, v[2:3]
	v_mul_f32_e32 v5, 0x3c800000, v78
	global_store_dwordx2 v[6:7], v[8:9], off
	v_mul_f32_e32 v6, 0xbfb8aa3b, v5
	v_exp_f32_e32 v6, v6
	s_nop 0
	v_add_f32_e32 v6, 1.0, v6
	v_rcp_f32_e32 v6, v6
	s_nop 0
	v_mul_f32_e32 v5, v5, v6
	v_mul_f32_e32 v6, 0x3c800000, v79
	v_mul_f32_e32 v7, 0xbfb8aa3b, v6
	v_exp_f32_e32 v7, v7
	v_mul_f32_e32 v5, v5, v74
	v_mul_f32_e32 v5, 0x3e000000, v5
	v_med3_f32 v5, v5, s40, v190
	v_add_f32_e32 v7, 1.0, v7
	v_rcp_f32_e32 v7, v7
	s_nop 0
	v_mul_f32_e32 v6, v6, v7
	v_mul_f32_e32 v6, v6, v75
	v_mul_f32_e32 v7, 0x3e000000, v6
	v_mul_f32_e32 v6, 0x3c800000, v80
	v_mul_f32_e32 v8, 0xbfb8aa3b, v6
	v_exp_f32_e32 v8, v8
	v_med3_f32 v7, v7, s40, v190
	v_add_f32_e32 v8, 1.0, v8
	v_rcp_f32_e32 v8, v8
	s_nop 0
	v_mul_f32_e32 v6, v6, v8
	v_mul_f32_e32 v6, v6, v76
	v_mul_f32_e32 v9, 0x3e000000, v6
	v_mul_f32_e32 v6, 0x3c800000, v81
	v_mul_f32_e32 v8, 0xbfb8aa3b, v6
	v_exp_f32_e32 v8, v8
	s_nop 0
	v_add_f32_e32 v8, 1.0, v8
	v_rcp_f32_e32 v8, v8
	s_nop 0
	v_mul_f32_e32 v6, v6, v8
	v_mul_f32_e32 v6, v6, v77
	v_mul_f32_e32 v10, 0x3e000000, v6
	v_mul_f32_e32 v6, 0x3c800000, v70
	v_mul_f32_e32 v8, 0xbfb8aa3b, v6
	v_exp_f32_e32 v8, v8
	s_nop 0
	v_add_f32_e32 v8, 1.0, v8
	v_rcp_f32_e32 v8, v8
	s_nop 0
	v_mul_f32_e32 v6, v6, v8
	v_mul_f32_e32 v6, v6, v66
	v_mul_f32_e32 v11, 0x3e000000, v6
	v_mul_f32_e32 v6, 0x3c800000, v71
	v_mul_f32_e32 v8, 0xbfb8aa3b, v6
	v_exp_f32_e32 v8, v8
	s_nop 0
	v_add_f32_e32 v8, 1.0, v8
	v_rcp_f32_e32 v8, v8
	s_nop 0
	v_mul_f32_e32 v6, v6, v8
	v_mul_f32_e32 v6, v6, v67
	v_mul_f32_e32 v12, 0x3e000000, v6
	v_mul_f32_e32 v6, 0x3c800000, v72
	v_mul_f32_e32 v8, 0xbfb8aa3b, v6
	v_exp_f32_e32 v8, v8
	s_nop 0
	v_add_f32_e32 v8, 1.0, v8
	v_rcp_f32_e32 v8, v8
	s_nop 0
	v_mul_f32_e32 v6, v6, v8
	v_mul_f32_e32 v6, v6, v68
	v_mul_f32_e32 v13, 0x3e000000, v6
	v_mul_f32_e32 v6, 0x3c800000, v73
	v_mul_f32_e32 v8, 0xbfb8aa3b, v6
	v_exp_f32_e32 v8, v8
	s_nop 0
	v_add_f32_e32 v8, 1.0, v8
	v_rcp_f32_e32 v8, v8
	s_nop 0
	v_mul_f32_e32 v6, v6, v8
	v_mov_b32_e32 v8, v163
	v_cvt_pk_fp8_f32 v8, v5, v7
	v_med3_f32 v5, v9, s40, v190
	v_med3_f32 v7, v10, s40, v190
	v_mov_b32_e32 v9, v163
	v_cvt_pk_fp8_f32 v8, v5, v7 op_sel:[0,0,1]
	v_med3_f32 v5, v11, s40, v190
	v_med3_f32 v7, v12, s40, v190
	v_cvt_pk_fp8_f32 v9, v5, v7
	v_mul_f32_e32 v6, v6, v69
	v_mul_f32_e32 v14, 0x3e000000, v6
	v_add_u32_e32 v6, 0x90, v4
	v_med3_f32 v5, v13, s40, v190
	v_med3_f32 v7, v14, s40, v190
	v_cvt_pk_fp8_f32 v9, v5, v7 op_sel:[0,0,1]
	v_ashrrev_i32_e32 v7, 31, v6
	v_lshlrev_b64 v[6:7], 7, v[6:7]
	v_lshl_add_u64 v[6:7], s[10:11], 0, v[6:7]
	v_lshl_add_u64 v[6:7], v[6:7], 0, v[2:3]
	v_mul_f32_e32 v5, 0x3c800000, v62
	global_store_dwordx2 v[6:7], v[8:9], off
	v_mul_f32_e32 v6, 0xbfb8aa3b, v5
	v_exp_f32_e32 v6, v6
	s_nop 0
	v_add_f32_e32 v6, 1.0, v6
	v_rcp_f32_e32 v6, v6
	s_nop 0
	v_mul_f32_e32 v5, v5, v6
	v_mul_f32_e32 v6, 0x3c800000, v63
	v_mul_f32_e32 v7, 0xbfb8aa3b, v6
	v_exp_f32_e32 v7, v7
	v_mul_f32_e32 v5, v5, v58
	v_mul_f32_e32 v5, 0x3e000000, v5
	v_med3_f32 v5, v5, s40, v190
	v_add_f32_e32 v7, 1.0, v7
	v_rcp_f32_e32 v7, v7
	s_nop 0
	v_mul_f32_e32 v6, v6, v7
	v_mul_f32_e32 v6, v6, v59
	v_mul_f32_e32 v7, 0x3e000000, v6
	v_mul_f32_e32 v6, 0x3c800000, v64
	v_mul_f32_e32 v8, 0xbfb8aa3b, v6
	v_exp_f32_e32 v8, v8
	v_med3_f32 v7, v7, s40, v190
	v_add_f32_e32 v8, 1.0, v8
	v_rcp_f32_e32 v8, v8
	s_nop 0
	v_mul_f32_e32 v6, v6, v8
	v_mul_f32_e32 v6, v6, v60
	v_mul_f32_e32 v9, 0x3e000000, v6
	v_mul_f32_e32 v6, 0x3c800000, v65
	v_mul_f32_e32 v8, 0xbfb8aa3b, v6
	v_exp_f32_e32 v8, v8
	s_nop 0
	v_add_f32_e32 v8, 1.0, v8
	v_rcp_f32_e32 v8, v8
	s_nop 0
	v_mul_f32_e32 v6, v6, v8
	v_mul_f32_e32 v6, v6, v61
	v_mul_f32_e32 v10, 0x3e000000, v6
	v_mul_f32_e32 v6, 0x3c800000, v54
	v_mul_f32_e32 v8, 0xbfb8aa3b, v6
	v_exp_f32_e32 v8, v8
	s_nop 0
	v_add_f32_e32 v8, 1.0, v8
	v_rcp_f32_e32 v8, v8
	s_nop 0
	v_mul_f32_e32 v6, v6, v8
	v_mul_f32_e32 v6, v6, v50
	v_mul_f32_e32 v11, 0x3e000000, v6
	v_mul_f32_e32 v6, 0x3c800000, v55
	v_mul_f32_e32 v8, 0xbfb8aa3b, v6
	v_exp_f32_e32 v8, v8
	s_nop 0
	v_add_f32_e32 v8, 1.0, v8
	v_rcp_f32_e32 v8, v8
	s_nop 0
	v_mul_f32_e32 v6, v6, v8
	v_mul_f32_e32 v6, v6, v51
	v_mul_f32_e32 v12, 0x3e000000, v6
	v_mul_f32_e32 v6, 0x3c800000, v56
	v_mul_f32_e32 v8, 0xbfb8aa3b, v6
	v_exp_f32_e32 v8, v8
	s_nop 0
	v_add_f32_e32 v8, 1.0, v8
	v_rcp_f32_e32 v8, v8
	s_nop 0
	v_mul_f32_e32 v6, v6, v8
	v_mul_f32_e32 v6, v6, v52
	v_mul_f32_e32 v13, 0x3e000000, v6
	v_mul_f32_e32 v6, 0x3c800000, v57
	v_mul_f32_e32 v8, 0xbfb8aa3b, v6
	v_exp_f32_e32 v8, v8
	s_nop 0
	v_add_f32_e32 v8, 1.0, v8
	v_rcp_f32_e32 v8, v8
	s_nop 0
	v_mul_f32_e32 v6, v6, v8
	v_mov_b32_e32 v8, v163
	v_cvt_pk_fp8_f32 v8, v5, v7
	v_med3_f32 v5, v9, s40, v190
	v_med3_f32 v7, v10, s40, v190
	v_mov_b32_e32 v9, v163
	v_cvt_pk_fp8_f32 v8, v5, v7 op_sel:[0,0,1]
	v_med3_f32 v5, v11, s40, v190
	v_med3_f32 v7, v12, s40, v190
	v_cvt_pk_fp8_f32 v9, v5, v7
	v_mul_f32_e32 v6, v6, v53
	v_mul_f32_e32 v14, 0x3e000000, v6
	v_add_u32_e32 v6, 0xa0, v4
	v_med3_f32 v5, v13, s40, v190
	v_med3_f32 v7, v14, s40, v190
	v_cvt_pk_fp8_f32 v9, v5, v7 op_sel:[0,0,1]
	v_ashrrev_i32_e32 v7, 31, v6
	v_lshlrev_b64 v[6:7], 7, v[6:7]
	v_lshl_add_u64 v[6:7], s[10:11], 0, v[6:7]
	v_lshl_add_u64 v[6:7], v[6:7], 0, v[2:3]
	v_mul_f32_e32 v5, 0x3c800000, v46
	global_store_dwordx2 v[6:7], v[8:9], off
	v_mul_f32_e32 v6, 0xbfb8aa3b, v5
	v_exp_f32_e32 v6, v6
	v_add_u32_e32 v4, 0xb0, v4
	v_add_f32_e32 v6, 1.0, v6
	v_rcp_f32_e32 v6, v6
	s_nop 0
	v_mul_f32_e32 v5, v5, v6
	v_mul_f32_e32 v6, 0x3c800000, v47
	v_mul_f32_e32 v7, 0xbfb8aa3b, v6
	v_exp_f32_e32 v7, v7
	v_mul_f32_e32 v5, v5, v42
	v_mul_f32_e32 v5, 0x3e000000, v5
	v_med3_f32 v5, v5, s40, v190
	v_add_f32_e32 v7, 1.0, v7
	v_rcp_f32_e32 v7, v7
	s_nop 0
	v_mul_f32_e32 v6, v6, v7
	v_mul_f32_e32 v7, 0x3c800000, v48
	v_mul_f32_e32 v8, 0xbfb8aa3b, v7
	v_exp_f32_e32 v8, v8
	v_mul_f32_e32 v6, v6, v43
	v_mul_f32_e32 v6, 0x3e000000, v6
	v_add_f32_e32 v8, 1.0, v8
	v_rcp_f32_e32 v8, v8
	s_nop 0
	v_mul_f32_e32 v7, v7, v8
	v_mul_f32_e32 v8, 0x3c800000, v49
	v_mul_f32_e32 v9, 0xbfb8aa3b, v8
	v_exp_f32_e32 v9, v9
	v_mul_f32_e32 v7, v7, v44
	v_mul_f32_e32 v7, 0x3e000000, v7
	v_add_f32_e32 v9, 1.0, v9
	v_rcp_f32_e32 v9, v9
	s_nop 0
	v_mul_f32_e32 v8, v8, v9
	v_mul_f32_e32 v9, 0x3c800000, v38
	v_mul_f32_e32 v10, 0xbfb8aa3b, v9
	v_exp_f32_e32 v10, v10
	v_mul_f32_e32 v8, v8, v45
	v_mul_f32_e32 v8, 0x3e000000, v8
	v_add_f32_e32 v10, 1.0, v10
	v_rcp_f32_e32 v10, v10
	s_nop 0
	v_mul_f32_e32 v9, v9, v10
	v_mul_f32_e32 v10, 0x3c800000, v39
	v_mul_f32_e32 v11, 0xbfb8aa3b, v10
	v_exp_f32_e32 v11, v11
	v_mul_f32_e32 v9, v9, v34
	v_mul_f32_e32 v9, 0x3e000000, v9
	v_add_f32_e32 v11, 1.0, v11
	v_rcp_f32_e32 v11, v11
	s_nop 0
	v_mul_f32_e32 v10, v10, v11
	v_mul_f32_e32 v11, 0x3c800000, v40
	v_mul_f32_e32 v12, 0xbfb8aa3b, v11
	v_exp_f32_e32 v12, v12
	v_mul_f32_e32 v10, v10, v35
	v_mul_f32_e32 v10, 0x3e000000, v10
	v_add_f32_e32 v12, 1.0, v12
	v_rcp_f32_e32 v12, v12
	s_nop 0
	v_mul_f32_e32 v11, v11, v12
	v_mul_f32_e32 v12, 0x3c800000, v41
	v_mul_f32_e32 v13, 0xbfb8aa3b, v12
	v_exp_f32_e32 v13, v13
	v_mul_f32_e32 v11, v11, v36
	v_mul_f32_e32 v11, 0x3e000000, v11
	v_add_f32_e32 v13, 1.0, v13
	v_rcp_f32_e32 v13, v13
	s_nop 0
	v_mul_f32_e32 v12, v12, v13
	v_med3_f32 v13, v6, s40, v190
	v_mov_b32_e32 v6, v163
	v_cvt_pk_fp8_f32 v6, v5, v13
	v_med3_f32 v5, v7, s40, v190
	v_med3_f32 v7, v8, s40, v190
	v_med3_f32 v8, v10, s40, v190
	v_cvt_pk_fp8_f32 v6, v5, v7 op_sel:[0,0,1]
	v_med3_f32 v5, v9, s40, v190
	v_mov_b32_e32 v7, v163
	v_cvt_pk_fp8_f32 v7, v5, v8
	v_mul_f32_e32 v12, v12, v37
	v_mul_f32_e32 v12, 0x3e000000, v12
	v_med3_f32 v5, v11, s40, v190
	v_med3_f32 v8, v12, s40, v190
	v_cvt_pk_fp8_f32 v7, v5, v8 op_sel:[0,0,1]
	v_ashrrev_i32_e32 v5, 31, v4
	v_lshlrev_b64 v[4:5], 7, v[4:5]
	v_lshl_add_u64 v[4:5], s[10:11], 0, v[4:5]
	v_lshl_add_u64 v[2:3], v[4:5], 0, v[2:3]
	global_store_dwordx2 v[2:3], v[6:7], off
	s_cbranch_vccz .LBB0_677
	s_waitcnt vmcnt(0)
	s_cmpk_gt_u32 s42, 0xff
	s_cbranch_scc1 .LBB0_623
	s_barrier
	s_branch .LBB0_623

.LBB0_755:
	ds_read_b128 v[2:5], v169
	ds_read_b128 v[6:9], v169 offset:1024
	ds_read_b128 v[10:13], v169 offset:2048
	ds_read_b128 v[14:17], v169 offset:3072
	s_add_u32 s0, s26, 0x4000
	s_addc_u32 s1, s27, 0
	s_cmp_eq_u32 s53, 4
	s_cselect_b32 s34, s49, s0
	s_cselect_b32 s35, s19, s1
	s_cselect_b32 s28, s50, s51
	s_cselect_b32 s29, s17, s52
	s_add_u32 s30, s34, 0x8000
	s_addc_u32 s31, s35, 0
	v_lshl_add_u64 v[162:163], s[26:27], 0, v[156:157]
	s_add_i32 m0, s25, 0xc000
	ds_read_b128 v[174:177], v170
	ds_read_b128 v[178:181], v170 offset:1024
	ds_read_b128 v[182:185], v170 offset:2048
	ds_read_b128 v[186:189], v170 offset:3072
	ds_read_b128 v[190:193], v170 offset:4096
	ds_read_b128 v[194:197], v170 offset:5120
	ds_read_b128 v[198:201], v170 offset:6144
	ds_read_b128 v[202:205], v170 offset:7168
	global_load_lds_dwordx4 v[162:163], off
	v_lshl_add_u64 v[162:163], s[26:27], 0, v[154:155]
	s_add_i32 m0, s25, 0xe000
	s_nop 0
	global_load_lds_dwordx4 v[162:163], off
	s_waitcnt lgkmcnt(8)
	s_waitcnt vmcnt(10)
	s_barrier
	s_waitcnt lgkmcnt(0)
	v_mfma_scale_f32_16x16x128_f8f6f4 v[142:145], v[2:9], v[174:181], v[142:145], v171, v171 op_sel_hi:[0,0,0]
	v_mfma_scale_f32_16x16x128_f8f6f4 v[138:141], v[10:17], v[174:181], v[138:141], v171, v171 op_sel_hi:[0,0,0]
	v_mfma_scale_f32_16x16x128_f8f6f4 v[126:129], v[2:9], v[182:189], v[126:129], v171, v171 op_sel_hi:[0,0,0]
	v_mfma_scale_f32_16x16x128_f8f6f4 v[122:125], v[10:17], v[182:189], v[122:125], v171, v171 op_sel_hi:[0,0,0]
	v_mfma_scale_f32_16x16x128_f8f6f4 v[110:113], v[2:9], v[190:197], v[110:113], v171, v171 op_sel_hi:[0,0,0]
	v_mfma_scale_f32_16x16x128_f8f6f4 v[106:109], v[10:17], v[190:197], v[106:109], v171, v171 op_sel_hi:[0,0,0]
	v_mfma_scale_f32_16x16x128_f8f6f4 v[94:97], v[2:9], v[198:205], v[94:97], v171, v171 op_sel_hi:[0,0,0]
	v_mfma_scale_f32_16x16x128_f8f6f4 v[90:93], v[10:17], v[198:205], v[90:93], v171, v171 op_sel_hi:[0,0,0]
	s_barrier
	s_add_i32 s0, s45, s36
	v_lshl_add_u64 v[162:163], s[28:29], 0, v[150:151]
	s_mov_b32 m0, s0
	ds_read_b128 v[206:209], v172
	ds_read_b128 v[210:213], v172 offset:1024
	ds_read_b128 v[214:217], v172 offset:2048
	ds_read_b128 v[218:221], v172 offset:3072
	global_load_lds_dwordx4 v[162:163], off
	v_lshl_add_u64 v[164:165], s[28:29], 0, v[146:147]
	s_add_i32 m0, s0, 0x2000
	s_nop 0
	global_load_lds_dwordx4 v[164:165], off
	s_waitcnt vmcnt(10)
	s_barrier
	s_waitcnt lgkmcnt(0)
	v_mfma_scale_f32_16x16x128_f8f6f4 v[134:137], v[206:213], v[174:181], v[134:137], v171, v171 op_sel_hi:[0,0,0]
	v_mfma_scale_f32_16x16x128_f8f6f4 v[130:133], v[214:221], v[174:181], v[130:133], v171, v171 op_sel_hi:[0,0,0]
	v_mfma_scale_f32_16x16x128_f8f6f4 v[118:121], v[206:213], v[182:189], v[118:121], v171, v171 op_sel_hi:[0,0,0]
	v_mfma_scale_f32_16x16x128_f8f6f4 v[114:117], v[214:221], v[182:189], v[114:117], v171, v171 op_sel_hi:[0,0,0]
	v_mfma_scale_f32_16x16x128_f8f6f4 v[102:105], v[206:213], v[190:197], v[102:105], v171, v171 op_sel_hi:[0,0,0]
	v_mfma_scale_f32_16x16x128_f8f6f4 v[98:101], v[214:221], v[190:197], v[98:101], v171, v171 op_sel_hi:[0,0,0]
	v_mfma_scale_f32_16x16x128_f8f6f4 v[86:89], v[206:213], v[198:205], v[86:89], v171, v171 op_sel_hi:[0,0,0]
	v_mfma_scale_f32_16x16x128_f8f6f4 v[82:85], v[214:221], v[198:205], v[82:85], v171, v171 op_sel_hi:[0,0,0]
	s_mov_b32 m0, s25
	v_lshl_add_u64 v[222:223], s[34:35], 0, v[152:153]
	s_barrier
	ds_read_b128 v[174:177], v170 offset:16384
	ds_read_b128 v[178:181], v170 offset:17408
	ds_read_b128 v[182:185], v170 offset:18432
	ds_read_b128 v[186:189], v170 offset:19456
	ds_read_b128 v[190:193], v170 offset:20480
	ds_read_b128 v[194:197], v170 offset:21504
	ds_read_b128 v[198:201], v170 offset:22528
	ds_read_b128 v[202:205], v170 offset:23552
	global_load_lds_dwordx4 v[222:223], off
	v_lshl_add_u64 v[222:223], s[34:35], 0, v[148:149]
	s_mov_b32 m0, s37
	s_nop 0
	global_load_lds_dwordx4 v[222:223], off
	s_waitcnt vmcnt(10)
	s_barrier
	s_waitcnt lgkmcnt(0)
	v_mfma_scale_f32_16x16x128_f8f6f4 v[78:81], v[2:9], v[174:181], v[78:81], v171, v171 op_sel_hi:[0,0,0]
	v_mfma_scale_f32_16x16x128_f8f6f4 v[74:77], v[10:17], v[174:181], v[74:77], v171, v171 op_sel_hi:[0,0,0]
	v_mfma_scale_f32_16x16x128_f8f6f4 v[62:65], v[2:9], v[182:189], v[62:65], v171, v171 op_sel_hi:[0,0,0]
	v_mfma_scale_f32_16x16x128_f8f6f4 v[58:61], v[10:17], v[182:189], v[58:61], v171, v171 op_sel_hi:[0,0,0]
	v_mfma_scale_f32_16x16x128_f8f6f4 v[46:49], v[2:9], v[190:197], v[46:49], v171, v171 op_sel_hi:[0,0,0]
	v_mfma_scale_f32_16x16x128_f8f6f4 v[42:45], v[10:17], v[190:197], v[42:45], v171, v171 op_sel_hi:[0,0,0]
	v_mfma_scale_f32_16x16x128_f8f6f4 v[30:33], v[2:9], v[198:205], v[30:33], v171, v171 op_sel_hi:[0,0,0]
	v_mfma_scale_f32_16x16x128_f8f6f4 v[26:29], v[10:17], v[198:205], v[26:29], v171, v171 op_sel_hi:[0,0,0]
	s_barrier
	s_add_u32 s0, s28, 0x20000
	s_addc_u32 s1, s29, 0
	s_add_i32 s54, s46, s36
	v_lshl_add_u64 v[2:3], s[0:1], 0, v[150:151]
	s_mov_b32 m0, s54
	s_nop 0
	global_load_lds_dwordx4 v[2:3], off
	v_lshl_add_u64 v[2:3], s[0:1], 0, v[146:147]
	s_add_i32 m0, s54, 0x2000
	s_nop 0
	global_load_lds_dwordx4 v[2:3], off
	s_waitcnt vmcnt(10)
	s_barrier
	v_mfma_scale_f32_16x16x128_f8f6f4 v[70:73], v[206:213], v[174:181], v[70:73], v171, v171 op_sel_hi:[0,0,0]
	v_mfma_scale_f32_16x16x128_f8f6f4 v[66:69], v[214:221], v[174:181], v[66:69], v171, v171 op_sel_hi:[0,0,0]
	v_mfma_scale_f32_16x16x128_f8f6f4 v[54:57], v[206:213], v[182:189], v[54:57], v171, v171 op_sel_hi:[0,0,0]
	v_mfma_scale_f32_16x16x128_f8f6f4 v[50:53], v[214:221], v[182:189], v[50:53], v171, v171 op_sel_hi:[0,0,0]
	v_mfma_scale_f32_16x16x128_f8f6f4 v[38:41], v[206:213], v[190:197], v[38:41], v171, v171 op_sel_hi:[0,0,0]
	v_mfma_scale_f32_16x16x128_f8f6f4 v[34:37], v[214:221], v[190:197], v[34:37], v171, v171 op_sel_hi:[0,0,0]
	v_mfma_scale_f32_16x16x128_f8f6f4 v[22:25], v[206:213], v[198:205], v[22:25], v171, v171 op_sel_hi:[0,0,0]
	v_mfma_scale_f32_16x16x128_f8f6f4 v[18:21], v[214:221], v[198:205], v[18:21], v171, v171 op_sel_hi:[0,0,0]
	s_add_i32 s54, 0, 0x18000
	v_add_u32_e32 v14, s54, v168
	s_barrier
	ds_read_b128 v[2:5], v14
	ds_read_b128 v[6:9], v14 offset:1024
	ds_read_b128 v[10:13], v14 offset:2048
	ds_read_b128 v[14:17], v14 offset:3072
	s_add_u32 s0, s34, 0x4000
	s_addc_u32 s1, s35, 0
	s_mov_b32 m0, s38
	v_lshl_add_u64 v[206:207], s[0:1], 0, v[152:153]
	ds_read_b128 v[174:177], v170 offset:32768
	ds_read_b128 v[178:181], v170 offset:33792
	ds_read_b128 v[182:185], v170 offset:34816
	ds_read_b128 v[186:189], v170 offset:35840
	ds_read_b128 v[190:193], v170 offset:36864
	ds_read_b128 v[194:197], v170 offset:37888
	ds_read_b128 v[198:201], v170 offset:38912
	ds_read_b128 v[202:205], v170 offset:39936
	global_load_lds_dwordx4 v[206:207], off
	v_lshl_add_u64 v[206:207], s[0:1], 0, v[148:149]
	s_mov_b32 m0, s39
	s_nop 0
	global_load_lds_dwordx4 v[206:207], off
	s_waitcnt lgkmcnt(8)
	s_waitcnt vmcnt(10)
	s_barrier
	s_waitcnt lgkmcnt(0)
	v_mfma_scale_f32_16x16x128_f8f6f4 v[142:145], v[2:9], v[174:181], v[142:145], v171, v171 op_sel_hi:[0,0,0]
	v_mfma_scale_f32_16x16x128_f8f6f4 v[138:141], v[10:17], v[174:181], v[138:141], v171, v171 op_sel_hi:[0,0,0]
	v_mfma_scale_f32_16x16x128_f8f6f4 v[126:129], v[2:9], v[182:189], v[126:129], v171, v171 op_sel_hi:[0,0,0]
	v_mfma_scale_f32_16x16x128_f8f6f4 v[122:125], v[10:17], v[182:189], v[122:125], v171, v171 op_sel_hi:[0,0,0]
	v_mfma_scale_f32_16x16x128_f8f6f4 v[110:113], v[2:9], v[190:197], v[110:113], v171, v171 op_sel_hi:[0,0,0]
	v_mfma_scale_f32_16x16x128_f8f6f4 v[106:109], v[10:17], v[190:197], v[106:109], v171, v171 op_sel_hi:[0,0,0]
	v_mfma_scale_f32_16x16x128_f8f6f4 v[94:97], v[2:9], v[198:205], v[94:97], v171, v171 op_sel_hi:[0,0,0]
	v_mfma_scale_f32_16x16x128_f8f6f4 v[90:93], v[10:17], v[198:205], v[90:93], v171, v171 op_sel_hi:[0,0,0]
	s_barrier
	s_add_i32 s34, 0, 0x1c000
	s_add_i32 s0, s54, s36
	v_add_u32_e32 v218, s34, v168
	v_lshl_add_u64 v[162:163], v[162:163], 0, s[12:13]
	s_mov_b32 m0, s0
	ds_read_b128 v[206:209], v218
	ds_read_b128 v[210:213], v218 offset:1024
	ds_read_b128 v[214:217], v218 offset:2048
	ds_read_b128 v[218:221], v218 offset:3072
	global_load_lds_dwordx4 v[162:163], off
	v_lshl_add_u64 v[162:163], v[164:165], 0, s[12:13]
	s_add_i32 m0, s0, 0x2000
	s_nop 0
	global_load_lds_dwordx4 v[162:163], off
	s_waitcnt vmcnt(10)
	s_barrier
	s_waitcnt lgkmcnt(0)
	v_mfma_scale_f32_16x16x128_f8f6f4 v[134:137], v[206:213], v[174:181], v[134:137], v171, v171 op_sel_hi:[0,0,0]
	v_mfma_scale_f32_16x16x128_f8f6f4 v[130:133], v[214:221], v[174:181], v[130:133], v171, v171 op_sel_hi:[0,0,0]
	v_mfma_scale_f32_16x16x128_f8f6f4 v[118:121], v[206:213], v[182:189], v[118:121], v171, v171 op_sel_hi:[0,0,0]
	v_mfma_scale_f32_16x16x128_f8f6f4 v[114:117], v[214:221], v[182:189], v[114:117], v171, v171 op_sel_hi:[0,0,0]
	v_mfma_scale_f32_16x16x128_f8f6f4 v[102:105], v[206:213], v[190:197], v[102:105], v171, v171 op_sel_hi:[0,0,0]
	v_mfma_scale_f32_16x16x128_f8f6f4 v[98:101], v[214:221], v[190:197], v[98:101], v171, v171 op_sel_hi:[0,0,0]
	v_mfma_scale_f32_16x16x128_f8f6f4 v[86:89], v[206:213], v[198:205], v[86:89], v171, v171 op_sel_hi:[0,0,0]
	v_mfma_scale_f32_16x16x128_f8f6f4 v[82:85], v[214:221], v[198:205], v[82:85], v171, v171 op_sel_hi:[0,0,0]
	s_mov_b32 m0, s43
	v_lshl_add_u64 v[162:163], s[30:31], 0, v[152:153]
	s_barrier
	ds_read_b128 v[174:177], v170 offset:49152
	ds_read_b128 v[178:181], v170 offset:50176
	ds_read_b128 v[182:185], v170 offset:51200
	ds_read_b128 v[186:189], v170 offset:52224
	ds_read_b128 v[190:193], v170 offset:53248
	ds_read_b128 v[194:197], v170 offset:54272
	ds_read_b128 v[198:201], v170 offset:55296
	ds_read_b128 v[202:205], v170 offset:56320
	global_load_lds_dwordx4 v[162:163], off
	v_lshl_add_u64 v[162:163], s[30:31], 0, v[148:149]
	s_mov_b32 m0, s44
	s_nop 0
	global_load_lds_dwordx4 v[162:163], off
	s_waitcnt vmcnt(10)
	s_barrier
	s_waitcnt lgkmcnt(0)
	v_mfma_scale_f32_16x16x128_f8f6f4 v[78:81], v[2:9], v[174:181], v[78:81], v171, v171 op_sel_hi:[0,0,0]
	v_mfma_scale_f32_16x16x128_f8f6f4 v[74:77], v[10:17], v[174:181], v[74:77], v171, v171 op_sel_hi:[0,0,0]
	v_mfma_scale_f32_16x16x128_f8f6f4 v[62:65], v[2:9], v[182:189], v[62:65], v171, v171 op_sel_hi:[0,0,0]
	v_mfma_scale_f32_16x16x128_f8f6f4 v[58:61], v[10:17], v[182:189], v[58:61], v171, v171 op_sel_hi:[0,0,0]
	v_mfma_scale_f32_16x16x128_f8f6f4 v[46:49], v[2:9], v[190:197], v[46:49], v171, v171 op_sel_hi:[0,0,0]
	v_mfma_scale_f32_16x16x128_f8f6f4 v[42:45], v[10:17], v[190:197], v[42:45], v171, v171 op_sel_hi:[0,0,0]
	v_mfma_scale_f32_16x16x128_f8f6f4 v[30:33], v[2:9], v[198:205], v[30:33], v171, v171 op_sel_hi:[0,0,0]
	v_mfma_scale_f32_16x16x128_f8f6f4 v[26:29], v[10:17], v[198:205], v[26:29], v171, v171 op_sel_hi:[0,0,0]
	s_barrier
	s_add_u32 s0, s28, 0x20080
	s_addc_u32 s1, s29, 0
	s_add_i32 s28, s34, s36
	v_lshl_add_u64 v[2:3], s[0:1], 0, v[150:151]
	s_mov_b32 m0, s28
	s_nop 0
	global_load_lds_dwordx4 v[2:3], off
	v_lshl_add_u64 v[2:3], s[0:1], 0, v[146:147]
	s_add_i32 m0, s28, 0x2000
	s_nop 0
	global_load_lds_dwordx4 v[2:3], off
	s_waitcnt vmcnt(10)
	s_barrier
	v_mfma_scale_f32_16x16x128_f8f6f4 v[70:73], v[206:213], v[174:181], v[70:73], v171, v171 op_sel_hi:[0,0,0]
	v_mfma_scale_f32_16x16x128_f8f6f4 v[66:69], v[214:221], v[174:181], v[66:69], v171, v171 op_sel_hi:[0,0,0]
	v_mfma_scale_f32_16x16x128_f8f6f4 v[54:57], v[206:213], v[182:189], v[54:57], v171, v171 op_sel_hi:[0,0,0]
	v_mfma_scale_f32_16x16x128_f8f6f4 v[50:53], v[214:221], v[182:189], v[50:53], v171, v171 op_sel_hi:[0,0,0]
	v_mfma_scale_f32_16x16x128_f8f6f4 v[38:41], v[206:213], v[190:197], v[38:41], v171, v171 op_sel_hi:[0,0,0]
	v_mfma_scale_f32_16x16x128_f8f6f4 v[34:37], v[214:221], v[190:197], v[34:37], v171, v171 op_sel_hi:[0,0,0]
	v_mfma_scale_f32_16x16x128_f8f6f4 v[22:25], v[206:213], v[198:205], v[22:25], v171, v171 op_sel_hi:[0,0,0]
	v_mfma_scale_f32_16x16x128_f8f6f4 v[18:21], v[214:221], v[198:205], v[18:21], v171, v171 op_sel_hi:[0,0,0]
	s_add_i32 s53, s53, 2
	s_add_u32 s51, s51, 0x100
	s_addc_u32 s52, s52, 0
	s_add_u32 s26, s26, 0x10000
	s_addc_u32 s27, s27, 0
	s_cmp_gt_u32 s53, 5
	s_barrier
	s_cbranch_scc0 .LBB0_755
	v_pk_mul_f32 v[10:11], v[142:143], s[14:15] op_sel_hi:[1,0]
	v_pk_mul_f32 v[8:9], v[144:145], s[14:15] op_sel_hi:[1,0]
	v_med3_f32 v5, v10, s47, v173
	v_med3_f32 v11, v11, s47, v173
	v_mov_b32_e32 v10, 0
	v_cvt_pk_fp8_f32 v10, v5, v11
	v_mov_b32_e32 v3, v166
	v_mov_b32_e32 v2, v167
	s_lshl_b32 s0, s48, 8
	v_pk_mul_f32 v[14:15], v[138:139], s[14:15] op_sel_hi:[1,0]
	v_med3_f32 v5, v8, s47, v173
	v_med3_f32 v8, v9, s47, v173
	s_nop 15
	s_nop 15
	s_or_b32 s0, s0, s42
	v_cvt_pk_fp8_f32 v10, v5, v8 op_sel:[0,0,1]
	v_med3_f32 v5, v14, s47, v173
	v_med3_f32 v8, v15, s47, v173
	v_mov_b32_e32 v11, 0
	v_lshl_add_u32 v2, v2, 3, s0
	s_lshl_b32 s0, s24, 8
	v_cvt_pk_fp8_f32 v11, v5, v8
	s_add_i32 s0, s0, s41
	v_add_u32_e32 v4, s0, v3
	v_pk_mul_f32 v[12:13], v[140:141], s[14:15] op_sel_hi:[1,0]
	v_mov_b32_e32 v6, v4
	v_med3_f32 v5, v12, s47, v173
	v_med3_f32 v8, v13, s47, v173
	v_cvt_pk_fp8_f32 v11, v5, v8 op_sel:[0,0,1]
	v_ashrrev_i32_e32 v7, 31, v6
	v_lshlrev_b64 v[6:7], 10, v[6:7]
	v_ashrrev_i32_e32 v3, 31, v2
	v_lshl_add_u64 v[6:7], s[10:11], 0, v[6:7]
	v_lshl_add_u64 v[6:7], v[6:7], 0, v[2:3]
	global_store_dwordx2 v[6:7], v[10:11], off
	v_pk_mul_f32 v[10:11], v[134:135], s[14:15] op_sel_hi:[1,0]
	v_pk_mul_f32 v[8:9], v[136:137], s[14:15] op_sel_hi:[1,0]
	v_med3_f32 v5, v10, s47, v173
	v_med3_f32 v11, v11, s47, v173
	v_mov_b32_e32 v10, 0
	v_cvt_pk_fp8_f32 v10, v5, v11
	v_pk_mul_f32 v[14:15], v[130:131], s[14:15] op_sel_hi:[1,0]
	v_med3_f32 v5, v8, s47, v173
	v_med3_f32 v8, v9, s47, v173
	v_cvt_pk_fp8_f32 v10, v5, v8 op_sel:[0,0,1]
	v_med3_f32 v5, v14, s47, v173
	v_med3_f32 v8, v15, s47, v173
	v_mov_b32_e32 v11, 0
	v_cvt_pk_fp8_f32 v11, v5, v8
	v_pk_mul_f32 v[12:13], v[132:133], s[14:15] op_sel_hi:[1,0]
	v_pk_mul_f32 v[14:15], v[122:123], s[14:15] op_sel_hi:[1,0]
	v_med3_f32 v5, v12, s47, v173
	v_med3_f32 v8, v13, s47, v173
	v_cvt_pk_fp8_f32 v11, v5, v8 op_sel:[0,0,1]
	v_pk_mul_f32 v[8:9], v[128:129], s[14:15] op_sel_hi:[1,0]
	v_pk_mul_f32 v[12:13], v[124:125], s[14:15] op_sel_hi:[1,0]
	s_and_b64 vcc, exec, s[8:9]
	global_store_dwordx2 v[6:7], v[10:11], off offset:128
	v_pk_mul_f32 v[10:11], v[126:127], s[14:15] op_sel_hi:[1,0]
	v_add_u32_e32 v6, 16, v4
	v_med3_f32 v5, v10, s47, v173
	v_med3_f32 v11, v11, s47, v173
	v_mov_b32_e32 v10, 0
	v_cvt_pk_fp8_f32 v10, v5, v11
	v_med3_f32 v5, v8, s47, v173
	v_med3_f32 v8, v9, s47, v173
	v_mov_b32_e32 v11, 0
	v_cvt_pk_fp8_f32 v10, v5, v8 op_sel:[0,0,1]
	v_med3_f32 v5, v14, s47, v173
	v_med3_f32 v8, v15, s47, v173
	v_cvt_pk_fp8_f32 v11, v5, v8
	v_med3_f32 v5, v12, s47, v173
	v_med3_f32 v8, v13, s47, v173
	v_cvt_pk_fp8_f32 v11, v5, v8 op_sel:[0,0,1]
	v_ashrrev_i32_e32 v7, 31, v6
	v_lshlrev_b64 v[6:7], 10, v[6:7]
	v_lshl_add_u64 v[6:7], s[10:11], 0, v[6:7]
	v_lshl_add_u64 v[6:7], v[6:7], 0, v[2:3]
	global_store_dwordx2 v[6:7], v[10:11], off
	v_pk_mul_f32 v[10:11], v[118:119], s[14:15] op_sel_hi:[1,0]
	v_pk_mul_f32 v[8:9], v[120:121], s[14:15] op_sel_hi:[1,0]
	v_med3_f32 v5, v10, s47, v173
	v_med3_f32 v11, v11, s47, v173
	v_mov_b32_e32 v10, 0
	v_cvt_pk_fp8_f32 v10, v5, v11
	v_pk_mul_f32 v[14:15], v[114:115], s[14:15] op_sel_hi:[1,0]
	v_med3_f32 v5, v8, s47, v173
	v_med3_f32 v8, v9, s47, v173
	v_cvt_pk_fp8_f32 v10, v5, v8 op_sel:[0,0,1]
	v_med3_f32 v5, v14, s47, v173
	v_med3_f32 v8, v15, s47, v173
	v_mov_b32_e32 v11, 0
	v_cvt_pk_fp8_f32 v11, v5, v8
	v_pk_mul_f32 v[12:13], v[116:117], s[14:15] op_sel_hi:[1,0]
	v_pk_mul_f32 v[14:15], v[106:107], s[14:15] op_sel_hi:[1,0]
	v_med3_f32 v5, v12, s47, v173
	v_med3_f32 v8, v13, s47, v173
	v_cvt_pk_fp8_f32 v11, v5, v8 op_sel:[0,0,1]
	v_pk_mul_f32 v[8:9], v[112:113], s[14:15] op_sel_hi:[1,0]
	v_pk_mul_f32 v[12:13], v[108:109], s[14:15] op_sel_hi:[1,0]
	s_mov_b32 s48, s16
	global_store_dwordx2 v[6:7], v[10:11], off offset:128
	v_pk_mul_f32 v[10:11], v[110:111], s[14:15] op_sel_hi:[1,0]
	v_add_u32_e32 v6, 32, v4
	v_med3_f32 v5, v10, s47, v173
	v_med3_f32 v11, v11, s47, v173
	v_mov_b32_e32 v10, 0
	v_cvt_pk_fp8_f32 v10, v5, v11
	v_med3_f32 v5, v8, s47, v173
	v_med3_f32 v8, v9, s47, v173
	v_mov_b32_e32 v11, 0
	v_cvt_pk_fp8_f32 v10, v5, v8 op_sel:[0,0,1]
	v_med3_f32 v5, v14, s47, v173
	v_med3_f32 v8, v15, s47, v173
	v_cvt_pk_fp8_f32 v11, v5, v8
	v_med3_f32 v5, v12, s47, v173
	v_med3_f32 v8, v13, s47, v173
	v_cvt_pk_fp8_f32 v11, v5, v8 op_sel:[0,0,1]
	v_ashrrev_i32_e32 v7, 31, v6
	v_lshlrev_b64 v[6:7], 10, v[6:7]
	v_lshl_add_u64 v[6:7], s[10:11], 0, v[6:7]
	v_lshl_add_u64 v[6:7], v[6:7], 0, v[2:3]
	global_store_dwordx2 v[6:7], v[10:11], off
	v_pk_mul_f32 v[10:11], v[102:103], s[14:15] op_sel_hi:[1,0]
	v_pk_mul_f32 v[8:9], v[104:105], s[14:15] op_sel_hi:[1,0]
	v_med3_f32 v5, v10, s47, v173
	v_med3_f32 v11, v11, s47, v173
	v_mov_b32_e32 v10, 0
	v_cvt_pk_fp8_f32 v10, v5, v11
	v_pk_mul_f32 v[14:15], v[98:99], s[14:15] op_sel_hi:[1,0]
	v_med3_f32 v5, v8, s47, v173
	v_med3_f32 v8, v9, s47, v173
	v_cvt_pk_fp8_f32 v10, v5, v8 op_sel:[0,0,1]
	v_med3_f32 v5, v14, s47, v173
	v_med3_f32 v8, v15, s47, v173
	v_mov_b32_e32 v11, 0
	v_cvt_pk_fp8_f32 v11, v5, v8
	v_pk_mul_f32 v[12:13], v[100:101], s[14:15] op_sel_hi:[1,0]
	v_pk_mul_f32 v[14:15], v[90:91], s[14:15] op_sel_hi:[1,0]
	v_med3_f32 v5, v12, s47, v173
	v_med3_f32 v8, v13, s47, v173
	v_cvt_pk_fp8_f32 v11, v5, v8 op_sel:[0,0,1]
	v_pk_mul_f32 v[8:9], v[96:97], s[14:15] op_sel_hi:[1,0]
	v_pk_mul_f32 v[12:13], v[92:93], s[14:15] op_sel_hi:[1,0]
	s_mov_b32 s24, s18
	global_store_dwordx2 v[6:7], v[10:11], off offset:128
	v_pk_mul_f32 v[10:11], v[94:95], s[14:15] op_sel_hi:[1,0]
	v_add_u32_e32 v6, 48, v4
	v_med3_f32 v5, v10, s47, v173
	v_med3_f32 v11, v11, s47, v173
	v_mov_b32_e32 v10, 0
	v_cvt_pk_fp8_f32 v10, v5, v11
	v_med3_f32 v5, v8, s47, v173
	v_med3_f32 v8, v9, s47, v173
	v_mov_b32_e32 v11, 0
	v_cvt_pk_fp8_f32 v10, v5, v8 op_sel:[0,0,1]
	v_med3_f32 v5, v14, s47, v173
	v_med3_f32 v8, v15, s47, v173
	v_cvt_pk_fp8_f32 v11, v5, v8
	v_med3_f32 v5, v12, s47, v173
	v_med3_f32 v8, v13, s47, v173
	v_cvt_pk_fp8_f32 v11, v5, v8 op_sel:[0,0,1]
	v_ashrrev_i32_e32 v7, 31, v6
	v_lshlrev_b64 v[6:7], 10, v[6:7]
	v_lshl_add_u64 v[6:7], s[10:11], 0, v[6:7]
	v_lshl_add_u64 v[6:7], v[6:7], 0, v[2:3]
	global_store_dwordx2 v[6:7], v[10:11], off
	v_pk_mul_f32 v[10:11], v[86:87], s[14:15] op_sel_hi:[1,0]
	v_pk_mul_f32 v[8:9], v[88:89], s[14:15] op_sel_hi:[1,0]
	v_med3_f32 v5, v10, s47, v173
	v_med3_f32 v11, v11, s47, v173
	v_mov_b32_e32 v10, 0
	v_cvt_pk_fp8_f32 v10, v5, v11
	v_pk_mul_f32 v[14:15], v[82:83], s[14:15] op_sel_hi:[1,0]
	v_med3_f32 v5, v8, s47, v173
	v_med3_f32 v8, v9, s47, v173
	v_cvt_pk_fp8_f32 v10, v5, v8 op_sel:[0,0,1]
	v_med3_f32 v5, v14, s47, v173
	v_med3_f32 v8, v15, s47, v173
	v_mov_b32_e32 v11, 0
	v_cvt_pk_fp8_f32 v11, v5, v8
	v_pk_mul_f32 v[12:13], v[84:85], s[14:15] op_sel_hi:[1,0]
	v_pk_mul_f32 v[14:15], v[74:75], s[14:15] op_sel_hi:[1,0]
	v_med3_f32 v5, v12, s47, v173
	v_med3_f32 v8, v13, s47, v173
	v_cvt_pk_fp8_f32 v11, v5, v8 op_sel:[0,0,1]
	v_pk_mul_f32 v[8:9], v[80:81], s[14:15] op_sel_hi:[1,0]
	v_pk_mul_f32 v[12:13], v[76:77], s[14:15] op_sel_hi:[1,0]
	s_mov_b64 s[26:27], s[22:23]
	global_store_dwordx2 v[6:7], v[10:11], off offset:128
	v_pk_mul_f32 v[10:11], v[78:79], s[14:15] op_sel_hi:[1,0]
	v_add_u32_e32 v6, 0x80, v4
	v_med3_f32 v5, v10, s47, v173
	v_med3_f32 v11, v11, s47, v173
	v_mov_b32_e32 v10, 0
	v_cvt_pk_fp8_f32 v10, v5, v11
	v_med3_f32 v5, v8, s47, v173
	v_med3_f32 v8, v9, s47, v173
	v_mov_b32_e32 v11, 0
	v_cvt_pk_fp8_f32 v10, v5, v8 op_sel:[0,0,1]
	v_med3_f32 v5, v14, s47, v173
	v_med3_f32 v8, v15, s47, v173
	v_cvt_pk_fp8_f32 v11, v5, v8
	v_med3_f32 v5, v12, s47, v173
	v_med3_f32 v8, v13, s47, v173
	v_cvt_pk_fp8_f32 v11, v5, v8 op_sel:[0,0,1]
	v_ashrrev_i32_e32 v7, 31, v6
	v_lshlrev_b64 v[6:7], 10, v[6:7]
	v_lshl_add_u64 v[6:7], s[10:11], 0, v[6:7]
	v_lshl_add_u64 v[6:7], v[6:7], 0, v[2:3]
	global_store_dwordx2 v[6:7], v[10:11], off
	v_pk_mul_f32 v[10:11], v[70:71], s[14:15] op_sel_hi:[1,0]
	v_pk_mul_f32 v[8:9], v[72:73], s[14:15] op_sel_hi:[1,0]
	v_med3_f32 v5, v10, s47, v173
	v_med3_f32 v11, v11, s47, v173
	v_mov_b32_e32 v10, 0
	v_cvt_pk_fp8_f32 v10, v5, v11
	v_pk_mul_f32 v[14:15], v[66:67], s[14:15] op_sel_hi:[1,0]
	v_med3_f32 v5, v8, s47, v173
	v_med3_f32 v8, v9, s47, v173
	v_cvt_pk_fp8_f32 v10, v5, v8 op_sel:[0,0,1]
	v_med3_f32 v5, v14, s47, v173
	v_med3_f32 v8, v15, s47, v173
	v_mov_b32_e32 v11, 0
	v_cvt_pk_fp8_f32 v11, v5, v8
	v_pk_mul_f32 v[12:13], v[68:69], s[14:15] op_sel_hi:[1,0]
	v_pk_mul_f32 v[14:15], v[58:59], s[14:15] op_sel_hi:[1,0]
	v_med3_f32 v5, v12, s47, v173
	v_med3_f32 v8, v13, s47, v173
	v_cvt_pk_fp8_f32 v11, v5, v8 op_sel:[0,0,1]
	v_pk_mul_f32 v[8:9], v[64:65], s[14:15] op_sel_hi:[1,0]
	v_pk_mul_f32 v[12:13], v[60:61], s[14:15] op_sel_hi:[1,0]
	s_mov_b64 s[28:29], s[20:21]
	global_store_dwordx2 v[6:7], v[10:11], off offset:128
	v_pk_mul_f32 v[10:11], v[62:63], s[14:15] op_sel_hi:[1,0]
	v_add_u32_e32 v6, 0x90, v4
	v_med3_f32 v5, v10, s47, v173
	v_med3_f32 v11, v11, s47, v173
	v_mov_b32_e32 v10, 0
	v_cvt_pk_fp8_f32 v10, v5, v11
	v_med3_f32 v5, v8, s47, v173
	v_med3_f32 v8, v9, s47, v173
	v_mov_b32_e32 v11, 0
	v_cvt_pk_fp8_f32 v10, v5, v8 op_sel:[0,0,1]
	v_med3_f32 v5, v14, s47, v173
	v_med3_f32 v8, v15, s47, v173
	v_cvt_pk_fp8_f32 v11, v5, v8
	v_med3_f32 v5, v12, s47, v173
	v_med3_f32 v8, v13, s47, v173
	v_cvt_pk_fp8_f32 v11, v5, v8 op_sel:[0,0,1]
	v_ashrrev_i32_e32 v7, 31, v6
	v_lshlrev_b64 v[6:7], 10, v[6:7]
	v_lshl_add_u64 v[6:7], s[10:11], 0, v[6:7]
	v_lshl_add_u64 v[6:7], v[6:7], 0, v[2:3]
	global_store_dwordx2 v[6:7], v[10:11], off
	v_pk_mul_f32 v[10:11], v[54:55], s[14:15] op_sel_hi:[1,0]
	v_pk_mul_f32 v[8:9], v[56:57], s[14:15] op_sel_hi:[1,0]
	v_med3_f32 v5, v10, s47, v173
	v_med3_f32 v11, v11, s47, v173
	v_mov_b32_e32 v10, 0
	v_cvt_pk_fp8_f32 v10, v5, v11
	v_pk_mul_f32 v[14:15], v[50:51], s[14:15] op_sel_hi:[1,0]
	v_med3_f32 v5, v8, s47, v173
	v_med3_f32 v8, v9, s47, v173
	v_cvt_pk_fp8_f32 v10, v5, v8 op_sel:[0,0,1]
	v_med3_f32 v5, v14, s47, v173
	v_med3_f32 v8, v15, s47, v173
	v_mov_b32_e32 v11, 0
	v_cvt_pk_fp8_f32 v11, v5, v8
	v_pk_mul_f32 v[12:13], v[52:53], s[14:15] op_sel_hi:[1,0]
	v_pk_mul_f32 v[14:15], v[42:43], s[14:15] op_sel_hi:[1,0]
	v_med3_f32 v5, v12, s47, v173
	v_med3_f32 v8, v13, s47, v173
	v_cvt_pk_fp8_f32 v11, v5, v8 op_sel:[0,0,1]
	v_pk_mul_f32 v[8:9], v[48:49], s[14:15] op_sel_hi:[1,0]
	v_pk_mul_f32 v[12:13], v[44:45], s[14:15] op_sel_hi:[1,0]
	global_store_dwordx2 v[6:7], v[10:11], off offset:128
	v_pk_mul_f32 v[10:11], v[46:47], s[14:15] op_sel_hi:[1,0]
	v_add_u32_e32 v6, 0xa0, v4
	v_med3_f32 v5, v10, s47, v173
	v_med3_f32 v11, v11, s47, v173
	v_mov_b32_e32 v10, 0
	v_cvt_pk_fp8_f32 v10, v5, v11
	v_med3_f32 v5, v8, s47, v173
	v_med3_f32 v8, v9, s47, v173
	v_mov_b32_e32 v11, 0
	v_cvt_pk_fp8_f32 v10, v5, v8 op_sel:[0,0,1]
	v_med3_f32 v5, v14, s47, v173
	v_med3_f32 v8, v15, s47, v173
	v_cvt_pk_fp8_f32 v11, v5, v8
	v_med3_f32 v5, v12, s47, v173
	v_med3_f32 v8, v13, s47, v173
	v_cvt_pk_fp8_f32 v11, v5, v8 op_sel:[0,0,1]
	v_ashrrev_i32_e32 v7, 31, v6
	v_lshlrev_b64 v[6:7], 10, v[6:7]
	v_lshl_add_u64 v[6:7], s[10:11], 0, v[6:7]
	v_lshl_add_u64 v[6:7], v[6:7], 0, v[2:3]
	global_store_dwordx2 v[6:7], v[10:11], off
	v_pk_mul_f32 v[10:11], v[38:39], s[14:15] op_sel_hi:[1,0]
	v_pk_mul_f32 v[8:9], v[40:41], s[14:15] op_sel_hi:[1,0]
	v_med3_f32 v5, v10, s47, v173
	v_med3_f32 v11, v11, s47, v173
	v_mov_b32_e32 v10, 0
	v_cvt_pk_fp8_f32 v10, v5, v11
	v_pk_mul_f32 v[14:15], v[34:35], s[14:15] op_sel_hi:[1,0]
	v_med3_f32 v5, v8, s47, v173
	v_med3_f32 v8, v9, s47, v173
	v_cvt_pk_fp8_f32 v10, v5, v8 op_sel:[0,0,1]
	v_med3_f32 v5, v14, s47, v173
	v_med3_f32 v8, v15, s47, v173
	v_mov_b32_e32 v11, 0
	v_cvt_pk_fp8_f32 v11, v5, v8
	v_pk_mul_f32 v[12:13], v[36:37], s[14:15] op_sel_hi:[1,0]
	v_add_u32_e32 v4, 0xb0, v4
	v_med3_f32 v5, v12, s47, v173
	v_med3_f32 v8, v13, s47, v173
	v_cvt_pk_fp8_f32 v11, v5, v8 op_sel:[0,0,1]
	v_pk_mul_f32 v[8:9], v[28:29], s[14:15] op_sel_hi:[1,0]
	global_store_dwordx2 v[6:7], v[10:11], off offset:128
	v_pk_mul_f32 v[6:7], v[30:31], s[14:15] op_sel_hi:[1,0]
	v_pk_mul_f32 v[10:11], v[26:27], s[14:15] op_sel_hi:[1,0]
	v_ashrrev_i32_e32 v5, 31, v4
	v_med3_f32 v12, v6, s47, v173
	v_med3_f32 v7, v7, s47, v173
	v_mov_b32_e32 v6, 0
	v_lshlrev_b64 v[4:5], 10, v[4:5]
	v_cvt_pk_fp8_f32 v6, v12, v7
	v_lshl_add_u64 v[4:5], s[10:11], 0, v[4:5]
	v_lshl_add_u64 v[2:3], v[4:5], 0, v[2:3]
	v_pk_mul_f32 v[4:5], v[32:33], s[14:15] op_sel_hi:[1,0]
	v_mov_b32_e32 v7, 0
	v_med3_f32 v4, v4, s47, v173
	v_med3_f32 v5, v5, s47, v173
	v_cvt_pk_fp8_f32 v6, v4, v5 op_sel:[0,0,1]
	v_med3_f32 v4, v10, s47, v173
	v_med3_f32 v5, v11, s47, v173
	v_cvt_pk_fp8_f32 v7, v4, v5
	v_med3_f32 v4, v8, s47, v173
	v_med3_f32 v5, v9, s47, v173
	v_pk_mul_f32 v[10:11], v[18:19], s[14:15] op_sel_hi:[1,0]
	v_cvt_pk_fp8_f32 v7, v4, v5 op_sel:[0,0,1]
	v_pk_mul_f32 v[4:5], v[24:25], s[14:15] op_sel_hi:[1,0]
	v_pk_mul_f32 v[8:9], v[20:21], s[14:15] op_sel_hi:[1,0]
	v_med3_f32 v4, v4, s47, v173
	global_store_dwordx2 v[2:3], v[6:7], off
	v_pk_mul_f32 v[6:7], v[22:23], s[14:15] op_sel_hi:[1,0]
	v_med3_f32 v5, v5, s47, v173
	v_med3_f32 v12, v6, s47, v173
	v_med3_f32 v7, v7, s47, v173
	v_mov_b32_e32 v6, 0
	v_cvt_pk_fp8_f32 v6, v12, v7
	v_mov_b32_e32 v7, 0
	v_cvt_pk_fp8_f32 v6, v4, v5 op_sel:[0,0,1]
	v_med3_f32 v4, v10, s47, v173
	v_med3_f32 v5, v11, s47, v173
	v_cvt_pk_fp8_f32 v7, v4, v5
	v_med3_f32 v4, v8, s47, v173
	v_med3_f32 v5, v9, s47, v173
	v_cvt_pk_fp8_f32 v7, v4, v5 op_sel:[0,0,1]
	global_store_dwordx2 v[2:3], v[6:7], off offset:128
	s_cbranch_vccz .LBB0_748
	s_waitcnt vmcnt(0)
	s_cmpk_gt_u32 s4, 0xff
	s_cbranch_scc1 .LBB0_759
	s_barrier

.LBB0_895:
	ds_read_b128 v[156:159], v152
	ds_read_b128 v[160:163], v152 offset:1024
	ds_read_b128 v[164:167], v152 offset:2048
	ds_read_b128 v[168:171], v152 offset:3072
	s_add_u32 s0, s30, 0xfffc0080
	s_addc_u32 s1, s31, -1
	s_cmp_eq_u32 s55, 12
	s_cselect_b32 s37, s23, s1
	s_cselect_b32 s36, s51, s0
	s_cselect_b32 s35, s21, s54
	s_cselect_b32 s34, s52, s53
	v_lshl_add_u64 v[148:149], s[30:31], 0, v[140:141]
	s_add_i32 m0, s25, 0xc000
	ds_read_b128 v[172:175], v153
	ds_read_b128 v[176:179], v153 offset:1024
	ds_read_b128 v[180:183], v153 offset:2048
	ds_read_b128 v[184:187], v153 offset:3072
	ds_read_b128 v[188:191], v153 offset:4096
	ds_read_b128 v[192:195], v153 offset:5120
	ds_read_b128 v[196:199], v153 offset:6144
	ds_read_b128 v[200:203], v153 offset:7168
	global_load_lds_dwordx4 v[148:149], off
	v_lshl_add_u64 v[148:149], s[30:31], 0, v[138:139]
	s_add_i32 m0, s25, 0xe000
	s_nop 0
	global_load_lds_dwordx4 v[148:149], off
	s_waitcnt lgkmcnt(8)
	s_waitcnt vmcnt(10)
	s_barrier
	s_waitcnt lgkmcnt(0)
	v_mfma_f32_16x16x32_bf16 v[126:129], v[156:159], v[172:175], v[126:129]
	v_mfma_f32_16x16x32_bf16 v[122:125], v[164:167], v[172:175], v[122:125]
	v_mfma_f32_16x16x32_bf16 v[118:121], v[156:159], v[180:183], v[118:121]
	v_mfma_f32_16x16x32_bf16 v[110:113], v[164:167], v[180:183], v[110:113]
	v_mfma_f32_16x16x32_bf16 v[102:105], v[156:159], v[188:191], v[102:105]
	v_mfma_f32_16x16x32_bf16 v[94:97], v[164:167], v[188:191], v[94:97]
	v_mfma_f32_16x16x32_bf16 v[86:89], v[156:159], v[196:199], v[86:89]
	v_mfma_f32_16x16x32_bf16 v[78:81], v[164:167], v[196:199], v[78:81]
	v_mfma_f32_16x16x32_bf16 v[126:129], v[160:163], v[176:179], v[126:129]
	v_mfma_f32_16x16x32_bf16 v[122:125], v[168:171], v[176:179], v[122:125]
	v_mfma_f32_16x16x32_bf16 v[118:121], v[160:163], v[184:187], v[118:121]
	v_mfma_f32_16x16x32_bf16 v[110:113], v[168:171], v[184:187], v[110:113]
	v_mfma_f32_16x16x32_bf16 v[102:105], v[160:163], v[192:195], v[102:105]
	v_mfma_f32_16x16x32_bf16 v[94:97], v[168:171], v[192:195], v[94:97]
	v_mfma_f32_16x16x32_bf16 v[86:89], v[160:163], v[200:203], v[86:89]
	v_mfma_f32_16x16x32_bf16 v[78:81], v[168:171], v[200:203], v[78:81]
	s_barrier
	s_add_i32 s0, s47, s11
	v_lshl_add_u64 v[148:149], s[34:35], 0, v[134:135]
	s_mov_b32 m0, s0
	ds_read_b128 v[204:207], v154
	ds_read_b128 v[208:211], v154 offset:1024
	ds_read_b128 v[212:215], v154 offset:2048
	ds_read_b128 v[216:219], v154 offset:3072
	global_load_lds_dwordx4 v[148:149], off
	v_lshl_add_u64 v[220:221], s[34:35], 0, v[130:131]
	s_add_i32 m0, s0, 0x2000
	s_nop 0
	global_load_lds_dwordx4 v[220:221], off
	s_waitcnt vmcnt(10)
	s_barrier
	s_waitcnt lgkmcnt(0)
	v_mfma_f32_16x16x32_bf16 v[114:117], v[204:207], v[172:175], v[114:117]
	v_mfma_f32_16x16x32_bf16 v[106:109], v[212:215], v[172:175], v[106:109]
	v_mfma_f32_16x16x32_bf16 v[98:101], v[204:207], v[180:183], v[98:101]
	v_mfma_f32_16x16x32_bf16 v[90:93], v[212:215], v[180:183], v[90:93]
	v_mfma_f32_16x16x32_bf16 v[82:85], v[204:207], v[188:191], v[82:85]
	v_mfma_f32_16x16x32_bf16 v[74:77], v[212:215], v[188:191], v[74:77]
	v_mfma_f32_16x16x32_bf16 v[70:73], v[204:207], v[196:199], v[70:73]
	v_mfma_f32_16x16x32_bf16 v[66:69], v[212:215], v[196:199], v[66:69]
	v_mfma_f32_16x16x32_bf16 v[114:117], v[208:211], v[176:179], v[114:117]
	v_mfma_f32_16x16x32_bf16 v[106:109], v[216:219], v[176:179], v[106:109]
	v_mfma_f32_16x16x32_bf16 v[98:101], v[208:211], v[184:187], v[98:101]
	v_mfma_f32_16x16x32_bf16 v[90:93], v[216:219], v[184:187], v[90:93]
	v_mfma_f32_16x16x32_bf16 v[82:85], v[208:211], v[192:195], v[82:85]
	v_mfma_f32_16x16x32_bf16 v[74:77], v[216:219], v[192:195], v[74:77]
	v_mfma_f32_16x16x32_bf16 v[70:73], v[208:211], v[200:203], v[70:73]
	v_mfma_f32_16x16x32_bf16 v[66:69], v[216:219], v[200:203], v[66:69]
	s_mov_b32 m0, s25
	v_lshl_add_u64 v[222:223], s[36:37], 0, v[136:137]
	s_barrier
	ds_read_b128 v[172:175], v153 offset:16384
	ds_read_b128 v[176:179], v153 offset:17408
	ds_read_b128 v[180:183], v153 offset:18432
	ds_read_b128 v[184:187], v153 offset:19456
	ds_read_b128 v[188:191], v153 offset:20480
	ds_read_b128 v[192:195], v153 offset:21504
	ds_read_b128 v[196:199], v153 offset:22528
	ds_read_b128 v[200:203], v153 offset:23552
	global_load_lds_dwordx4 v[222:223], off
	v_lshl_add_u64 v[224:225], s[36:37], 0, v[132:133]
	s_mov_b32 m0, s39
	s_nop 0
	global_load_lds_dwordx4 v[224:225], off
	s_waitcnt vmcnt(10)
	s_barrier
	s_waitcnt lgkmcnt(0)
	v_mfma_f32_16x16x32_bf16 v[62:65], v[156:159], v[172:175], v[62:65]
	v_mfma_f32_16x16x32_bf16 v[58:61], v[164:167], v[172:175], v[58:61]
	v_mfma_f32_16x16x32_bf16 v[54:57], v[156:159], v[180:183], v[54:57]
	v_mfma_f32_16x16x32_bf16 v[46:49], v[164:167], v[180:183], v[46:49]
	v_mfma_f32_16x16x32_bf16 v[38:41], v[156:159], v[188:191], v[38:41]
	v_mfma_f32_16x16x32_bf16 v[30:33], v[164:167], v[188:191], v[30:33]
	v_mfma_f32_16x16x32_bf16 v[22:25], v[156:159], v[196:199], v[22:25]
	v_mfma_f32_16x16x32_bf16 v[14:17], v[164:167], v[196:199], v[14:17]
	v_mfma_f32_16x16x32_bf16 v[62:65], v[160:163], v[176:179], v[62:65]
	v_mfma_f32_16x16x32_bf16 v[58:61], v[168:171], v[176:179], v[58:61]
	v_mfma_f32_16x16x32_bf16 v[54:57], v[160:163], v[184:187], v[54:57]
	v_mfma_f32_16x16x32_bf16 v[46:49], v[168:171], v[184:187], v[46:49]
	v_mfma_f32_16x16x32_bf16 v[38:41], v[160:163], v[192:195], v[38:41]
	v_mfma_f32_16x16x32_bf16 v[30:33], v[168:171], v[192:195], v[30:33]
	v_mfma_f32_16x16x32_bf16 v[22:25], v[160:163], v[200:203], v[22:25]
	v_mfma_f32_16x16x32_bf16 v[14:17], v[168:171], v[200:203], v[14:17]
	s_barrier
	s_add_u32 s0, s34, 0x40000
	s_addc_u32 s1, s35, 0
	s_add_i32 s56, s48, s11
	v_lshl_add_u64 v[156:157], s[0:1], 0, v[134:135]
	s_mov_b32 m0, s56
	s_nop 0
	global_load_lds_dwordx4 v[156:157], off
	v_lshl_add_u64 v[156:157], s[0:1], 0, v[130:131]
	s_add_i32 m0, s56, 0x2000
	s_nop 0
	global_load_lds_dwordx4 v[156:157], off
	s_waitcnt vmcnt(10)
	s_barrier
	v_mfma_f32_16x16x32_bf16 v[50:53], v[204:207], v[172:175], v[50:53]
	v_mfma_f32_16x16x32_bf16 v[42:45], v[212:215], v[172:175], v[42:45]
	v_mfma_f32_16x16x32_bf16 v[34:37], v[204:207], v[180:183], v[34:37]
	v_mfma_f32_16x16x32_bf16 v[26:29], v[212:215], v[180:183], v[26:29]
	v_mfma_f32_16x16x32_bf16 v[18:21], v[204:207], v[188:191], v[18:21]
	v_mfma_f32_16x16x32_bf16 v[10:13], v[212:215], v[188:191], v[10:13]
	v_mfma_f32_16x16x32_bf16 v[6:9], v[204:207], v[196:199], v[6:9]
	v_mfma_f32_16x16x32_bf16 v[2:5], v[212:215], v[196:199], v[2:5]
	v_mfma_f32_16x16x32_bf16 v[50:53], v[208:211], v[176:179], v[50:53]
	v_mfma_f32_16x16x32_bf16 v[42:45], v[216:219], v[176:179], v[42:45]
	v_mfma_f32_16x16x32_bf16 v[34:37], v[208:211], v[184:187], v[34:37]
	v_mfma_f32_16x16x32_bf16 v[26:29], v[216:219], v[184:187], v[26:29]
	v_mfma_f32_16x16x32_bf16 v[18:21], v[208:211], v[192:195], v[18:21]
	v_mfma_f32_16x16x32_bf16 v[10:13], v[216:219], v[192:195], v[10:13]
	v_mfma_f32_16x16x32_bf16 v[6:9], v[208:211], v[200:203], v[6:9]
	v_mfma_f32_16x16x32_bf16 v[2:5], v[216:219], v[200:203], v[2:5]
	s_add_i32 s56, 0, 0x18000
	v_add_u32_e32 v146, s56, v151
	s_barrier
	ds_read_b128 v[156:159], v146
	ds_read_b128 v[160:163], v146 offset:1024
	ds_read_b128 v[164:167], v146 offset:2048
	ds_read_b128 v[168:171], v146 offset:3072
	s_add_u32 s0, s36, 0x40000
	s_addc_u32 s1, s37, 0
	s_mov_b32 m0, s40
	v_lshl_add_u64 v[204:205], s[0:1], 0, v[136:137]
	ds_read_b128 v[172:175], v153 offset:32768
	ds_read_b128 v[176:179], v153 offset:33792
	ds_read_b128 v[180:183], v153 offset:34816
	ds_read_b128 v[184:187], v153 offset:35840
	ds_read_b128 v[188:191], v153 offset:36864
	ds_read_b128 v[192:195], v153 offset:37888
	ds_read_b128 v[196:199], v153 offset:38912
	ds_read_b128 v[200:203], v153 offset:39936
	global_load_lds_dwordx4 v[204:205], off
	v_lshl_add_u64 v[204:205], s[0:1], 0, v[132:133]
	s_mov_b32 m0, s41
	s_nop 0
	global_load_lds_dwordx4 v[204:205], off
	s_waitcnt lgkmcnt(8)
	s_waitcnt vmcnt(10)
	s_barrier
	s_waitcnt lgkmcnt(0)
	v_mfma_f32_16x16x32_bf16 v[126:129], v[156:159], v[172:175], v[126:129]
	v_mfma_f32_16x16x32_bf16 v[122:125], v[164:167], v[172:175], v[122:125]
	v_mfma_f32_16x16x32_bf16 v[118:121], v[156:159], v[180:183], v[118:121]
	v_mfma_f32_16x16x32_bf16 v[110:113], v[164:167], v[180:183], v[110:113]
	v_mfma_f32_16x16x32_bf16 v[102:105], v[156:159], v[188:191], v[102:105]
	v_mfma_f32_16x16x32_bf16 v[94:97], v[164:167], v[188:191], v[94:97]
	v_mfma_f32_16x16x32_bf16 v[86:89], v[156:159], v[196:199], v[86:89]
	v_mfma_f32_16x16x32_bf16 v[78:81], v[164:167], v[196:199], v[78:81]
	v_mfma_f32_16x16x32_bf16 v[126:129], v[160:163], v[176:179], v[126:129]
	v_mfma_f32_16x16x32_bf16 v[122:125], v[168:171], v[176:179], v[122:125]
	v_mfma_f32_16x16x32_bf16 v[118:121], v[160:163], v[184:187], v[118:121]
	v_mfma_f32_16x16x32_bf16 v[110:113], v[168:171], v[184:187], v[110:113]
	v_mfma_f32_16x16x32_bf16 v[102:105], v[160:163], v[192:195], v[102:105]
	v_mfma_f32_16x16x32_bf16 v[94:97], v[168:171], v[192:195], v[94:97]
	v_mfma_f32_16x16x32_bf16 v[86:89], v[160:163], v[200:203], v[86:89]
	v_mfma_f32_16x16x32_bf16 v[78:81], v[168:171], v[200:203], v[78:81]
	s_barrier
	s_add_i32 s36, 0, 0x1c000
	s_add_i32 s0, s56, s11
	v_add_u32_e32 v146, s36, v151
	v_lshl_add_u64 v[148:149], v[148:149], 0, s[16:17]
	s_mov_b32 m0, s0
	ds_read_b128 v[204:207], v146
	ds_read_b128 v[208:211], v146 offset:1024
	ds_read_b128 v[212:215], v146 offset:2048
	ds_read_b128 v[216:219], v146 offset:3072
	global_load_lds_dwordx4 v[148:149], off
	v_lshl_add_u64 v[148:149], v[220:221], 0, s[16:17]
	s_add_i32 m0, s0, 0x2000
	s_nop 0
	global_load_lds_dwordx4 v[148:149], off
	s_waitcnt vmcnt(10)
	s_barrier
	s_waitcnt lgkmcnt(0)
	v_mfma_f32_16x16x32_bf16 v[114:117], v[204:207], v[172:175], v[114:117]
	v_mfma_f32_16x16x32_bf16 v[106:109], v[212:215], v[172:175], v[106:109]
	v_mfma_f32_16x16x32_bf16 v[98:101], v[204:207], v[180:183], v[98:101]
	v_mfma_f32_16x16x32_bf16 v[90:93], v[212:215], v[180:183], v[90:93]
	v_mfma_f32_16x16x32_bf16 v[82:85], v[204:207], v[188:191], v[82:85]
	v_mfma_f32_16x16x32_bf16 v[74:77], v[212:215], v[188:191], v[74:77]
	v_mfma_f32_16x16x32_bf16 v[70:73], v[204:207], v[196:199], v[70:73]
	v_mfma_f32_16x16x32_bf16 v[66:69], v[212:215], v[196:199], v[66:69]
	v_mfma_f32_16x16x32_bf16 v[114:117], v[208:211], v[176:179], v[114:117]
	v_mfma_f32_16x16x32_bf16 v[106:109], v[216:219], v[176:179], v[106:109]
	v_mfma_f32_16x16x32_bf16 v[98:101], v[208:211], v[184:187], v[98:101]
	v_mfma_f32_16x16x32_bf16 v[90:93], v[216:219], v[184:187], v[90:93]
	v_mfma_f32_16x16x32_bf16 v[82:85], v[208:211], v[192:195], v[82:85]
	v_mfma_f32_16x16x32_bf16 v[74:77], v[216:219], v[192:195], v[74:77]
	v_mfma_f32_16x16x32_bf16 v[70:73], v[208:211], v[200:203], v[70:73]
	v_mfma_f32_16x16x32_bf16 v[66:69], v[216:219], v[200:203], v[66:69]
	s_mov_b32 m0, s45
	v_lshl_add_u64 v[148:149], v[222:223], 0, s[16:17]
	s_barrier
	ds_read_b128 v[172:175], v153 offset:49152
	ds_read_b128 v[176:179], v153 offset:50176
	ds_read_b128 v[180:183], v153 offset:51200
	ds_read_b128 v[184:187], v153 offset:52224
	ds_read_b128 v[188:191], v153 offset:53248
	ds_read_b128 v[192:195], v153 offset:54272
	ds_read_b128 v[196:199], v153 offset:55296
	ds_read_b128 v[200:203], v153 offset:56320
	global_load_lds_dwordx4 v[148:149], off
	v_lshl_add_u64 v[148:149], v[224:225], 0, s[16:17]
	s_mov_b32 m0, s46
	s_nop 0
	global_load_lds_dwordx4 v[148:149], off
	s_waitcnt vmcnt(10)
	s_barrier
	s_waitcnt lgkmcnt(0)
	v_mfma_f32_16x16x32_bf16 v[62:65], v[156:159], v[172:175], v[62:65]
	v_mfma_f32_16x16x32_bf16 v[58:61], v[164:167], v[172:175], v[58:61]
	v_mfma_f32_16x16x32_bf16 v[54:57], v[156:159], v[180:183], v[54:57]
	v_mfma_f32_16x16x32_bf16 v[46:49], v[164:167], v[180:183], v[46:49]
	v_mfma_f32_16x16x32_bf16 v[38:41], v[156:159], v[188:191], v[38:41]
	v_mfma_f32_16x16x32_bf16 v[30:33], v[164:167], v[188:191], v[30:33]
	v_mfma_f32_16x16x32_bf16 v[22:25], v[156:159], v[196:199], v[22:25]
	v_mfma_f32_16x16x32_bf16 v[14:17], v[164:167], v[196:199], v[14:17]
	v_mfma_f32_16x16x32_bf16 v[62:65], v[160:163], v[176:179], v[62:65]
	v_mfma_f32_16x16x32_bf16 v[58:61], v[168:171], v[176:179], v[58:61]
	v_mfma_f32_16x16x32_bf16 v[54:57], v[160:163], v[184:187], v[54:57]
	v_mfma_f32_16x16x32_bf16 v[46:49], v[168:171], v[184:187], v[46:49]
	v_mfma_f32_16x16x32_bf16 v[38:41], v[160:163], v[192:195], v[38:41]
	v_mfma_f32_16x16x32_bf16 v[30:33], v[168:171], v[192:195], v[30:33]
	v_mfma_f32_16x16x32_bf16 v[22:25], v[160:163], v[200:203], v[22:25]
	v_mfma_f32_16x16x32_bf16 v[14:17], v[168:171], v[200:203], v[14:17]
	s_barrier
	s_add_u32 s0, s34, 0x40080
	s_addc_u32 s1, s35, 0
	s_add_i32 s34, s36, s11
	v_lshl_add_u64 v[148:149], s[0:1], 0, v[134:135]
	s_mov_b32 m0, s34
	s_nop 0
	global_load_lds_dwordx4 v[148:149], off
	v_lshl_add_u64 v[148:149], s[0:1], 0, v[130:131]
	s_add_i32 m0, s34, 0x2000
	s_nop 0
	global_load_lds_dwordx4 v[148:149], off
	s_waitcnt vmcnt(10)
	s_barrier
	v_mfma_f32_16x16x32_bf16 v[50:53], v[204:207], v[172:175], v[50:53]
	v_mfma_f32_16x16x32_bf16 v[42:45], v[212:215], v[172:175], v[42:45]
	v_mfma_f32_16x16x32_bf16 v[34:37], v[204:207], v[180:183], v[34:37]
	v_mfma_f32_16x16x32_bf16 v[26:29], v[212:215], v[180:183], v[26:29]
	v_mfma_f32_16x16x32_bf16 v[18:21], v[204:207], v[188:191], v[18:21]
	v_mfma_f32_16x16x32_bf16 v[10:13], v[212:215], v[188:191], v[10:13]
	v_mfma_f32_16x16x32_bf16 v[6:9], v[204:207], v[196:199], v[6:9]
	v_mfma_f32_16x16x32_bf16 v[2:5], v[212:215], v[196:199], v[2:5]
	v_mfma_f32_16x16x32_bf16 v[50:53], v[208:211], v[176:179], v[50:53]
	v_mfma_f32_16x16x32_bf16 v[42:45], v[216:219], v[176:179], v[42:45]
	v_mfma_f32_16x16x32_bf16 v[34:37], v[208:211], v[184:187], v[34:37]
	v_mfma_f32_16x16x32_bf16 v[26:29], v[216:219], v[184:187], v[26:29]
	v_mfma_f32_16x16x32_bf16 v[18:21], v[208:211], v[192:195], v[18:21]
	v_mfma_f32_16x16x32_bf16 v[10:13], v[216:219], v[192:195], v[10:13]
	v_mfma_f32_16x16x32_bf16 v[6:9], v[208:211], v[200:203], v[6:9]
	v_mfma_f32_16x16x32_bf16 v[2:5], v[216:219], v[200:203], v[2:5]
	s_add_i32 s55, s55, 2
	s_add_u32 s53, s53, 0x100
	s_addc_u32 s54, s54, 0
	s_add_u32 s30, s30, 0x100
	s_addc_u32 s31, s31, 0
	s_cmp_gt_u32 s55, 13
	s_barrier
	s_cbranch_scc0 .LBB0_895
	v_mov_b32_e32 v156, v147
	v_mov_b32_e32 v146, v150
	s_cmp_gt_i32 s50, 11
	s_mov_b64 s[30:31], -1
	s_cbranch_scc0 .LBB0_900
	s_cmp_eq_u32 s50, 12
	s_cselect_b64 s[0:1], -1, 0
	s_and_b64 s[0:1], s[0:1], s[18:19]
	v_cmp_gt_i32_e32 vcc, 4, v146
	s_and_b64 s[0:1], s[0:1], vcc
	s_and_saveexec_b64 s[30:31], s[0:1]
	s_cbranch_execz .LBB0_899
	s_lshl_b32 s0, s24, 8
	s_add_i32 s0, s0, s43
	v_add_u32_e32 v157, s0, v156
	v_mov_b32_e32 v158, v157
	v_lshlrev_b32_e32 v148, 3, v146
	v_ashrrev_i32_e32 v149, 31, v148
	v_ashrrev_i32_e32 v159, 31, v158
	v_lshlrev_b64 v[158:159], 7, v[158:159]
	v_lshl_add_u64 v[158:159], s[14:15], 0, v[158:159]
	v_lshlrev_b64 v[148:149], 2, v[148:149]
	v_lshl_add_u64 v[162:163], v[158:159], 0, v[148:149]
	v_pk_add_f32 v[160:161], v[128:129], 0 op_sel_hi:[1,0]
	v_pk_add_f32 v[158:159], v[126:127], 0 op_sel_hi:[1,0]
	global_store_dwordx4 v[162:163], v[158:161], off
	s_nop 1
	v_pk_add_f32 v[160:161], v[124:125], 0 op_sel_hi:[1,0]
	v_pk_add_f32 v[158:159], v[122:123], 0 op_sel_hi:[1,0]
	global_store_dwordx4 v[162:163], v[158:161], off offset:16
	s_nop 1
	v_add_u32_e32 v158, 16, v157
	v_pk_add_f32 v[160:161], v[120:121], 0 op_sel_hi:[1,0]
	v_ashrrev_i32_e32 v159, 31, v158
	v_lshlrev_b64 v[158:159], 7, v[158:159]
	v_lshl_add_u64 v[158:159], s[14:15], 0, v[158:159]
	v_lshl_add_u64 v[162:163], v[158:159], 0, v[148:149]
	v_pk_add_f32 v[158:159], v[118:119], 0 op_sel_hi:[1,0]
	global_store_dwordx4 v[162:163], v[158:161], off
	s_nop 1
	v_pk_add_f32 v[160:161], v[112:113], 0 op_sel_hi:[1,0]
	v_pk_add_f32 v[158:159], v[110:111], 0 op_sel_hi:[1,0]
	global_store_dwordx4 v[162:163], v[158:161], off offset:16
	s_nop 1
	v_add_u32_e32 v158, 32, v157
	v_pk_add_f32 v[160:161], v[104:105], 0 op_sel_hi:[1,0]
	v_ashrrev_i32_e32 v159, 31, v158
	v_lshlrev_b64 v[158:159], 7, v[158:159]
	v_lshl_add_u64 v[158:159], s[14:15], 0, v[158:159]
	v_lshl_add_u64 v[162:163], v[158:159], 0, v[148:149]
	v_pk_add_f32 v[158:159], v[102:103], 0 op_sel_hi:[1,0]
	global_store_dwordx4 v[162:163], v[158:161], off
	s_nop 1
	v_pk_add_f32 v[160:161], v[96:97], 0 op_sel_hi:[1,0]
	v_pk_add_f32 v[158:159], v[94:95], 0 op_sel_hi:[1,0]
	global_store_dwordx4 v[162:163], v[158:161], off offset:16
	s_nop 1
	v_add_u32_e32 v158, 48, v157
	v_pk_add_f32 v[160:161], v[88:89], 0 op_sel_hi:[1,0]
	v_ashrrev_i32_e32 v159, 31, v158
	v_lshlrev_b64 v[158:159], 7, v[158:159]
	v_lshl_add_u64 v[158:159], s[14:15], 0, v[158:159]
	v_lshl_add_u64 v[162:163], v[158:159], 0, v[148:149]
	v_pk_add_f32 v[158:159], v[86:87], 0 op_sel_hi:[1,0]
	global_store_dwordx4 v[162:163], v[158:161], off
	s_nop 1
	v_pk_add_f32 v[160:161], v[80:81], 0 op_sel_hi:[1,0]
	v_pk_add_f32 v[158:159], v[78:79], 0 op_sel_hi:[1,0]
	global_store_dwordx4 v[162:163], v[158:161], off offset:16
	s_nop 1
	v_add_u32_e32 v158, 0x80, v157
	v_pk_add_f32 v[160:161], v[64:65], 0 op_sel_hi:[1,0]
	v_ashrrev_i32_e32 v159, 31, v158
	v_lshlrev_b64 v[158:159], 7, v[158:159]
	v_lshl_add_u64 v[158:159], s[14:15], 0, v[158:159]
	v_lshl_add_u64 v[162:163], v[158:159], 0, v[148:149]
	v_pk_add_f32 v[158:159], v[62:63], 0 op_sel_hi:[1,0]
	global_store_dwordx4 v[162:163], v[158:161], off
	s_nop 1
	v_pk_add_f32 v[160:161], v[60:61], 0 op_sel_hi:[1,0]
	v_pk_add_f32 v[158:159], v[58:59], 0 op_sel_hi:[1,0]
	global_store_dwordx4 v[162:163], v[158:161], off offset:16
	s_nop 1
	v_add_u32_e32 v158, 0x90, v157
	v_pk_add_f32 v[160:161], v[56:57], 0 op_sel_hi:[1,0]
	v_ashrrev_i32_e32 v159, 31, v158
	v_lshlrev_b64 v[158:159], 7, v[158:159]
	v_lshl_add_u64 v[158:159], s[14:15], 0, v[158:159]
	v_lshl_add_u64 v[162:163], v[158:159], 0, v[148:149]
	v_pk_add_f32 v[158:159], v[54:55], 0 op_sel_hi:[1,0]
	global_store_dwordx4 v[162:163], v[158:161], off
	s_nop 1
	v_pk_add_f32 v[160:161], v[48:49], 0 op_sel_hi:[1,0]
	v_pk_add_f32 v[158:159], v[46:47], 0 op_sel_hi:[1,0]
	global_store_dwordx4 v[162:163], v[158:161], off offset:16
	s_nop 1
	v_add_u32_e32 v158, 0xa0, v157
	v_pk_add_f32 v[160:161], v[40:41], 0 op_sel_hi:[1,0]
	v_ashrrev_i32_e32 v159, 31, v158
	v_lshlrev_b64 v[158:159], 7, v[158:159]
	v_lshl_add_u64 v[158:159], s[14:15], 0, v[158:159]
	v_lshl_add_u64 v[162:163], v[158:159], 0, v[148:149]
	v_pk_add_f32 v[158:159], v[38:39], 0 op_sel_hi:[1,0]
	global_store_dwordx4 v[162:163], v[158:161], off
	s_nop 1
	v_pk_add_f32 v[160:161], v[32:33], 0 op_sel_hi:[1,0]
	v_pk_add_f32 v[158:159], v[30:31], 0 op_sel_hi:[1,0]
	global_store_dwordx4 v[162:163], v[158:161], off offset:16
	s_nop 1
	v_add_u32_e32 v158, 0xb0, v157
	v_pk_add_f32 v[160:161], v[24:25], 0 op_sel_hi:[1,0]
	v_ashrrev_i32_e32 v159, 31, v158
	v_lshlrev_b64 v[158:159], 7, v[158:159]
	v_lshl_add_u64 v[158:159], s[14:15], 0, v[158:159]
	v_lshl_add_u64 v[148:149], v[158:159], 0, v[148:149]
	v_pk_add_f32 v[158:159], v[22:23], 0 op_sel_hi:[1,0]
	global_store_dwordx4 v[148:149], v[158:161], off
	s_nop 1
	v_pk_add_f32 v[160:161], v[16:17], 0 op_sel_hi:[1,0]
	v_pk_add_f32 v[158:159], v[14:15], 0 op_sel_hi:[1,0]
	global_store_dwordx4 v[148:149], v[158:161], off offset:16

.LBB0_969:
	v_mov_b32_e32 v86, v159
	s_waitcnt lgkmcnt(0)
	s_barrier
	v_cvt_pk_bf16_f32 v194, v58, v59
	v_and_b32_e32 v84, 31, v86
	v_bfe_u32 v192, v86, 5, 1
	v_lshlrev_b32_e32 v87, 4, v86
	v_lshlrev_b32_e32 v200, 4, v192
	v_lshlrev_b32_e32 v193, 8, v84
	v_and_b32_e32 v201, 0x70, v87
	v_bitop3_b32 v66, v201, v193, v200 bitop3:0xde
	v_add_u32_e32 v70, 0, v66
	ds_read_b128 v[66:69], v70 offset:8192
	ds_read_b128 v[70:73], v70
	s_waitcnt lgkmcnt(0)
	v_mfma_f32_32x32x16_bf16 v[68:83], v[66:69], v[70:73], 0
	v_or_b32_e32 v66, 32, v200
	v_bitop3_b32 v66, v66, v193, v201 bitop3:0xde
	v_add_u32_e32 v66, 0, v66
	ds_read_b128 v[140:143], v66 offset:8192
	ds_read_b128 v[144:147], v66
	v_or_b32_e32 v66, 64, v200
	v_bitop3_b32 v66, v66, v193, v201 bitop3:0xde
	v_add_u32_e32 v66, 0, v66
	s_waitcnt lgkmcnt(0)
	v_mfma_f32_32x32x16_bf16 v[68:83], v[140:143], v[144:147], v[68:83]
	ds_read_b128 v[140:143], v66 offset:8192
	ds_read_b128 v[144:147], v66
	v_or_b32_e32 v66, 0x60, v200
	v_bitop3_b32 v66, v66, v193, v201 bitop3:0xde
	v_add_u32_e32 v66, 0, v66
	ds_read_b128 v[148:151], v66 offset:8192
	v_and_b32_e32 v67, 63, v86
	v_lshlrev_b32_e32 v86, 1, v86
	s_waitcnt lgkmcnt(0)
	v_mfma_f32_32x32x16_bf16 v[68:83], v[140:143], v[144:147], v[68:83]
	ds_read_b128 v[140:143], v66
	v_or_b32_e32 v66, 0x80, v200
	v_bitop3_b32 v66, v66, v193, v201 bitop3:0xde
	v_add_u32_e32 v66, 0, v66
	ds_read_b128 v[144:147], v66 offset:8192
	v_lshlrev_b32_e32 v67, 3, v67
	v_and_b32_e32 v87, 0xc0, v87
	s_waitcnt lgkmcnt(0)
	v_mfma_f32_32x32x16_bf16 v[68:83], v[148:151], v[140:143], v[68:83]
	ds_read_b128 v[140:143], v66
	v_or_b32_e32 v66, 0xa0, v200
	v_bitop3_b32 v66, v66, v193, v201 bitop3:0xde
	v_add_u32_e32 v66, 0, v66
	ds_read_b128 v[148:151], v66 offset:8192
	v_and_b32_e32 v152, 32, v86
	v_lshlrev_b32_e32 v86, 2, v192
	s_waitcnt lgkmcnt(0)
	v_mfma_f32_32x32x16_bf16 v[68:83], v[144:147], v[140:143], v[68:83]
	ds_read_b128 v[140:143], v66
	v_or_b32_e32 v66, 0xc0, v200
	v_bitop3_b32 v66, v66, v193, v201 bitop3:0xde
	v_add_u32_e32 v66, 0, v66
	ds_read_b128 v[144:147], v66 offset:8192
	v_and_b32_e32 v153, 0x100, v67
	v_and_or_b32 v67, v67, 24, v87
	s_waitcnt lgkmcnt(0)
	v_mfma_f32_32x32x16_bf16 v[68:83], v[148:151], v[140:143], v[68:83]
	ds_read_b128 v[140:143], v66
	v_or_b32_e32 v66, 0xe0, v200
	v_bitop3_b32 v66, v66, v193, v201 bitop3:0xde
	v_add_u32_e32 v66, 0, v66
	ds_read_b128 v[148:151], v66 offset:8192
	v_cmp_le_u32_e32 vcc, v86, v84
	v_or3_b32 v204, v67, v152, v153
	s_waitcnt lgkmcnt(0)
	v_mfma_f32_32x32x16_bf16 v[68:83], v[144:147], v[140:143], v[68:83]
	ds_read_b128 v[140:143], v66
	v_or_b32_e32 v191, 2, v86
	v_or_b32_e32 v190, 3, v86
	v_or_b32_e32 v189, 8, v86
	v_or_b32_e32 v188, 9, v86
	v_or_b32_e32 v187, 10, v86
	v_lshlrev_b32_e32 v203, 3, v192
	s_waitcnt lgkmcnt(0)
	v_mfma_f32_32x32x16_bf16 v[68:83], v[148:151], v[140:143], v[68:83]
	v_add_u32_e32 v205, 0, v193
	v_or_b32_e32 v186, 11, v86
	v_or_b32_e32 v185, 16, v86
	v_or_b32_e32 v184, 17, v86
	v_or_b32_e32 v183, 18, v86
	v_or_b32_e32 v182, 19, v86
	v_or_b32_e32 v181, 24, v86
	s_nop 4
	v_cvt_pk_bf16_f32 v66, v68, s0
	v_cndmask_b32_e32 v66, 0, v66, vcc
	v_cvt_pk_bf16_f32 v67, v69, s0
	v_cmp_lt_u32_e32 vcc, v86, v84
	v_add3_u32 v69, v205, v201, v203
	ds_read2_b64 v[142:145], v69 offset1:16
	v_cndmask_b32_e32 v67, 0, v67, vcc
	v_perm_b32 v152, v67, v66, s45
	v_cvt_pk_bf16_f32 v66, v70, s0
	v_cmp_le_u32_e32 vcc, v191, v84
	v_cvt_pk_bf16_f32 v67, v71, s0
	v_or_b32_e32 v70, 16, v203
	v_cndmask_b32_e32 v66, 0, v66, vcc
	v_cmp_le_u32_e32 vcc, v190, v84
	v_xad_u32 v70, v70, v201, v205
	s_waitcnt lgkmcnt(0)
	v_mov_b32_e32 v71, v143
	v_cndmask_b32_e32 v67, 0, v67, vcc
	v_perm_b32 v153, v67, v66, s45
	v_cvt_pk_bf16_f32 v66, v72, s0
	v_cmp_le_u32_e32 vcc, v189, v84
	v_cvt_pk_bf16_f32 v67, v73, s0
	ds_read_b64 v[72:73], v70
	v_cndmask_b32_e32 v66, 0, v66, vcc
	v_cmp_le_u32_e32 vcc, v188, v84
	v_mov_b32_e32 v70, v142
	v_cvt_pk_bf16_f32 v68, v54, v55
	v_cndmask_b32_e32 v67, 0, v67, vcc
	v_perm_b32 v154, v67, v66, s45
	v_cvt_pk_bf16_f32 v66, v74, s0
	v_cmp_le_u32_e32 vcc, v187, v84
	v_cvt_pk_bf16_f32 v67, v75, s0
	v_or_b32_e32 v74, 32, v203
	v_cndmask_b32_e32 v66, 0, v66, vcc
	v_cmp_le_u32_e32 vcc, v186, v84
	v_or_b32_e32 v75, 48, v203
	v_cvt_pk_bf16_f32 v69, v56, v57
	v_cndmask_b32_e32 v67, 0, v67, vcc
	v_perm_b32 v155, v67, v66, s45
	v_cvt_pk_bf16_f32 v66, v76, s0
	v_cmp_le_u32_e32 vcc, v185, v84
	v_cvt_pk_bf16_f32 v67, v77, s0
	v_or_b32_e32 v76, 64, v203
	v_cndmask_b32_e32 v66, 0, v66, vcc
	v_cmp_le_u32_e32 vcc, v184, v84
	v_xad_u32 v74, v74, v201, v205
	v_xad_u32 v75, v75, v201, v205
	v_cndmask_b32_e32 v67, 0, v67, vcc
	v_perm_b32 v140, v67, v66, s45
	v_cvt_pk_bf16_f32 v66, v78, s0
	v_cmp_le_u32_e32 vcc, v183, v84
	v_cvt_pk_bf16_f32 v67, v79, s0
	v_xad_u32 v76, v76, v201, v205
	v_cndmask_b32_e32 v66, 0, v66, vcc
	v_cmp_le_u32_e32 vcc, v182, v84
	v_cvt_pk_bf16_f32 v151, v81, s0
	ds_read_b64 v[146:147], v74
	ds_read_b64 v[148:149], v75
	ds_read_b64 v[192:193], v76
	v_cndmask_b32_e32 v67, 0, v67, vcc
	v_perm_b32 v141, v67, v66, s45
	v_cvt_pk_bf16_f32 v66, v80, s0
	v_cmp_le_u32_e32 vcc, v181, v84
	v_cvt_pk_bf16_f32 v67, v52, v53
	v_or_b32_e32 v143, 0x50, v203
	v_cndmask_b32_e32 v150, 0, v66, vcc
	v_cvt_pk_bf16_f32 v66, v50, v51
	v_cvt_pk_bf16_f32 v195, v60, v61
	v_cvt_pk_bf16_f32 v196, v62, v63
	s_waitcnt lgkmcnt(0)
	v_mfma_f32_32x32x16_bf16 v[66:81], v[70:73], v[66:69], 0
	v_cvt_pk_bf16_f32 v197, v64, v65
	v_xad_u32 v143, v143, v201, v205
	v_or_b32_e32 v167, 25, v86
	v_cmp_le_u32_e32 vcc, v167, v84
	v_or_b32_e32 v163, 26, v86
	v_or_b32_e32 v87, 27, v86
	v_cndmask_b32_e32 v142, 0, v151, vcc
	v_mfma_f32_32x32x16_bf16 v[66:81], v[146:149], v[194:197], v[66:81]
	ds_read_b64 v[194:195], v143
	v_cvt_pk_bf16_f32 v146, v34, v35
	v_cvt_pk_bf16_f32 v147, v36, v37
	v_cvt_pk_bf16_f32 v148, v38, v39
	v_cvt_pk_bf16_f32 v149, v40, v41
	v_perm_b32 v142, v142, v150, s45
	v_or_b32_e32 v143, 0x60, v203
	s_waitcnt lgkmcnt(0)
	v_mfma_f32_32x32x16_bf16 v[66:81], v[192:195], v[146:149], v[66:81]
	v_or_b32_e32 v150, 0x70, v203
	v_or_b32_e32 v151, 0x90, v203
	v_xad_u32 v143, v143, v201, v205
	v_xad_u32 v150, v150, v201, v205
	v_xad_u32 v151, v151, v201, v205
	ds_read_b64 v[196:197], v143
	ds_read_b64 v[198:199], v150
	ds_read_b64 v[150:151], v151
	v_cvt_pk_bf16_f32 v146, v42, v43
	v_cvt_pk_bf16_f32 v147, v44, v45
	v_cvt_pk_bf16_f32 v148, v46, v47
	v_cvt_pk_bf16_f32 v149, v48, v49
	v_or_b32_e32 v143, 0xa0, v203
	v_xad_u32 v143, v143, v201, v205
	s_waitcnt lgkmcnt(0)
	v_mfma_f32_32x32x16_bf16 v[66:81], v[196:199], v[146:149], v[66:81]
	v_mov_b32_e32 v148, v144
	v_mov_b32_e32 v149, v145
	v_cvt_pk_bf16_f32 v144, v18, v19
	v_cvt_pk_bf16_f32 v145, v20, v21
	v_cvt_pk_bf16_f32 v146, v22, v23
	v_cvt_pk_bf16_f32 v147, v24, v25
	v_or_b32_e32 v192, 0xd0, v203
	v_xad_u32 v194, v192, v201, v205
	v_mfma_f32_32x32x16_bf16 v[66:81], v[148:151], v[144:147], v[66:81]
	v_or_b32_e32 v146, 0xb0, v203
	v_xad_u32 v146, v146, v201, v205
	ds_read_b64 v[148:149], v143
	ds_read_b64 v[150:151], v146
	v_cvt_pk_bf16_f32 v144, v26, v27
	v_cvt_pk_bf16_f32 v145, v28, v29
	v_cvt_pk_bf16_f32 v146, v30, v31
	v_cvt_pk_bf16_f32 v147, v32, v33
	v_or_b32_e32 v143, 0xc0, v203
	v_xad_u32 v143, v143, v201, v205
	s_waitcnt lgkmcnt(0)
	v_mfma_f32_32x32x16_bf16 v[66:81], v[148:151], v[144:147], v[66:81]
	ds_read_b64 v[192:193], v143
	ds_read_b64 v[194:195], v194
	v_cvt_pk_bf16_f32 v82, v82, s0
	v_cmp_le_u32_e32 vcc, v163, v84
	v_cvt_pk_bf16_f32 v83, v83, s0
	v_cvt_pk_bf16_f32 v144, v2, v3
	v_cndmask_b32_e32 v82, 0, v82, vcc
	v_cmp_le_u32_e32 vcc, v87, v84
	v_cvt_pk_bf16_f32 v145, v4, v5
	v_cvt_pk_bf16_f32 v146, v6, v7
	v_cvt_pk_bf16_f32 v147, v8, v9
	v_cndmask_b32_e32 v83, 0, v83, vcc
	v_perm_b32 v143, v83, v82, s45
	s_waitcnt lgkmcnt(0)
	v_mfma_f32_32x32x16_bf16 v[66:81], v[192:195], v[144:147], v[66:81]
	v_or_b32_e32 v82, 0xe0, v203
	v_xad_u32 v82, v82, v201, v205
	v_or_b32_e32 v83, 0xf0, v203
	v_xad_u32 v83, v83, v201, v205
	ds_read_b64 v[144:145], v82
	ds_read_b64 v[146:147], v83
	v_cvt_pk_bf16_f32 v148, v10, v11
	v_cvt_pk_bf16_f32 v149, v12, v13
	v_cvt_pk_bf16_f32 v150, v14, v15
	v_cvt_pk_bf16_f32 v151, v16, v17
	v_add_u32_e32 v202, s7, v204
	s_add_i32 s14, s20, -2
	s_waitcnt lgkmcnt(0)
	v_mfma_f32_32x32x16_bf16 v[66:81], v[144:147], v[148:151], v[66:81]
	ds_read_b64_tr_b16 v[144:145], v202 offset:0
	ds_read_b64_tr_b16 v[146:147], v202 offset:0x800
	ds_read_b64_tr_b16 v[148:149], v202 offset:0x1000
	ds_read_b64_tr_b16 v[150:151], v202 offset:0x1800
	s_waitcnt lgkmcnt(0)
	v_permlane32_swap_b32_e32 v152, v154
	v_permlane32_swap_b32_e32 v153, v155
	v_permlane32_swap_b32_e32 v140, v142
	v_permlane32_swap_b32_e32 v141, v143
	v_add_u32_e32 v82, 0, v200
	v_add_u32_e32 v83, 0x14400, v82
	v_mfma_f32_32x32x16_bf16 v[66:81], v[152:155], v[144:147], v[66:81]
	ds_read_b128 v[152:155], v83
	v_add_u32_e32 v83, 0x14420, v82
	ds_read_b128 v[192:195], v83
	v_add_u32_e32 v83, 0x14440, v82
	ds_read_b128 v[196:199], v83
	v_add_u32_e32 v83, 0x14460, v82
	ds_read_b128 v[200:203], v83
	s_waitcnt lgkmcnt(0)
	v_pk_mul_f32 v[50:51], v[50:51], v[152:153]
	v_add_u32_e32 v83, s51, v204
	ds_read_b64_tr_b16 v[152:153], v83 offset:0
	v_pk_mul_f32 v[52:53], v[52:53], v[154:155]
	ds_read_b64_tr_b16 v[154:155], v83 offset:0x800
	v_pk_mul_f32 v[54:55], v[54:55], v[192:193]
	ds_read_b64_tr_b16 v[192:193], v83 offset:0x1000
	v_pk_mul_f32 v[56:57], v[56:57], v[194:195]
	ds_read_b64_tr_b16 v[194:195], v83 offset:0x1800
	s_waitcnt lgkmcnt(0)
	v_pk_mul_f32 v[62:63], v[62:63], v[200:201]
	v_pk_mul_f32 v[58:59], v[58:59], v[196:197]
	v_pk_mul_f32 v[64:65], v[64:65], v[202:203]
	v_pk_mul_f32 v[60:61], v[60:61], v[198:199]
	s_nop 1
	v_mfma_f32_32x32x16_bf16 v[50:65], v[152:155], v[144:147], v[50:65]
	v_add_u32_e32 v152, 0x14480, v82
	ds_read_b128 v[152:155], v152
	v_add_u32_e32 v196, 0x144c0, v82
	v_add_u32_e32 v200, 0x144e0, v82
	ds_read_b128 v[196:199], v196
	ds_read_b128 v[200:203], v200
	s_waitcnt lgkmcnt(0)
	v_pk_mul_f32 v[42:43], v[42:43], v[196:197]
	v_mfma_f32_32x32x16_bf16 v[50:65], v[192:195], v[148:151], v[50:65]
	v_add_u32_e32 v192, 0x144a0, v82
	ds_read_b128 v[192:195], v192
	v_mul_f32_e64 v34, v34, v152
	v_mul_f32_e64 v35, v35, v153
	ds_read_b64_tr_b16 v[152:153], v83 offset:0x200
	v_mul_f32_e64 v36, v36, v154
	v_mul_f32_e64 v37, v37, v155
	ds_read_b64_tr_b16 v[154:155], v83 offset:0xa00
	s_waitcnt lgkmcnt(0)
	v_pk_mul_f32 v[38:39], v[38:39], v[192:193]
	ds_read_b64_tr_b16 v[192:193], v83 offset:0x1200
	v_pk_mul_f32 v[40:41], v[40:41], v[194:195]
	ds_read_b64_tr_b16 v[194:195], v83 offset:0x1a00
	s_waitcnt lgkmcnt(0)
	v_pk_mul_f32 v[46:47], v[46:47], v[200:201]
	v_pk_mul_f32 v[48:49], v[48:49], v[202:203]
	v_pk_mul_f32 v[44:45], v[44:45], v[198:199]
	s_nop 1
	v_mfma_f32_32x32x16_bf16 v[34:49], v[152:155], v[144:147], v[34:49]
	v_add_u32_e32 v152, 0x14500, v82
	ds_read_b128 v[152:155], v152
	v_add_u32_e32 v196, 0x14540, v82
	v_add_u32_e32 v200, 0x14560, v82
	ds_read_b128 v[196:199], v196
	ds_read_b128 v[200:203], v200
	s_waitcnt lgkmcnt(0)
	v_pk_mul_f32 v[26:27], v[26:27], v[196:197]
	v_mfma_f32_32x32x16_bf16 v[34:49], v[192:195], v[148:151], v[34:49]
	v_add_u32_e32 v192, 0x14520, v82
	ds_read_b128 v[192:195], v192
	v_mul_f32_e64 v18, v18, v152
	v_mul_f32_e64 v19, v19, v153
	ds_read_b64_tr_b16 v[152:153], v83 offset:0x400
	v_mul_f32_e64 v20, v20, v154
	v_mul_f32_e64 v21, v21, v155
	ds_read_b64_tr_b16 v[154:155], v83 offset:0xc00
	s_waitcnt lgkmcnt(0)
	v_pk_mul_f32 v[22:23], v[22:23], v[192:193]
	ds_read_b64_tr_b16 v[192:193], v83 offset:0x1400
	v_pk_mul_f32 v[24:25], v[24:25], v[194:195]
	ds_read_b64_tr_b16 v[194:195], v83 offset:0x1c00
	s_waitcnt lgkmcnt(0)
	v_pk_mul_f32 v[30:31], v[30:31], v[200:201]
	v_pk_mul_f32 v[32:33], v[32:33], v[202:203]
	v_pk_mul_f32 v[28:29], v[28:29], v[198:199]
	s_nop 1
	v_mfma_f32_32x32x16_bf16 v[18:33], v[152:155], v[144:147], v[18:33]
	v_add_u32_e32 v152, 0x14580, v82
	ds_read_b128 v[152:155], v152
	v_add_u32_e32 v196, 0x145c0, v82
	ds_read_b128 v[196:199], v196
	s_waitcnt lgkmcnt(0)
	v_pk_mul_f32 v[10:11], v[10:11], v[196:197]
	v_mfma_f32_32x32x16_bf16 v[18:33], v[192:195], v[148:151], v[18:33]
	v_add_u32_e32 v192, 0x145a0, v82
	v_add_u32_e32 v82, 0x145e0, v82
	ds_read_b128 v[192:195], v192
	ds_read_b128 v[200:203], v82
	v_mul_f32_e64 v2, v2, v152
	v_mul_f32_e64 v3, v3, v153
	v_pk_mul_f32 v[4:5], v[4:5], v[154:155]
	v_pk_mul_f32 v[12:13], v[12:13], v[198:199]
	v_mfma_f32_32x32x16_bf16 v[66:81], v[140:143], v[148:151], v[66:81]
	ds_read_b64_tr_b16 v[140:141], v83 offset:0x600
	ds_read_b64_tr_b16 v[142:143], v83 offset:0xe00
	ds_read_b64_tr_b16 v[152:153], v83 offset:0x1600
	ds_read_b64_tr_b16 v[154:155], v83 offset:0x1e00
	s_waitcnt lgkmcnt(0)
	v_mul_f32_e64 v14, v14, v200
	v_mul_f32_e64 v15, v15, v201
	v_mul_f32_e64 v6, v6, v192
	v_mul_f32_e64 v7, v7, v193
	v_pk_mul_f32 v[16:17], v[16:17], v[202:203]
	v_pk_mul_f32 v[8:9], v[8:9], v[194:195]
	s_add_i32 s15, s48, -1
	s_and_b64 s[0:1], s[12:13], exec
	s_cselect_b32 s0, s14, s15
	v_lshlrev_b32_e32 v84, 1, v84
	s_lshl_b32 s0, s0, 5
	v_lshl_add_u64 v[82:83], s[28:29], 0, v[84:85]
	v_xor_b32_e32 v84, 31, v86
	s_add_i32 s0, s0, s47
	v_cndmask_b32_e64 v84, v84, v86, s[12:13]
	v_or_b32_e32 v84, s0, v84
	v_lshlrev_b32_e32 v84, 11, v84
	v_mfma_f32_32x32x16_bf16 v[2:17], v[140:143], v[144:147], v[2:17]
	v_cvt_pk_bf16_f32 v66, v66, s0
	v_lshl_add_u64 v[140:141], v[82:83], 0, v[84:85]
	global_store_short v[140:141], v66, off
	v_cvt_pk_bf16_f32 v140, v67, s0
	v_or_b32_e32 v66, 1, v86
	v_xor_b32_e32 v67, 30, v86
	v_cndmask_b32_e64 v66, v67, v66, s[12:13]
	v_or_b32_e32 v66, s0, v66
	v_lshlrev_b32_e32 v84, 11, v66
	v_lshl_add_u64 v[66:67], v[82:83], 0, v[84:85]
	global_store_short v[66:67], v140, off
	v_xor_b32_e32 v66, 29, v86
	v_cndmask_b32_e64 v66, v66, v191, s[12:13]
	v_or_b32_e32 v66, s0, v66
	v_lshlrev_b32_e32 v84, 11, v66
	v_cvt_pk_bf16_f32 v68, v68, s0
	v_lshl_add_u64 v[66:67], v[82:83], 0, v[84:85]
	global_store_short v[66:67], v68, off
	v_xor_b32_e32 v66, 28, v86
	v_cndmask_b32_e64 v66, v66, v190, s[12:13]
	v_or_b32_e32 v66, s0, v66
	v_lshlrev_b32_e32 v84, 11, v66
	v_cvt_pk_bf16_f32 v68, v69, s0
	v_lshl_add_u64 v[66:67], v[82:83], 0, v[84:85]
	global_store_short v[66:67], v68, off
	v_xor_b32_e32 v66, 23, v86
	v_cndmask_b32_e64 v66, v66, v189, s[12:13]
	v_or_b32_e32 v66, s0, v66
	v_lshlrev_b32_e32 v84, 11, v66
	v_cvt_pk_bf16_f32 v68, v70, s0
	v_lshl_add_u64 v[66:67], v[82:83], 0, v[84:85]
	global_store_short v[66:67], v68, off
	v_xor_b32_e32 v66, 22, v86
	v_cndmask_b32_e64 v66, v66, v188, s[12:13]
	v_or_b32_e32 v66, s0, v66
	v_lshlrev_b32_e32 v84, 11, v66
	v_cvt_pk_bf16_f32 v68, v71, s0
	v_lshl_add_u64 v[66:67], v[82:83], 0, v[84:85]
	global_store_short v[66:67], v68, off
	v_xor_b32_e32 v66, 21, v86
	v_cndmask_b32_e64 v66, v66, v187, s[12:13]
	v_or_b32_e32 v66, s0, v66
	v_lshlrev_b32_e32 v84, 11, v66
	v_cvt_pk_bf16_f32 v68, v72, s0
	v_lshl_add_u64 v[66:67], v[82:83], 0, v[84:85]
	global_store_short v[66:67], v68, off
	v_xor_b32_e32 v66, 20, v86
	v_cndmask_b32_e64 v66, v66, v186, s[12:13]
	v_or_b32_e32 v66, s0, v66
	v_lshlrev_b32_e32 v84, 11, v66
	v_cvt_pk_bf16_f32 v68, v73, s0
	v_lshl_add_u64 v[66:67], v[82:83], 0, v[84:85]
	global_store_short v[66:67], v68, off
	v_xor_b32_e32 v66, 15, v86
	v_cndmask_b32_e64 v66, v66, v185, s[12:13]
	v_or_b32_e32 v66, s0, v66
	v_lshlrev_b32_e32 v84, 11, v66
	v_cvt_pk_bf16_f32 v68, v74, s0
	v_lshl_add_u64 v[66:67], v[82:83], 0, v[84:85]
	global_store_short v[66:67], v68, off
	v_xor_b32_e32 v66, 14, v86
	v_cndmask_b32_e64 v66, v66, v184, s[12:13]
	v_or_b32_e32 v66, s0, v66
	v_lshlrev_b32_e32 v84, 11, v66
	v_cvt_pk_bf16_f32 v68, v75, s0
	v_lshl_add_u64 v[66:67], v[82:83], 0, v[84:85]
	global_store_short v[66:67], v68, off
	v_xor_b32_e32 v66, 13, v86
	v_cndmask_b32_e64 v66, v66, v183, s[12:13]
	v_or_b32_e32 v66, s0, v66
	v_lshlrev_b32_e32 v84, 11, v66
	v_cvt_pk_bf16_f32 v68, v76, s0
	v_lshl_add_u64 v[66:67], v[82:83], 0, v[84:85]
	global_store_short v[66:67], v68, off
	v_xor_b32_e32 v66, 12, v86
	v_cndmask_b32_e64 v66, v66, v182, s[12:13]
	v_or_b32_e32 v66, s0, v66
	v_lshlrev_b32_e32 v84, 11, v66
	v_cvt_pk_bf16_f32 v68, v77, s0
	v_lshl_add_u64 v[66:67], v[82:83], 0, v[84:85]
	global_store_short v[66:67], v68, off
	v_xor_b32_e32 v66, 7, v86
	v_cndmask_b32_e64 v66, v66, v181, s[12:13]
	v_or_b32_e32 v66, s0, v66
	v_lshlrev_b32_e32 v84, 11, v66
	v_cvt_pk_bf16_f32 v68, v78, s0
	v_lshl_add_u64 v[66:67], v[82:83], 0, v[84:85]
	global_store_short v[66:67], v68, off
	v_xor_b32_e32 v66, 6, v86
	v_cndmask_b32_e64 v66, v66, v167, s[12:13]
	v_or_b32_e32 v66, s0, v66
	v_lshlrev_b32_e32 v84, 11, v66
	v_cvt_pk_bf16_f32 v68, v79, s0
	v_lshl_add_u64 v[66:67], v[82:83], 0, v[84:85]
	global_store_short v[66:67], v68, off
	v_xor_b32_e32 v66, 5, v86
	v_cndmask_b32_e64 v66, v66, v163, s[12:13]
	v_mfma_f32_32x32x16_bf16 v[2:17], v[152:155], v[148:151], v[2:17]
	v_or_b32_e32 v66, s0, v66
	v_lshlrev_b32_e32 v84, 11, v66
	v_cvt_pk_bf16_f32 v68, v80, s0
	v_lshl_add_u64 v[66:67], v[82:83], 0, v[84:85]
	global_store_short v[66:67], v68, off
	v_xor_b32_e32 v66, 4, v86
	v_cndmask_b32_e64 v66, v66, v87, s[12:13]
	v_or_b32_e32 v66, s0, v66
	v_lshlrev_b32_e32 v84, 11, v66
	s_add_i32 s20, s20, 2
	s_add_i32 s48, s48, -2
	v_cvt_pk_bf16_f32 v68, v81, s0
	v_lshl_add_u64 v[66:67], v[82:83], 0, v[84:85]
	s_cmp_gt_u32 s49, 61
	global_store_short v[66:67], v68, off
	s_cbranch_scc1 .LBB0_960

.LBB0_977:
	v_mov_b32_e32 v86, v159
	s_waitcnt lgkmcnt(0)
	s_barrier
	v_cvt_pk_bf16_f32 v194, v58, v59
	v_and_b32_e32 v84, 31, v86
	v_bfe_u32 v192, v86, 5, 1
	v_lshlrev_b32_e32 v87, 4, v86
	v_lshlrev_b32_e32 v200, 4, v192
	v_lshlrev_b32_e32 v193, 8, v84
	v_and_b32_e32 v201, 0x70, v87
	v_bitop3_b32 v66, v201, v193, v200 bitop3:0xde
	v_add_u32_e32 v70, 0, v66
	ds_read_b128 v[66:69], v70 offset:8192
	ds_read_b128 v[70:73], v70
	s_waitcnt lgkmcnt(0)
	v_mfma_f32_32x32x16_bf16 v[68:83], v[66:69], v[70:73], 0
	v_or_b32_e32 v66, 32, v200
	v_bitop3_b32 v66, v66, v193, v201 bitop3:0xde
	v_add_u32_e32 v66, 0, v66
	ds_read_b128 v[140:143], v66 offset:8192
	ds_read_b128 v[144:147], v66
	v_or_b32_e32 v66, 64, v200
	v_bitop3_b32 v66, v66, v193, v201 bitop3:0xde
	v_add_u32_e32 v66, 0, v66
	s_waitcnt lgkmcnt(0)
	v_mfma_f32_32x32x16_bf16 v[68:83], v[140:143], v[144:147], v[68:83]
	ds_read_b128 v[140:143], v66 offset:8192
	ds_read_b128 v[144:147], v66
	v_or_b32_e32 v66, 0x60, v200
	v_bitop3_b32 v66, v66, v193, v201 bitop3:0xde
	v_add_u32_e32 v66, 0, v66
	ds_read_b128 v[148:151], v66 offset:8192
	v_and_b32_e32 v67, 63, v86
	v_lshlrev_b32_e32 v67, 3, v67
	s_waitcnt lgkmcnt(0)
	v_mfma_f32_32x32x16_bf16 v[68:83], v[140:143], v[144:147], v[68:83]
	ds_read_b128 v[140:143], v66
	v_or_b32_e32 v66, 0x80, v200
	v_bitop3_b32 v66, v66, v193, v201 bitop3:0xde
	v_add_u32_e32 v66, 0, v66
	ds_read_b128 v[144:147], v66 offset:8192
	v_and_b32_e32 v87, 0xc0, v87
	v_and_b32_e32 v153, 0x100, v67
	s_waitcnt lgkmcnt(0)
	v_mfma_f32_32x32x16_bf16 v[68:83], v[148:151], v[140:143], v[68:83]
	ds_read_b128 v[140:143], v66
	v_or_b32_e32 v66, 0xa0, v200
	v_bitop3_b32 v66, v66, v193, v201 bitop3:0xde
	v_add_u32_e32 v66, 0, v66
	ds_read_b128 v[148:151], v66 offset:8192
	v_lshlrev_b32_e32 v86, 1, v86
	v_and_b32_e32 v152, 32, v86
	s_waitcnt lgkmcnt(0)
	v_mfma_f32_32x32x16_bf16 v[68:83], v[144:147], v[140:143], v[68:83]
	ds_read_b128 v[140:143], v66
	v_or_b32_e32 v66, 0xc0, v200
	v_bitop3_b32 v66, v66, v193, v201 bitop3:0xde
	v_add_u32_e32 v66, 0, v66
	ds_read_b128 v[144:147], v66 offset:8192
	v_lshlrev_b32_e32 v86, 2, v192
	v_cmp_le_u32_e32 vcc, v86, v84
	s_waitcnt lgkmcnt(0)
	v_mfma_f32_32x32x16_bf16 v[68:83], v[148:151], v[140:143], v[68:83]
	ds_read_b128 v[140:143], v66
	v_or_b32_e32 v148, 0xe0, v200
	v_and_or_b32 v66, v67, 24, v87
	v_bitop3_b32 v67, v148, v193, v201 bitop3:0xde
	v_add_u32_e32 v67, 0, v67
	ds_read_b128 v[148:151], v67 offset:8192
	v_or3_b32 v204, v66, v152, v153
	s_waitcnt lgkmcnt(0)
	v_mfma_f32_32x32x16_bf16 v[68:83], v[144:147], v[140:143], v[68:83]
	ds_read_b128 v[140:143], v67
	v_or_b32_e32 v191, 2, v86
	v_or_b32_e32 v190, 3, v86
	v_or_b32_e32 v189, 8, v86
	v_or_b32_e32 v188, 9, v86
	v_or_b32_e32 v187, 10, v86
	v_lshlrev_b32_e32 v203, 3, v192
	s_waitcnt lgkmcnt(0)
	v_mfma_f32_32x32x16_bf16 v[68:83], v[148:151], v[140:143], v[68:83]
	v_add_u32_e32 v205, 0, v193
	v_or_b32_e32 v186, 11, v86
	v_or_b32_e32 v185, 16, v86
	v_or_b32_e32 v184, 17, v86
	v_or_b32_e32 v183, 18, v86
	v_or_b32_e32 v182, 19, v86
	v_or_b32_e32 v181, 24, v86
	s_nop 4
	v_cvt_pk_bf16_f32 v66, v68, s0
	v_cndmask_b32_e32 v66, 0, v66, vcc
	v_cvt_pk_bf16_f32 v67, v69, s0
	v_cmp_lt_u32_e32 vcc, v86, v84
	v_add3_u32 v69, v205, v201, v203
	ds_read2_b64 v[142:145], v69 offset1:16
	v_cndmask_b32_e32 v67, 0, v67, vcc
	v_perm_b32 v152, v67, v66, s45
	v_cvt_pk_bf16_f32 v66, v70, s0
	v_cmp_le_u32_e32 vcc, v191, v84
	v_cvt_pk_bf16_f32 v67, v71, s0
	v_or_b32_e32 v70, 16, v203
	v_cndmask_b32_e32 v66, 0, v66, vcc
	v_cmp_le_u32_e32 vcc, v190, v84
	v_xad_u32 v70, v70, v201, v205
	s_waitcnt lgkmcnt(0)
	v_mov_b32_e32 v71, v143
	v_cndmask_b32_e32 v67, 0, v67, vcc
	v_perm_b32 v153, v67, v66, s45
	v_cvt_pk_bf16_f32 v66, v72, s0
	v_cmp_le_u32_e32 vcc, v189, v84
	v_cvt_pk_bf16_f32 v67, v73, s0
	ds_read_b64 v[72:73], v70
	v_cndmask_b32_e32 v66, 0, v66, vcc
	v_cmp_le_u32_e32 vcc, v188, v84
	v_mov_b32_e32 v70, v142
	v_cvt_pk_bf16_f32 v68, v54, v55
	v_cndmask_b32_e32 v67, 0, v67, vcc
	v_perm_b32 v154, v67, v66, s45
	v_cvt_pk_bf16_f32 v66, v74, s0
	v_cmp_le_u32_e32 vcc, v187, v84
	v_cvt_pk_bf16_f32 v67, v75, s0
	v_or_b32_e32 v74, 32, v203
	v_cndmask_b32_e32 v66, 0, v66, vcc
	v_cmp_le_u32_e32 vcc, v186, v84
	v_or_b32_e32 v75, 48, v203
	v_cvt_pk_bf16_f32 v69, v56, v57
	v_cndmask_b32_e32 v67, 0, v67, vcc
	v_perm_b32 v155, v67, v66, s45
	v_cvt_pk_bf16_f32 v66, v76, s0
	v_cmp_le_u32_e32 vcc, v185, v84
	v_cvt_pk_bf16_f32 v67, v77, s0
	v_or_b32_e32 v76, 64, v203
	v_cndmask_b32_e32 v66, 0, v66, vcc
	v_cmp_le_u32_e32 vcc, v184, v84
	v_xad_u32 v74, v74, v201, v205
	v_xad_u32 v75, v75, v201, v205
	v_cndmask_b32_e32 v67, 0, v67, vcc
	v_perm_b32 v140, v67, v66, s45
	v_cvt_pk_bf16_f32 v66, v78, s0
	v_cmp_le_u32_e32 vcc, v183, v84
	v_cvt_pk_bf16_f32 v67, v79, s0
	v_xad_u32 v76, v76, v201, v205
	v_cndmask_b32_e32 v66, 0, v66, vcc
	v_cmp_le_u32_e32 vcc, v182, v84
	v_cvt_pk_bf16_f32 v151, v81, s0
	ds_read_b64 v[146:147], v74
	ds_read_b64 v[148:149], v75
	ds_read_b64 v[192:193], v76
	v_cndmask_b32_e32 v67, 0, v67, vcc
	v_perm_b32 v141, v67, v66, s45
	v_cvt_pk_bf16_f32 v66, v80, s0
	v_cmp_le_u32_e32 vcc, v181, v84
	v_cvt_pk_bf16_f32 v67, v52, v53
	v_or_b32_e32 v143, 0x50, v203
	v_cndmask_b32_e32 v150, 0, v66, vcc
	v_cvt_pk_bf16_f32 v66, v50, v51
	v_cvt_pk_bf16_f32 v195, v60, v61
	v_cvt_pk_bf16_f32 v196, v62, v63
	s_waitcnt lgkmcnt(0)
	v_mfma_f32_32x32x16_bf16 v[66:81], v[70:73], v[66:69], 0
	v_cvt_pk_bf16_f32 v197, v64, v65
	v_xad_u32 v143, v143, v201, v205
	v_or_b32_e32 v167, 25, v86
	v_cmp_le_u32_e32 vcc, v167, v84
	v_or_b32_e32 v163, 26, v86
	v_or_b32_e32 v87, 27, v86
	v_cndmask_b32_e32 v142, 0, v151, vcc
	v_mfma_f32_32x32x16_bf16 v[66:81], v[146:149], v[194:197], v[66:81]
	ds_read_b64 v[194:195], v143
	v_cvt_pk_bf16_f32 v146, v34, v35
	v_cvt_pk_bf16_f32 v147, v36, v37
	v_cvt_pk_bf16_f32 v148, v38, v39
	v_cvt_pk_bf16_f32 v149, v40, v41
	v_perm_b32 v142, v142, v150, s45
	v_or_b32_e32 v143, 0x60, v203
	s_waitcnt lgkmcnt(0)
	v_mfma_f32_32x32x16_bf16 v[66:81], v[192:195], v[146:149], v[66:81]
	v_or_b32_e32 v150, 0x70, v203
	v_or_b32_e32 v151, 0x90, v203
	v_xad_u32 v143, v143, v201, v205
	v_xad_u32 v150, v150, v201, v205
	v_xad_u32 v151, v151, v201, v205
	ds_read_b64 v[196:197], v143
	ds_read_b64 v[198:199], v150
	ds_read_b64 v[150:151], v151
	v_cvt_pk_bf16_f32 v146, v42, v43
	v_cvt_pk_bf16_f32 v147, v44, v45
	v_cvt_pk_bf16_f32 v148, v46, v47
	v_cvt_pk_bf16_f32 v149, v48, v49
	v_or_b32_e32 v143, 0xa0, v203
	v_xad_u32 v143, v143, v201, v205
	s_waitcnt lgkmcnt(0)
	v_mfma_f32_32x32x16_bf16 v[66:81], v[196:199], v[146:149], v[66:81]
	v_mov_b32_e32 v148, v144
	v_mov_b32_e32 v149, v145
	v_cvt_pk_bf16_f32 v144, v18, v19
	v_cvt_pk_bf16_f32 v145, v20, v21
	v_cvt_pk_bf16_f32 v146, v22, v23
	v_cvt_pk_bf16_f32 v147, v24, v25
	v_or_b32_e32 v192, 0xd0, v203
	v_xad_u32 v194, v192, v201, v205
	v_mfma_f32_32x32x16_bf16 v[66:81], v[148:151], v[144:147], v[66:81]
	v_or_b32_e32 v146, 0xb0, v203
	v_xad_u32 v146, v146, v201, v205
	ds_read_b64 v[148:149], v143
	ds_read_b64 v[150:151], v146
	v_cvt_pk_bf16_f32 v144, v26, v27
	v_cvt_pk_bf16_f32 v145, v28, v29
	v_cvt_pk_bf16_f32 v146, v30, v31
	v_cvt_pk_bf16_f32 v147, v32, v33
	v_or_b32_e32 v143, 0xc0, v203
	v_xad_u32 v143, v143, v201, v205
	s_waitcnt lgkmcnt(0)
	v_mfma_f32_32x32x16_bf16 v[66:81], v[148:151], v[144:147], v[66:81]
	ds_read_b64 v[192:193], v143
	ds_read_b64 v[194:195], v194
	v_cvt_pk_bf16_f32 v82, v82, s0
	v_cmp_le_u32_e32 vcc, v163, v84
	v_cvt_pk_bf16_f32 v83, v83, s0
	v_cvt_pk_bf16_f32 v144, v2, v3
	v_cndmask_b32_e32 v82, 0, v82, vcc
	v_cmp_le_u32_e32 vcc, v87, v84
	v_cvt_pk_bf16_f32 v145, v4, v5
	v_cvt_pk_bf16_f32 v146, v6, v7
	v_cvt_pk_bf16_f32 v147, v8, v9
	v_cndmask_b32_e32 v83, 0, v83, vcc
	v_perm_b32 v143, v83, v82, s45
	s_waitcnt lgkmcnt(0)
	v_mfma_f32_32x32x16_bf16 v[66:81], v[192:195], v[144:147], v[66:81]
	v_or_b32_e32 v82, 0xe0, v203
	v_xad_u32 v82, v82, v201, v205
	v_or_b32_e32 v83, 0xf0, v203
	v_xad_u32 v83, v83, v201, v205
	ds_read_b64 v[144:145], v82
	ds_read_b64 v[146:147], v83
	v_cvt_pk_bf16_f32 v148, v10, v11
	v_cvt_pk_bf16_f32 v149, v12, v13
	v_cvt_pk_bf16_f32 v150, v14, v15
	v_cvt_pk_bf16_f32 v151, v16, v17
	v_add_u32_e32 v202, s7, v204
	v_permlane32_swap_b32_e32 v152, v154
	s_waitcnt lgkmcnt(0)
	v_mfma_f32_32x32x16_bf16 v[66:81], v[144:147], v[148:151], v[66:81]
	ds_read_b64_tr_b16 v[144:145], v202 offset:0
	ds_read_b64_tr_b16 v[146:147], v202 offset:0x800
	ds_read_b64_tr_b16 v[148:149], v202 offset:0x1000
	ds_read_b64_tr_b16 v[150:151], v202 offset:0x1800
	s_waitcnt lgkmcnt(0)
	v_permlane32_swap_b32_e32 v153, v155
	v_permlane32_swap_b32_e32 v140, v142
	v_permlane32_swap_b32_e32 v141, v143
	v_add_u32_e32 v82, 0, v200
	v_add_u32_e32 v83, 0x14200, v82
	v_mfma_f32_32x32x16_bf16 v[66:81], v[152:155], v[144:147], v[66:81]
	ds_read_b128 v[152:155], v83
	v_add_u32_e32 v83, 0x14220, v82
	ds_read_b128 v[192:195], v83
	v_add_u32_e32 v83, 0x14240, v82
	ds_read_b128 v[196:199], v83
	v_add_u32_e32 v83, 0x14260, v82
	s_add_i32 s51, 0, 0x4000
	ds_read_b128 v[200:203], v83
	s_waitcnt lgkmcnt(0)
	v_pk_mul_f32 v[50:51], v[50:51], v[152:153]
	v_add_u32_e32 v83, s51, v204
	ds_read_b64_tr_b16 v[152:153], v83 offset:0
	v_pk_mul_f32 v[52:53], v[52:53], v[154:155]
	ds_read_b64_tr_b16 v[154:155], v83 offset:0x800
	v_pk_mul_f32 v[54:55], v[54:55], v[192:193]
	ds_read_b64_tr_b16 v[192:193], v83 offset:0x1000
	v_pk_mul_f32 v[56:57], v[56:57], v[194:195]
	ds_read_b64_tr_b16 v[194:195], v83 offset:0x1800
	s_waitcnt lgkmcnt(0)
	v_pk_mul_f32 v[62:63], v[62:63], v[200:201]
	v_pk_mul_f32 v[58:59], v[58:59], v[196:197]
	v_pk_mul_f32 v[64:65], v[64:65], v[202:203]
	v_pk_mul_f32 v[60:61], v[60:61], v[198:199]
	s_nop 1
	v_mfma_f32_32x32x16_bf16 v[50:65], v[152:155], v[144:147], v[50:65]
	v_add_u32_e32 v152, 0x14280, v82
	ds_read_b128 v[152:155], v152
	v_add_u32_e32 v196, 0x142c0, v82
	v_add_u32_e32 v200, 0x142e0, v82
	ds_read_b128 v[196:199], v196
	ds_read_b128 v[200:203], v200
	s_waitcnt lgkmcnt(0)
	v_pk_mul_f32 v[42:43], v[42:43], v[196:197]
	v_mfma_f32_32x32x16_bf16 v[50:65], v[192:195], v[148:151], v[50:65]
	v_add_u32_e32 v192, 0x142a0, v82
	ds_read_b128 v[192:195], v192
	v_mul_f32_e64 v34, v34, v152
	v_mul_f32_e64 v35, v35, v153
	ds_read_b64_tr_b16 v[152:153], v83 offset:0x200
	v_mul_f32_e64 v36, v36, v154
	v_mul_f32_e64 v37, v37, v155
	ds_read_b64_tr_b16 v[154:155], v83 offset:0xa00
	s_waitcnt lgkmcnt(0)
	v_pk_mul_f32 v[38:39], v[38:39], v[192:193]
	ds_read_b64_tr_b16 v[192:193], v83 offset:0x1200
	v_pk_mul_f32 v[40:41], v[40:41], v[194:195]
	ds_read_b64_tr_b16 v[194:195], v83 offset:0x1a00
	s_waitcnt lgkmcnt(0)
	v_pk_mul_f32 v[46:47], v[46:47], v[200:201]
	v_pk_mul_f32 v[48:49], v[48:49], v[202:203]
	v_pk_mul_f32 v[44:45], v[44:45], v[198:199]
	s_nop 1
	v_mfma_f32_32x32x16_bf16 v[34:49], v[152:155], v[144:147], v[34:49]
	v_add_u32_e32 v152, 0x14300, v82
	ds_read_b128 v[152:155], v152
	v_add_u32_e32 v196, 0x14340, v82
	v_add_u32_e32 v200, 0x14360, v82
	ds_read_b128 v[196:199], v196
	ds_read_b128 v[200:203], v200
	s_waitcnt lgkmcnt(0)
	v_pk_mul_f32 v[26:27], v[26:27], v[196:197]
	v_mfma_f32_32x32x16_bf16 v[34:49], v[192:195], v[148:151], v[34:49]
	v_add_u32_e32 v192, 0x14320, v82
	ds_read_b128 v[192:195], v192
	v_mul_f32_e64 v18, v18, v152
	v_mul_f32_e64 v19, v19, v153
	ds_read_b64_tr_b16 v[152:153], v83 offset:0x400
	v_mul_f32_e64 v20, v20, v154
	v_mul_f32_e64 v21, v21, v155
	ds_read_b64_tr_b16 v[154:155], v83 offset:0xc00
	s_waitcnt lgkmcnt(0)
	v_pk_mul_f32 v[22:23], v[22:23], v[192:193]
	ds_read_b64_tr_b16 v[192:193], v83 offset:0x1400
	v_pk_mul_f32 v[24:25], v[24:25], v[194:195]
	ds_read_b64_tr_b16 v[194:195], v83 offset:0x1c00
	s_waitcnt lgkmcnt(0)
	v_pk_mul_f32 v[30:31], v[30:31], v[200:201]
	v_pk_mul_f32 v[32:33], v[32:33], v[202:203]
	v_pk_mul_f32 v[28:29], v[28:29], v[198:199]
	s_nop 1
	v_mfma_f32_32x32x16_bf16 v[18:33], v[152:155], v[144:147], v[18:33]
	v_add_u32_e32 v152, 0x14380, v82
	ds_read_b128 v[152:155], v152
	v_add_u32_e32 v196, 0x143c0, v82
	ds_read_b128 v[196:199], v196
	s_waitcnt lgkmcnt(0)
	v_pk_mul_f32 v[10:11], v[10:11], v[196:197]
	v_mfma_f32_32x32x16_bf16 v[18:33], v[192:195], v[148:151], v[18:33]
	v_add_u32_e32 v192, 0x143a0, v82
	v_add_u32_e32 v82, 0x143e0, v82
	ds_read_b128 v[192:195], v192
	ds_read_b128 v[200:203], v82
	v_mul_f32_e64 v2, v2, v152
	v_mul_f32_e64 v3, v3, v153
	v_pk_mul_f32 v[4:5], v[4:5], v[154:155]
	v_pk_mul_f32 v[12:13], v[12:13], v[198:199]
	v_mfma_f32_32x32x16_bf16 v[66:81], v[140:143], v[148:151], v[66:81]
	ds_read_b64_tr_b16 v[140:141], v83 offset:0x600
	ds_read_b64_tr_b16 v[142:143], v83 offset:0xe00
	ds_read_b64_tr_b16 v[152:153], v83 offset:0x1600
	ds_read_b64_tr_b16 v[154:155], v83 offset:0x1e00
	s_waitcnt lgkmcnt(0)
	v_mul_f32_e64 v14, v14, v200
	v_mul_f32_e64 v15, v15, v201
	v_mul_f32_e64 v6, v6, v192
	v_mul_f32_e64 v7, v7, v193
	v_pk_mul_f32 v[16:17], v[16:17], v[202:203]
	v_pk_mul_f32 v[8:9], v[8:9], v[194:195]
	s_and_b64 s[0:1], s[12:13], exec
	s_cselect_b32 s0, s49, s48
	v_lshlrev_b32_e32 v84, 1, v84
	s_lshl_b32 s0, s0, 5
	v_lshl_add_u64 v[82:83], s[28:29], 0, v[84:85]
	v_xor_b32_e32 v84, 31, v86
	s_add_i32 s0, s0, s47
	v_cndmask_b32_e64 v84, v84, v86, s[12:13]
	v_or_b32_e32 v84, s0, v84
	v_lshlrev_b32_e32 v84, 11, v84
	v_mfma_f32_32x32x16_bf16 v[2:17], v[140:143], v[144:147], v[2:17]
	v_cvt_pk_bf16_f32 v66, v66, s0
	v_lshl_add_u64 v[140:141], v[82:83], 0, v[84:85]
	global_store_short v[140:141], v66, off
	v_cvt_pk_bf16_f32 v140, v67, s0
	v_or_b32_e32 v66, 1, v86
	v_xor_b32_e32 v67, 30, v86
	v_cndmask_b32_e64 v66, v67, v66, s[12:13]
	v_or_b32_e32 v66, s0, v66
	v_lshlrev_b32_e32 v84, 11, v66
	v_lshl_add_u64 v[66:67], v[82:83], 0, v[84:85]
	global_store_short v[66:67], v140, off
	v_xor_b32_e32 v66, 29, v86
	v_cndmask_b32_e64 v66, v66, v191, s[12:13]
	v_or_b32_e32 v66, s0, v66
	v_lshlrev_b32_e32 v84, 11, v66
	v_cvt_pk_bf16_f32 v68, v68, s0
	v_lshl_add_u64 v[66:67], v[82:83], 0, v[84:85]
	global_store_short v[66:67], v68, off
	v_xor_b32_e32 v66, 28, v86
	v_cndmask_b32_e64 v66, v66, v190, s[12:13]
	v_or_b32_e32 v66, s0, v66
	v_lshlrev_b32_e32 v84, 11, v66
	v_cvt_pk_bf16_f32 v68, v69, s0
	v_lshl_add_u64 v[66:67], v[82:83], 0, v[84:85]
	global_store_short v[66:67], v68, off
	v_xor_b32_e32 v66, 23, v86
	v_cndmask_b32_e64 v66, v66, v189, s[12:13]
	v_or_b32_e32 v66, s0, v66
	v_lshlrev_b32_e32 v84, 11, v66
	v_cvt_pk_bf16_f32 v68, v70, s0
	v_lshl_add_u64 v[66:67], v[82:83], 0, v[84:85]
	global_store_short v[66:67], v68, off
	v_xor_b32_e32 v66, 22, v86
	v_cndmask_b32_e64 v66, v66, v188, s[12:13]
	v_or_b32_e32 v66, s0, v66
	v_lshlrev_b32_e32 v84, 11, v66
	v_cvt_pk_bf16_f32 v68, v71, s0
	v_lshl_add_u64 v[66:67], v[82:83], 0, v[84:85]
	global_store_short v[66:67], v68, off
	v_xor_b32_e32 v66, 21, v86
	v_cndmask_b32_e64 v66, v66, v187, s[12:13]
	v_or_b32_e32 v66, s0, v66
	v_lshlrev_b32_e32 v84, 11, v66
	v_cvt_pk_bf16_f32 v68, v72, s0
	v_lshl_add_u64 v[66:67], v[82:83], 0, v[84:85]
	global_store_short v[66:67], v68, off
	v_xor_b32_e32 v66, 20, v86
	v_cndmask_b32_e64 v66, v66, v186, s[12:13]
	v_or_b32_e32 v66, s0, v66
	v_lshlrev_b32_e32 v84, 11, v66
	v_cvt_pk_bf16_f32 v68, v73, s0
	v_lshl_add_u64 v[66:67], v[82:83], 0, v[84:85]
	global_store_short v[66:67], v68, off
	v_xor_b32_e32 v66, 15, v86
	v_cndmask_b32_e64 v66, v66, v185, s[12:13]
	v_or_b32_e32 v66, s0, v66
	v_lshlrev_b32_e32 v84, 11, v66
	v_cvt_pk_bf16_f32 v68, v74, s0
	v_lshl_add_u64 v[66:67], v[82:83], 0, v[84:85]
	global_store_short v[66:67], v68, off
	v_xor_b32_e32 v66, 14, v86
	v_cndmask_b32_e64 v66, v66, v184, s[12:13]
	v_or_b32_e32 v66, s0, v66
	v_lshlrev_b32_e32 v84, 11, v66
	v_cvt_pk_bf16_f32 v68, v75, s0
	v_lshl_add_u64 v[66:67], v[82:83], 0, v[84:85]
	global_store_short v[66:67], v68, off
	v_xor_b32_e32 v66, 13, v86
	v_cndmask_b32_e64 v66, v66, v183, s[12:13]
	v_or_b32_e32 v66, s0, v66
	v_lshlrev_b32_e32 v84, 11, v66
	v_cvt_pk_bf16_f32 v68, v76, s0
	v_lshl_add_u64 v[66:67], v[82:83], 0, v[84:85]
	global_store_short v[66:67], v68, off
	v_xor_b32_e32 v66, 12, v86
	v_cndmask_b32_e64 v66, v66, v182, s[12:13]
	v_or_b32_e32 v66, s0, v66
	v_lshlrev_b32_e32 v84, 11, v66
	v_cvt_pk_bf16_f32 v68, v77, s0
	v_lshl_add_u64 v[66:67], v[82:83], 0, v[84:85]
	global_store_short v[66:67], v68, off
	v_xor_b32_e32 v66, 7, v86
	v_cndmask_b32_e64 v66, v66, v181, s[12:13]
	v_or_b32_e32 v66, s0, v66
	v_lshlrev_b32_e32 v84, 11, v66
	v_cvt_pk_bf16_f32 v68, v78, s0
	v_lshl_add_u64 v[66:67], v[82:83], 0, v[84:85]
	global_store_short v[66:67], v68, off
	v_xor_b32_e32 v66, 6, v86
	v_cndmask_b32_e64 v66, v66, v167, s[12:13]
	v_or_b32_e32 v66, s0, v66
	v_lshlrev_b32_e32 v84, 11, v66
	v_cvt_pk_bf16_f32 v68, v79, s0
	v_lshl_add_u64 v[66:67], v[82:83], 0, v[84:85]
	global_store_short v[66:67], v68, off
	v_xor_b32_e32 v66, 5, v86
	v_cndmask_b32_e64 v66, v66, v163, s[12:13]
	v_mfma_f32_32x32x16_bf16 v[2:17], v[152:155], v[148:151], v[2:17]
	v_or_b32_e32 v66, s0, v66
	v_lshlrev_b32_e32 v84, 11, v66
	v_cvt_pk_bf16_f32 v68, v80, s0
	v_lshl_add_u64 v[66:67], v[82:83], 0, v[84:85]
	global_store_short v[66:67], v68, off
	v_xor_b32_e32 v66, 4, v86
	v_cndmask_b32_e64 v66, v66, v87, s[12:13]
	v_or_b32_e32 v66, s0, v66
	v_lshlrev_b32_e32 v84, 11, v66
	v_cvt_pk_bf16_f32 v68, v81, s0
	v_lshl_add_u64 v[66:67], v[82:83], 0, v[84:85]
	v_mov_b32_e32 v82, v159
	s_and_b64 vcc, exec, s[8:9]
	global_store_short v[66:67], v68, off
	s_cbranch_vccnz .LBB0_981
	v_cvt_pk_bf16_f32 v66, v132, v133
	v_cvt_pk_bf16_f32 v67, v134, v135
	v_cvt_pk_bf16_f32 v68, v136, v137
	v_cvt_pk_bf16_f32 v69, v138, v139
	v_and_b32_e32 v87, 63, v82
	v_and_b32_e32 v83, 31, v82
	v_mfma_f32_32x32x16_bf16 v[66:81], v[66:69], v[128:131], 0
	s_nop 11
	v_add_f32_e32 v66, v180, v66
	v_mul_f32_e64 v84, |v66|, s40
	v_exp_f32_e32 v84, v84
	v_add_f32_e32 v67, v180, v67
	v_mul_f32_e64 v86, |v67|, s40
	v_exp_f32_e32 v86, v86
	v_add_f32_e32 v84, 1.0, v84
	v_cmp_gt_f32_e32 vcc, s41, v84
	v_min_f32_e32 v66, 0, v66
	v_add_f32_e32 v86, 1.0, v86
	v_cndmask_b32_e64 v140, 0, 32, vcc
	v_ldexp_f32 v84, v84, v140
	v_log_f32_e32 v84, v84
	v_cmp_gt_f32_e64 s[14:15], s41, v86
	v_cndmask_b32_e32 v140, 0, v179, vcc
	v_add_f32_e32 v68, v180, v68
	v_cndmask_b32_e64 v141, 0, 32, s[14:15]
	v_ldexp_f32 v86, v86, v141
	v_mul_f32_e32 v141, 0x3f317217, v84
	v_fma_f32 v141, v84, s42, -v141
	v_fmac_f32_e32 v141, 0x3377d1cf, v84
	v_log_f32_e32 v86, v86
	v_fmac_f32_e32 v141, 0x3f317217, v84
	v_cmp_lt_f32_e64 vcc, |v84|, s43
	s_nop 1
	v_cndmask_b32_e32 v84, v84, v141, vcc
	v_sub_f32_e32 v84, v84, v140
	v_sub_f32_e32 v66, v66, v84
	v_fma_f32 v84, v66, s44, 0
	v_min_f32_e32 v66, 0, v67
	v_mul_f32_e32 v67, 0x3f317217, v86
	v_mul_f32_e64 v140, |v68|, s40
	v_fma_f32 v67, v86, s42, -v67
	v_exp_f32_e32 v140, v140
	v_fmac_f32_e32 v67, 0x3377d1cf, v86
	v_fmac_f32_e32 v67, 0x3f317217, v86
	v_cmp_lt_f32_e64 vcc, |v86|, s43
	s_nop 1
	v_cndmask_b32_e32 v67, v86, v67, vcc
	v_cndmask_b32_e64 v86, 0, v179, s[14:15]
	v_sub_f32_e32 v67, v67, v86
	v_add_f32_e32 v86, 1.0, v140
	v_cmp_gt_f32_e32 vcc, s41, v86
	v_sub_f32_e32 v66, v66, v67
	s_nop 0
	v_cndmask_b32_e64 v140, 0, 32, vcc
	v_ldexp_f32 v86, v86, v140
	v_log_f32_e32 v86, v86
	v_fmamk_f32 v140, v66, 0x3d800000, v84
	v_min_f32_e32 v66, 0, v68
	v_add_f32_e32 v68, v180, v69
	v_mul_f32_e64 v69, |v68|, s40
	v_exp_f32_e32 v69, v69
	v_mul_f32_e32 v67, 0x3f317217, v86
	v_fma_f32 v67, v86, s42, -v67
	v_fmac_f32_e32 v67, 0x3377d1cf, v86
	v_fmac_f32_e32 v67, 0x3f317217, v86
	v_cmp_lt_f32_e64 s[14:15], |v86|, s43
	v_add_f32_e32 v69, 1.0, v69
	s_nop 0
	v_cndmask_b32_e64 v67, v86, v67, s[14:15]
	v_cndmask_b32_e32 v86, 0, v179, vcc
	v_cmp_gt_f32_e32 vcc, s41, v69
	v_sub_f32_e32 v67, v67, v86
	v_sub_f32_e32 v66, v66, v67
	v_cndmask_b32_e64 v86, 0, 32, vcc
	v_ldexp_f32 v69, v69, v86
	v_log_f32_e32 v69, v69
	v_fmamk_f32 v86, v66, 0x3d800000, v140
	v_min_f32_e32 v66, 0, v68
	v_add_f32_e32 v68, v180, v70
	v_mul_f32_e32 v67, 0x3f317217, v69
	v_mul_f32_e64 v70, |v68|, s40
	v_fma_f32 v67, v69, s42, -v67
	v_exp_f32_e32 v70, v70
	v_fmac_f32_e32 v67, 0x3377d1cf, v69
	v_fmac_f32_e32 v67, 0x3f317217, v69
	v_cmp_lt_f32_e64 s[14:15], |v69|, s43
	s_nop 1
	v_cndmask_b32_e64 v67, v69, v67, s[14:15]
	v_cndmask_b32_e32 v69, 0, v179, vcc
	v_sub_f32_e32 v67, v67, v69
	v_add_f32_e32 v69, 1.0, v70
	v_cmp_gt_f32_e32 vcc, s41, v69
	v_sub_f32_e32 v66, v66, v67
	v_min_f32_e32 v67, 0, v68
	v_cndmask_b32_e64 v70, 0, 32, vcc
	v_ldexp_f32 v69, v69, v70
	v_log_f32_e32 v69, v69
	v_add_f32_e32 v70, v180, v71
	v_mul_f32_e64 v71, |v70|, s40
	v_exp_f32_e32 v71, v71
	v_mul_f32_e32 v68, 0x3f317217, v69
	v_fma_f32 v68, v69, s42, -v68
	v_fmac_f32_e32 v68, 0x3377d1cf, v69
	v_fmac_f32_e32 v68, 0x3f317217, v69
	v_cmp_lt_f32_e64 s[14:15], |v69|, s43
	v_fmamk_f32 v66, v66, 0x3d800000, v86
	s_nop 0
	v_cndmask_b32_e64 v68, v69, v68, s[14:15]
	v_cndmask_b32_e32 v69, 0, v179, vcc
	v_sub_f32_e32 v68, v68, v69
	v_add_f32_e32 v69, 1.0, v71
	v_cmp_gt_f32_e32 vcc, s41, v69
	v_sub_f32_e32 v67, v67, v68
	v_fma_f32 v141, v67, s44, 0
	v_cndmask_b32_e64 v71, 0, 32, vcc
	v_ldexp_f32 v69, v69, v71
	v_log_f32_e32 v69, v69
	v_min_f32_e32 v67, 0, v70
	v_add_f32_e32 v70, v180, v72
	v_mul_f32_e64 v71, |v70|, s40
	v_mul_f32_e32 v68, 0x3f317217, v69
	v_fma_f32 v68, v69, s42, -v68
	v_exp_f32_e32 v71, v71
	v_fmac_f32_e32 v68, 0x3377d1cf, v69
	v_fmac_f32_e32 v68, 0x3f317217, v69
	v_cmp_lt_f32_e64 s[14:15], |v69|, s43
	s_nop 1
	v_cndmask_b32_e64 v68, v69, v68, s[14:15]
	v_cndmask_b32_e32 v69, 0, v179, vcc
	v_sub_f32_e32 v68, v68, v69
	v_add_f32_e32 v69, 1.0, v71
	v_cmp_gt_f32_e32 vcc, s41, v69
	v_sub_f32_e32 v67, v67, v68
	v_fmamk_f32 v142, v67, 0x3d800000, v141
	v_cndmask_b32_e64 v71, 0, 32, vcc
	v_ldexp_f32 v69, v69, v71
	v_log_f32_e32 v69, v69
	v_min_f32_e32 v67, 0, v70
	v_add_f32_e32 v70, v180, v73
	v_mul_f32_e64 v71, |v70|, s40
	v_mul_f32_e32 v68, 0x3f317217, v69
	v_fma_f32 v68, v69, s42, -v68
	v_exp_f32_e32 v71, v71
	v_fmac_f32_e32 v68, 0x3377d1cf, v69
	v_fmac_f32_e32 v68, 0x3f317217, v69
	v_cmp_lt_f32_e64 s[14:15], |v69|, s43
	s_nop 1
	v_cndmask_b32_e64 v68, v69, v68, s[14:15]
	v_cndmask_b32_e32 v69, 0, v179, vcc
	v_sub_f32_e32 v68, v68, v69
	v_add_f32_e32 v69, 1.0, v71
	v_cmp_gt_f32_e32 vcc, s41, v69
	v_sub_f32_e32 v67, v67, v68
	v_fmamk_f32 v143, v67, 0x3d800000, v142
	v_cndmask_b32_e64 v71, 0, 32, vcc
	v_ldexp_f32 v69, v69, v71
	v_log_f32_e32 v69, v69
	v_min_f32_e32 v67, 0, v70
	v_add_f32_e32 v70, v180, v74
	v_mul_f32_e64 v71, |v70|, s40
	v_mul_f32_e32 v68, 0x3f317217, v69
	v_fma_f32 v68, v69, s42, -v68
	v_exp_f32_e32 v71, v71
	v_fmac_f32_e32 v68, 0x3377d1cf, v69
	v_fmac_f32_e32 v68, 0x3f317217, v69
	v_cmp_lt_f32_e64 s[14:15], |v69|, s43
	s_nop 1
	v_cndmask_b32_e64 v68, v69, v68, s[14:15]
	v_cndmask_b32_e32 v69, 0, v179, vcc
	v_sub_f32_e32 v68, v68, v69
	v_add_f32_e32 v69, 1.0, v71
	v_cmp_gt_f32_e32 vcc, s41, v69
	v_sub_f32_e32 v67, v67, v68
	v_min_f32_e32 v68, 0, v70
	v_cndmask_b32_e64 v71, 0, 32, vcc
	v_ldexp_f32 v69, v69, v71
	v_log_f32_e32 v69, v69
	v_add_f32_e32 v71, v180, v75
	v_mul_f32_e64 v72, |v71|, s40
	v_exp_f32_e32 v72, v72
	v_mul_f32_e32 v70, 0x3f317217, v69
	v_fma_f32 v70, v69, s42, -v70
	v_fmac_f32_e32 v70, 0x3377d1cf, v69
	v_fmac_f32_e32 v70, 0x3f317217, v69
	v_cmp_lt_f32_e64 s[14:15], |v69|, s43
	v_fmamk_f32 v67, v67, 0x3d800000, v143
	s_nop 0
	v_cndmask_b32_e64 v69, v69, v70, s[14:15]
	v_cndmask_b32_e32 v70, 0, v179, vcc
	v_sub_f32_e32 v69, v69, v70
	v_add_f32_e32 v70, 1.0, v72
	v_cmp_gt_f32_e32 vcc, s41, v70
	v_sub_f32_e32 v68, v68, v69
	v_fma_f32 v75, v68, s44, 0
	v_cndmask_b32_e64 v72, 0, 32, vcc
	v_ldexp_f32 v70, v70, v72
	v_log_f32_e32 v70, v70
	v_min_f32_e32 v68, 0, v71
	v_add_f32_e32 v71, v180, v76
	v_mul_f32_e64 v72, |v71|, s40
	v_mul_f32_e32 v69, 0x3f317217, v70
	v_fma_f32 v69, v70, s42, -v69
	v_exp_f32_e32 v72, v72
	v_fmac_f32_e32 v69, 0x3377d1cf, v70
	v_fmac_f32_e32 v69, 0x3f317217, v70
	v_cmp_lt_f32_e64 s[14:15], |v70|, s43
	s_nop 1
	v_cndmask_b32_e64 v69, v70, v69, s[14:15]
	v_cndmask_b32_e32 v70, 0, v179, vcc
	v_sub_f32_e32 v69, v69, v70
	v_add_f32_e32 v70, 1.0, v72
	v_cmp_gt_f32_e32 vcc, s41, v70
	v_sub_f32_e32 v68, v68, v69
	v_fmamk_f32 v76, v68, 0x3d800000, v75
	v_cndmask_b32_e64 v72, 0, 32, vcc
	v_ldexp_f32 v70, v70, v72
	v_log_f32_e32 v70, v70
	v_min_f32_e32 v68, 0, v71
	v_add_f32_e32 v71, v180, v77
	v_mul_f32_e64 v72, |v71|, s40
	v_mul_f32_e32 v69, 0x3f317217, v70
	v_fma_f32 v69, v70, s42, -v69
	v_exp_f32_e32 v72, v72
	v_fmac_f32_e32 v69, 0x3377d1cf, v70
	v_fmac_f32_e32 v69, 0x3f317217, v70
	v_cmp_lt_f32_e64 s[14:15], |v70|, s43
	s_nop 1
	v_cndmask_b32_e64 v69, v70, v69, s[14:15]
	v_cndmask_b32_e32 v70, 0, v179, vcc
	v_sub_f32_e32 v69, v69, v70
	v_add_f32_e32 v70, 1.0, v72
	v_cmp_gt_f32_e32 vcc, s41, v70
	v_sub_f32_e32 v68, v68, v69
	v_fmamk_f32 v77, v68, 0x3d800000, v76
	v_cndmask_b32_e64 v72, 0, 32, vcc
	v_ldexp_f32 v70, v70, v72
	v_log_f32_e32 v70, v70
	v_min_f32_e32 v68, 0, v71
	v_add_f32_e32 v71, v180, v78
	v_mul_f32_e64 v72, |v71|, s40
	v_mul_f32_e32 v69, 0x3f317217, v70
	v_fma_f32 v69, v70, s42, -v69
	v_exp_f32_e32 v72, v72
	v_fmac_f32_e32 v69, 0x3377d1cf, v70
	v_fmac_f32_e32 v69, 0x3f317217, v70
	v_cmp_lt_f32_e64 s[14:15], |v70|, s43
	s_nop 1
	v_cndmask_b32_e64 v69, v70, v69, s[14:15]
	v_cndmask_b32_e32 v70, 0, v179, vcc
	v_sub_f32_e32 v69, v69, v70
	v_add_f32_e32 v70, 1.0, v72
	v_cmp_gt_f32_e32 vcc, s41, v70
	v_sub_f32_e32 v68, v68, v69
	v_min_f32_e32 v69, 0, v71
	v_cndmask_b32_e64 v72, 0, 32, vcc
	v_ldexp_f32 v70, v70, v72
	v_log_f32_e32 v70, v70
	v_add_f32_e32 v72, v180, v79
	v_mul_f32_e64 v73, |v72|, s40
	v_exp_f32_e32 v73, v73
	v_mul_f32_e32 v71, 0x3f317217, v70
	v_fma_f32 v71, v70, s42, -v71
	v_fmac_f32_e32 v71, 0x3377d1cf, v70
	v_fmac_f32_e32 v71, 0x3f317217, v70
	v_cmp_lt_f32_e64 s[14:15], |v70|, s43
	v_fmamk_f32 v68, v68, 0x3d800000, v77
	s_nop 0
	v_cndmask_b32_e64 v70, v70, v71, s[14:15]
	v_cndmask_b32_e32 v71, 0, v179, vcc
	v_sub_f32_e32 v70, v70, v71
	v_add_f32_e32 v71, 1.0, v73
	v_cmp_gt_f32_e32 vcc, s41, v71
	v_sub_f32_e32 v69, v69, v70
	v_fma_f32 v78, v69, s44, 0
	v_cndmask_b32_e64 v73, 0, 32, vcc
	v_ldexp_f32 v71, v71, v73
	v_log_f32_e32 v71, v71
	v_min_f32_e32 v69, 0, v72
	v_add_f32_e32 v72, v180, v80
	v_mul_f32_e64 v73, |v72|, s40
	v_mul_f32_e32 v70, 0x3f317217, v71
	v_fma_f32 v70, v71, s42, -v70
	v_exp_f32_e32 v73, v73
	v_fmac_f32_e32 v70, 0x3377d1cf, v71
	v_fmac_f32_e32 v70, 0x3f317217, v71
	v_cmp_lt_f32_e64 s[14:15], |v71|, s43
	s_nop 1
	v_cndmask_b32_e64 v70, v71, v70, s[14:15]
	v_cndmask_b32_e32 v71, 0, v179, vcc
	v_sub_f32_e32 v70, v70, v71
	v_add_f32_e32 v71, 1.0, v73
	v_cmp_gt_f32_e32 vcc, s41, v71
	v_sub_f32_e32 v69, v69, v70
	v_fmamk_f32 v79, v69, 0x3d800000, v78
	v_cndmask_b32_e64 v73, 0, 32, vcc
	v_ldexp_f32 v71, v71, v73
	v_log_f32_e32 v71, v71
	v_min_f32_e32 v69, 0, v72
	v_add_f32_e32 v72, v180, v81
	v_mul_f32_e64 v73, |v72|, s40
	v_mul_f32_e32 v70, 0x3f317217, v71
	v_fma_f32 v70, v71, s42, -v70
	v_exp_f32_e32 v73, v73
	v_fmac_f32_e32 v70, 0x3377d1cf, v71
	v_fmac_f32_e32 v70, 0x3f317217, v71
	v_cmp_lt_f32_e64 s[14:15], |v71|, s43
	s_nop 1
	v_cndmask_b32_e64 v70, v71, v70, s[14:15]
	v_cndmask_b32_e32 v71, 0, v179, vcc
	v_sub_f32_e32 v70, v70, v71
	v_add_f32_e32 v71, 1.0, v73
	v_cmp_gt_f32_e32 vcc, s41, v71
	v_sub_f32_e32 v69, v69, v70
	v_fmamk_f32 v80, v69, 0x3d800000, v79
	v_cndmask_b32_e64 v73, 0, 32, vcc
	v_ldexp_f32 v71, v71, v73
	v_log_f32_e32 v71, v71
	v_min_f32_e32 v69, 0, v72
	v_mov_b32_e32 v72, v67
	v_mov_b32_e32 v73, v68
	v_mul_f32_e32 v70, 0x3f317217, v71
	v_fma_f32 v70, v71, s42, -v70
	v_fmac_f32_e32 v70, 0x3377d1cf, v71
	v_fmac_f32_e32 v70, 0x3f317217, v71
	v_cmp_lt_f32_e64 s[14:15], |v71|, s43
	s_nop 1
	v_cndmask_b32_e64 v70, v71, v70, s[14:15]
	v_cndmask_b32_e32 v71, 0, v179, vcc
	v_sub_f32_e32 v70, v70, v71
	v_sub_f32_e32 v69, v69, v70
	v_mov_b32_e32 v70, v66
	v_mov_b32_e32 v71, v66
	s_nop 1
	v_permlane32_swap_b32_e32 v70, v71
	v_cmp_gt_u32_e32 vcc, 32, v87
	v_fmamk_f32 v69, v69, 0x3d800000, v80
	v_mov_b32_e32 v74, v69
	v_cndmask_b32_e32 v70, v70, v71, vcc
	v_mov_b32_e32 v71, v67
	s_nop 1
	v_permlane32_swap_b32_e32 v71, v72
	v_cndmask_b32_e32 v71, v71, v72, vcc
	v_mov_b32_e32 v72, v68
	s_nop 1
	v_permlane32_swap_b32_e32 v72, v73
	v_cndmask_b32_e32 v72, v72, v73, vcc
	v_mov_b32_e32 v73, v69
	s_nop 1
	v_permlane32_swap_b32_e32 v73, v74
	v_cndmask_b32_e32 v74, v73, v74, vcc
	v_lshlrev_b32_e32 v73, 6, v82
	v_cndmask_b32_e64 v81, v70, 0, vcc
	v_and_b32_e32 v82, 0x800, v73
	v_lshlrev_b32_e32 v73, 2, v83
	v_add_f32_e32 v83, v81, v84
	v_add3_u32 v82, s4, v73, v82
	v_add_f32_e32 v84, v81, v140
	ds_write2st64_b32 v82, v83, v84 offset1:2
	v_add_f32_e32 v83, v81, v86
	v_add_f32_e32 v84, v81, v66
	ds_write2st64_b32 v82, v83, v84 offset0:4 offset1:6
	v_cndmask_b32_e32 v83, v71, v70, vcc
	v_add_f32_e32 v83, v83, v66
	v_add_f32_e32 v81, v81, v83
	v_add_f32_e32 v83, v141, v81
	v_add_f32_e32 v84, v142, v81
	ds_write2st64_b32 v82, v83, v84 offset0:16 offset1:18
	v_add_f32_e32 v83, v143, v81
	v_add_f32_e32 v84, v67, v81
	ds_write2st64_b32 v82, v83, v84 offset0:20 offset1:22
	v_cndmask_b32_e32 v83, v72, v71, vcc
	v_add_f32_e32 v83, v83, v67
	v_add_f32_e32 v81, v83, v81
	v_add_f32_e32 v75, v75, v81
	v_add_f32_e32 v76, v76, v81
	ds_write2st64_b32 v82, v75, v76 offset0:32 offset1:34
	v_add_f32_e32 v75, v77, v81
	v_add_f32_e32 v76, v68, v81
	ds_write2st64_b32 v82, v75, v76 offset0:36 offset1:38
	v_cndmask_b32_e32 v75, v74, v72, vcc
	v_add_f32_e32 v75, v75, v68
	v_add_f32_e32 v75, v75, v81
	v_add_f32_e32 v76, v78, v75
	v_add_f32_e32 v77, v79, v75
	ds_write2st64_b32 v82, v76, v77 offset0:48 offset1:50
	v_add_f32_e32 v76, v80, v75
	v_add_f32_e32 v75, v69, v75
	ds_write2st64_b32 v82, v76, v75 offset0:52 offset1:54
	s_and_saveexec_b64 s[14:15], vcc
	s_cbranch_execz .LBB0_980
	v_add_f32_e32 v66, v66, v67
	v_add_f32_e32 v67, v68, v69
	v_add_f32_e32 v66, v66, v67
	v_add_f32_e32 v67, v70, v71
	v_add_f32_e32 v66, v67, v66
	v_add_f32_e32 v67, v72, v74
	v_add_f32_e32 v66, v67, v66
	v_mul_f32_e32 v67, 0x3fb8aa3b, v66
	v_exp_f32_e32 v67, v67
	v_add_u32_e32 v68, s5, v73
	ds_write_b32 v68, v66
	v_add_u32_e32 v66, s10, v73
	ds_write_b32 v66, v67

.LBB0_1047:
	ds_read_b128 v[130:133], v170
	ds_read_b128 v[134:137], v170 offset:1024
	ds_read_b128 v[138:141], v170 offset:2048
	ds_read_b128 v[142:145], v170 offset:3072
	s_add_u32 s0, s38, 0xfffc0080
	s_addc_u32 s1, s39, -1
	s_cmp_eq_u32 s69, 12
	s_cselect_b32 s43, s60, s1
	s_cselect_b32 s42, s61, s0
	s_cselect_b32 s41, s62, s65
	s_cselect_b32 s40, s63, s64
	s_mov_b32 m0, s50
	v_lshl_add_u64 v[166:167], s[38:39], 0, v[164:165]
	ds_read_b128 v[146:149], v171
	ds_read_b128 v[174:177], v171 offset:1024
	ds_read_b128 v[178:181], v171 offset:2048
	ds_read_b128 v[182:185], v171 offset:3072
	ds_read_b128 v[186:189], v171 offset:4096
	ds_read_b128 v[190:193], v171 offset:5120
	ds_read_b128 v[194:197], v171 offset:6144
	ds_read_b128 v[198:201], v171 offset:7168
	global_load_lds_dwordx4 v[166:167], off
	v_lshl_add_u64 v[166:167], s[38:39], 0, v[162:163]
	s_mov_b32 m0, s51
	s_nop 0
	global_load_lds_dwordx4 v[166:167], off
	s_waitcnt lgkmcnt(8)
	s_waitcnt vmcnt(10)
	s_barrier
	s_waitcnt lgkmcnt(0)
	v_mfma_f32_16x16x32_bf16 v[126:129], v[130:133], v[146:149], v[126:129]
	v_mfma_f32_16x16x32_bf16 v[122:125], v[138:141], v[146:149], v[122:125]
	v_mfma_f32_16x16x32_bf16 v[118:121], v[130:133], v[178:181], v[118:121]
	v_mfma_f32_16x16x32_bf16 v[110:113], v[138:141], v[178:181], v[110:113]
	v_mfma_f32_16x16x32_bf16 v[98:101], v[130:133], v[186:189], v[98:101]
	v_mfma_f32_16x16x32_bf16 v[90:93], v[138:141], v[186:189], v[90:93]
	v_mfma_f32_16x16x32_bf16 v[82:85], v[130:133], v[194:197], v[82:85]
	v_mfma_f32_16x16x32_bf16 v[74:77], v[138:141], v[194:197], v[74:77]
	v_mfma_f32_16x16x32_bf16 v[126:129], v[134:137], v[174:177], v[126:129]
	v_mfma_f32_16x16x32_bf16 v[122:125], v[142:145], v[174:177], v[122:125]
	v_mfma_f32_16x16x32_bf16 v[118:121], v[134:137], v[182:185], v[118:121]
	v_mfma_f32_16x16x32_bf16 v[110:113], v[142:145], v[182:185], v[110:113]
	v_mfma_f32_16x16x32_bf16 v[98:101], v[134:137], v[190:193], v[98:101]
	v_mfma_f32_16x16x32_bf16 v[90:93], v[142:145], v[190:193], v[90:93]
	v_mfma_f32_16x16x32_bf16 v[82:85], v[134:137], v[198:201], v[82:85]
	v_mfma_f32_16x16x32_bf16 v[74:77], v[142:145], v[198:201], v[74:77]
	s_barrier
	s_mov_b32 m0, s52
	v_lshl_add_u64 v[166:167], s[40:41], 0, v[158:159]
	ds_read_b128 v[202:205], v172
	ds_read_b128 v[206:209], v172 offset:1024
	ds_read_b128 v[210:213], v172 offset:2048
	ds_read_b128 v[214:217], v172 offset:3072
	global_load_lds_dwordx4 v[166:167], off
	v_lshl_add_u64 v[218:219], s[40:41], 0, v[154:155]
	s_mov_b32 m0, s53
	s_nop 0
	global_load_lds_dwordx4 v[218:219], off
	s_waitcnt vmcnt(10)
	s_barrier
	s_waitcnt lgkmcnt(0)
	v_mfma_f32_16x16x32_bf16 v[114:117], v[202:205], v[146:149], v[114:117]
	v_mfma_f32_16x16x32_bf16 v[106:109], v[210:213], v[146:149], v[106:109]
	v_mfma_f32_16x16x32_bf16 v[102:105], v[202:205], v[178:181], v[102:105]
	v_mfma_f32_16x16x32_bf16 v[94:97], v[210:213], v[178:181], v[94:97]
	v_mfma_f32_16x16x32_bf16 v[86:89], v[202:205], v[186:189], v[86:89]
	v_mfma_f32_16x16x32_bf16 v[78:81], v[210:213], v[186:189], v[78:81]
	v_mfma_f32_16x16x32_bf16 v[70:73], v[202:205], v[194:197], v[70:73]
	v_mfma_f32_16x16x32_bf16 v[66:69], v[210:213], v[194:197], v[66:69]
	v_mfma_f32_16x16x32_bf16 v[114:117], v[206:209], v[174:177], v[114:117]
	v_mfma_f32_16x16x32_bf16 v[106:109], v[214:217], v[174:177], v[106:109]
	v_mfma_f32_16x16x32_bf16 v[102:105], v[206:209], v[182:185], v[102:105]
	v_mfma_f32_16x16x32_bf16 v[94:97], v[214:217], v[182:185], v[94:97]
	v_mfma_f32_16x16x32_bf16 v[86:89], v[206:209], v[190:193], v[86:89]
	v_mfma_f32_16x16x32_bf16 v[78:81], v[214:217], v[190:193], v[78:81]
	v_mfma_f32_16x16x32_bf16 v[70:73], v[206:209], v[198:201], v[70:73]
	v_mfma_f32_16x16x32_bf16 v[66:69], v[214:217], v[198:201], v[66:69]
	s_mov_b32 m0, s6
	v_lshl_add_u64 v[220:221], s[42:43], 0, v[160:161]
	s_barrier
	ds_read_b128 v[146:149], v171 offset:16384
	ds_read_b128 v[174:177], v171 offset:17408
	ds_read_b128 v[178:181], v171 offset:18432
	ds_read_b128 v[182:185], v171 offset:19456
	ds_read_b128 v[186:189], v171 offset:20480
	ds_read_b128 v[190:193], v171 offset:21504
	ds_read_b128 v[194:197], v171 offset:22528
	ds_read_b128 v[198:201], v171 offset:23552
	global_load_lds_dwordx4 v[220:221], off
	v_lshl_add_u64 v[222:223], s[42:43], 0, v[156:157]
	s_mov_b32 m0, s7
	s_nop 0
	global_load_lds_dwordx4 v[222:223], off
	s_waitcnt vmcnt(10)
	s_barrier
	s_waitcnt lgkmcnt(0)
	v_mfma_f32_16x16x32_bf16 v[62:65], v[130:133], v[146:149], v[62:65]
	v_mfma_f32_16x16x32_bf16 v[58:61], v[138:141], v[146:149], v[58:61]
	v_mfma_f32_16x16x32_bf16 v[50:53], v[130:133], v[178:181], v[50:53]
	v_mfma_f32_16x16x32_bf16 v[42:45], v[138:141], v[178:181], v[42:45]
	v_mfma_f32_16x16x32_bf16 v[34:37], v[130:133], v[186:189], v[34:37]
	v_mfma_f32_16x16x32_bf16 v[26:29], v[138:141], v[186:189], v[26:29]
	v_mfma_f32_16x16x32_bf16 v[18:21], v[130:133], v[194:197], v[18:21]
	v_mfma_f32_16x16x32_bf16 v[10:13], v[138:141], v[194:197], v[10:13]
	v_mfma_f32_16x16x32_bf16 v[62:65], v[134:137], v[174:177], v[62:65]
	v_mfma_f32_16x16x32_bf16 v[58:61], v[142:145], v[174:177], v[58:61]
	v_mfma_f32_16x16x32_bf16 v[50:53], v[134:137], v[182:185], v[50:53]
	v_mfma_f32_16x16x32_bf16 v[42:45], v[142:145], v[182:185], v[42:45]
	v_mfma_f32_16x16x32_bf16 v[34:37], v[134:137], v[190:193], v[34:37]
	v_mfma_f32_16x16x32_bf16 v[26:29], v[142:145], v[190:193], v[26:29]
	v_mfma_f32_16x16x32_bf16 v[18:21], v[134:137], v[198:201], v[18:21]
	v_mfma_f32_16x16x32_bf16 v[10:13], v[142:145], v[198:201], v[10:13]
	s_barrier
	s_add_u32 s0, s40, 0x40000
	s_addc_u32 s1, s41, 0
	s_mov_b32 m0, s54
	v_lshl_add_u64 v[130:131], s[0:1], 0, v[158:159]
	global_load_lds_dwordx4 v[130:131], off
	v_lshl_add_u64 v[130:131], s[0:1], 0, v[154:155]
	s_add_i32 m0, s54, 0x2000
	s_nop 0
	global_load_lds_dwordx4 v[130:131], off
	s_waitcnt vmcnt(10)
	s_barrier
	v_mfma_f32_16x16x32_bf16 v[54:57], v[202:205], v[146:149], v[54:57]
	v_mfma_f32_16x16x32_bf16 v[46:49], v[210:213], v[146:149], v[46:49]
	v_mfma_f32_16x16x32_bf16 v[38:41], v[202:205], v[178:181], v[38:41]
	v_mfma_f32_16x16x32_bf16 v[30:33], v[210:213], v[178:181], v[30:33]
	v_mfma_f32_16x16x32_bf16 v[22:25], v[202:205], v[186:189], v[22:25]
	v_mfma_f32_16x16x32_bf16 v[14:17], v[210:213], v[186:189], v[14:17]
	v_mfma_f32_16x16x32_bf16 v[6:9], v[202:205], v[194:197], v[6:9]
	v_mfma_f32_16x16x32_bf16 v[2:5], v[210:213], v[194:197], v[2:5]
	v_mfma_f32_16x16x32_bf16 v[54:57], v[206:209], v[174:177], v[54:57]
	v_mfma_f32_16x16x32_bf16 v[46:49], v[214:217], v[174:177], v[46:49]
	v_mfma_f32_16x16x32_bf16 v[38:41], v[206:209], v[182:185], v[38:41]
	v_mfma_f32_16x16x32_bf16 v[30:33], v[214:217], v[182:185], v[30:33]
	v_mfma_f32_16x16x32_bf16 v[22:25], v[206:209], v[190:193], v[22:25]
	v_mfma_f32_16x16x32_bf16 v[14:17], v[214:217], v[190:193], v[14:17]
	v_mfma_f32_16x16x32_bf16 v[6:9], v[206:209], v[198:201], v[6:9]
	v_mfma_f32_16x16x32_bf16 v[2:5], v[214:217], v[198:201], v[2:5]
	s_add_i32 s70, 0, 0x18000
	v_add_u32_e32 v142, s70, v169
	s_barrier
	ds_read_b128 v[130:133], v142
	ds_read_b128 v[134:137], v142 offset:1024
	ds_read_b128 v[138:141], v142 offset:2048
	ds_read_b128 v[142:145], v142 offset:3072
	s_add_u32 s0, s42, 0x40000
	s_addc_u32 s1, s43, 0
	s_mov_b32 m0, s10
	v_lshl_add_u64 v[202:203], s[0:1], 0, v[160:161]
	ds_read_b128 v[146:149], v171 offset:32768
	ds_read_b128 v[174:177], v171 offset:33792
	ds_read_b128 v[178:181], v171 offset:34816
	ds_read_b128 v[182:185], v171 offset:35840
	ds_read_b128 v[186:189], v171 offset:36864
	ds_read_b128 v[190:193], v171 offset:37888
	ds_read_b128 v[194:197], v171 offset:38912
	ds_read_b128 v[198:201], v171 offset:39936
	global_load_lds_dwordx4 v[202:203], off
	v_lshl_add_u64 v[202:203], s[0:1], 0, v[156:157]
	s_mov_b32 m0, s11
	s_nop 0
	global_load_lds_dwordx4 v[202:203], off
	s_waitcnt lgkmcnt(8)
	s_waitcnt vmcnt(10)
	s_barrier
	s_waitcnt lgkmcnt(0)
	v_mfma_f32_16x16x32_bf16 v[126:129], v[130:133], v[146:149], v[126:129]
	v_mfma_f32_16x16x32_bf16 v[122:125], v[138:141], v[146:149], v[122:125]
	v_mfma_f32_16x16x32_bf16 v[118:121], v[130:133], v[178:181], v[118:121]
	v_mfma_f32_16x16x32_bf16 v[110:113], v[138:141], v[178:181], v[110:113]
	v_mfma_f32_16x16x32_bf16 v[98:101], v[130:133], v[186:189], v[98:101]
	v_mfma_f32_16x16x32_bf16 v[90:93], v[138:141], v[186:189], v[90:93]
	v_mfma_f32_16x16x32_bf16 v[82:85], v[130:133], v[194:197], v[82:85]
	v_mfma_f32_16x16x32_bf16 v[74:77], v[138:141], v[194:197], v[74:77]
	v_mfma_f32_16x16x32_bf16 v[126:129], v[134:137], v[174:177], v[126:129]
	v_mfma_f32_16x16x32_bf16 v[122:125], v[142:145], v[174:177], v[122:125]
	v_mfma_f32_16x16x32_bf16 v[118:121], v[134:137], v[182:185], v[118:121]
	v_mfma_f32_16x16x32_bf16 v[110:113], v[142:145], v[182:185], v[110:113]
	v_mfma_f32_16x16x32_bf16 v[98:101], v[134:137], v[190:193], v[98:101]
	v_mfma_f32_16x16x32_bf16 v[90:93], v[142:145], v[190:193], v[90:93]
	v_mfma_f32_16x16x32_bf16 v[82:85], v[134:137], v[198:201], v[82:85]
	v_mfma_f32_16x16x32_bf16 v[74:77], v[142:145], v[198:201], v[74:77]
	s_barrier
	s_add_i32 s42, 0, 0x1c000
	s_add_i32 s0, s70, s5
	v_add_u32_e32 v173, s42, v169
	v_lshl_add_u64 v[166:167], v[166:167], 0, s[28:29]
	s_mov_b32 m0, s0
	ds_read_b128 v[202:205], v173
	ds_read_b128 v[206:209], v173 offset:1024
	ds_read_b128 v[210:213], v173 offset:2048
	ds_read_b128 v[214:217], v173 offset:3072
	global_load_lds_dwordx4 v[166:167], off
	v_lshl_add_u64 v[166:167], v[218:219], 0, s[28:29]
	s_add_i32 m0, s0, 0x2000
	s_nop 0
	global_load_lds_dwordx4 v[166:167], off
	s_waitcnt vmcnt(10)
	s_barrier
	s_waitcnt lgkmcnt(0)
	v_mfma_f32_16x16x32_bf16 v[114:117], v[202:205], v[146:149], v[114:117]
	v_mfma_f32_16x16x32_bf16 v[106:109], v[210:213], v[146:149], v[106:109]
	v_mfma_f32_16x16x32_bf16 v[102:105], v[202:205], v[178:181], v[102:105]
	v_mfma_f32_16x16x32_bf16 v[94:97], v[210:213], v[178:181], v[94:97]
	v_mfma_f32_16x16x32_bf16 v[86:89], v[202:205], v[186:189], v[86:89]
	v_mfma_f32_16x16x32_bf16 v[78:81], v[210:213], v[186:189], v[78:81]
	v_mfma_f32_16x16x32_bf16 v[70:73], v[202:205], v[194:197], v[70:73]
	v_mfma_f32_16x16x32_bf16 v[66:69], v[210:213], v[194:197], v[66:69]
	v_mfma_f32_16x16x32_bf16 v[114:117], v[206:209], v[174:177], v[114:117]
	v_mfma_f32_16x16x32_bf16 v[106:109], v[214:217], v[174:177], v[106:109]
	v_mfma_f32_16x16x32_bf16 v[102:105], v[206:209], v[182:185], v[102:105]
	v_mfma_f32_16x16x32_bf16 v[94:97], v[214:217], v[182:185], v[94:97]
	v_mfma_f32_16x16x32_bf16 v[86:89], v[206:209], v[190:193], v[86:89]
	v_mfma_f32_16x16x32_bf16 v[78:81], v[214:217], v[190:193], v[78:81]
	v_mfma_f32_16x16x32_bf16 v[70:73], v[206:209], v[198:201], v[70:73]
	v_mfma_f32_16x16x32_bf16 v[66:69], v[214:217], v[198:201], v[66:69]
	s_mov_b32 m0, s48
	v_lshl_add_u64 v[166:167], v[220:221], 0, s[28:29]
	s_barrier
	ds_read_b128 v[146:149], v171 offset:49152
	ds_read_b128 v[174:177], v171 offset:50176
	ds_read_b128 v[178:181], v171 offset:51200
	ds_read_b128 v[182:185], v171 offset:52224
	ds_read_b128 v[186:189], v171 offset:53248
	ds_read_b128 v[190:193], v171 offset:54272
	ds_read_b128 v[194:197], v171 offset:55296
	ds_read_b128 v[198:201], v171 offset:56320
	global_load_lds_dwordx4 v[166:167], off
	v_lshl_add_u64 v[166:167], v[222:223], 0, s[28:29]
	s_mov_b32 m0, s49
	s_nop 0
	global_load_lds_dwordx4 v[166:167], off
	s_waitcnt vmcnt(10)
	s_barrier
	s_waitcnt lgkmcnt(0)
	v_mfma_f32_16x16x32_bf16 v[62:65], v[130:133], v[146:149], v[62:65]
	v_mfma_f32_16x16x32_bf16 v[58:61], v[138:141], v[146:149], v[58:61]
	v_mfma_f32_16x16x32_bf16 v[50:53], v[130:133], v[178:181], v[50:53]
	v_mfma_f32_16x16x32_bf16 v[42:45], v[138:141], v[178:181], v[42:45]
	v_mfma_f32_16x16x32_bf16 v[34:37], v[130:133], v[186:189], v[34:37]
	v_mfma_f32_16x16x32_bf16 v[26:29], v[138:141], v[186:189], v[26:29]
	v_mfma_f32_16x16x32_bf16 v[18:21], v[130:133], v[194:197], v[18:21]
	v_mfma_f32_16x16x32_bf16 v[10:13], v[138:141], v[194:197], v[10:13]
	v_mfma_f32_16x16x32_bf16 v[62:65], v[134:137], v[174:177], v[62:65]
	v_mfma_f32_16x16x32_bf16 v[58:61], v[142:145], v[174:177], v[58:61]
	v_mfma_f32_16x16x32_bf16 v[50:53], v[134:137], v[182:185], v[50:53]
	v_mfma_f32_16x16x32_bf16 v[42:45], v[142:145], v[182:185], v[42:45]
	v_mfma_f32_16x16x32_bf16 v[34:37], v[134:137], v[190:193], v[34:37]
	v_mfma_f32_16x16x32_bf16 v[26:29], v[142:145], v[190:193], v[26:29]
	v_mfma_f32_16x16x32_bf16 v[18:21], v[134:137], v[198:201], v[18:21]
	v_mfma_f32_16x16x32_bf16 v[10:13], v[142:145], v[198:201], v[10:13]
	s_barrier
	s_add_u32 s0, s40, 0x40080
	s_addc_u32 s1, s41, 0
	s_add_i32 s40, s42, s5
	v_lshl_add_u64 v[130:131], s[0:1], 0, v[158:159]
	s_mov_b32 m0, s40
	s_nop 0
	global_load_lds_dwordx4 v[130:131], off
	v_lshl_add_u64 v[130:131], s[0:1], 0, v[154:155]
	s_add_i32 m0, s40, 0x2000
	s_nop 0
	global_load_lds_dwordx4 v[130:131], off
	s_waitcnt vmcnt(10)
	s_barrier
	v_mfma_f32_16x16x32_bf16 v[54:57], v[202:205], v[146:149], v[54:57]
	v_mfma_f32_16x16x32_bf16 v[46:49], v[210:213], v[146:149], v[46:49]
	v_mfma_f32_16x16x32_bf16 v[38:41], v[202:205], v[178:181], v[38:41]
	v_mfma_f32_16x16x32_bf16 v[30:33], v[210:213], v[178:181], v[30:33]
	v_mfma_f32_16x16x32_bf16 v[22:25], v[202:205], v[186:189], v[22:25]
	v_mfma_f32_16x16x32_bf16 v[14:17], v[210:213], v[186:189], v[14:17]
	v_mfma_f32_16x16x32_bf16 v[6:9], v[202:205], v[194:197], v[6:9]
	v_mfma_f32_16x16x32_bf16 v[2:5], v[210:213], v[194:197], v[2:5]
	v_mfma_f32_16x16x32_bf16 v[54:57], v[206:209], v[174:177], v[54:57]
	v_mfma_f32_16x16x32_bf16 v[46:49], v[214:217], v[174:177], v[46:49]
	v_mfma_f32_16x16x32_bf16 v[38:41], v[206:209], v[182:185], v[38:41]
	v_mfma_f32_16x16x32_bf16 v[30:33], v[214:217], v[182:185], v[30:33]
	v_mfma_f32_16x16x32_bf16 v[22:25], v[206:209], v[190:193], v[22:25]
	v_mfma_f32_16x16x32_bf16 v[14:17], v[214:217], v[190:193], v[14:17]
	v_mfma_f32_16x16x32_bf16 v[6:9], v[206:209], v[198:201], v[6:9]
	v_mfma_f32_16x16x32_bf16 v[2:5], v[214:217], v[198:201], v[2:5]
	s_add_i32 s69, s69, 2
	s_add_u32 s64, s64, 0x100
	s_addc_u32 s65, s65, 0
	s_add_u32 s38, s38, 0x100
	s_addc_u32 s39, s39, 0
	s_cmp_gt_u32 s69, 13
	s_barrier
	s_cbranch_scc0 .LBB0_1047
	s_lshl_b32 s0, s58, 8
	v_mov_b32_e32 v130, v151
	v_mov_b32_e32 v131, v153
	s_or_b32 s0, s0, s45
	s_mov_b32 s58, s57
	v_lshl_add_u32 v166, v131, 3, s0
	s_lshl_b32 s0, s59, 8
	s_add_i32 s0, s0, s44
	v_add_u32_e32 v173, s0, v130
	v_mov_b32_e32 v130, v173
	v_ashrrev_i32_e32 v167, 31, v166
	v_ashrrev_i32_e32 v131, 31, v130
	v_lshlrev_b64 v[130:131], 10, v[130:131]
	v_lshl_add_u64 v[130:131], v[130:131], 0, v[166:167]
	v_lshlrev_b64 v[186:187], 1, v[130:131]
	v_lshl_add_u64 v[130:131], s[12:13], 0, v[186:187]
	global_load_dwordx4 v[174:177], v[130:131], off
	global_load_dwordx4 v[178:181], v[130:131], off offset:256
	v_add_co_u32_e32 v132, vcc, s47, v130
	s_mov_b32 s59, s56
	s_nop 0
	v_addc_co_u32_e32 v133, vcc, 0, v131, vcc
	global_load_dwordx4 v[182:185], v[132:133], off
	global_load_dwordx4 v[146:149], v[132:133], off offset:256
	v_add_co_u32_e32 v132, vcc, s31, v130
	s_waitcnt vmcnt(0) lgkmcnt(0)
	v_lshlrev_b32_e32 v188, 16, v174
	v_addc_co_u32_e32 v133, vcc, 0, v131, vcc
	global_load_dwordx4 v[142:145], v[132:133], off
	global_load_dwordx4 v[138:141], v[132:133], off offset:256
	v_add_co_u32_e32 v130, vcc, s46, v130
	v_and_b32_e32 v189, 0xffff0000, v174
	s_nop 0
	v_addc_co_u32_e32 v131, vcc, 0, v131, vcc
	global_load_dwordx4 v[134:137], v[130:131], off
	s_nop 0
	global_load_dwordx4 v[130:133], v[130:131], off offset:256
	v_lshlrev_b32_e32 v174, 16, v175
	v_and_b32_e32 v175, 0xffff0000, v175
	v_lshlrev_b32_e32 v190, 16, v176
	v_and_b32_e32 v191, 0xffff0000, v176
	v_lshlrev_b32_e32 v176, 16, v177
	v_and_b32_e32 v177, 0xffff0000, v177
	v_pk_fma_f32 v[128:129], v[174:175], s[30:31], v[128:129] op_sel_hi:[1,0,1]
	v_pk_fma_f32 v[126:127], v[188:189], s[30:31], v[126:127] op_sel_hi:[1,0,1]
	v_pk_fma_f32 v[174:175], v[176:177], s[30:31], v[124:125] op_sel_hi:[1,0,1]
	v_pk_fma_f32 v[122:123], v[190:191], s[30:31], v[122:123] op_sel_hi:[1,0,1]
	v_cvt_pk_bf16_f32 v124, v126, v127
	v_cvt_pk_bf16_f32 v125, v128, v129
	v_cvt_pk_bf16_f32 v126, v122, v123
	v_cvt_pk_bf16_f32 v127, v174, v175
	v_lshl_add_u64 v[122:123], s[24:25], 0, v[186:187]
	global_store_dwordx4 v[122:123], v[124:127], off
	v_lshlrev_b32_e32 v128, 16, v180
	v_and_b32_e32 v129, 0xffff0000, v180
	v_lshlrev_b32_e32 v124, 16, v178
	v_and_b32_e32 v125, 0xffff0000, v178
	v_lshlrev_b32_e32 v126, 16, v179
	v_and_b32_e32 v127, 0xffff0000, v179
	v_lshlrev_b32_e32 v174, 16, v181
	v_and_b32_e32 v175, 0xffff0000, v181
	v_pk_fma_f32 v[116:117], v[126:127], s[30:31], v[116:117] op_sel_hi:[1,0,1]
	v_pk_fma_f32 v[114:115], v[124:125], s[30:31], v[114:115] op_sel_hi:[1,0,1]
	v_pk_fma_f32 v[124:125], v[174:175], s[30:31], v[108:109] op_sel_hi:[1,0,1]
	v_pk_fma_f32 v[108:109], v[128:129], s[30:31], v[106:107] op_sel_hi:[1,0,1]
	v_cvt_pk_bf16_f32 v106, v114, v115
	v_cvt_pk_bf16_f32 v107, v116, v117
	v_cvt_pk_bf16_f32 v108, v108, v109
	v_cvt_pk_bf16_f32 v109, v124, v125
	global_store_dwordx4 v[122:123], v[106:109], off offset:256
	v_lshlrev_b32_e32 v114, 16, v184
	v_and_b32_e32 v115, 0xffff0000, v184
	v_lshlrev_b32_e32 v106, 16, v182
	v_and_b32_e32 v107, 0xffff0000, v182
	v_lshlrev_b32_e32 v108, 16, v183
	v_and_b32_e32 v109, 0xffff0000, v183
	v_lshlrev_b32_e32 v116, 16, v185
	v_and_b32_e32 v117, 0xffff0000, v185
	v_pk_fma_f32 v[108:109], v[108:109], s[30:31], v[120:121] op_sel_hi:[1,0,1]
	v_pk_fma_f32 v[106:107], v[106:107], s[30:31], v[118:119] op_sel_hi:[1,0,1]
	v_pk_fma_f32 v[110:111], v[114:115], s[30:31], v[110:111] op_sel_hi:[1,0,1]
	v_pk_fma_f32 v[112:113], v[116:117], s[30:31], v[112:113] op_sel_hi:[1,0,1]
	v_cvt_pk_bf16_f32 v106, v106, v107
	v_cvt_pk_bf16_f32 v107, v108, v109
	v_cvt_pk_bf16_f32 v108, v110, v111
	v_add_co_u32_e32 v110, vcc, s47, v122
	v_cvt_pk_bf16_f32 v109, v112, v113
	s_nop 0
	v_addc_co_u32_e32 v111, vcc, 0, v123, vcc
	global_store_dwordx4 v[110:111], v[106:109], off
	v_lshlrev_b32_e32 v112, 16, v148
	v_and_b32_e32 v113, 0xffff0000, v148
	v_lshlrev_b32_e32 v106, 16, v146
	v_and_b32_e32 v107, 0xffff0000, v146
	v_lshlrev_b32_e32 v108, 16, v147
	v_and_b32_e32 v109, 0xffff0000, v147
	v_lshlrev_b32_e32 v114, 16, v149
	v_and_b32_e32 v115, 0xffff0000, v149
	v_pk_fma_f32 v[104:105], v[108:109], s[30:31], v[104:105] op_sel_hi:[1,0,1]
	v_pk_fma_f32 v[102:103], v[106:107], s[30:31], v[102:103] op_sel_hi:[1,0,1]
	v_pk_fma_f32 v[106:107], v[114:115], s[30:31], v[96:97] op_sel_hi:[1,0,1]
	v_pk_fma_f32 v[96:97], v[112:113], s[30:31], v[94:95] op_sel_hi:[1,0,1]
	v_cvt_pk_bf16_f32 v94, v102, v103
	v_cvt_pk_bf16_f32 v95, v104, v105
	v_cvt_pk_bf16_f32 v96, v96, v97
	v_cvt_pk_bf16_f32 v97, v106, v107
	global_store_dwordx4 v[110:111], v[94:97], off offset:256
	s_waitcnt vmcnt(0) lgkmcnt(0)
	v_lshlrev_b32_e32 v102, 16, v144
	v_lshlrev_b32_e32 v94, 16, v142
	v_and_b32_e32 v95, 0xffff0000, v142
	v_lshlrev_b32_e32 v96, 16, v143
	v_and_b32_e32 v97, 0xffff0000, v143
	v_and_b32_e32 v103, 0xffff0000, v144
	v_lshlrev_b32_e32 v104, 16, v145
	v_and_b32_e32 v105, 0xffff0000, v145
	v_pk_fma_f32 v[94:95], v[94:95], s[30:31], v[98:99] op_sel_hi:[1,0,1]
	v_pk_fma_f32 v[96:97], v[96:97], s[30:31], v[100:101] op_sel_hi:[1,0,1]
	v_pk_fma_f32 v[98:99], v[104:105], s[30:31], v[92:93] op_sel_hi:[1,0,1]
	v_pk_fma_f32 v[92:93], v[102:103], s[30:31], v[90:91] op_sel_hi:[1,0,1]
	v_cvt_pk_bf16_f32 v90, v94, v95
	v_add_co_u32_e32 v94, vcc, s31, v122
	v_cvt_pk_bf16_f32 v91, v96, v97
	v_cvt_pk_bf16_f32 v92, v92, v93
	v_cvt_pk_bf16_f32 v93, v98, v99
	v_addc_co_u32_e32 v95, vcc, 0, v123, vcc
	global_store_dwordx4 v[94:95], v[90:93], off
	v_lshlrev_b32_e32 v96, 16, v140
	v_and_b32_e32 v97, 0xffff0000, v140
	v_lshlrev_b32_e32 v90, 16, v138
	v_and_b32_e32 v91, 0xffff0000, v138
	v_lshlrev_b32_e32 v92, 16, v139
	v_and_b32_e32 v93, 0xffff0000, v139
	v_lshlrev_b32_e32 v98, 16, v141
	v_and_b32_e32 v99, 0xffff0000, v141
	v_pk_fma_f32 v[88:89], v[92:93], s[30:31], v[88:89] op_sel_hi:[1,0,1]
	v_pk_fma_f32 v[86:87], v[90:91], s[30:31], v[86:87] op_sel_hi:[1,0,1]
	v_pk_fma_f32 v[90:91], v[98:99], s[30:31], v[80:81] op_sel_hi:[1,0,1]
	v_pk_fma_f32 v[80:81], v[96:97], s[30:31], v[78:79] op_sel_hi:[1,0,1]
	v_cvt_pk_bf16_f32 v78, v86, v87
	v_cvt_pk_bf16_f32 v79, v88, v89
	v_cvt_pk_bf16_f32 v80, v80, v81
	v_cvt_pk_bf16_f32 v81, v90, v91
	global_store_dwordx4 v[94:95], v[78:81], off offset:256
	v_lshlrev_b32_e32 v86, 16, v136
	v_and_b32_e32 v87, 0xffff0000, v136
	v_lshlrev_b32_e32 v78, 16, v134
	v_and_b32_e32 v79, 0xffff0000, v134
	v_lshlrev_b32_e32 v80, 16, v135
	v_and_b32_e32 v81, 0xffff0000, v135
	v_lshlrev_b32_e32 v88, 16, v137
	v_and_b32_e32 v89, 0xffff0000, v137
	v_pk_fma_f32 v[78:79], v[78:79], s[30:31], v[82:83] op_sel_hi:[1,0,1]
	v_pk_fma_f32 v[80:81], v[80:81], s[30:31], v[84:85] op_sel_hi:[1,0,1]
	v_pk_fma_f32 v[82:83], v[88:89], s[30:31], v[76:77] op_sel_hi:[1,0,1]
	v_pk_fma_f32 v[76:77], v[86:87], s[30:31], v[74:75] op_sel_hi:[1,0,1]
	v_cvt_pk_bf16_f32 v74, v78, v79
	v_add_co_u32_e32 v78, vcc, s46, v122
	v_cvt_pk_bf16_f32 v75, v80, v81
	v_cvt_pk_bf16_f32 v76, v76, v77
	v_cvt_pk_bf16_f32 v77, v82, v83
	v_addc_co_u32_e32 v79, vcc, 0, v123, vcc
	global_store_dwordx4 v[78:79], v[74:77], off
	v_lshlrev_b32_e32 v80, 16, v132
	v_and_b32_e32 v81, 0xffff0000, v132
	v_lshlrev_b32_e32 v74, 16, v130
	v_and_b32_e32 v75, 0xffff0000, v130
	v_lshlrev_b32_e32 v76, 16, v131
	v_and_b32_e32 v77, 0xffff0000, v131
	v_lshlrev_b32_e32 v82, 16, v133
	v_and_b32_e32 v83, 0xffff0000, v133
	v_pk_fma_f32 v[72:73], v[76:77], s[30:31], v[72:73] op_sel_hi:[1,0,1]
	v_pk_fma_f32 v[70:71], v[74:75], s[30:31], v[70:71] op_sel_hi:[1,0,1]
	v_pk_fma_f32 v[74:75], v[82:83], s[30:31], v[68:69] op_sel_hi:[1,0,1]
	v_pk_fma_f32 v[68:69], v[80:81], s[30:31], v[66:67] op_sel_hi:[1,0,1]
	v_cvt_pk_bf16_f32 v66, v70, v71
	v_cvt_pk_bf16_f32 v67, v72, v73
	v_cvt_pk_bf16_f32 v68, v68, v69
	v_cvt_pk_bf16_f32 v69, v74, v75
	global_store_dwordx4 v[78:79], v[66:69], off offset:256
	s_nop 1
	v_add_u32_e32 v66, 0x80, v173
	s_nop 0
	v_ashrrev_i32_e32 v67, 31, v66
	v_lshlrev_b64 v[66:67], 10, v[66:67]
	v_lshl_add_u64 v[66:67], v[66:67], 0, v[166:167]
	v_lshlrev_b64 v[98:99], 1, v[66:67]
	v_lshl_add_u64 v[90:91], s[12:13], 0, v[98:99]
	global_load_dwordx4 v[66:69], v[90:91], off
	global_load_dwordx4 v[70:73], v[90:91], off offset:256
	v_add_co_u32_e32 v78, vcc, s47, v90
	s_waitcnt vmcnt(0) lgkmcnt(0)
	v_lshlrev_b32_e32 v100, 16, v66
	v_addc_co_u32_e32 v79, vcc, 0, v91, vcc
	global_load_dwordx4 v[74:77], v[78:79], off
	s_nop 0
	global_load_dwordx4 v[78:81], v[78:79], off offset:256
	v_add_co_u32_e32 v86, vcc, s31, v90
	v_and_b32_e32 v101, 0xffff0000, v66
	s_nop 0
	v_addc_co_u32_e32 v87, vcc, 0, v91, vcc
	global_load_dwordx4 v[82:85], v[86:87], off
	s_nop 0
	global_load_dwordx4 v[86:89], v[86:87], off offset:256
	v_add_co_u32_e32 v94, vcc, s46, v90
	v_lshlrev_b32_e32 v66, 16, v67
	s_nop 0
	v_addc_co_u32_e32 v95, vcc, 0, v91, vcc
	global_load_dwordx4 v[90:93], v[94:95], off
	s_nop 0
	global_load_dwordx4 v[94:97], v[94:95], off offset:256
	v_and_b32_e32 v67, 0xffff0000, v67
	v_lshlrev_b32_e32 v102, 16, v68
	v_and_b32_e32 v103, 0xffff0000, v68
	v_lshlrev_b32_e32 v68, 16, v69
	v_and_b32_e32 v69, 0xffff0000, v69
	v_pk_fma_f32 v[64:65], v[66:67], s[30:31], v[64:65] op_sel_hi:[1,0,1]
	v_pk_fma_f32 v[62:63], v[100:101], s[30:31], v[62:63] op_sel_hi:[1,0,1]
	v_pk_fma_f32 v[66:67], v[68:69], s[30:31], v[60:61] op_sel_hi:[1,0,1]
	v_pk_fma_f32 v[60:61], v[102:103], s[30:31], v[58:59] op_sel_hi:[1,0,1]
	v_cvt_pk_bf16_f32 v58, v62, v63
	v_cvt_pk_bf16_f32 v59, v64, v65
	v_cvt_pk_bf16_f32 v60, v60, v61
	v_cvt_pk_bf16_f32 v61, v66, v67
	v_lshl_add_u64 v[62:63], s[24:25], 0, v[98:99]
	global_store_dwordx4 v[62:63], v[58:61], off
	v_lshlrev_b32_e32 v64, 16, v72
	v_and_b32_e32 v65, 0xffff0000, v72
	v_lshlrev_b32_e32 v58, 16, v70
	v_and_b32_e32 v59, 0xffff0000, v70
	v_lshlrev_b32_e32 v60, 16, v71
	v_and_b32_e32 v61, 0xffff0000, v71
	v_lshlrev_b32_e32 v66, 16, v73
	v_and_b32_e32 v67, 0xffff0000, v73
	v_pk_fma_f32 v[56:57], v[60:61], s[30:31], v[56:57] op_sel_hi:[1,0,1]
	v_pk_fma_f32 v[54:55], v[58:59], s[30:31], v[54:55] op_sel_hi:[1,0,1]
	v_pk_fma_f32 v[58:59], v[66:67], s[30:31], v[48:49] op_sel_hi:[1,0,1]
	v_pk_fma_f32 v[48:49], v[64:65], s[30:31], v[46:47] op_sel_hi:[1,0,1]
	v_cvt_pk_bf16_f32 v46, v54, v55
	v_cvt_pk_bf16_f32 v47, v56, v57
	v_cvt_pk_bf16_f32 v48, v48, v49
	v_cvt_pk_bf16_f32 v49, v58, v59
	global_store_dwordx4 v[62:63], v[46:49], off offset:256
	s_waitcnt vmcnt(0) lgkmcnt(0)
	v_lshlrev_b32_e32 v54, 16, v76
	v_lshlrev_b32_e32 v46, 16, v74
	v_and_b32_e32 v47, 0xffff0000, v74
	v_lshlrev_b32_e32 v48, 16, v75
	v_and_b32_e32 v49, 0xffff0000, v75
	v_and_b32_e32 v55, 0xffff0000, v76
	v_lshlrev_b32_e32 v56, 16, v77
	v_and_b32_e32 v57, 0xffff0000, v77
	v_pk_fma_f32 v[46:47], v[46:47], s[30:31], v[50:51] op_sel_hi:[1,0,1]
	v_pk_fma_f32 v[48:49], v[48:49], s[30:31], v[52:53] op_sel_hi:[1,0,1]
	v_pk_fma_f32 v[50:51], v[56:57], s[30:31], v[44:45] op_sel_hi:[1,0,1]
	v_pk_fma_f32 v[44:45], v[54:55], s[30:31], v[42:43] op_sel_hi:[1,0,1]
	v_cvt_pk_bf16_f32 v42, v46, v47
	v_add_co_u32_e32 v46, vcc, s47, v62
	v_cvt_pk_bf16_f32 v43, v48, v49
	v_cvt_pk_bf16_f32 v44, v44, v45
	v_cvt_pk_bf16_f32 v45, v50, v51
	v_addc_co_u32_e32 v47, vcc, 0, v63, vcc
	global_store_dwordx4 v[46:47], v[42:45], off
	v_lshlrev_b32_e32 v48, 16, v80
	v_and_b32_e32 v49, 0xffff0000, v80
	v_lshlrev_b32_e32 v42, 16, v78
	v_and_b32_e32 v43, 0xffff0000, v78
	v_lshlrev_b32_e32 v44, 16, v79
	v_and_b32_e32 v45, 0xffff0000, v79
	v_lshlrev_b32_e32 v50, 16, v81
	v_and_b32_e32 v51, 0xffff0000, v81
	v_pk_fma_f32 v[40:41], v[44:45], s[30:31], v[40:41] op_sel_hi:[1,0,1]
	v_pk_fma_f32 v[38:39], v[42:43], s[30:31], v[38:39] op_sel_hi:[1,0,1]
	v_pk_fma_f32 v[42:43], v[50:51], s[30:31], v[32:33] op_sel_hi:[1,0,1]
	v_pk_fma_f32 v[32:33], v[48:49], s[30:31], v[30:31] op_sel_hi:[1,0,1]
	v_cvt_pk_bf16_f32 v30, v38, v39
	v_cvt_pk_bf16_f32 v31, v40, v41
	v_cvt_pk_bf16_f32 v32, v32, v33
	v_cvt_pk_bf16_f32 v33, v42, v43
	global_store_dwordx4 v[46:47], v[30:33], off offset:256
	v_lshlrev_b32_e32 v38, 16, v84
	v_and_b32_e32 v39, 0xffff0000, v84
	v_lshlrev_b32_e32 v30, 16, v82
	v_and_b32_e32 v31, 0xffff0000, v82
	v_lshlrev_b32_e32 v32, 16, v83
	v_and_b32_e32 v33, 0xffff0000, v83
	v_lshlrev_b32_e32 v40, 16, v85
	v_and_b32_e32 v41, 0xffff0000, v85
	v_pk_fma_f32 v[30:31], v[30:31], s[30:31], v[34:35] op_sel_hi:[1,0,1]
	v_pk_fma_f32 v[32:33], v[32:33], s[30:31], v[36:37] op_sel_hi:[1,0,1]
	v_pk_fma_f32 v[34:35], v[40:41], s[30:31], v[28:29] op_sel_hi:[1,0,1]
	v_pk_fma_f32 v[28:29], v[38:39], s[30:31], v[26:27] op_sel_hi:[1,0,1]
	v_cvt_pk_bf16_f32 v26, v30, v31
	v_add_co_u32_e32 v30, vcc, s31, v62
	v_cvt_pk_bf16_f32 v27, v32, v33
	v_cvt_pk_bf16_f32 v28, v28, v29
	v_cvt_pk_bf16_f32 v29, v34, v35
	v_addc_co_u32_e32 v31, vcc, 0, v63, vcc
	global_store_dwordx4 v[30:31], v[26:29], off
	v_lshlrev_b32_e32 v32, 16, v88
	v_and_b32_e32 v33, 0xffff0000, v88
	v_lshlrev_b32_e32 v26, 16, v86
	v_and_b32_e32 v27, 0xffff0000, v86
	v_lshlrev_b32_e32 v28, 16, v87
	v_and_b32_e32 v29, 0xffff0000, v87
	v_lshlrev_b32_e32 v34, 16, v89
	v_and_b32_e32 v35, 0xffff0000, v89
	v_pk_fma_f32 v[24:25], v[28:29], s[30:31], v[24:25] op_sel_hi:[1,0,1]
	v_pk_fma_f32 v[22:23], v[26:27], s[30:31], v[22:23] op_sel_hi:[1,0,1]
	v_pk_fma_f32 v[26:27], v[34:35], s[30:31], v[16:17] op_sel_hi:[1,0,1]
	v_pk_fma_f32 v[16:17], v[32:33], s[30:31], v[14:15] op_sel_hi:[1,0,1]
	v_cvt_pk_bf16_f32 v14, v22, v23
	v_cvt_pk_bf16_f32 v15, v24, v25
	v_cvt_pk_bf16_f32 v16, v16, v17
	v_cvt_pk_bf16_f32 v17, v26, v27
	global_store_dwordx4 v[30:31], v[14:17], off offset:256
	v_lshlrev_b32_e32 v22, 16, v92
	v_and_b32_e32 v23, 0xffff0000, v92
	v_lshlrev_b32_e32 v14, 16, v90
	v_and_b32_e32 v15, 0xffff0000, v90
	v_lshlrev_b32_e32 v16, 16, v91
	v_and_b32_e32 v17, 0xffff0000, v91
	v_lshlrev_b32_e32 v24, 16, v93
	v_and_b32_e32 v25, 0xffff0000, v93
	v_pk_fma_f32 v[14:15], v[14:15], s[30:31], v[18:19] op_sel_hi:[1,0,1]
	v_pk_fma_f32 v[16:17], v[16:17], s[30:31], v[20:21] op_sel_hi:[1,0,1]
	v_pk_fma_f32 v[18:19], v[24:25], s[30:31], v[12:13] op_sel_hi:[1,0,1]
	v_pk_fma_f32 v[12:13], v[22:23], s[30:31], v[10:11] op_sel_hi:[1,0,1]
	v_cvt_pk_bf16_f32 v10, v14, v15
	v_add_co_u32_e32 v14, vcc, s46, v62
	v_cvt_pk_bf16_f32 v11, v16, v17
	v_cvt_pk_bf16_f32 v12, v12, v13
	v_cvt_pk_bf16_f32 v13, v18, v19
	v_addc_co_u32_e32 v15, vcc, 0, v63, vcc
	global_store_dwordx4 v[14:15], v[10:13], off
	v_lshlrev_b32_e32 v16, 16, v96
	v_and_b32_e32 v17, 0xffff0000, v96
	v_lshlrev_b32_e32 v10, 16, v94
	v_and_b32_e32 v11, 0xffff0000, v94
	v_lshlrev_b32_e32 v12, 16, v95
	v_and_b32_e32 v13, 0xffff0000, v95
	v_lshlrev_b32_e32 v18, 16, v97
	v_and_b32_e32 v19, 0xffff0000, v97
	v_pk_fma_f32 v[8:9], v[12:13], s[30:31], v[8:9] op_sel_hi:[1,0,1]
	v_pk_fma_f32 v[6:7], v[10:11], s[30:31], v[6:7] op_sel_hi:[1,0,1]
	v_pk_fma_f32 v[10:11], v[18:19], s[30:31], v[4:5] op_sel_hi:[1,0,1]
	v_pk_fma_f32 v[4:5], v[16:17], s[30:31], v[2:3] op_sel_hi:[1,0,1]
	v_cvt_pk_bf16_f32 v2, v6, v7
	v_cvt_pk_bf16_f32 v3, v8, v9
	v_cvt_pk_bf16_f32 v4, v4, v5
	v_cvt_pk_bf16_f32 v5, v10, v11
	s_and_b64 vcc, exec, s[34:35]
	global_store_dwordx4 v[14:15], v[2:5], off offset:256
	s_cbranch_vccz .LBB0_1046
	s_waitcnt vmcnt(0)
	s_cmpk_gt_u32 s4, 0xff
	s_cbranch_scc1 .LBB0_1051
	s_barrier

.LBB0_1302:
	s_add_u32 s12, s36, 0x100
	s_addc_u32 s13, s37, 0
	s_add_u32 s34, s31, s36
	s_addc_u32 s35, s55, s37
	s_cmpk_eq_i32 s36, 0x300
	s_cselect_b64 vcc, -1, 0
	s_and_b64 s[0:1], vcc, exec
	s_cselect_b32 s1, 0, s12
	s_cselect_b32 s0, 0, s13
	s_cselect_b32 s34, s29, s34
	s_cselect_b32 s35, s27, s35
	s_add_u32 s38, s16, s1
	s_addc_u32 s39, s17, s0
	s_add_i32 s1, 0, 0x10000
	v_add_u32_e32 v14, s1, v197
	ds_read_b128 v[2:5], v14
	ds_read_b128 v[6:9], v14 offset:1024
	ds_read_b128 v[10:13], v14 offset:2048
	ds_read_b128 v[14:17], v14 offset:3072
	v_cndmask_b32_e32 v162, v168, v171, vcc
	v_cndmask_b32_e32 v184, v170, v198, vcc
	v_cndmask_b32_e32 v175, v172, v199, vcc
	v_cndmask_b32_e32 v173, v174, v200, vcc
	v_lshl_add_u64 v[18:19], v[178:179], 0, s[36:37]
	s_add_i32 m0, s45, 0xc000
	ds_read_b128 v[202:205], v169
	ds_read_b128 v[206:209], v169 offset:1024
	ds_read_b128 v[210:213], v169 offset:2048
	ds_read_b128 v[214:217], v169 offset:3072
	ds_read_b128 v[218:221], v169 offset:4096
	ds_read_b128 v[222:225], v169 offset:5120
	ds_read_b128 v[226:229], v169 offset:6144
	ds_read_b128 v[230:233], v169 offset:7168
	global_load_lds_dwordx4 v[18:19], off
	v_lshl_add_u64 v[18:19], v[176:177], 0, s[36:37]
	s_add_i32 m0, s45, 0xe000
	s_nop 0
	global_load_lds_dwordx4 v[18:19], off
	s_waitcnt lgkmcnt(8)
	s_waitcnt vmcnt(10)
	s_barrier
	s_waitcnt lgkmcnt(0)
	v_mfma_scale_f32_16x16x128_f8f6f4 v[158:161], v[2:9], v[202:209], v[158:161], v188, v188 op_sel_hi:[0,0,0]
	v_mfma_scale_f32_16x16x128_f8f6f4 v[150:153], v[10:17], v[202:209], v[150:153], v188, v188 op_sel_hi:[0,0,0]
	v_mfma_scale_f32_16x16x128_f8f6f4 v[142:145], v[2:9], v[210:217], v[142:145], v188, v188 op_sel_hi:[0,0,0]
	v_mfma_scale_f32_16x16x128_f8f6f4 v[134:137], v[10:17], v[210:217], v[134:137], v188, v188 op_sel_hi:[0,0,0]
	v_mfma_scale_f32_16x16x128_f8f6f4 v[126:129], v[2:9], v[218:225], v[126:129], v188, v188 op_sel_hi:[0,0,0]
	v_mfma_scale_f32_16x16x128_f8f6f4 v[118:121], v[10:17], v[218:225], v[118:121], v188, v188 op_sel_hi:[0,0,0]
	v_mfma_scale_f32_16x16x128_f8f6f4 v[110:113], v[2:9], v[226:233], v[110:113], v188, v188 op_sel_hi:[0,0,0]
	v_mfma_scale_f32_16x16x128_f8f6f4 v[102:105], v[10:17], v[226:233], v[102:105], v188, v188 op_sel_hi:[0,0,0]
	s_barrier
	s_add_i32 s0, 0, 0x14000
	s_add_i32 s1, s1, s43
	v_add_u32_e32 v30, s0, v197
	v_lshl_add_u64 v[180:181], s[34:35], 0, v[164:165]
	s_mov_b32 m0, s1
	ds_read_b128 v[18:21], v30
	ds_read_b128 v[22:25], v30 offset:1024
	ds_read_b128 v[26:29], v30 offset:2048
	ds_read_b128 v[30:33], v30 offset:3072
	global_load_lds_dwordx4 v[180:181], off
	v_lshl_add_u64 v[182:183], s[34:35], 0, v[166:167]
	s_add_i32 m0, s1, 0x2000
	s_nop 0
	global_load_lds_dwordx4 v[182:183], off
	s_waitcnt vmcnt(10)
	s_barrier
	s_waitcnt lgkmcnt(0)
	v_mfma_scale_f32_16x16x128_f8f6f4 v[154:157], v[18:25], v[202:209], v[154:157], v188, v188 op_sel_hi:[0,0,0]
	v_mfma_scale_f32_16x16x128_f8f6f4 v[146:149], v[26:33], v[202:209], v[146:149], v188, v188 op_sel_hi:[0,0,0]
	v_mfma_scale_f32_16x16x128_f8f6f4 v[138:141], v[18:25], v[210:217], v[138:141], v188, v188 op_sel_hi:[0,0,0]
	v_mfma_scale_f32_16x16x128_f8f6f4 v[130:133], v[26:33], v[210:217], v[130:133], v188, v188 op_sel_hi:[0,0,0]
	v_mfma_scale_f32_16x16x128_f8f6f4 v[122:125], v[18:25], v[218:225], v[122:125], v188, v188 op_sel_hi:[0,0,0]
	v_mfma_scale_f32_16x16x128_f8f6f4 v[114:117], v[26:33], v[218:225], v[114:117], v188, v188 op_sel_hi:[0,0,0]
	v_mfma_scale_f32_16x16x128_f8f6f4 v[106:109], v[18:25], v[226:233], v[106:109], v188, v188 op_sel_hi:[0,0,0]
	v_mfma_scale_f32_16x16x128_f8f6f4 v[98:101], v[26:33], v[226:233], v[98:101], v188, v188 op_sel_hi:[0,0,0]
	s_mov_b32 m0, s45
	s_barrier
	ds_read_b128 v[202:205], v169 offset:16384
	ds_read_b128 v[206:209], v169 offset:17408
	ds_read_b128 v[210:213], v169 offset:18432
	ds_read_b128 v[214:217], v169 offset:19456
	ds_read_b128 v[218:221], v169 offset:20480
	ds_read_b128 v[222:225], v169 offset:21504
	ds_read_b128 v[226:229], v169 offset:22528
	ds_read_b128 v[230:233], v169 offset:23552
	global_load_lds_dwordx4 v162, s[38:39]
	s_mov_b32 m0, s46
	v_mov_b32_e32 v185, v163
	global_load_lds_dwordx4 v184, s[38:39]
	s_waitcnt vmcnt(10)
	s_barrier
	s_waitcnt lgkmcnt(0)
	v_lshl_add_u64 v[186:187], s[38:39], 0, v[162:163]
	v_lshl_add_u64 v[184:185], s[38:39], 0, v[184:185]
	s_waitcnt lgkmcnt(0)
	v_mfma_scale_f32_16x16x128_f8f6f4 v[94:97], v[2:9], v[202:209], v[94:97], v188, v188 op_sel_hi:[0,0,0]
	v_mfma_scale_f32_16x16x128_f8f6f4 v[86:89], v[10:17], v[202:209], v[86:89], v188, v188 op_sel_hi:[0,0,0]
	v_mfma_scale_f32_16x16x128_f8f6f4 v[78:81], v[2:9], v[210:217], v[78:81], v188, v188 op_sel_hi:[0,0,0]
	v_mfma_scale_f32_16x16x128_f8f6f4 v[70:73], v[10:17], v[210:217], v[70:73], v188, v188 op_sel_hi:[0,0,0]
	v_mfma_scale_f32_16x16x128_f8f6f4 v[62:65], v[2:9], v[218:225], v[62:65], v188, v188 op_sel_hi:[0,0,0]
	v_mfma_scale_f32_16x16x128_f8f6f4 v[54:57], v[10:17], v[218:225], v[54:57], v188, v188 op_sel_hi:[0,0,0]
	v_mfma_scale_f32_16x16x128_f8f6f4 v[46:49], v[2:9], v[226:233], v[46:49], v188, v188 op_sel_hi:[0,0,0]
	v_mfma_scale_f32_16x16x128_f8f6f4 v[38:41], v[10:17], v[226:233], v[38:41], v188, v188 op_sel_hi:[0,0,0]
	s_barrier
	s_add_u32 s36, s34, 0x20000
	s_addc_u32 s37, s35, 0
	s_add_i32 s0, s0, s43
	v_lshl_add_u64 v[2:3], s[36:37], 0, v[164:165]
	s_mov_b32 m0, s0
	s_nop 0
	global_load_lds_dwordx4 v[2:3], off
	v_lshl_add_u64 v[2:3], s[36:37], 0, v[166:167]
	s_add_i32 m0, s0, 0x2000
	s_nop 0
	global_load_lds_dwordx4 v[2:3], off
	s_waitcnt vmcnt(10)
	s_barrier
	v_mfma_scale_f32_16x16x128_f8f6f4 v[90:93], v[18:25], v[202:209], v[90:93], v188, v188 op_sel_hi:[0,0,0]
	v_mfma_scale_f32_16x16x128_f8f6f4 v[82:85], v[26:33], v[202:209], v[82:85], v188, v188 op_sel_hi:[0,0,0]
	v_mfma_scale_f32_16x16x128_f8f6f4 v[74:77], v[18:25], v[210:217], v[74:77], v188, v188 op_sel_hi:[0,0,0]
	v_mfma_scale_f32_16x16x128_f8f6f4 v[66:69], v[26:33], v[210:217], v[66:69], v188, v188 op_sel_hi:[0,0,0]
	v_mfma_scale_f32_16x16x128_f8f6f4 v[58:61], v[18:25], v[218:225], v[58:61], v188, v188 op_sel_hi:[0,0,0]
	v_mfma_scale_f32_16x16x128_f8f6f4 v[50:53], v[26:33], v[218:225], v[50:53], v188, v188 op_sel_hi:[0,0,0]
	v_mfma_scale_f32_16x16x128_f8f6f4 v[42:45], v[18:25], v[226:233], v[42:45], v188, v188 op_sel_hi:[0,0,0]
	v_mfma_scale_f32_16x16x128_f8f6f4 v[34:37], v[26:33], v[226:233], v[34:37], v188, v188 op_sel_hi:[0,0,0]
	s_add_i32 s0, 0, 0x18000
	v_add_u32_e32 v14, s0, v197
	s_barrier
	ds_read_b128 v[2:5], v14
	ds_read_b128 v[6:9], v14 offset:1024
	ds_read_b128 v[10:13], v14 offset:2048
	ds_read_b128 v[14:17], v14 offset:3072
	s_mov_b32 m0, s47
	ds_read_b128 v[18:21], v169 offset:32768
	ds_read_b128 v[22:25], v169 offset:33792
	ds_read_b128 v[26:29], v169 offset:34816
	ds_read_b128 v[30:33], v169 offset:35840
	ds_read_b128 v[202:205], v169 offset:36864
	ds_read_b128 v[206:209], v169 offset:37888
	ds_read_b128 v[210:213], v169 offset:38912
	ds_read_b128 v[214:217], v169 offset:39936
	global_load_lds_dwordx4 v175, s[38:39]
	s_mov_b32 m0, s48
	s_nop 0
	global_load_lds_dwordx4 v173, s[38:39]
	s_waitcnt lgkmcnt(8)
	s_waitcnt vmcnt(10)
	s_barrier
	s_waitcnt lgkmcnt(0)
	v_mfma_scale_f32_16x16x128_f8f6f4 v[158:161], v[2:9], v[18:25], v[158:161], v188, v188 op_sel_hi:[0,0,0]
	v_mfma_scale_f32_16x16x128_f8f6f4 v[150:153], v[10:17], v[18:25], v[150:153], v188, v188 op_sel_hi:[0,0,0]
	v_mfma_scale_f32_16x16x128_f8f6f4 v[142:145], v[2:9], v[26:33], v[142:145], v188, v188 op_sel_hi:[0,0,0]
	v_mfma_scale_f32_16x16x128_f8f6f4 v[134:137], v[10:17], v[26:33], v[134:137], v188, v188 op_sel_hi:[0,0,0]
	v_mfma_scale_f32_16x16x128_f8f6f4 v[126:129], v[2:9], v[202:209], v[126:129], v188, v188 op_sel_hi:[0,0,0]
	v_mfma_scale_f32_16x16x128_f8f6f4 v[118:121], v[10:17], v[202:209], v[118:121], v188, v188 op_sel_hi:[0,0,0]
	v_mfma_scale_f32_16x16x128_f8f6f4 v[110:113], v[2:9], v[210:217], v[110:113], v188, v188 op_sel_hi:[0,0,0]
	v_mfma_scale_f32_16x16x128_f8f6f4 v[102:105], v[10:17], v[210:217], v[102:105], v188, v188 op_sel_hi:[0,0,0]
	s_barrier
	s_add_i32 s36, 0, 0x1c000
	s_add_i32 s0, s0, s43
	v_add_u32_e32 v162, s36, v197
	v_lshl_add_u64 v[180:181], v[180:181], 0, s[22:23]
	s_mov_b32 m0, s0
	ds_read_b128 v[218:221], v162
	ds_read_b128 v[222:225], v162 offset:1024
	ds_read_b128 v[226:229], v162 offset:2048
	ds_read_b128 v[230:233], v162 offset:3072
	global_load_lds_dwordx4 v[180:181], off
	v_lshl_add_u64 v[180:181], v[182:183], 0, s[22:23]
	s_add_i32 m0, s0, 0x2000
	s_nop 0
	global_load_lds_dwordx4 v[180:181], off
	s_waitcnt vmcnt(10)
	s_barrier
	s_waitcnt lgkmcnt(0)
	v_mfma_scale_f32_16x16x128_f8f6f4 v[154:157], v[218:225], v[18:25], v[154:157], v188, v188 op_sel_hi:[0,0,0]
	v_mfma_scale_f32_16x16x128_f8f6f4 v[146:149], v[226:233], v[18:25], v[146:149], v188, v188 op_sel_hi:[0,0,0]
	v_mfma_scale_f32_16x16x128_f8f6f4 v[138:141], v[218:225], v[26:33], v[138:141], v188, v188 op_sel_hi:[0,0,0]
	v_mfma_scale_f32_16x16x128_f8f6f4 v[130:133], v[226:233], v[26:33], v[130:133], v188, v188 op_sel_hi:[0,0,0]
	v_mfma_scale_f32_16x16x128_f8f6f4 v[122:125], v[218:225], v[202:209], v[122:125], v188, v188 op_sel_hi:[0,0,0]
	v_mfma_scale_f32_16x16x128_f8f6f4 v[114:117], v[226:233], v[202:209], v[114:117], v188, v188 op_sel_hi:[0,0,0]
	v_mfma_scale_f32_16x16x128_f8f6f4 v[106:109], v[218:225], v[210:217], v[106:109], v188, v188 op_sel_hi:[0,0,0]
	v_mfma_scale_f32_16x16x128_f8f6f4 v[98:101], v[226:233], v[210:217], v[98:101], v188, v188 op_sel_hi:[0,0,0]
	s_mov_b32 m0, s51
	v_lshl_add_u64 v[180:181], v[186:187], 0, s[22:23]
	s_barrier
	ds_read_b128 v[18:21], v169 offset:49152
	ds_read_b128 v[22:25], v169 offset:50176
	ds_read_b128 v[26:29], v169 offset:51200
	ds_read_b128 v[30:33], v169 offset:52224
	ds_read_b128 v[202:205], v169 offset:53248
	ds_read_b128 v[206:209], v169 offset:54272
	ds_read_b128 v[210:213], v169 offset:55296
	ds_read_b128 v[214:217], v169 offset:56320
	global_load_lds_dwordx4 v[180:181], off
	v_lshl_add_u64 v[180:181], v[184:185], 0, s[22:23]
	s_mov_b32 m0, s52
	s_nop 0
	global_load_lds_dwordx4 v[180:181], off
	s_waitcnt vmcnt(10)
	s_barrier
	s_waitcnt lgkmcnt(0)
	v_mfma_scale_f32_16x16x128_f8f6f4 v[94:97], v[2:9], v[18:25], v[94:97], v188, v188 op_sel_hi:[0,0,0]
	v_mfma_scale_f32_16x16x128_f8f6f4 v[86:89], v[10:17], v[18:25], v[86:89], v188, v188 op_sel_hi:[0,0,0]
	v_mfma_scale_f32_16x16x128_f8f6f4 v[78:81], v[2:9], v[26:33], v[78:81], v188, v188 op_sel_hi:[0,0,0]
	v_mfma_scale_f32_16x16x128_f8f6f4 v[70:73], v[10:17], v[26:33], v[70:73], v188, v188 op_sel_hi:[0,0,0]
	v_mfma_scale_f32_16x16x128_f8f6f4 v[62:65], v[2:9], v[202:209], v[62:65], v188, v188 op_sel_hi:[0,0,0]
	v_mfma_scale_f32_16x16x128_f8f6f4 v[54:57], v[10:17], v[202:209], v[54:57], v188, v188 op_sel_hi:[0,0,0]
	v_mfma_scale_f32_16x16x128_f8f6f4 v[46:49], v[2:9], v[210:217], v[46:49], v188, v188 op_sel_hi:[0,0,0]
	v_mfma_scale_f32_16x16x128_f8f6f4 v[38:41], v[10:17], v[210:217], v[38:41], v188, v188 op_sel_hi:[0,0,0]
	s_barrier
	s_add_u32 s0, s34, 0x20080
	s_addc_u32 s1, s35, 0
	s_add_i32 s34, s36, s43
	v_lshl_add_u64 v[2:3], s[0:1], 0, v[164:165]
	s_mov_b32 m0, s34
	s_nop 0
	global_load_lds_dwordx4 v[2:3], off
	v_lshl_add_u64 v[2:3], s[0:1], 0, v[166:167]
	s_add_i32 m0, s34, 0x2000
	s_nop 0
	global_load_lds_dwordx4 v[2:3], off
	s_waitcnt vmcnt(10)
	s_barrier
	v_mfma_scale_f32_16x16x128_f8f6f4 v[90:93], v[218:225], v[18:25], v[90:93], v188, v188 op_sel_hi:[0,0,0]
	v_mfma_scale_f32_16x16x128_f8f6f4 v[82:85], v[226:233], v[18:25], v[82:85], v188, v188 op_sel_hi:[0,0,0]
	v_mfma_scale_f32_16x16x128_f8f6f4 v[74:77], v[218:225], v[26:33], v[74:77], v188, v188 op_sel_hi:[0,0,0]
	v_mfma_scale_f32_16x16x128_f8f6f4 v[66:69], v[226:233], v[26:33], v[66:69], v188, v188 op_sel_hi:[0,0,0]
	v_mfma_scale_f32_16x16x128_f8f6f4 v[58:61], v[218:225], v[202:209], v[58:61], v188, v188 op_sel_hi:[0,0,0]
	v_mfma_scale_f32_16x16x128_f8f6f4 v[50:53], v[226:233], v[202:209], v[50:53], v188, v188 op_sel_hi:[0,0,0]
	v_mfma_scale_f32_16x16x128_f8f6f4 v[42:45], v[218:225], v[210:217], v[42:45], v188, v188 op_sel_hi:[0,0,0]
	v_mfma_scale_f32_16x16x128_f8f6f4 v[34:37], v[226:233], v[210:217], v[34:37], v188, v188 op_sel_hi:[0,0,0]
	s_add_i32 s56, s56, 2
	s_cmp_gt_u32 s56, 5
	s_mov_b64 s[36:37], s[12:13]
	s_barrier
	s_cbranch_scc0 .LBB0_1302
	v_mul_f32_e32 v5, 0x3c800000, v158
	v_mul_f32_e32 v6, 0xbfb8aa3b, v5
	v_exp_f32_e32 v6, v6
	s_ashr_i32 s31, s30, 31
	s_ashr_i32 s29, s28, 31
	s_lshl_b64 s[12:13], s[30:31], 18
	v_add_f32_e32 v6, 1.0, v6
	v_rcp_f32_e32 v6, v6
	s_lshl_b64 s[28:29], s[28:29], 15
	v_mov_b32_e32 v3, v195
	s_add_u32 s0, s6, s12
	v_mul_f32_e32 v5, v5, v6
	v_mul_f32_e32 v6, 0x3c800000, v159
	v_mul_f32_e32 v7, 0xbfb8aa3b, v6
	v_exp_f32_e32 v7, v7
	v_mul_f32_e32 v5, v5, v154
	v_mul_f32_e32 v5, 0x3e000000, v5
	v_med3_f32 v5, v5, s40, v190
	v_add_f32_e32 v7, 1.0, v7
	v_rcp_f32_e32 v7, v7
	s_nop 15
	s_nop 15
	v_mov_b32_e32 v2, v196
	v_mul_f32_e32 v6, v6, v7
	v_mul_f32_e32 v7, 0x3c800000, v160
	v_mul_f32_e32 v8, 0xbfb8aa3b, v7
	v_exp_f32_e32 v8, v8
	v_mul_f32_e32 v6, v6, v155
	v_mul_f32_e32 v6, 0x3e000000, v6
	v_add_u32_e32 v4, s49, v3
	v_add_f32_e32 v8, 1.0, v8
	v_rcp_f32_e32 v8, v8
	s_addc_u32 s1, s7, s13
	s_add_u32 s12, s0, s28
	v_mul_f32_e32 v7, v7, v8
	v_mul_f32_e32 v8, 0x3c800000, v161
	v_mul_f32_e32 v9, 0xbfb8aa3b, v8
	v_exp_f32_e32 v9, v9
	v_mul_f32_e32 v7, v7, v156
	v_mul_f32_e32 v7, 0x3e000000, v7
	v_lshl_add_u32 v2, v2, 3, s50
	v_add_f32_e32 v9, 1.0, v9
	v_rcp_f32_e32 v9, v9
	s_addc_u32 s13, s1, s29
	v_ashrrev_i32_e32 v3, 31, v2
	s_and_b64 vcc, exec, s[8:9]
	v_mul_f32_e32 v8, v8, v9
	v_mul_f32_e32 v9, 0x3c800000, v150
	v_mul_f32_e32 v10, 0xbfb8aa3b, v9
	v_exp_f32_e32 v10, v10
	v_mul_f32_e32 v8, v8, v157
	v_mul_f32_e32 v8, 0x3e000000, v8
	v_mov_b32_e32 v174, v200
	v_add_f32_e32 v10, 1.0, v10
	v_rcp_f32_e32 v10, v10
	v_mov_b32_e32 v172, v199
	v_mov_b32_e32 v170, v198
	v_mov_b32_e32 v168, v171
	v_mul_f32_e32 v9, v9, v10
	v_mul_f32_e32 v10, 0x3c800000, v151
	v_mul_f32_e32 v11, 0xbfb8aa3b, v10
	v_exp_f32_e32 v11, v11
	v_mul_f32_e32 v9, v9, v146
	v_mul_f32_e32 v9, 0x3e000000, v9
	s_mov_b32 s28, s26
	v_add_f32_e32 v11, 1.0, v11
	v_rcp_f32_e32 v11, v11
	s_mov_b32 s30, s54
	s_mov_b64 s[34:35], s[14:15]
	v_mul_f32_e32 v10, v10, v11
	v_mul_f32_e32 v11, 0x3c800000, v152
	v_mul_f32_e32 v12, 0xbfb8aa3b, v11
	v_exp_f32_e32 v12, v12
	v_mul_f32_e32 v10, v10, v147
	v_mul_f32_e32 v10, 0x3e000000, v10
	v_add_f32_e32 v12, 1.0, v12
	v_rcp_f32_e32 v12, v12
	s_nop 0
	v_mul_f32_e32 v11, v11, v12
	v_mul_f32_e32 v12, 0x3c800000, v153
	v_mul_f32_e32 v13, 0xbfb8aa3b, v12
	v_exp_f32_e32 v13, v13
	v_mul_f32_e32 v11, v11, v148
	v_mul_f32_e32 v11, 0x3e000000, v11
	v_add_f32_e32 v13, 1.0, v13
	v_rcp_f32_e32 v13, v13
	s_nop 0
	v_mul_f32_e32 v12, v12, v13
	v_med3_f32 v13, v6, s40, v190
	v_mov_b32_e32 v6, v163
	v_cvt_pk_fp8_f32 v6, v5, v13
	v_med3_f32 v5, v7, s40, v190
	v_med3_f32 v7, v8, s40, v190
	v_med3_f32 v8, v10, s40, v190
	v_cvt_pk_fp8_f32 v6, v5, v7 op_sel:[0,0,1]
	v_med3_f32 v5, v9, s40, v190
	v_mov_b32_e32 v7, v163
	v_cvt_pk_fp8_f32 v7, v5, v8
	v_mul_f32_e32 v12, v12, v149
	v_mul_f32_e32 v12, 0x3e000000, v12
	v_med3_f32 v5, v11, s40, v190
	v_med3_f32 v8, v12, s40, v190
	v_cvt_pk_fp8_f32 v7, v5, v8 op_sel:[0,0,1]
	v_ashrrev_i32_e32 v5, 31, v4
	v_lshlrev_b64 v[8:9], 7, v[4:5]
	v_lshl_add_u64 v[8:9], s[12:13], 0, v[8:9]
	v_lshl_add_u64 v[8:9], v[8:9], 0, v[2:3]
	v_mul_f32_e32 v5, 0x3c800000, v142
	global_store_dwordx2 v[8:9], v[6:7], off
	v_mul_f32_e32 v6, 0xbfb8aa3b, v5
	v_exp_f32_e32 v6, v6
	s_nop 0
	v_add_f32_e32 v6, 1.0, v6
	v_rcp_f32_e32 v6, v6
	s_nop 0
	v_mul_f32_e32 v5, v5, v6
	v_mul_f32_e32 v6, 0x3c800000, v143
	v_mul_f32_e32 v7, 0xbfb8aa3b, v6
	v_exp_f32_e32 v7, v7
	v_mul_f32_e32 v5, v5, v138
	v_mul_f32_e32 v5, 0x3e000000, v5
	v_med3_f32 v5, v5, s40, v190
	v_add_f32_e32 v7, 1.0, v7
	v_rcp_f32_e32 v7, v7
	s_nop 0
	v_mul_f32_e32 v6, v6, v7
	v_mul_f32_e32 v6, v6, v139
	v_mul_f32_e32 v7, 0x3e000000, v6
	v_mul_f32_e32 v6, 0x3c800000, v144
	v_mul_f32_e32 v8, 0xbfb8aa3b, v6
	v_exp_f32_e32 v8, v8
	v_med3_f32 v7, v7, s40, v190
	v_add_f32_e32 v8, 1.0, v8
	v_rcp_f32_e32 v8, v8
	s_nop 0
	v_mul_f32_e32 v6, v6, v8
	v_mul_f32_e32 v6, v6, v140
	v_mul_f32_e32 v9, 0x3e000000, v6
	v_mul_f32_e32 v6, 0x3c800000, v145
	v_mul_f32_e32 v8, 0xbfb8aa3b, v6
	v_exp_f32_e32 v8, v8
	s_nop 0
	v_add_f32_e32 v8, 1.0, v8
	v_rcp_f32_e32 v8, v8
	s_nop 0
	v_mul_f32_e32 v6, v6, v8
	v_mul_f32_e32 v6, v6, v141
	v_mul_f32_e32 v10, 0x3e000000, v6
	v_mul_f32_e32 v6, 0x3c800000, v134
	v_mul_f32_e32 v8, 0xbfb8aa3b, v6
	v_exp_f32_e32 v8, v8
	s_nop 0
	v_add_f32_e32 v8, 1.0, v8
	v_rcp_f32_e32 v8, v8
	s_nop 0
	v_mul_f32_e32 v6, v6, v8
	v_mul_f32_e32 v6, v6, v130
	v_mul_f32_e32 v11, 0x3e000000, v6
	v_mul_f32_e32 v6, 0x3c800000, v135
	v_mul_f32_e32 v8, 0xbfb8aa3b, v6
	v_exp_f32_e32 v8, v8
	s_nop 0
	v_add_f32_e32 v8, 1.0, v8
	v_rcp_f32_e32 v8, v8
	s_nop 0
	v_mul_f32_e32 v6, v6, v8
	v_mul_f32_e32 v6, v6, v131
	v_mul_f32_e32 v12, 0x3e000000, v6
	v_mul_f32_e32 v6, 0x3c800000, v136
	v_mul_f32_e32 v8, 0xbfb8aa3b, v6
	v_exp_f32_e32 v8, v8
	s_nop 0
	v_add_f32_e32 v8, 1.0, v8
	v_rcp_f32_e32 v8, v8
	s_nop 0
	v_mul_f32_e32 v6, v6, v8
	v_mul_f32_e32 v6, v6, v132
	v_mul_f32_e32 v13, 0x3e000000, v6
	v_mul_f32_e32 v6, 0x3c800000, v137
	v_mul_f32_e32 v8, 0xbfb8aa3b, v6
	v_exp_f32_e32 v8, v8
	s_nop 0
	v_add_f32_e32 v8, 1.0, v8
	v_rcp_f32_e32 v8, v8
	s_nop 0
	v_mul_f32_e32 v6, v6, v8
	v_mov_b32_e32 v8, v163
	v_cvt_pk_fp8_f32 v8, v5, v7
	v_med3_f32 v5, v9, s40, v190
	v_med3_f32 v7, v10, s40, v190
	v_mov_b32_e32 v9, v163
	v_cvt_pk_fp8_f32 v8, v5, v7 op_sel:[0,0,1]
	v_med3_f32 v5, v11, s40, v190
	v_med3_f32 v7, v12, s40, v190
	v_cvt_pk_fp8_f32 v9, v5, v7
	v_mul_f32_e32 v6, v6, v133
	v_mul_f32_e32 v14, 0x3e000000, v6
	v_add_u32_e32 v6, 16, v4
	v_med3_f32 v5, v13, s40, v190
	v_med3_f32 v7, v14, s40, v190
	v_cvt_pk_fp8_f32 v9, v5, v7 op_sel:[0,0,1]
	v_ashrrev_i32_e32 v7, 31, v6
	v_lshlrev_b64 v[6:7], 7, v[6:7]
	v_lshl_add_u64 v[6:7], s[12:13], 0, v[6:7]
	v_lshl_add_u64 v[6:7], v[6:7], 0, v[2:3]
	v_mul_f32_e32 v5, 0x3c800000, v126
	global_store_dwordx2 v[6:7], v[8:9], off
	v_mul_f32_e32 v6, 0xbfb8aa3b, v5
	v_exp_f32_e32 v6, v6
	s_nop 0
	v_add_f32_e32 v6, 1.0, v6
	v_rcp_f32_e32 v6, v6
	s_nop 0
	v_mul_f32_e32 v5, v5, v6
	v_mul_f32_e32 v6, 0x3c800000, v127
	v_mul_f32_e32 v7, 0xbfb8aa3b, v6
	v_exp_f32_e32 v7, v7
	v_mul_f32_e32 v5, v5, v122
	v_mul_f32_e32 v5, 0x3e000000, v5
	v_med3_f32 v5, v5, s40, v190
	v_add_f32_e32 v7, 1.0, v7
	v_rcp_f32_e32 v7, v7
	s_nop 0
	v_mul_f32_e32 v6, v6, v7
	v_mul_f32_e32 v6, v6, v123
	v_mul_f32_e32 v7, 0x3e000000, v6
	v_mul_f32_e32 v6, 0x3c800000, v128
	v_mul_f32_e32 v8, 0xbfb8aa3b, v6
	v_exp_f32_e32 v8, v8
	v_med3_f32 v7, v7, s40, v190
	v_add_f32_e32 v8, 1.0, v8
	v_rcp_f32_e32 v8, v8
	s_nop 0
	v_mul_f32_e32 v6, v6, v8
	v_mul_f32_e32 v6, v6, v124
	v_mul_f32_e32 v9, 0x3e000000, v6
	v_mul_f32_e32 v6, 0x3c800000, v129
	v_mul_f32_e32 v8, 0xbfb8aa3b, v6
	v_exp_f32_e32 v8, v8
	s_nop 0
	v_add_f32_e32 v8, 1.0, v8
	v_rcp_f32_e32 v8, v8
	s_nop 0
	v_mul_f32_e32 v6, v6, v8
	v_mul_f32_e32 v6, v6, v125
	v_mul_f32_e32 v10, 0x3e000000, v6
	v_mul_f32_e32 v6, 0x3c800000, v118
	v_mul_f32_e32 v8, 0xbfb8aa3b, v6
	v_exp_f32_e32 v8, v8
	s_nop 0
	v_add_f32_e32 v8, 1.0, v8
	v_rcp_f32_e32 v8, v8
	s_nop 0
	v_mul_f32_e32 v6, v6, v8
	v_mul_f32_e32 v6, v6, v114
	v_mul_f32_e32 v11, 0x3e000000, v6
	v_mul_f32_e32 v6, 0x3c800000, v119
	v_mul_f32_e32 v8, 0xbfb8aa3b, v6
	v_exp_f32_e32 v8, v8
	s_nop 0
	v_add_f32_e32 v8, 1.0, v8
	v_rcp_f32_e32 v8, v8
	s_nop 0
	v_mul_f32_e32 v6, v6, v8
	v_mul_f32_e32 v6, v6, v115
	v_mul_f32_e32 v12, 0x3e000000, v6
	v_mul_f32_e32 v6, 0x3c800000, v120
	v_mul_f32_e32 v8, 0xbfb8aa3b, v6
	v_exp_f32_e32 v8, v8
	s_nop 0
	v_add_f32_e32 v8, 1.0, v8
	v_rcp_f32_e32 v8, v8
	s_nop 0
	v_mul_f32_e32 v6, v6, v8
	v_mul_f32_e32 v6, v6, v116
	v_mul_f32_e32 v13, 0x3e000000, v6
	v_mul_f32_e32 v6, 0x3c800000, v121
	v_mul_f32_e32 v8, 0xbfb8aa3b, v6
	v_exp_f32_e32 v8, v8
	s_nop 0
	v_add_f32_e32 v8, 1.0, v8
	v_rcp_f32_e32 v8, v8
	s_nop 0
	v_mul_f32_e32 v6, v6, v8
	v_mov_b32_e32 v8, v163
	v_cvt_pk_fp8_f32 v8, v5, v7
	v_med3_f32 v5, v9, s40, v190
	v_med3_f32 v7, v10, s40, v190
	v_mov_b32_e32 v9, v163
	v_cvt_pk_fp8_f32 v8, v5, v7 op_sel:[0,0,1]
	v_med3_f32 v5, v11, s40, v190
	v_med3_f32 v7, v12, s40, v190
	v_cvt_pk_fp8_f32 v9, v5, v7
	v_mul_f32_e32 v6, v6, v117
	v_mul_f32_e32 v14, 0x3e000000, v6
	v_add_u32_e32 v6, 32, v4
	v_med3_f32 v5, v13, s40, v190
	v_med3_f32 v7, v14, s40, v190
	v_cvt_pk_fp8_f32 v9, v5, v7 op_sel:[0,0,1]
	v_ashrrev_i32_e32 v7, 31, v6
	v_lshlrev_b64 v[6:7], 7, v[6:7]
	v_lshl_add_u64 v[6:7], s[12:13], 0, v[6:7]
	v_lshl_add_u64 v[6:7], v[6:7], 0, v[2:3]
	v_mul_f32_e32 v5, 0x3c800000, v110
	global_store_dwordx2 v[6:7], v[8:9], off
	v_mul_f32_e32 v6, 0xbfb8aa3b, v5
	v_exp_f32_e32 v6, v6
	s_nop 0
	v_add_f32_e32 v6, 1.0, v6
	v_rcp_f32_e32 v6, v6
	s_nop 0
	v_mul_f32_e32 v5, v5, v6
	v_mul_f32_e32 v6, 0x3c800000, v111
	v_mul_f32_e32 v7, 0xbfb8aa3b, v6
	v_exp_f32_e32 v7, v7
	v_mul_f32_e32 v5, v5, v106
	v_mul_f32_e32 v5, 0x3e000000, v5
	v_med3_f32 v5, v5, s40, v190
	v_add_f32_e32 v7, 1.0, v7
	v_rcp_f32_e32 v7, v7
	s_nop 0
	v_mul_f32_e32 v6, v6, v7
	v_mul_f32_e32 v6, v6, v107
	v_mul_f32_e32 v7, 0x3e000000, v6
	v_mul_f32_e32 v6, 0x3c800000, v112
	v_mul_f32_e32 v8, 0xbfb8aa3b, v6
	v_exp_f32_e32 v8, v8
	v_med3_f32 v7, v7, s40, v190
	v_add_f32_e32 v8, 1.0, v8
	v_rcp_f32_e32 v8, v8
	s_nop 0
	v_mul_f32_e32 v6, v6, v8
	v_mul_f32_e32 v6, v6, v108
	v_mul_f32_e32 v9, 0x3e000000, v6
	v_mul_f32_e32 v6, 0x3c800000, v113
	v_mul_f32_e32 v8, 0xbfb8aa3b, v6
	v_exp_f32_e32 v8, v8
	s_nop 0
	v_add_f32_e32 v8, 1.0, v8
	v_rcp_f32_e32 v8, v8
	s_nop 0
	v_mul_f32_e32 v6, v6, v8
	v_mul_f32_e32 v6, v6, v109
	v_mul_f32_e32 v10, 0x3e000000, v6
	v_mul_f32_e32 v6, 0x3c800000, v102
	v_mul_f32_e32 v8, 0xbfb8aa3b, v6
	v_exp_f32_e32 v8, v8
	s_nop 0
	v_add_f32_e32 v8, 1.0, v8
	v_rcp_f32_e32 v8, v8
	s_nop 0
	v_mul_f32_e32 v6, v6, v8
	v_mul_f32_e32 v6, v6, v98
	v_mul_f32_e32 v11, 0x3e000000, v6
	v_mul_f32_e32 v6, 0x3c800000, v103
	v_mul_f32_e32 v8, 0xbfb8aa3b, v6
	v_exp_f32_e32 v8, v8
	s_nop 0
	v_add_f32_e32 v8, 1.0, v8
	v_rcp_f32_e32 v8, v8
	s_nop 0
	v_mul_f32_e32 v6, v6, v8
	v_mul_f32_e32 v6, v6, v99
	v_mul_f32_e32 v12, 0x3e000000, v6
	v_mul_f32_e32 v6, 0x3c800000, v104
	v_mul_f32_e32 v8, 0xbfb8aa3b, v6
	v_exp_f32_e32 v8, v8
	s_nop 0
	v_add_f32_e32 v8, 1.0, v8
	v_rcp_f32_e32 v8, v8
	s_nop 0
	v_mul_f32_e32 v6, v6, v8
	v_mul_f32_e32 v6, v6, v100
	v_mul_f32_e32 v13, 0x3e000000, v6
	v_mul_f32_e32 v6, 0x3c800000, v105
	v_mul_f32_e32 v8, 0xbfb8aa3b, v6
	v_exp_f32_e32 v8, v8
	s_nop 0
	v_add_f32_e32 v8, 1.0, v8
	v_rcp_f32_e32 v8, v8
	s_nop 0
	v_mul_f32_e32 v6, v6, v8
	v_mov_b32_e32 v8, v163
	v_cvt_pk_fp8_f32 v8, v5, v7
	v_med3_f32 v5, v9, s40, v190
	v_med3_f32 v7, v10, s40, v190
	v_mov_b32_e32 v9, v163
	v_cvt_pk_fp8_f32 v8, v5, v7 op_sel:[0,0,1]
	v_med3_f32 v5, v11, s40, v190
	v_med3_f32 v7, v12, s40, v190
	v_cvt_pk_fp8_f32 v9, v5, v7
	v_mul_f32_e32 v6, v6, v101
	v_mul_f32_e32 v14, 0x3e000000, v6
	v_add_u32_e32 v6, 48, v4
	v_med3_f32 v5, v13, s40, v190
	v_med3_f32 v7, v14, s40, v190
	v_cvt_pk_fp8_f32 v9, v5, v7 op_sel:[0,0,1]
	v_ashrrev_i32_e32 v7, 31, v6
	v_lshlrev_b64 v[6:7], 7, v[6:7]
	v_lshl_add_u64 v[6:7], s[12:13], 0, v[6:7]
	v_lshl_add_u64 v[6:7], v[6:7], 0, v[2:3]
	v_mul_f32_e32 v5, 0x3c800000, v94
	global_store_dwordx2 v[6:7], v[8:9], off
	v_mul_f32_e32 v7, 0xbfb8aa3b, v5
	v_exp_f32_e32 v7, v7
	v_add_u32_e32 v6, 0x80, v4
	v_add_f32_e32 v7, 1.0, v7
	v_rcp_f32_e32 v7, v7
	s_nop 0
	v_mul_f32_e32 v5, v5, v7
	v_mul_f32_e32 v7, 0x3c800000, v95
	v_mul_f32_e32 v8, 0xbfb8aa3b, v7
	v_exp_f32_e32 v8, v8
	v_mul_f32_e32 v5, v5, v90
	v_mul_f32_e32 v5, 0x3e000000, v5
	v_med3_f32 v5, v5, s40, v190
	v_add_f32_e32 v8, 1.0, v8
	v_rcp_f32_e32 v8, v8
	s_nop 0
	v_mul_f32_e32 v7, v7, v8
	v_mul_f32_e32 v8, 0x3c800000, v96
	v_mul_f32_e32 v9, 0xbfb8aa3b, v8
	v_exp_f32_e32 v9, v9
	v_mul_f32_e32 v7, v7, v91
	v_mul_f32_e32 v7, 0x3e000000, v7
	v_med3_f32 v7, v7, s40, v190
	v_add_f32_e32 v9, 1.0, v9
	v_rcp_f32_e32 v9, v9
	s_nop 0
	v_mul_f32_e32 v8, v8, v9
	v_mul_f32_e32 v8, v8, v92
	v_mul_f32_e32 v9, 0x3e000000, v8
	v_mul_f32_e32 v8, 0x3c800000, v97
	v_mul_f32_e32 v10, 0xbfb8aa3b, v8
	v_exp_f32_e32 v10, v10
	s_nop 0
	v_add_f32_e32 v10, 1.0, v10
	v_rcp_f32_e32 v10, v10
	s_nop 0
	v_mul_f32_e32 v8, v8, v10
	v_mul_f32_e32 v8, v8, v93
	v_mul_f32_e32 v10, 0x3e000000, v8
	v_mul_f32_e32 v8, 0x3c800000, v86
	v_mul_f32_e32 v11, 0xbfb8aa3b, v8
	v_exp_f32_e32 v11, v11
	s_nop 0
	v_add_f32_e32 v11, 1.0, v11
	v_rcp_f32_e32 v11, v11
	s_nop 0
	v_mul_f32_e32 v8, v8, v11
	v_mul_f32_e32 v8, v8, v82
	v_mul_f32_e32 v11, 0x3e000000, v8
	v_mul_f32_e32 v8, 0x3c800000, v87
	v_mul_f32_e32 v12, 0xbfb8aa3b, v8
	v_exp_f32_e32 v12, v12
	s_nop 0
	v_add_f32_e32 v12, 1.0, v12
	v_rcp_f32_e32 v12, v12
	s_nop 0
	v_mul_f32_e32 v8, v8, v12
	v_mul_f32_e32 v8, v8, v83
	v_mul_f32_e32 v12, 0x3e000000, v8
	v_mul_f32_e32 v8, 0x3c800000, v88
	v_mul_f32_e32 v13, 0xbfb8aa3b, v8
	v_exp_f32_e32 v13, v13
	s_nop 0
	v_add_f32_e32 v13, 1.0, v13
	v_rcp_f32_e32 v13, v13
	s_nop 0
	v_mul_f32_e32 v8, v8, v13
	v_mul_f32_e32 v8, v8, v84
	v_mul_f32_e32 v13, 0x3e000000, v8
	v_mul_f32_e32 v8, 0x3c800000, v89
	v_mul_f32_e32 v14, 0xbfb8aa3b, v8
	v_exp_f32_e32 v14, v14
	s_nop 0
	v_add_f32_e32 v14, 1.0, v14
	v_rcp_f32_e32 v14, v14
	s_nop 0
	v_mul_f32_e32 v8, v8, v14
	v_mul_f32_e32 v8, v8, v85
	v_mul_f32_e32 v14, 0x3e000000, v8
	v_mov_b32_e32 v8, v163
	v_cvt_pk_fp8_f32 v8, v5, v7
	v_med3_f32 v5, v9, s40, v190
	v_med3_f32 v7, v10, s40, v190
	v_mov_b32_e32 v9, v163
	v_cvt_pk_fp8_f32 v8, v5, v7 op_sel:[0,0,1]
	v_med3_f32 v5, v11, s40, v190
	v_med3_f32 v7, v12, s40, v190
	v_cvt_pk_fp8_f32 v9, v5, v7
	v_med3_f32 v5, v13, s40, v190
	v_med3_f32 v7, v14, s40, v190
	v_cvt_pk_fp8_f32 v9, v5, v7 op_sel:[0,0,1]
	v_ashrrev_i32_e32 v7, 31, v6
	v_lshlrev_b64 v[6:7], 7, v[6:7]
	v_lshl_add_u64 v[6:7], s[12:13], 0, v[6:7]
	v_lshl_add_u64 v[6:7], v[6:7], 0, v[2:3]
	v_mul_f32_e32 v5, 0x3c800000, v78
	global_store_dwordx2 v[6:7], v[8:9], off
	v_mul_f32_e32 v6, 0xbfb8aa3b, v5
	v_exp_f32_e32 v6, v6
	s_nop 0
	v_add_f32_e32 v6, 1.0, v6
	v_rcp_f32_e32 v6, v6
	s_nop 0
	v_mul_f32_e32 v5, v5, v6
	v_mul_f32_e32 v6, 0x3c800000, v79
	v_mul_f32_e32 v7, 0xbfb8aa3b, v6
	v_exp_f32_e32 v7, v7
	v_mul_f32_e32 v5, v5, v74
	v_mul_f32_e32 v5, 0x3e000000, v5
	v_med3_f32 v5, v5, s40, v190
	v_add_f32_e32 v7, 1.0, v7
	v_rcp_f32_e32 v7, v7
	s_nop 0
	v_mul_f32_e32 v6, v6, v7
	v_mul_f32_e32 v6, v6, v75
	v_mul_f32_e32 v7, 0x3e000000, v6
	v_mul_f32_e32 v6, 0x3c800000, v80
	v_mul_f32_e32 v8, 0xbfb8aa3b, v6
	v_exp_f32_e32 v8, v8
	v_med3_f32 v7, v7, s40, v190
	v_add_f32_e32 v8, 1.0, v8
	v_rcp_f32_e32 v8, v8
	s_nop 0
	v_mul_f32_e32 v6, v6, v8
	v_mul_f32_e32 v6, v6, v76
	v_mul_f32_e32 v9, 0x3e000000, v6
	v_mul_f32_e32 v6, 0x3c800000, v81
	v_mul_f32_e32 v8, 0xbfb8aa3b, v6
	v_exp_f32_e32 v8, v8
	s_nop 0
	v_add_f32_e32 v8, 1.0, v8
	v_rcp_f32_e32 v8, v8
	s_nop 0
	v_mul_f32_e32 v6, v6, v8
	v_mul_f32_e32 v6, v6, v77
	v_mul_f32_e32 v10, 0x3e000000, v6
	v_mul_f32_e32 v6, 0x3c800000, v70
	v_mul_f32_e32 v8, 0xbfb8aa3b, v6
	v_exp_f32_e32 v8, v8
	s_nop 0
	v_add_f32_e32 v8, 1.0, v8
	v_rcp_f32_e32 v8, v8
	s_nop 0
	v_mul_f32_e32 v6, v6, v8
	v_mul_f32_e32 v6, v6, v66
	v_mul_f32_e32 v11, 0x3e000000, v6
	v_mul_f32_e32 v6, 0x3c800000, v71
	v_mul_f32_e32 v8, 0xbfb8aa3b, v6
	v_exp_f32_e32 v8, v8
	s_nop 0
	v_add_f32_e32 v8, 1.0, v8
	v_rcp_f32_e32 v8, v8
	s_nop 0
	v_mul_f32_e32 v6, v6, v8
	v_mul_f32_e32 v6, v6, v67
	v_mul_f32_e32 v12, 0x3e000000, v6
	v_mul_f32_e32 v6, 0x3c800000, v72
	v_mul_f32_e32 v8, 0xbfb8aa3b, v6
	v_exp_f32_e32 v8, v8
	s_nop 0
	v_add_f32_e32 v8, 1.0, v8
	v_rcp_f32_e32 v8, v8
	s_nop 0
	v_mul_f32_e32 v6, v6, v8
	v_mul_f32_e32 v6, v6, v68
	v_mul_f32_e32 v13, 0x3e000000, v6
	v_mul_f32_e32 v6, 0x3c800000, v73
	v_mul_f32_e32 v8, 0xbfb8aa3b, v6
	v_exp_f32_e32 v8, v8
	s_nop 0
	v_add_f32_e32 v8, 1.0, v8
	v_rcp_f32_e32 v8, v8
	s_nop 0
	v_mul_f32_e32 v6, v6, v8
	v_mov_b32_e32 v8, v163
	v_cvt_pk_fp8_f32 v8, v5, v7
	v_med3_f32 v5, v9, s40, v190
	v_med3_f32 v7, v10, s40, v190
	v_mov_b32_e32 v9, v163
	v_cvt_pk_fp8_f32 v8, v5, v7 op_sel:[0,0,1]
	v_med3_f32 v5, v11, s40, v190
	v_med3_f32 v7, v12, s40, v190
	v_cvt_pk_fp8_f32 v9, v5, v7
	v_mul_f32_e32 v6, v6, v69
	v_mul_f32_e32 v14, 0x3e000000, v6
	v_add_u32_e32 v6, 0x90, v4
	v_med3_f32 v5, v13, s40, v190
	v_med3_f32 v7, v14, s40, v190
	v_cvt_pk_fp8_f32 v9, v5, v7 op_sel:[0,0,1]
	v_ashrrev_i32_e32 v7, 31, v6
	v_lshlrev_b64 v[6:7], 7, v[6:7]
	v_lshl_add_u64 v[6:7], s[12:13], 0, v[6:7]
	v_lshl_add_u64 v[6:7], v[6:7], 0, v[2:3]
	v_mul_f32_e32 v5, 0x3c800000, v62
	global_store_dwordx2 v[6:7], v[8:9], off
	v_mul_f32_e32 v6, 0xbfb8aa3b, v5
	v_exp_f32_e32 v6, v6
	s_nop 0
	v_add_f32_e32 v6, 1.0, v6
	v_rcp_f32_e32 v6, v6
	s_nop 0
	v_mul_f32_e32 v5, v5, v6
	v_mul_f32_e32 v6, 0x3c800000, v63
	v_mul_f32_e32 v7, 0xbfb8aa3b, v6
	v_exp_f32_e32 v7, v7
	v_mul_f32_e32 v5, v5, v58
	v_mul_f32_e32 v5, 0x3e000000, v5
	v_med3_f32 v5, v5, s40, v190
	v_add_f32_e32 v7, 1.0, v7
	v_rcp_f32_e32 v7, v7
	s_nop 0
	v_mul_f32_e32 v6, v6, v7
	v_mul_f32_e32 v6, v6, v59
	v_mul_f32_e32 v7, 0x3e000000, v6
	v_mul_f32_e32 v6, 0x3c800000, v64
	v_mul_f32_e32 v8, 0xbfb8aa3b, v6
	v_exp_f32_e32 v8, v8
	v_med3_f32 v7, v7, s40, v190
	v_add_f32_e32 v8, 1.0, v8
	v_rcp_f32_e32 v8, v8
	s_nop 0
	v_mul_f32_e32 v6, v6, v8
	v_mul_f32_e32 v6, v6, v60
	v_mul_f32_e32 v9, 0x3e000000, v6
	v_mul_f32_e32 v6, 0x3c800000, v65
	v_mul_f32_e32 v8, 0xbfb8aa3b, v6
	v_exp_f32_e32 v8, v8
	s_nop 0
	v_add_f32_e32 v8, 1.0, v8
	v_rcp_f32_e32 v8, v8
	s_nop 0
	v_mul_f32_e32 v6, v6, v8
	v_mul_f32_e32 v6, v6, v61
	v_mul_f32_e32 v10, 0x3e000000, v6
	v_mul_f32_e32 v6, 0x3c800000, v54
	v_mul_f32_e32 v8, 0xbfb8aa3b, v6
	v_exp_f32_e32 v8, v8
	s_nop 0
	v_add_f32_e32 v8, 1.0, v8
	v_rcp_f32_e32 v8, v8
	s_nop 0
	v_mul_f32_e32 v6, v6, v8
	v_mul_f32_e32 v6, v6, v50
	v_mul_f32_e32 v11, 0x3e000000, v6
	v_mul_f32_e32 v6, 0x3c800000, v55
	v_mul_f32_e32 v8, 0xbfb8aa3b, v6
	v_exp_f32_e32 v8, v8
	s_nop 0
	v_add_f32_e32 v8, 1.0, v8
	v_rcp_f32_e32 v8, v8
	s_nop 0
	v_mul_f32_e32 v6, v6, v8
	v_mul_f32_e32 v6, v6, v51
	v_mul_f32_e32 v12, 0x3e000000, v6
	v_mul_f32_e32 v6, 0x3c800000, v56
	v_mul_f32_e32 v8, 0xbfb8aa3b, v6
	v_exp_f32_e32 v8, v8
	s_nop 0
	v_add_f32_e32 v8, 1.0, v8
	v_rcp_f32_e32 v8, v8
	s_nop 0
	v_mul_f32_e32 v6, v6, v8
	v_mul_f32_e32 v6, v6, v52
	v_mul_f32_e32 v13, 0x3e000000, v6
	v_mul_f32_e32 v6, 0x3c800000, v57
	v_mul_f32_e32 v8, 0xbfb8aa3b, v6
	v_exp_f32_e32 v8, v8
	s_nop 0
	v_add_f32_e32 v8, 1.0, v8
	v_rcp_f32_e32 v8, v8
	s_nop 0
	v_mul_f32_e32 v6, v6, v8
	v_mov_b32_e32 v8, v163
	v_cvt_pk_fp8_f32 v8, v5, v7
	v_med3_f32 v5, v9, s40, v190
	v_med3_f32 v7, v10, s40, v190
	v_mov_b32_e32 v9, v163
	v_cvt_pk_fp8_f32 v8, v5, v7 op_sel:[0,0,1]
	v_med3_f32 v5, v11, s40, v190
	v_med3_f32 v7, v12, s40, v190
	v_cvt_pk_fp8_f32 v9, v5, v7
	v_mul_f32_e32 v6, v6, v53
	v_mul_f32_e32 v14, 0x3e000000, v6
	v_add_u32_e32 v6, 0xa0, v4
	v_med3_f32 v5, v13, s40, v190
	v_med3_f32 v7, v14, s40, v190
	v_cvt_pk_fp8_f32 v9, v5, v7 op_sel:[0,0,1]
	v_ashrrev_i32_e32 v7, 31, v6
	v_lshlrev_b64 v[6:7], 7, v[6:7]
	v_lshl_add_u64 v[6:7], s[12:13], 0, v[6:7]
	v_lshl_add_u64 v[6:7], v[6:7], 0, v[2:3]
	v_mul_f32_e32 v5, 0x3c800000, v46
	global_store_dwordx2 v[6:7], v[8:9], off
	v_mul_f32_e32 v6, 0xbfb8aa3b, v5
	v_exp_f32_e32 v6, v6
	v_add_u32_e32 v4, 0xb0, v4
	v_add_f32_e32 v6, 1.0, v6
	v_rcp_f32_e32 v6, v6
	s_nop 0
	v_mul_f32_e32 v5, v5, v6
	v_mul_f32_e32 v6, 0x3c800000, v47
	v_mul_f32_e32 v7, 0xbfb8aa3b, v6
	v_exp_f32_e32 v7, v7
	v_mul_f32_e32 v5, v5, v42
	v_mul_f32_e32 v5, 0x3e000000, v5
	v_med3_f32 v5, v5, s40, v190
	v_add_f32_e32 v7, 1.0, v7
	v_rcp_f32_e32 v7, v7
	s_nop 0
	v_mul_f32_e32 v6, v6, v7
	v_mul_f32_e32 v7, 0x3c800000, v48
	v_mul_f32_e32 v8, 0xbfb8aa3b, v7
	v_exp_f32_e32 v8, v8
	v_mul_f32_e32 v6, v6, v43
	v_mul_f32_e32 v6, 0x3e000000, v6
	v_add_f32_e32 v8, 1.0, v8
	v_rcp_f32_e32 v8, v8
	s_nop 0
	v_mul_f32_e32 v7, v7, v8
	v_mul_f32_e32 v8, 0x3c800000, v49
	v_mul_f32_e32 v9, 0xbfb8aa3b, v8
	v_exp_f32_e32 v9, v9
	v_mul_f32_e32 v7, v7, v44
	v_mul_f32_e32 v7, 0x3e000000, v7
	v_add_f32_e32 v9, 1.0, v9
	v_rcp_f32_e32 v9, v9
	s_nop 0
	v_mul_f32_e32 v8, v8, v9
	v_mul_f32_e32 v9, 0x3c800000, v38
	v_mul_f32_e32 v10, 0xbfb8aa3b, v9
	v_exp_f32_e32 v10, v10
	v_mul_f32_e32 v8, v8, v45
	v_mul_f32_e32 v8, 0x3e000000, v8
	v_add_f32_e32 v10, 1.0, v10
	v_rcp_f32_e32 v10, v10
	s_nop 0
	v_mul_f32_e32 v9, v9, v10
	v_mul_f32_e32 v10, 0x3c800000, v39
	v_mul_f32_e32 v11, 0xbfb8aa3b, v10
	v_exp_f32_e32 v11, v11
	v_mul_f32_e32 v9, v9, v34
	v_mul_f32_e32 v9, 0x3e000000, v9
	v_add_f32_e32 v11, 1.0, v11
	v_rcp_f32_e32 v11, v11
	s_nop 0
	v_mul_f32_e32 v10, v10, v11
	v_mul_f32_e32 v11, 0x3c800000, v40
	v_mul_f32_e32 v12, 0xbfb8aa3b, v11
	v_exp_f32_e32 v12, v12
	v_mul_f32_e32 v10, v10, v35
	v_mul_f32_e32 v10, 0x3e000000, v10
	v_add_f32_e32 v12, 1.0, v12
	v_rcp_f32_e32 v12, v12
	s_nop 0
	v_mul_f32_e32 v11, v11, v12
	v_mul_f32_e32 v12, 0x3c800000, v41
	v_mul_f32_e32 v13, 0xbfb8aa3b, v12
	v_exp_f32_e32 v13, v13
	v_mul_f32_e32 v11, v11, v36
	v_mul_f32_e32 v11, 0x3e000000, v11
	v_add_f32_e32 v13, 1.0, v13
	v_rcp_f32_e32 v13, v13
	s_nop 0
	v_mul_f32_e32 v12, v12, v13
	v_med3_f32 v13, v6, s40, v190
	v_mov_b32_e32 v6, v163
	v_cvt_pk_fp8_f32 v6, v5, v13
	v_med3_f32 v5, v7, s40, v190
	v_med3_f32 v7, v8, s40, v190
	v_med3_f32 v8, v10, s40, v190
	v_cvt_pk_fp8_f32 v6, v5, v7 op_sel:[0,0,1]
	v_med3_f32 v5, v9, s40, v190
	v_mov_b32_e32 v7, v163
	v_cvt_pk_fp8_f32 v7, v5, v8
	v_mul_f32_e32 v12, v12, v37
	v_mul_f32_e32 v12, 0x3e000000, v12
	v_med3_f32 v5, v11, s40, v190
	v_med3_f32 v8, v12, s40, v190
	v_cvt_pk_fp8_f32 v7, v5, v8 op_sel:[0,0,1]
	v_ashrrev_i32_e32 v5, 31, v4
	v_lshlrev_b64 v[4:5], 7, v[4:5]
	v_lshl_add_u64 v[4:5], s[12:13], 0, v[4:5]
	v_lshl_add_u64 v[2:3], v[4:5], 0, v[2:3]
	global_store_dwordx2 v[2:3], v[6:7], off
	s_cbranch_vccz .LBB0_1291
	s_waitcnt vmcnt(0)
	s_cmpk_gt_u32 s42, 0xff
	s_cbranch_scc1 .LBB0_1237
	s_barrier
	s_branch .LBB0_1237

.LBB0_1369:
	ds_read_b128 v[2:5], v169
	ds_read_b128 v[6:9], v169 offset:1024
	ds_read_b128 v[10:13], v169 offset:2048
	ds_read_b128 v[14:17], v169 offset:3072
	s_add_u32 s0, s28, 0x4000
	s_addc_u32 s1, s29, 0
	s_cmp_eq_u32 s53, 4
	s_cselect_b32 s36, s49, s0
	s_cselect_b32 s37, s21, s1
	s_cselect_b32 s30, s50, s51
	s_cselect_b32 s31, s19, s52
	s_add_u32 s34, s36, 0x8000
	s_addc_u32 s35, s37, 0
	v_lshl_add_u64 v[162:163], s[28:29], 0, v[156:157]
	s_add_i32 m0, s17, 0xc000
	ds_read_b128 v[174:177], v170
	ds_read_b128 v[178:181], v170 offset:1024
	ds_read_b128 v[182:185], v170 offset:2048
	ds_read_b128 v[186:189], v170 offset:3072
	ds_read_b128 v[190:193], v170 offset:4096
	ds_read_b128 v[194:197], v170 offset:5120
	ds_read_b128 v[198:201], v170 offset:6144
	ds_read_b128 v[202:205], v170 offset:7168
	global_load_lds_dwordx4 v[162:163], off
	v_lshl_add_u64 v[162:163], s[28:29], 0, v[154:155]
	s_add_i32 m0, s17, 0xe000
	s_nop 0
	global_load_lds_dwordx4 v[162:163], off
	s_waitcnt lgkmcnt(8)
	s_waitcnt vmcnt(10)
	s_barrier
	s_waitcnt lgkmcnt(0)
	v_mfma_scale_f32_16x16x128_f8f6f4 v[142:145], v[2:9], v[174:181], v[142:145], v171, v171 op_sel_hi:[0,0,0]
	v_mfma_scale_f32_16x16x128_f8f6f4 v[138:141], v[10:17], v[174:181], v[138:141], v171, v171 op_sel_hi:[0,0,0]
	v_mfma_scale_f32_16x16x128_f8f6f4 v[126:129], v[2:9], v[182:189], v[126:129], v171, v171 op_sel_hi:[0,0,0]
	v_mfma_scale_f32_16x16x128_f8f6f4 v[122:125], v[10:17], v[182:189], v[122:125], v171, v171 op_sel_hi:[0,0,0]
	v_mfma_scale_f32_16x16x128_f8f6f4 v[110:113], v[2:9], v[190:197], v[110:113], v171, v171 op_sel_hi:[0,0,0]
	v_mfma_scale_f32_16x16x128_f8f6f4 v[106:109], v[10:17], v[190:197], v[106:109], v171, v171 op_sel_hi:[0,0,0]
	v_mfma_scale_f32_16x16x128_f8f6f4 v[94:97], v[2:9], v[198:205], v[94:97], v171, v171 op_sel_hi:[0,0,0]
	v_mfma_scale_f32_16x16x128_f8f6f4 v[90:93], v[10:17], v[198:205], v[90:93], v171, v171 op_sel_hi:[0,0,0]
	s_barrier
	s_add_i32 s0, s45, s11
	v_lshl_add_u64 v[162:163], s[30:31], 0, v[150:151]
	s_mov_b32 m0, s0
	ds_read_b128 v[206:209], v172
	ds_read_b128 v[210:213], v172 offset:1024
	ds_read_b128 v[214:217], v172 offset:2048
	ds_read_b128 v[218:221], v172 offset:3072
	global_load_lds_dwordx4 v[162:163], off
	v_lshl_add_u64 v[164:165], s[30:31], 0, v[146:147]
	s_add_i32 m0, s0, 0x2000
	s_nop 0
	global_load_lds_dwordx4 v[164:165], off
	s_waitcnt vmcnt(10)
	s_barrier
	s_waitcnt lgkmcnt(0)
	v_mfma_scale_f32_16x16x128_f8f6f4 v[134:137], v[206:213], v[174:181], v[134:137], v171, v171 op_sel_hi:[0,0,0]
	v_mfma_scale_f32_16x16x128_f8f6f4 v[130:133], v[214:221], v[174:181], v[130:133], v171, v171 op_sel_hi:[0,0,0]
	v_mfma_scale_f32_16x16x128_f8f6f4 v[118:121], v[206:213], v[182:189], v[118:121], v171, v171 op_sel_hi:[0,0,0]
	v_mfma_scale_f32_16x16x128_f8f6f4 v[114:117], v[214:221], v[182:189], v[114:117], v171, v171 op_sel_hi:[0,0,0]
	v_mfma_scale_f32_16x16x128_f8f6f4 v[102:105], v[206:213], v[190:197], v[102:105], v171, v171 op_sel_hi:[0,0,0]
	v_mfma_scale_f32_16x16x128_f8f6f4 v[98:101], v[214:221], v[190:197], v[98:101], v171, v171 op_sel_hi:[0,0,0]
	v_mfma_scale_f32_16x16x128_f8f6f4 v[86:89], v[206:213], v[198:205], v[86:89], v171, v171 op_sel_hi:[0,0,0]
	v_mfma_scale_f32_16x16x128_f8f6f4 v[82:85], v[214:221], v[198:205], v[82:85], v171, v171 op_sel_hi:[0,0,0]
	s_mov_b32 m0, s17
	v_lshl_add_u64 v[222:223], s[36:37], 0, v[152:153]
	s_barrier
	ds_read_b128 v[174:177], v170 offset:16384
	ds_read_b128 v[178:181], v170 offset:17408
	ds_read_b128 v[182:185], v170 offset:18432
	ds_read_b128 v[186:189], v170 offset:19456
	ds_read_b128 v[190:193], v170 offset:20480
	ds_read_b128 v[194:197], v170 offset:21504
	ds_read_b128 v[198:201], v170 offset:22528
	ds_read_b128 v[202:205], v170 offset:23552
	global_load_lds_dwordx4 v[222:223], off
	v_lshl_add_u64 v[222:223], s[36:37], 0, v[148:149]
	s_mov_b32 m0, s27
	s_nop 0
	global_load_lds_dwordx4 v[222:223], off
	s_waitcnt vmcnt(10)
	s_barrier
	s_waitcnt lgkmcnt(0)
	v_mfma_scale_f32_16x16x128_f8f6f4 v[78:81], v[2:9], v[174:181], v[78:81], v171, v171 op_sel_hi:[0,0,0]
	v_mfma_scale_f32_16x16x128_f8f6f4 v[74:77], v[10:17], v[174:181], v[74:77], v171, v171 op_sel_hi:[0,0,0]
	v_mfma_scale_f32_16x16x128_f8f6f4 v[62:65], v[2:9], v[182:189], v[62:65], v171, v171 op_sel_hi:[0,0,0]
	v_mfma_scale_f32_16x16x128_f8f6f4 v[58:61], v[10:17], v[182:189], v[58:61], v171, v171 op_sel_hi:[0,0,0]
	v_mfma_scale_f32_16x16x128_f8f6f4 v[46:49], v[2:9], v[190:197], v[46:49], v171, v171 op_sel_hi:[0,0,0]
	v_mfma_scale_f32_16x16x128_f8f6f4 v[42:45], v[10:17], v[190:197], v[42:45], v171, v171 op_sel_hi:[0,0,0]
	v_mfma_scale_f32_16x16x128_f8f6f4 v[30:33], v[2:9], v[198:205], v[30:33], v171, v171 op_sel_hi:[0,0,0]
	v_mfma_scale_f32_16x16x128_f8f6f4 v[26:29], v[10:17], v[198:205], v[26:29], v171, v171 op_sel_hi:[0,0,0]
	s_barrier
	s_add_u32 s0, s30, 0x20000
	s_addc_u32 s1, s31, 0
	s_add_i32 s54, s46, s11
	v_lshl_add_u64 v[2:3], s[0:1], 0, v[150:151]
	s_mov_b32 m0, s54
	s_nop 0
	global_load_lds_dwordx4 v[2:3], off
	v_lshl_add_u64 v[2:3], s[0:1], 0, v[146:147]
	s_add_i32 m0, s54, 0x2000
	s_nop 0
	global_load_lds_dwordx4 v[2:3], off
	s_waitcnt vmcnt(10)
	s_barrier
	v_mfma_scale_f32_16x16x128_f8f6f4 v[70:73], v[206:213], v[174:181], v[70:73], v171, v171 op_sel_hi:[0,0,0]
	v_mfma_scale_f32_16x16x128_f8f6f4 v[66:69], v[214:221], v[174:181], v[66:69], v171, v171 op_sel_hi:[0,0,0]
	v_mfma_scale_f32_16x16x128_f8f6f4 v[54:57], v[206:213], v[182:189], v[54:57], v171, v171 op_sel_hi:[0,0,0]
	v_mfma_scale_f32_16x16x128_f8f6f4 v[50:53], v[214:221], v[182:189], v[50:53], v171, v171 op_sel_hi:[0,0,0]
	v_mfma_scale_f32_16x16x128_f8f6f4 v[38:41], v[206:213], v[190:197], v[38:41], v171, v171 op_sel_hi:[0,0,0]
	v_mfma_scale_f32_16x16x128_f8f6f4 v[34:37], v[214:221], v[190:197], v[34:37], v171, v171 op_sel_hi:[0,0,0]
	v_mfma_scale_f32_16x16x128_f8f6f4 v[22:25], v[206:213], v[198:205], v[22:25], v171, v171 op_sel_hi:[0,0,0]
	v_mfma_scale_f32_16x16x128_f8f6f4 v[18:21], v[214:221], v[198:205], v[18:21], v171, v171 op_sel_hi:[0,0,0]
	s_add_i32 s54, 0, 0x18000
	v_add_u32_e32 v14, s54, v168
	s_barrier
	ds_read_b128 v[2:5], v14
	ds_read_b128 v[6:9], v14 offset:1024
	ds_read_b128 v[10:13], v14 offset:2048
	ds_read_b128 v[14:17], v14 offset:3072
	s_add_u32 s0, s36, 0x4000
	s_addc_u32 s1, s37, 0
	s_mov_b32 m0, s38
	v_lshl_add_u64 v[206:207], s[0:1], 0, v[152:153]
	ds_read_b128 v[174:177], v170 offset:32768
	ds_read_b128 v[178:181], v170 offset:33792
	ds_read_b128 v[182:185], v170 offset:34816
	ds_read_b128 v[186:189], v170 offset:35840
	ds_read_b128 v[190:193], v170 offset:36864
	ds_read_b128 v[194:197], v170 offset:37888
	ds_read_b128 v[198:201], v170 offset:38912
	ds_read_b128 v[202:205], v170 offset:39936
	global_load_lds_dwordx4 v[206:207], off
	v_lshl_add_u64 v[206:207], s[0:1], 0, v[148:149]
	s_mov_b32 m0, s39
	s_nop 0
	global_load_lds_dwordx4 v[206:207], off
	s_waitcnt lgkmcnt(8)
	s_waitcnt vmcnt(10)
	s_barrier
	s_waitcnt lgkmcnt(0)
	v_mfma_scale_f32_16x16x128_f8f6f4 v[142:145], v[2:9], v[174:181], v[142:145], v171, v171 op_sel_hi:[0,0,0]
	v_mfma_scale_f32_16x16x128_f8f6f4 v[138:141], v[10:17], v[174:181], v[138:141], v171, v171 op_sel_hi:[0,0,0]
	v_mfma_scale_f32_16x16x128_f8f6f4 v[126:129], v[2:9], v[182:189], v[126:129], v171, v171 op_sel_hi:[0,0,0]
	v_mfma_scale_f32_16x16x128_f8f6f4 v[122:125], v[10:17], v[182:189], v[122:125], v171, v171 op_sel_hi:[0,0,0]
	v_mfma_scale_f32_16x16x128_f8f6f4 v[110:113], v[2:9], v[190:197], v[110:113], v171, v171 op_sel_hi:[0,0,0]
	v_mfma_scale_f32_16x16x128_f8f6f4 v[106:109], v[10:17], v[190:197], v[106:109], v171, v171 op_sel_hi:[0,0,0]
	v_mfma_scale_f32_16x16x128_f8f6f4 v[94:97], v[2:9], v[198:205], v[94:97], v171, v171 op_sel_hi:[0,0,0]
	v_mfma_scale_f32_16x16x128_f8f6f4 v[90:93], v[10:17], v[198:205], v[90:93], v171, v171 op_sel_hi:[0,0,0]
	s_barrier
	s_add_i32 s36, 0, 0x1c000
	s_add_i32 s0, s54, s11
	v_add_u32_e32 v218, s36, v168
	v_lshl_add_u64 v[162:163], v[162:163], 0, s[14:15]
	s_mov_b32 m0, s0
	ds_read_b128 v[206:209], v218
	ds_read_b128 v[210:213], v218 offset:1024
	ds_read_b128 v[214:217], v218 offset:2048
	ds_read_b128 v[218:221], v218 offset:3072
	global_load_lds_dwordx4 v[162:163], off
	v_lshl_add_u64 v[162:163], v[164:165], 0, s[14:15]
	s_add_i32 m0, s0, 0x2000
	s_nop 0
	global_load_lds_dwordx4 v[162:163], off
	s_waitcnt vmcnt(10)
	s_barrier
	s_waitcnt lgkmcnt(0)
	v_mfma_scale_f32_16x16x128_f8f6f4 v[134:137], v[206:213], v[174:181], v[134:137], v171, v171 op_sel_hi:[0,0,0]
	v_mfma_scale_f32_16x16x128_f8f6f4 v[130:133], v[214:221], v[174:181], v[130:133], v171, v171 op_sel_hi:[0,0,0]
	v_mfma_scale_f32_16x16x128_f8f6f4 v[118:121], v[206:213], v[182:189], v[118:121], v171, v171 op_sel_hi:[0,0,0]
	v_mfma_scale_f32_16x16x128_f8f6f4 v[114:117], v[214:221], v[182:189], v[114:117], v171, v171 op_sel_hi:[0,0,0]
	v_mfma_scale_f32_16x16x128_f8f6f4 v[102:105], v[206:213], v[190:197], v[102:105], v171, v171 op_sel_hi:[0,0,0]
	v_mfma_scale_f32_16x16x128_f8f6f4 v[98:101], v[214:221], v[190:197], v[98:101], v171, v171 op_sel_hi:[0,0,0]
	v_mfma_scale_f32_16x16x128_f8f6f4 v[86:89], v[206:213], v[198:205], v[86:89], v171, v171 op_sel_hi:[0,0,0]
	v_mfma_scale_f32_16x16x128_f8f6f4 v[82:85], v[214:221], v[198:205], v[82:85], v171, v171 op_sel_hi:[0,0,0]
	s_mov_b32 m0, s43
	v_lshl_add_u64 v[162:163], s[34:35], 0, v[152:153]
	s_barrier
	ds_read_b128 v[174:177], v170 offset:49152
	ds_read_b128 v[178:181], v170 offset:50176
	ds_read_b128 v[182:185], v170 offset:51200
	ds_read_b128 v[186:189], v170 offset:52224
	ds_read_b128 v[190:193], v170 offset:53248
	ds_read_b128 v[194:197], v170 offset:54272
	ds_read_b128 v[198:201], v170 offset:55296
	ds_read_b128 v[202:205], v170 offset:56320
	global_load_lds_dwordx4 v[162:163], off
	v_lshl_add_u64 v[162:163], s[34:35], 0, v[148:149]
	s_mov_b32 m0, s44
	s_nop 0
	global_load_lds_dwordx4 v[162:163], off
	s_waitcnt vmcnt(10)
	s_barrier
	s_waitcnt lgkmcnt(0)
	v_mfma_scale_f32_16x16x128_f8f6f4 v[78:81], v[2:9], v[174:181], v[78:81], v171, v171 op_sel_hi:[0,0,0]
	v_mfma_scale_f32_16x16x128_f8f6f4 v[74:77], v[10:17], v[174:181], v[74:77], v171, v171 op_sel_hi:[0,0,0]
	v_mfma_scale_f32_16x16x128_f8f6f4 v[62:65], v[2:9], v[182:189], v[62:65], v171, v171 op_sel_hi:[0,0,0]
	v_mfma_scale_f32_16x16x128_f8f6f4 v[58:61], v[10:17], v[182:189], v[58:61], v171, v171 op_sel_hi:[0,0,0]
	v_mfma_scale_f32_16x16x128_f8f6f4 v[46:49], v[2:9], v[190:197], v[46:49], v171, v171 op_sel_hi:[0,0,0]
	v_mfma_scale_f32_16x16x128_f8f6f4 v[42:45], v[10:17], v[190:197], v[42:45], v171, v171 op_sel_hi:[0,0,0]
	v_mfma_scale_f32_16x16x128_f8f6f4 v[30:33], v[2:9], v[198:205], v[30:33], v171, v171 op_sel_hi:[0,0,0]
	v_mfma_scale_f32_16x16x128_f8f6f4 v[26:29], v[10:17], v[198:205], v[26:29], v171, v171 op_sel_hi:[0,0,0]
	s_barrier
	s_add_u32 s0, s30, 0x20080
	s_addc_u32 s1, s31, 0
	s_add_i32 s30, s36, s11
	v_lshl_add_u64 v[2:3], s[0:1], 0, v[150:151]
	s_mov_b32 m0, s30
	s_nop 0
	global_load_lds_dwordx4 v[2:3], off
	v_lshl_add_u64 v[2:3], s[0:1], 0, v[146:147]
	s_add_i32 m0, s30, 0x2000
	s_nop 0
	global_load_lds_dwordx4 v[2:3], off
	s_waitcnt vmcnt(10)
	s_barrier
	v_mfma_scale_f32_16x16x128_f8f6f4 v[70:73], v[206:213], v[174:181], v[70:73], v171, v171 op_sel_hi:[0,0,0]
	v_mfma_scale_f32_16x16x128_f8f6f4 v[66:69], v[214:221], v[174:181], v[66:69], v171, v171 op_sel_hi:[0,0,0]
	v_mfma_scale_f32_16x16x128_f8f6f4 v[54:57], v[206:213], v[182:189], v[54:57], v171, v171 op_sel_hi:[0,0,0]
	v_mfma_scale_f32_16x16x128_f8f6f4 v[50:53], v[214:221], v[182:189], v[50:53], v171, v171 op_sel_hi:[0,0,0]
	v_mfma_scale_f32_16x16x128_f8f6f4 v[38:41], v[206:213], v[190:197], v[38:41], v171, v171 op_sel_hi:[0,0,0]
	v_mfma_scale_f32_16x16x128_f8f6f4 v[34:37], v[214:221], v[190:197], v[34:37], v171, v171 op_sel_hi:[0,0,0]
	v_mfma_scale_f32_16x16x128_f8f6f4 v[22:25], v[206:213], v[198:205], v[22:25], v171, v171 op_sel_hi:[0,0,0]
	v_mfma_scale_f32_16x16x128_f8f6f4 v[18:21], v[214:221], v[198:205], v[18:21], v171, v171 op_sel_hi:[0,0,0]
	s_add_i32 s53, s53, 2
	s_add_u32 s51, s51, 0x100
	s_addc_u32 s52, s52, 0
	s_add_u32 s28, s28, 0x10000
	s_addc_u32 s29, s29, 0
	s_cmp_gt_u32 s53, 5
	s_barrier
	s_cbranch_scc0 .LBB0_1369
	v_pk_mul_f32 v[10:11], v[142:143], s[16:17] op_sel_hi:[1,0]
	v_pk_mul_f32 v[8:9], v[144:145], s[16:17] op_sel_hi:[1,0]
	v_med3_f32 v5, v10, s47, v173
	v_med3_f32 v11, v11, s47, v173
	v_mov_b32_e32 v10, 0
	v_cvt_pk_fp8_f32 v10, v5, v11
	v_mov_b32_e32 v3, v166
	v_mov_b32_e32 v2, v167
	s_lshl_b32 s0, s48, 8
	v_pk_mul_f32 v[14:15], v[138:139], s[16:17] op_sel_hi:[1,0]
	v_med3_f32 v5, v8, s47, v173
	v_med3_f32 v8, v9, s47, v173
	s_nop 15
	s_nop 15
	s_or_b32 s0, s0, s42
	v_cvt_pk_fp8_f32 v10, v5, v8 op_sel:[0,0,1]
	v_med3_f32 v5, v14, s47, v173
	v_med3_f32 v8, v15, s47, v173
	v_mov_b32_e32 v11, 0
	v_lshl_add_u32 v2, v2, 3, s0
	s_lshl_b32 s0, s26, 8
	v_cvt_pk_fp8_f32 v11, v5, v8
	s_add_i32 s0, s0, s41
	v_add_u32_e32 v4, s0, v3
	v_pk_mul_f32 v[12:13], v[140:141], s[16:17] op_sel_hi:[1,0]
	v_mov_b32_e32 v6, v4
	v_med3_f32 v5, v12, s47, v173
	v_med3_f32 v8, v13, s47, v173
	v_cvt_pk_fp8_f32 v11, v5, v8 op_sel:[0,0,1]
	v_ashrrev_i32_e32 v7, 31, v6
	v_lshlrev_b64 v[6:7], 10, v[6:7]
	v_ashrrev_i32_e32 v3, 31, v2
	v_lshl_add_u64 v[6:7], s[12:13], 0, v[6:7]
	v_lshl_add_u64 v[6:7], v[6:7], 0, v[2:3]
	global_store_dwordx2 v[6:7], v[10:11], off
	v_pk_mul_f32 v[10:11], v[134:135], s[16:17] op_sel_hi:[1,0]
	v_pk_mul_f32 v[8:9], v[136:137], s[16:17] op_sel_hi:[1,0]
	v_med3_f32 v5, v10, s47, v173
	v_med3_f32 v11, v11, s47, v173
	v_mov_b32_e32 v10, 0
	v_cvt_pk_fp8_f32 v10, v5, v11
	v_pk_mul_f32 v[14:15], v[130:131], s[16:17] op_sel_hi:[1,0]
	v_med3_f32 v5, v8, s47, v173
	v_med3_f32 v8, v9, s47, v173
	v_cvt_pk_fp8_f32 v10, v5, v8 op_sel:[0,0,1]
	v_med3_f32 v5, v14, s47, v173
	v_med3_f32 v8, v15, s47, v173
	v_mov_b32_e32 v11, 0
	v_cvt_pk_fp8_f32 v11, v5, v8
	v_pk_mul_f32 v[12:13], v[132:133], s[16:17] op_sel_hi:[1,0]
	v_pk_mul_f32 v[14:15], v[122:123], s[16:17] op_sel_hi:[1,0]
	v_med3_f32 v5, v12, s47, v173
	v_med3_f32 v8, v13, s47, v173
	v_cvt_pk_fp8_f32 v11, v5, v8 op_sel:[0,0,1]
	v_pk_mul_f32 v[8:9], v[128:129], s[16:17] op_sel_hi:[1,0]
	v_pk_mul_f32 v[12:13], v[124:125], s[16:17] op_sel_hi:[1,0]
	s_and_b64 vcc, exec, s[8:9]
	global_store_dwordx2 v[6:7], v[10:11], off offset:128
	v_pk_mul_f32 v[10:11], v[126:127], s[16:17] op_sel_hi:[1,0]
	v_add_u32_e32 v6, 16, v4
	v_med3_f32 v5, v10, s47, v173
	v_med3_f32 v11, v11, s47, v173
	v_mov_b32_e32 v10, 0
	v_cvt_pk_fp8_f32 v10, v5, v11
	v_med3_f32 v5, v8, s47, v173
	v_med3_f32 v8, v9, s47, v173
	v_mov_b32_e32 v11, 0
	v_cvt_pk_fp8_f32 v10, v5, v8 op_sel:[0,0,1]
	v_med3_f32 v5, v14, s47, v173
	v_med3_f32 v8, v15, s47, v173
	v_cvt_pk_fp8_f32 v11, v5, v8
	v_med3_f32 v5, v12, s47, v173
	v_med3_f32 v8, v13, s47, v173
	v_cvt_pk_fp8_f32 v11, v5, v8 op_sel:[0,0,1]
	v_ashrrev_i32_e32 v7, 31, v6
	v_lshlrev_b64 v[6:7], 10, v[6:7]
	v_lshl_add_u64 v[6:7], s[12:13], 0, v[6:7]
	v_lshl_add_u64 v[6:7], v[6:7], 0, v[2:3]
	global_store_dwordx2 v[6:7], v[10:11], off
	v_pk_mul_f32 v[10:11], v[118:119], s[16:17] op_sel_hi:[1,0]
	v_pk_mul_f32 v[8:9], v[120:121], s[16:17] op_sel_hi:[1,0]
	v_med3_f32 v5, v10, s47, v173
	v_med3_f32 v11, v11, s47, v173
	v_mov_b32_e32 v10, 0
	v_cvt_pk_fp8_f32 v10, v5, v11
	v_pk_mul_f32 v[14:15], v[114:115], s[16:17] op_sel_hi:[1,0]
	v_med3_f32 v5, v8, s47, v173
	v_med3_f32 v8, v9, s47, v173
	v_cvt_pk_fp8_f32 v10, v5, v8 op_sel:[0,0,1]
	v_med3_f32 v5, v14, s47, v173
	v_med3_f32 v8, v15, s47, v173
	v_mov_b32_e32 v11, 0
	v_cvt_pk_fp8_f32 v11, v5, v8
	v_pk_mul_f32 v[12:13], v[116:117], s[16:17] op_sel_hi:[1,0]
	v_pk_mul_f32 v[14:15], v[106:107], s[16:17] op_sel_hi:[1,0]
	v_med3_f32 v5, v12, s47, v173
	v_med3_f32 v8, v13, s47, v173
	v_cvt_pk_fp8_f32 v11, v5, v8 op_sel:[0,0,1]
	v_pk_mul_f32 v[8:9], v[112:113], s[16:17] op_sel_hi:[1,0]
	v_pk_mul_f32 v[12:13], v[108:109], s[16:17] op_sel_hi:[1,0]
	s_mov_b32 s48, s18
	global_store_dwordx2 v[6:7], v[10:11], off offset:128
	v_pk_mul_f32 v[10:11], v[110:111], s[16:17] op_sel_hi:[1,0]
	v_add_u32_e32 v6, 32, v4
	v_med3_f32 v5, v10, s47, v173
	v_med3_f32 v11, v11, s47, v173
	v_mov_b32_e32 v10, 0
	v_cvt_pk_fp8_f32 v10, v5, v11
	v_med3_f32 v5, v8, s47, v173
	v_med3_f32 v8, v9, s47, v173
	v_mov_b32_e32 v11, 0
	v_cvt_pk_fp8_f32 v10, v5, v8 op_sel:[0,0,1]
	v_med3_f32 v5, v14, s47, v173
	v_med3_f32 v8, v15, s47, v173
	v_cvt_pk_fp8_f32 v11, v5, v8
	v_med3_f32 v5, v12, s47, v173
	v_med3_f32 v8, v13, s47, v173
	v_cvt_pk_fp8_f32 v11, v5, v8 op_sel:[0,0,1]
	v_ashrrev_i32_e32 v7, 31, v6
	v_lshlrev_b64 v[6:7], 10, v[6:7]
	v_lshl_add_u64 v[6:7], s[12:13], 0, v[6:7]
	v_lshl_add_u64 v[6:7], v[6:7], 0, v[2:3]
	global_store_dwordx2 v[6:7], v[10:11], off
	v_pk_mul_f32 v[10:11], v[102:103], s[16:17] op_sel_hi:[1,0]
	v_pk_mul_f32 v[8:9], v[104:105], s[16:17] op_sel_hi:[1,0]
	v_med3_f32 v5, v10, s47, v173
	v_med3_f32 v11, v11, s47, v173
	v_mov_b32_e32 v10, 0
	v_cvt_pk_fp8_f32 v10, v5, v11
	v_pk_mul_f32 v[14:15], v[98:99], s[16:17] op_sel_hi:[1,0]
	v_med3_f32 v5, v8, s47, v173
	v_med3_f32 v8, v9, s47, v173
	v_cvt_pk_fp8_f32 v10, v5, v8 op_sel:[0,0,1]
	v_med3_f32 v5, v14, s47, v173
	v_med3_f32 v8, v15, s47, v173
	v_mov_b32_e32 v11, 0
	v_cvt_pk_fp8_f32 v11, v5, v8
	v_pk_mul_f32 v[12:13], v[100:101], s[16:17] op_sel_hi:[1,0]
	v_pk_mul_f32 v[14:15], v[90:91], s[16:17] op_sel_hi:[1,0]
	v_med3_f32 v5, v12, s47, v173
	v_med3_f32 v8, v13, s47, v173
	v_cvt_pk_fp8_f32 v11, v5, v8 op_sel:[0,0,1]
	v_pk_mul_f32 v[8:9], v[96:97], s[16:17] op_sel_hi:[1,0]
	v_pk_mul_f32 v[12:13], v[92:93], s[16:17] op_sel_hi:[1,0]
	s_mov_b32 s26, s20
	global_store_dwordx2 v[6:7], v[10:11], off offset:128
	v_pk_mul_f32 v[10:11], v[94:95], s[16:17] op_sel_hi:[1,0]
	v_add_u32_e32 v6, 48, v4
	v_med3_f32 v5, v10, s47, v173
	v_med3_f32 v11, v11, s47, v173
	v_mov_b32_e32 v10, 0
	v_cvt_pk_fp8_f32 v10, v5, v11
	v_med3_f32 v5, v8, s47, v173
	v_med3_f32 v8, v9, s47, v173
	v_mov_b32_e32 v11, 0
	v_cvt_pk_fp8_f32 v10, v5, v8 op_sel:[0,0,1]
	v_med3_f32 v5, v14, s47, v173
	v_med3_f32 v8, v15, s47, v173
	v_cvt_pk_fp8_f32 v11, v5, v8
	v_med3_f32 v5, v12, s47, v173
	v_med3_f32 v8, v13, s47, v173
	v_cvt_pk_fp8_f32 v11, v5, v8 op_sel:[0,0,1]
	v_ashrrev_i32_e32 v7, 31, v6
	v_lshlrev_b64 v[6:7], 10, v[6:7]
	v_lshl_add_u64 v[6:7], s[12:13], 0, v[6:7]
	v_lshl_add_u64 v[6:7], v[6:7], 0, v[2:3]
	global_store_dwordx2 v[6:7], v[10:11], off
	v_pk_mul_f32 v[10:11], v[86:87], s[16:17] op_sel_hi:[1,0]
	v_pk_mul_f32 v[8:9], v[88:89], s[16:17] op_sel_hi:[1,0]
	v_med3_f32 v5, v10, s47, v173
	v_med3_f32 v11, v11, s47, v173
	v_mov_b32_e32 v10, 0
	v_cvt_pk_fp8_f32 v10, v5, v11
	v_pk_mul_f32 v[14:15], v[82:83], s[16:17] op_sel_hi:[1,0]
	v_med3_f32 v5, v8, s47, v173
	v_med3_f32 v8, v9, s47, v173
	v_cvt_pk_fp8_f32 v10, v5, v8 op_sel:[0,0,1]
	v_med3_f32 v5, v14, s47, v173
	v_med3_f32 v8, v15, s47, v173
	v_mov_b32_e32 v11, 0
	v_cvt_pk_fp8_f32 v11, v5, v8
	v_pk_mul_f32 v[12:13], v[84:85], s[16:17] op_sel_hi:[1,0]
	v_pk_mul_f32 v[14:15], v[74:75], s[16:17] op_sel_hi:[1,0]
	v_med3_f32 v5, v12, s47, v173
	v_med3_f32 v8, v13, s47, v173
	v_cvt_pk_fp8_f32 v11, v5, v8 op_sel:[0,0,1]
	v_pk_mul_f32 v[8:9], v[80:81], s[16:17] op_sel_hi:[1,0]
	v_pk_mul_f32 v[12:13], v[76:77], s[16:17] op_sel_hi:[1,0]
	s_mov_b64 s[28:29], s[24:25]
	global_store_dwordx2 v[6:7], v[10:11], off offset:128
	v_pk_mul_f32 v[10:11], v[78:79], s[16:17] op_sel_hi:[1,0]
	v_add_u32_e32 v6, 0x80, v4
	v_med3_f32 v5, v10, s47, v173
	v_med3_f32 v11, v11, s47, v173
	v_mov_b32_e32 v10, 0
	v_cvt_pk_fp8_f32 v10, v5, v11
	v_med3_f32 v5, v8, s47, v173
	v_med3_f32 v8, v9, s47, v173
	v_mov_b32_e32 v11, 0
	v_cvt_pk_fp8_f32 v10, v5, v8 op_sel:[0,0,1]
	v_med3_f32 v5, v14, s47, v173
	v_med3_f32 v8, v15, s47, v173
	v_cvt_pk_fp8_f32 v11, v5, v8
	v_med3_f32 v5, v12, s47, v173
	v_med3_f32 v8, v13, s47, v173
	v_cvt_pk_fp8_f32 v11, v5, v8 op_sel:[0,0,1]
	v_ashrrev_i32_e32 v7, 31, v6
	v_lshlrev_b64 v[6:7], 10, v[6:7]
	v_lshl_add_u64 v[6:7], s[12:13], 0, v[6:7]
	v_lshl_add_u64 v[6:7], v[6:7], 0, v[2:3]
	global_store_dwordx2 v[6:7], v[10:11], off
	v_pk_mul_f32 v[10:11], v[70:71], s[16:17] op_sel_hi:[1,0]
	v_pk_mul_f32 v[8:9], v[72:73], s[16:17] op_sel_hi:[1,0]
	v_med3_f32 v5, v10, s47, v173
	v_med3_f32 v11, v11, s47, v173
	v_mov_b32_e32 v10, 0
	v_cvt_pk_fp8_f32 v10, v5, v11
	v_pk_mul_f32 v[14:15], v[66:67], s[16:17] op_sel_hi:[1,0]
	v_med3_f32 v5, v8, s47, v173
	v_med3_f32 v8, v9, s47, v173
	v_cvt_pk_fp8_f32 v10, v5, v8 op_sel:[0,0,1]
	v_med3_f32 v5, v14, s47, v173
	v_med3_f32 v8, v15, s47, v173
	v_mov_b32_e32 v11, 0
	v_cvt_pk_fp8_f32 v11, v5, v8
	v_pk_mul_f32 v[12:13], v[68:69], s[16:17] op_sel_hi:[1,0]
	v_pk_mul_f32 v[14:15], v[58:59], s[16:17] op_sel_hi:[1,0]
	v_med3_f32 v5, v12, s47, v173
	v_med3_f32 v8, v13, s47, v173
	v_cvt_pk_fp8_f32 v11, v5, v8 op_sel:[0,0,1]
	v_pk_mul_f32 v[8:9], v[64:65], s[16:17] op_sel_hi:[1,0]
	v_pk_mul_f32 v[12:13], v[60:61], s[16:17] op_sel_hi:[1,0]
	s_mov_b64 s[30:31], s[22:23]
	global_store_dwordx2 v[6:7], v[10:11], off offset:128
	v_pk_mul_f32 v[10:11], v[62:63], s[16:17] op_sel_hi:[1,0]
	v_add_u32_e32 v6, 0x90, v4
	v_med3_f32 v5, v10, s47, v173
	v_med3_f32 v11, v11, s47, v173
	v_mov_b32_e32 v10, 0
	v_cvt_pk_fp8_f32 v10, v5, v11
	v_med3_f32 v5, v8, s47, v173
	v_med3_f32 v8, v9, s47, v173
	v_mov_b32_e32 v11, 0
	v_cvt_pk_fp8_f32 v10, v5, v8 op_sel:[0,0,1]
	v_med3_f32 v5, v14, s47, v173
	v_med3_f32 v8, v15, s47, v173
	v_cvt_pk_fp8_f32 v11, v5, v8
	v_med3_f32 v5, v12, s47, v173
	v_med3_f32 v8, v13, s47, v173
	v_cvt_pk_fp8_f32 v11, v5, v8 op_sel:[0,0,1]
	v_ashrrev_i32_e32 v7, 31, v6
	v_lshlrev_b64 v[6:7], 10, v[6:7]
	v_lshl_add_u64 v[6:7], s[12:13], 0, v[6:7]
	v_lshl_add_u64 v[6:7], v[6:7], 0, v[2:3]
	global_store_dwordx2 v[6:7], v[10:11], off
	v_pk_mul_f32 v[10:11], v[54:55], s[16:17] op_sel_hi:[1,0]
	v_pk_mul_f32 v[8:9], v[56:57], s[16:17] op_sel_hi:[1,0]
	v_med3_f32 v5, v10, s47, v173
	v_med3_f32 v11, v11, s47, v173
	v_mov_b32_e32 v10, 0
	v_cvt_pk_fp8_f32 v10, v5, v11
	v_pk_mul_f32 v[14:15], v[50:51], s[16:17] op_sel_hi:[1,0]
	v_med3_f32 v5, v8, s47, v173
	v_med3_f32 v8, v9, s47, v173
	v_cvt_pk_fp8_f32 v10, v5, v8 op_sel:[0,0,1]
	v_med3_f32 v5, v14, s47, v173
	v_med3_f32 v8, v15, s47, v173
	v_mov_b32_e32 v11, 0
	v_cvt_pk_fp8_f32 v11, v5, v8
	v_pk_mul_f32 v[12:13], v[52:53], s[16:17] op_sel_hi:[1,0]
	v_pk_mul_f32 v[14:15], v[42:43], s[16:17] op_sel_hi:[1,0]
	v_med3_f32 v5, v12, s47, v173
	v_med3_f32 v8, v13, s47, v173
	v_cvt_pk_fp8_f32 v11, v5, v8 op_sel:[0,0,1]
	v_pk_mul_f32 v[8:9], v[48:49], s[16:17] op_sel_hi:[1,0]
	v_pk_mul_f32 v[12:13], v[44:45], s[16:17] op_sel_hi:[1,0]
	global_store_dwordx2 v[6:7], v[10:11], off offset:128
	v_pk_mul_f32 v[10:11], v[46:47], s[16:17] op_sel_hi:[1,0]
	v_add_u32_e32 v6, 0xa0, v4
	v_med3_f32 v5, v10, s47, v173
	v_med3_f32 v11, v11, s47, v173
	v_mov_b32_e32 v10, 0
	v_cvt_pk_fp8_f32 v10, v5, v11
	v_med3_f32 v5, v8, s47, v173
	v_med3_f32 v8, v9, s47, v173
	v_mov_b32_e32 v11, 0
	v_cvt_pk_fp8_f32 v10, v5, v8 op_sel:[0,0,1]
	v_med3_f32 v5, v14, s47, v173
	v_med3_f32 v8, v15, s47, v173
	v_cvt_pk_fp8_f32 v11, v5, v8
	v_med3_f32 v5, v12, s47, v173
	v_med3_f32 v8, v13, s47, v173
	v_cvt_pk_fp8_f32 v11, v5, v8 op_sel:[0,0,1]
	v_ashrrev_i32_e32 v7, 31, v6
	v_lshlrev_b64 v[6:7], 10, v[6:7]
	v_lshl_add_u64 v[6:7], s[12:13], 0, v[6:7]
	v_lshl_add_u64 v[6:7], v[6:7], 0, v[2:3]
	global_store_dwordx2 v[6:7], v[10:11], off
	v_pk_mul_f32 v[10:11], v[38:39], s[16:17] op_sel_hi:[1,0]
	v_pk_mul_f32 v[8:9], v[40:41], s[16:17] op_sel_hi:[1,0]
	v_med3_f32 v5, v10, s47, v173
	v_med3_f32 v11, v11, s47, v173
	v_mov_b32_e32 v10, 0
	v_cvt_pk_fp8_f32 v10, v5, v11
	v_pk_mul_f32 v[14:15], v[34:35], s[16:17] op_sel_hi:[1,0]
	v_med3_f32 v5, v8, s47, v173
	v_med3_f32 v8, v9, s47, v173
	v_cvt_pk_fp8_f32 v10, v5, v8 op_sel:[0,0,1]
	v_med3_f32 v5, v14, s47, v173
	v_med3_f32 v8, v15, s47, v173
	v_mov_b32_e32 v11, 0
	v_cvt_pk_fp8_f32 v11, v5, v8
	v_pk_mul_f32 v[12:13], v[36:37], s[16:17] op_sel_hi:[1,0]
	v_add_u32_e32 v4, 0xb0, v4
	v_med3_f32 v5, v12, s47, v173
	v_med3_f32 v8, v13, s47, v173
	v_cvt_pk_fp8_f32 v11, v5, v8 op_sel:[0,0,1]
	v_pk_mul_f32 v[8:9], v[28:29], s[16:17] op_sel_hi:[1,0]
	global_store_dwordx2 v[6:7], v[10:11], off offset:128
	v_pk_mul_f32 v[6:7], v[30:31], s[16:17] op_sel_hi:[1,0]
	v_pk_mul_f32 v[10:11], v[26:27], s[16:17] op_sel_hi:[1,0]
	v_ashrrev_i32_e32 v5, 31, v4
	v_med3_f32 v12, v6, s47, v173
	v_med3_f32 v7, v7, s47, v173
	v_mov_b32_e32 v6, 0
	v_lshlrev_b64 v[4:5], 10, v[4:5]
	v_cvt_pk_fp8_f32 v6, v12, v7
	v_lshl_add_u64 v[4:5], s[12:13], 0, v[4:5]
	v_lshl_add_u64 v[2:3], v[4:5], 0, v[2:3]
	v_pk_mul_f32 v[4:5], v[32:33], s[16:17] op_sel_hi:[1,0]
	v_mov_b32_e32 v7, 0
	v_med3_f32 v4, v4, s47, v173
	v_med3_f32 v5, v5, s47, v173
	v_cvt_pk_fp8_f32 v6, v4, v5 op_sel:[0,0,1]
	v_med3_f32 v4, v10, s47, v173
	v_med3_f32 v5, v11, s47, v173
	v_cvt_pk_fp8_f32 v7, v4, v5
	v_med3_f32 v4, v8, s47, v173
	v_med3_f32 v5, v9, s47, v173
	v_pk_mul_f32 v[10:11], v[18:19], s[16:17] op_sel_hi:[1,0]
	v_cvt_pk_fp8_f32 v7, v4, v5 op_sel:[0,0,1]
	v_pk_mul_f32 v[4:5], v[24:25], s[16:17] op_sel_hi:[1,0]
	v_pk_mul_f32 v[8:9], v[20:21], s[16:17] op_sel_hi:[1,0]
	v_med3_f32 v4, v4, s47, v173
	global_store_dwordx2 v[2:3], v[6:7], off
	v_pk_mul_f32 v[6:7], v[22:23], s[16:17] op_sel_hi:[1,0]
	v_med3_f32 v5, v5, s47, v173
	v_med3_f32 v12, v6, s47, v173
	v_med3_f32 v7, v7, s47, v173
	v_mov_b32_e32 v6, 0
	v_cvt_pk_fp8_f32 v6, v12, v7
	v_mov_b32_e32 v7, 0
	v_cvt_pk_fp8_f32 v6, v4, v5 op_sel:[0,0,1]
	v_med3_f32 v4, v10, s47, v173
	v_med3_f32 v5, v11, s47, v173
	v_cvt_pk_fp8_f32 v7, v4, v5
	v_med3_f32 v4, v8, s47, v173
	v_med3_f32 v5, v9, s47, v173
	v_cvt_pk_fp8_f32 v7, v4, v5 op_sel:[0,0,1]
	global_store_dwordx2 v[2:3], v[6:7], off offset:128
	s_cbranch_vccz .LBB0_1362
	s_waitcnt vmcnt(0)
	s_cmpk_gt_u32 s4, 0xff
	s_cbranch_scc1 .LBB0_1373
	s_barrier

.LBB0_1513:
	ds_read_b128 v[152:155], v149
	ds_read_b128 v[156:159], v149 offset:1024
	ds_read_b128 v[160:163], v149 offset:2048
	ds_read_b128 v[164:167], v149 offset:3072
	s_add_u32 s0, s26, 0xfffc0080
	s_addc_u32 s1, s27, -1
	s_cmp_eq_u32 s49, 12
	s_cselect_b32 s31, s21, s1
	s_cselect_b32 s30, s45, s0
	s_cselect_b32 s29, s19, s48
	s_cselect_b32 s28, s46, s47
	v_lshl_add_u64 v[200:201], s[26:27], 0, v[140:141]
	s_add_i32 m0, s10, 0xc000
	ds_read_b128 v[168:171], v150
	ds_read_b128 v[172:175], v150 offset:1024
	ds_read_b128 v[176:179], v150 offset:2048
	ds_read_b128 v[180:183], v150 offset:3072
	ds_read_b128 v[184:187], v150 offset:4096
	ds_read_b128 v[188:191], v150 offset:5120
	ds_read_b128 v[192:195], v150 offset:6144
	ds_read_b128 v[196:199], v150 offset:7168
	global_load_lds_dwordx4 v[200:201], off
	v_lshl_add_u64 v[200:201], s[26:27], 0, v[138:139]
	s_add_i32 m0, s10, 0xe000
	s_nop 0
	global_load_lds_dwordx4 v[200:201], off
	s_waitcnt lgkmcnt(8)
	s_waitcnt vmcnt(10)
	s_barrier
	s_waitcnt lgkmcnt(0)
	v_mfma_f32_16x16x32_bf16 v[126:129], v[152:155], v[168:171], v[126:129]
	v_mfma_f32_16x16x32_bf16 v[122:125], v[160:163], v[168:171], v[122:125]
	v_mfma_f32_16x16x32_bf16 v[118:121], v[152:155], v[176:179], v[118:121]
	v_mfma_f32_16x16x32_bf16 v[110:113], v[160:163], v[176:179], v[110:113]
	v_mfma_f32_16x16x32_bf16 v[102:105], v[152:155], v[184:187], v[102:105]
	v_mfma_f32_16x16x32_bf16 v[94:97], v[160:163], v[184:187], v[94:97]
	v_mfma_f32_16x16x32_bf16 v[86:89], v[152:155], v[192:195], v[86:89]
	v_mfma_f32_16x16x32_bf16 v[78:81], v[160:163], v[192:195], v[78:81]
	v_mfma_f32_16x16x32_bf16 v[126:129], v[156:159], v[172:175], v[126:129]
	v_mfma_f32_16x16x32_bf16 v[122:125], v[164:167], v[172:175], v[122:125]
	v_mfma_f32_16x16x32_bf16 v[118:121], v[156:159], v[180:183], v[118:121]
	v_mfma_f32_16x16x32_bf16 v[110:113], v[164:167], v[180:183], v[110:113]
	v_mfma_f32_16x16x32_bf16 v[102:105], v[156:159], v[188:191], v[102:105]
	v_mfma_f32_16x16x32_bf16 v[94:97], v[164:167], v[188:191], v[94:97]
	v_mfma_f32_16x16x32_bf16 v[86:89], v[156:159], v[196:199], v[86:89]
	v_mfma_f32_16x16x32_bf16 v[78:81], v[164:167], v[196:199], v[78:81]
	s_barrier
	s_add_i32 s0, s42, s9
	v_lshl_add_u64 v[216:217], s[28:29], 0, v[134:135]
	s_mov_b32 m0, s0
	ds_read_b128 v[200:203], v151
	ds_read_b128 v[204:207], v151 offset:1024
	ds_read_b128 v[208:211], v151 offset:2048
	ds_read_b128 v[212:215], v151 offset:3072
	global_load_lds_dwordx4 v[216:217], off
	v_lshl_add_u64 v[218:219], s[28:29], 0, v[130:131]
	s_add_i32 m0, s0, 0x2000
	s_nop 0
	global_load_lds_dwordx4 v[218:219], off
	s_waitcnt vmcnt(10)
	s_barrier
	s_waitcnt lgkmcnt(0)
	v_mfma_f32_16x16x32_bf16 v[114:117], v[200:203], v[168:171], v[114:117]
	v_mfma_f32_16x16x32_bf16 v[106:109], v[208:211], v[168:171], v[106:109]
	v_mfma_f32_16x16x32_bf16 v[98:101], v[200:203], v[176:179], v[98:101]
	v_mfma_f32_16x16x32_bf16 v[90:93], v[208:211], v[176:179], v[90:93]
	v_mfma_f32_16x16x32_bf16 v[82:85], v[200:203], v[184:187], v[82:85]
	v_mfma_f32_16x16x32_bf16 v[74:77], v[208:211], v[184:187], v[74:77]
	v_mfma_f32_16x16x32_bf16 v[70:73], v[200:203], v[192:195], v[70:73]
	v_mfma_f32_16x16x32_bf16 v[66:69], v[208:211], v[192:195], v[66:69]
	v_mfma_f32_16x16x32_bf16 v[114:117], v[204:207], v[172:175], v[114:117]
	v_mfma_f32_16x16x32_bf16 v[106:109], v[212:215], v[172:175], v[106:109]
	v_mfma_f32_16x16x32_bf16 v[98:101], v[204:207], v[180:183], v[98:101]
	v_mfma_f32_16x16x32_bf16 v[90:93], v[212:215], v[180:183], v[90:93]
	v_mfma_f32_16x16x32_bf16 v[82:85], v[204:207], v[188:191], v[82:85]
	v_mfma_f32_16x16x32_bf16 v[74:77], v[212:215], v[188:191], v[74:77]
	v_mfma_f32_16x16x32_bf16 v[70:73], v[204:207], v[196:199], v[70:73]
	v_mfma_f32_16x16x32_bf16 v[66:69], v[212:215], v[196:199], v[66:69]
	s_mov_b32 m0, s10
	v_lshl_add_u64 v[220:221], s[30:31], 0, v[136:137]
	s_barrier
	ds_read_b128 v[168:171], v150 offset:16384
	ds_read_b128 v[172:175], v150 offset:17408
	ds_read_b128 v[176:179], v150 offset:18432
	ds_read_b128 v[180:183], v150 offset:19456
	ds_read_b128 v[184:187], v150 offset:20480
	ds_read_b128 v[188:191], v150 offset:21504
	ds_read_b128 v[192:195], v150 offset:22528
	ds_read_b128 v[196:199], v150 offset:23552
	global_load_lds_dwordx4 v[220:221], off
	v_lshl_add_u64 v[222:223], s[30:31], 0, v[132:133]
	s_mov_b32 m0, s11
	s_nop 0
	global_load_lds_dwordx4 v[222:223], off
	s_waitcnt vmcnt(10)
	s_barrier
	s_waitcnt lgkmcnt(0)
	v_mfma_f32_16x16x32_bf16 v[62:65], v[152:155], v[168:171], v[62:65]
	v_mfma_f32_16x16x32_bf16 v[58:61], v[160:163], v[168:171], v[58:61]
	v_mfma_f32_16x16x32_bf16 v[54:57], v[152:155], v[176:179], v[54:57]
	v_mfma_f32_16x16x32_bf16 v[50:53], v[160:163], v[176:179], v[50:53]
	v_mfma_f32_16x16x32_bf16 v[38:41], v[152:155], v[184:187], v[38:41]
	v_mfma_f32_16x16x32_bf16 v[34:37], v[160:163], v[184:187], v[34:37]
	v_mfma_f32_16x16x32_bf16 v[22:25], v[152:155], v[192:195], v[22:25]
	v_mfma_f32_16x16x32_bf16 v[18:21], v[160:163], v[192:195], v[18:21]
	v_mfma_f32_16x16x32_bf16 v[62:65], v[156:159], v[172:175], v[62:65]
	v_mfma_f32_16x16x32_bf16 v[58:61], v[164:167], v[172:175], v[58:61]
	v_mfma_f32_16x16x32_bf16 v[54:57], v[156:159], v[180:183], v[54:57]
	v_mfma_f32_16x16x32_bf16 v[50:53], v[164:167], v[180:183], v[50:53]
	v_mfma_f32_16x16x32_bf16 v[38:41], v[156:159], v[188:191], v[38:41]
	v_mfma_f32_16x16x32_bf16 v[34:37], v[164:167], v[188:191], v[34:37]
	v_mfma_f32_16x16x32_bf16 v[22:25], v[156:159], v[196:199], v[22:25]
	v_mfma_f32_16x16x32_bf16 v[18:21], v[164:167], v[196:199], v[18:21]
	s_barrier
	s_add_u32 s0, s28, 0x40000
	s_addc_u32 s1, s29, 0
	s_add_i32 s50, s43, s9
	v_lshl_add_u64 v[152:153], s[0:1], 0, v[134:135]
	s_mov_b32 m0, s50
	s_nop 0
	global_load_lds_dwordx4 v[152:153], off
	v_lshl_add_u64 v[152:153], s[0:1], 0, v[130:131]
	s_add_i32 m0, s50, 0x2000
	s_nop 0
	global_load_lds_dwordx4 v[152:153], off
	s_waitcnt vmcnt(10)
	s_barrier
	v_mfma_f32_16x16x32_bf16 v[46:49], v[200:203], v[168:171], v[46:49]
	v_mfma_f32_16x16x32_bf16 v[42:45], v[208:211], v[168:171], v[42:45]
	v_mfma_f32_16x16x32_bf16 v[30:33], v[200:203], v[176:179], v[30:33]
	v_mfma_f32_16x16x32_bf16 v[26:29], v[208:211], v[176:179], v[26:29]
	v_mfma_f32_16x16x32_bf16 v[14:17], v[200:203], v[184:187], v[14:17]
	v_mfma_f32_16x16x32_bf16 v[10:13], v[208:211], v[184:187], v[10:13]
	v_mfma_f32_16x16x32_bf16 v[6:9], v[200:203], v[192:195], v[6:9]
	v_mfma_f32_16x16x32_bf16 v[2:5], v[208:211], v[192:195], v[2:5]
	v_mfma_f32_16x16x32_bf16 v[46:49], v[204:207], v[172:175], v[46:49]
	v_mfma_f32_16x16x32_bf16 v[42:45], v[212:215], v[172:175], v[42:45]
	v_mfma_f32_16x16x32_bf16 v[30:33], v[204:207], v[180:183], v[30:33]
	v_mfma_f32_16x16x32_bf16 v[26:29], v[212:215], v[180:183], v[26:29]
	v_mfma_f32_16x16x32_bf16 v[14:17], v[204:207], v[188:191], v[14:17]
	v_mfma_f32_16x16x32_bf16 v[10:13], v[212:215], v[188:191], v[10:13]
	v_mfma_f32_16x16x32_bf16 v[6:9], v[204:207], v[196:199], v[6:9]
	v_mfma_f32_16x16x32_bf16 v[2:5], v[212:215], v[196:199], v[2:5]
	s_add_i32 s50, 0, 0x18000
	v_add_u32_e32 v164, s50, v148
	s_barrier
	ds_read_b128 v[152:155], v164
	ds_read_b128 v[156:159], v164 offset:1024
	ds_read_b128 v[160:163], v164 offset:2048
	ds_read_b128 v[164:167], v164 offset:3072
	s_add_u32 s0, s30, 0x40000
	s_addc_u32 s1, s31, 0
	s_mov_b32 m0, s17
	v_lshl_add_u64 v[200:201], s[0:1], 0, v[136:137]
	ds_read_b128 v[168:171], v150 offset:32768
	ds_read_b128 v[172:175], v150 offset:33792
	ds_read_b128 v[176:179], v150 offset:34816
	ds_read_b128 v[180:183], v150 offset:35840
	ds_read_b128 v[184:187], v150 offset:36864
	ds_read_b128 v[188:191], v150 offset:37888
	ds_read_b128 v[192:195], v150 offset:38912
	ds_read_b128 v[196:199], v150 offset:39936
	global_load_lds_dwordx4 v[200:201], off
	v_lshl_add_u64 v[200:201], s[0:1], 0, v[132:133]
	s_mov_b32 m0, s34
	s_nop 0
	global_load_lds_dwordx4 v[200:201], off
	s_waitcnt lgkmcnt(8)
	s_waitcnt vmcnt(10)
	s_barrier
	s_waitcnt lgkmcnt(0)
	v_mfma_f32_16x16x32_bf16 v[126:129], v[152:155], v[168:171], v[126:129]
	v_mfma_f32_16x16x32_bf16 v[122:125], v[160:163], v[168:171], v[122:125]
	v_mfma_f32_16x16x32_bf16 v[118:121], v[152:155], v[176:179], v[118:121]
	v_mfma_f32_16x16x32_bf16 v[110:113], v[160:163], v[176:179], v[110:113]
	v_mfma_f32_16x16x32_bf16 v[102:105], v[152:155], v[184:187], v[102:105]
	v_mfma_f32_16x16x32_bf16 v[94:97], v[160:163], v[184:187], v[94:97]
	v_mfma_f32_16x16x32_bf16 v[86:89], v[152:155], v[192:195], v[86:89]
	v_mfma_f32_16x16x32_bf16 v[78:81], v[160:163], v[192:195], v[78:81]
	v_mfma_f32_16x16x32_bf16 v[126:129], v[156:159], v[172:175], v[126:129]
	v_mfma_f32_16x16x32_bf16 v[122:125], v[164:167], v[172:175], v[122:125]
	v_mfma_f32_16x16x32_bf16 v[118:121], v[156:159], v[180:183], v[118:121]
	v_mfma_f32_16x16x32_bf16 v[110:113], v[164:167], v[180:183], v[110:113]
	v_mfma_f32_16x16x32_bf16 v[102:105], v[156:159], v[188:191], v[102:105]
	v_mfma_f32_16x16x32_bf16 v[94:97], v[164:167], v[188:191], v[94:97]
	v_mfma_f32_16x16x32_bf16 v[86:89], v[156:159], v[196:199], v[86:89]
	v_mfma_f32_16x16x32_bf16 v[78:81], v[164:167], v[196:199], v[78:81]
	s_barrier
	s_add_i32 s30, 0, 0x1c000
	s_add_i32 s0, s50, s9
	v_add_u32_e32 v212, s30, v148
	v_lshl_add_u64 v[216:217], v[216:217], 0, s[14:15]
	s_mov_b32 m0, s0
	ds_read_b128 v[200:203], v212
	ds_read_b128 v[204:207], v212 offset:1024
	ds_read_b128 v[208:211], v212 offset:2048
	ds_read_b128 v[212:215], v212 offset:3072
	global_load_lds_dwordx4 v[216:217], off
	v_lshl_add_u64 v[216:217], v[218:219], 0, s[14:15]
	s_add_i32 m0, s0, 0x2000
	s_nop 0
	global_load_lds_dwordx4 v[216:217], off
	s_waitcnt vmcnt(10)
	s_barrier
	s_waitcnt lgkmcnt(0)
	v_mfma_f32_16x16x32_bf16 v[114:117], v[200:203], v[168:171], v[114:117]
	v_mfma_f32_16x16x32_bf16 v[106:109], v[208:211], v[168:171], v[106:109]
	v_mfma_f32_16x16x32_bf16 v[98:101], v[200:203], v[176:179], v[98:101]
	v_mfma_f32_16x16x32_bf16 v[90:93], v[208:211], v[176:179], v[90:93]
	v_mfma_f32_16x16x32_bf16 v[82:85], v[200:203], v[184:187], v[82:85]
	v_mfma_f32_16x16x32_bf16 v[74:77], v[208:211], v[184:187], v[74:77]
	v_mfma_f32_16x16x32_bf16 v[70:73], v[200:203], v[192:195], v[70:73]
	v_mfma_f32_16x16x32_bf16 v[66:69], v[208:211], v[192:195], v[66:69]
	v_mfma_f32_16x16x32_bf16 v[114:117], v[204:207], v[172:175], v[114:117]
	v_mfma_f32_16x16x32_bf16 v[106:109], v[212:215], v[172:175], v[106:109]
	v_mfma_f32_16x16x32_bf16 v[98:101], v[204:207], v[180:183], v[98:101]
	v_mfma_f32_16x16x32_bf16 v[90:93], v[212:215], v[180:183], v[90:93]
	v_mfma_f32_16x16x32_bf16 v[82:85], v[204:207], v[188:191], v[82:85]
	v_mfma_f32_16x16x32_bf16 v[74:77], v[212:215], v[188:191], v[74:77]
	v_mfma_f32_16x16x32_bf16 v[70:73], v[204:207], v[196:199], v[70:73]
	v_mfma_f32_16x16x32_bf16 v[66:69], v[212:215], v[196:199], v[66:69]
	s_mov_b32 m0, s40
	v_lshl_add_u64 v[216:217], v[220:221], 0, s[14:15]
	s_barrier
	ds_read_b128 v[168:171], v150 offset:49152
	ds_read_b128 v[172:175], v150 offset:50176
	ds_read_b128 v[176:179], v150 offset:51200
	ds_read_b128 v[180:183], v150 offset:52224
	ds_read_b128 v[184:187], v150 offset:53248
	ds_read_b128 v[188:191], v150 offset:54272
	ds_read_b128 v[192:195], v150 offset:55296
	ds_read_b128 v[196:199], v150 offset:56320
	global_load_lds_dwordx4 v[216:217], off
	v_lshl_add_u64 v[216:217], v[222:223], 0, s[14:15]
	s_mov_b32 m0, s41
	s_nop 0
	global_load_lds_dwordx4 v[216:217], off
	s_waitcnt vmcnt(10)
	s_barrier
	s_waitcnt lgkmcnt(0)
	v_mfma_f32_16x16x32_bf16 v[62:65], v[152:155], v[168:171], v[62:65]
	v_mfma_f32_16x16x32_bf16 v[58:61], v[160:163], v[168:171], v[58:61]
	v_mfma_f32_16x16x32_bf16 v[54:57], v[152:155], v[176:179], v[54:57]
	v_mfma_f32_16x16x32_bf16 v[50:53], v[160:163], v[176:179], v[50:53]
	v_mfma_f32_16x16x32_bf16 v[38:41], v[152:155], v[184:187], v[38:41]
	v_mfma_f32_16x16x32_bf16 v[34:37], v[160:163], v[184:187], v[34:37]
	v_mfma_f32_16x16x32_bf16 v[22:25], v[152:155], v[192:195], v[22:25]
	v_mfma_f32_16x16x32_bf16 v[18:21], v[160:163], v[192:195], v[18:21]
	v_mfma_f32_16x16x32_bf16 v[62:65], v[156:159], v[172:175], v[62:65]
	v_mfma_f32_16x16x32_bf16 v[58:61], v[164:167], v[172:175], v[58:61]
	v_mfma_f32_16x16x32_bf16 v[54:57], v[156:159], v[180:183], v[54:57]
	v_mfma_f32_16x16x32_bf16 v[50:53], v[164:167], v[180:183], v[50:53]
	v_mfma_f32_16x16x32_bf16 v[38:41], v[156:159], v[188:191], v[38:41]
	v_mfma_f32_16x16x32_bf16 v[34:37], v[164:167], v[188:191], v[34:37]
	v_mfma_f32_16x16x32_bf16 v[22:25], v[156:159], v[196:199], v[22:25]
	v_mfma_f32_16x16x32_bf16 v[18:21], v[164:167], v[196:199], v[18:21]
	s_barrier
	s_add_u32 s0, s28, 0x40080
	s_addc_u32 s1, s29, 0
	s_add_i32 s28, s30, s9
	v_lshl_add_u64 v[152:153], s[0:1], 0, v[134:135]
	s_mov_b32 m0, s28
	s_nop 0
	global_load_lds_dwordx4 v[152:153], off
	v_lshl_add_u64 v[152:153], s[0:1], 0, v[130:131]
	s_add_i32 m0, s28, 0x2000
	s_nop 0
	global_load_lds_dwordx4 v[152:153], off
	s_waitcnt vmcnt(10)
	s_barrier
	v_mfma_f32_16x16x32_bf16 v[46:49], v[200:203], v[168:171], v[46:49]
	v_mfma_f32_16x16x32_bf16 v[42:45], v[208:211], v[168:171], v[42:45]
	v_mfma_f32_16x16x32_bf16 v[30:33], v[200:203], v[176:179], v[30:33]
	v_mfma_f32_16x16x32_bf16 v[26:29], v[208:211], v[176:179], v[26:29]
	v_mfma_f32_16x16x32_bf16 v[14:17], v[200:203], v[184:187], v[14:17]
	v_mfma_f32_16x16x32_bf16 v[10:13], v[208:211], v[184:187], v[10:13]
	v_mfma_f32_16x16x32_bf16 v[6:9], v[200:203], v[192:195], v[6:9]
	v_mfma_f32_16x16x32_bf16 v[2:5], v[208:211], v[192:195], v[2:5]
	v_mfma_f32_16x16x32_bf16 v[46:49], v[204:207], v[172:175], v[46:49]
	v_mfma_f32_16x16x32_bf16 v[42:45], v[212:215], v[172:175], v[42:45]
	v_mfma_f32_16x16x32_bf16 v[30:33], v[204:207], v[180:183], v[30:33]
	v_mfma_f32_16x16x32_bf16 v[26:29], v[212:215], v[180:183], v[26:29]
	v_mfma_f32_16x16x32_bf16 v[14:17], v[204:207], v[188:191], v[14:17]
	v_mfma_f32_16x16x32_bf16 v[10:13], v[212:215], v[188:191], v[10:13]
	v_mfma_f32_16x16x32_bf16 v[6:9], v[204:207], v[196:199], v[6:9]
	v_mfma_f32_16x16x32_bf16 v[2:5], v[212:215], v[196:199], v[2:5]
	s_add_i32 s49, s49, 2
	s_add_u32 s47, s47, 0x100
	s_addc_u32 s48, s48, 0
	s_add_u32 s26, s26, 0x100
	s_addc_u32 s27, s27, 0
	s_cmp_gt_u32 s49, 13
	s_barrier
	s_cbranch_scc0 .LBB0_1513
	v_mov_b32_e32 v152, v146
	v_mov_b32_e32 v153, v147
	s_cmp_gt_i32 s44, 7
	s_cbranch_scc1 .LBB0_1505
	s_ashr_i32 s0, s44, 31
	s_lshr_b32 s0, s0, 30
	s_add_i32 s0, s44, s0
	s_ashr_i32 s0, s0, 2
	s_ashr_i32 s1, s0, 31
	s_lshl_b32 s19, s44, 8
	s_lshl_b64 s[26:27], s[0:1], 27
	s_add_u32 s26, s36, s26
	s_addc_u32 s27, s37, s27
	s_or_b32 s1, s19, s39
	s_lshl_b32 s0, s0, 10
	s_sub_i32 s0, s1, s0
	v_lshl_add_u32 v154, v153, 3, s0
	s_lshl_b32 s0, s16, 8
	s_add_i32 s0, s0, s38
	v_add_u32_e32 v156, s0, v152
	v_mov_b32_e32 v152, v156
	v_ashrrev_i32_e32 v155, 31, v154
	v_lshl_add_u64 v[154:155], v[154:155], 1, s[26:27]
	v_ashrrev_i32_e32 v153, 31, v152
	v_lshlrev_b64 v[152:153], 11, v[152:153]
	v_lshl_add_u64 v[152:153], v[154:155], 0, v[152:153]
	v_cvt_pk_bf16_f32 v126, v126, v127
	v_cvt_pk_bf16_f32 v127, v128, v129
	v_cvt_pk_bf16_f32 v128, v122, v123
	v_cvt_pk_bf16_f32 v129, v124, v125
	v_cvt_pk_bf16_f32 v114, v114, v115
	v_cvt_pk_bf16_f32 v115, v116, v117
	v_cvt_pk_bf16_f32 v116, v106, v107
	v_cvt_pk_bf16_f32 v117, v108, v109
	v_add_u32_e32 v106, 16, v156
	global_store_dwordx4 v[152:153], v[126:129], off
	global_store_dwordx4 v[152:153], v[114:117], off offset:256
	v_cvt_pk_bf16_f32 v108, v110, v111
	v_ashrrev_i32_e32 v107, 31, v106
	v_lshlrev_b64 v[106:107], 11, v[106:107]
	v_lshl_add_u64 v[114:115], v[154:155], 0, v[106:107]
	v_cvt_pk_bf16_f32 v106, v118, v119
	v_cvt_pk_bf16_f32 v107, v120, v121
	v_cvt_pk_bf16_f32 v109, v112, v113
	v_cvt_pk_bf16_f32 v98, v98, v99
	v_cvt_pk_bf16_f32 v99, v100, v101
	v_cvt_pk_bf16_f32 v100, v90, v91
	v_cvt_pk_bf16_f32 v101, v92, v93
	v_add_u32_e32 v90, 32, v156
	global_store_dwordx4 v[114:115], v[106:109], off
	global_store_dwordx4 v[114:115], v[98:101], off offset:256
	v_cvt_pk_bf16_f32 v92, v94, v95
	v_ashrrev_i32_e32 v91, 31, v90
	v_lshlrev_b64 v[90:91], 11, v[90:91]
	v_lshl_add_u64 v[98:99], v[154:155], 0, v[90:91]
	v_cvt_pk_bf16_f32 v90, v102, v103
	v_cvt_pk_bf16_f32 v91, v104, v105
	v_cvt_pk_bf16_f32 v93, v96, v97
	v_cvt_pk_bf16_f32 v82, v82, v83
	v_cvt_pk_bf16_f32 v83, v84, v85
	v_cvt_pk_bf16_f32 v84, v74, v75
	v_cvt_pk_bf16_f32 v85, v76, v77
	v_add_u32_e32 v74, 48, v156
	global_store_dwordx4 v[98:99], v[90:93], off
	global_store_dwordx4 v[98:99], v[82:85], off offset:256
	v_cvt_pk_bf16_f32 v76, v78, v79
	v_ashrrev_i32_e32 v75, 31, v74
	v_lshlrev_b64 v[74:75], 11, v[74:75]
	v_lshl_add_u64 v[82:83], v[154:155], 0, v[74:75]
	v_cvt_pk_bf16_f32 v74, v86, v87
	v_cvt_pk_bf16_f32 v75, v88, v89
	v_cvt_pk_bf16_f32 v77, v80, v81
	v_cvt_pk_bf16_f32 v70, v70, v71
	v_cvt_pk_bf16_f32 v71, v72, v73
	v_cvt_pk_bf16_f32 v72, v66, v67
	v_cvt_pk_bf16_f32 v73, v68, v69
	v_add_u32_e32 v66, 0x80, v156
	global_store_dwordx4 v[82:83], v[74:77], off
	global_store_dwordx4 v[82:83], v[70:73], off offset:256
	v_cvt_pk_bf16_f32 v62, v62, v63
	v_ashrrev_i32_e32 v67, 31, v66
	v_lshlrev_b64 v[66:67], 11, v[66:67]
	v_lshl_add_u64 v[66:67], v[154:155], 0, v[66:67]
	v_cvt_pk_bf16_f32 v63, v64, v65
	v_cvt_pk_bf16_f32 v64, v58, v59
	v_cvt_pk_bf16_f32 v65, v60, v61
	v_cvt_pk_bf16_f32 v46, v46, v47
	v_cvt_pk_bf16_f32 v47, v48, v49
	v_cvt_pk_bf16_f32 v48, v42, v43
	v_cvt_pk_bf16_f32 v49, v44, v45
	v_add_u32_e32 v42, 0x90, v156
	global_store_dwordx4 v[66:67], v[62:65], off
	global_store_dwordx4 v[66:67], v[46:49], off offset:256
	v_cvt_pk_bf16_f32 v44, v50, v51
	v_ashrrev_i32_e32 v43, 31, v42
	v_lshlrev_b64 v[42:43], 11, v[42:43]
	v_lshl_add_u64 v[46:47], v[154:155], 0, v[42:43]
	v_cvt_pk_bf16_f32 v42, v54, v55
	v_cvt_pk_bf16_f32 v43, v56, v57
	v_cvt_pk_bf16_f32 v45, v52, v53
	v_cvt_pk_bf16_f32 v30, v30, v31
	v_cvt_pk_bf16_f32 v31, v32, v33
	v_cvt_pk_bf16_f32 v32, v26, v27
	v_cvt_pk_bf16_f32 v33, v28, v29
	v_add_u32_e32 v26, 0xa0, v156
	global_store_dwordx4 v[46:47], v[42:45], off
	global_store_dwordx4 v[46:47], v[30:33], off offset:256
	v_cvt_pk_bf16_f32 v28, v34, v35
	v_ashrrev_i32_e32 v27, 31, v26
	v_lshlrev_b64 v[26:27], 11, v[26:27]
	v_lshl_add_u64 v[30:31], v[154:155], 0, v[26:27]
	v_cvt_pk_bf16_f32 v26, v38, v39
	v_cvt_pk_bf16_f32 v27, v40, v41
	v_cvt_pk_bf16_f32 v29, v36, v37
	v_cvt_pk_bf16_f32 v14, v14, v15
	v_cvt_pk_bf16_f32 v15, v16, v17
	v_cvt_pk_bf16_f32 v16, v10, v11
	v_cvt_pk_bf16_f32 v17, v12, v13
	v_add_u32_e32 v10, 0xb0, v156
	global_store_dwordx4 v[30:31], v[26:29], off
	global_store_dwordx4 v[30:31], v[14:17], off offset:256
	v_cvt_pk_bf16_f32 v12, v18, v19
	v_ashrrev_i32_e32 v11, 31, v10
	v_lshlrev_b64 v[10:11], 11, v[10:11]
	v_lshl_add_u64 v[14:15], v[154:155], 0, v[10:11]
	v_cvt_pk_bf16_f32 v10, v22, v23
	v_cvt_pk_bf16_f32 v11, v24, v25
	v_cvt_pk_bf16_f32 v13, v20, v21
	v_cvt_pk_bf16_f32 v6, v6, v7
	v_cvt_pk_bf16_f32 v7, v8, v9
	v_cvt_pk_bf16_f32 v8, v2, v3
	v_cvt_pk_bf16_f32 v9, v4, v5
	global_store_dwordx4 v[14:15], v[10:13], off
	global_store_dwordx4 v[14:15], v[6:9], off offset:256
	s_branch .LBB0_1505

.LBB0_1645:
	s_add_u32 s57, s48, s56
	s_addc_u32 s58, s49, 0
	s_add_u32 s59, s57, 0x100
	s_addc_u32 s60, s58, 0
	s_and_b64 s[0:1], s[54:55], exec
	s_cselect_b32 s61, s43, s60
	s_cselect_b32 s60, s83, s59
	s_add_u32 s0, s14, s56
	s_addc_u32 s1, s15, 0
	s_add_u32 s56, s0, 0x100
	s_addc_u32 s59, s1, 0
	s_and_b64 s[0:1], s[54:55], exec
	s_cselect_b32 s63, s41, s59
	s_cselect_b32 s62, s94, s56
	s_add_u32 s64, s57, 0x40080
	s_addc_u32 s65, s58, 0
	s_add_i32 s0, s85, s37
	s_add_i32 m0, s39, 0xc000
	s_add_i32 s71, s39, 0xe000
	s_add_i32 s70, s0, 0x2000
	s_add_u32 s58, s62, 0x10000
	s_addc_u32 s59, s63, 0
	s_add_i32 s1, s4, s37
	ds_read_b128 v[26:29], v225
	ds_read_b128 v[30:33], v225 offset:1024
	ds_read_b128 v[42:45], v225 offset:2048
	ds_read_b128 v[46:49], v225 offset:3072
	s_add_i32 s96, s1, 0x2000
	s_add_i32 s81, 0, 0x18000
	s_add_u32 s56, s60, 0x40000
	s_addc_u32 s57, s61, 0
	s_add_i32 s78, s81, s37
	s_add_i32 s79, 0, 0x1c000
	s_add_i32 s80, s78, 0x2000
	s_add_u32 s54, s62, 0x10080
	s_addc_u32 s55, s63, 0
	s_add_i32 vcc_hi, s79, s37
	s_add_i32 vcc_lo, vcc_hi, 0x2000
	v_lshl_add_u64 v[190:191], s[64:65], 0, v[160:161]
	ds_read_b128 v[146:149], v226
	ds_read_b128 v[150:153], v226 offset:1024
	ds_read_b128 v[166:169], v226 offset:2048
	ds_read_b128 v[170:173], v226 offset:3072
	ds_read_b128 v[174:177], v226 offset:4096
	ds_read_b128 v[178:181], v226 offset:5120
	ds_read_b128 v[182:185], v226 offset:6144
	ds_read_b128 v[186:189], v226 offset:7168
	global_load_lds_dwordx4 v[190:191], off
	v_lshl_add_u64 v[190:191], s[64:65], 0, v[156:157]
	s_mov_b32 m0, s71
	s_nop 0
	global_load_lds_dwordx4 v[190:191], off
	s_waitcnt lgkmcnt(8)
	s_waitcnt vmcnt(10)
	s_barrier
	s_waitcnt lgkmcnt(0)
	v_mfma_f32_16x16x32_bf16 v[142:145], v[26:29], v[146:149], v[142:145]
	v_mfma_f32_16x16x32_bf16 v[134:137], v[42:45], v[146:149], v[134:137]
	v_mfma_f32_16x16x32_bf16 v[126:129], v[26:29], v[166:169], v[126:129]
	v_mfma_f32_16x16x32_bf16 v[118:121], v[42:45], v[166:169], v[118:121]
	v_mfma_f32_16x16x32_bf16 v[110:113], v[26:29], v[174:177], v[110:113]
	v_mfma_f32_16x16x32_bf16 v[102:105], v[42:45], v[174:177], v[102:105]
	v_mfma_f32_16x16x32_bf16 v[94:97], v[26:29], v[182:185], v[94:97]
	v_mfma_f32_16x16x32_bf16 v[86:89], v[42:45], v[182:185], v[86:89]
	v_mfma_f32_16x16x32_bf16 v[142:145], v[30:33], v[150:153], v[142:145]
	v_mfma_f32_16x16x32_bf16 v[134:137], v[46:49], v[150:153], v[134:137]
	v_mfma_f32_16x16x32_bf16 v[126:129], v[30:33], v[170:173], v[126:129]
	v_mfma_f32_16x16x32_bf16 v[118:121], v[46:49], v[170:173], v[118:121]
	v_mfma_f32_16x16x32_bf16 v[110:113], v[30:33], v[178:181], v[110:113]
	v_mfma_f32_16x16x32_bf16 v[102:105], v[46:49], v[178:181], v[102:105]
	v_mfma_f32_16x16x32_bf16 v[94:97], v[30:33], v[186:189], v[94:97]
	v_mfma_f32_16x16x32_bf16 v[86:89], v[46:49], v[186:189], v[86:89]
	s_barrier
	s_mov_b32 m0, s0
	v_lshl_add_u64 v[206:207], s[62:63], 0, v[158:159]
	ds_read_b128 v[190:193], v227
	ds_read_b128 v[194:197], v227 offset:1024
	ds_read_b128 v[198:201], v227 offset:2048
	ds_read_b128 v[202:205], v227 offset:3072
	global_load_lds_dwordx4 v[206:207], off
	v_lshl_add_u64 v[208:209], s[62:63], 0, v[154:155]
	s_mov_b32 m0, s70
	s_nop 0
	global_load_lds_dwordx4 v[208:209], off
	s_waitcnt vmcnt(10)
	s_barrier
	s_waitcnt lgkmcnt(0)
	v_mfma_f32_16x16x32_bf16 v[138:141], v[190:193], v[146:149], v[138:141]
	v_mfma_f32_16x16x32_bf16 v[130:133], v[198:201], v[146:149], v[130:133]
	v_mfma_f32_16x16x32_bf16 v[122:125], v[190:193], v[166:169], v[122:125]
	v_mfma_f32_16x16x32_bf16 v[114:117], v[198:201], v[166:169], v[114:117]
	v_mfma_f32_16x16x32_bf16 v[106:109], v[190:193], v[174:177], v[106:109]
	v_mfma_f32_16x16x32_bf16 v[98:101], v[198:201], v[174:177], v[98:101]
	v_mfma_f32_16x16x32_bf16 v[90:93], v[190:193], v[182:185], v[90:93]
	v_mfma_f32_16x16x32_bf16 v[82:85], v[198:201], v[182:185], v[82:85]
	v_mfma_f32_16x16x32_bf16 v[138:141], v[194:197], v[150:153], v[138:141]
	v_mfma_f32_16x16x32_bf16 v[130:133], v[202:205], v[150:153], v[130:133]
	v_mfma_f32_16x16x32_bf16 v[122:125], v[194:197], v[170:173], v[122:125]
	v_mfma_f32_16x16x32_bf16 v[114:117], v[202:205], v[170:173], v[114:117]
	v_mfma_f32_16x16x32_bf16 v[106:109], v[194:197], v[178:181], v[106:109]
	v_mfma_f32_16x16x32_bf16 v[98:101], v[202:205], v[178:181], v[98:101]
	v_mfma_f32_16x16x32_bf16 v[90:93], v[194:197], v[186:189], v[90:93]
	v_mfma_f32_16x16x32_bf16 v[82:85], v[202:205], v[186:189], v[82:85]
	s_mov_b32 m0, s39
	v_lshl_add_u64 v[210:211], s[60:61], 0, v[160:161]
	s_barrier
	ds_read_b128 v[146:149], v226 offset:16384
	ds_read_b128 v[150:153], v226 offset:17408
	ds_read_b128 v[166:169], v226 offset:18432
	ds_read_b128 v[170:173], v226 offset:19456
	ds_read_b128 v[174:177], v226 offset:20480
	ds_read_b128 v[178:181], v226 offset:21504
	ds_read_b128 v[182:185], v226 offset:22528
	ds_read_b128 v[186:189], v226 offset:23552
	global_load_lds_dwordx4 v[210:211], off
	v_lshl_add_u64 v[212:213], s[60:61], 0, v[156:157]
	s_mov_b32 m0, s53
	s_nop 0
	global_load_lds_dwordx4 v[212:213], off
	s_waitcnt vmcnt(10)
	s_barrier
	s_waitcnt lgkmcnt(0)
	v_mfma_f32_16x16x32_bf16 v[78:81], v[26:29], v[146:149], v[78:81]
	v_mfma_f32_16x16x32_bf16 v[70:73], v[42:45], v[146:149], v[70:73]
	v_mfma_f32_16x16x32_bf16 v[62:65], v[26:29], v[166:169], v[62:65]
	v_mfma_f32_16x16x32_bf16 v[54:57], v[42:45], v[166:169], v[54:57]
	v_mfma_f32_16x16x32_bf16 v[38:41], v[26:29], v[174:177], v[38:41]
	v_mfma_f32_16x16x32_bf16 v[22:25], v[42:45], v[174:177], v[22:25]
	v_mfma_f32_16x16x32_bf16 v[14:17], v[26:29], v[182:185], v[14:17]
	v_mfma_f32_16x16x32_bf16 v[6:9], v[42:45], v[182:185], v[6:9]
	v_mfma_f32_16x16x32_bf16 v[78:81], v[30:33], v[150:153], v[78:81]
	v_mfma_f32_16x16x32_bf16 v[70:73], v[46:49], v[150:153], v[70:73]
	v_mfma_f32_16x16x32_bf16 v[62:65], v[30:33], v[170:173], v[62:65]
	v_mfma_f32_16x16x32_bf16 v[54:57], v[46:49], v[170:173], v[54:57]
	v_mfma_f32_16x16x32_bf16 v[38:41], v[30:33], v[178:181], v[38:41]
	v_mfma_f32_16x16x32_bf16 v[22:25], v[46:49], v[178:181], v[22:25]
	v_mfma_f32_16x16x32_bf16 v[14:17], v[30:33], v[186:189], v[14:17]
	v_mfma_f32_16x16x32_bf16 v[6:9], v[46:49], v[186:189], v[6:9]
	s_barrier
	s_mov_b32 m0, s1
	v_lshl_add_u64 v[26:27], s[58:59], 0, v[158:159]
	global_load_lds_dwordx4 v[26:27], off
	v_lshl_add_u64 v[26:27], s[58:59], 0, v[154:155]
	s_mov_b32 m0, s96
	s_nop 0
	global_load_lds_dwordx4 v[26:27], off
	s_waitcnt vmcnt(10)
	s_barrier
	v_mfma_f32_16x16x32_bf16 v[34:37], v[190:193], v[174:177], v[34:37]
	v_mfma_f32_16x16x32_bf16 v[18:21], v[198:201], v[174:177], v[18:21]
	v_mfma_f32_16x16x32_bf16 v[10:13], v[190:193], v[182:185], v[10:13]
	v_mfma_f32_16x16x32_bf16 v[2:5], v[198:201], v[182:185], v[2:5]
	v_mfma_f32_16x16x32_bf16 v[26:29], v[190:193], v[146:149], v[74:77]
	v_mfma_f32_16x16x32_bf16 v[30:33], v[198:201], v[146:149], v[66:69]
	v_mfma_f32_16x16x32_bf16 v[42:45], v[190:193], v[166:169], v[58:61]
	v_mfma_f32_16x16x32_bf16 v[46:49], v[198:201], v[166:169], v[50:53]
	v_mfma_f32_16x16x32_bf16 v[34:37], v[194:197], v[178:181], v[34:37]
	v_mfma_f32_16x16x32_bf16 v[18:21], v[202:205], v[178:181], v[18:21]
	v_mfma_f32_16x16x32_bf16 v[10:13], v[194:197], v[186:189], v[10:13]
	v_mfma_f32_16x16x32_bf16 v[2:5], v[202:205], v[186:189], v[2:5]
	v_mfma_f32_16x16x32_bf16 v[26:29], v[194:197], v[150:153], v[26:29]
	v_mfma_f32_16x16x32_bf16 v[30:33], v[202:205], v[150:153], v[30:33]
	v_mfma_f32_16x16x32_bf16 v[42:45], v[194:197], v[170:173], v[42:45]
	v_mfma_f32_16x16x32_bf16 v[46:49], v[202:205], v[170:173], v[46:49]
	v_add_u32_e32 v74, s81, v224
	s_barrier
	ds_read_b128 v[50:53], v74
	ds_read_b128 v[58:61], v74 offset:1024
	ds_read_b128 v[66:69], v74 offset:2048
	ds_read_b128 v[74:77], v74 offset:3072
	s_mov_b32 m0, s66
	v_lshl_add_u64 v[190:191], s[56:57], 0, v[160:161]
	ds_read_b128 v[146:149], v226 offset:32768
	ds_read_b128 v[150:153], v226 offset:33792
	ds_read_b128 v[166:169], v226 offset:34816
	ds_read_b128 v[170:173], v226 offset:35840
	ds_read_b128 v[174:177], v226 offset:36864
	ds_read_b128 v[178:181], v226 offset:37888
	ds_read_b128 v[182:185], v226 offset:38912
	ds_read_b128 v[186:189], v226 offset:39936
	global_load_lds_dwordx4 v[190:191], off
	v_lshl_add_u64 v[190:191], s[56:57], 0, v[156:157]
	s_mov_b32 m0, s67
	s_nop 0
	global_load_lds_dwordx4 v[190:191], off
	s_waitcnt lgkmcnt(8)
	s_waitcnt vmcnt(10)
	s_barrier
	s_waitcnt lgkmcnt(0)
	v_mfma_f32_16x16x32_bf16 v[142:145], v[50:53], v[146:149], v[142:145]
	v_mfma_f32_16x16x32_bf16 v[134:137], v[66:69], v[146:149], v[134:137]
	v_mfma_f32_16x16x32_bf16 v[126:129], v[50:53], v[166:169], v[126:129]
	v_mfma_f32_16x16x32_bf16 v[118:121], v[66:69], v[166:169], v[118:121]
	v_mfma_f32_16x16x32_bf16 v[110:113], v[50:53], v[174:177], v[110:113]
	v_mfma_f32_16x16x32_bf16 v[102:105], v[66:69], v[174:177], v[102:105]
	v_mfma_f32_16x16x32_bf16 v[94:97], v[50:53], v[182:185], v[94:97]
	v_mfma_f32_16x16x32_bf16 v[86:89], v[66:69], v[182:185], v[86:89]
	v_mfma_f32_16x16x32_bf16 v[142:145], v[58:61], v[150:153], v[142:145]
	v_mfma_f32_16x16x32_bf16 v[134:137], v[74:77], v[150:153], v[134:137]
	v_mfma_f32_16x16x32_bf16 v[126:129], v[58:61], v[170:173], v[126:129]
	v_mfma_f32_16x16x32_bf16 v[118:121], v[74:77], v[170:173], v[118:121]
	v_mfma_f32_16x16x32_bf16 v[110:113], v[58:61], v[178:181], v[110:113]
	v_mfma_f32_16x16x32_bf16 v[102:105], v[74:77], v[178:181], v[102:105]
	v_mfma_f32_16x16x32_bf16 v[94:97], v[58:61], v[186:189], v[94:97]
	v_mfma_f32_16x16x32_bf16 v[86:89], v[74:77], v[186:189], v[86:89]
	s_barrier
	s_mov_b32 m0, s78
	v_add_u32_e32 v202, s79, v224
	v_lshl_add_u64 v[206:207], v[206:207], 0, s[26:27]
	ds_read_b128 v[190:193], v202
	ds_read_b128 v[194:197], v202 offset:1024
	ds_read_b128 v[198:201], v202 offset:2048
	ds_read_b128 v[202:205], v202 offset:3072
	global_load_lds_dwordx4 v[206:207], off
	v_lshl_add_u64 v[206:207], v[208:209], 0, s[26:27]
	s_mov_b32 m0, s80
	s_nop 0
	global_load_lds_dwordx4 v[206:207], off
	s_waitcnt vmcnt(10)
	s_barrier
	s_waitcnt lgkmcnt(0)
	v_mfma_f32_16x16x32_bf16 v[138:141], v[190:193], v[146:149], v[138:141]
	v_mfma_f32_16x16x32_bf16 v[130:133], v[198:201], v[146:149], v[130:133]
	v_mfma_f32_16x16x32_bf16 v[122:125], v[190:193], v[166:169], v[122:125]
	v_mfma_f32_16x16x32_bf16 v[114:117], v[198:201], v[166:169], v[114:117]
	v_mfma_f32_16x16x32_bf16 v[106:109], v[190:193], v[174:177], v[106:109]
	v_mfma_f32_16x16x32_bf16 v[98:101], v[198:201], v[174:177], v[98:101]
	v_mfma_f32_16x16x32_bf16 v[90:93], v[190:193], v[182:185], v[90:93]
	v_mfma_f32_16x16x32_bf16 v[82:85], v[198:201], v[182:185], v[82:85]
	v_mfma_f32_16x16x32_bf16 v[138:141], v[194:197], v[150:153], v[138:141]
	v_mfma_f32_16x16x32_bf16 v[130:133], v[202:205], v[150:153], v[130:133]
	v_mfma_f32_16x16x32_bf16 v[122:125], v[194:197], v[170:173], v[122:125]
	v_mfma_f32_16x16x32_bf16 v[114:117], v[202:205], v[170:173], v[114:117]
	v_mfma_f32_16x16x32_bf16 v[106:109], v[194:197], v[178:181], v[106:109]
	v_mfma_f32_16x16x32_bf16 v[98:101], v[202:205], v[178:181], v[98:101]
	v_mfma_f32_16x16x32_bf16 v[90:93], v[194:197], v[186:189], v[90:93]
	v_mfma_f32_16x16x32_bf16 v[82:85], v[202:205], v[186:189], v[82:85]
	s_mov_b32 m0, s6
	v_lshl_add_u64 v[206:207], v[210:211], 0, s[26:27]
	s_barrier
	ds_read_b128 v[146:149], v226 offset:49152
	ds_read_b128 v[150:153], v226 offset:50176
	ds_read_b128 v[166:169], v226 offset:51200
	ds_read_b128 v[170:173], v226 offset:52224
	ds_read_b128 v[174:177], v226 offset:53248
	ds_read_b128 v[178:181], v226 offset:54272
	ds_read_b128 v[182:185], v226 offset:55296
	ds_read_b128 v[186:189], v226 offset:56320
	global_load_lds_dwordx4 v[206:207], off
	v_lshl_add_u64 v[206:207], v[212:213], 0, s[26:27]
	s_mov_b32 m0, s7
	s_nop 0
	global_load_lds_dwordx4 v[206:207], off
	s_waitcnt vmcnt(10)
	s_barrier
	s_waitcnt lgkmcnt(0)
	v_mfma_f32_16x16x32_bf16 v[78:81], v[50:53], v[146:149], v[78:81]
	v_mfma_f32_16x16x32_bf16 v[70:73], v[66:69], v[146:149], v[70:73]
	v_mfma_f32_16x16x32_bf16 v[62:65], v[50:53], v[166:169], v[62:65]
	v_mfma_f32_16x16x32_bf16 v[54:57], v[66:69], v[166:169], v[54:57]
	v_mfma_f32_16x16x32_bf16 v[38:41], v[50:53], v[174:177], v[38:41]
	v_mfma_f32_16x16x32_bf16 v[22:25], v[66:69], v[174:177], v[22:25]
	v_mfma_f32_16x16x32_bf16 v[14:17], v[50:53], v[182:185], v[14:17]
	v_mfma_f32_16x16x32_bf16 v[6:9], v[66:69], v[182:185], v[6:9]
	v_mfma_f32_16x16x32_bf16 v[78:81], v[58:61], v[150:153], v[78:81]
	v_mfma_f32_16x16x32_bf16 v[70:73], v[74:77], v[150:153], v[70:73]
	v_mfma_f32_16x16x32_bf16 v[62:65], v[58:61], v[170:173], v[62:65]
	v_mfma_f32_16x16x32_bf16 v[54:57], v[74:77], v[170:173], v[54:57]
	v_mfma_f32_16x16x32_bf16 v[38:41], v[58:61], v[178:181], v[38:41]
	v_mfma_f32_16x16x32_bf16 v[22:25], v[74:77], v[178:181], v[22:25]
	v_mfma_f32_16x16x32_bf16 v[14:17], v[58:61], v[186:189], v[14:17]
	v_mfma_f32_16x16x32_bf16 v[6:9], v[74:77], v[186:189], v[6:9]
	s_barrier
	s_mov_b32 m0, vcc_hi
	v_lshl_add_u64 v[50:51], s[54:55], 0, v[158:159]
	global_load_lds_dwordx4 v[50:51], off
	v_lshl_add_u64 v[50:51], s[54:55], 0, v[154:155]
	s_mov_b32 m0, vcc_lo
	s_nop 0
	global_load_lds_dwordx4 v[50:51], off
	s_waitcnt vmcnt(10)
	s_barrier
	v_mfma_f32_16x16x32_bf16 v[26:29], v[190:193], v[146:149], v[26:29]
	v_mfma_f32_16x16x32_bf16 v[74:77], v[194:197], v[150:153], v[26:29]
	v_mfma_f32_16x16x32_bf16 v[26:29], v[198:201], v[146:149], v[30:33]
	v_mfma_f32_16x16x32_bf16 v[66:69], v[202:205], v[150:153], v[26:29]
	v_mfma_f32_16x16x32_bf16 v[26:29], v[190:193], v[166:169], v[42:45]
	v_mfma_f32_16x16x32_bf16 v[58:61], v[194:197], v[170:173], v[26:29]
	v_mfma_f32_16x16x32_bf16 v[26:29], v[198:201], v[166:169], v[46:49]
	v_mfma_f32_16x16x32_bf16 v[50:53], v[202:205], v[170:173], v[26:29]
	v_mfma_f32_16x16x32_bf16 v[26:29], v[190:193], v[174:177], v[34:37]
	v_mfma_f32_16x16x32_bf16 v[18:21], v[198:201], v[174:177], v[18:21]
	v_mfma_f32_16x16x32_bf16 v[10:13], v[190:193], v[182:185], v[10:13]
	v_mfma_f32_16x16x32_bf16 v[2:5], v[198:201], v[182:185], v[2:5]
	v_mfma_f32_16x16x32_bf16 v[34:37], v[194:197], v[178:181], v[26:29]
	v_mfma_f32_16x16x32_bf16 v[18:21], v[202:205], v[178:181], v[18:21]
	v_mfma_f32_16x16x32_bf16 v[10:13], v[194:197], v[186:189], v[10:13]
	v_mfma_f32_16x16x32_bf16 v[2:5], v[202:205], v[186:189], v[2:5]
	s_movk_i32 s56, 0x100
	s_andn2_b64 vcc, exec, s[50:51]
	s_mov_b64 s[54:55], -1
	s_mov_b64 s[50:51], 0
	s_barrier
	s_cbranch_vccz .LBB0_1645
	s_lshl_b32 s0, s82, 7
	s_and_b32 s1, s0, 0x380
	v_mov_b32_e32 v167, v222
	v_mov_b32_e32 v26, v223
	s_or_b32 s1, s1, s11
	s_cmp_lt_u32 s82, 8
	v_lshl_add_u32 v166, v26, 3, s1
	s_mov_b32 s1, 0x32100000
	s_cselect_b32 s1, s1, 0x1a100000
	s_cselect_b32 s49, s9, s17
	s_cselect_b32 s48, s8, s16
	s_add_u32 s50, s18, s1
	s_addc_u32 s51, s19, 0
	s_and_b32 s0, s0, 0xfffffc00
	v_add_u32_e32 v26, s0, v166
	s_load_dwordx2 s[0:1], s[20:21], 0x78
	v_ashrrev_i32_e32 v27, 31, v26
	v_readlane_b32 s56, v254, 5
	v_lshlrev_b64 v[146:147], 2, v[26:27]
	v_readlane_b32 s57, v254, 6
	v_readlane_b32 s58, v254, 7
	v_readlane_b32 s59, v254, 8
	s_waitcnt lgkmcnt(0)
	v_lshl_add_u64 v[26:27], s[0:1], 0, v[146:147]
	v_lshl_add_u64 v[42:43], s[56:57], 0, v[146:147]
	v_lshl_add_u64 v[150:151], s[58:59], 0, v[146:147]
	global_load_dwordx4 v[30:33], v[26:27], off offset:16
	global_load_dwordx4 v[46:49], v[26:27], off
	s_nop 0
	global_load_dwordx4 v[26:29], v[42:43], off offset:16
	s_nop 0
	global_load_dwordx4 v[42:45], v[42:43], off
	s_nop 0
	global_load_dwordx4 v[146:149], v[150:151], off offset:16
	s_nop 0
	global_load_dwordx4 v[150:153], v[150:151], off
	s_lshl_b32 s0, s52, 8
	s_add_i32 s0, s0, s10
	s_waitcnt vmcnt(0)
	v_add_f32_e32 v134, v134, v30
	v_add_f32_e32 v142, v142, v46
	v_add_f32_e32 v138, v138, v42
	v_max_f32_e32 v168, v150, v150
	v_mul_f32_e64 v150, |v150|, s5
	v_exp_f32_e32 v232, v150
	v_mul_f32_e32 v138, 0xbfb8aa3b, v138
	v_exp_f32_e32 v138, v138
	v_mul_f32_e32 v142, 0xbfb8aa3b, v142
	v_add_f32_e32 v172, 1.0, v232
	v_add_f32_e32 v150, -1.0, v172
	v_sub_f32_e32 v169, v150, v172
	v_add_f32_e32 v169, 1.0, v169
	v_sub_f32_e32 v150, v232, v150
	v_add_f32_e32 v174, v150, v169
	v_max_f32_e32 v150, v151, v151
	v_min_f32_e32 v169, 0, v150
	v_mul_f32_e64 v150, |v151|, s5
	v_exp_f32_e32 v233, v150
	v_cvt_f64_f32_e32 v[170:171], v172
	v_frexp_exp_i32_f64_e32 v170, v[170:171]
	v_frexp_mant_f32_e32 v173, v172
	v_add_f32_e32 v171, 1.0, v233
	v_add_f32_e32 v150, -1.0, v171
	v_sub_f32_e32 v151, v150, v171
	v_add_f32_e32 v151, 1.0, v151
	v_sub_f32_e32 v150, v233, v150
	v_add_f32_e32 v175, v150, v151
	v_frexp_mant_f32_e32 v176, v171
	v_cvt_f64_f32_e32 v[150:151], v171
	v_cmp_gt_f32_e32 vcc, s72, v173
	v_frexp_exp_i32_f64_e32 v150, v[150:151]
	v_cmp_gt_f32_e64 s[14:15], s72, v176
	v_subbrev_co_u32_e32 v176, vcc, 0, v170, vcc
	s_nop 0
	v_subbrev_co_u32_e64 v173, s[14:15], 0, v150, s[14:15]
	v_sub_u32_e32 v151, 0, v176
	v_ldexp_f32 v150, v172, v151
	v_sub_u32_e32 v172, 0, v173
	v_ldexp_f32 v170, v174, v151
	v_ldexp_f32 v151, v171, v172
	v_ldexp_f32 v171, v175, v172
	v_pk_add_f32 v[174:175], v[150:151], 1.0 op_sel_hi:[1,0]
	v_pk_add_f32 v[184:185], v[150:151], -1.0 op_sel_hi:[1,0]
	v_pk_add_f32 v[178:179], v[174:175], -1.0 op_sel_hi:[1,0]
	v_pk_add_f32 v[186:187], v[184:185], 1.0 op_sel_hi:[1,0]
	v_pk_add_f32 v[178:179], v[150:151], v[178:179] neg_lo:[0,1] neg_hi:[0,1]
	v_pk_add_f32 v[150:151], v[150:151], v[186:187] neg_lo:[0,1] neg_hi:[0,1]
	v_pk_add_f32 v[178:179], v[170:171], v[178:179]
	v_pk_add_f32 v[150:151], v[170:171], v[150:151]
	v_pk_add_f32 v[180:181], v[174:175], v[178:179]
	v_pk_add_f32 v[170:171], v[184:185], v[150:151]
	v_rcp_f32_e32 v182, v180
	v_rcp_f32_e32 v183, v181
	v_pk_add_f32 v[174:175], v[180:181], v[174:175] neg_lo:[0,1] neg_hi:[0,1]
	v_pk_add_f32 v[184:185], v[170:171], v[184:185] neg_lo:[0,1] neg_hi:[0,1]
	v_pk_add_f32 v[174:175], v[178:179], v[174:175] neg_lo:[0,1] neg_hi:[0,1]
	v_pk_mul_f32 v[186:187], v[170:171], v[182:183]
	v_pk_add_f32 v[150:151], v[150:151], v[184:185] neg_lo:[0,1] neg_hi:[0,1]
	v_pk_mul_f32 v[178:179], v[180:181], v[186:187]
	s_mov_b32 s14, 0x3ecc95a3
	v_pk_fma_f32 v[184:185], v[186:187], v[180:181], v[178:179] neg_lo:[0,0,1] neg_hi:[0,0,1]
	v_cvt_f32_i32_e32 v177, v173
	v_pk_fma_f32 v[184:185], v[186:187], v[174:175], v[184:185]
	v_cvt_f32_i32_e32 v176, v176
	v_pk_add_f32 v[188:189], v[178:179], v[184:185]
	v_add_f32_e32 v138, 1.0, v138
	v_pk_add_f32 v[190:191], v[170:171], v[188:189] neg_lo:[0,1] neg_hi:[0,1]
	v_pk_add_f32 v[178:179], v[188:189], v[178:179] neg_lo:[0,1] neg_hi:[0,1]
	v_pk_add_f32 v[170:171], v[170:171], v[190:191] neg_lo:[0,1] neg_hi:[0,1]
	v_rcp_f32_e32 v249, v138
	v_pk_add_f32 v[170:171], v[170:171], v[188:189] neg_lo:[0,1] neg_hi:[0,1]
	v_add_f32_e32 v138, v143, v47
	v_pk_add_f32 v[150:151], v[150:151], v[170:171]
	v_pk_add_f32 v[170:171], v[178:179], v[184:185] neg_lo:[0,1] neg_hi:[0,1]
	v_mul_f32_e32 v138, 0xbfb8aa3b, v138
	v_pk_add_f32 v[150:151], v[170:171], v[150:151]
	v_exp_f32_e32 v138, v138
	v_pk_add_f32 v[170:171], v[190:191], v[150:151]
	v_exp_f32_e32 v142, v142
	v_pk_mul_f32 v[178:179], v[182:183], v[170:171]
	v_pk_add_f32 v[190:191], v[190:191], v[170:171] neg_lo:[0,1] neg_hi:[0,1]
	v_pk_mul_f32 v[184:185], v[180:181], v[178:179]
	v_pk_add_f32 v[150:151], v[150:151], v[190:191]
	v_pk_fma_f32 v[180:181], v[178:179], v[180:181], v[184:185] neg_lo:[0,0,1] neg_hi:[0,0,1]
	v_pk_add_f32 v[196:197], v[186:187], v[178:179]
	v_pk_fma_f32 v[174:175], v[178:179], v[174:175], v[180:181]
	v_add_f32_e32 v138, 1.0, v138
	v_pk_add_f32 v[180:181], v[184:185], v[174:175]
	v_rcp_f32_e32 v143, v138
	v_pk_add_f32 v[192:193], v[170:171], v[180:181] neg_lo:[0,1] neg_hi:[0,1]
	v_pk_add_f32 v[188:189], v[180:181], v[184:185] neg_lo:[0,1] neg_hi:[0,1]
	v_pk_add_f32 v[194:195], v[170:171], v[192:193] neg_lo:[0,1] neg_hi:[0,1]
	v_mov_b32_e32 v170, v181
	v_mov_b32_e32 v184, v185
	v_mov_b32_e32 v185, v193
	v_pk_add_f32 v[194:195], v[194:195], v[180:181] neg_lo:[0,1] neg_hi:[0,1]
	v_pk_add_f32 v[170:171], v[170:171], v[184:185] neg_lo:[0,1] neg_hi:[0,1]
	v_mov_b32_e32 v180, v175
	v_pk_add_f32 v[170:171], v[170:171], v[180:181] neg_lo:[0,1] neg_hi:[0,1]
	v_pk_add_f32 v[188:189], v[188:189], v[174:175] neg_lo:[0,1] neg_hi:[0,1]
	v_mov_b32_e32 v195, v171
	v_pk_add_f32 v[150:151], v[150:151], v[194:195]
	v_mov_b32_e32 v189, v170
	v_pk_add_f32 v[150:151], v[188:189], v[150:151]
	v_pk_add_f32 v[170:171], v[196:197], v[186:187] neg_lo:[0,1] neg_hi:[0,1]
	v_pk_add_f32 v[150:151], v[192:193], v[150:151]
	v_pk_add_f32 v[170:171], v[178:179], v[170:171] neg_lo:[0,1] neg_hi:[0,1]
	v_pk_mul_f32 v[150:151], v[182:183], v[150:151]
	v_pk_mul_f32 v[182:183], v[176:177], s[34:35] op_sel_hi:[1,0]
	v_pk_add_f32 v[150:151], v[170:171], v[150:151]
	v_pk_fma_f32 v[184:185], v[176:177], s[34:35], v[182:183] op_sel_hi:[1,0,1] neg_lo:[0,0,1] neg_hi:[0,0,1]
	v_pk_add_f32 v[174:175], v[196:197], v[150:151]
	v_pk_fma_f32 v[184:185], v[176:177], s[36:37], v[184:185] op_sel_hi:[1,0,1]
	v_pk_add_f32 v[170:171], v[174:175], v[196:197] neg_lo:[0,1] neg_hi:[0,1]
	v_pk_mul_f32 v[178:179], v[174:175], v[174:175]
	v_pk_add_f32 v[170:171], v[150:151], v[170:171] neg_lo:[0,1] neg_hi:[0,1]
	v_mov_b64_e32 v[150:151], s[14:15]
	v_pk_fma_f32 v[180:181], v[178:179], s[28:29], v[150:151] op_sel_hi:[1,0,0]
	v_ldexp_f32 v172, v174, 1
	v_pk_fma_f32 v[180:181], v[178:179], v[180:181], s[30:31] op_sel_hi:[1,1,0]
	v_ldexp_f32 v173, v175, 1
	v_pk_mul_f32 v[174:175], v[174:175], v[178:179]
	v_ldexp_f32 v170, v170, 1
	v_pk_mul_f32 v[174:175], v[174:175], v[180:181]
	v_ldexp_f32 v171, v171, 1
	v_pk_add_f32 v[178:179], v[172:173], v[174:175]
	v_pk_add_f32 v[176:177], v[182:183], v[184:185]
	v_pk_add_f32 v[172:173], v[178:179], v[172:173] neg_lo:[0,1] neg_hi:[0,1]
	v_pk_add_f32 v[182:183], v[176:177], v[182:183] neg_lo:[0,1] neg_hi:[0,1]
	v_pk_add_f32 v[172:173], v[174:175], v[172:173] neg_lo:[0,1] neg_hi:[0,1]
	v_pk_add_f32 v[182:183], v[184:185], v[182:183] neg_lo:[0,1] neg_hi:[0,1]
	v_pk_add_f32 v[170:171], v[170:171], v[172:173]
	v_add_f32_e32 v138, v139, v43
	v_pk_add_f32 v[190:191], v[178:179], v[170:171]
	v_mul_f32_e32 v138, 0xbfb8aa3b, v138
	v_pk_add_f32 v[172:173], v[190:191], v[178:179] neg_lo:[0,1] neg_hi:[0,1]
	v_exp_f32_e32 v138, v138
	v_pk_add_f32 v[170:171], v[170:171], v[172:173] neg_lo:[0,1] neg_hi:[0,1]
	v_add_f32_e32 v142, 1.0, v142
	v_pk_add_f32 v[184:185], v[182:183], v[170:171]
	v_add_f32_e32 v138, 1.0, v138
	v_pk_add_f32 v[172:173], v[184:185], v[182:183] neg_lo:[0,1] neg_hi:[0,1]
	v_rcp_f32_e32 v250, v138
	v_pk_add_f32 v[188:189], v[170:171], v[172:173] neg_lo:[0,1] neg_hi:[0,1]
	v_max_f32_e32 v170, v152, v152
	v_mul_f32_e64 v152, |v152|, s5
	v_exp_f32_e32 v236, v152
	v_pk_add_f32 v[174:175], v[184:185], v[172:173] neg_lo:[0,1] neg_hi:[0,1]
	v_min_f32_e32 v180, 0, v170
	v_pk_add_f32 v[186:187], v[182:183], v[174:175] neg_lo:[0,1] neg_hi:[0,1]
	v_add_f32_e32 v172, 1.0, v236
	v_add_f32_e32 v152, -1.0, v172
	v_sub_f32_e32 v170, v152, v172
	v_add_f32_e32 v170, 1.0, v170
	v_sub_f32_e32 v152, v236, v152
	v_add_f32_e32 v173, v152, v170
	v_max_f32_e32 v152, v153, v153
	v_min_f32_e32 v181, 0, v152
	v_mul_f32_e64 v152, |v153|, s5
	v_exp_f32_e32 v238, v152
	v_cvt_f64_f32_e32 v[170:171], v172
	v_frexp_exp_i32_f64_e32 v170, v[170:171]
	v_frexp_mant_f32_e32 v174, v172
	v_add_f32_e32 v171, 1.0, v238
	v_add_f32_e32 v152, -1.0, v171
	v_sub_f32_e32 v153, v152, v171
	v_add_f32_e32 v153, 1.0, v153
	v_sub_f32_e32 v152, v238, v152
	v_add_f32_e32 v175, v152, v153
	v_frexp_mant_f32_e32 v178, v171
	v_cvt_f64_f32_e32 v[152:153], v171
	v_cmp_gt_f32_e32 vcc, s72, v174
	v_frexp_exp_i32_f64_e32 v152, v[152:153]
	v_cmp_gt_f32_e64 s[14:15], s72, v178
	v_subbrev_co_u32_e32 v207, vcc, 0, v170, vcc
	s_nop 0
	v_subbrev_co_u32_e64 v206, s[14:15], 0, v152, s[14:15]
	v_sub_u32_e32 v153, 0, v207
	v_ldexp_f32 v152, v172, v153
	v_sub_u32_e32 v172, 0, v206
	v_ldexp_f32 v170, v173, v153
	v_ldexp_f32 v153, v171, v172
	v_ldexp_f32 v171, v175, v172
	v_pk_add_f32 v[172:173], v[152:153], 1.0 op_sel_hi:[1,0]
	v_pk_add_f32 v[192:193], v[152:153], -1.0 op_sel_hi:[1,0]
	v_pk_add_f32 v[174:175], v[172:173], -1.0 op_sel_hi:[1,0]
	v_pk_add_f32 v[194:195], v[192:193], 1.0 op_sel_hi:[1,0]
	v_pk_add_f32 v[174:175], v[152:153], v[174:175] neg_lo:[0,1] neg_hi:[0,1]
	v_pk_add_f32 v[152:153], v[152:153], v[194:195] neg_lo:[0,1] neg_hi:[0,1]
	v_pk_add_f32 v[174:175], v[170:171], v[174:175]
	v_pk_add_f32 v[152:153], v[170:171], v[152:153]
	v_pk_add_f32 v[178:179], v[172:173], v[174:175]
	v_pk_add_f32 v[170:171], v[192:193], v[152:153]
	v_rcp_f32_e32 v182, v178
	v_rcp_f32_e32 v183, v179
	v_pk_add_f32 v[172:173], v[178:179], v[172:173] neg_lo:[0,1] neg_hi:[0,1]
	v_pk_add_f32 v[192:193], v[170:171], v[192:193] neg_lo:[0,1] neg_hi:[0,1]
	v_pk_add_f32 v[172:173], v[174:175], v[172:173] neg_lo:[0,1] neg_hi:[0,1]
	v_pk_mul_f32 v[194:195], v[170:171], v[182:183]
	v_pk_add_f32 v[152:153], v[152:153], v[192:193] neg_lo:[0,1] neg_hi:[0,1]
	v_pk_mul_f32 v[174:175], v[178:179], v[194:195]
	v_add_f32_e32 v138, v144, v48
	v_pk_fma_f32 v[192:193], v[194:195], v[178:179], v[174:175] neg_lo:[0,0,1] neg_hi:[0,0,1]
	v_mul_f32_e32 v138, 0xbfb8aa3b, v138
	v_pk_fma_f32 v[192:193], v[194:195], v[172:173], v[192:193]
	v_exp_f32_e32 v138, v138
	v_pk_add_f32 v[196:197], v[174:175], v[192:193]
	v_rcp_f32_e32 v142, v142
	v_pk_add_f32 v[198:199], v[170:171], v[196:197] neg_lo:[0,1] neg_hi:[0,1]
	v_pk_add_f32 v[174:175], v[196:197], v[174:175] neg_lo:[0,1] neg_hi:[0,1]
	v_pk_add_f32 v[170:171], v[170:171], v[198:199] neg_lo:[0,1] neg_hi:[0,1]
	v_add_f32_e32 v138, 1.0, v138
	v_pk_add_f32 v[170:171], v[170:171], v[196:197] neg_lo:[0,1] neg_hi:[0,1]
	v_min_f32_e32 v168, 0, v168
	v_pk_add_f32 v[152:153], v[152:153], v[170:171]
	v_pk_add_f32 v[170:171], v[174:175], v[192:193] neg_lo:[0,1] neg_hi:[0,1]
	v_add_f32_e32 v130, v130, v26
	v_pk_add_f32 v[152:153], v[170:171], v[152:153]
	v_mul_f32_e32 v130, 0xbfb8aa3b, v130
	v_pk_add_f32 v[170:171], v[198:199], v[152:153]
	v_exp_f32_e32 v130, v130
	v_pk_mul_f32 v[174:175], v[182:183], v[170:171]
	v_pk_add_f32 v[198:199], v[198:199], v[170:171] neg_lo:[0,1] neg_hi:[0,1]
	v_pk_mul_f32 v[192:193], v[178:179], v[174:175]
	v_pk_add_f32 v[152:153], v[152:153], v[198:199]
	v_pk_fma_f32 v[178:179], v[174:175], v[178:179], v[192:193] neg_lo:[0,0,1] neg_hi:[0,0,1]
	v_pk_add_f32 v[204:205], v[194:195], v[174:175]
	v_pk_fma_f32 v[172:173], v[174:175], v[172:173], v[178:179]
	v_add_f32_e32 v130, 1.0, v130
	v_pk_add_f32 v[178:179], v[192:193], v[172:173]
	v_mul_f32_e32 v134, 0xbfb8aa3b, v134
	v_pk_add_f32 v[200:201], v[170:171], v[178:179] neg_lo:[0,1] neg_hi:[0,1]
	v_pk_add_f32 v[196:197], v[178:179], v[192:193] neg_lo:[0,1] neg_hi:[0,1]
	v_pk_add_f32 v[202:203], v[170:171], v[200:201] neg_lo:[0,1] neg_hi:[0,1]
	v_mov_b32_e32 v170, v179
	v_mov_b32_e32 v192, v193
	v_mov_b32_e32 v193, v201
	v_pk_add_f32 v[202:203], v[202:203], v[178:179] neg_lo:[0,1] neg_hi:[0,1]
	v_pk_add_f32 v[170:171], v[170:171], v[192:193] neg_lo:[0,1] neg_hi:[0,1]
	v_mov_b32_e32 v178, v173
	v_pk_add_f32 v[170:171], v[170:171], v[178:179] neg_lo:[0,1] neg_hi:[0,1]
	v_pk_add_f32 v[196:197], v[196:197], v[172:173] neg_lo:[0,1] neg_hi:[0,1]
	v_mov_b32_e32 v203, v171
	v_pk_add_f32 v[152:153], v[152:153], v[202:203]
	v_mov_b32_e32 v197, v170
	v_pk_add_f32 v[152:153], v[196:197], v[152:153]
	v_pk_add_f32 v[170:171], v[204:205], v[194:195] neg_lo:[0,1] neg_hi:[0,1]
	v_pk_add_f32 v[152:153], v[200:201], v[152:153]
	v_pk_add_f32 v[170:171], v[174:175], v[170:171] neg_lo:[0,1] neg_hi:[0,1]
	v_pk_mul_f32 v[152:153], v[182:183], v[152:153]
	v_cvt_f32_i32_e32 v183, v206
	v_pk_add_f32 v[152:153], v[170:171], v[152:153]
	v_cvt_f32_i32_e32 v182, v207
	v_pk_add_f32 v[170:171], v[204:205], v[152:153]
	v_exp_f32_e32 v134, v134
	v_pk_mul_f32 v[174:175], v[170:171], v[170:171]
	v_pk_add_f32 v[172:173], v[170:171], v[204:205] neg_lo:[0,1] neg_hi:[0,1]
	v_pk_fma_f32 v[178:179], v[174:175], s[28:29], v[150:151] op_sel_hi:[1,0,0]
	v_pk_add_f32 v[152:153], v[152:153], v[172:173] neg_lo:[0,1] neg_hi:[0,1]
	v_ldexp_f32 v172, v170, 1
	v_pk_fma_f32 v[178:179], v[174:175], v[178:179], s[30:31] op_sel_hi:[1,1,0]
	v_ldexp_f32 v173, v171, 1
	v_pk_mul_f32 v[170:171], v[170:171], v[174:175]
	v_pk_mul_f32 v[192:193], v[182:183], s[34:35] op_sel_hi:[1,0]
	v_pk_mul_f32 v[170:171], v[170:171], v[178:179]
	v_ldexp_f32 v152, v152, 1
	v_pk_add_f32 v[174:175], v[172:173], v[170:171]
	v_pk_fma_f32 v[194:195], v[182:183], s[34:35], v[192:193] op_sel_hi:[1,0,1] neg_lo:[0,0,1] neg_hi:[0,0,1]
	v_pk_add_f32 v[172:173], v[174:175], v[172:173] neg_lo:[0,1] neg_hi:[0,1]
	v_ldexp_f32 v153, v153, 1
	v_pk_add_f32 v[170:171], v[170:171], v[172:173] neg_lo:[0,1] neg_hi:[0,1]
	v_pk_fma_f32 v[182:183], v[182:183], s[36:37], v[194:195] op_sel_hi:[1,0,1]
	v_pk_add_f32 v[152:153], v[152:153], v[170:171]
	v_pk_add_f32 v[202:203], v[192:193], v[182:183]
	v_pk_add_f32 v[210:211], v[174:175], v[152:153]
	v_pk_add_f32 v[192:193], v[202:203], v[192:193] neg_lo:[0,1] neg_hi:[0,1]
	v_pk_add_f32 v[170:171], v[210:211], v[174:175] neg_lo:[0,1] neg_hi:[0,1]
	v_pk_add_f32 v[182:183], v[182:183], v[192:193] neg_lo:[0,1] neg_hi:[0,1]
	v_pk_add_f32 v[152:153], v[152:153], v[170:171] neg_lo:[0,1] neg_hi:[0,1]
	v_add_f32_e32 v134, 1.0, v134
	v_pk_add_f32 v[204:205], v[182:183], v[152:153]
	v_rcp_f32_e32 v134, v134
	v_pk_add_f32 v[170:171], v[204:205], v[182:183] neg_lo:[0,1] neg_hi:[0,1]
	v_add_f32_e32 v126, v126, v46
	v_pk_add_f32 v[208:209], v[152:153], v[170:171] neg_lo:[0,1] neg_hi:[0,1]
	v_max_f32_e32 v152, v146, v146
	v_mul_f32_e64 v146, |v146|, s5
	v_exp_f32_e32 v235, v146
	v_pk_add_f32 v[172:173], v[204:205], v[170:171] neg_lo:[0,1] neg_hi:[0,1]
	v_min_f32_e32 v178, 0, v152
	v_pk_add_f32 v[206:207], v[182:183], v[172:173] neg_lo:[0,1] neg_hi:[0,1]
	v_add_f32_e32 v170, 1.0, v235
	v_add_f32_e32 v146, -1.0, v170
	v_sub_f32_e32 v152, v146, v170
	v_add_f32_e32 v152, 1.0, v152
	v_sub_f32_e32 v146, v235, v146
	v_add_f32_e32 v171, v146, v152
	v_max_f32_e32 v146, v147, v147
	v_min_f32_e32 v179, 0, v146
	v_mul_f32_e64 v146, |v147|, s5
	v_exp_f32_e32 v237, v146
	v_cvt_f64_f32_e32 v[152:153], v170
	v_frexp_exp_i32_f64_e32 v152, v[152:153]
	v_frexp_mant_f32_e32 v172, v170
	v_add_f32_e32 v153, 1.0, v237
	v_add_f32_e32 v146, -1.0, v153
	v_sub_f32_e32 v147, v146, v153
	v_add_f32_e32 v147, 1.0, v147
	v_sub_f32_e32 v146, v237, v146
	v_add_f32_e32 v173, v146, v147
	v_frexp_mant_f32_e32 v174, v153
	v_cvt_f64_f32_e32 v[146:147], v153
	v_cmp_gt_f32_e32 vcc, s72, v172
	v_frexp_exp_i32_f64_e32 v146, v[146:147]
	v_cmp_gt_f32_e64 s[14:15], s72, v174
	v_subbrev_co_u32_e32 v217, vcc, 0, v152, vcc
	s_nop 0
	v_subbrev_co_u32_e64 v216, s[14:15], 0, v146, s[14:15]
	v_sub_u32_e32 v147, 0, v217
	v_ldexp_f32 v146, v170, v147
	v_sub_u32_e32 v170, 0, v216
	v_ldexp_f32 v152, v171, v147
	v_ldexp_f32 v147, v153, v170
	v_ldexp_f32 v153, v173, v170
	v_pk_add_f32 v[170:171], v[146:147], 1.0 op_sel_hi:[1,0]
	v_pk_add_f32 v[192:193], v[146:147], -1.0 op_sel_hi:[1,0]
	v_pk_add_f32 v[172:173], v[170:171], -1.0 op_sel_hi:[1,0]
	v_pk_add_f32 v[194:195], v[192:193], 1.0 op_sel_hi:[1,0]
	v_pk_add_f32 v[172:173], v[146:147], v[172:173] neg_lo:[0,1] neg_hi:[0,1]
	v_pk_add_f32 v[146:147], v[146:147], v[194:195] neg_lo:[0,1] neg_hi:[0,1]
	v_pk_add_f32 v[172:173], v[152:153], v[172:173]
	v_pk_add_f32 v[146:147], v[152:153], v[146:147]
	v_pk_add_f32 v[174:175], v[170:171], v[172:173]
	v_pk_add_f32 v[152:153], v[192:193], v[146:147]
	v_rcp_f32_e32 v182, v174
	v_rcp_f32_e32 v183, v175
	v_pk_add_f32 v[170:171], v[174:175], v[170:171] neg_lo:[0,1] neg_hi:[0,1]
	v_pk_add_f32 v[192:193], v[152:153], v[192:193] neg_lo:[0,1] neg_hi:[0,1]
	v_pk_add_f32 v[170:171], v[172:173], v[170:171] neg_lo:[0,1] neg_hi:[0,1]
	v_pk_mul_f32 v[194:195], v[152:153], v[182:183]
	v_pk_add_f32 v[146:147], v[146:147], v[192:193] neg_lo:[0,1] neg_hi:[0,1]
	v_pk_mul_f32 v[172:173], v[174:175], v[194:195]
	v_mul_f32_e32 v126, 0xbfb8aa3b, v126
	v_pk_fma_f32 v[192:193], v[194:195], v[174:175], v[172:173] neg_lo:[0,0,1] neg_hi:[0,0,1]
	v_exp_f32_e32 v126, v126
	v_pk_fma_f32 v[192:193], v[194:195], v[170:171], v[192:193]
	v_add_f32_e32 v122, v122, v42
	v_pk_add_f32 v[196:197], v[172:173], v[192:193]
	v_add_f32_e32 v126, 1.0, v126
	v_pk_add_f32 v[198:199], v[152:153], v[196:197] neg_lo:[0,1] neg_hi:[0,1]
	v_pk_add_f32 v[172:173], v[196:197], v[172:173] neg_lo:[0,1] neg_hi:[0,1]
	v_pk_add_f32 v[152:153], v[152:153], v[198:199] neg_lo:[0,1] neg_hi:[0,1]
	v_rcp_f32_e32 v126, v126
	v_pk_add_f32 v[152:153], v[152:153], v[196:197] neg_lo:[0,1] neg_hi:[0,1]
	v_mul_f32_e32 v122, 0xbfb8aa3b, v122
	v_pk_add_f32 v[146:147], v[146:147], v[152:153]
	v_pk_add_f32 v[152:153], v[172:173], v[192:193] neg_lo:[0,1] neg_hi:[0,1]
	v_exp_f32_e32 v122, v122
	v_pk_add_f32 v[146:147], v[152:153], v[146:147]
	v_add_f32_e32 v123, v123, v43
	v_pk_add_f32 v[152:153], v[198:199], v[146:147]
	v_add_f32_e32 v122, 1.0, v122
	v_pk_mul_f32 v[172:173], v[182:183], v[152:153]
	v_pk_add_f32 v[198:199], v[198:199], v[152:153] neg_lo:[0,1] neg_hi:[0,1]
	v_pk_mul_f32 v[192:193], v[174:175], v[172:173]
	v_pk_add_f32 v[146:147], v[146:147], v[198:199]
	v_pk_fma_f32 v[174:175], v[172:173], v[174:175], v[192:193] neg_lo:[0,0,1] neg_hi:[0,0,1]
	v_pk_add_f32 v[214:215], v[194:195], v[172:173]
	v_pk_fma_f32 v[170:171], v[172:173], v[170:171], v[174:175]
	v_rcp_f32_e32 v122, v122
	v_pk_add_f32 v[174:175], v[192:193], v[170:171]
	v_mul_f32_e32 v123, 0xbfb8aa3b, v123
	v_pk_add_f32 v[200:201], v[152:153], v[174:175] neg_lo:[0,1] neg_hi:[0,1]
	v_pk_add_f32 v[196:197], v[174:175], v[192:193] neg_lo:[0,1] neg_hi:[0,1]
	v_pk_add_f32 v[212:213], v[152:153], v[200:201] neg_lo:[0,1] neg_hi:[0,1]
	v_mov_b32_e32 v152, v175
	v_mov_b32_e32 v192, v193
	v_mov_b32_e32 v193, v201
	v_pk_add_f32 v[212:213], v[212:213], v[174:175] neg_lo:[0,1] neg_hi:[0,1]
	v_pk_add_f32 v[152:153], v[152:153], v[192:193] neg_lo:[0,1] neg_hi:[0,1]
	v_mov_b32_e32 v174, v171
	v_pk_add_f32 v[152:153], v[152:153], v[174:175] neg_lo:[0,1] neg_hi:[0,1]
	v_pk_add_f32 v[196:197], v[196:197], v[170:171] neg_lo:[0,1] neg_hi:[0,1]
	v_mov_b32_e32 v213, v153
	v_pk_add_f32 v[146:147], v[146:147], v[212:213]
	v_mov_b32_e32 v197, v152
	v_pk_add_f32 v[146:147], v[196:197], v[146:147]
	v_pk_add_f32 v[152:153], v[214:215], v[194:195] neg_lo:[0,1] neg_hi:[0,1]
	v_pk_add_f32 v[146:147], v[200:201], v[146:147]
	v_pk_add_f32 v[152:153], v[172:173], v[152:153] neg_lo:[0,1] neg_hi:[0,1]
	v_pk_mul_f32 v[146:147], v[182:183], v[146:147]
	v_cvt_f32_i32_e32 v183, v216
	v_pk_add_f32 v[146:147], v[152:153], v[146:147]
	v_cvt_f32_i32_e32 v182, v217
	v_pk_add_f32 v[152:153], v[214:215], v[146:147]
	v_exp_f32_e32 v123, v123
	v_pk_mul_f32 v[172:173], v[152:153], v[152:153]
	v_pk_add_f32 v[170:171], v[152:153], v[214:215] neg_lo:[0,1] neg_hi:[0,1]
	v_pk_fma_f32 v[174:175], v[172:173], s[28:29], v[150:151] op_sel_hi:[1,0,0]
	v_pk_add_f32 v[146:147], v[146:147], v[170:171] neg_lo:[0,1] neg_hi:[0,1]
	v_ldexp_f32 v170, v152, 1
	v_pk_fma_f32 v[174:175], v[172:173], v[174:175], s[30:31] op_sel_hi:[1,1,0]
	v_ldexp_f32 v171, v153, 1
	v_pk_mul_f32 v[152:153], v[152:153], v[172:173]
	v_pk_mul_f32 v[194:195], v[182:183], s[34:35] op_sel_hi:[1,0]
	v_pk_mul_f32 v[152:153], v[152:153], v[174:175]
	v_ldexp_f32 v146, v146, 1
	v_pk_add_f32 v[172:173], v[170:171], v[152:153]
	v_pk_fma_f32 v[192:193], v[182:183], s[34:35], v[194:195] op_sel_hi:[1,0,1] neg_lo:[0,0,1] neg_hi:[0,0,1]
	v_pk_add_f32 v[170:171], v[172:173], v[170:171] neg_lo:[0,1] neg_hi:[0,1]
	v_ldexp_f32 v147, v147, 1
	v_pk_add_f32 v[152:153], v[152:153], v[170:171] neg_lo:[0,1] neg_hi:[0,1]
	v_pk_fma_f32 v[182:183], v[182:183], s[36:37], v[192:193] op_sel_hi:[1,0,1]
	v_pk_add_f32 v[146:147], v[146:147], v[152:153]
	v_pk_add_f32 v[192:193], v[194:195], v[182:183]
	v_pk_add_f32 v[200:201], v[172:173], v[146:147]
	v_pk_add_f32 v[194:195], v[192:193], v[194:195] neg_lo:[0,1] neg_hi:[0,1]
	v_pk_add_f32 v[152:153], v[200:201], v[172:173] neg_lo:[0,1] neg_hi:[0,1]
	v_pk_add_f32 v[182:183], v[182:183], v[194:195] neg_lo:[0,1] neg_hi:[0,1]
	v_pk_add_f32 v[146:147], v[146:147], v[152:153] neg_lo:[0,1] neg_hi:[0,1]
	v_add_f32_e32 v123, 1.0, v123
	v_pk_add_f32 v[194:195], v[182:183], v[146:147]
	v_rcp_f32_e32 v123, v123
	v_pk_add_f32 v[152:153], v[194:195], v[182:183] neg_lo:[0,1] neg_hi:[0,1]
	v_add_f32_e32 v124, v124, v44
	v_pk_add_f32 v[170:171], v[194:195], v[152:153] neg_lo:[0,1] neg_hi:[0,1]
	v_pk_add_f32 v[198:199], v[146:147], v[152:153] neg_lo:[0,1] neg_hi:[0,1]
	v_max_f32_e32 v146, v148, v148
	v_pk_add_f32 v[196:197], v[182:183], v[170:171] neg_lo:[0,1] neg_hi:[0,1]
	v_min_f32_e32 v182, 0, v146
	v_mul_f32_e64 v146, |v148|, s5
	v_exp_f32_e32 v239, v146
	v_mul_f32_e32 v124, 0xbfb8aa3b, v124
	v_exp_f32_e32 v124, v124
	v_add_f32_e32 v118, v118, v30
	v_add_f32_e32 v148, 1.0, v239
	v_add_f32_e32 v146, -1.0, v148
	v_sub_f32_e32 v147, v146, v148
	v_add_f32_e32 v147, 1.0, v147
	v_sub_f32_e32 v146, v239, v146
	v_add_f32_e32 v152, v146, v147
	v_cvt_f64_f32_e32 v[146:147], v148
	v_frexp_exp_i32_f64_e32 v170, v[146:147]
	v_max_f32_e32 v146, v149, v149
	v_min_f32_e32 v183, 0, v146
	v_mul_f32_e64 v146, |v149|, s5
	v_exp_f32_e32 v240, v146
	v_frexp_mant_f32_e32 v153, v148
	v_cmp_gt_f32_e32 vcc, s72, v153
	v_add_f32_e32 v124, 1.0, v124
	v_add_f32_e32 v149, 1.0, v240
	v_add_f32_e32 v146, -1.0, v149
	v_sub_f32_e32 v147, v146, v149
	v_add_f32_e32 v147, 1.0, v147
	v_sub_f32_e32 v146, v240, v146
	v_add_f32_e32 v171, v146, v147
	v_frexp_mant_f32_e32 v172, v149
	v_cvt_f64_f32_e32 v[146:147], v149
	v_frexp_exp_i32_f64_e32 v146, v[146:147]
	v_cmp_gt_f32_e64 s[14:15], s72, v172
	v_subbrev_co_u32_e32 v241, vcc, 0, v170, vcc
	s_nop 0
	v_subbrev_co_u32_e64 v234, s[14:15], 0, v146, s[14:15]
	v_sub_u32_e32 v147, 0, v241
	v_ldexp_f32 v146, v148, v147
	v_ldexp_f32 v148, v152, v147
	v_sub_u32_e32 v152, 0, v234
	v_ldexp_f32 v147, v149, v152
	v_ldexp_f32 v149, v171, v152
	v_pk_add_f32 v[152:153], v[146:147], 1.0 op_sel_hi:[1,0]
	v_pk_add_f32 v[212:213], v[146:147], -1.0 op_sel_hi:[1,0]
	v_pk_add_f32 v[170:171], v[152:153], -1.0 op_sel_hi:[1,0]
	v_pk_add_f32 v[214:215], v[212:213], 1.0 op_sel_hi:[1,0]
	v_pk_add_f32 v[170:171], v[146:147], v[170:171] neg_lo:[0,1] neg_hi:[0,1]
	v_pk_add_f32 v[146:147], v[146:147], v[214:215] neg_lo:[0,1] neg_hi:[0,1]
	v_pk_add_f32 v[170:171], v[148:149], v[170:171]
	v_pk_add_f32 v[146:147], v[148:149], v[146:147]
	v_pk_add_f32 v[172:173], v[152:153], v[170:171]
	v_pk_add_f32 v[148:149], v[212:213], v[146:147]
	v_rcp_f32_e32 v174, v172
	v_rcp_f32_e32 v175, v173
	v_pk_add_f32 v[152:153], v[172:173], v[152:153] neg_lo:[0,1] neg_hi:[0,1]
	v_pk_add_f32 v[212:213], v[148:149], v[212:213] neg_lo:[0,1] neg_hi:[0,1]
	v_pk_add_f32 v[152:153], v[170:171], v[152:153] neg_lo:[0,1] neg_hi:[0,1]
	v_pk_mul_f32 v[214:215], v[148:149], v[174:175]
	v_pk_add_f32 v[146:147], v[146:147], v[212:213] neg_lo:[0,1] neg_hi:[0,1]
	v_pk_mul_f32 v[170:171], v[172:173], v[214:215]
	v_cmp_lt_f32_e64 s[14:15], |v233|, s77
	v_pk_fma_f32 v[212:213], v[214:215], v[172:173], v[170:171] neg_lo:[0,0,1] neg_hi:[0,0,1]
	v_rcp_f32_e32 v124, v124
	v_pk_fma_f32 v[212:213], v[214:215], v[152:153], v[212:213]
	v_add_f32_e32 v125, v125, v45
	v_pk_add_f32 v[216:217], v[170:171], v[212:213]
	v_mul_f32_e32 v118, 0xbfb8aa3b, v118
	v_pk_add_f32 v[218:219], v[148:149], v[216:217] neg_lo:[0,1] neg_hi:[0,1]
	v_pk_add_f32 v[170:171], v[216:217], v[170:171] neg_lo:[0,1] neg_hi:[0,1]
	v_pk_add_f32 v[148:149], v[148:149], v[218:219] neg_lo:[0,1] neg_hi:[0,1]
	v_mul_f32_e32 v125, 0xbfb8aa3b, v125
	v_pk_add_f32 v[148:149], v[148:149], v[216:217] neg_lo:[0,1] neg_hi:[0,1]
	v_exp_f32_e32 v118, v118
	v_pk_add_f32 v[146:147], v[146:147], v[148:149]
	v_pk_add_f32 v[148:149], v[170:171], v[212:213] neg_lo:[0,1] neg_hi:[0,1]
	v_exp_f32_e32 v125, v125
	v_pk_add_f32 v[146:147], v[148:149], v[146:147]
	v_add_f32_e32 v118, 1.0, v118
	v_pk_add_f32 v[148:149], v[218:219], v[146:147]
	v_add_f32_e32 v125, 1.0, v125
	v_pk_mul_f32 v[170:171], v[174:175], v[148:149]
	v_pk_add_f32 v[218:219], v[218:219], v[148:149] neg_lo:[0,1] neg_hi:[0,1]
	v_pk_mul_f32 v[212:213], v[172:173], v[170:171]
	v_pk_add_f32 v[146:147], v[146:147], v[218:219]
	v_pk_fma_f32 v[172:173], v[170:171], v[172:173], v[212:213] neg_lo:[0,0,1] neg_hi:[0,0,1]
	v_pk_add_f32 v[244:245], v[214:215], v[170:171]
	v_pk_fma_f32 v[152:153], v[170:171], v[152:153], v[172:173]
	v_rcp_f32_e32 v118, v118
	v_pk_add_f32 v[172:173], v[212:213], v[152:153]
	v_rcp_f32_e32 v125, v125
	v_pk_add_f32 v[220:221], v[148:149], v[172:173] neg_lo:[0,1] neg_hi:[0,1]
	v_pk_add_f32 v[216:217], v[172:173], v[212:213] neg_lo:[0,1] neg_hi:[0,1]
	v_pk_add_f32 v[242:243], v[148:149], v[220:221] neg_lo:[0,1] neg_hi:[0,1]
	v_mov_b32_e32 v148, v173
	v_mov_b32_e32 v212, v213
	v_mov_b32_e32 v213, v221
	v_pk_add_f32 v[242:243], v[242:243], v[172:173] neg_lo:[0,1] neg_hi:[0,1]
	v_pk_add_f32 v[148:149], v[148:149], v[212:213] neg_lo:[0,1] neg_hi:[0,1]
	v_mov_b32_e32 v172, v153
	v_pk_add_f32 v[148:149], v[148:149], v[172:173] neg_lo:[0,1] neg_hi:[0,1]
	v_pk_add_f32 v[216:217], v[216:217], v[152:153] neg_lo:[0,1] neg_hi:[0,1]
	v_mov_b32_e32 v243, v149
	v_pk_add_f32 v[146:147], v[146:147], v[242:243]
	v_mov_b32_e32 v217, v148
	v_pk_add_f32 v[146:147], v[216:217], v[146:147]
	v_pk_add_f32 v[148:149], v[244:245], v[214:215] neg_lo:[0,1] neg_hi:[0,1]
	v_pk_add_f32 v[146:147], v[220:221], v[146:147]
	v_pk_add_f32 v[148:149], v[170:171], v[148:149] neg_lo:[0,1] neg_hi:[0,1]
	v_pk_mul_f32 v[146:147], v[174:175], v[146:147]
	v_cvt_f32_i32_e32 v173, v234
	v_pk_add_f32 v[146:147], v[148:149], v[146:147]
	v_cvt_f32_i32_e32 v172, v241
	v_pk_add_f32 v[148:149], v[244:245], v[146:147]
	v_add_u32_e32 v234, s0, v167
	v_pk_mul_f32 v[170:171], v[148:149], v[148:149]
	v_pk_add_f32 v[152:153], v[148:149], v[244:245] neg_lo:[0,1] neg_hi:[0,1]
	v_pk_fma_f32 v[150:151], v[170:171], s[28:29], v[150:151] op_sel_hi:[1,0,0]
	v_pk_add_f32 v[146:147], v[146:147], v[152:153] neg_lo:[0,1] neg_hi:[0,1]
	v_ldexp_f32 v152, v148, 1
	v_pk_fma_f32 v[150:151], v[170:171], v[150:151], s[30:31] op_sel_hi:[1,1,0]
	v_ldexp_f32 v153, v149, 1
	v_pk_mul_f32 v[148:149], v[148:149], v[170:171]
	v_pk_mul_f32 v[174:175], v[172:173], s[34:35] op_sel_hi:[1,0]
	v_pk_mul_f32 v[148:149], v[148:149], v[150:151]
	v_ldexp_f32 v146, v146, 1
	v_pk_add_f32 v[150:151], v[152:153], v[148:149]
	v_pk_fma_f32 v[212:213], v[172:173], s[34:35], v[174:175] op_sel_hi:[1,0,1] neg_lo:[0,0,1] neg_hi:[0,0,1]
	v_pk_add_f32 v[152:153], v[150:151], v[152:153] neg_lo:[0,1] neg_hi:[0,1]
	v_ldexp_f32 v147, v147, 1
	v_pk_add_f32 v[148:149], v[148:149], v[152:153] neg_lo:[0,1] neg_hi:[0,1]
	v_pk_fma_f32 v[172:173], v[172:173], s[36:37], v[212:213] op_sel_hi:[1,0,1]
	v_pk_add_f32 v[146:147], v[146:147], v[148:149]
	v_pk_add_f32 v[212:213], v[174:175], v[172:173]
	v_pk_add_f32 v[220:221], v[150:151], v[146:147]
	v_pk_add_f32 v[174:175], v[212:213], v[174:175] neg_lo:[0,1] neg_hi:[0,1]
	v_pk_add_f32 v[148:149], v[220:221], v[150:151] neg_lo:[0,1] neg_hi:[0,1]
	v_pk_add_f32 v[172:173], v[172:173], v[174:175] neg_lo:[0,1] neg_hi:[0,1]
	v_pk_add_f32 v[146:147], v[146:147], v[148:149] neg_lo:[0,1] neg_hi:[0,1]
	v_ashrrev_i32_e32 v167, 31, v166
	v_pk_add_f32 v[214:215], v[172:173], v[146:147]
	v_mov_b32_e32 v242, v190
	v_pk_add_f32 v[148:149], v[214:215], v[172:173] neg_lo:[0,1] neg_hi:[0,1]
	v_mov_b32_e32 v243, v176
	v_pk_add_f32 v[218:219], v[146:147], v[148:149] neg_lo:[0,1] neg_hi:[0,1]
	v_mov_b32_e32 v146, v234
	v_pk_add_f32 v[150:151], v[214:215], v[148:149] neg_lo:[0,1] neg_hi:[0,1]
	v_ashrrev_i32_e32 v147, 31, v146
	v_lshlrev_b64 v[146:147], 10, v[146:147]
	v_lshl_add_u64 v[146:147], v[146:147], 0, v[166:167]
	v_lshlrev_b64 v[148:149], 1, v[146:147]
	v_lshl_add_u64 v[174:175], s[24:25], 0, v[148:149]
	v_pk_add_f32 v[216:217], v[172:173], v[150:151] neg_lo:[0,1] neg_hi:[0,1]
	global_load_dwordx4 v[150:153], v[174:175], off
	v_lshl_add_u64 v[170:171], s[50:51], 0, v[146:147]
	v_add_co_u32_e32 v146, vcc, s84, v174
	v_lshl_add_u64 v[172:173], s[48:49], 0, v[148:149]
	s_nop 0
	v_addc_co_u32_e32 v147, vcc, 0, v175, vcc
	global_load_dwordx4 v[146:149], v[146:147], off
	v_cmp_neq_f32_e32 vcc, s73, v232
	v_add_f32_e32 v114, v114, v26
	v_add_f32_e32 v119, v119, v31
	v_mul_f32_e32 v114, 0xbfb8aa3b, v114
	v_mul_f32_e32 v119, 0xbfb8aa3b, v119
	v_exp_f32_e32 v114, v114
	v_exp_f32_e32 v119, v119
	v_add_f32_e32 v120, v120, v32
	v_add_f32_e32 v115, v115, v27
	v_add_f32_e32 v114, 1.0, v114
	v_add_f32_e32 v119, 1.0, v119
	v_rcp_f32_e32 v114, v114
	v_rcp_f32_e32 v119, v119
	v_mul_f32_e32 v120, 0xbfb8aa3b, v120
	v_mul_f32_e32 v115, 0xbfb8aa3b, v115
	v_exp_f32_e32 v120, v120
	v_exp_f32_e32 v115, v115
	v_add_f32_e32 v121, v121, v33
	v_add_f32_e32 v116, v116, v28
	v_add_f32_e32 v120, 1.0, v120
	v_add_f32_e32 v115, 1.0, v115
	v_rcp_f32_e32 v120, v120
	v_rcp_f32_e32 v115, v115
	v_mul_f32_e32 v121, 0xbfb8aa3b, v121
	v_mul_f32_e32 v116, 0xbfb8aa3b, v116
	v_exp_f32_e32 v121, v121
	v_exp_f32_e32 v116, v116
	v_add_f32_e32 v117, v117, v29
	v_mul_f32_e32 v117, 0xbfb8aa3b, v117
	v_add_f32_e32 v121, 1.0, v121
	v_add_f32_e32 v116, 1.0, v116
	v_rcp_f32_e32 v121, v121
	v_rcp_f32_e32 v116, v116
	v_exp_f32_e32 v117, v117
	s_waitcnt vmcnt(0) lgkmcnt(0)
	v_lshlrev_b32_e32 v241, 16, v150
	v_and_b32_e32 v246, 0xffff0000, v150
	v_rcp_f32_e32 v150, v138
	v_add_f32_e32 v138, v140, v44
	v_mul_f32_e32 v138, 0xbfb8aa3b, v138
	v_exp_f32_e32 v138, v138
	v_lshlrev_b32_e32 v247, 16, v151
	v_and_b32_e32 v248, 0xffff0000, v151
	v_add_f32_e32 v117, 1.0, v117
	v_add_f32_e32 v138, 1.0, v138
	v_rcp_f32_e32 v251, v138
	v_add_f32_e32 v138, v145, v49
	v_mul_f32_e32 v138, 0xbfb8aa3b, v138
	v_exp_f32_e32 v138, v138
	v_rcp_f32_e32 v117, v117
	v_add_f32_e32 v138, 1.0, v138
	v_rcp_f32_e32 v151, v138
	v_add_f32_e32 v138, v141, v45
	v_mul_f32_e32 v138, 0xbfb8aa3b, v138
	v_exp_f32_e32 v138, v138
	s_nop 0
	v_add_f32_e32 v138, 1.0, v138
	v_rcp_f32_e32 v252, v138
	v_pk_add_f32 v[138:139], v[176:177], v[190:191]
	s_nop 0
	v_pk_add_f32 v[140:141], v[138:139], v[176:177] neg_lo:[0,1] neg_hi:[0,1]
	v_mov_b32_e32 v176, v191
	v_pk_add_f32 v[144:145], v[138:139], v[140:141] neg_lo:[0,1] neg_hi:[0,1]
	v_mov_b32_e32 v244, v140
	v_mov_b32_e32 v245, v144
	v_mov_b32_e32 v144, v141
	v_pk_add_f32 v[242:243], v[242:243], v[244:245] neg_lo:[0,1] neg_hi:[0,1]
	v_pk_add_f32 v[140:141], v[176:177], v[144:145] neg_lo:[0,1] neg_hi:[0,1]
	v_pk_add_f32 v[242:243], v[242:243], v[242:243] op_sel:[0,1] op_sel_hi:[1,0]
	v_pk_add_f32 v[140:141], v[140:141], v[140:141] op_sel_hi:[0,1]
	v_mov_b32_e32 v243, v185
	v_mov_b32_e32 v185, v141
	v_pk_add_f32 v[140:141], v[242:243], v[184:185]
	v_pk_add_f32 v[176:177], v[188:189], v[186:187]
	v_pk_add_f32 v[144:145], v[138:139], v[140:141]
	s_nop 0
	v_pk_add_f32 v[138:139], v[144:145], v[138:139] neg_lo:[0,1] neg_hi:[0,1]
	s_nop 0
	v_pk_add_f32 v[138:139], v[140:141], v[138:139] neg_lo:[0,1] neg_hi:[0,1]
	s_nop 0
	v_pk_add_f32 v[138:139], v[176:177], v[138:139]
	v_mov_b32_e32 v176, v210
	v_pk_add_f32 v[138:139], v[144:145], v[138:139]
	v_mov_b32_e32 v177, v202
	v_cndmask_b32_e32 v138, v228, v138, vcc
	v_cmp_neq_f32_e32 vcc, s73, v233
	s_nop 1
	v_cndmask_b32_e32 v139, v228, v139, vcc
	v_cmp_ngt_f32_e32 vcc, -1.0, v233
	s_nop 1
	v_cndmask_b32_e32 v139, v229, v139, vcc
	v_cmp_ngt_f32_e32 vcc, -1.0, v232
	s_nop 1
	v_cndmask_b32_e32 v138, v229, v138, vcc
	v_cmp_neq_f32_e32 vcc, -1.0, v232
	s_nop 1
	v_cndmask_b32_e32 v138, v230, v138, vcc
	v_cmp_neq_f32_e32 vcc, -1.0, v233
	s_nop 1
	v_cndmask_b32_e32 v139, v230, v139, vcc
	v_cmp_lt_f32_e64 vcc, |v232|, s77
	v_cndmask_b32_e64 v139, v139, v233, s[14:15]
	v_cmp_lt_f32_e64 s[14:15], |v238|, s77
	v_cndmask_b32_e32 v138, v138, v232, vcc
	v_pk_add_f32 v[138:139], v[168:169], v[138:139] neg_lo:[0,1] neg_hi:[0,1]
	v_cmp_neq_f32_e32 vcc, s73, v236
	v_pk_mul_f32 v[144:145], v[138:139], s[38:39] op_sel_hi:[1,0]
	s_nop 0
	v_pk_mul_f32 v[138:139], v[142:143], v[144:145]
	v_mul_f32_e32 v126, v126, v144
	v_add_f32_e32 v140, v138, v138
	v_mul_f32_e32 v140, 0x3fb8aa3b, v140
	v_exp_f32_e32 v140, v140
	v_cvt_pk_bf16_f32 v138, v138, v139
	v_sub_f32_e32 v140, 1.0, v140
	v_max_f32_e32 v140, 0, v140
	v_sqrt_f32_e32 v140, v140
	s_nop 0
	v_mul_f32_e32 v140, v249, v140
	v_mul_f32_e32 v186, v140, v241
	v_add_f32_e32 v140, v139, v139
	v_mul_f32_e32 v140, 0x3fb8aa3b, v140
	v_exp_f32_e32 v140, v140
	s_nop 0
	v_sub_f32_e32 v140, 1.0, v140
	v_max_f32_e32 v140, 0, v140
	v_sqrt_f32_e32 v140, v140
	s_nop 0
	v_mul_f32_e32 v140, v250, v140
	v_mul_f32_e32 v187, v140, v246
	v_pk_add_f32 v[140:141], v[202:203], v[210:211]
	s_nop 0
	v_pk_add_f32 v[142:143], v[140:141], v[202:203] neg_lo:[0,1] neg_hi:[0,1]
	v_mov_b32_e32 v202, v211
	v_pk_add_f32 v[168:169], v[140:141], v[142:143] neg_lo:[0,1] neg_hi:[0,1]
	v_mov_b32_e32 v184, v142
	v_mov_b32_e32 v185, v168
	v_mov_b32_e32 v168, v143
	v_pk_add_f32 v[176:177], v[176:177], v[184:185] neg_lo:[0,1] neg_hi:[0,1]
	v_pk_add_f32 v[142:143], v[202:203], v[168:169] neg_lo:[0,1] neg_hi:[0,1]
	v_pk_add_f32 v[176:177], v[176:177], v[176:177] op_sel:[0,1] op_sel_hi:[1,0]
	v_pk_add_f32 v[142:143], v[142:143], v[142:143] op_sel_hi:[0,1]
	v_mov_b32_e32 v177, v205
	v_mov_b32_e32 v205, v143
	v_pk_add_f32 v[142:143], v[176:177], v[204:205]
	v_pk_add_f32 v[176:177], v[208:209], v[206:207]
	v_pk_add_f32 v[168:169], v[140:141], v[142:143]
	s_nop 0
	v_pk_add_f32 v[140:141], v[168:169], v[140:141] neg_lo:[0,1] neg_hi:[0,1]
	s_nop 0
	v_pk_add_f32 v[140:141], v[142:143], v[140:141] neg_lo:[0,1] neg_hi:[0,1]
	s_nop 0
	v_pk_add_f32 v[140:141], v[176:177], v[140:141]
	v_rcp_f32_e32 v177, v130
	v_add_f32_e32 v130, v135, v31
	v_pk_add_f32 v[140:141], v[168:169], v[140:141]
	v_mul_f32_e32 v130, 0xbfb8aa3b, v130
	v_cndmask_b32_e32 v139, v228, v140, vcc
	v_cmp_neq_f32_e32 vcc, s73, v238
	v_exp_f32_e32 v130, v130
	v_and_b32_e32 v176, 0xffff0000, v152
	v_cndmask_b32_e32 v140, v228, v141, vcc
	v_cmp_ngt_f32_e32 vcc, -1.0, v238
	v_add_f32_e32 v130, 1.0, v130
	v_rcp_f32_e32 v135, v130
	v_cndmask_b32_e32 v140, v229, v140, vcc
	v_cmp_ngt_f32_e32 vcc, -1.0, v236
	v_add_f32_e32 v130, v131, v27
	v_mul_f32_e32 v130, 0xbfb8aa3b, v130
	v_cndmask_b32_e32 v139, v229, v139, vcc
	v_cmp_neq_f32_e32 vcc, -1.0, v236
	v_exp_f32_e32 v130, v130
	s_nop 0
	v_cndmask_b32_e32 v139, v230, v139, vcc
	v_cmp_neq_f32_e32 vcc, -1.0, v238
	v_add_f32_e32 v130, 1.0, v130
	v_rcp_f32_e32 v184, v130
	v_cndmask_b32_e32 v140, v230, v140, vcc
	v_cmp_lt_f32_e64 vcc, |v236|, s77
	v_cndmask_b32_e64 v141, v140, v238, s[14:15]
	v_add_f32_e32 v130, v136, v32
	v_cndmask_b32_e32 v140, v139, v236, vcc
	v_pk_add_f32 v[140:141], v[180:181], v[140:141] neg_lo:[0,1] neg_hi:[0,1]
	v_mul_f32_e32 v130, 0xbfb8aa3b, v130
	v_pk_mul_f32 v[142:143], v[140:141], s[38:39] op_sel_hi:[1,0]
	v_exp_f32_e32 v130, v130
	v_pk_mul_f32 v[140:141], v[150:151], v[142:143]
	v_lshlrev_b32_e32 v180, 16, v153
	v_add_f32_e32 v139, v140, v140
	v_mul_f32_e32 v139, 0x3fb8aa3b, v139
	v_exp_f32_e32 v139, v139
	v_add_f32_e32 v130, 1.0, v130
	v_rcp_f32_e32 v136, v130
	v_add_f32_e32 v130, v132, v28
	v_sub_f32_e32 v139, 1.0, v139
	v_max_f32_e32 v139, 0, v139
	v_sqrt_f32_e32 v139, v139
	v_mul_f32_e32 v130, 0xbfb8aa3b, v130
	v_exp_f32_e32 v130, v130
	v_and_b32_e32 v181, 0xffff0000, v153
	v_mul_f32_e32 v139, v251, v139
	v_mul_f32_e32 v150, v139, v247
	v_add_f32_e32 v139, v141, v141
	v_mul_f32_e32 v139, 0x3fb8aa3b, v139
	v_exp_f32_e32 v139, v139
	v_add_f32_e32 v130, 1.0, v130
	v_rcp_f32_e32 v185, v130
	v_add_f32_e32 v130, v137, v33
	v_mul_f32_e32 v130, 0xbfb8aa3b, v130
	v_exp_f32_e32 v130, v130
	v_sub_f32_e32 v139, 1.0, v139
	v_max_f32_e32 v139, 0, v139
	v_sqrt_f32_e32 v139, v139
	v_add_f32_e32 v130, 1.0, v130
	v_rcp_f32_e32 v137, v130
	v_add_f32_e32 v130, v133, v29
	v_mul_f32_e32 v130, 0xbfb8aa3b, v130
	v_mul_f32_e32 v139, v252, v139
	v_exp_f32_e32 v130, v130
	v_mul_f32_e32 v151, v139, v248
	v_cvt_pk_bf16_f32 v139, v140, v141
	v_mul_f32_e32 v140, 0x42000000, v186
	v_mul_f32_e32 v141, 0x42000000, v187
	v_mul_f32_e32 v168, 0x42000000, v150
	v_med3_f32 v140, v140, s29, v231
	v_med3_f32 v141, v141, s29, v231
	v_mov_b32_e32 v150, 0
	v_cvt_pk_fp8_f32 v150, v140, v141
	v_add_f32_e32 v130, 1.0, v130
	v_mul_f32_e32 v151, 0x42000000, v151
	v_rcp_f32_e32 v186, v130
	v_pk_add_f32 v[130:131], v[192:193], v[200:201]
	v_med3_f32 v140, v168, s29, v231
	v_med3_f32 v141, v151, s29, v231
	v_pk_add_f32 v[132:133], v[130:131], v[192:193] neg_lo:[0,1] neg_hi:[0,1]
	v_cvt_pk_fp8_f32 v150, v140, v141 op_sel:[0,0,1]
	v_pk_add_f32 v[140:141], v[130:131], v[132:133] neg_lo:[0,1] neg_hi:[0,1]
	v_lshlrev_b32_e32 v151, 16, v152
	v_mov_b32_e32 v152, v200
	v_mov_b32_e32 v153, v192
	v_mov_b32_e32 v168, v132
	v_mov_b32_e32 v169, v140
	v_mov_b32_e32 v192, v201
	v_mov_b32_e32 v140, v133
	v_pk_add_f32 v[152:153], v[152:153], v[168:169] neg_lo:[0,1] neg_hi:[0,1]
	v_pk_add_f32 v[132:133], v[192:193], v[140:141] neg_lo:[0,1] neg_hi:[0,1]
	v_pk_add_f32 v[152:153], v[152:153], v[152:153] op_sel:[0,1] op_sel_hi:[1,0]
	v_pk_add_f32 v[132:133], v[132:133], v[132:133] op_sel_hi:[0,1]
	v_mov_b32_e32 v153, v195
	v_mov_b32_e32 v195, v133
	v_pk_add_f32 v[132:133], v[152:153], v[194:195]
	v_pk_add_f32 v[152:153], v[198:199], v[196:197]
	v_pk_add_f32 v[140:141], v[130:131], v[132:133]
	v_cmp_neq_f32_e32 vcc, s73, v235
	v_pk_add_f32 v[130:131], v[140:141], v[130:131] neg_lo:[0,1] neg_hi:[0,1]
	v_cmp_lt_f32_e64 s[14:15], |v237|, s77
	v_pk_add_f32 v[130:131], v[132:133], v[130:131] neg_lo:[0,1] neg_hi:[0,1]
	v_mov_b32_e32 v168, v220
	v_pk_add_f32 v[130:131], v[152:153], v[130:131]
	v_mov_b32_e32 v169, v212
	v_pk_add_f32 v[130:131], v[140:141], v[130:131]
	s_nop 0
	v_cndmask_b32_e32 v130, v228, v130, vcc
	v_cmp_neq_f32_e32 vcc, s73, v237
	s_nop 1
	v_cndmask_b32_e32 v131, v228, v131, vcc
	v_cmp_ngt_f32_e32 vcc, -1.0, v237
	s_nop 1
	v_cndmask_b32_e32 v131, v229, v131, vcc
	v_cmp_ngt_f32_e32 vcc, -1.0, v235
	s_nop 1
	v_cndmask_b32_e32 v130, v229, v130, vcc
	v_cmp_neq_f32_e32 vcc, -1.0, v235
	s_nop 1
	v_cndmask_b32_e32 v130, v230, v130, vcc
	v_cmp_neq_f32_e32 vcc, -1.0, v237
	s_nop 1
	v_cndmask_b32_e32 v131, v230, v131, vcc
	v_cmp_lt_f32_e64 vcc, |v235|, s77
	v_cndmask_b32_e64 v131, v131, v237, s[14:15]
	v_cmp_lt_f32_e64 s[14:15], |v240|, s77
	v_cndmask_b32_e32 v130, v130, v235, vcc
	v_pk_add_f32 v[130:131], v[178:179], v[130:131] neg_lo:[0,1] neg_hi:[0,1]
	v_cmp_neq_f32_e32 vcc, s73, v239
	v_pk_mul_f32 v[130:131], v[130:131], s[38:39] op_sel_hi:[1,0]
	s_nop 0
	v_pk_mul_f32 v[132:133], v[134:135], v[130:131]
	v_mul_f32_e32 v118, v118, v130
	v_add_f32_e32 v134, v132, v132
	v_mul_f32_e32 v134, 0x3fb8aa3b, v134
	v_exp_f32_e32 v134, v134
	v_cvt_pk_bf16_f32 v140, v132, v133
	v_mul_f32_e32 v119, v119, v131
	v_sub_f32_e32 v134, 1.0, v134
	v_max_f32_e32 v134, 0, v134
	v_sqrt_f32_e32 v134, v134
	s_nop 0
	v_mul_f32_e32 v134, v177, v134
	v_mul_f32_e32 v151, v134, v151
	v_add_f32_e32 v134, v133, v133
	v_mul_f32_e32 v134, 0x3fb8aa3b, v134
	v_exp_f32_e32 v134, v134
	v_pk_add_f32 v[132:133], v[212:213], v[220:221]
	v_sub_f32_e32 v134, 1.0, v134
	v_max_f32_e32 v134, 0, v134
	v_sqrt_f32_e32 v134, v134
	s_nop 0
	v_mul_f32_e32 v134, v184, v134
	v_mul_f32_e32 v178, v134, v176
	v_pk_add_f32 v[134:135], v[132:133], v[212:213] neg_lo:[0,1] neg_hi:[0,1]
	v_mov_b32_e32 v212, v221
	v_pk_add_f32 v[152:153], v[132:133], v[134:135] neg_lo:[0,1] neg_hi:[0,1]
	v_mov_b32_e32 v176, v134
	v_mov_b32_e32 v177, v152
	v_mov_b32_e32 v152, v135
	v_pk_add_f32 v[168:169], v[168:169], v[176:177] neg_lo:[0,1] neg_hi:[0,1]
	v_pk_add_f32 v[134:135], v[212:213], v[152:153] neg_lo:[0,1] neg_hi:[0,1]
	v_pk_add_f32 v[168:169], v[168:169], v[168:169] op_sel:[0,1] op_sel_hi:[1,0]
	v_pk_add_f32 v[134:135], v[134:135], v[134:135] op_sel_hi:[0,1]
	v_mov_b32_e32 v169, v215
	v_mov_b32_e32 v215, v135
	v_pk_add_f32 v[134:135], v[168:169], v[214:215]
	v_pk_add_f32 v[168:169], v[218:219], v[216:217]
	v_pk_add_f32 v[152:153], v[132:133], v[134:135]
	s_nop 0
	v_pk_add_f32 v[132:133], v[152:153], v[132:133] neg_lo:[0,1] neg_hi:[0,1]
	s_nop 0
	v_pk_add_f32 v[132:133], v[134:135], v[132:133] neg_lo:[0,1] neg_hi:[0,1]
	s_nop 0
	v_pk_add_f32 v[132:133], v[168:169], v[132:133]
	s_nop 0
	v_pk_add_f32 v[132:133], v[152:153], v[132:133]
	s_nop 0
	v_cndmask_b32_e32 v132, v228, v132, vcc
	v_cmp_neq_f32_e32 vcc, s73, v240
	s_nop 1
	v_cndmask_b32_e32 v133, v228, v133, vcc
	v_cmp_ngt_f32_e32 vcc, -1.0, v240
	s_nop 1
	v_cndmask_b32_e32 v133, v229, v133, vcc
	v_cmp_ngt_f32_e32 vcc, -1.0, v239
	s_nop 1
	v_cndmask_b32_e32 v132, v229, v132, vcc
	v_cmp_neq_f32_e32 vcc, -1.0, v239
	s_nop 1
	v_cndmask_b32_e32 v132, v230, v132, vcc
	v_cmp_neq_f32_e32 vcc, -1.0, v240
	s_nop 1
	v_cndmask_b32_e32 v133, v230, v133, vcc
	v_cmp_lt_f32_e64 vcc, |v239|, s77
	v_cndmask_b32_e64 v133, v133, v240, s[14:15]
	s_nop 0
	v_cndmask_b32_e32 v132, v132, v239, vcc
	v_pk_add_f32 v[132:133], v[182:183], v[132:133] neg_lo:[0,1] neg_hi:[0,1]
	s_nop 0
	v_pk_mul_f32 v[132:133], v[132:133], s[38:39] op_sel_hi:[1,0]
	s_nop 0
	v_pk_mul_f32 v[134:135], v[136:137], v[132:133]
	v_mul_f32_e32 v120, v120, v132
	v_add_f32_e32 v136, v134, v134
	v_add_f32_e32 v137, v135, v135
	v_mul_f32_e32 v136, 0x3fb8aa3b, v136
	v_mul_f32_e32 v137, 0x3fb8aa3b, v137
	v_exp_f32_e32 v136, v136
	v_exp_f32_e32 v137, v137
	v_cvt_pk_bf16_f32 v141, v134, v135
	v_mul_f32_e32 v134, 0x42000000, v151
	v_sub_f32_e32 v136, 1.0, v136
	v_sub_f32_e32 v137, 1.0, v137
	v_max_f32_e32 v136, 0, v136
	v_max_f32_e32 v137, 0, v137
	v_sqrt_f32_e32 v136, v136
	v_sqrt_f32_e32 v137, v137
	v_mul_f32_e32 v135, 0x42000000, v178
	v_med3_f32 v134, v134, s29, v231
	v_med3_f32 v135, v135, s29, v231
	v_mov_b32_e32 v151, 0
	v_mul_f32_e32 v136, v185, v136
	v_mul_f32_e32 v137, v186, v137
	v_cvt_pk_fp8_f32 v151, v134, v135
	v_mul_f32_e32 v136, v136, v180
	v_mul_f32_e32 v137, v137, v181
	v_mul_f32_e32 v136, 0x42000000, v136
	v_mul_f32_e32 v137, 0x42000000, v137
	v_med3_f32 v134, v136, s29, v231
	v_med3_f32 v135, v137, s29, v231
	v_cvt_pk_fp8_f32 v151, v134, v135 op_sel:[0,0,1]
	global_store_dwordx4 v[172:173], v[138:141], off
	global_store_dwordx2 v[170:171], v[150:151], off
	s_nop 0
	v_add_f32_e32 v138, v126, v126
	v_mul_f32_e32 v138, 0x3fb8aa3b, v138
	v_exp_f32_e32 v138, v138
	v_lshlrev_b32_e32 v134, 16, v146
	v_and_b32_e32 v135, 0xffff0000, v146
	v_lshlrev_b32_e32 v136, 16, v147
	v_sub_f32_e32 v138, 1.0, v138
	v_max_f32_e32 v138, 0, v138
	v_sqrt_f32_e32 v138, v138
	v_and_b32_e32 v137, 0xffff0000, v147
	v_mul_f32_e32 v121, v121, v133
	v_mul_f32_e32 v122, v122, v138
	v_mul_f32_e32 v134, v122, v134
	v_add_f32_e32 v122, v127, v47
	v_mul_f32_e32 v122, 0xbfb8aa3b, v122
	v_exp_f32_e32 v122, v122
	s_nop 0
	v_add_f32_e32 v122, 1.0, v122
	v_rcp_f32_e32 v122, v122
	s_nop 0
	v_mul_f32_e32 v122, v122, v145
	v_add_f32_e32 v127, v122, v122
	v_mul_f32_e32 v127, 0x3fb8aa3b, v127
	v_exp_f32_e32 v127, v127
	v_cvt_pk_bf16_f32 v122, v126, v122
	v_mul_f32_e32 v126, 0x42000000, v134
	v_sub_f32_e32 v127, 1.0, v127
	v_max_f32_e32 v127, 0, v127
	v_sqrt_f32_e32 v127, v127
	s_nop 0
	v_mul_f32_e32 v123, v123, v127
	v_mul_f32_e32 v127, v123, v135
	v_add_f32_e32 v123, v128, v48
	v_mul_f32_e32 v123, 0xbfb8aa3b, v123
	v_exp_f32_e32 v123, v123
	v_mul_f32_e32 v127, 0x42000000, v127
	v_med3_f32 v127, v127, s29, v231
	v_add_f32_e32 v123, 1.0, v123
	v_rcp_f32_e32 v123, v123
	s_nop 0
	v_mul_f32_e32 v123, v123, v142
	v_add_f32_e32 v128, v123, v123
	v_mul_f32_e32 v128, 0x3fb8aa3b, v128
	v_exp_f32_e32 v128, v128
	s_nop 0
	v_sub_f32_e32 v128, 1.0, v128
	v_max_f32_e32 v128, 0, v128
	v_sqrt_f32_e32 v128, v128
	s_nop 0
	v_mul_f32_e32 v124, v124, v128
	v_add_f32_e32 v128, v129, v49
	v_mul_f32_e32 v128, 0xbfb8aa3b, v128
	v_exp_f32_e32 v128, v128
	v_mul_f32_e32 v124, v124, v136
	v_mul_f32_e32 v124, 0x42000000, v124
	v_med3_f32 v124, v124, s29, v231
	v_add_f32_e32 v128, 1.0, v128
	v_rcp_f32_e32 v128, v128
	s_nop 0
	v_mul_f32_e32 v128, v128, v143
	v_add_f32_e32 v129, v128, v128
	v_mul_f32_e32 v129, 0x3fb8aa3b, v129
	v_exp_f32_e32 v129, v129
	v_cvt_pk_bf16_f32 v123, v123, v128
	v_med3_f32 v128, v126, s29, v231
	v_mov_b32_e32 v126, 0
	v_sub_f32_e32 v129, 1.0, v129
	v_max_f32_e32 v129, 0, v129
	v_sqrt_f32_e32 v129, v129
	v_cvt_pk_fp8_f32 v126, v128, v127
	v_lshlrev_b32_e32 v127, 16, v149
	v_and_b32_e32 v128, 0xffff0000, v149
	v_mul_f32_e32 v125, v125, v129
	v_add_f32_e32 v129, v118, v118
	v_mul_f32_e32 v129, 0x3fb8aa3b, v129
	v_exp_f32_e32 v129, v129
	v_mul_f32_e32 v125, v125, v137
	v_mul_f32_e32 v125, 0x42000000, v125
	v_med3_f32 v125, v125, s29, v231
	v_sub_f32_e32 v129, 1.0, v129
	v_max_f32_e32 v129, 0, v129
	v_sqrt_f32_e32 v129, v129
	v_cvt_pk_fp8_f32 v126, v124, v125 op_sel:[0,0,1]
	v_lshlrev_b32_e32 v124, 16, v148
	v_and_b32_e32 v125, 0xffff0000, v148
	v_mul_f32_e32 v114, v114, v129
	v_mul_f32_e32 v114, v114, v124
	v_add_f32_e32 v124, v119, v119
	v_mul_f32_e32 v124, 0x3fb8aa3b, v124
	v_exp_f32_e32 v124, v124
	v_mul_f32_e32 v114, 0x42000000, v114
	v_med3_f32 v114, v114, s29, v231
	v_sub_f32_e32 v124, 1.0, v124
	v_max_f32_e32 v124, 0, v124
	v_sqrt_f32_e32 v124, v124
	s_nop 0
	v_mul_f32_e32 v115, v115, v124
	v_add_f32_e32 v124, v120, v120
	v_mul_f32_e32 v124, 0x3fb8aa3b, v124
	v_exp_f32_e32 v124, v124
	v_mul_f32_e32 v115, v115, v125
	v_mul_f32_e32 v115, 0x42000000, v115
	v_med3_f32 v115, v115, s29, v231
	v_sub_f32_e32 v124, 1.0, v124
	v_max_f32_e32 v124, 0, v124
	v_sqrt_f32_e32 v124, v124
	v_cvt_pk_bf16_f32 v125, v120, v121
	v_mul_f32_e32 v116, v116, v124
	v_add_f32_e32 v124, v121, v121
	v_mul_f32_e32 v124, 0x3fb8aa3b, v124
	v_exp_f32_e32 v124, v124
	v_mul_f32_e32 v116, v116, v127
	v_mov_b32_e32 v127, 0
	v_cvt_pk_fp8_f32 v127, v114, v115
	v_sub_f32_e32 v124, 1.0, v124
	v_max_f32_e32 v124, 0, v124
	v_sqrt_f32_e32 v124, v124
	v_mul_f32_e32 v116, 0x42000000, v116
	v_med3_f32 v114, v116, s29, v231
	v_mul_f32_e32 v117, v117, v124
	v_mul_f32_e32 v117, v117, v128
	v_mul_f32_e32 v117, 0x42000000, v117
	v_med3_f32 v115, v117, s29, v231
	v_cvt_pk_fp8_f32 v127, v114, v115 op_sel:[0,0,1]
	v_add_co_u32_e32 v114, vcc, s84, v172
	v_cvt_pk_bf16_f32 v124, v118, v119
	s_nop 0
	v_addc_co_u32_e32 v115, vcc, 0, v173, vcc
	global_store_dwordx4 v[114:115], v[122:125], off
	v_add_co_u32_e32 v114, vcc, s93, v170
	s_nop 1
	v_addc_co_u32_e32 v115, vcc, 0, v171, vcc
	global_store_dwordx2 v[114:115], v[126:127], off
	v_add_co_u32_e32 v114, vcc, s92, v174
	v_add_f32_e32 v110, v110, v46
	s_nop 0
	v_addc_co_u32_e32 v115, vcc, 0, v175, vcc
	global_load_dwordx4 v[114:117], v[114:115], off
	v_mul_f32_e32 v110, 0xbfb8aa3b, v110
	v_add_f32_e32 v111, v111, v47
	v_exp_f32_e32 v110, v110
	v_mul_f32_e32 v111, 0xbfb8aa3b, v111
	v_exp_f32_e32 v111, v111
	v_add_f32_e32 v112, v112, v48
	v_add_f32_e32 v113, v113, v49
	v_add_f32_e32 v110, 1.0, v110
	v_mul_f32_e32 v112, 0xbfb8aa3b, v112
	v_mul_f32_e32 v113, 0xbfb8aa3b, v113
	v_rcp_f32_e32 v110, v110
	v_exp_f32_e32 v112, v112
	v_exp_f32_e32 v113, v113
	v_add_f32_e32 v111, 1.0, v111
	v_rcp_f32_e32 v111, v111
	v_add_co_u32_e32 v118, vcc, s89, v174
	v_add_f32_e32 v120, v106, v42
	s_nop 0
	v_addc_co_u32_e32 v119, vcc, 0, v175, vcc
	v_add_f32_e32 v122, v108, v44
	v_mul_f32_e32 v110, v110, v144
	v_add_f32_e32 v121, v107, v43
	v_add_f32_e32 v123, v109, v45
	global_load_dwordx4 v[106:109], v[118:119], off
	v_mul_f32_e32 v118, 0xbfb8aa3b, v120
	v_mul_f32_e32 v120, 0xbfb8aa3b, v122
	v_add_f32_e32 v112, 1.0, v112
	v_add_f32_e32 v113, 1.0, v113
	v_add_f32_e32 v122, v110, v110
	v_rcp_f32_e32 v112, v112
	v_rcp_f32_e32 v113, v113
	v_mul_f32_e32 v111, v111, v145
	v_mul_f32_e32 v122, 0x3fb8aa3b, v122
	v_mul_f32_e32 v119, 0xbfb8aa3b, v121
	v_mul_f32_e32 v121, 0xbfb8aa3b, v123
	v_add_f32_e32 v123, v111, v111
	v_exp_f32_e32 v122, v122
	v_exp_f32_e32 v118, v118
	v_mul_f32_e32 v123, 0x3fb8aa3b, v123
	v_exp_f32_e32 v123, v123
	v_exp_f32_e32 v119, v119
	v_mul_f32_e32 v112, v112, v142
	v_mul_f32_e32 v113, v113, v143
	v_add_f32_e32 v124, v112, v112
	v_add_f32_e32 v125, v113, v113
	v_sub_f32_e32 v122, 1.0, v122
	v_add_f32_e32 v118, 1.0, v118
	v_mul_f32_e32 v124, 0x3fb8aa3b, v124
	v_mul_f32_e32 v125, 0x3fb8aa3b, v125
	v_max_f32_e32 v122, 0, v122
	v_rcp_f32_e32 v118, v118
	v_exp_f32_e32 v124, v124
	v_exp_f32_e32 v125, v125
	v_sub_f32_e32 v123, 1.0, v123
	v_sqrt_f32_e32 v122, v122
	v_exp_f32_e32 v120, v120
	v_exp_f32_e32 v121, v121
	v_add_f32_e32 v119, 1.0, v119
	v_max_f32_e32 v123, 0, v123
	v_rcp_f32_e32 v119, v119
	v_sqrt_f32_e32 v123, v123
	v_add_f32_e32 v102, v102, v30
	v_mul_f32_e32 v102, 0xbfb8aa3b, v102
	v_sub_f32_e32 v124, 1.0, v124
	v_sub_f32_e32 v125, 1.0, v125
	v_mul_f32_e32 v118, v118, v122
	v_exp_f32_e32 v102, v102
	v_add_f32_e32 v120, 1.0, v120
	v_add_f32_e32 v121, 1.0, v121
	v_max_f32_e32 v124, 0, v124
	v_rcp_f32_e32 v120, v120
	v_rcp_f32_e32 v121, v121
	v_sqrt_f32_e32 v124, v124
	v_mul_f32_e32 v119, v119, v123
	v_cvt_pk_bf16_f32 v110, v110, v111
	v_cvt_pk_bf16_f32 v111, v112, v113
	v_add_f32_e32 v102, 1.0, v102
	v_rcp_f32_e32 v102, v102
	s_waitcnt vmcnt(0) lgkmcnt(0)
	v_lshlrev_b32_e32 v122, 16, v114
	v_mul_f32_e32 v118, v118, v122
	v_max_f32_e32 v122, 0, v125
	v_and_b32_e32 v114, 0xffff0000, v114
	v_sqrt_f32_e32 v122, v122
	v_mul_f32_e32 v114, v119, v114
	v_mul_f32_e32 v112, 0x42000000, v118
	v_mul_f32_e32 v113, 0x42000000, v114
	v_med3_f32 v112, v112, s29, v231
	v_med3_f32 v113, v113, s29, v231
	v_mov_b32_e32 v114, 0
	v_lshlrev_b32_e32 v123, 16, v115
	v_and_b32_e32 v115, 0xffff0000, v115
	v_mul_f32_e32 v119, v120, v124
	v_mul_f32_e32 v120, v121, v122
	v_cvt_pk_fp8_f32 v114, v112, v113
	v_mul_f32_e32 v119, v119, v123
	v_mul_f32_e32 v115, v120, v115
	v_mul_f32_e32 v118, 0x42000000, v119
	v_mul_f32_e32 v112, 0x42000000, v115
	v_med3_f32 v113, v118, s29, v231
	v_med3_f32 v112, v112, s29, v231
	v_mul_f32_e32 v102, v102, v130
	v_cvt_pk_fp8_f32 v114, v113, v112 op_sel:[0,0,1]
	v_lshlrev_b32_e32 v112, 16, v116
	v_and_b32_e32 v113, 0xffff0000, v116
	v_add_f32_e32 v116, v102, v102
	v_add_f32_e32 v103, v103, v31
	v_add_f32_e32 v98, v98, v26
	v_mul_f32_e32 v116, 0x3fb8aa3b, v116
	v_mul_f32_e32 v103, 0xbfb8aa3b, v103
	v_mul_f32_e32 v98, 0xbfb8aa3b, v98
	v_exp_f32_e32 v116, v116
	v_exp_f32_e32 v103, v103
	v_exp_f32_e32 v98, v98
	v_add_f32_e32 v104, v104, v32
	v_sub_f32_e32 v116, 1.0, v116
	v_add_f32_e32 v103, 1.0, v103
	v_add_f32_e32 v98, 1.0, v98
	v_max_f32_e32 v116, 0, v116
	v_rcp_f32_e32 v103, v103
	v_rcp_f32_e32 v98, v98
	v_sqrt_f32_e32 v116, v116
	v_add_f32_e32 v105, v105, v33
	v_mul_f32_e32 v103, v103, v131
	v_add_f32_e32 v99, v99, v27
	v_mul_f32_e32 v98, v98, v116
	v_add_f32_e32 v116, v103, v103
	v_mul_f32_e32 v116, 0x3fb8aa3b, v116
	v_mul_f32_e32 v104, 0xbfb8aa3b, v104
	v_mul_f32_e32 v105, 0xbfb8aa3b, v105
	v_mul_f32_e32 v99, 0xbfb8aa3b, v99
	v_exp_f32_e32 v116, v116
	v_exp_f32_e32 v104, v104
	v_exp_f32_e32 v105, v105
	v_exp_f32_e32 v99, v99
	v_sub_f32_e32 v116, 1.0, v116
	v_add_f32_e32 v104, 1.0, v104
	v_add_f32_e32 v105, 1.0, v105
	v_add_f32_e32 v99, 1.0, v99
	v_max_f32_e32 v116, 0, v116
	v_rcp_f32_e32 v104, v104
	v_rcp_f32_e32 v105, v105
	v_rcp_f32_e32 v99, v99
	v_sqrt_f32_e32 v116, v116
	v_mul_f32_e32 v104, v104, v132
	v_mul_f32_e32 v105, v105, v133
	v_mul_f32_e32 v98, v98, v112
	v_mul_f32_e32 v99, v99, v116
	v_add_f32_e32 v112, v104, v104
	v_add_f32_e32 v116, v105, v105
	v_add_f32_e32 v100, v100, v28
	v_mul_f32_e32 v112, 0x3fb8aa3b, v112
	v_add_f32_e32 v101, v101, v29
	v_mul_f32_e32 v116, 0x3fb8aa3b, v116
	v_mul_f32_e32 v100, 0xbfb8aa3b, v100
	v_exp_f32_e32 v112, v112
	v_mul_f32_e32 v101, 0xbfb8aa3b, v101
	v_exp_f32_e32 v116, v116
	v_add_f32_e32 v94, v94, v46
	v_exp_f32_e32 v100, v100
	v_exp_f32_e32 v101, v101
	v_mul_f32_e32 v94, 0xbfb8aa3b, v94
	v_exp_f32_e32 v94, v94
	v_sub_f32_e32 v112, 1.0, v112
	v_sub_f32_e32 v116, 1.0, v116
	v_add_f32_e32 v100, 1.0, v100
	v_max_f32_e32 v112, 0, v112
	v_add_f32_e32 v101, 1.0, v101
	v_max_f32_e32 v116, 0, v116
	v_rcp_f32_e32 v100, v100
	v_sqrt_f32_e32 v112, v112
	v_rcp_f32_e32 v101, v101
	v_sqrt_f32_e32 v116, v116
	v_add_f32_e32 v94, 1.0, v94
	v_rcp_f32_e32 v94, v94
	v_mul_f32_e32 v99, v99, v113
	v_lshlrev_b32_e32 v115, 16, v117
	v_and_b32_e32 v117, 0xffff0000, v117
	v_mul_f32_e32 v100, v100, v112
	v_mul_f32_e32 v101, v101, v116
	v_mul_f32_e32 v98, 0x42000000, v98
	v_mul_f32_e32 v99, 0x42000000, v99
	v_mul_f32_e32 v100, v100, v115
	v_mul_f32_e32 v101, v101, v117
	v_med3_f32 v98, v98, s29, v231
	v_med3_f32 v99, v99, s29, v231
	v_mov_b32_e32 v115, 0
	v_mul_f32_e32 v94, v94, v144
	v_cvt_pk_fp8_f32 v115, v98, v99
	v_mul_f32_e32 v98, 0x42000000, v101
	v_add_f32_e32 v101, v94, v94
	v_add_f32_e32 v95, v95, v47
	v_add_f32_e32 v90, v90, v42
	v_mul_f32_e32 v101, 0x3fb8aa3b, v101
	v_mul_f32_e32 v95, 0xbfb8aa3b, v95
	v_mul_f32_e32 v90, 0xbfb8aa3b, v90
	v_exp_f32_e32 v101, v101
	v_exp_f32_e32 v95, v95
	v_exp_f32_e32 v90, v90
	v_add_f32_e32 v91, v91, v43
	v_sub_f32_e32 v101, 1.0, v101
	v_add_f32_e32 v95, 1.0, v95
	v_add_f32_e32 v90, 1.0, v90
	v_max_f32_e32 v101, 0, v101
	v_rcp_f32_e32 v95, v95
	v_rcp_f32_e32 v90, v90
	v_sqrt_f32_e32 v101, v101
	v_add_f32_e32 v96, v96, v48
	v_mul_f32_e32 v95, v95, v145
	v_mul_f32_e32 v91, 0xbfb8aa3b, v91
	v_mul_f32_e32 v90, v90, v101
	v_add_f32_e32 v101, v95, v95
	v_mul_f32_e32 v101, 0x3fb8aa3b, v101
	v_exp_f32_e32 v101, v101
	v_mul_f32_e32 v96, 0xbfb8aa3b, v96
	v_add_f32_e32 v97, v97, v49
	v_exp_f32_e32 v91, v91
	v_exp_f32_e32 v96, v96
	v_mul_f32_e32 v97, 0xbfb8aa3b, v97
	v_exp_f32_e32 v97, v97
	v_mul_f32_e32 v100, 0x42000000, v100
	v_med3_f32 v99, v100, s29, v231
	v_med3_f32 v98, v98, s29, v231
	v_sub_f32_e32 v101, 1.0, v101
	v_add_f32_e32 v92, v92, v44
	v_cvt_pk_fp8_f32 v115, v99, v98 op_sel:[0,0,1]
	v_add_co_u32_e32 v98, vcc, s92, v172
	v_add_f32_e32 v91, 1.0, v91
	v_max_f32_e32 v101, 0, v101
	v_add_f32_e32 v96, 1.0, v96
	v_mul_f32_e32 v92, 0xbfb8aa3b, v92
	v_cvt_pk_bf16_f32 v112, v102, v103
	v_cvt_pk_bf16_f32 v113, v104, v105
	v_addc_co_u32_e32 v99, vcc, 0, v173, vcc
	v_rcp_f32_e32 v91, v91
	v_sqrt_f32_e32 v101, v101
	v_exp_f32_e32 v92, v92
	v_rcp_f32_e32 v96, v96
	v_add_f32_e32 v97, 1.0, v97
	global_store_dwordx4 v[98:99], v[110:113], off
	v_add_co_u32_e32 v98, vcc, s84, v170
	v_rcp_f32_e32 v97, v97
	s_nop 0
	v_addc_co_u32_e32 v99, vcc, 0, v171, vcc
	global_store_dwordx2 v[98:99], v[114:115], off
	v_lshlrev_b32_e32 v98, 16, v106
	v_mul_f32_e32 v98, v90, v98
	v_mul_f32_e32 v90, v91, v101
	v_add_f32_e32 v91, 1.0, v92
	v_mul_f32_e32 v92, v96, v142
	v_add_f32_e32 v96, v92, v92
	v_mul_f32_e32 v97, v97, v143
	v_mul_f32_e32 v96, 0x3fb8aa3b, v96
	v_add_f32_e32 v101, v97, v97
	v_exp_f32_e32 v96, v96
	v_add_f32_e32 v93, v93, v45
	v_mul_f32_e32 v101, 0x3fb8aa3b, v101
	v_mul_f32_e32 v93, 0xbfb8aa3b, v93
	v_exp_f32_e32 v101, v101
	v_exp_f32_e32 v93, v93
	v_add_f32_e32 v86, v86, v30
	v_mul_f32_e32 v86, 0xbfb8aa3b, v86
	v_sub_f32_e32 v96, 1.0, v96
	v_exp_f32_e32 v86, v86
	v_max_f32_e32 v96, 0, v96
	v_sub_f32_e32 v101, 1.0, v101
	v_rcp_f32_e32 v91, v91
	v_sqrt_f32_e32 v96, v96
	v_add_f32_e32 v93, 1.0, v93
	v_max_f32_e32 v101, 0, v101
	v_rcp_f32_e32 v93, v93
	v_sqrt_f32_e32 v101, v101
	v_add_f32_e32 v86, 1.0, v86
	v_and_b32_e32 v99, 0xffff0000, v106
	v_rcp_f32_e32 v86, v86
	v_lshlrev_b32_e32 v100, 16, v107
	v_mul_f32_e32 v99, v90, v99
	v_mul_f32_e32 v90, v91, v96
	v_and_b32_e32 v102, 0xffff0000, v107
	v_mul_f32_e32 v96, v90, v100
	v_mul_f32_e32 v90, v93, v101
	v_mul_f32_e32 v93, v90, v102
	v_cvt_pk_bf16_f32 v90, v94, v95
	v_cvt_pk_bf16_f32 v91, v92, v97
	v_mul_f32_e32 v92, 0x42000000, v98
	v_mul_f32_e32 v94, 0x42000000, v99
	v_mul_f32_e32 v95, 0x42000000, v96
	v_med3_f32 v92, v92, s29, v231
	v_med3_f32 v96, v94, s29, v231
	v_mov_b32_e32 v94, 0
	v_mul_f32_e32 v86, v86, v130
	v_cvt_pk_fp8_f32 v94, v92, v96
	v_add_f32_e32 v96, v86, v86
	v_add_f32_e32 v87, v87, v31
	v_add_f32_e32 v82, v82, v26
	v_mul_f32_e32 v96, 0x3fb8aa3b, v96
	v_mul_f32_e32 v87, 0xbfb8aa3b, v87
	v_mul_f32_e32 v82, 0xbfb8aa3b, v82
	v_exp_f32_e32 v96, v96
	v_exp_f32_e32 v87, v87
	v_exp_f32_e32 v82, v82
	v_add_f32_e32 v88, v88, v32
	v_sub_f32_e32 v96, 1.0, v96
	v_add_f32_e32 v87, 1.0, v87
	v_add_f32_e32 v82, 1.0, v82
	v_max_f32_e32 v96, 0, v96
	v_rcp_f32_e32 v87, v87
	v_rcp_f32_e32 v82, v82
	v_sqrt_f32_e32 v96, v96
	v_mul_f32_e32 v88, 0xbfb8aa3b, v88
	v_mul_f32_e32 v87, v87, v131
	v_exp_f32_e32 v88, v88
	v_mul_f32_e32 v82, v82, v96
	v_add_f32_e32 v96, v87, v87
	v_add_f32_e32 v89, v89, v33
	v_add_f32_e32 v83, v83, v27
	v_mul_f32_e32 v96, 0x3fb8aa3b, v96
	v_mul_f32_e32 v89, 0xbfb8aa3b, v89
	v_mul_f32_e32 v83, 0xbfb8aa3b, v83
	v_exp_f32_e32 v96, v96
	v_exp_f32_e32 v89, v89
	v_exp_f32_e32 v83, v83
	v_add_f32_e32 v88, 1.0, v88
	v_rcp_f32_e32 v88, v88
	v_sub_f32_e32 v96, 1.0, v96
	v_add_f32_e32 v89, 1.0, v89
	v_mul_f32_e32 v92, 0x42000000, v93
	v_add_f32_e32 v83, 1.0, v83
	v_max_f32_e32 v96, 0, v96
	v_rcp_f32_e32 v89, v89
	v_med3_f32 v93, v95, s29, v231
	v_med3_f32 v92, v92, s29, v231
	v_rcp_f32_e32 v83, v83
	v_sqrt_f32_e32 v96, v96
	v_cvt_pk_fp8_f32 v94, v93, v92 op_sel:[0,0,1]
	v_lshlrev_b32_e32 v92, 16, v108
	v_mul_f32_e32 v88, v88, v132
	v_mul_f32_e32 v82, v82, v92
	v_add_f32_e32 v92, v88, v88
	v_add_f32_e32 v84, v84, v28
	v_mul_f32_e32 v92, 0x3fb8aa3b, v92
	v_mul_f32_e32 v89, v89, v133
	v_mul_f32_e32 v84, 0xbfb8aa3b, v84
	v_mul_f32_e32 v83, v83, v96
	v_exp_f32_e32 v92, v92
	v_add_f32_e32 v96, v89, v89
	v_exp_f32_e32 v84, v84
	v_add_f32_e32 v85, v85, v29
	v_mul_f32_e32 v96, 0x3fb8aa3b, v96
	v_mul_f32_e32 v85, 0xbfb8aa3b, v85
	v_exp_f32_e32 v96, v96
	v_exp_f32_e32 v85, v85
	v_sub_f32_e32 v92, 1.0, v92
	v_add_f32_e32 v84, 1.0, v84
	v_max_f32_e32 v92, 0, v92
	v_rcp_f32_e32 v84, v84
	v_sqrt_f32_e32 v92, v92
	v_sub_f32_e32 v96, 1.0, v96
	v_add_f32_e32 v85, 1.0, v85
	v_max_f32_e32 v96, 0, v96
	v_and_b32_e32 v93, 0xffff0000, v108
	v_rcp_f32_e32 v85, v85
	v_sqrt_f32_e32 v96, v96
	v_mul_f32_e32 v83, v83, v93
	v_lshlrev_b32_e32 v95, 16, v109
	v_mul_f32_e32 v84, v84, v92
	v_mul_f32_e32 v82, 0x42000000, v82
	v_mul_f32_e32 v83, 0x42000000, v83
	v_mul_f32_e32 v84, v84, v95
	v_med3_f32 v82, v82, s29, v231
	v_med3_f32 v83, v83, s29, v231
	v_mov_b32_e32 v95, 0
	v_and_b32_e32 v97, 0xffff0000, v109
	v_mul_f32_e32 v85, v85, v96
	v_cvt_pk_fp8_f32 v95, v82, v83
	v_mul_f32_e32 v85, v85, v97
	v_mul_f32_e32 v84, 0x42000000, v84
	v_mul_f32_e32 v82, 0x42000000, v85
	v_med3_f32 v83, v84, s29, v231
	v_med3_f32 v82, v82, s29, v231
	v_cvt_pk_fp8_f32 v95, v83, v82 op_sel:[0,0,1]
	v_add_co_u32_e32 v82, vcc, s89, v172
	v_cvt_pk_bf16_f32 v92, v86, v87
	v_cvt_pk_bf16_f32 v93, v88, v89
	v_addc_co_u32_e32 v83, vcc, 0, v173, vcc
	s_mov_b32 s0, 0xc000
	global_store_dwordx4 v[82:83], v[90:93], off
	v_add_co_u32_e32 v82, vcc, s0, v170
	s_nop 1
	v_addc_co_u32_e32 v83, vcc, 0, v171, vcc
	global_store_dwordx2 v[82:83], v[94:95], off
	v_add_u32_e32 v82, 0x80, v234
	v_add_f32_e32 v78, v78, v46
	v_ashrrev_i32_e32 v83, 31, v82
	v_lshlrev_b64 v[82:83], 10, v[82:83]
	v_lshl_add_u64 v[88:89], v[82:83], 0, v[166:167]
	v_lshlrev_b64 v[90:91], 1, v[88:89]
	v_lshl_add_u64 v[82:83], s[24:25], 0, v[90:91]
	global_load_dwordx4 v[84:87], v[82:83], off
	v_mul_f32_e32 v78, 0xbfb8aa3b, v78
	v_exp_f32_e32 v92, v78
	v_add_f32_e32 v79, v79, v47
	v_add_f32_e32 v80, v80, v48
	v_mul_f32_e32 v79, 0xbfb8aa3b, v79
	v_add_f32_e32 v74, v74, v42
	v_add_f32_e32 v81, v81, v49
	v_mul_f32_e32 v80, 0xbfb8aa3b, v80
	v_exp_f32_e32 v93, v79
	v_add_f32_e32 v75, v75, v43
	v_add_f32_e32 v76, v76, v44
	v_add_f32_e32 v77, v77, v45
	v_mul_f32_e32 v74, 0xbfb8aa3b, v74
	v_mul_f32_e32 v81, 0xbfb8aa3b, v81
	v_exp_f32_e32 v94, v80
	v_lshl_add_u64 v[78:79], s[50:51], 0, v[88:89]
	v_add_f32_e32 v88, 1.0, v92
	v_mul_f32_e32 v75, 0xbfb8aa3b, v75
	v_mul_f32_e32 v76, 0xbfb8aa3b, v76
	v_mul_f32_e32 v77, 0xbfb8aa3b, v77
	v_exp_f32_e32 v74, v74
	v_exp_f32_e32 v95, v81
	v_rcp_f32_e32 v88, v88
	v_exp_f32_e32 v75, v75
	v_exp_f32_e32 v76, v76
	v_exp_f32_e32 v77, v77
	v_lshl_add_u64 v[80:81], s[48:49], 0, v[90:91]
	v_add_f32_e32 v90, 1.0, v93
	v_add_f32_e32 v92, 1.0, v94
	v_rcp_f32_e32 v90, v90
	v_add_f32_e32 v89, 1.0, v74
	v_add_f32_e32 v93, 1.0, v95
	v_add_co_u32_e32 v74, vcc, s84, v82
	v_rcp_f32_e32 v92, v92
	v_mul_f32_e32 v88, v88, v144
	v_add_f32_e32 v91, 1.0, v75
	v_add_f32_e32 v76, 1.0, v76
	v_add_f32_e32 v77, 1.0, v77
	v_addc_co_u32_e32 v75, vcc, 0, v83, vcc
	v_rcp_f32_e32 v93, v93
	v_add_f32_e32 v96, v88, v88
	v_rcp_f32_e32 v94, v76
	v_rcp_f32_e32 v95, v77
	global_load_dwordx4 v[74:77], v[74:75], off
	v_mul_f32_e32 v96, 0x3fb8aa3b, v96
	v_mul_f32_e32 v90, v90, v145
	v_exp_f32_e32 v96, v96
	v_mul_f32_e32 v92, v92, v142
	v_add_f32_e32 v97, v90, v90
	v_mul_f32_e32 v93, v93, v143
	v_add_f32_e32 v98, v92, v92
	v_mul_f32_e32 v97, 0x3fb8aa3b, v97
	v_add_f32_e32 v99, v93, v93
	v_mul_f32_e32 v98, 0x3fb8aa3b, v98
	v_exp_f32_e32 v97, v97
	v_mul_f32_e32 v99, 0x3fb8aa3b, v99
	v_exp_f32_e32 v98, v98
	v_sub_f32_e32 v96, 1.0, v96
	v_exp_f32_e32 v99, v99
	v_max_f32_e32 v96, 0, v96
	v_rcp_f32_e32 v89, v89
	v_sqrt_f32_e32 v96, v96
	v_add_f32_e32 v70, v70, v30
	v_sub_f32_e32 v97, 1.0, v97
	v_mul_f32_e32 v70, 0xbfb8aa3b, v70
	v_sub_f32_e32 v98, 1.0, v98
	v_max_f32_e32 v97, 0, v97
	v_exp_f32_e32 v70, v70
	v_rcp_f32_e32 v91, v91
	v_sub_f32_e32 v99, 1.0, v99
	v_max_f32_e32 v98, 0, v98
	v_sqrt_f32_e32 v97, v97
	v_max_f32_e32 v99, 0, v99
	v_sqrt_f32_e32 v98, v98
	v_mul_f32_e32 v89, v89, v96
	v_add_f32_e32 v70, 1.0, v70
	v_mul_f32_e32 v91, v91, v97
	s_waitcnt vmcnt(0) lgkmcnt(0)
	v_lshlrev_b32_e32 v96, 16, v84
	v_mul_f32_e32 v89, v89, v96
	v_sqrt_f32_e32 v96, v99
	v_and_b32_e32 v84, 0xffff0000, v84
	v_rcp_f32_e32 v70, v70
	v_lshlrev_b32_e32 v97, 16, v85
	v_mul_f32_e32 v91, v91, v84
	v_mul_f32_e32 v84, v94, v98
	v_and_b32_e32 v85, 0xffff0000, v85
	v_mul_f32_e32 v94, v84, v97
	v_mul_f32_e32 v84, v95, v96
	v_mul_f32_e32 v95, v84, v85
	v_cvt_pk_bf16_f32 v84, v88, v90
	v_mul_f32_e32 v88, 0x42000000, v89
	v_mul_f32_e32 v89, 0x42000000, v91
	v_med3_f32 v91, v88, s29, v231
	v_med3_f32 v89, v89, s29, v231
	v_mov_b32_e32 v88, 0
	v_mul_f32_e32 v70, v70, v130
	v_cvt_pk_fp8_f32 v88, v91, v89
	v_add_f32_e32 v91, v70, v70
	v_add_f32_e32 v71, v71, v31
	v_add_f32_e32 v66, v66, v26
	v_mul_f32_e32 v91, 0x3fb8aa3b, v91
	v_mul_f32_e32 v71, 0xbfb8aa3b, v71
	v_mul_f32_e32 v66, 0xbfb8aa3b, v66
	v_exp_f32_e32 v91, v91
	v_exp_f32_e32 v71, v71
	v_exp_f32_e32 v66, v66
	v_add_f32_e32 v73, v73, v33
	v_sub_f32_e32 v91, 1.0, v91
	v_add_f32_e32 v71, 1.0, v71
	v_add_f32_e32 v66, 1.0, v66
	v_max_f32_e32 v91, 0, v91
	v_rcp_f32_e32 v71, v71
	v_rcp_f32_e32 v66, v66
	v_sqrt_f32_e32 v91, v91
	v_add_f32_e32 v67, v67, v27
	v_mul_f32_e32 v71, v71, v131
	v_add_f32_e32 v72, v72, v32
	v_mul_f32_e32 v66, v66, v91
	v_add_f32_e32 v91, v71, v71
	v_mul_f32_e32 v91, 0x3fb8aa3b, v91
	v_mul_f32_e32 v73, 0xbfb8aa3b, v73
	v_mul_f32_e32 v67, 0xbfb8aa3b, v67
	v_exp_f32_e32 v91, v91
	v_mul_f32_e32 v72, 0xbfb8aa3b, v72
	v_exp_f32_e32 v73, v73
	v_exp_f32_e32 v67, v67
	v_exp_f32_e32 v72, v72
	v_sub_f32_e32 v91, 1.0, v91
	v_add_f32_e32 v73, 1.0, v73
	v_add_f32_e32 v67, 1.0, v67
	v_max_f32_e32 v91, 0, v91
	v_add_f32_e32 v72, 1.0, v72
	v_rcp_f32_e32 v73, v73
	v_rcp_f32_e32 v67, v67
	v_sqrt_f32_e32 v91, v91
	v_rcp_f32_e32 v72, v72
	v_mul_f32_e32 v90, 0x42000000, v94
	v_mul_f32_e32 v89, 0x42000000, v95
	v_med3_f32 v90, v90, s29, v231
	v_med3_f32 v89, v89, s29, v231
	v_mul_f32_e32 v73, v73, v133
	v_cvt_pk_fp8_f32 v88, v90, v89 op_sel:[0,0,1]
	v_lshlrev_b32_e32 v89, 16, v86
	v_mul_f32_e32 v67, v67, v91
	v_mul_f32_e32 v72, v72, v132
	v_add_f32_e32 v91, v73, v73
	v_mul_f32_e32 v66, v66, v89
	v_add_f32_e32 v89, v72, v72
	v_add_f32_e32 v69, v69, v29
	v_mul_f32_e32 v91, 0x3fb8aa3b, v91
	v_add_f32_e32 v68, v68, v28
	v_mul_f32_e32 v89, 0x3fb8aa3b, v89
	v_mul_f32_e32 v69, 0xbfb8aa3b, v69
	v_exp_f32_e32 v91, v91
	v_add_f32_e32 v62, v62, v46
	v_mul_f32_e32 v68, 0xbfb8aa3b, v68
	v_exp_f32_e32 v89, v89
	v_exp_f32_e32 v69, v69
	v_mul_f32_e32 v62, 0xbfb8aa3b, v62
	v_exp_f32_e32 v68, v68
	v_exp_f32_e32 v62, v62
	v_sub_f32_e32 v91, 1.0, v91
	v_sub_f32_e32 v89, 1.0, v89
	v_add_f32_e32 v69, 1.0, v69
	v_max_f32_e32 v91, 0, v91
	v_add_f32_e32 v68, 1.0, v68
	v_max_f32_e32 v89, 0, v89
	v_rcp_f32_e32 v69, v69
	v_sqrt_f32_e32 v91, v91
	v_add_f32_e32 v62, 1.0, v62
	v_rcp_f32_e32 v68, v68
	v_sqrt_f32_e32 v89, v89
	v_rcp_f32_e32 v62, v62
	v_and_b32_e32 v86, 0xffff0000, v86
	v_mul_f32_e32 v67, v67, v86
	v_lshlrev_b32_e32 v90, 16, v87
	v_and_b32_e32 v87, 0xffff0000, v87
	v_mul_f32_e32 v69, v69, v91
	v_mul_f32_e32 v66, 0x42000000, v66
	v_mul_f32_e32 v67, 0x42000000, v67
	v_mul_f32_e32 v68, v68, v89
	v_mul_f32_e32 v69, v69, v87
	v_med3_f32 v66, v66, s29, v231
	v_med3_f32 v67, v67, s29, v231
	v_mov_b32_e32 v89, 0
	v_mul_f32_e32 v62, v62, v144
	v_cvt_pk_fp8_f32 v89, v66, v67
	v_mul_f32_e32 v66, 0x42000000, v69
	v_add_f32_e32 v69, v62, v62
	v_add_f32_e32 v63, v63, v47
	v_add_f32_e32 v58, v58, v42
	v_mul_f32_e32 v69, 0x3fb8aa3b, v69
	v_mul_f32_e32 v63, 0xbfb8aa3b, v63
	v_mul_f32_e32 v58, 0xbfb8aa3b, v58
	v_exp_f32_e32 v69, v69
	v_exp_f32_e32 v63, v63
	v_exp_f32_e32 v58, v58
	v_add_f32_e32 v59, v59, v43
	v_sub_f32_e32 v69, 1.0, v69
	v_add_f32_e32 v63, 1.0, v63
	v_add_f32_e32 v58, 1.0, v58
	v_max_f32_e32 v69, 0, v69
	v_rcp_f32_e32 v63, v63
	v_rcp_f32_e32 v58, v58
	v_sqrt_f32_e32 v69, v69
	v_add_f32_e32 v64, v64, v48
	v_mul_f32_e32 v63, v63, v145
	v_mul_f32_e32 v59, 0xbfb8aa3b, v59
	v_mul_f32_e32 v58, v58, v69
	v_add_f32_e32 v69, v63, v63
	v_mul_f32_e32 v69, 0x3fb8aa3b, v69
	v_exp_f32_e32 v69, v69
	v_mul_f32_e32 v64, 0xbfb8aa3b, v64
	v_add_f32_e32 v65, v65, v49
	v_exp_f32_e32 v59, v59
	v_exp_f32_e32 v64, v64
	v_mul_f32_e32 v65, 0xbfb8aa3b, v65
	v_exp_f32_e32 v65, v65
	v_sub_f32_e32 v69, 1.0, v69
	v_add_f32_e32 v60, v60, v44
	v_add_f32_e32 v59, 1.0, v59
	v_max_f32_e32 v69, 0, v69
	v_add_f32_e32 v64, 1.0, v64
	v_mul_f32_e32 v60, 0xbfb8aa3b, v60
	v_mul_f32_e32 v68, v68, v90
	v_rcp_f32_e32 v59, v59
	v_sqrt_f32_e32 v69, v69
	v_exp_f32_e32 v60, v60
	v_rcp_f32_e32 v64, v64
	v_add_f32_e32 v65, 1.0, v65
	v_mul_f32_e32 v68, 0x42000000, v68
	v_rcp_f32_e32 v65, v65
	v_med3_f32 v67, v68, s29, v231
	v_med3_f32 v66, v66, s29, v231
	v_cvt_pk_fp8_f32 v89, v67, v66 op_sel:[0,0,1]
	v_lshlrev_b32_e32 v66, 16, v74
	v_mul_f32_e32 v66, v58, v66
	v_mul_f32_e32 v58, v59, v69
	v_add_f32_e32 v59, 1.0, v60
	v_mul_f32_e32 v60, v64, v142
	v_add_f32_e32 v64, v60, v60
	v_mul_f32_e32 v65, v65, v143
	v_mul_f32_e32 v64, 0x3fb8aa3b, v64
	v_add_f32_e32 v69, v65, v65
	v_exp_f32_e32 v64, v64
	v_add_f32_e32 v61, v61, v45
	v_mul_f32_e32 v69, 0x3fb8aa3b, v69
	v_mul_f32_e32 v61, 0xbfb8aa3b, v61
	v_exp_f32_e32 v69, v69
	v_exp_f32_e32 v61, v61
	v_add_f32_e32 v54, v54, v30
	v_mul_f32_e32 v54, 0xbfb8aa3b, v54
	v_sub_f32_e32 v64, 1.0, v64
	v_exp_f32_e32 v54, v54
	v_max_f32_e32 v64, 0, v64
	v_sub_f32_e32 v69, 1.0, v69
	v_rcp_f32_e32 v59, v59
	v_sqrt_f32_e32 v64, v64
	v_add_f32_e32 v61, 1.0, v61
	v_max_f32_e32 v69, 0, v69
	v_rcp_f32_e32 v61, v61
	v_sqrt_f32_e32 v69, v69
	v_add_f32_e32 v54, 1.0, v54
	v_and_b32_e32 v67, 0xffff0000, v74
	v_rcp_f32_e32 v54, v54
	v_lshlrev_b32_e32 v68, 16, v75
	v_mul_f32_e32 v67, v58, v67
	v_mul_f32_e32 v58, v59, v64
	v_cvt_pk_bf16_f32 v86, v70, v71
	v_and_b32_e32 v70, 0xffff0000, v75
	v_mul_f32_e32 v64, v58, v68
	v_mul_f32_e32 v58, v61, v69
	v_mul_f32_e32 v61, v58, v70
	v_cvt_pk_bf16_f32 v58, v62, v63
	v_cvt_pk_bf16_f32 v59, v60, v65
	v_mul_f32_e32 v60, 0x42000000, v66
	v_mul_f32_e32 v62, 0x42000000, v67
	v_mul_f32_e32 v63, 0x42000000, v64
	v_med3_f32 v60, v60, s29, v231
	v_med3_f32 v64, v62, s29, v231
	v_mov_b32_e32 v62, 0
	v_mul_f32_e32 v54, v54, v130
	v_cvt_pk_fp8_f32 v62, v60, v64
	v_add_f32_e32 v64, v54, v54
	v_add_f32_e32 v55, v55, v31
	v_add_f32_e32 v50, v50, v26
	v_mul_f32_e32 v64, 0x3fb8aa3b, v64
	v_mul_f32_e32 v55, 0xbfb8aa3b, v55
	v_mul_f32_e32 v50, 0xbfb8aa3b, v50
	v_exp_f32_e32 v64, v64
	v_exp_f32_e32 v55, v55
	v_exp_f32_e32 v50, v50
	v_add_f32_e32 v56, v56, v32
	v_sub_f32_e32 v64, 1.0, v64
	v_add_f32_e32 v55, 1.0, v55
	v_add_f32_e32 v50, 1.0, v50
	v_max_f32_e32 v64, 0, v64
	v_rcp_f32_e32 v55, v55
	v_rcp_f32_e32 v50, v50
	v_sqrt_f32_e32 v64, v64
	v_mul_f32_e32 v56, 0xbfb8aa3b, v56
	v_mul_f32_e32 v55, v55, v131
	v_exp_f32_e32 v56, v56
	v_mul_f32_e32 v50, v50, v64
	v_add_f32_e32 v64, v55, v55
	v_add_f32_e32 v57, v57, v33
	v_add_f32_e32 v51, v51, v27
	v_mul_f32_e32 v64, 0x3fb8aa3b, v64
	v_mul_f32_e32 v57, 0xbfb8aa3b, v57
	v_mul_f32_e32 v51, 0xbfb8aa3b, v51
	v_exp_f32_e32 v64, v64
	v_exp_f32_e32 v57, v57
	v_exp_f32_e32 v51, v51
	v_add_f32_e32 v56, 1.0, v56
	v_rcp_f32_e32 v56, v56
	v_sub_f32_e32 v64, 1.0, v64
	v_add_f32_e32 v57, 1.0, v57
	v_mul_f32_e32 v60, 0x42000000, v61
	v_add_f32_e32 v51, 1.0, v51
	v_max_f32_e32 v64, 0, v64
	v_rcp_f32_e32 v57, v57
	v_med3_f32 v61, v63, s29, v231
	v_med3_f32 v60, v60, s29, v231
	v_rcp_f32_e32 v51, v51
	v_sqrt_f32_e32 v64, v64
	v_cvt_pk_fp8_f32 v62, v61, v60 op_sel:[0,0,1]
	v_lshlrev_b32_e32 v60, 16, v76
	v_mul_f32_e32 v56, v56, v132
	v_mul_f32_e32 v50, v50, v60
	v_add_f32_e32 v60, v56, v56
	v_add_f32_e32 v52, v52, v28
	v_mul_f32_e32 v60, 0x3fb8aa3b, v60
	v_mul_f32_e32 v57, v57, v133
	v_mul_f32_e32 v52, 0xbfb8aa3b, v52
	v_mul_f32_e32 v51, v51, v64
	v_exp_f32_e32 v60, v60
	v_add_f32_e32 v64, v57, v57
	v_exp_f32_e32 v52, v52
	v_add_f32_e32 v53, v53, v29
	v_mul_f32_e32 v64, 0x3fb8aa3b, v64
	v_mul_f32_e32 v53, 0xbfb8aa3b, v53
	v_exp_f32_e32 v64, v64
	v_exp_f32_e32 v53, v53
	v_sub_f32_e32 v60, 1.0, v60
	v_add_f32_e32 v52, 1.0, v52
	v_max_f32_e32 v60, 0, v60
	v_rcp_f32_e32 v52, v52
	v_sqrt_f32_e32 v60, v60
	v_sub_f32_e32 v64, 1.0, v64
	v_add_f32_e32 v53, 1.0, v53
	v_max_f32_e32 v64, 0, v64
	v_and_b32_e32 v61, 0xffff0000, v76
	v_rcp_f32_e32 v53, v53
	v_sqrt_f32_e32 v64, v64
	v_mul_f32_e32 v51, v51, v61
	v_lshlrev_b32_e32 v63, 16, v77
	v_mul_f32_e32 v52, v52, v60
	v_mul_f32_e32 v50, 0x42000000, v50
	v_mul_f32_e32 v51, 0x42000000, v51
	v_mul_f32_e32 v52, v52, v63
	v_med3_f32 v50, v50, s29, v231
	v_med3_f32 v51, v51, s29, v231
	v_mov_b32_e32 v63, 0
	v_and_b32_e32 v65, 0xffff0000, v77
	v_mul_f32_e32 v53, v53, v64
	v_cvt_pk_fp8_f32 v63, v50, v51
	v_mul_f32_e32 v53, v53, v65
	v_mul_f32_e32 v52, 0x42000000, v52
	v_mul_f32_e32 v50, 0x42000000, v53
	v_med3_f32 v51, v52, s29, v231
	v_med3_f32 v50, v50, s29, v231
	v_cvt_pk_fp8_f32 v63, v51, v50 op_sel:[0,0,1]
	v_add_co_u32_e32 v50, vcc, s84, v80
	v_cvt_pk_bf16_f32 v85, v92, v93
	v_cvt_pk_bf16_f32 v87, v72, v73
	v_cvt_pk_bf16_f32 v60, v54, v55
	v_cvt_pk_bf16_f32 v61, v56, v57
	v_addc_co_u32_e32 v51, vcc, 0, v81, vcc
	global_store_dwordx4 v[80:81], v[84:87], off
	global_store_dwordx2 v[78:79], v[88:89], off
	global_store_dwordx4 v[50:51], v[58:61], off
	v_add_co_u32_e32 v50, vcc, s93, v78
	s_nop 1
	v_addc_co_u32_e32 v51, vcc, 0, v79, vcc
	global_store_dwordx2 v[50:51], v[62:63], off
	v_add_co_u32_e32 v50, vcc, s92, v82
	v_add_f32_e32 v38, v38, v46
	s_nop 0
	v_addc_co_u32_e32 v51, vcc, 0, v83, vcc
	global_load_dwordx4 v[54:57], v[50:51], off
	v_mul_f32_e32 v38, 0xbfb8aa3b, v38
	v_exp_f32_e32 v38, v38
	v_add_f32_e32 v34, v34, v42
	v_mul_f32_e32 v34, 0xbfb8aa3b, v34
	v_exp_f32_e32 v34, v34
	v_add_f32_e32 v38, 1.0, v38
	v_rcp_f32_e32 v38, v38
	v_add_f32_e32 v39, v39, v47
	v_add_f32_e32 v34, 1.0, v34
	v_mul_f32_e32 v39, 0xbfb8aa3b, v39
	v_exp_f32_e32 v39, v39
	v_add_f32_e32 v35, v35, v43
	v_mul_f32_e32 v35, 0xbfb8aa3b, v35
	v_exp_f32_e32 v35, v35
	v_add_f32_e32 v39, 1.0, v39
	v_rcp_f32_e32 v39, v39
	v_add_f32_e32 v36, v36, v44
	v_add_f32_e32 v35, 1.0, v35
	v_rcp_f32_e32 v35, v35
	v_mul_f32_e32 v39, v39, v145
	v_mul_f32_e32 v36, 0xbfb8aa3b, v36
	v_exp_f32_e32 v36, v36
	v_add_co_u32_e32 v50, vcc, s89, v82
	v_add_f32_e32 v22, v22, v30
	v_add_f32_e32 v36, 1.0, v36
	v_rcp_f32_e32 v36, v36
	v_addc_co_u32_e32 v51, vcc, 0, v83, vcc
	global_load_dwordx4 v[50:53], v[50:51], off
	v_add_f32_e32 v37, v37, v45
	v_mul_f32_e32 v22, 0xbfb8aa3b, v22
	v_mul_f32_e32 v37, 0xbfb8aa3b, v37
	v_exp_f32_e32 v22, v22
	v_exp_f32_e32 v37, v37
	v_add_f32_e32 v18, v18, v26
	v_add_f32_e32 v23, v23, v31
	v_add_f32_e32 v22, 1.0, v22
	v_add_f32_e32 v37, 1.0, v37
	v_rcp_f32_e32 v22, v22
	v_rcp_f32_e32 v37, v37
	v_mul_f32_e32 v18, 0xbfb8aa3b, v18
	v_mul_f32_e32 v23, 0xbfb8aa3b, v23
	v_mul_f32_e32 v22, v22, v130
	v_exp_f32_e32 v18, v18
	v_exp_f32_e32 v23, v23
	v_add_f32_e32 v24, v24, v32
	v_add_f32_e32 v19, v19, v27
	v_add_f32_e32 v18, 1.0, v18
	v_add_f32_e32 v23, 1.0, v23
	v_rcp_f32_e32 v18, v18
	v_rcp_f32_e32 v23, v23
	v_mul_f32_e32 v24, 0xbfb8aa3b, v24
	v_mul_f32_e32 v19, 0xbfb8aa3b, v19
	v_exp_f32_e32 v24, v24
	v_mul_f32_e32 v23, v23, v131
	v_exp_f32_e32 v19, v19
	v_add_f32_e32 v25, v25, v33
	v_add_f32_e32 v24, 1.0, v24
	v_rcp_f32_e32 v24, v24
	v_add_f32_e32 v19, 1.0, v19
	v_rcp_f32_e32 v19, v19
	v_add_f32_e32 v20, v20, v28
	v_mul_f32_e32 v24, v24, v132
	v_mul_f32_e32 v25, 0xbfb8aa3b, v25
	v_mul_f32_e32 v20, 0xbfb8aa3b, v20
	v_exp_f32_e32 v25, v25
	v_exp_f32_e32 v20, v20
	v_add_f32_e32 v14, v14, v46
	v_add_f32_e32 v21, v21, v29
	v_add_f32_e32 v25, 1.0, v25
	v_add_f32_e32 v20, 1.0, v20
	v_rcp_f32_e32 v25, v25
	v_rcp_f32_e32 v20, v20
	v_mul_f32_e32 v14, 0xbfb8aa3b, v14
	v_mul_f32_e32 v21, 0xbfb8aa3b, v21
	v_mul_f32_e32 v25, v25, v133
	v_exp_f32_e32 v14, v14
	v_exp_f32_e32 v21, v21
	s_waitcnt vmcnt(0) lgkmcnt(0)
	v_lshlrev_b32_e32 v58, 16, v54
	v_and_b32_e32 v59, 0xffff0000, v54
	v_lshlrev_b32_e32 v60, 16, v55
	v_and_b32_e32 v54, 0xffff0000, v55
	v_rcp_f32_e32 v55, v34
	v_mul_f32_e32 v34, v38, v144
	v_add_f32_e32 v38, v34, v34
	v_mul_f32_e32 v38, 0x3fb8aa3b, v38
	v_exp_f32_e32 v38, v38
	v_cvt_pk_bf16_f32 v34, v34, v39
	v_add_f32_e32 v14, 1.0, v14
	v_add_f32_e32 v21, 1.0, v21
	v_sub_f32_e32 v38, 1.0, v38
	v_max_f32_e32 v38, 0, v38
	v_sqrt_f32_e32 v38, v38
	v_rcp_f32_e32 v14, v14
	v_rcp_f32_e32 v21, v21
	v_add_f32_e32 v10, v10, v42
	v_mul_f32_e32 v38, v55, v38
	v_add_f32_e32 v55, v39, v39
	v_mul_f32_e32 v55, 0x3fb8aa3b, v55
	v_exp_f32_e32 v55, v55
	v_mul_f32_e32 v38, v38, v58
	v_mul_f32_e32 v38, 0x42000000, v38
	v_mul_f32_e32 v14, v14, v144
	v_sub_f32_e32 v55, 1.0, v55
	v_max_f32_e32 v55, 0, v55
	v_sqrt_f32_e32 v55, v55
	v_mul_f32_e32 v10, 0xbfb8aa3b, v10
	v_exp_f32_e32 v10, v10
	v_add_f32_e32 v11, v11, v43
	v_mul_f32_e32 v35, v35, v55
	v_mul_f32_e32 v55, v35, v59
	v_add_f32_e32 v35, v40, v48
	v_mul_f32_e32 v35, 0xbfb8aa3b, v35
	v_exp_f32_e32 v35, v35
	v_mul_f32_e32 v39, 0x42000000, v55
	v_med3_f32 v39, v39, s29, v231
	v_add_f32_e32 v10, 1.0, v10
	v_add_f32_e32 v35, 1.0, v35
	v_rcp_f32_e32 v35, v35
	v_rcp_f32_e32 v10, v10
	v_mul_f32_e32 v11, 0xbfb8aa3b, v11
	v_exp_f32_e32 v11, v11
	v_mul_f32_e32 v35, v35, v142
	v_add_f32_e32 v40, v35, v35
	v_mul_f32_e32 v40, 0x3fb8aa3b, v40
	v_exp_f32_e32 v40, v40
	v_add_f32_e32 v11, 1.0, v11
	v_rcp_f32_e32 v11, v11
	v_add_f32_e32 v12, v12, v44
	v_sub_f32_e32 v40, 1.0, v40
	v_max_f32_e32 v40, 0, v40
	v_sqrt_f32_e32 v40, v40
	v_mul_f32_e32 v12, 0xbfb8aa3b, v12
	v_exp_f32_e32 v12, v12
	v_add_f32_e32 v6, v6, v30
	v_mul_f32_e32 v36, v36, v40
	v_add_f32_e32 v40, v41, v49
	v_mul_f32_e32 v40, 0xbfb8aa3b, v40
	v_exp_f32_e32 v40, v40
	v_mul_f32_e32 v36, v36, v60
	v_mul_f32_e32 v36, 0x42000000, v36
	v_med3_f32 v36, v36, s29, v231
	v_add_f32_e32 v40, 1.0, v40
	v_rcp_f32_e32 v40, v40
	v_add_f32_e32 v12, 1.0, v12
	v_rcp_f32_e32 v12, v12
	v_add_f32_e32 v13, v13, v45
	v_mul_f32_e32 v40, v40, v143
	v_add_f32_e32 v41, v40, v40
	v_mul_f32_e32 v41, 0x3fb8aa3b, v41
	v_exp_f32_e32 v41, v41
	v_cvt_pk_bf16_f32 v35, v35, v40
	v_med3_f32 v40, v38, s29, v231
	v_mov_b32_e32 v38, 0
	v_sub_f32_e32 v41, 1.0, v41
	v_max_f32_e32 v41, 0, v41
	v_sqrt_f32_e32 v41, v41
	v_cvt_pk_fp8_f32 v38, v40, v39
	v_lshlrev_b32_e32 v39, 16, v57
	v_and_b32_e32 v40, 0xffff0000, v57
	v_mul_f32_e32 v37, v37, v41
	v_add_f32_e32 v41, v22, v22
	v_mul_f32_e32 v41, 0x3fb8aa3b, v41
	v_exp_f32_e32 v41, v41
	v_mul_f32_e32 v37, v37, v54
	v_mul_f32_e32 v37, 0x42000000, v37
	v_med3_f32 v37, v37, s29, v231
	v_sub_f32_e32 v41, 1.0, v41
	v_max_f32_e32 v41, 0, v41
	v_sqrt_f32_e32 v41, v41
	v_cvt_pk_fp8_f32 v38, v36, v37 op_sel:[0,0,1]
	v_lshlrev_b32_e32 v36, 16, v56
	v_and_b32_e32 v37, 0xffff0000, v56
	v_mul_f32_e32 v18, v18, v41
	v_mul_f32_e32 v18, v18, v36
	v_add_f32_e32 v36, v23, v23
	v_mul_f32_e32 v36, 0x3fb8aa3b, v36
	v_exp_f32_e32 v36, v36
	v_mul_f32_e32 v18, 0x42000000, v18
	v_med3_f32 v18, v18, s29, v231
	v_mul_f32_e32 v6, 0xbfb8aa3b, v6
	v_sub_f32_e32 v36, 1.0, v36
	v_max_f32_e32 v36, 0, v36
	v_sqrt_f32_e32 v36, v36
	v_mul_f32_e32 v13, 0xbfb8aa3b, v13
	v_exp_f32_e32 v6, v6
	v_exp_f32_e32 v13, v13
	v_mul_f32_e32 v19, v19, v36
	v_add_f32_e32 v36, v24, v24
	v_mul_f32_e32 v36, 0x3fb8aa3b, v36
	v_exp_f32_e32 v36, v36
	v_mul_f32_e32 v19, v19, v37
	v_mul_f32_e32 v19, 0x42000000, v19
	v_med3_f32 v19, v19, s29, v231
	v_sub_f32_e32 v36, 1.0, v36
	v_max_f32_e32 v36, 0, v36
	v_sqrt_f32_e32 v36, v36
	v_cvt_pk_bf16_f32 v37, v24, v25
	v_add_f32_e32 v6, 1.0, v6
	v_add_f32_e32 v13, 1.0, v13
	v_mul_f32_e32 v20, v20, v36
	v_add_f32_e32 v36, v25, v25
	v_mul_f32_e32 v36, 0x3fb8aa3b, v36
	v_exp_f32_e32 v36, v36
	v_mul_f32_e32 v20, v20, v39
	v_mov_b32_e32 v39, 0
	v_cvt_pk_fp8_f32 v39, v18, v19
	v_sub_f32_e32 v36, 1.0, v36
	v_max_f32_e32 v36, 0, v36
	v_sqrt_f32_e32 v36, v36
	v_mul_f32_e32 v20, 0x42000000, v20
	v_med3_f32 v18, v20, s29, v231
	v_rcp_f32_e32 v6, v6
	v_mul_f32_e32 v21, v21, v36
	v_cvt_pk_bf16_f32 v36, v22, v23
	v_add_f32_e32 v22, v14, v14
	v_mul_f32_e32 v22, 0x3fb8aa3b, v22
	v_exp_f32_e32 v22, v22
	v_mul_f32_e32 v21, v21, v40
	v_mul_f32_e32 v21, 0x42000000, v21
	v_med3_f32 v19, v21, s29, v231
	v_sub_f32_e32 v22, 1.0, v22
	v_max_f32_e32 v22, 0, v22
	v_cvt_pk_fp8_f32 v39, v18, v19 op_sel:[0,0,1]
	v_add_co_u32_e32 v18, vcc, s92, v80
	v_sqrt_f32_e32 v22, v22
	s_nop 0
	v_addc_co_u32_e32 v19, vcc, 0, v81, vcc
	global_store_dwordx4 v[18:19], v[34:37], off
	v_add_co_u32_e32 v18, vcc, s84, v78
	v_mul_f32_e32 v10, v10, v22
	s_nop 0
	v_addc_co_u32_e32 v19, vcc, 0, v79, vcc
	global_store_dwordx2 v[18:19], v[38:39], off
	v_lshlrev_b32_e32 v18, 16, v50
	v_mul_f32_e32 v18, v10, v18
	v_add_f32_e32 v10, v15, v47
	v_mul_f32_e32 v10, 0xbfb8aa3b, v10
	v_exp_f32_e32 v10, v10
	v_and_b32_e32 v19, 0xffff0000, v50
	v_rcp_f32_e32 v13, v13
	v_mul_f32_e32 v6, v6, v130
	v_add_f32_e32 v10, 1.0, v10
	v_rcp_f32_e32 v10, v10
	v_add_f32_e32 v2, v2, v26
	v_add_f32_e32 v7, v7, v31
	v_mul_f32_e32 v2, 0xbfb8aa3b, v2
	v_mul_f32_e32 v10, v10, v145
	v_add_f32_e32 v15, v10, v10
	v_mul_f32_e32 v15, 0x3fb8aa3b, v15
	v_exp_f32_e32 v15, v15
	v_mul_f32_e32 v7, 0xbfb8aa3b, v7
	v_exp_f32_e32 v2, v2
	v_exp_f32_e32 v7, v7
	v_sub_f32_e32 v15, 1.0, v15
	v_max_f32_e32 v15, 0, v15
	v_sqrt_f32_e32 v15, v15
	v_cvt_pk_bf16_f32 v10, v14, v10
	v_mul_f32_e32 v14, 0x42000000, v18
	v_add_f32_e32 v2, 1.0, v2
	v_mul_f32_e32 v11, v11, v15
	v_mul_f32_e32 v15, v11, v19
	v_add_f32_e32 v11, v16, v48
	v_mul_f32_e32 v11, 0xbfb8aa3b, v11
	v_exp_f32_e32 v11, v11
	v_mul_f32_e32 v15, 0x42000000, v15
	v_med3_f32 v15, v15, s29, v231
	v_add_f32_e32 v7, 1.0, v7
	v_add_f32_e32 v11, 1.0, v11
	v_rcp_f32_e32 v11, v11
	v_lshlrev_b32_e32 v20, 16, v51
	v_and_b32_e32 v21, 0xffff0000, v51
	v_rcp_f32_e32 v2, v2
	v_mul_f32_e32 v11, v11, v142
	v_add_f32_e32 v16, v11, v11
	v_mul_f32_e32 v16, 0x3fb8aa3b, v16
	v_exp_f32_e32 v16, v16
	v_rcp_f32_e32 v7, v7
	v_add_f32_e32 v8, v8, v32
	v_add_f32_e32 v3, v3, v27
	v_sub_f32_e32 v16, 1.0, v16
	v_max_f32_e32 v16, 0, v16
	v_sqrt_f32_e32 v16, v16
	v_mul_f32_e32 v7, v7, v131
	v_mul_f32_e32 v8, 0xbfb8aa3b, v8
	v_mul_f32_e32 v3, 0xbfb8aa3b, v3
	v_mul_f32_e32 v12, v12, v16
	v_add_f32_e32 v16, v17, v49
	v_mul_f32_e32 v16, 0xbfb8aa3b, v16
	v_exp_f32_e32 v16, v16
	v_mul_f32_e32 v12, v12, v20
	v_mul_f32_e32 v12, 0x42000000, v12
	v_med3_f32 v12, v12, s29, v231
	v_add_f32_e32 v16, 1.0, v16
	v_rcp_f32_e32 v16, v16
	v_exp_f32_e32 v8, v8
	v_exp_f32_e32 v3, v3
	v_add_f32_e32 v9, v9, v33
	v_mul_f32_e32 v16, v16, v143
	v_add_f32_e32 v17, v16, v16
	v_mul_f32_e32 v17, 0x3fb8aa3b, v17
	v_exp_f32_e32 v17, v17
	v_cvt_pk_bf16_f32 v11, v11, v16
	v_med3_f32 v16, v14, s29, v231
	v_mov_b32_e32 v14, 0
	v_sub_f32_e32 v17, 1.0, v17
	v_max_f32_e32 v17, 0, v17
	v_sqrt_f32_e32 v17, v17
	v_cvt_pk_fp8_f32 v14, v16, v15
	v_add_f32_e32 v8, 1.0, v8
	v_add_f32_e32 v3, 1.0, v3
	v_mul_f32_e32 v13, v13, v17
	v_add_f32_e32 v17, v6, v6
	v_mul_f32_e32 v17, 0x3fb8aa3b, v17
	v_exp_f32_e32 v17, v17
	v_mul_f32_e32 v13, v13, v21
	v_mul_f32_e32 v13, 0x42000000, v13
	v_med3_f32 v13, v13, s29, v231
	v_sub_f32_e32 v17, 1.0, v17
	v_max_f32_e32 v17, 0, v17
	v_sqrt_f32_e32 v17, v17
	v_cvt_pk_fp8_f32 v14, v12, v13 op_sel:[0,0,1]
	v_lshlrev_b32_e32 v12, 16, v52
	v_rcp_f32_e32 v8, v8
	v_mul_f32_e32 v2, v2, v17
	v_mul_f32_e32 v2, v2, v12
	v_add_f32_e32 v12, v7, v7
	v_mul_f32_e32 v12, 0x3fb8aa3b, v12
	v_exp_f32_e32 v12, v12
	v_rcp_f32_e32 v3, v3
	v_mul_f32_e32 v8, v8, v132
	v_add_f32_e32 v4, v4, v28
	v_sub_f32_e32 v12, 1.0, v12
	v_max_f32_e32 v12, 0, v12
	v_sqrt_f32_e32 v12, v12
	v_mul_f32_e32 v9, 0xbfb8aa3b, v9
	v_mul_f32_e32 v4, 0xbfb8aa3b, v4
	v_exp_f32_e32 v9, v9
	v_mul_f32_e32 v3, v3, v12
	v_add_f32_e32 v12, v8, v8
	v_mul_f32_e32 v12, 0x3fb8aa3b, v12
	v_exp_f32_e32 v12, v12
	v_exp_f32_e32 v4, v4
	v_add_f32_e32 v9, 1.0, v9
	v_rcp_f32_e32 v9, v9
	v_sub_f32_e32 v12, 1.0, v12
	v_add_f32_e32 v4, 1.0, v4
	v_max_f32_e32 v12, 0, v12
	v_rcp_f32_e32 v4, v4
	v_sqrt_f32_e32 v12, v12
	v_mul_f32_e32 v9, v9, v133
	v_add_f32_e32 v5, v5, v29
	v_mul_f32_e32 v5, 0xbfb8aa3b, v5
	v_mul_f32_e32 v4, v4, v12
	v_add_f32_e32 v12, v9, v9
	v_mul_f32_e32 v12, 0x3fb8aa3b, v12
	v_exp_f32_e32 v12, v12
	v_exp_f32_e32 v5, v5
	v_and_b32_e32 v13, 0xffff0000, v52
	v_mul_f32_e32 v3, v3, v13
	v_sub_f32_e32 v12, 1.0, v12
	v_add_f32_e32 v5, 1.0, v5
	v_max_f32_e32 v12, 0, v12
	v_rcp_f32_e32 v5, v5
	v_sqrt_f32_e32 v12, v12
	v_lshlrev_b32_e32 v15, 16, v53
	v_mul_f32_e32 v2, 0x42000000, v2
	v_mul_f32_e32 v3, 0x42000000, v3
	v_mul_f32_e32 v4, v4, v15
	v_med3_f32 v2, v2, s29, v231
	v_med3_f32 v3, v3, s29, v231
	v_mov_b32_e32 v15, 0
	v_and_b32_e32 v16, 0xffff0000, v53
	v_mul_f32_e32 v5, v5, v12
	v_cvt_pk_fp8_f32 v15, v2, v3
	v_mul_f32_e32 v5, v5, v16
	v_mul_f32_e32 v4, 0x42000000, v4
	v_mul_f32_e32 v5, 0x42000000, v5
	v_med3_f32 v2, v4, s29, v231
	v_med3_f32 v3, v5, s29, v231
	v_cvt_pk_fp8_f32 v15, v2, v3 op_sel:[0,0,1]
	v_add_co_u32_e32 v2, vcc, 0x18000, v80
	v_cvt_pk_bf16_f32 v12, v6, v7
	v_cvt_pk_bf16_f32 v13, v8, v9
	v_addc_co_u32_e32 v3, vcc, 0, v81, vcc
	global_store_dwordx4 v[2:3], v[10:13], off
	v_add_co_u32_e32 v2, vcc, 0xc000, v78
	s_nop 1
	v_addc_co_u32_e32 v3, vcc, 0, v79, vcc
	global_store_dwordx2 v[2:3], v[14:15], off
	s_and_b64 vcc, exec, s[12:13]
	s_mov_b32 s82, s40
	s_mov_b32 s52, s42
	s_mov_b64 s[14:15], s[46:47]
	s_mov_b64 s[48:49], s[44:45]
	s_mov_b32 s94, s23
	s_cbranch_vccz .LBB0_1638
	s_waitcnt vmcnt(0)
	s_cmpk_gt_u32 s22, 0xff
	v_readlane_b32 s81, v253, 46
	v_readlane_b32 s80, v253, 45
	v_readlane_b32 s89, v253, 44
	s_cbranch_scc1 .LBB0_1649
	s_barrier

.LBB0_1786:
	ds_read_b128 v[130:133], v168
	ds_read_b128 v[134:137], v168 offset:1024
	ds_read_b128 v[138:141], v168 offset:2048
	ds_read_b128 v[142:145], v168 offset:3072
	s_add_u32 s0, s38, 0xfffc0080
	s_addc_u32 s1, s39, -1
	s_cmp_eq_u32 s66, 12
	s_cselect_b32 s43, s60, s1
	s_cselect_b32 s42, s61, s0
	s_cselect_b32 s41, s62, s65
	s_cselect_b32 s40, s63, s64
	s_mov_b32 m0, s50
	v_lshl_add_u64 v[164:165], s[38:39], 0, v[162:163]
	ds_read_b128 v[146:149], v169
	ds_read_b128 v[172:175], v169 offset:1024
	ds_read_b128 v[176:179], v169 offset:2048
	ds_read_b128 v[180:183], v169 offset:3072
	ds_read_b128 v[184:187], v169 offset:4096
	ds_read_b128 v[188:191], v169 offset:5120
	ds_read_b128 v[192:195], v169 offset:6144
	ds_read_b128 v[196:199], v169 offset:7168
	global_load_lds_dwordx4 v[164:165], off
	v_lshl_add_u64 v[164:165], s[38:39], 0, v[160:161]
	s_mov_b32 m0, s51
	s_nop 0
	global_load_lds_dwordx4 v[164:165], off
	s_waitcnt lgkmcnt(8)
	s_waitcnt vmcnt(10)
	s_barrier
	s_waitcnt lgkmcnt(0)
	v_mfma_f32_16x16x32_bf16 v[126:129], v[130:133], v[146:149], v[126:129]
	v_mfma_f32_16x16x32_bf16 v[122:125], v[138:141], v[146:149], v[122:125]
	v_mfma_f32_16x16x32_bf16 v[118:121], v[130:133], v[176:179], v[118:121]
	v_mfma_f32_16x16x32_bf16 v[110:113], v[138:141], v[176:179], v[110:113]
	v_mfma_f32_16x16x32_bf16 v[98:101], v[130:133], v[184:187], v[98:101]
	v_mfma_f32_16x16x32_bf16 v[90:93], v[138:141], v[184:187], v[90:93]
	v_mfma_f32_16x16x32_bf16 v[82:85], v[130:133], v[192:195], v[82:85]
	v_mfma_f32_16x16x32_bf16 v[74:77], v[138:141], v[192:195], v[74:77]
	v_mfma_f32_16x16x32_bf16 v[126:129], v[134:137], v[172:175], v[126:129]
	v_mfma_f32_16x16x32_bf16 v[122:125], v[142:145], v[172:175], v[122:125]
	v_mfma_f32_16x16x32_bf16 v[118:121], v[134:137], v[180:183], v[118:121]
	v_mfma_f32_16x16x32_bf16 v[110:113], v[142:145], v[180:183], v[110:113]
	v_mfma_f32_16x16x32_bf16 v[98:101], v[134:137], v[188:191], v[98:101]
	v_mfma_f32_16x16x32_bf16 v[90:93], v[142:145], v[188:191], v[90:93]
	v_mfma_f32_16x16x32_bf16 v[82:85], v[134:137], v[196:199], v[82:85]
	v_mfma_f32_16x16x32_bf16 v[74:77], v[142:145], v[196:199], v[74:77]
	s_barrier
	s_mov_b32 m0, s52
	v_lshl_add_u64 v[164:165], s[40:41], 0, v[156:157]
	ds_read_b128 v[200:203], v170
	ds_read_b128 v[204:207], v170 offset:1024
	ds_read_b128 v[208:211], v170 offset:2048
	ds_read_b128 v[212:215], v170 offset:3072
	global_load_lds_dwordx4 v[164:165], off
	v_lshl_add_u64 v[216:217], s[40:41], 0, v[152:153]
	s_mov_b32 m0, s53
	s_nop 0
	global_load_lds_dwordx4 v[216:217], off
	s_waitcnt vmcnt(10)
	s_barrier
	s_waitcnt lgkmcnt(0)
	v_mfma_f32_16x16x32_bf16 v[114:117], v[200:203], v[146:149], v[114:117]
	v_mfma_f32_16x16x32_bf16 v[106:109], v[208:211], v[146:149], v[106:109]
	v_mfma_f32_16x16x32_bf16 v[102:105], v[200:203], v[176:179], v[102:105]
	v_mfma_f32_16x16x32_bf16 v[94:97], v[208:211], v[176:179], v[94:97]
	v_mfma_f32_16x16x32_bf16 v[86:89], v[200:203], v[184:187], v[86:89]
	v_mfma_f32_16x16x32_bf16 v[78:81], v[208:211], v[184:187], v[78:81]
	v_mfma_f32_16x16x32_bf16 v[70:73], v[200:203], v[192:195], v[70:73]
	v_mfma_f32_16x16x32_bf16 v[66:69], v[208:211], v[192:195], v[66:69]
	v_mfma_f32_16x16x32_bf16 v[114:117], v[204:207], v[172:175], v[114:117]
	v_mfma_f32_16x16x32_bf16 v[106:109], v[212:215], v[172:175], v[106:109]
	v_mfma_f32_16x16x32_bf16 v[102:105], v[204:207], v[180:183], v[102:105]
	v_mfma_f32_16x16x32_bf16 v[94:97], v[212:215], v[180:183], v[94:97]
	v_mfma_f32_16x16x32_bf16 v[86:89], v[204:207], v[188:191], v[86:89]
	v_mfma_f32_16x16x32_bf16 v[78:81], v[212:215], v[188:191], v[78:81]
	v_mfma_f32_16x16x32_bf16 v[70:73], v[204:207], v[196:199], v[70:73]
	v_mfma_f32_16x16x32_bf16 v[66:69], v[212:215], v[196:199], v[66:69]
	s_mov_b32 m0, s8
	v_lshl_add_u64 v[218:219], s[42:43], 0, v[158:159]
	s_barrier
	ds_read_b128 v[146:149], v169 offset:16384
	ds_read_b128 v[172:175], v169 offset:17408
	ds_read_b128 v[176:179], v169 offset:18432
	ds_read_b128 v[180:183], v169 offset:19456
	ds_read_b128 v[184:187], v169 offset:20480
	ds_read_b128 v[188:191], v169 offset:21504
	ds_read_b128 v[192:195], v169 offset:22528
	ds_read_b128 v[196:199], v169 offset:23552
	global_load_lds_dwordx4 v[218:219], off
	v_lshl_add_u64 v[220:221], s[42:43], 0, v[154:155]
	s_mov_b32 m0, s9
	s_nop 0
	global_load_lds_dwordx4 v[220:221], off
	s_waitcnt vmcnt(10)
	s_barrier
	s_waitcnt lgkmcnt(0)
	v_mfma_f32_16x16x32_bf16 v[62:65], v[130:133], v[146:149], v[62:65]
	v_mfma_f32_16x16x32_bf16 v[58:61], v[138:141], v[146:149], v[58:61]
	v_mfma_f32_16x16x32_bf16 v[50:53], v[130:133], v[176:179], v[50:53]
	v_mfma_f32_16x16x32_bf16 v[42:45], v[138:141], v[176:179], v[42:45]
	v_mfma_f32_16x16x32_bf16 v[34:37], v[130:133], v[184:187], v[34:37]
	v_mfma_f32_16x16x32_bf16 v[26:29], v[138:141], v[184:187], v[26:29]
	v_mfma_f32_16x16x32_bf16 v[18:21], v[130:133], v[192:195], v[18:21]
	v_mfma_f32_16x16x32_bf16 v[10:13], v[138:141], v[192:195], v[10:13]
	v_mfma_f32_16x16x32_bf16 v[62:65], v[134:137], v[172:175], v[62:65]
	v_mfma_f32_16x16x32_bf16 v[58:61], v[142:145], v[172:175], v[58:61]
	v_mfma_f32_16x16x32_bf16 v[50:53], v[134:137], v[180:183], v[50:53]
	v_mfma_f32_16x16x32_bf16 v[42:45], v[142:145], v[180:183], v[42:45]
	v_mfma_f32_16x16x32_bf16 v[34:37], v[134:137], v[188:191], v[34:37]
	v_mfma_f32_16x16x32_bf16 v[26:29], v[142:145], v[188:191], v[26:29]
	v_mfma_f32_16x16x32_bf16 v[18:21], v[134:137], v[196:199], v[18:21]
	v_mfma_f32_16x16x32_bf16 v[10:13], v[142:145], v[196:199], v[10:13]
	s_barrier
	s_add_u32 s0, s40, 0x40000
	s_addc_u32 s1, s41, 0
	s_mov_b32 m0, s54
	v_lshl_add_u64 v[130:131], s[0:1], 0, v[156:157]
	global_load_lds_dwordx4 v[130:131], off
	v_lshl_add_u64 v[130:131], s[0:1], 0, v[152:153]
	s_add_i32 m0, s54, 0x2000
	s_nop 0
	global_load_lds_dwordx4 v[130:131], off
	s_waitcnt vmcnt(10)
	s_barrier
	v_mfma_f32_16x16x32_bf16 v[54:57], v[200:203], v[146:149], v[54:57]
	v_mfma_f32_16x16x32_bf16 v[46:49], v[208:211], v[146:149], v[46:49]
	v_mfma_f32_16x16x32_bf16 v[38:41], v[200:203], v[176:179], v[38:41]
	v_mfma_f32_16x16x32_bf16 v[30:33], v[208:211], v[176:179], v[30:33]
	v_mfma_f32_16x16x32_bf16 v[22:25], v[200:203], v[184:187], v[22:25]
	v_mfma_f32_16x16x32_bf16 v[14:17], v[208:211], v[184:187], v[14:17]
	v_mfma_f32_16x16x32_bf16 v[6:9], v[200:203], v[192:195], v[6:9]
	v_mfma_f32_16x16x32_bf16 v[2:5], v[208:211], v[192:195], v[2:5]
	v_mfma_f32_16x16x32_bf16 v[54:57], v[204:207], v[172:175], v[54:57]
	v_mfma_f32_16x16x32_bf16 v[46:49], v[212:215], v[172:175], v[46:49]
	v_mfma_f32_16x16x32_bf16 v[38:41], v[204:207], v[180:183], v[38:41]
	v_mfma_f32_16x16x32_bf16 v[30:33], v[212:215], v[180:183], v[30:33]
	v_mfma_f32_16x16x32_bf16 v[22:25], v[204:207], v[188:191], v[22:25]
	v_mfma_f32_16x16x32_bf16 v[14:17], v[212:215], v[188:191], v[14:17]
	v_mfma_f32_16x16x32_bf16 v[6:9], v[204:207], v[196:199], v[6:9]
	v_mfma_f32_16x16x32_bf16 v[2:5], v[212:215], v[196:199], v[2:5]
	s_add_i32 s67, 0, 0x18000
	v_add_u32_e32 v142, s67, v167
	s_barrier
	ds_read_b128 v[130:133], v142
	ds_read_b128 v[134:137], v142 offset:1024
	ds_read_b128 v[138:141], v142 offset:2048
	ds_read_b128 v[142:145], v142 offset:3072
	s_add_u32 s0, s42, 0x40000
	s_addc_u32 s1, s43, 0
	s_mov_b32 m0, s10
	v_lshl_add_u64 v[200:201], s[0:1], 0, v[158:159]
	ds_read_b128 v[146:149], v169 offset:32768
	ds_read_b128 v[172:175], v169 offset:33792
	ds_read_b128 v[176:179], v169 offset:34816
	ds_read_b128 v[180:183], v169 offset:35840
	ds_read_b128 v[184:187], v169 offset:36864
	ds_read_b128 v[188:191], v169 offset:37888
	ds_read_b128 v[192:195], v169 offset:38912
	ds_read_b128 v[196:199], v169 offset:39936
	global_load_lds_dwordx4 v[200:201], off
	v_lshl_add_u64 v[200:201], s[0:1], 0, v[154:155]
	s_mov_b32 m0, s11
	s_nop 0
	global_load_lds_dwordx4 v[200:201], off
	s_waitcnt lgkmcnt(8)
	s_waitcnt vmcnt(10)
	s_barrier
	s_waitcnt lgkmcnt(0)
	v_mfma_f32_16x16x32_bf16 v[126:129], v[130:133], v[146:149], v[126:129]
	v_mfma_f32_16x16x32_bf16 v[122:125], v[138:141], v[146:149], v[122:125]
	v_mfma_f32_16x16x32_bf16 v[118:121], v[130:133], v[176:179], v[118:121]
	v_mfma_f32_16x16x32_bf16 v[110:113], v[138:141], v[176:179], v[110:113]
	v_mfma_f32_16x16x32_bf16 v[98:101], v[130:133], v[184:187], v[98:101]
	v_mfma_f32_16x16x32_bf16 v[90:93], v[138:141], v[184:187], v[90:93]
	v_mfma_f32_16x16x32_bf16 v[82:85], v[130:133], v[192:195], v[82:85]
	v_mfma_f32_16x16x32_bf16 v[74:77], v[138:141], v[192:195], v[74:77]
	v_mfma_f32_16x16x32_bf16 v[126:129], v[134:137], v[172:175], v[126:129]
	v_mfma_f32_16x16x32_bf16 v[122:125], v[142:145], v[172:175], v[122:125]
	v_mfma_f32_16x16x32_bf16 v[118:121], v[134:137], v[180:183], v[118:121]
	v_mfma_f32_16x16x32_bf16 v[110:113], v[142:145], v[180:183], v[110:113]
	v_mfma_f32_16x16x32_bf16 v[98:101], v[134:137], v[188:191], v[98:101]
	v_mfma_f32_16x16x32_bf16 v[90:93], v[142:145], v[188:191], v[90:93]
	v_mfma_f32_16x16x32_bf16 v[82:85], v[134:137], v[196:199], v[82:85]
	v_mfma_f32_16x16x32_bf16 v[74:77], v[142:145], v[196:199], v[74:77]
	s_barrier
	s_add_i32 s42, 0, 0x1c000
	s_add_i32 s0, s67, s7
	v_add_u32_e32 v171, s42, v167
	v_lshl_add_u64 v[164:165], v[164:165], 0, s[28:29]
	s_mov_b32 m0, s0
	ds_read_b128 v[200:203], v171
	ds_read_b128 v[204:207], v171 offset:1024
	ds_read_b128 v[208:211], v171 offset:2048
	ds_read_b128 v[212:215], v171 offset:3072
	global_load_lds_dwordx4 v[164:165], off
	v_lshl_add_u64 v[164:165], v[216:217], 0, s[28:29]
	s_add_i32 m0, s0, 0x2000
	s_nop 0
	global_load_lds_dwordx4 v[164:165], off
	s_waitcnt vmcnt(10)
	s_barrier
	s_waitcnt lgkmcnt(0)
	v_mfma_f32_16x16x32_bf16 v[114:117], v[200:203], v[146:149], v[114:117]
	v_mfma_f32_16x16x32_bf16 v[106:109], v[208:211], v[146:149], v[106:109]
	v_mfma_f32_16x16x32_bf16 v[102:105], v[200:203], v[176:179], v[102:105]
	v_mfma_f32_16x16x32_bf16 v[94:97], v[208:211], v[176:179], v[94:97]
	v_mfma_f32_16x16x32_bf16 v[86:89], v[200:203], v[184:187], v[86:89]
	v_mfma_f32_16x16x32_bf16 v[78:81], v[208:211], v[184:187], v[78:81]
	v_mfma_f32_16x16x32_bf16 v[70:73], v[200:203], v[192:195], v[70:73]
	v_mfma_f32_16x16x32_bf16 v[66:69], v[208:211], v[192:195], v[66:69]
	v_mfma_f32_16x16x32_bf16 v[114:117], v[204:207], v[172:175], v[114:117]
	v_mfma_f32_16x16x32_bf16 v[106:109], v[212:215], v[172:175], v[106:109]
	v_mfma_f32_16x16x32_bf16 v[102:105], v[204:207], v[180:183], v[102:105]
	v_mfma_f32_16x16x32_bf16 v[94:97], v[212:215], v[180:183], v[94:97]
	v_mfma_f32_16x16x32_bf16 v[86:89], v[204:207], v[188:191], v[86:89]
	v_mfma_f32_16x16x32_bf16 v[78:81], v[212:215], v[188:191], v[78:81]
	v_mfma_f32_16x16x32_bf16 v[70:73], v[204:207], v[196:199], v[70:73]
	v_mfma_f32_16x16x32_bf16 v[66:69], v[212:215], v[196:199], v[66:69]
	s_mov_b32 m0, s48
	v_lshl_add_u64 v[164:165], v[218:219], 0, s[28:29]
	s_barrier
	ds_read_b128 v[146:149], v169 offset:49152
	ds_read_b128 v[172:175], v169 offset:50176
	ds_read_b128 v[176:179], v169 offset:51200
	ds_read_b128 v[180:183], v169 offset:52224
	ds_read_b128 v[184:187], v169 offset:53248
	ds_read_b128 v[188:191], v169 offset:54272
	ds_read_b128 v[192:195], v169 offset:55296
	ds_read_b128 v[196:199], v169 offset:56320
	global_load_lds_dwordx4 v[164:165], off
	v_lshl_add_u64 v[164:165], v[220:221], 0, s[28:29]
	s_mov_b32 m0, s49
	s_nop 0
	global_load_lds_dwordx4 v[164:165], off
	s_waitcnt vmcnt(10)
	s_barrier
	s_waitcnt lgkmcnt(0)
	v_mfma_f32_16x16x32_bf16 v[62:65], v[130:133], v[146:149], v[62:65]
	v_mfma_f32_16x16x32_bf16 v[58:61], v[138:141], v[146:149], v[58:61]
	v_mfma_f32_16x16x32_bf16 v[50:53], v[130:133], v[176:179], v[50:53]
	v_mfma_f32_16x16x32_bf16 v[42:45], v[138:141], v[176:179], v[42:45]
	v_mfma_f32_16x16x32_bf16 v[34:37], v[130:133], v[184:187], v[34:37]
	v_mfma_f32_16x16x32_bf16 v[26:29], v[138:141], v[184:187], v[26:29]
	v_mfma_f32_16x16x32_bf16 v[18:21], v[130:133], v[192:195], v[18:21]
	v_mfma_f32_16x16x32_bf16 v[10:13], v[138:141], v[192:195], v[10:13]
	v_mfma_f32_16x16x32_bf16 v[62:65], v[134:137], v[172:175], v[62:65]
	v_mfma_f32_16x16x32_bf16 v[58:61], v[142:145], v[172:175], v[58:61]
	v_mfma_f32_16x16x32_bf16 v[50:53], v[134:137], v[180:183], v[50:53]
	v_mfma_f32_16x16x32_bf16 v[42:45], v[142:145], v[180:183], v[42:45]
	v_mfma_f32_16x16x32_bf16 v[34:37], v[134:137], v[188:191], v[34:37]
	v_mfma_f32_16x16x32_bf16 v[26:29], v[142:145], v[188:191], v[26:29]
	v_mfma_f32_16x16x32_bf16 v[18:21], v[134:137], v[196:199], v[18:21]
	v_mfma_f32_16x16x32_bf16 v[10:13], v[142:145], v[196:199], v[10:13]
	s_barrier
	s_add_u32 s0, s40, 0x40080
	s_addc_u32 s1, s41, 0
	s_add_i32 s40, s42, s7
	v_lshl_add_u64 v[130:131], s[0:1], 0, v[156:157]
	s_mov_b32 m0, s40
	s_nop 0
	global_load_lds_dwordx4 v[130:131], off
	v_lshl_add_u64 v[130:131], s[0:1], 0, v[152:153]
	s_add_i32 m0, s40, 0x2000
	s_nop 0
	global_load_lds_dwordx4 v[130:131], off
	s_waitcnt vmcnt(10)
	s_barrier
	v_mfma_f32_16x16x32_bf16 v[54:57], v[200:203], v[146:149], v[54:57]
	v_mfma_f32_16x16x32_bf16 v[46:49], v[208:211], v[146:149], v[46:49]
	v_mfma_f32_16x16x32_bf16 v[38:41], v[200:203], v[176:179], v[38:41]
	v_mfma_f32_16x16x32_bf16 v[30:33], v[208:211], v[176:179], v[30:33]
	v_mfma_f32_16x16x32_bf16 v[22:25], v[200:203], v[184:187], v[22:25]
	v_mfma_f32_16x16x32_bf16 v[14:17], v[208:211], v[184:187], v[14:17]
	v_mfma_f32_16x16x32_bf16 v[6:9], v[200:203], v[192:195], v[6:9]
	v_mfma_f32_16x16x32_bf16 v[2:5], v[208:211], v[192:195], v[2:5]
	v_mfma_f32_16x16x32_bf16 v[54:57], v[204:207], v[172:175], v[54:57]
	v_mfma_f32_16x16x32_bf16 v[46:49], v[212:215], v[172:175], v[46:49]
	v_mfma_f32_16x16x32_bf16 v[38:41], v[204:207], v[180:183], v[38:41]
	v_mfma_f32_16x16x32_bf16 v[30:33], v[212:215], v[180:183], v[30:33]
	v_mfma_f32_16x16x32_bf16 v[22:25], v[204:207], v[188:191], v[22:25]
	v_mfma_f32_16x16x32_bf16 v[14:17], v[212:215], v[188:191], v[14:17]
	v_mfma_f32_16x16x32_bf16 v[6:9], v[204:207], v[196:199], v[6:9]
	v_mfma_f32_16x16x32_bf16 v[2:5], v[212:215], v[196:199], v[2:5]
	s_add_i32 s66, s66, 2
	s_add_u32 s64, s64, 0x100
	s_addc_u32 s65, s65, 0
	s_add_u32 s38, s38, 0x100
	s_addc_u32 s39, s39, 0
	s_cmp_gt_u32 s66, 13
	s_barrier
	s_cbranch_scc0 .LBB0_1786
	s_lshl_b32 s0, s58, 8
	v_mov_b32_e32 v130, v151
	v_mov_b32_e32 v131, v166
	s_or_b32 s0, s0, s45
	s_mov_b32 s58, s57
	v_lshl_add_u32 v164, v131, 3, s0
	s_lshl_b32 s0, s59, 8
	s_add_i32 s0, s0, s44
	v_add_u32_e32 v171, s0, v130
	v_mov_b32_e32 v130, v171
	v_ashrrev_i32_e32 v165, 31, v164
	v_ashrrev_i32_e32 v131, 31, v130
	v_lshlrev_b64 v[130:131], 10, v[130:131]
	v_lshl_add_u64 v[130:131], v[130:131], 0, v[164:165]
	v_lshlrev_b64 v[184:185], 1, v[130:131]
	v_lshl_add_u64 v[130:131], s[14:15], 0, v[184:185]
	global_load_dwordx4 v[172:175], v[130:131], off
	global_load_dwordx4 v[176:179], v[130:131], off offset:256
	v_add_co_u32_e32 v132, vcc, s47, v130
	s_mov_b32 s59, s56
	s_nop 0
	v_addc_co_u32_e32 v133, vcc, 0, v131, vcc
	global_load_dwordx4 v[180:183], v[132:133], off
	global_load_dwordx4 v[146:149], v[132:133], off offset:256
	v_add_co_u32_e32 v132, vcc, s31, v130
	s_waitcnt vmcnt(0) lgkmcnt(0)
	v_lshlrev_b32_e32 v186, 16, v172
	v_addc_co_u32_e32 v133, vcc, 0, v131, vcc
	global_load_dwordx4 v[142:145], v[132:133], off
	global_load_dwordx4 v[138:141], v[132:133], off offset:256
	v_add_co_u32_e32 v130, vcc, s46, v130
	v_and_b32_e32 v187, 0xffff0000, v172
	s_nop 0
	v_addc_co_u32_e32 v131, vcc, 0, v131, vcc
	global_load_dwordx4 v[134:137], v[130:131], off
	s_nop 0
	global_load_dwordx4 v[130:133], v[130:131], off offset:256
	v_lshlrev_b32_e32 v172, 16, v173
	v_and_b32_e32 v173, 0xffff0000, v173
	v_lshlrev_b32_e32 v188, 16, v174
	v_and_b32_e32 v189, 0xffff0000, v174
	v_lshlrev_b32_e32 v174, 16, v175
	v_and_b32_e32 v175, 0xffff0000, v175
	v_pk_fma_f32 v[128:129], v[172:173], s[30:31], v[128:129] op_sel_hi:[1,0,1]
	v_pk_fma_f32 v[126:127], v[186:187], s[30:31], v[126:127] op_sel_hi:[1,0,1]
	v_pk_fma_f32 v[172:173], v[174:175], s[30:31], v[124:125] op_sel_hi:[1,0,1]
	v_pk_fma_f32 v[122:123], v[188:189], s[30:31], v[122:123] op_sel_hi:[1,0,1]
	v_cvt_pk_bf16_f32 v124, v126, v127
	v_cvt_pk_bf16_f32 v125, v128, v129
	v_cvt_pk_bf16_f32 v126, v122, v123
	v_cvt_pk_bf16_f32 v127, v172, v173
	v_lshl_add_u64 v[122:123], s[20:21], 0, v[184:185]
	global_store_dwordx4 v[122:123], v[124:127], off
	v_lshlrev_b32_e32 v128, 16, v178
	v_and_b32_e32 v129, 0xffff0000, v178
	v_lshlrev_b32_e32 v124, 16, v176
	v_and_b32_e32 v125, 0xffff0000, v176
	v_lshlrev_b32_e32 v126, 16, v177
	v_and_b32_e32 v127, 0xffff0000, v177
	v_lshlrev_b32_e32 v172, 16, v179
	v_and_b32_e32 v173, 0xffff0000, v179
	v_pk_fma_f32 v[116:117], v[126:127], s[30:31], v[116:117] op_sel_hi:[1,0,1]
	v_pk_fma_f32 v[114:115], v[124:125], s[30:31], v[114:115] op_sel_hi:[1,0,1]
	v_pk_fma_f32 v[124:125], v[172:173], s[30:31], v[108:109] op_sel_hi:[1,0,1]
	v_pk_fma_f32 v[108:109], v[128:129], s[30:31], v[106:107] op_sel_hi:[1,0,1]
	v_cvt_pk_bf16_f32 v106, v114, v115
	v_cvt_pk_bf16_f32 v107, v116, v117
	v_cvt_pk_bf16_f32 v108, v108, v109
	v_cvt_pk_bf16_f32 v109, v124, v125
	global_store_dwordx4 v[122:123], v[106:109], off offset:256
	v_lshlrev_b32_e32 v114, 16, v182
	v_and_b32_e32 v115, 0xffff0000, v182
	v_lshlrev_b32_e32 v106, 16, v180
	v_and_b32_e32 v107, 0xffff0000, v180
	v_lshlrev_b32_e32 v108, 16, v181
	v_and_b32_e32 v109, 0xffff0000, v181
	v_lshlrev_b32_e32 v116, 16, v183
	v_and_b32_e32 v117, 0xffff0000, v183
	v_pk_fma_f32 v[108:109], v[108:109], s[30:31], v[120:121] op_sel_hi:[1,0,1]
	v_pk_fma_f32 v[106:107], v[106:107], s[30:31], v[118:119] op_sel_hi:[1,0,1]
	v_pk_fma_f32 v[110:111], v[114:115], s[30:31], v[110:111] op_sel_hi:[1,0,1]
	v_pk_fma_f32 v[112:113], v[116:117], s[30:31], v[112:113] op_sel_hi:[1,0,1]
	v_cvt_pk_bf16_f32 v106, v106, v107
	v_cvt_pk_bf16_f32 v107, v108, v109
	v_cvt_pk_bf16_f32 v108, v110, v111
	v_add_co_u32_e32 v110, vcc, s47, v122
	v_cvt_pk_bf16_f32 v109, v112, v113
	s_nop 0
	v_addc_co_u32_e32 v111, vcc, 0, v123, vcc
	global_store_dwordx4 v[110:111], v[106:109], off
	v_lshlrev_b32_e32 v112, 16, v148
	v_and_b32_e32 v113, 0xffff0000, v148
	v_lshlrev_b32_e32 v106, 16, v146
	v_and_b32_e32 v107, 0xffff0000, v146
	v_lshlrev_b32_e32 v108, 16, v147
	v_and_b32_e32 v109, 0xffff0000, v147
	v_lshlrev_b32_e32 v114, 16, v149
	v_and_b32_e32 v115, 0xffff0000, v149
	v_pk_fma_f32 v[104:105], v[108:109], s[30:31], v[104:105] op_sel_hi:[1,0,1]
	v_pk_fma_f32 v[102:103], v[106:107], s[30:31], v[102:103] op_sel_hi:[1,0,1]
	v_pk_fma_f32 v[106:107], v[114:115], s[30:31], v[96:97] op_sel_hi:[1,0,1]
	v_pk_fma_f32 v[96:97], v[112:113], s[30:31], v[94:95] op_sel_hi:[1,0,1]
	v_cvt_pk_bf16_f32 v94, v102, v103
	v_cvt_pk_bf16_f32 v95, v104, v105
	v_cvt_pk_bf16_f32 v96, v96, v97
	v_cvt_pk_bf16_f32 v97, v106, v107
	global_store_dwordx4 v[110:111], v[94:97], off offset:256
	s_waitcnt vmcnt(0) lgkmcnt(0)
	v_lshlrev_b32_e32 v102, 16, v144
	v_lshlrev_b32_e32 v94, 16, v142
	v_and_b32_e32 v95, 0xffff0000, v142
	v_lshlrev_b32_e32 v96, 16, v143
	v_and_b32_e32 v97, 0xffff0000, v143
	v_and_b32_e32 v103, 0xffff0000, v144
	v_lshlrev_b32_e32 v104, 16, v145
	v_and_b32_e32 v105, 0xffff0000, v145
	v_pk_fma_f32 v[94:95], v[94:95], s[30:31], v[98:99] op_sel_hi:[1,0,1]
	v_pk_fma_f32 v[96:97], v[96:97], s[30:31], v[100:101] op_sel_hi:[1,0,1]
	v_pk_fma_f32 v[98:99], v[104:105], s[30:31], v[92:93] op_sel_hi:[1,0,1]
	v_pk_fma_f32 v[92:93], v[102:103], s[30:31], v[90:91] op_sel_hi:[1,0,1]
	v_cvt_pk_bf16_f32 v90, v94, v95
	v_add_co_u32_e32 v94, vcc, s31, v122
	v_cvt_pk_bf16_f32 v91, v96, v97
	v_cvt_pk_bf16_f32 v92, v92, v93
	v_cvt_pk_bf16_f32 v93, v98, v99
	v_addc_co_u32_e32 v95, vcc, 0, v123, vcc
	global_store_dwordx4 v[94:95], v[90:93], off
	v_lshlrev_b32_e32 v96, 16, v140
	v_and_b32_e32 v97, 0xffff0000, v140
	v_lshlrev_b32_e32 v90, 16, v138
	v_and_b32_e32 v91, 0xffff0000, v138
	v_lshlrev_b32_e32 v92, 16, v139
	v_and_b32_e32 v93, 0xffff0000, v139
	v_lshlrev_b32_e32 v98, 16, v141
	v_and_b32_e32 v99, 0xffff0000, v141
	v_pk_fma_f32 v[88:89], v[92:93], s[30:31], v[88:89] op_sel_hi:[1,0,1]
	v_pk_fma_f32 v[86:87], v[90:91], s[30:31], v[86:87] op_sel_hi:[1,0,1]
	v_pk_fma_f32 v[90:91], v[98:99], s[30:31], v[80:81] op_sel_hi:[1,0,1]
	v_pk_fma_f32 v[80:81], v[96:97], s[30:31], v[78:79] op_sel_hi:[1,0,1]
	v_cvt_pk_bf16_f32 v78, v86, v87
	v_cvt_pk_bf16_f32 v79, v88, v89
	v_cvt_pk_bf16_f32 v80, v80, v81
	v_cvt_pk_bf16_f32 v81, v90, v91
	global_store_dwordx4 v[94:95], v[78:81], off offset:256
	v_lshlrev_b32_e32 v86, 16, v136
	v_and_b32_e32 v87, 0xffff0000, v136
	v_lshlrev_b32_e32 v78, 16, v134
	v_and_b32_e32 v79, 0xffff0000, v134
	v_lshlrev_b32_e32 v80, 16, v135
	v_and_b32_e32 v81, 0xffff0000, v135
	v_lshlrev_b32_e32 v88, 16, v137
	v_and_b32_e32 v89, 0xffff0000, v137
	v_pk_fma_f32 v[78:79], v[78:79], s[30:31], v[82:83] op_sel_hi:[1,0,1]
	v_pk_fma_f32 v[80:81], v[80:81], s[30:31], v[84:85] op_sel_hi:[1,0,1]
	v_pk_fma_f32 v[82:83], v[88:89], s[30:31], v[76:77] op_sel_hi:[1,0,1]
	v_pk_fma_f32 v[76:77], v[86:87], s[30:31], v[74:75] op_sel_hi:[1,0,1]
	v_cvt_pk_bf16_f32 v74, v78, v79
	v_add_co_u32_e32 v78, vcc, s46, v122
	v_cvt_pk_bf16_f32 v75, v80, v81
	v_cvt_pk_bf16_f32 v76, v76, v77
	v_cvt_pk_bf16_f32 v77, v82, v83
	v_addc_co_u32_e32 v79, vcc, 0, v123, vcc
	global_store_dwordx4 v[78:79], v[74:77], off
	v_lshlrev_b32_e32 v80, 16, v132
	v_and_b32_e32 v81, 0xffff0000, v132
	v_lshlrev_b32_e32 v74, 16, v130
	v_and_b32_e32 v75, 0xffff0000, v130
	v_lshlrev_b32_e32 v76, 16, v131
	v_and_b32_e32 v77, 0xffff0000, v131
	v_lshlrev_b32_e32 v82, 16, v133
	v_and_b32_e32 v83, 0xffff0000, v133
	v_pk_fma_f32 v[72:73], v[76:77], s[30:31], v[72:73] op_sel_hi:[1,0,1]
	v_pk_fma_f32 v[70:71], v[74:75], s[30:31], v[70:71] op_sel_hi:[1,0,1]
	v_pk_fma_f32 v[74:75], v[82:83], s[30:31], v[68:69] op_sel_hi:[1,0,1]
	v_pk_fma_f32 v[68:69], v[80:81], s[30:31], v[66:67] op_sel_hi:[1,0,1]
	v_cvt_pk_bf16_f32 v66, v70, v71
	v_cvt_pk_bf16_f32 v67, v72, v73
	v_cvt_pk_bf16_f32 v68, v68, v69
	v_cvt_pk_bf16_f32 v69, v74, v75
	global_store_dwordx4 v[78:79], v[66:69], off offset:256
	s_nop 1
	v_add_u32_e32 v66, 0x80, v171
	s_nop 0
	v_ashrrev_i32_e32 v67, 31, v66
	v_lshlrev_b64 v[66:67], 10, v[66:67]
	v_lshl_add_u64 v[66:67], v[66:67], 0, v[164:165]
	v_lshlrev_b64 v[98:99], 1, v[66:67]
	v_lshl_add_u64 v[90:91], s[14:15], 0, v[98:99]
	global_load_dwordx4 v[66:69], v[90:91], off
	global_load_dwordx4 v[70:73], v[90:91], off offset:256
	v_add_co_u32_e32 v78, vcc, s47, v90
	s_waitcnt vmcnt(0) lgkmcnt(0)
	v_lshlrev_b32_e32 v100, 16, v66
	v_addc_co_u32_e32 v79, vcc, 0, v91, vcc
	global_load_dwordx4 v[74:77], v[78:79], off
	s_nop 0
	global_load_dwordx4 v[78:81], v[78:79], off offset:256
	v_add_co_u32_e32 v86, vcc, s31, v90
	v_and_b32_e32 v101, 0xffff0000, v66
	s_nop 0
	v_addc_co_u32_e32 v87, vcc, 0, v91, vcc
	global_load_dwordx4 v[82:85], v[86:87], off
	s_nop 0
	global_load_dwordx4 v[86:89], v[86:87], off offset:256
	v_add_co_u32_e32 v94, vcc, s46, v90
	v_lshlrev_b32_e32 v66, 16, v67
	s_nop 0
	v_addc_co_u32_e32 v95, vcc, 0, v91, vcc
	global_load_dwordx4 v[90:93], v[94:95], off
	s_nop 0
	global_load_dwordx4 v[94:97], v[94:95], off offset:256
	v_and_b32_e32 v67, 0xffff0000, v67
	v_lshlrev_b32_e32 v102, 16, v68
	v_and_b32_e32 v103, 0xffff0000, v68
	v_lshlrev_b32_e32 v68, 16, v69
	v_and_b32_e32 v69, 0xffff0000, v69
	v_pk_fma_f32 v[64:65], v[66:67], s[30:31], v[64:65] op_sel_hi:[1,0,1]
	v_pk_fma_f32 v[62:63], v[100:101], s[30:31], v[62:63] op_sel_hi:[1,0,1]
	v_pk_fma_f32 v[66:67], v[68:69], s[30:31], v[60:61] op_sel_hi:[1,0,1]
	v_pk_fma_f32 v[60:61], v[102:103], s[30:31], v[58:59] op_sel_hi:[1,0,1]
	v_cvt_pk_bf16_f32 v58, v62, v63
	v_cvt_pk_bf16_f32 v59, v64, v65
	v_cvt_pk_bf16_f32 v60, v60, v61
	v_cvt_pk_bf16_f32 v61, v66, v67
	v_lshl_add_u64 v[62:63], s[20:21], 0, v[98:99]
	global_store_dwordx4 v[62:63], v[58:61], off
	v_lshlrev_b32_e32 v64, 16, v72
	v_and_b32_e32 v65, 0xffff0000, v72
	v_lshlrev_b32_e32 v58, 16, v70
	v_and_b32_e32 v59, 0xffff0000, v70
	v_lshlrev_b32_e32 v60, 16, v71
	v_and_b32_e32 v61, 0xffff0000, v71
	v_lshlrev_b32_e32 v66, 16, v73
	v_and_b32_e32 v67, 0xffff0000, v73
	v_pk_fma_f32 v[56:57], v[60:61], s[30:31], v[56:57] op_sel_hi:[1,0,1]
	v_pk_fma_f32 v[54:55], v[58:59], s[30:31], v[54:55] op_sel_hi:[1,0,1]
	v_pk_fma_f32 v[58:59], v[66:67], s[30:31], v[48:49] op_sel_hi:[1,0,1]
	v_pk_fma_f32 v[48:49], v[64:65], s[30:31], v[46:47] op_sel_hi:[1,0,1]
	v_cvt_pk_bf16_f32 v46, v54, v55
	v_cvt_pk_bf16_f32 v47, v56, v57
	v_cvt_pk_bf16_f32 v48, v48, v49
	v_cvt_pk_bf16_f32 v49, v58, v59
	global_store_dwordx4 v[62:63], v[46:49], off offset:256
	s_waitcnt vmcnt(0) lgkmcnt(0)
	v_lshlrev_b32_e32 v54, 16, v76
	v_lshlrev_b32_e32 v46, 16, v74
	v_and_b32_e32 v47, 0xffff0000, v74
	v_lshlrev_b32_e32 v48, 16, v75
	v_and_b32_e32 v49, 0xffff0000, v75
	v_and_b32_e32 v55, 0xffff0000, v76
	v_lshlrev_b32_e32 v56, 16, v77
	v_and_b32_e32 v57, 0xffff0000, v77
	v_pk_fma_f32 v[46:47], v[46:47], s[30:31], v[50:51] op_sel_hi:[1,0,1]
	v_pk_fma_f32 v[48:49], v[48:49], s[30:31], v[52:53] op_sel_hi:[1,0,1]
	v_pk_fma_f32 v[50:51], v[56:57], s[30:31], v[44:45] op_sel_hi:[1,0,1]
	v_pk_fma_f32 v[44:45], v[54:55], s[30:31], v[42:43] op_sel_hi:[1,0,1]
	v_cvt_pk_bf16_f32 v42, v46, v47
	v_add_co_u32_e32 v46, vcc, s47, v62
	v_cvt_pk_bf16_f32 v43, v48, v49
	v_cvt_pk_bf16_f32 v44, v44, v45
	v_cvt_pk_bf16_f32 v45, v50, v51
	v_addc_co_u32_e32 v47, vcc, 0, v63, vcc
	global_store_dwordx4 v[46:47], v[42:45], off
	v_lshlrev_b32_e32 v48, 16, v80
	v_and_b32_e32 v49, 0xffff0000, v80
	v_lshlrev_b32_e32 v42, 16, v78
	v_and_b32_e32 v43, 0xffff0000, v78
	v_lshlrev_b32_e32 v44, 16, v79
	v_and_b32_e32 v45, 0xffff0000, v79
	v_lshlrev_b32_e32 v50, 16, v81
	v_and_b32_e32 v51, 0xffff0000, v81
	v_pk_fma_f32 v[40:41], v[44:45], s[30:31], v[40:41] op_sel_hi:[1,0,1]
	v_pk_fma_f32 v[38:39], v[42:43], s[30:31], v[38:39] op_sel_hi:[1,0,1]
	v_pk_fma_f32 v[42:43], v[50:51], s[30:31], v[32:33] op_sel_hi:[1,0,1]
	v_pk_fma_f32 v[32:33], v[48:49], s[30:31], v[30:31] op_sel_hi:[1,0,1]
	v_cvt_pk_bf16_f32 v30, v38, v39
	v_cvt_pk_bf16_f32 v31, v40, v41
	v_cvt_pk_bf16_f32 v32, v32, v33
	v_cvt_pk_bf16_f32 v33, v42, v43
	global_store_dwordx4 v[46:47], v[30:33], off offset:256
	v_lshlrev_b32_e32 v38, 16, v84
	v_and_b32_e32 v39, 0xffff0000, v84
	v_lshlrev_b32_e32 v30, 16, v82
	v_and_b32_e32 v31, 0xffff0000, v82
	v_lshlrev_b32_e32 v32, 16, v83
	v_and_b32_e32 v33, 0xffff0000, v83
	v_lshlrev_b32_e32 v40, 16, v85
	v_and_b32_e32 v41, 0xffff0000, v85
	v_pk_fma_f32 v[30:31], v[30:31], s[30:31], v[34:35] op_sel_hi:[1,0,1]
	v_pk_fma_f32 v[32:33], v[32:33], s[30:31], v[36:37] op_sel_hi:[1,0,1]
	v_pk_fma_f32 v[34:35], v[40:41], s[30:31], v[28:29] op_sel_hi:[1,0,1]
	v_pk_fma_f32 v[28:29], v[38:39], s[30:31], v[26:27] op_sel_hi:[1,0,1]
	v_cvt_pk_bf16_f32 v26, v30, v31
	v_add_co_u32_e32 v30, vcc, s31, v62
	v_cvt_pk_bf16_f32 v27, v32, v33
	v_cvt_pk_bf16_f32 v28, v28, v29
	v_cvt_pk_bf16_f32 v29, v34, v35
	v_addc_co_u32_e32 v31, vcc, 0, v63, vcc
	global_store_dwordx4 v[30:31], v[26:29], off
	v_lshlrev_b32_e32 v32, 16, v88
	v_and_b32_e32 v33, 0xffff0000, v88
	v_lshlrev_b32_e32 v26, 16, v86
	v_and_b32_e32 v27, 0xffff0000, v86
	v_lshlrev_b32_e32 v28, 16, v87
	v_and_b32_e32 v29, 0xffff0000, v87
	v_lshlrev_b32_e32 v34, 16, v89
	v_and_b32_e32 v35, 0xffff0000, v89
	v_pk_fma_f32 v[24:25], v[28:29], s[30:31], v[24:25] op_sel_hi:[1,0,1]
	v_pk_fma_f32 v[22:23], v[26:27], s[30:31], v[22:23] op_sel_hi:[1,0,1]
	v_pk_fma_f32 v[26:27], v[34:35], s[30:31], v[16:17] op_sel_hi:[1,0,1]
	v_pk_fma_f32 v[16:17], v[32:33], s[30:31], v[14:15] op_sel_hi:[1,0,1]
	v_cvt_pk_bf16_f32 v14, v22, v23
	v_cvt_pk_bf16_f32 v15, v24, v25
	v_cvt_pk_bf16_f32 v16, v16, v17
	v_cvt_pk_bf16_f32 v17, v26, v27
	global_store_dwordx4 v[30:31], v[14:17], off offset:256
	v_lshlrev_b32_e32 v22, 16, v92
	v_and_b32_e32 v23, 0xffff0000, v92
	v_lshlrev_b32_e32 v14, 16, v90
	v_and_b32_e32 v15, 0xffff0000, v90
	v_lshlrev_b32_e32 v16, 16, v91
	v_and_b32_e32 v17, 0xffff0000, v91
	v_lshlrev_b32_e32 v24, 16, v93
	v_and_b32_e32 v25, 0xffff0000, v93
	v_pk_fma_f32 v[14:15], v[14:15], s[30:31], v[18:19] op_sel_hi:[1,0,1]
	v_pk_fma_f32 v[16:17], v[16:17], s[30:31], v[20:21] op_sel_hi:[1,0,1]
	v_pk_fma_f32 v[18:19], v[24:25], s[30:31], v[12:13] op_sel_hi:[1,0,1]
	v_pk_fma_f32 v[12:13], v[22:23], s[30:31], v[10:11] op_sel_hi:[1,0,1]
	v_cvt_pk_bf16_f32 v10, v14, v15
	v_add_co_u32_e32 v14, vcc, s46, v62
	v_cvt_pk_bf16_f32 v11, v16, v17
	v_cvt_pk_bf16_f32 v12, v12, v13
	v_cvt_pk_bf16_f32 v13, v18, v19
	v_addc_co_u32_e32 v15, vcc, 0, v63, vcc
	global_store_dwordx4 v[14:15], v[10:13], off
	v_lshlrev_b32_e32 v16, 16, v96
	v_and_b32_e32 v17, 0xffff0000, v96
	v_lshlrev_b32_e32 v10, 16, v94
	v_and_b32_e32 v11, 0xffff0000, v94
	v_lshlrev_b32_e32 v12, 16, v95
	v_and_b32_e32 v13, 0xffff0000, v95
	v_lshlrev_b32_e32 v18, 16, v97
	v_and_b32_e32 v19, 0xffff0000, v97
	v_pk_fma_f32 v[8:9], v[12:13], s[30:31], v[8:9] op_sel_hi:[1,0,1]
	v_pk_fma_f32 v[6:7], v[10:11], s[30:31], v[6:7] op_sel_hi:[1,0,1]
	v_pk_fma_f32 v[10:11], v[18:19], s[30:31], v[4:5] op_sel_hi:[1,0,1]
	v_pk_fma_f32 v[4:5], v[16:17], s[30:31], v[2:3] op_sel_hi:[1,0,1]
	v_cvt_pk_bf16_f32 v2, v6, v7
	v_cvt_pk_bf16_f32 v3, v8, v9
	v_cvt_pk_bf16_f32 v4, v4, v5
	v_cvt_pk_bf16_f32 v5, v10, v11
	s_and_b64 vcc, exec, s[34:35]
	global_store_dwordx4 v[14:15], v[2:5], off offset:256
	s_cbranch_vccz .LBB0_1785
	s_waitcnt vmcnt(0)
	s_cmpk_gt_u32 s4, 0xff
	s_cbranch_scc1 .LBB0_1790
	s_barrier

.LBB0_2041:
	s_add_u32 s14, s38, 0x100
	s_addc_u32 s15, s39, 0
	s_add_u32 s36, s35, s38
	s_addc_u32 s37, s55, s39
	s_cmpk_eq_i32 s38, 0x300
	s_cselect_b64 vcc, -1, 0
	s_and_b64 s[0:1], vcc, exec
	s_cselect_b32 s1, 0, s14
	s_cselect_b32 s0, 0, s15
	s_cselect_b32 s36, s31, s36
	s_cselect_b32 s37, s29, s37
	s_add_u32 s40, s18, s1
	s_addc_u32 s41, s19, s0
	s_add_i32 s1, 0, 0x10000
	v_add_u32_e32 v14, s1, v197
	ds_read_b128 v[2:5], v14
	ds_read_b128 v[6:9], v14 offset:1024
	ds_read_b128 v[10:13], v14 offset:2048
	ds_read_b128 v[14:17], v14 offset:3072
	v_cndmask_b32_e32 v162, v168, v171, vcc
	v_cndmask_b32_e32 v184, v170, v198, vcc
	v_cndmask_b32_e32 v175, v172, v199, vcc
	v_cndmask_b32_e32 v173, v174, v200, vcc
	v_lshl_add_u64 v[18:19], v[178:179], 0, s[38:39]
	s_add_i32 m0, s45, 0xc000
	ds_read_b128 v[202:205], v169
	ds_read_b128 v[206:209], v169 offset:1024
	ds_read_b128 v[210:213], v169 offset:2048
	ds_read_b128 v[214:217], v169 offset:3072
	ds_read_b128 v[218:221], v169 offset:4096
	ds_read_b128 v[222:225], v169 offset:5120
	ds_read_b128 v[226:229], v169 offset:6144
	ds_read_b128 v[230:233], v169 offset:7168
	global_load_lds_dwordx4 v[18:19], off
	v_lshl_add_u64 v[18:19], v[176:177], 0, s[38:39]
	s_add_i32 m0, s45, 0xe000
	s_nop 0
	global_load_lds_dwordx4 v[18:19], off
	s_waitcnt lgkmcnt(8)
	s_waitcnt vmcnt(10)
	s_barrier
	s_waitcnt lgkmcnt(0)
	v_mfma_scale_f32_16x16x128_f8f6f4 v[158:161], v[2:9], v[202:209], v[158:161], v188, v188 op_sel_hi:[0,0,0]
	v_mfma_scale_f32_16x16x128_f8f6f4 v[150:153], v[10:17], v[202:209], v[150:153], v188, v188 op_sel_hi:[0,0,0]
	v_mfma_scale_f32_16x16x128_f8f6f4 v[142:145], v[2:9], v[210:217], v[142:145], v188, v188 op_sel_hi:[0,0,0]
	v_mfma_scale_f32_16x16x128_f8f6f4 v[134:137], v[10:17], v[210:217], v[134:137], v188, v188 op_sel_hi:[0,0,0]
	v_mfma_scale_f32_16x16x128_f8f6f4 v[126:129], v[2:9], v[218:225], v[126:129], v188, v188 op_sel_hi:[0,0,0]
	v_mfma_scale_f32_16x16x128_f8f6f4 v[118:121], v[10:17], v[218:225], v[118:121], v188, v188 op_sel_hi:[0,0,0]
	v_mfma_scale_f32_16x16x128_f8f6f4 v[110:113], v[2:9], v[226:233], v[110:113], v188, v188 op_sel_hi:[0,0,0]
	v_mfma_scale_f32_16x16x128_f8f6f4 v[102:105], v[10:17], v[226:233], v[102:105], v188, v188 op_sel_hi:[0,0,0]
	s_barrier
	s_add_i32 s0, 0, 0x14000
	s_add_i32 s1, s1, s43
	v_add_u32_e32 v30, s0, v197
	v_lshl_add_u64 v[180:181], s[36:37], 0, v[164:165]
	s_mov_b32 m0, s1
	ds_read_b128 v[18:21], v30
	ds_read_b128 v[22:25], v30 offset:1024
	ds_read_b128 v[26:29], v30 offset:2048
	ds_read_b128 v[30:33], v30 offset:3072
	global_load_lds_dwordx4 v[180:181], off
	v_lshl_add_u64 v[182:183], s[36:37], 0, v[166:167]
	s_add_i32 m0, s1, 0x2000
	s_nop 0
	global_load_lds_dwordx4 v[182:183], off
	s_waitcnt vmcnt(10)
	s_barrier
	s_waitcnt lgkmcnt(0)
	v_mfma_scale_f32_16x16x128_f8f6f4 v[154:157], v[18:25], v[202:209], v[154:157], v188, v188 op_sel_hi:[0,0,0]
	v_mfma_scale_f32_16x16x128_f8f6f4 v[146:149], v[26:33], v[202:209], v[146:149], v188, v188 op_sel_hi:[0,0,0]
	v_mfma_scale_f32_16x16x128_f8f6f4 v[138:141], v[18:25], v[210:217], v[138:141], v188, v188 op_sel_hi:[0,0,0]
	v_mfma_scale_f32_16x16x128_f8f6f4 v[130:133], v[26:33], v[210:217], v[130:133], v188, v188 op_sel_hi:[0,0,0]
	v_mfma_scale_f32_16x16x128_f8f6f4 v[122:125], v[18:25], v[218:225], v[122:125], v188, v188 op_sel_hi:[0,0,0]
	v_mfma_scale_f32_16x16x128_f8f6f4 v[114:117], v[26:33], v[218:225], v[114:117], v188, v188 op_sel_hi:[0,0,0]
	v_mfma_scale_f32_16x16x128_f8f6f4 v[106:109], v[18:25], v[226:233], v[106:109], v188, v188 op_sel_hi:[0,0,0]
	v_mfma_scale_f32_16x16x128_f8f6f4 v[98:101], v[26:33], v[226:233], v[98:101], v188, v188 op_sel_hi:[0,0,0]
	s_mov_b32 m0, s45
	s_barrier
	ds_read_b128 v[202:205], v169 offset:16384
	ds_read_b128 v[206:209], v169 offset:17408
	ds_read_b128 v[210:213], v169 offset:18432
	ds_read_b128 v[214:217], v169 offset:19456
	ds_read_b128 v[218:221], v169 offset:20480
	ds_read_b128 v[222:225], v169 offset:21504
	ds_read_b128 v[226:229], v169 offset:22528
	ds_read_b128 v[230:233], v169 offset:23552
	global_load_lds_dwordx4 v162, s[40:41]
	s_mov_b32 m0, s46
	v_mov_b32_e32 v185, v163
	global_load_lds_dwordx4 v184, s[40:41]
	s_waitcnt vmcnt(10)
	s_barrier
	s_waitcnt lgkmcnt(0)
	v_lshl_add_u64 v[186:187], s[40:41], 0, v[162:163]
	v_lshl_add_u64 v[184:185], s[40:41], 0, v[184:185]
	s_waitcnt lgkmcnt(0)
	v_mfma_scale_f32_16x16x128_f8f6f4 v[94:97], v[2:9], v[202:209], v[94:97], v188, v188 op_sel_hi:[0,0,0]
	v_mfma_scale_f32_16x16x128_f8f6f4 v[86:89], v[10:17], v[202:209], v[86:89], v188, v188 op_sel_hi:[0,0,0]
	v_mfma_scale_f32_16x16x128_f8f6f4 v[78:81], v[2:9], v[210:217], v[78:81], v188, v188 op_sel_hi:[0,0,0]
	v_mfma_scale_f32_16x16x128_f8f6f4 v[70:73], v[10:17], v[210:217], v[70:73], v188, v188 op_sel_hi:[0,0,0]
	v_mfma_scale_f32_16x16x128_f8f6f4 v[62:65], v[2:9], v[218:225], v[62:65], v188, v188 op_sel_hi:[0,0,0]
	v_mfma_scale_f32_16x16x128_f8f6f4 v[54:57], v[10:17], v[218:225], v[54:57], v188, v188 op_sel_hi:[0,0,0]
	v_mfma_scale_f32_16x16x128_f8f6f4 v[46:49], v[2:9], v[226:233], v[46:49], v188, v188 op_sel_hi:[0,0,0]
	v_mfma_scale_f32_16x16x128_f8f6f4 v[38:41], v[10:17], v[226:233], v[38:41], v188, v188 op_sel_hi:[0,0,0]
	s_barrier
	s_add_u32 s38, s36, 0x20000
	s_addc_u32 s39, s37, 0
	s_add_i32 s0, s0, s43
	v_lshl_add_u64 v[2:3], s[38:39], 0, v[164:165]
	s_mov_b32 m0, s0
	s_nop 0
	global_load_lds_dwordx4 v[2:3], off
	v_lshl_add_u64 v[2:3], s[38:39], 0, v[166:167]
	s_add_i32 m0, s0, 0x2000
	s_nop 0
	global_load_lds_dwordx4 v[2:3], off
	s_waitcnt vmcnt(10)
	s_barrier
	v_mfma_scale_f32_16x16x128_f8f6f4 v[90:93], v[18:25], v[202:209], v[90:93], v188, v188 op_sel_hi:[0,0,0]
	v_mfma_scale_f32_16x16x128_f8f6f4 v[82:85], v[26:33], v[202:209], v[82:85], v188, v188 op_sel_hi:[0,0,0]
	v_mfma_scale_f32_16x16x128_f8f6f4 v[74:77], v[18:25], v[210:217], v[74:77], v188, v188 op_sel_hi:[0,0,0]
	v_mfma_scale_f32_16x16x128_f8f6f4 v[66:69], v[26:33], v[210:217], v[66:69], v188, v188 op_sel_hi:[0,0,0]
	v_mfma_scale_f32_16x16x128_f8f6f4 v[58:61], v[18:25], v[218:225], v[58:61], v188, v188 op_sel_hi:[0,0,0]
	v_mfma_scale_f32_16x16x128_f8f6f4 v[50:53], v[26:33], v[218:225], v[50:53], v188, v188 op_sel_hi:[0,0,0]
	v_mfma_scale_f32_16x16x128_f8f6f4 v[42:45], v[18:25], v[226:233], v[42:45], v188, v188 op_sel_hi:[0,0,0]
	v_mfma_scale_f32_16x16x128_f8f6f4 v[34:37], v[26:33], v[226:233], v[34:37], v188, v188 op_sel_hi:[0,0,0]
	s_add_i32 s0, 0, 0x18000
	v_add_u32_e32 v14, s0, v197
	s_barrier
	ds_read_b128 v[2:5], v14
	ds_read_b128 v[6:9], v14 offset:1024
	ds_read_b128 v[10:13], v14 offset:2048
	ds_read_b128 v[14:17], v14 offset:3072
	s_mov_b32 m0, s47
	ds_read_b128 v[18:21], v169 offset:32768
	ds_read_b128 v[22:25], v169 offset:33792
	ds_read_b128 v[26:29], v169 offset:34816
	ds_read_b128 v[30:33], v169 offset:35840
	ds_read_b128 v[202:205], v169 offset:36864
	ds_read_b128 v[206:209], v169 offset:37888
	ds_read_b128 v[210:213], v169 offset:38912
	ds_read_b128 v[214:217], v169 offset:39936
	global_load_lds_dwordx4 v175, s[40:41]
	s_mov_b32 m0, s48
	s_nop 0
	global_load_lds_dwordx4 v173, s[40:41]
	s_waitcnt lgkmcnt(8)
	s_waitcnt vmcnt(10)
	s_barrier
	s_waitcnt lgkmcnt(0)
	v_mfma_scale_f32_16x16x128_f8f6f4 v[158:161], v[2:9], v[18:25], v[158:161], v188, v188 op_sel_hi:[0,0,0]
	v_mfma_scale_f32_16x16x128_f8f6f4 v[150:153], v[10:17], v[18:25], v[150:153], v188, v188 op_sel_hi:[0,0,0]
	v_mfma_scale_f32_16x16x128_f8f6f4 v[142:145], v[2:9], v[26:33], v[142:145], v188, v188 op_sel_hi:[0,0,0]
	v_mfma_scale_f32_16x16x128_f8f6f4 v[134:137], v[10:17], v[26:33], v[134:137], v188, v188 op_sel_hi:[0,0,0]
	v_mfma_scale_f32_16x16x128_f8f6f4 v[126:129], v[2:9], v[202:209], v[126:129], v188, v188 op_sel_hi:[0,0,0]
	v_mfma_scale_f32_16x16x128_f8f6f4 v[118:121], v[10:17], v[202:209], v[118:121], v188, v188 op_sel_hi:[0,0,0]
	v_mfma_scale_f32_16x16x128_f8f6f4 v[110:113], v[2:9], v[210:217], v[110:113], v188, v188 op_sel_hi:[0,0,0]
	v_mfma_scale_f32_16x16x128_f8f6f4 v[102:105], v[10:17], v[210:217], v[102:105], v188, v188 op_sel_hi:[0,0,0]
	s_barrier
	s_add_i32 s38, 0, 0x1c000
	s_add_i32 s0, s0, s43
	v_add_u32_e32 v162, s38, v197
	v_lshl_add_u64 v[180:181], v[180:181], 0, s[24:25]
	s_mov_b32 m0, s0
	ds_read_b128 v[218:221], v162
	ds_read_b128 v[222:225], v162 offset:1024
	ds_read_b128 v[226:229], v162 offset:2048
	ds_read_b128 v[230:233], v162 offset:3072
	global_load_lds_dwordx4 v[180:181], off
	v_lshl_add_u64 v[180:181], v[182:183], 0, s[24:25]
	s_add_i32 m0, s0, 0x2000
	s_nop 0
	global_load_lds_dwordx4 v[180:181], off
	s_waitcnt vmcnt(10)
	s_barrier
	s_waitcnt lgkmcnt(0)
	v_mfma_scale_f32_16x16x128_f8f6f4 v[154:157], v[218:225], v[18:25], v[154:157], v188, v188 op_sel_hi:[0,0,0]
	v_mfma_scale_f32_16x16x128_f8f6f4 v[146:149], v[226:233], v[18:25], v[146:149], v188, v188 op_sel_hi:[0,0,0]
	v_mfma_scale_f32_16x16x128_f8f6f4 v[138:141], v[218:225], v[26:33], v[138:141], v188, v188 op_sel_hi:[0,0,0]
	v_mfma_scale_f32_16x16x128_f8f6f4 v[130:133], v[226:233], v[26:33], v[130:133], v188, v188 op_sel_hi:[0,0,0]
	v_mfma_scale_f32_16x16x128_f8f6f4 v[122:125], v[218:225], v[202:209], v[122:125], v188, v188 op_sel_hi:[0,0,0]
	v_mfma_scale_f32_16x16x128_f8f6f4 v[114:117], v[226:233], v[202:209], v[114:117], v188, v188 op_sel_hi:[0,0,0]
	v_mfma_scale_f32_16x16x128_f8f6f4 v[106:109], v[218:225], v[210:217], v[106:109], v188, v188 op_sel_hi:[0,0,0]
	v_mfma_scale_f32_16x16x128_f8f6f4 v[98:101], v[226:233], v[210:217], v[98:101], v188, v188 op_sel_hi:[0,0,0]
	s_mov_b32 m0, s51
	v_lshl_add_u64 v[180:181], v[186:187], 0, s[24:25]
	s_barrier
	ds_read_b128 v[18:21], v169 offset:49152
	ds_read_b128 v[22:25], v169 offset:50176
	ds_read_b128 v[26:29], v169 offset:51200
	ds_read_b128 v[30:33], v169 offset:52224
	ds_read_b128 v[202:205], v169 offset:53248
	ds_read_b128 v[206:209], v169 offset:54272
	ds_read_b128 v[210:213], v169 offset:55296
	ds_read_b128 v[214:217], v169 offset:56320
	global_load_lds_dwordx4 v[180:181], off
	v_lshl_add_u64 v[180:181], v[184:185], 0, s[24:25]
	s_mov_b32 m0, s52
	s_nop 0
	global_load_lds_dwordx4 v[180:181], off
	s_waitcnt vmcnt(10)
	s_barrier
	s_waitcnt lgkmcnt(0)
	v_mfma_scale_f32_16x16x128_f8f6f4 v[94:97], v[2:9], v[18:25], v[94:97], v188, v188 op_sel_hi:[0,0,0]
	v_mfma_scale_f32_16x16x128_f8f6f4 v[86:89], v[10:17], v[18:25], v[86:89], v188, v188 op_sel_hi:[0,0,0]
	v_mfma_scale_f32_16x16x128_f8f6f4 v[78:81], v[2:9], v[26:33], v[78:81], v188, v188 op_sel_hi:[0,0,0]
	v_mfma_scale_f32_16x16x128_f8f6f4 v[70:73], v[10:17], v[26:33], v[70:73], v188, v188 op_sel_hi:[0,0,0]
	v_mfma_scale_f32_16x16x128_f8f6f4 v[62:65], v[2:9], v[202:209], v[62:65], v188, v188 op_sel_hi:[0,0,0]
	v_mfma_scale_f32_16x16x128_f8f6f4 v[54:57], v[10:17], v[202:209], v[54:57], v188, v188 op_sel_hi:[0,0,0]
	v_mfma_scale_f32_16x16x128_f8f6f4 v[46:49], v[2:9], v[210:217], v[46:49], v188, v188 op_sel_hi:[0,0,0]
	v_mfma_scale_f32_16x16x128_f8f6f4 v[38:41], v[10:17], v[210:217], v[38:41], v188, v188 op_sel_hi:[0,0,0]
	s_barrier
	s_add_u32 s0, s36, 0x20080
	s_addc_u32 s1, s37, 0
	s_add_i32 s36, s38, s43
	v_lshl_add_u64 v[2:3], s[0:1], 0, v[164:165]
	s_mov_b32 m0, s36
	s_nop 0
	global_load_lds_dwordx4 v[2:3], off
	v_lshl_add_u64 v[2:3], s[0:1], 0, v[166:167]
	s_add_i32 m0, s36, 0x2000
	s_nop 0
	global_load_lds_dwordx4 v[2:3], off
	s_waitcnt vmcnt(10)
	s_barrier
	v_mfma_scale_f32_16x16x128_f8f6f4 v[90:93], v[218:225], v[18:25], v[90:93], v188, v188 op_sel_hi:[0,0,0]
	v_mfma_scale_f32_16x16x128_f8f6f4 v[82:85], v[226:233], v[18:25], v[82:85], v188, v188 op_sel_hi:[0,0,0]
	v_mfma_scale_f32_16x16x128_f8f6f4 v[74:77], v[218:225], v[26:33], v[74:77], v188, v188 op_sel_hi:[0,0,0]
	v_mfma_scale_f32_16x16x128_f8f6f4 v[66:69], v[226:233], v[26:33], v[66:69], v188, v188 op_sel_hi:[0,0,0]
	v_mfma_scale_f32_16x16x128_f8f6f4 v[58:61], v[218:225], v[202:209], v[58:61], v188, v188 op_sel_hi:[0,0,0]
	v_mfma_scale_f32_16x16x128_f8f6f4 v[50:53], v[226:233], v[202:209], v[50:53], v188, v188 op_sel_hi:[0,0,0]
	v_mfma_scale_f32_16x16x128_f8f6f4 v[42:45], v[218:225], v[210:217], v[42:45], v188, v188 op_sel_hi:[0,0,0]
	v_mfma_scale_f32_16x16x128_f8f6f4 v[34:37], v[226:233], v[210:217], v[34:37], v188, v188 op_sel_hi:[0,0,0]
	s_add_i32 s56, s56, 2
	s_cmp_gt_u32 s56, 5
	s_mov_b64 s[38:39], s[14:15]
	s_barrier
	s_cbranch_scc0 .LBB0_2041
	v_mul_f32_e32 v5, 0x3c800000, v158
	v_mul_f32_e32 v6, 0xbfb8aa3b, v5
	v_exp_f32_e32 v6, v6
	s_ashr_i32 s35, s34, 31
	s_ashr_i32 s31, s30, 31
	s_lshl_b64 s[14:15], s[34:35], 18
	v_add_f32_e32 v6, 1.0, v6
	v_rcp_f32_e32 v6, v6
	s_lshl_b64 s[30:31], s[30:31], 15
	v_mov_b32_e32 v3, v195
	s_add_u32 s0, s6, s14
	v_mul_f32_e32 v5, v5, v6
	v_mul_f32_e32 v6, 0x3c800000, v159
	v_mul_f32_e32 v7, 0xbfb8aa3b, v6
	v_exp_f32_e32 v7, v7
	v_mul_f32_e32 v5, v5, v154
	v_mul_f32_e32 v5, 0x3e000000, v5
	v_med3_f32 v5, v5, s10, v190
	v_add_f32_e32 v7, 1.0, v7
	v_rcp_f32_e32 v7, v7
	s_nop 15
	s_nop 15
	v_mov_b32_e32 v2, v196
	v_mul_f32_e32 v6, v6, v7
	v_mul_f32_e32 v7, 0x3c800000, v160
	v_mul_f32_e32 v8, 0xbfb8aa3b, v7
	v_exp_f32_e32 v8, v8
	v_mul_f32_e32 v6, v6, v155
	v_mul_f32_e32 v6, 0x3e000000, v6
	v_add_u32_e32 v4, s49, v3
	v_add_f32_e32 v8, 1.0, v8
	v_rcp_f32_e32 v8, v8
	s_addc_u32 s1, s7, s15
	s_add_u32 s14, s0, s30
	v_mul_f32_e32 v7, v7, v8
	v_mul_f32_e32 v8, 0x3c800000, v161
	v_mul_f32_e32 v9, 0xbfb8aa3b, v8
	v_exp_f32_e32 v9, v9
	v_mul_f32_e32 v7, v7, v156
	v_mul_f32_e32 v7, 0x3e000000, v7
	v_lshl_add_u32 v2, v2, 3, s50
	v_add_f32_e32 v9, 1.0, v9
	v_rcp_f32_e32 v9, v9
	s_addc_u32 s15, s1, s31
	v_ashrrev_i32_e32 v3, 31, v2
	s_and_b64 vcc, exec, s[12:13]
	v_mul_f32_e32 v8, v8, v9
	v_mul_f32_e32 v9, 0x3c800000, v150
	v_mul_f32_e32 v10, 0xbfb8aa3b, v9
	v_exp_f32_e32 v10, v10
	v_mul_f32_e32 v8, v8, v157
	v_mul_f32_e32 v8, 0x3e000000, v8
	v_mov_b32_e32 v174, v200
	v_add_f32_e32 v10, 1.0, v10
	v_rcp_f32_e32 v10, v10
	v_mov_b32_e32 v172, v199
	v_mov_b32_e32 v170, v198
	v_mov_b32_e32 v168, v171
	v_mul_f32_e32 v9, v9, v10
	v_mul_f32_e32 v10, 0x3c800000, v151
	v_mul_f32_e32 v11, 0xbfb8aa3b, v10
	v_exp_f32_e32 v11, v11
	v_mul_f32_e32 v9, v9, v146
	v_mul_f32_e32 v9, 0x3e000000, v9
	s_mov_b32 s30, s28
	v_add_f32_e32 v11, 1.0, v11
	v_rcp_f32_e32 v11, v11
	s_mov_b32 s34, s54
	s_mov_b64 s[36:37], s[16:17]
	v_mul_f32_e32 v10, v10, v11
	v_mul_f32_e32 v11, 0x3c800000, v152
	v_mul_f32_e32 v12, 0xbfb8aa3b, v11
	v_exp_f32_e32 v12, v12
	v_mul_f32_e32 v10, v10, v147
	v_mul_f32_e32 v10, 0x3e000000, v10
	v_add_f32_e32 v12, 1.0, v12
	v_rcp_f32_e32 v12, v12
	s_nop 0
	v_mul_f32_e32 v11, v11, v12
	v_mul_f32_e32 v12, 0x3c800000, v153
	v_mul_f32_e32 v13, 0xbfb8aa3b, v12
	v_exp_f32_e32 v13, v13
	v_mul_f32_e32 v11, v11, v148
	v_mul_f32_e32 v11, 0x3e000000, v11
	v_add_f32_e32 v13, 1.0, v13
	v_rcp_f32_e32 v13, v13
	s_nop 0
	v_mul_f32_e32 v12, v12, v13
	v_med3_f32 v13, v6, s10, v190
	v_mov_b32_e32 v6, v163
	v_cvt_pk_fp8_f32 v6, v5, v13
	v_med3_f32 v5, v7, s10, v190
	v_med3_f32 v7, v8, s10, v190
	v_med3_f32 v8, v10, s10, v190
	v_cvt_pk_fp8_f32 v6, v5, v7 op_sel:[0,0,1]
	v_med3_f32 v5, v9, s10, v190
	v_mov_b32_e32 v7, v163
	v_cvt_pk_fp8_f32 v7, v5, v8
	v_mul_f32_e32 v12, v12, v149
	v_mul_f32_e32 v12, 0x3e000000, v12
	v_med3_f32 v5, v11, s10, v190
	v_med3_f32 v8, v12, s10, v190
	v_cvt_pk_fp8_f32 v7, v5, v8 op_sel:[0,0,1]
	v_ashrrev_i32_e32 v5, 31, v4
	v_lshlrev_b64 v[8:9], 7, v[4:5]
	v_lshl_add_u64 v[8:9], s[14:15], 0, v[8:9]
	v_lshl_add_u64 v[8:9], v[8:9], 0, v[2:3]
	v_mul_f32_e32 v5, 0x3c800000, v142
	global_store_dwordx2 v[8:9], v[6:7], off
	v_mul_f32_e32 v6, 0xbfb8aa3b, v5
	v_exp_f32_e32 v6, v6
	s_nop 0
	v_add_f32_e32 v6, 1.0, v6
	v_rcp_f32_e32 v6, v6
	s_nop 0
	v_mul_f32_e32 v5, v5, v6
	v_mul_f32_e32 v6, 0x3c800000, v143
	v_mul_f32_e32 v7, 0xbfb8aa3b, v6
	v_exp_f32_e32 v7, v7
	v_mul_f32_e32 v5, v5, v138
	v_mul_f32_e32 v5, 0x3e000000, v5
	v_med3_f32 v5, v5, s10, v190
	v_add_f32_e32 v7, 1.0, v7
	v_rcp_f32_e32 v7, v7
	s_nop 0
	v_mul_f32_e32 v6, v6, v7
	v_mul_f32_e32 v6, v6, v139
	v_mul_f32_e32 v7, 0x3e000000, v6
	v_mul_f32_e32 v6, 0x3c800000, v144
	v_mul_f32_e32 v8, 0xbfb8aa3b, v6
	v_exp_f32_e32 v8, v8
	v_med3_f32 v7, v7, s10, v190
	v_add_f32_e32 v8, 1.0, v8
	v_rcp_f32_e32 v8, v8
	s_nop 0
	v_mul_f32_e32 v6, v6, v8
	v_mul_f32_e32 v6, v6, v140
	v_mul_f32_e32 v9, 0x3e000000, v6
	v_mul_f32_e32 v6, 0x3c800000, v145
	v_mul_f32_e32 v8, 0xbfb8aa3b, v6
	v_exp_f32_e32 v8, v8
	s_nop 0
	v_add_f32_e32 v8, 1.0, v8
	v_rcp_f32_e32 v8, v8
	s_nop 0
	v_mul_f32_e32 v6, v6, v8
	v_mul_f32_e32 v6, v6, v141
	v_mul_f32_e32 v10, 0x3e000000, v6
	v_mul_f32_e32 v6, 0x3c800000, v134
	v_mul_f32_e32 v8, 0xbfb8aa3b, v6
	v_exp_f32_e32 v8, v8
	s_nop 0
	v_add_f32_e32 v8, 1.0, v8
	v_rcp_f32_e32 v8, v8
	s_nop 0
	v_mul_f32_e32 v6, v6, v8
	v_mul_f32_e32 v6, v6, v130
	v_mul_f32_e32 v11, 0x3e000000, v6
	v_mul_f32_e32 v6, 0x3c800000, v135
	v_mul_f32_e32 v8, 0xbfb8aa3b, v6
	v_exp_f32_e32 v8, v8
	s_nop 0
	v_add_f32_e32 v8, 1.0, v8
	v_rcp_f32_e32 v8, v8
	s_nop 0
	v_mul_f32_e32 v6, v6, v8
	v_mul_f32_e32 v6, v6, v131
	v_mul_f32_e32 v12, 0x3e000000, v6
	v_mul_f32_e32 v6, 0x3c800000, v136
	v_mul_f32_e32 v8, 0xbfb8aa3b, v6
	v_exp_f32_e32 v8, v8
	s_nop 0
	v_add_f32_e32 v8, 1.0, v8
	v_rcp_f32_e32 v8, v8
	s_nop 0
	v_mul_f32_e32 v6, v6, v8
	v_mul_f32_e32 v6, v6, v132
	v_mul_f32_e32 v13, 0x3e000000, v6
	v_mul_f32_e32 v6, 0x3c800000, v137
	v_mul_f32_e32 v8, 0xbfb8aa3b, v6
	v_exp_f32_e32 v8, v8
	s_nop 0
	v_add_f32_e32 v8, 1.0, v8
	v_rcp_f32_e32 v8, v8
	s_nop 0
	v_mul_f32_e32 v6, v6, v8
	v_mov_b32_e32 v8, v163
	v_cvt_pk_fp8_f32 v8, v5, v7
	v_med3_f32 v5, v9, s10, v190
	v_med3_f32 v7, v10, s10, v190
	v_mov_b32_e32 v9, v163
	v_cvt_pk_fp8_f32 v8, v5, v7 op_sel:[0,0,1]
	v_med3_f32 v5, v11, s10, v190
	v_med3_f32 v7, v12, s10, v190
	v_cvt_pk_fp8_f32 v9, v5, v7
	v_mul_f32_e32 v6, v6, v133
	v_mul_f32_e32 v14, 0x3e000000, v6
	v_add_u32_e32 v6, 16, v4
	v_med3_f32 v5, v13, s10, v190
	v_med3_f32 v7, v14, s10, v190
	v_cvt_pk_fp8_f32 v9, v5, v7 op_sel:[0,0,1]
	v_ashrrev_i32_e32 v7, 31, v6
	v_lshlrev_b64 v[6:7], 7, v[6:7]
	v_lshl_add_u64 v[6:7], s[14:15], 0, v[6:7]
	v_lshl_add_u64 v[6:7], v[6:7], 0, v[2:3]
	v_mul_f32_e32 v5, 0x3c800000, v126
	global_store_dwordx2 v[6:7], v[8:9], off
	v_mul_f32_e32 v6, 0xbfb8aa3b, v5
	v_exp_f32_e32 v6, v6
	s_nop 0
	v_add_f32_e32 v6, 1.0, v6
	v_rcp_f32_e32 v6, v6
	s_nop 0
	v_mul_f32_e32 v5, v5, v6
	v_mul_f32_e32 v6, 0x3c800000, v127
	v_mul_f32_e32 v7, 0xbfb8aa3b, v6
	v_exp_f32_e32 v7, v7
	v_mul_f32_e32 v5, v5, v122
	v_mul_f32_e32 v5, 0x3e000000, v5
	v_med3_f32 v5, v5, s10, v190
	v_add_f32_e32 v7, 1.0, v7
	v_rcp_f32_e32 v7, v7
	s_nop 0
	v_mul_f32_e32 v6, v6, v7
	v_mul_f32_e32 v6, v6, v123
	v_mul_f32_e32 v7, 0x3e000000, v6
	v_mul_f32_e32 v6, 0x3c800000, v128
	v_mul_f32_e32 v8, 0xbfb8aa3b, v6
	v_exp_f32_e32 v8, v8
	v_med3_f32 v7, v7, s10, v190
	v_add_f32_e32 v8, 1.0, v8
	v_rcp_f32_e32 v8, v8
	s_nop 0
	v_mul_f32_e32 v6, v6, v8
	v_mul_f32_e32 v6, v6, v124
	v_mul_f32_e32 v9, 0x3e000000, v6
	v_mul_f32_e32 v6, 0x3c800000, v129
	v_mul_f32_e32 v8, 0xbfb8aa3b, v6
	v_exp_f32_e32 v8, v8
	s_nop 0
	v_add_f32_e32 v8, 1.0, v8
	v_rcp_f32_e32 v8, v8
	s_nop 0
	v_mul_f32_e32 v6, v6, v8
	v_mul_f32_e32 v6, v6, v125
	v_mul_f32_e32 v10, 0x3e000000, v6
	v_mul_f32_e32 v6, 0x3c800000, v118
	v_mul_f32_e32 v8, 0xbfb8aa3b, v6
	v_exp_f32_e32 v8, v8
	s_nop 0
	v_add_f32_e32 v8, 1.0, v8
	v_rcp_f32_e32 v8, v8
	s_nop 0
	v_mul_f32_e32 v6, v6, v8
	v_mul_f32_e32 v6, v6, v114
	v_mul_f32_e32 v11, 0x3e000000, v6
	v_mul_f32_e32 v6, 0x3c800000, v119
	v_mul_f32_e32 v8, 0xbfb8aa3b, v6
	v_exp_f32_e32 v8, v8
	s_nop 0
	v_add_f32_e32 v8, 1.0, v8
	v_rcp_f32_e32 v8, v8
	s_nop 0
	v_mul_f32_e32 v6, v6, v8
	v_mul_f32_e32 v6, v6, v115
	v_mul_f32_e32 v12, 0x3e000000, v6
	v_mul_f32_e32 v6, 0x3c800000, v120
	v_mul_f32_e32 v8, 0xbfb8aa3b, v6
	v_exp_f32_e32 v8, v8
	s_nop 0
	v_add_f32_e32 v8, 1.0, v8
	v_rcp_f32_e32 v8, v8
	s_nop 0
	v_mul_f32_e32 v6, v6, v8
	v_mul_f32_e32 v6, v6, v116
	v_mul_f32_e32 v13, 0x3e000000, v6
	v_mul_f32_e32 v6, 0x3c800000, v121
	v_mul_f32_e32 v8, 0xbfb8aa3b, v6
	v_exp_f32_e32 v8, v8
	s_nop 0
	v_add_f32_e32 v8, 1.0, v8
	v_rcp_f32_e32 v8, v8
	s_nop 0
	v_mul_f32_e32 v6, v6, v8
	v_mov_b32_e32 v8, v163
	v_cvt_pk_fp8_f32 v8, v5, v7
	v_med3_f32 v5, v9, s10, v190
	v_med3_f32 v7, v10, s10, v190
	v_mov_b32_e32 v9, v163
	v_cvt_pk_fp8_f32 v8, v5, v7 op_sel:[0,0,1]
	v_med3_f32 v5, v11, s10, v190
	v_med3_f32 v7, v12, s10, v190
	v_cvt_pk_fp8_f32 v9, v5, v7
	v_mul_f32_e32 v6, v6, v117
	v_mul_f32_e32 v14, 0x3e000000, v6
	v_add_u32_e32 v6, 32, v4
	v_med3_f32 v5, v13, s10, v190
	v_med3_f32 v7, v14, s10, v190
	v_cvt_pk_fp8_f32 v9, v5, v7 op_sel:[0,0,1]
	v_ashrrev_i32_e32 v7, 31, v6
	v_lshlrev_b64 v[6:7], 7, v[6:7]
	v_lshl_add_u64 v[6:7], s[14:15], 0, v[6:7]
	v_lshl_add_u64 v[6:7], v[6:7], 0, v[2:3]
	v_mul_f32_e32 v5, 0x3c800000, v110
	global_store_dwordx2 v[6:7], v[8:9], off
	v_mul_f32_e32 v6, 0xbfb8aa3b, v5
	v_exp_f32_e32 v6, v6
	s_nop 0
	v_add_f32_e32 v6, 1.0, v6
	v_rcp_f32_e32 v6, v6
	s_nop 0
	v_mul_f32_e32 v5, v5, v6
	v_mul_f32_e32 v6, 0x3c800000, v111
	v_mul_f32_e32 v7, 0xbfb8aa3b, v6
	v_exp_f32_e32 v7, v7
	v_mul_f32_e32 v5, v5, v106
	v_mul_f32_e32 v5, 0x3e000000, v5
	v_med3_f32 v5, v5, s10, v190
	v_add_f32_e32 v7, 1.0, v7
	v_rcp_f32_e32 v7, v7
	s_nop 0
	v_mul_f32_e32 v6, v6, v7
	v_mul_f32_e32 v6, v6, v107
	v_mul_f32_e32 v7, 0x3e000000, v6
	v_mul_f32_e32 v6, 0x3c800000, v112
	v_mul_f32_e32 v8, 0xbfb8aa3b, v6
	v_exp_f32_e32 v8, v8
	v_med3_f32 v7, v7, s10, v190
	v_add_f32_e32 v8, 1.0, v8
	v_rcp_f32_e32 v8, v8
	s_nop 0
	v_mul_f32_e32 v6, v6, v8
	v_mul_f32_e32 v6, v6, v108
	v_mul_f32_e32 v9, 0x3e000000, v6
	v_mul_f32_e32 v6, 0x3c800000, v113
	v_mul_f32_e32 v8, 0xbfb8aa3b, v6
	v_exp_f32_e32 v8, v8
	s_nop 0
	v_add_f32_e32 v8, 1.0, v8
	v_rcp_f32_e32 v8, v8
	s_nop 0
	v_mul_f32_e32 v6, v6, v8
	v_mul_f32_e32 v6, v6, v109
	v_mul_f32_e32 v10, 0x3e000000, v6
	v_mul_f32_e32 v6, 0x3c800000, v102
	v_mul_f32_e32 v8, 0xbfb8aa3b, v6
	v_exp_f32_e32 v8, v8
	s_nop 0
	v_add_f32_e32 v8, 1.0, v8
	v_rcp_f32_e32 v8, v8
	s_nop 0
	v_mul_f32_e32 v6, v6, v8
	v_mul_f32_e32 v6, v6, v98
	v_mul_f32_e32 v11, 0x3e000000, v6
	v_mul_f32_e32 v6, 0x3c800000, v103
	v_mul_f32_e32 v8, 0xbfb8aa3b, v6
	v_exp_f32_e32 v8, v8
	s_nop 0
	v_add_f32_e32 v8, 1.0, v8
	v_rcp_f32_e32 v8, v8
	s_nop 0
	v_mul_f32_e32 v6, v6, v8
	v_mul_f32_e32 v6, v6, v99
	v_mul_f32_e32 v12, 0x3e000000, v6
	v_mul_f32_e32 v6, 0x3c800000, v104
	v_mul_f32_e32 v8, 0xbfb8aa3b, v6
	v_exp_f32_e32 v8, v8
	s_nop 0
	v_add_f32_e32 v8, 1.0, v8
	v_rcp_f32_e32 v8, v8
	s_nop 0
	v_mul_f32_e32 v6, v6, v8
	v_mul_f32_e32 v6, v6, v100
	v_mul_f32_e32 v13, 0x3e000000, v6
	v_mul_f32_e32 v6, 0x3c800000, v105
	v_mul_f32_e32 v8, 0xbfb8aa3b, v6
	v_exp_f32_e32 v8, v8
	s_nop 0
	v_add_f32_e32 v8, 1.0, v8
	v_rcp_f32_e32 v8, v8
	s_nop 0
	v_mul_f32_e32 v6, v6, v8
	v_mov_b32_e32 v8, v163
	v_cvt_pk_fp8_f32 v8, v5, v7
	v_med3_f32 v5, v9, s10, v190
	v_med3_f32 v7, v10, s10, v190
	v_mov_b32_e32 v9, v163
	v_cvt_pk_fp8_f32 v8, v5, v7 op_sel:[0,0,1]
	v_med3_f32 v5, v11, s10, v190
	v_med3_f32 v7, v12, s10, v190
	v_cvt_pk_fp8_f32 v9, v5, v7
	v_mul_f32_e32 v6, v6, v101
	v_mul_f32_e32 v14, 0x3e000000, v6
	v_add_u32_e32 v6, 48, v4
	v_med3_f32 v5, v13, s10, v190
	v_med3_f32 v7, v14, s10, v190
	v_cvt_pk_fp8_f32 v9, v5, v7 op_sel:[0,0,1]
	v_ashrrev_i32_e32 v7, 31, v6
	v_lshlrev_b64 v[6:7], 7, v[6:7]
	v_lshl_add_u64 v[6:7], s[14:15], 0, v[6:7]
	v_lshl_add_u64 v[6:7], v[6:7], 0, v[2:3]
	v_mul_f32_e32 v5, 0x3c800000, v94
	global_store_dwordx2 v[6:7], v[8:9], off
	v_mul_f32_e32 v7, 0xbfb8aa3b, v5
	v_exp_f32_e32 v7, v7
	v_add_u32_e32 v6, 0x80, v4
	v_add_f32_e32 v7, 1.0, v7
	v_rcp_f32_e32 v7, v7
	s_nop 0
	v_mul_f32_e32 v5, v5, v7
	v_mul_f32_e32 v7, 0x3c800000, v95
	v_mul_f32_e32 v8, 0xbfb8aa3b, v7
	v_exp_f32_e32 v8, v8
	v_mul_f32_e32 v5, v5, v90
	v_mul_f32_e32 v5, 0x3e000000, v5
	v_med3_f32 v5, v5, s10, v190
	v_add_f32_e32 v8, 1.0, v8
	v_rcp_f32_e32 v8, v8
	s_nop 0
	v_mul_f32_e32 v7, v7, v8
	v_mul_f32_e32 v8, 0x3c800000, v96
	v_mul_f32_e32 v9, 0xbfb8aa3b, v8
	v_exp_f32_e32 v9, v9
	v_mul_f32_e32 v7, v7, v91
	v_mul_f32_e32 v7, 0x3e000000, v7
	v_med3_f32 v7, v7, s10, v190
	v_add_f32_e32 v9, 1.0, v9
	v_rcp_f32_e32 v9, v9
	s_nop 0
	v_mul_f32_e32 v8, v8, v9
	v_mul_f32_e32 v8, v8, v92
	v_mul_f32_e32 v9, 0x3e000000, v8
	v_mul_f32_e32 v8, 0x3c800000, v97
	v_mul_f32_e32 v10, 0xbfb8aa3b, v8
	v_exp_f32_e32 v10, v10
	s_nop 0
	v_add_f32_e32 v10, 1.0, v10
	v_rcp_f32_e32 v10, v10
	s_nop 0
	v_mul_f32_e32 v8, v8, v10
	v_mul_f32_e32 v8, v8, v93
	v_mul_f32_e32 v10, 0x3e000000, v8
	v_mul_f32_e32 v8, 0x3c800000, v86
	v_mul_f32_e32 v11, 0xbfb8aa3b, v8
	v_exp_f32_e32 v11, v11
	s_nop 0
	v_add_f32_e32 v11, 1.0, v11
	v_rcp_f32_e32 v11, v11
	s_nop 0
	v_mul_f32_e32 v8, v8, v11
	v_mul_f32_e32 v8, v8, v82
	v_mul_f32_e32 v11, 0x3e000000, v8
	v_mul_f32_e32 v8, 0x3c800000, v87
	v_mul_f32_e32 v12, 0xbfb8aa3b, v8
	v_exp_f32_e32 v12, v12
	s_nop 0
	v_add_f32_e32 v12, 1.0, v12
	v_rcp_f32_e32 v12, v12
	s_nop 0
	v_mul_f32_e32 v8, v8, v12
	v_mul_f32_e32 v8, v8, v83
	v_mul_f32_e32 v12, 0x3e000000, v8
	v_mul_f32_e32 v8, 0x3c800000, v88
	v_mul_f32_e32 v13, 0xbfb8aa3b, v8
	v_exp_f32_e32 v13, v13
	s_nop 0
	v_add_f32_e32 v13, 1.0, v13
	v_rcp_f32_e32 v13, v13
	s_nop 0
	v_mul_f32_e32 v8, v8, v13
	v_mul_f32_e32 v8, v8, v84
	v_mul_f32_e32 v13, 0x3e000000, v8
	v_mul_f32_e32 v8, 0x3c800000, v89
	v_mul_f32_e32 v14, 0xbfb8aa3b, v8
	v_exp_f32_e32 v14, v14
	s_nop 0
	v_add_f32_e32 v14, 1.0, v14
	v_rcp_f32_e32 v14, v14
	s_nop 0
	v_mul_f32_e32 v8, v8, v14
	v_mul_f32_e32 v8, v8, v85
	v_mul_f32_e32 v14, 0x3e000000, v8
	v_mov_b32_e32 v8, v163
	v_cvt_pk_fp8_f32 v8, v5, v7
	v_med3_f32 v5, v9, s10, v190
	v_med3_f32 v7, v10, s10, v190
	v_mov_b32_e32 v9, v163
	v_cvt_pk_fp8_f32 v8, v5, v7 op_sel:[0,0,1]
	v_med3_f32 v5, v11, s10, v190
	v_med3_f32 v7, v12, s10, v190
	v_cvt_pk_fp8_f32 v9, v5, v7
	v_med3_f32 v5, v13, s10, v190
	v_med3_f32 v7, v14, s10, v190
	v_cvt_pk_fp8_f32 v9, v5, v7 op_sel:[0,0,1]
	v_ashrrev_i32_e32 v7, 31, v6
	v_lshlrev_b64 v[6:7], 7, v[6:7]
	v_lshl_add_u64 v[6:7], s[14:15], 0, v[6:7]
	v_lshl_add_u64 v[6:7], v[6:7], 0, v[2:3]
	v_mul_f32_e32 v5, 0x3c800000, v78
	global_store_dwordx2 v[6:7], v[8:9], off
	v_mul_f32_e32 v6, 0xbfb8aa3b, v5
	v_exp_f32_e32 v6, v6
	s_nop 0
	v_add_f32_e32 v6, 1.0, v6
	v_rcp_f32_e32 v6, v6
	s_nop 0
	v_mul_f32_e32 v5, v5, v6
	v_mul_f32_e32 v6, 0x3c800000, v79
	v_mul_f32_e32 v7, 0xbfb8aa3b, v6
	v_exp_f32_e32 v7, v7
	v_mul_f32_e32 v5, v5, v74
	v_mul_f32_e32 v5, 0x3e000000, v5
	v_med3_f32 v5, v5, s10, v190
	v_add_f32_e32 v7, 1.0, v7
	v_rcp_f32_e32 v7, v7
	s_nop 0
	v_mul_f32_e32 v6, v6, v7
	v_mul_f32_e32 v6, v6, v75
	v_mul_f32_e32 v7, 0x3e000000, v6
	v_mul_f32_e32 v6, 0x3c800000, v80
	v_mul_f32_e32 v8, 0xbfb8aa3b, v6
	v_exp_f32_e32 v8, v8
	v_med3_f32 v7, v7, s10, v190
	v_add_f32_e32 v8, 1.0, v8
	v_rcp_f32_e32 v8, v8
	s_nop 0
	v_mul_f32_e32 v6, v6, v8
	v_mul_f32_e32 v6, v6, v76
	v_mul_f32_e32 v9, 0x3e000000, v6
	v_mul_f32_e32 v6, 0x3c800000, v81
	v_mul_f32_e32 v8, 0xbfb8aa3b, v6
	v_exp_f32_e32 v8, v8
	s_nop 0
	v_add_f32_e32 v8, 1.0, v8
	v_rcp_f32_e32 v8, v8
	s_nop 0
	v_mul_f32_e32 v6, v6, v8
	v_mul_f32_e32 v6, v6, v77
	v_mul_f32_e32 v10, 0x3e000000, v6
	v_mul_f32_e32 v6, 0x3c800000, v70
	v_mul_f32_e32 v8, 0xbfb8aa3b, v6
	v_exp_f32_e32 v8, v8
	s_nop 0
	v_add_f32_e32 v8, 1.0, v8
	v_rcp_f32_e32 v8, v8
	s_nop 0
	v_mul_f32_e32 v6, v6, v8
	v_mul_f32_e32 v6, v6, v66
	v_mul_f32_e32 v11, 0x3e000000, v6
	v_mul_f32_e32 v6, 0x3c800000, v71
	v_mul_f32_e32 v8, 0xbfb8aa3b, v6
	v_exp_f32_e32 v8, v8
	s_nop 0
	v_add_f32_e32 v8, 1.0, v8
	v_rcp_f32_e32 v8, v8
	s_nop 0
	v_mul_f32_e32 v6, v6, v8
	v_mul_f32_e32 v6, v6, v67
	v_mul_f32_e32 v12, 0x3e000000, v6
	v_mul_f32_e32 v6, 0x3c800000, v72
	v_mul_f32_e32 v8, 0xbfb8aa3b, v6
	v_exp_f32_e32 v8, v8
	s_nop 0
	v_add_f32_e32 v8, 1.0, v8
	v_rcp_f32_e32 v8, v8
	s_nop 0
	v_mul_f32_e32 v6, v6, v8
	v_mul_f32_e32 v6, v6, v68
	v_mul_f32_e32 v13, 0x3e000000, v6
	v_mul_f32_e32 v6, 0x3c800000, v73
	v_mul_f32_e32 v8, 0xbfb8aa3b, v6
	v_exp_f32_e32 v8, v8
	s_nop 0
	v_add_f32_e32 v8, 1.0, v8
	v_rcp_f32_e32 v8, v8
	s_nop 0
	v_mul_f32_e32 v6, v6, v8
	v_mov_b32_e32 v8, v163
	v_cvt_pk_fp8_f32 v8, v5, v7
	v_med3_f32 v5, v9, s10, v190
	v_med3_f32 v7, v10, s10, v190
	v_mov_b32_e32 v9, v163
	v_cvt_pk_fp8_f32 v8, v5, v7 op_sel:[0,0,1]
	v_med3_f32 v5, v11, s10, v190
	v_med3_f32 v7, v12, s10, v190
	v_cvt_pk_fp8_f32 v9, v5, v7
	v_mul_f32_e32 v6, v6, v69
	v_mul_f32_e32 v14, 0x3e000000, v6
	v_add_u32_e32 v6, 0x90, v4
	v_med3_f32 v5, v13, s10, v190
	v_med3_f32 v7, v14, s10, v190
	v_cvt_pk_fp8_f32 v9, v5, v7 op_sel:[0,0,1]
	v_ashrrev_i32_e32 v7, 31, v6
	v_lshlrev_b64 v[6:7], 7, v[6:7]
	v_lshl_add_u64 v[6:7], s[14:15], 0, v[6:7]
	v_lshl_add_u64 v[6:7], v[6:7], 0, v[2:3]
	v_mul_f32_e32 v5, 0x3c800000, v62
	global_store_dwordx2 v[6:7], v[8:9], off
	v_mul_f32_e32 v6, 0xbfb8aa3b, v5
	v_exp_f32_e32 v6, v6
	s_nop 0
	v_add_f32_e32 v6, 1.0, v6
	v_rcp_f32_e32 v6, v6
	s_nop 0
	v_mul_f32_e32 v5, v5, v6
	v_mul_f32_e32 v6, 0x3c800000, v63
	v_mul_f32_e32 v7, 0xbfb8aa3b, v6
	v_exp_f32_e32 v7, v7
	v_mul_f32_e32 v5, v5, v58
	v_mul_f32_e32 v5, 0x3e000000, v5
	v_med3_f32 v5, v5, s10, v190
	v_add_f32_e32 v7, 1.0, v7
	v_rcp_f32_e32 v7, v7
	s_nop 0
	v_mul_f32_e32 v6, v6, v7
	v_mul_f32_e32 v6, v6, v59
	v_mul_f32_e32 v7, 0x3e000000, v6
	v_mul_f32_e32 v6, 0x3c800000, v64
	v_mul_f32_e32 v8, 0xbfb8aa3b, v6
	v_exp_f32_e32 v8, v8
	v_med3_f32 v7, v7, s10, v190
	v_add_f32_e32 v8, 1.0, v8
	v_rcp_f32_e32 v8, v8
	s_nop 0
	v_mul_f32_e32 v6, v6, v8
	v_mul_f32_e32 v6, v6, v60
	v_mul_f32_e32 v9, 0x3e000000, v6
	v_mul_f32_e32 v6, 0x3c800000, v65
	v_mul_f32_e32 v8, 0xbfb8aa3b, v6
	v_exp_f32_e32 v8, v8
	s_nop 0
	v_add_f32_e32 v8, 1.0, v8
	v_rcp_f32_e32 v8, v8
	s_nop 0
	v_mul_f32_e32 v6, v6, v8
	v_mul_f32_e32 v6, v6, v61
	v_mul_f32_e32 v10, 0x3e000000, v6
	v_mul_f32_e32 v6, 0x3c800000, v54
	v_mul_f32_e32 v8, 0xbfb8aa3b, v6
	v_exp_f32_e32 v8, v8
	s_nop 0
	v_add_f32_e32 v8, 1.0, v8
	v_rcp_f32_e32 v8, v8
	s_nop 0
	v_mul_f32_e32 v6, v6, v8
	v_mul_f32_e32 v6, v6, v50
	v_mul_f32_e32 v11, 0x3e000000, v6
	v_mul_f32_e32 v6, 0x3c800000, v55
	v_mul_f32_e32 v8, 0xbfb8aa3b, v6
	v_exp_f32_e32 v8, v8
	s_nop 0
	v_add_f32_e32 v8, 1.0, v8
	v_rcp_f32_e32 v8, v8
	s_nop 0
	v_mul_f32_e32 v6, v6, v8
	v_mul_f32_e32 v6, v6, v51
	v_mul_f32_e32 v12, 0x3e000000, v6
	v_mul_f32_e32 v6, 0x3c800000, v56
	v_mul_f32_e32 v8, 0xbfb8aa3b, v6
	v_exp_f32_e32 v8, v8
	s_nop 0
	v_add_f32_e32 v8, 1.0, v8
	v_rcp_f32_e32 v8, v8
	s_nop 0
	v_mul_f32_e32 v6, v6, v8
	v_mul_f32_e32 v6, v6, v52
	v_mul_f32_e32 v13, 0x3e000000, v6
	v_mul_f32_e32 v6, 0x3c800000, v57
	v_mul_f32_e32 v8, 0xbfb8aa3b, v6
	v_exp_f32_e32 v8, v8
	s_nop 0
	v_add_f32_e32 v8, 1.0, v8
	v_rcp_f32_e32 v8, v8
	s_nop 0
	v_mul_f32_e32 v6, v6, v8
	v_mov_b32_e32 v8, v163
	v_cvt_pk_fp8_f32 v8, v5, v7
	v_med3_f32 v5, v9, s10, v190
	v_med3_f32 v7, v10, s10, v190
	v_mov_b32_e32 v9, v163
	v_cvt_pk_fp8_f32 v8, v5, v7 op_sel:[0,0,1]
	v_med3_f32 v5, v11, s10, v190
	v_med3_f32 v7, v12, s10, v190
	v_cvt_pk_fp8_f32 v9, v5, v7
	v_mul_f32_e32 v6, v6, v53
	v_mul_f32_e32 v14, 0x3e000000, v6
	v_add_u32_e32 v6, 0xa0, v4
	v_med3_f32 v5, v13, s10, v190
	v_med3_f32 v7, v14, s10, v190
	v_cvt_pk_fp8_f32 v9, v5, v7 op_sel:[0,0,1]
	v_ashrrev_i32_e32 v7, 31, v6
	v_lshlrev_b64 v[6:7], 7, v[6:7]
	v_lshl_add_u64 v[6:7], s[14:15], 0, v[6:7]
	v_lshl_add_u64 v[6:7], v[6:7], 0, v[2:3]
	v_mul_f32_e32 v5, 0x3c800000, v46
	global_store_dwordx2 v[6:7], v[8:9], off
	v_mul_f32_e32 v6, 0xbfb8aa3b, v5
	v_exp_f32_e32 v6, v6
	v_add_u32_e32 v4, 0xb0, v4
	v_add_f32_e32 v6, 1.0, v6
	v_rcp_f32_e32 v6, v6
	s_nop 0
	v_mul_f32_e32 v5, v5, v6
	v_mul_f32_e32 v6, 0x3c800000, v47
	v_mul_f32_e32 v7, 0xbfb8aa3b, v6
	v_exp_f32_e32 v7, v7
	v_mul_f32_e32 v5, v5, v42
	v_mul_f32_e32 v5, 0x3e000000, v5
	v_med3_f32 v5, v5, s10, v190
	v_add_f32_e32 v7, 1.0, v7
	v_rcp_f32_e32 v7, v7
	s_nop 0
	v_mul_f32_e32 v6, v6, v7
	v_mul_f32_e32 v7, 0x3c800000, v48
	v_mul_f32_e32 v8, 0xbfb8aa3b, v7
	v_exp_f32_e32 v8, v8
	v_mul_f32_e32 v6, v6, v43
	v_mul_f32_e32 v6, 0x3e000000, v6
	v_add_f32_e32 v8, 1.0, v8
	v_rcp_f32_e32 v8, v8
	s_nop 0
	v_mul_f32_e32 v7, v7, v8
	v_mul_f32_e32 v8, 0x3c800000, v49
	v_mul_f32_e32 v9, 0xbfb8aa3b, v8
	v_exp_f32_e32 v9, v9
	v_mul_f32_e32 v7, v7, v44
	v_mul_f32_e32 v7, 0x3e000000, v7
	v_add_f32_e32 v9, 1.0, v9
	v_rcp_f32_e32 v9, v9
	s_nop 0
	v_mul_f32_e32 v8, v8, v9
	v_mul_f32_e32 v9, 0x3c800000, v38
	v_mul_f32_e32 v10, 0xbfb8aa3b, v9
	v_exp_f32_e32 v10, v10
	v_mul_f32_e32 v8, v8, v45
	v_mul_f32_e32 v8, 0x3e000000, v8
	v_add_f32_e32 v10, 1.0, v10
	v_rcp_f32_e32 v10, v10
	s_nop 0
	v_mul_f32_e32 v9, v9, v10
	v_mul_f32_e32 v10, 0x3c800000, v39
	v_mul_f32_e32 v11, 0xbfb8aa3b, v10
	v_exp_f32_e32 v11, v11
	v_mul_f32_e32 v9, v9, v34
	v_mul_f32_e32 v9, 0x3e000000, v9
	v_add_f32_e32 v11, 1.0, v11
	v_rcp_f32_e32 v11, v11
	s_nop 0
	v_mul_f32_e32 v10, v10, v11
	v_mul_f32_e32 v11, 0x3c800000, v40
	v_mul_f32_e32 v12, 0xbfb8aa3b, v11
	v_exp_f32_e32 v12, v12
	v_mul_f32_e32 v10, v10, v35
	v_mul_f32_e32 v10, 0x3e000000, v10
	v_add_f32_e32 v12, 1.0, v12
	v_rcp_f32_e32 v12, v12
	s_nop 0
	v_mul_f32_e32 v11, v11, v12
	v_mul_f32_e32 v12, 0x3c800000, v41
	v_mul_f32_e32 v13, 0xbfb8aa3b, v12
	v_exp_f32_e32 v13, v13
	v_mul_f32_e32 v11, v11, v36
	v_mul_f32_e32 v11, 0x3e000000, v11
	v_add_f32_e32 v13, 1.0, v13
	v_rcp_f32_e32 v13, v13
	s_nop 0
	v_mul_f32_e32 v12, v12, v13
	v_med3_f32 v13, v6, s10, v190
	v_mov_b32_e32 v6, v163
	v_cvt_pk_fp8_f32 v6, v5, v13
	v_med3_f32 v5, v7, s10, v190
	v_med3_f32 v7, v8, s10, v190
	v_med3_f32 v8, v10, s10, v190
	v_cvt_pk_fp8_f32 v6, v5, v7 op_sel:[0,0,1]
	v_med3_f32 v5, v9, s10, v190
	v_mov_b32_e32 v7, v163
	v_cvt_pk_fp8_f32 v7, v5, v8
	v_mul_f32_e32 v12, v12, v37
	v_mul_f32_e32 v12, 0x3e000000, v12
	v_med3_f32 v5, v11, s10, v190
	v_med3_f32 v8, v12, s10, v190
	v_cvt_pk_fp8_f32 v7, v5, v8 op_sel:[0,0,1]
	v_ashrrev_i32_e32 v5, 31, v4
	v_lshlrev_b64 v[4:5], 7, v[4:5]
	v_lshl_add_u64 v[4:5], s[14:15], 0, v[4:5]
	v_lshl_add_u64 v[2:3], v[4:5], 0, v[2:3]
	global_store_dwordx2 v[2:3], v[6:7], off
	s_cbranch_vccz .LBB0_2030
	s_waitcnt vmcnt(0)
	s_cmpk_gt_u32 s42, 0xff
	s_cbranch_scc1 .LBB0_1976
	s_barrier
	s_branch .LBB0_1976

.LBB0_2108:
	ds_read_b128 v[2:5], v169
	ds_read_b128 v[6:9], v169 offset:1024
	ds_read_b128 v[10:13], v169 offset:2048
	ds_read_b128 v[14:17], v169 offset:3072
	s_add_u32 s0, s30, 0x4000
	s_addc_u32 s1, s31, 0
	s_cmp_eq_u32 s53, 4
	s_cselect_b32 s38, s49, s0
	s_cselect_b32 s39, s23, s1
	s_cselect_b32 s34, s50, s51
	s_cselect_b32 s35, s21, s52
	s_add_u32 s36, s38, 0x8000
	s_addc_u32 s37, s39, 0
	v_lshl_add_u64 v[162:163], s[30:31], 0, v[156:157]
	s_add_i32 m0, s10, 0xc000
	ds_read_b128 v[174:177], v170
	ds_read_b128 v[178:181], v170 offset:1024
	ds_read_b128 v[182:185], v170 offset:2048
	ds_read_b128 v[186:189], v170 offset:3072
	ds_read_b128 v[190:193], v170 offset:4096
	ds_read_b128 v[194:197], v170 offset:5120
	ds_read_b128 v[198:201], v170 offset:6144
	ds_read_b128 v[202:205], v170 offset:7168
	global_load_lds_dwordx4 v[162:163], off
	v_lshl_add_u64 v[162:163], s[30:31], 0, v[154:155]
	s_add_i32 m0, s10, 0xe000
	s_nop 0
	global_load_lds_dwordx4 v[162:163], off
	s_waitcnt lgkmcnt(8)
	s_waitcnt vmcnt(10)
	s_barrier
	s_waitcnt lgkmcnt(0)
	v_mfma_scale_f32_16x16x128_f8f6f4 v[142:145], v[2:9], v[174:181], v[142:145], v171, v171 op_sel_hi:[0,0,0]
	v_mfma_scale_f32_16x16x128_f8f6f4 v[138:141], v[10:17], v[174:181], v[138:141], v171, v171 op_sel_hi:[0,0,0]
	v_mfma_scale_f32_16x16x128_f8f6f4 v[126:129], v[2:9], v[182:189], v[126:129], v171, v171 op_sel_hi:[0,0,0]
	v_mfma_scale_f32_16x16x128_f8f6f4 v[122:125], v[10:17], v[182:189], v[122:125], v171, v171 op_sel_hi:[0,0,0]
	v_mfma_scale_f32_16x16x128_f8f6f4 v[110:113], v[2:9], v[190:197], v[110:113], v171, v171 op_sel_hi:[0,0,0]
	v_mfma_scale_f32_16x16x128_f8f6f4 v[106:109], v[10:17], v[190:197], v[106:109], v171, v171 op_sel_hi:[0,0,0]
	v_mfma_scale_f32_16x16x128_f8f6f4 v[94:97], v[2:9], v[198:205], v[94:97], v171, v171 op_sel_hi:[0,0,0]
	v_mfma_scale_f32_16x16x128_f8f6f4 v[90:93], v[10:17], v[198:205], v[90:93], v171, v171 op_sel_hi:[0,0,0]
	s_barrier
	s_add_i32 s0, s45, s9
	v_lshl_add_u64 v[162:163], s[34:35], 0, v[150:151]
	s_mov_b32 m0, s0
	ds_read_b128 v[206:209], v172
	ds_read_b128 v[210:213], v172 offset:1024
	ds_read_b128 v[214:217], v172 offset:2048
	ds_read_b128 v[218:221], v172 offset:3072
	global_load_lds_dwordx4 v[162:163], off
	v_lshl_add_u64 v[164:165], s[34:35], 0, v[146:147]
	s_add_i32 m0, s0, 0x2000
	s_nop 0
	global_load_lds_dwordx4 v[164:165], off
	s_waitcnt vmcnt(10)
	s_barrier
	s_waitcnt lgkmcnt(0)
	v_mfma_scale_f32_16x16x128_f8f6f4 v[134:137], v[206:213], v[174:181], v[134:137], v171, v171 op_sel_hi:[0,0,0]
	v_mfma_scale_f32_16x16x128_f8f6f4 v[130:133], v[214:221], v[174:181], v[130:133], v171, v171 op_sel_hi:[0,0,0]
	v_mfma_scale_f32_16x16x128_f8f6f4 v[118:121], v[206:213], v[182:189], v[118:121], v171, v171 op_sel_hi:[0,0,0]
	v_mfma_scale_f32_16x16x128_f8f6f4 v[114:117], v[214:221], v[182:189], v[114:117], v171, v171 op_sel_hi:[0,0,0]
	v_mfma_scale_f32_16x16x128_f8f6f4 v[102:105], v[206:213], v[190:197], v[102:105], v171, v171 op_sel_hi:[0,0,0]
	v_mfma_scale_f32_16x16x128_f8f6f4 v[98:101], v[214:221], v[190:197], v[98:101], v171, v171 op_sel_hi:[0,0,0]
	v_mfma_scale_f32_16x16x128_f8f6f4 v[86:89], v[206:213], v[198:205], v[86:89], v171, v171 op_sel_hi:[0,0,0]
	v_mfma_scale_f32_16x16x128_f8f6f4 v[82:85], v[214:221], v[198:205], v[82:85], v171, v171 op_sel_hi:[0,0,0]
	s_mov_b32 m0, s10
	v_lshl_add_u64 v[222:223], s[38:39], 0, v[152:153]
	s_barrier
	ds_read_b128 v[174:177], v170 offset:16384
	ds_read_b128 v[178:181], v170 offset:17408
	ds_read_b128 v[182:185], v170 offset:18432
	ds_read_b128 v[186:189], v170 offset:19456
	ds_read_b128 v[190:193], v170 offset:20480
	ds_read_b128 v[194:197], v170 offset:21504
	ds_read_b128 v[198:201], v170 offset:22528
	ds_read_b128 v[202:205], v170 offset:23552
	global_load_lds_dwordx4 v[222:223], off
	v_lshl_add_u64 v[222:223], s[38:39], 0, v[148:149]
	s_mov_b32 m0, s11
	s_nop 0
	global_load_lds_dwordx4 v[222:223], off
	s_waitcnt vmcnt(10)
	s_barrier
	s_waitcnt lgkmcnt(0)
	v_mfma_scale_f32_16x16x128_f8f6f4 v[78:81], v[2:9], v[174:181], v[78:81], v171, v171 op_sel_hi:[0,0,0]
	v_mfma_scale_f32_16x16x128_f8f6f4 v[74:77], v[10:17], v[174:181], v[74:77], v171, v171 op_sel_hi:[0,0,0]
	v_mfma_scale_f32_16x16x128_f8f6f4 v[62:65], v[2:9], v[182:189], v[62:65], v171, v171 op_sel_hi:[0,0,0]
	v_mfma_scale_f32_16x16x128_f8f6f4 v[58:61], v[10:17], v[182:189], v[58:61], v171, v171 op_sel_hi:[0,0,0]
	v_mfma_scale_f32_16x16x128_f8f6f4 v[46:49], v[2:9], v[190:197], v[46:49], v171, v171 op_sel_hi:[0,0,0]
	v_mfma_scale_f32_16x16x128_f8f6f4 v[42:45], v[10:17], v[190:197], v[42:45], v171, v171 op_sel_hi:[0,0,0]
	v_mfma_scale_f32_16x16x128_f8f6f4 v[30:33], v[2:9], v[198:205], v[30:33], v171, v171 op_sel_hi:[0,0,0]
	v_mfma_scale_f32_16x16x128_f8f6f4 v[26:29], v[10:17], v[198:205], v[26:29], v171, v171 op_sel_hi:[0,0,0]
	s_barrier
	s_add_u32 s0, s34, 0x20000
	s_addc_u32 s1, s35, 0
	s_add_i32 s54, s46, s9
	v_lshl_add_u64 v[2:3], s[0:1], 0, v[150:151]
	s_mov_b32 m0, s54
	s_nop 0
	global_load_lds_dwordx4 v[2:3], off
	v_lshl_add_u64 v[2:3], s[0:1], 0, v[146:147]
	s_add_i32 m0, s54, 0x2000
	s_nop 0
	global_load_lds_dwordx4 v[2:3], off
	s_waitcnt vmcnt(10)
	s_barrier
	v_mfma_scale_f32_16x16x128_f8f6f4 v[70:73], v[206:213], v[174:181], v[70:73], v171, v171 op_sel_hi:[0,0,0]
	v_mfma_scale_f32_16x16x128_f8f6f4 v[66:69], v[214:221], v[174:181], v[66:69], v171, v171 op_sel_hi:[0,0,0]
	v_mfma_scale_f32_16x16x128_f8f6f4 v[54:57], v[206:213], v[182:189], v[54:57], v171, v171 op_sel_hi:[0,0,0]
	v_mfma_scale_f32_16x16x128_f8f6f4 v[50:53], v[214:221], v[182:189], v[50:53], v171, v171 op_sel_hi:[0,0,0]
	v_mfma_scale_f32_16x16x128_f8f6f4 v[38:41], v[206:213], v[190:197], v[38:41], v171, v171 op_sel_hi:[0,0,0]
	v_mfma_scale_f32_16x16x128_f8f6f4 v[34:37], v[214:221], v[190:197], v[34:37], v171, v171 op_sel_hi:[0,0,0]
	v_mfma_scale_f32_16x16x128_f8f6f4 v[22:25], v[206:213], v[198:205], v[22:25], v171, v171 op_sel_hi:[0,0,0]
	v_mfma_scale_f32_16x16x128_f8f6f4 v[18:21], v[214:221], v[198:205], v[18:21], v171, v171 op_sel_hi:[0,0,0]
	s_add_i32 s54, 0, 0x18000
	v_add_u32_e32 v14, s54, v168
	s_barrier
	ds_read_b128 v[2:5], v14
	ds_read_b128 v[6:9], v14 offset:1024
	ds_read_b128 v[10:13], v14 offset:2048
	ds_read_b128 v[14:17], v14 offset:3072
	s_add_u32 s0, s38, 0x4000
	s_addc_u32 s1, s39, 0
	s_mov_b32 m0, s19
	v_lshl_add_u64 v[206:207], s[0:1], 0, v[152:153]
	ds_read_b128 v[174:177], v170 offset:32768
	ds_read_b128 v[178:181], v170 offset:33792
	ds_read_b128 v[182:185], v170 offset:34816
	ds_read_b128 v[186:189], v170 offset:35840
	ds_read_b128 v[190:193], v170 offset:36864
	ds_read_b128 v[194:197], v170 offset:37888
	ds_read_b128 v[198:201], v170 offset:38912
	ds_read_b128 v[202:205], v170 offset:39936
	global_load_lds_dwordx4 v[206:207], off
	v_lshl_add_u64 v[206:207], s[0:1], 0, v[148:149]
	s_mov_b32 m0, s29
	s_nop 0
	global_load_lds_dwordx4 v[206:207], off
	s_waitcnt lgkmcnt(8)
	s_waitcnt vmcnt(10)
	s_barrier
	s_waitcnt lgkmcnt(0)
	v_mfma_scale_f32_16x16x128_f8f6f4 v[142:145], v[2:9], v[174:181], v[142:145], v171, v171 op_sel_hi:[0,0,0]
	v_mfma_scale_f32_16x16x128_f8f6f4 v[138:141], v[10:17], v[174:181], v[138:141], v171, v171 op_sel_hi:[0,0,0]
	v_mfma_scale_f32_16x16x128_f8f6f4 v[126:129], v[2:9], v[182:189], v[126:129], v171, v171 op_sel_hi:[0,0,0]
	v_mfma_scale_f32_16x16x128_f8f6f4 v[122:125], v[10:17], v[182:189], v[122:125], v171, v171 op_sel_hi:[0,0,0]
	v_mfma_scale_f32_16x16x128_f8f6f4 v[110:113], v[2:9], v[190:197], v[110:113], v171, v171 op_sel_hi:[0,0,0]
	v_mfma_scale_f32_16x16x128_f8f6f4 v[106:109], v[10:17], v[190:197], v[106:109], v171, v171 op_sel_hi:[0,0,0]
	v_mfma_scale_f32_16x16x128_f8f6f4 v[94:97], v[2:9], v[198:205], v[94:97], v171, v171 op_sel_hi:[0,0,0]
	v_mfma_scale_f32_16x16x128_f8f6f4 v[90:93], v[10:17], v[198:205], v[90:93], v171, v171 op_sel_hi:[0,0,0]
	s_barrier
	s_add_i32 s38, 0, 0x1c000
	s_add_i32 s0, s54, s9
	v_add_u32_e32 v218, s38, v168
	v_lshl_add_u64 v[162:163], v[162:163], 0, s[16:17]
	s_mov_b32 m0, s0
	ds_read_b128 v[206:209], v218
	ds_read_b128 v[210:213], v218 offset:1024
	ds_read_b128 v[214:217], v218 offset:2048
	ds_read_b128 v[218:221], v218 offset:3072
	global_load_lds_dwordx4 v[162:163], off
	v_lshl_add_u64 v[162:163], v[164:165], 0, s[16:17]
	s_add_i32 m0, s0, 0x2000
	s_nop 0
	global_load_lds_dwordx4 v[162:163], off
	s_waitcnt vmcnt(10)
	s_barrier
	s_waitcnt lgkmcnt(0)
	v_mfma_scale_f32_16x16x128_f8f6f4 v[134:137], v[206:213], v[174:181], v[134:137], v171, v171 op_sel_hi:[0,0,0]
	v_mfma_scale_f32_16x16x128_f8f6f4 v[130:133], v[214:221], v[174:181], v[130:133], v171, v171 op_sel_hi:[0,0,0]
	v_mfma_scale_f32_16x16x128_f8f6f4 v[118:121], v[206:213], v[182:189], v[118:121], v171, v171 op_sel_hi:[0,0,0]
	v_mfma_scale_f32_16x16x128_f8f6f4 v[114:117], v[214:221], v[182:189], v[114:117], v171, v171 op_sel_hi:[0,0,0]
	v_mfma_scale_f32_16x16x128_f8f6f4 v[102:105], v[206:213], v[190:197], v[102:105], v171, v171 op_sel_hi:[0,0,0]
	v_mfma_scale_f32_16x16x128_f8f6f4 v[98:101], v[214:221], v[190:197], v[98:101], v171, v171 op_sel_hi:[0,0,0]
	v_mfma_scale_f32_16x16x128_f8f6f4 v[86:89], v[206:213], v[198:205], v[86:89], v171, v171 op_sel_hi:[0,0,0]
	v_mfma_scale_f32_16x16x128_f8f6f4 v[82:85], v[214:221], v[198:205], v[82:85], v171, v171 op_sel_hi:[0,0,0]
	s_mov_b32 m0, s43
	v_lshl_add_u64 v[162:163], s[36:37], 0, v[152:153]
	s_barrier
	ds_read_b128 v[174:177], v170 offset:49152
	ds_read_b128 v[178:181], v170 offset:50176
	ds_read_b128 v[182:185], v170 offset:51200
	ds_read_b128 v[186:189], v170 offset:52224
	ds_read_b128 v[190:193], v170 offset:53248
	ds_read_b128 v[194:197], v170 offset:54272
	ds_read_b128 v[198:201], v170 offset:55296
	ds_read_b128 v[202:205], v170 offset:56320
	global_load_lds_dwordx4 v[162:163], off
	v_lshl_add_u64 v[162:163], s[36:37], 0, v[148:149]
	s_mov_b32 m0, s44
	s_nop 0
	global_load_lds_dwordx4 v[162:163], off
	s_waitcnt vmcnt(10)
	s_barrier
	s_waitcnt lgkmcnt(0)
	v_mfma_scale_f32_16x16x128_f8f6f4 v[78:81], v[2:9], v[174:181], v[78:81], v171, v171 op_sel_hi:[0,0,0]
	v_mfma_scale_f32_16x16x128_f8f6f4 v[74:77], v[10:17], v[174:181], v[74:77], v171, v171 op_sel_hi:[0,0,0]
	v_mfma_scale_f32_16x16x128_f8f6f4 v[62:65], v[2:9], v[182:189], v[62:65], v171, v171 op_sel_hi:[0,0,0]
	v_mfma_scale_f32_16x16x128_f8f6f4 v[58:61], v[10:17], v[182:189], v[58:61], v171, v171 op_sel_hi:[0,0,0]
	v_mfma_scale_f32_16x16x128_f8f6f4 v[46:49], v[2:9], v[190:197], v[46:49], v171, v171 op_sel_hi:[0,0,0]
	v_mfma_scale_f32_16x16x128_f8f6f4 v[42:45], v[10:17], v[190:197], v[42:45], v171, v171 op_sel_hi:[0,0,0]
	v_mfma_scale_f32_16x16x128_f8f6f4 v[30:33], v[2:9], v[198:205], v[30:33], v171, v171 op_sel_hi:[0,0,0]
	v_mfma_scale_f32_16x16x128_f8f6f4 v[26:29], v[10:17], v[198:205], v[26:29], v171, v171 op_sel_hi:[0,0,0]
	s_barrier
	s_add_u32 s0, s34, 0x20080
	s_addc_u32 s1, s35, 0
	s_add_i32 s34, s38, s9
	v_lshl_add_u64 v[2:3], s[0:1], 0, v[150:151]
	s_mov_b32 m0, s34
	s_nop 0
	global_load_lds_dwordx4 v[2:3], off
	v_lshl_add_u64 v[2:3], s[0:1], 0, v[146:147]
	s_add_i32 m0, s34, 0x2000
	s_nop 0
	global_load_lds_dwordx4 v[2:3], off
	s_waitcnt vmcnt(10)
	s_barrier
	v_mfma_scale_f32_16x16x128_f8f6f4 v[70:73], v[206:213], v[174:181], v[70:73], v171, v171 op_sel_hi:[0,0,0]
	v_mfma_scale_f32_16x16x128_f8f6f4 v[66:69], v[214:221], v[174:181], v[66:69], v171, v171 op_sel_hi:[0,0,0]
	v_mfma_scale_f32_16x16x128_f8f6f4 v[54:57], v[206:213], v[182:189], v[54:57], v171, v171 op_sel_hi:[0,0,0]
	v_mfma_scale_f32_16x16x128_f8f6f4 v[50:53], v[214:221], v[182:189], v[50:53], v171, v171 op_sel_hi:[0,0,0]
	v_mfma_scale_f32_16x16x128_f8f6f4 v[38:41], v[206:213], v[190:197], v[38:41], v171, v171 op_sel_hi:[0,0,0]
	v_mfma_scale_f32_16x16x128_f8f6f4 v[34:37], v[214:221], v[190:197], v[34:37], v171, v171 op_sel_hi:[0,0,0]
	v_mfma_scale_f32_16x16x128_f8f6f4 v[22:25], v[206:213], v[198:205], v[22:25], v171, v171 op_sel_hi:[0,0,0]
	v_mfma_scale_f32_16x16x128_f8f6f4 v[18:21], v[214:221], v[198:205], v[18:21], v171, v171 op_sel_hi:[0,0,0]
	s_add_i32 s53, s53, 2
	s_add_u32 s51, s51, 0x100
	s_addc_u32 s52, s52, 0
	s_add_u32 s30, s30, 0x10000
	s_addc_u32 s31, s31, 0
	s_cmp_gt_u32 s53, 5
	s_barrier
	s_cbranch_scc0 .LBB0_2108
	v_pk_mul_f32 v[10:11], v[142:143], s[18:19] op_sel_hi:[1,0]
	v_pk_mul_f32 v[8:9], v[144:145], s[18:19] op_sel_hi:[1,0]
	v_med3_f32 v5, v10, s47, v173
	v_med3_f32 v11, v11, s47, v173
	v_mov_b32_e32 v10, 0
	v_cvt_pk_fp8_f32 v10, v5, v11
	v_mov_b32_e32 v3, v166
	v_mov_b32_e32 v2, v167
	s_lshl_b32 s0, s48, 8
	v_pk_mul_f32 v[14:15], v[138:139], s[18:19] op_sel_hi:[1,0]
	v_med3_f32 v5, v8, s47, v173
	v_med3_f32 v8, v9, s47, v173
	s_nop 15
	s_nop 15
	s_or_b32 s0, s0, s42
	v_cvt_pk_fp8_f32 v10, v5, v8 op_sel:[0,0,1]
	v_med3_f32 v5, v14, s47, v173
	v_med3_f32 v8, v15, s47, v173
	v_mov_b32_e32 v11, 0
	v_lshl_add_u32 v2, v2, 3, s0
	s_lshl_b32 s0, s28, 8
	v_cvt_pk_fp8_f32 v11, v5, v8
	s_add_i32 s0, s0, s41
	v_add_u32_e32 v4, s0, v3
	v_pk_mul_f32 v[12:13], v[140:141], s[18:19] op_sel_hi:[1,0]
	v_mov_b32_e32 v6, v4
	v_med3_f32 v5, v12, s47, v173
	v_med3_f32 v8, v13, s47, v173
	v_cvt_pk_fp8_f32 v11, v5, v8 op_sel:[0,0,1]
	v_ashrrev_i32_e32 v7, 31, v6
	v_lshlrev_b64 v[6:7], 10, v[6:7]
	v_ashrrev_i32_e32 v3, 31, v2
	v_lshl_add_u64 v[6:7], s[14:15], 0, v[6:7]
	v_lshl_add_u64 v[6:7], v[6:7], 0, v[2:3]
	global_store_dwordx2 v[6:7], v[10:11], off
	v_pk_mul_f32 v[10:11], v[134:135], s[18:19] op_sel_hi:[1,0]
	v_pk_mul_f32 v[8:9], v[136:137], s[18:19] op_sel_hi:[1,0]
	v_med3_f32 v5, v10, s47, v173
	v_med3_f32 v11, v11, s47, v173
	v_mov_b32_e32 v10, 0
	v_cvt_pk_fp8_f32 v10, v5, v11
	v_pk_mul_f32 v[14:15], v[130:131], s[18:19] op_sel_hi:[1,0]
	v_med3_f32 v5, v8, s47, v173
	v_med3_f32 v8, v9, s47, v173
	v_cvt_pk_fp8_f32 v10, v5, v8 op_sel:[0,0,1]
	v_med3_f32 v5, v14, s47, v173
	v_med3_f32 v8, v15, s47, v173
	v_mov_b32_e32 v11, 0
	v_cvt_pk_fp8_f32 v11, v5, v8
	v_pk_mul_f32 v[12:13], v[132:133], s[18:19] op_sel_hi:[1,0]
	v_pk_mul_f32 v[14:15], v[122:123], s[18:19] op_sel_hi:[1,0]
	v_med3_f32 v5, v12, s47, v173
	v_med3_f32 v8, v13, s47, v173
	v_cvt_pk_fp8_f32 v11, v5, v8 op_sel:[0,0,1]
	v_pk_mul_f32 v[8:9], v[128:129], s[18:19] op_sel_hi:[1,0]
	v_pk_mul_f32 v[12:13], v[124:125], s[18:19] op_sel_hi:[1,0]
	s_and_b64 vcc, exec, s[12:13]
	global_store_dwordx2 v[6:7], v[10:11], off offset:128
	v_pk_mul_f32 v[10:11], v[126:127], s[18:19] op_sel_hi:[1,0]
	v_add_u32_e32 v6, 16, v4
	v_med3_f32 v5, v10, s47, v173
	v_med3_f32 v11, v11, s47, v173
	v_mov_b32_e32 v10, 0
	v_cvt_pk_fp8_f32 v10, v5, v11
	v_med3_f32 v5, v8, s47, v173
	v_med3_f32 v8, v9, s47, v173
	v_mov_b32_e32 v11, 0
	v_cvt_pk_fp8_f32 v10, v5, v8 op_sel:[0,0,1]
	v_med3_f32 v5, v14, s47, v173
	v_med3_f32 v8, v15, s47, v173
	v_cvt_pk_fp8_f32 v11, v5, v8
	v_med3_f32 v5, v12, s47, v173
	v_med3_f32 v8, v13, s47, v173
	v_cvt_pk_fp8_f32 v11, v5, v8 op_sel:[0,0,1]
	v_ashrrev_i32_e32 v7, 31, v6
	v_lshlrev_b64 v[6:7], 10, v[6:7]
	v_lshl_add_u64 v[6:7], s[14:15], 0, v[6:7]
	v_lshl_add_u64 v[6:7], v[6:7], 0, v[2:3]
	global_store_dwordx2 v[6:7], v[10:11], off
	v_pk_mul_f32 v[10:11], v[118:119], s[18:19] op_sel_hi:[1,0]
	v_pk_mul_f32 v[8:9], v[120:121], s[18:19] op_sel_hi:[1,0]
	v_med3_f32 v5, v10, s47, v173
	v_med3_f32 v11, v11, s47, v173
	v_mov_b32_e32 v10, 0
	v_cvt_pk_fp8_f32 v10, v5, v11
	v_pk_mul_f32 v[14:15], v[114:115], s[18:19] op_sel_hi:[1,0]
	v_med3_f32 v5, v8, s47, v173
	v_med3_f32 v8, v9, s47, v173
	v_cvt_pk_fp8_f32 v10, v5, v8 op_sel:[0,0,1]
	v_med3_f32 v5, v14, s47, v173
	v_med3_f32 v8, v15, s47, v173
	v_mov_b32_e32 v11, 0
	v_cvt_pk_fp8_f32 v11, v5, v8
	v_pk_mul_f32 v[12:13], v[116:117], s[18:19] op_sel_hi:[1,0]
	v_pk_mul_f32 v[14:15], v[106:107], s[18:19] op_sel_hi:[1,0]
	v_med3_f32 v5, v12, s47, v173
	v_med3_f32 v8, v13, s47, v173
	v_cvt_pk_fp8_f32 v11, v5, v8 op_sel:[0,0,1]
	v_pk_mul_f32 v[8:9], v[112:113], s[18:19] op_sel_hi:[1,0]
	v_pk_mul_f32 v[12:13], v[108:109], s[18:19] op_sel_hi:[1,0]
	s_mov_b32 s48, s20
	global_store_dwordx2 v[6:7], v[10:11], off offset:128
	v_pk_mul_f32 v[10:11], v[110:111], s[18:19] op_sel_hi:[1,0]
	v_add_u32_e32 v6, 32, v4
	v_med3_f32 v5, v10, s47, v173
	v_med3_f32 v11, v11, s47, v173
	v_mov_b32_e32 v10, 0
	v_cvt_pk_fp8_f32 v10, v5, v11
	v_med3_f32 v5, v8, s47, v173
	v_med3_f32 v8, v9, s47, v173
	v_mov_b32_e32 v11, 0
	v_cvt_pk_fp8_f32 v10, v5, v8 op_sel:[0,0,1]
	v_med3_f32 v5, v14, s47, v173
	v_med3_f32 v8, v15, s47, v173
	v_cvt_pk_fp8_f32 v11, v5, v8
	v_med3_f32 v5, v12, s47, v173
	v_med3_f32 v8, v13, s47, v173
	v_cvt_pk_fp8_f32 v11, v5, v8 op_sel:[0,0,1]
	v_ashrrev_i32_e32 v7, 31, v6
	v_lshlrev_b64 v[6:7], 10, v[6:7]
	v_lshl_add_u64 v[6:7], s[14:15], 0, v[6:7]
	v_lshl_add_u64 v[6:7], v[6:7], 0, v[2:3]
	global_store_dwordx2 v[6:7], v[10:11], off
	v_pk_mul_f32 v[10:11], v[102:103], s[18:19] op_sel_hi:[1,0]
	v_pk_mul_f32 v[8:9], v[104:105], s[18:19] op_sel_hi:[1,0]
	v_med3_f32 v5, v10, s47, v173
	v_med3_f32 v11, v11, s47, v173
	v_mov_b32_e32 v10, 0
	v_cvt_pk_fp8_f32 v10, v5, v11
	v_pk_mul_f32 v[14:15], v[98:99], s[18:19] op_sel_hi:[1,0]
	v_med3_f32 v5, v8, s47, v173
	v_med3_f32 v8, v9, s47, v173
	v_cvt_pk_fp8_f32 v10, v5, v8 op_sel:[0,0,1]
	v_med3_f32 v5, v14, s47, v173
	v_med3_f32 v8, v15, s47, v173
	v_mov_b32_e32 v11, 0
	v_cvt_pk_fp8_f32 v11, v5, v8
	v_pk_mul_f32 v[12:13], v[100:101], s[18:19] op_sel_hi:[1,0]
	v_pk_mul_f32 v[14:15], v[90:91], s[18:19] op_sel_hi:[1,0]
	v_med3_f32 v5, v12, s47, v173
	v_med3_f32 v8, v13, s47, v173
	v_cvt_pk_fp8_f32 v11, v5, v8 op_sel:[0,0,1]
	v_pk_mul_f32 v[8:9], v[96:97], s[18:19] op_sel_hi:[1,0]
	v_pk_mul_f32 v[12:13], v[92:93], s[18:19] op_sel_hi:[1,0]
	s_mov_b32 s28, s22
	global_store_dwordx2 v[6:7], v[10:11], off offset:128
	v_pk_mul_f32 v[10:11], v[94:95], s[18:19] op_sel_hi:[1,0]
	v_add_u32_e32 v6, 48, v4
	v_med3_f32 v5, v10, s47, v173
	v_med3_f32 v11, v11, s47, v173
	v_mov_b32_e32 v10, 0
	v_cvt_pk_fp8_f32 v10, v5, v11
	v_med3_f32 v5, v8, s47, v173
	v_med3_f32 v8, v9, s47, v173
	v_mov_b32_e32 v11, 0
	v_cvt_pk_fp8_f32 v10, v5, v8 op_sel:[0,0,1]
	v_med3_f32 v5, v14, s47, v173
	v_med3_f32 v8, v15, s47, v173
	v_cvt_pk_fp8_f32 v11, v5, v8
	v_med3_f32 v5, v12, s47, v173
	v_med3_f32 v8, v13, s47, v173
	v_cvt_pk_fp8_f32 v11, v5, v8 op_sel:[0,0,1]
	v_ashrrev_i32_e32 v7, 31, v6
	v_lshlrev_b64 v[6:7], 10, v[6:7]
	v_lshl_add_u64 v[6:7], s[14:15], 0, v[6:7]
	v_lshl_add_u64 v[6:7], v[6:7], 0, v[2:3]
	global_store_dwordx2 v[6:7], v[10:11], off
	v_pk_mul_f32 v[10:11], v[86:87], s[18:19] op_sel_hi:[1,0]
	v_pk_mul_f32 v[8:9], v[88:89], s[18:19] op_sel_hi:[1,0]
	v_med3_f32 v5, v10, s47, v173
	v_med3_f32 v11, v11, s47, v173
	v_mov_b32_e32 v10, 0
	v_cvt_pk_fp8_f32 v10, v5, v11
	v_pk_mul_f32 v[14:15], v[82:83], s[18:19] op_sel_hi:[1,0]
	v_med3_f32 v5, v8, s47, v173
	v_med3_f32 v8, v9, s47, v173
	v_cvt_pk_fp8_f32 v10, v5, v8 op_sel:[0,0,1]
	v_med3_f32 v5, v14, s47, v173
	v_med3_f32 v8, v15, s47, v173
	v_mov_b32_e32 v11, 0
	v_cvt_pk_fp8_f32 v11, v5, v8
	v_pk_mul_f32 v[12:13], v[84:85], s[18:19] op_sel_hi:[1,0]
	v_pk_mul_f32 v[14:15], v[74:75], s[18:19] op_sel_hi:[1,0]
	v_med3_f32 v5, v12, s47, v173
	v_med3_f32 v8, v13, s47, v173
	v_cvt_pk_fp8_f32 v11, v5, v8 op_sel:[0,0,1]
	v_pk_mul_f32 v[8:9], v[80:81], s[18:19] op_sel_hi:[1,0]
	v_pk_mul_f32 v[12:13], v[76:77], s[18:19] op_sel_hi:[1,0]
	s_mov_b64 s[30:31], s[26:27]
	global_store_dwordx2 v[6:7], v[10:11], off offset:128
	v_pk_mul_f32 v[10:11], v[78:79], s[18:19] op_sel_hi:[1,0]
	v_add_u32_e32 v6, 0x80, v4
	v_med3_f32 v5, v10, s47, v173
	v_med3_f32 v11, v11, s47, v173
	v_mov_b32_e32 v10, 0
	v_cvt_pk_fp8_f32 v10, v5, v11
	v_med3_f32 v5, v8, s47, v173
	v_med3_f32 v8, v9, s47, v173
	v_mov_b32_e32 v11, 0
	v_cvt_pk_fp8_f32 v10, v5, v8 op_sel:[0,0,1]
	v_med3_f32 v5, v14, s47, v173
	v_med3_f32 v8, v15, s47, v173
	v_cvt_pk_fp8_f32 v11, v5, v8
	v_med3_f32 v5, v12, s47, v173
	v_med3_f32 v8, v13, s47, v173
	v_cvt_pk_fp8_f32 v11, v5, v8 op_sel:[0,0,1]
	v_ashrrev_i32_e32 v7, 31, v6
	v_lshlrev_b64 v[6:7], 10, v[6:7]
	v_lshl_add_u64 v[6:7], s[14:15], 0, v[6:7]
	v_lshl_add_u64 v[6:7], v[6:7], 0, v[2:3]
	global_store_dwordx2 v[6:7], v[10:11], off
	v_pk_mul_f32 v[10:11], v[70:71], s[18:19] op_sel_hi:[1,0]
	v_pk_mul_f32 v[8:9], v[72:73], s[18:19] op_sel_hi:[1,0]
	v_med3_f32 v5, v10, s47, v173
	v_med3_f32 v11, v11, s47, v173
	v_mov_b32_e32 v10, 0
	v_cvt_pk_fp8_f32 v10, v5, v11
	v_pk_mul_f32 v[14:15], v[66:67], s[18:19] op_sel_hi:[1,0]
	v_med3_f32 v5, v8, s47, v173
	v_med3_f32 v8, v9, s47, v173
	v_cvt_pk_fp8_f32 v10, v5, v8 op_sel:[0,0,1]
	v_med3_f32 v5, v14, s47, v173
	v_med3_f32 v8, v15, s47, v173
	v_mov_b32_e32 v11, 0
	v_cvt_pk_fp8_f32 v11, v5, v8
	v_pk_mul_f32 v[12:13], v[68:69], s[18:19] op_sel_hi:[1,0]
	v_pk_mul_f32 v[14:15], v[58:59], s[18:19] op_sel_hi:[1,0]
	v_med3_f32 v5, v12, s47, v173
	v_med3_f32 v8, v13, s47, v173
	v_cvt_pk_fp8_f32 v11, v5, v8 op_sel:[0,0,1]
	v_pk_mul_f32 v[8:9], v[64:65], s[18:19] op_sel_hi:[1,0]
	v_pk_mul_f32 v[12:13], v[60:61], s[18:19] op_sel_hi:[1,0]
	s_mov_b64 s[34:35], s[24:25]
	global_store_dwordx2 v[6:7], v[10:11], off offset:128
	v_pk_mul_f32 v[10:11], v[62:63], s[18:19] op_sel_hi:[1,0]
	v_add_u32_e32 v6, 0x90, v4
	v_med3_f32 v5, v10, s47, v173
	v_med3_f32 v11, v11, s47, v173
	v_mov_b32_e32 v10, 0
	v_cvt_pk_fp8_f32 v10, v5, v11
	v_med3_f32 v5, v8, s47, v173
	v_med3_f32 v8, v9, s47, v173
	v_mov_b32_e32 v11, 0
	v_cvt_pk_fp8_f32 v10, v5, v8 op_sel:[0,0,1]
	v_med3_f32 v5, v14, s47, v173
	v_med3_f32 v8, v15, s47, v173
	v_cvt_pk_fp8_f32 v11, v5, v8
	v_med3_f32 v5, v12, s47, v173
	v_med3_f32 v8, v13, s47, v173
	v_cvt_pk_fp8_f32 v11, v5, v8 op_sel:[0,0,1]
	v_ashrrev_i32_e32 v7, 31, v6
	v_lshlrev_b64 v[6:7], 10, v[6:7]
	v_lshl_add_u64 v[6:7], s[14:15], 0, v[6:7]
	v_lshl_add_u64 v[6:7], v[6:7], 0, v[2:3]
	global_store_dwordx2 v[6:7], v[10:11], off
	v_pk_mul_f32 v[10:11], v[54:55], s[18:19] op_sel_hi:[1,0]
	v_pk_mul_f32 v[8:9], v[56:57], s[18:19] op_sel_hi:[1,0]
	v_med3_f32 v5, v10, s47, v173
	v_med3_f32 v11, v11, s47, v173
	v_mov_b32_e32 v10, 0
	v_cvt_pk_fp8_f32 v10, v5, v11
	v_pk_mul_f32 v[14:15], v[50:51], s[18:19] op_sel_hi:[1,0]
	v_med3_f32 v5, v8, s47, v173
	v_med3_f32 v8, v9, s47, v173
	v_cvt_pk_fp8_f32 v10, v5, v8 op_sel:[0,0,1]
	v_med3_f32 v5, v14, s47, v173
	v_med3_f32 v8, v15, s47, v173
	v_mov_b32_e32 v11, 0
	v_cvt_pk_fp8_f32 v11, v5, v8
	v_pk_mul_f32 v[12:13], v[52:53], s[18:19] op_sel_hi:[1,0]
	v_pk_mul_f32 v[14:15], v[42:43], s[18:19] op_sel_hi:[1,0]
	v_med3_f32 v5, v12, s47, v173
	v_med3_f32 v8, v13, s47, v173
	v_cvt_pk_fp8_f32 v11, v5, v8 op_sel:[0,0,1]
	v_pk_mul_f32 v[8:9], v[48:49], s[18:19] op_sel_hi:[1,0]
	v_pk_mul_f32 v[12:13], v[44:45], s[18:19] op_sel_hi:[1,0]
	global_store_dwordx2 v[6:7], v[10:11], off offset:128
	v_pk_mul_f32 v[10:11], v[46:47], s[18:19] op_sel_hi:[1,0]
	v_add_u32_e32 v6, 0xa0, v4
	v_med3_f32 v5, v10, s47, v173
	v_med3_f32 v11, v11, s47, v173
	v_mov_b32_e32 v10, 0
	v_cvt_pk_fp8_f32 v10, v5, v11
	v_med3_f32 v5, v8, s47, v173
	v_med3_f32 v8, v9, s47, v173
	v_mov_b32_e32 v11, 0
	v_cvt_pk_fp8_f32 v10, v5, v8 op_sel:[0,0,1]
	v_med3_f32 v5, v14, s47, v173
	v_med3_f32 v8, v15, s47, v173
	v_cvt_pk_fp8_f32 v11, v5, v8
	v_med3_f32 v5, v12, s47, v173
	v_med3_f32 v8, v13, s47, v173
	v_cvt_pk_fp8_f32 v11, v5, v8 op_sel:[0,0,1]
	v_ashrrev_i32_e32 v7, 31, v6
	v_lshlrev_b64 v[6:7], 10, v[6:7]
	v_lshl_add_u64 v[6:7], s[14:15], 0, v[6:7]
	v_lshl_add_u64 v[6:7], v[6:7], 0, v[2:3]
	global_store_dwordx2 v[6:7], v[10:11], off
	v_pk_mul_f32 v[10:11], v[38:39], s[18:19] op_sel_hi:[1,0]
	v_pk_mul_f32 v[8:9], v[40:41], s[18:19] op_sel_hi:[1,0]
	v_med3_f32 v5, v10, s47, v173
	v_med3_f32 v11, v11, s47, v173
	v_mov_b32_e32 v10, 0
	v_cvt_pk_fp8_f32 v10, v5, v11
	v_pk_mul_f32 v[14:15], v[34:35], s[18:19] op_sel_hi:[1,0]
	v_med3_f32 v5, v8, s47, v173
	v_med3_f32 v8, v9, s47, v173
	v_cvt_pk_fp8_f32 v10, v5, v8 op_sel:[0,0,1]
	v_med3_f32 v5, v14, s47, v173
	v_med3_f32 v8, v15, s47, v173
	v_mov_b32_e32 v11, 0
	v_cvt_pk_fp8_f32 v11, v5, v8
	v_pk_mul_f32 v[12:13], v[36:37], s[18:19] op_sel_hi:[1,0]
	v_add_u32_e32 v4, 0xb0, v4
	v_med3_f32 v5, v12, s47, v173
	v_med3_f32 v8, v13, s47, v173
	v_cvt_pk_fp8_f32 v11, v5, v8 op_sel:[0,0,1]
	v_pk_mul_f32 v[8:9], v[28:29], s[18:19] op_sel_hi:[1,0]
	global_store_dwordx2 v[6:7], v[10:11], off offset:128
	v_pk_mul_f32 v[6:7], v[30:31], s[18:19] op_sel_hi:[1,0]
	v_pk_mul_f32 v[10:11], v[26:27], s[18:19] op_sel_hi:[1,0]
	v_ashrrev_i32_e32 v5, 31, v4
	v_med3_f32 v12, v6, s47, v173
	v_med3_f32 v7, v7, s47, v173
	v_mov_b32_e32 v6, 0
	v_lshlrev_b64 v[4:5], 10, v[4:5]
	v_cvt_pk_fp8_f32 v6, v12, v7
	v_lshl_add_u64 v[4:5], s[14:15], 0, v[4:5]
	v_lshl_add_u64 v[2:3], v[4:5], 0, v[2:3]
	v_pk_mul_f32 v[4:5], v[32:33], s[18:19] op_sel_hi:[1,0]
	v_mov_b32_e32 v7, 0
	v_med3_f32 v4, v4, s47, v173
	v_med3_f32 v5, v5, s47, v173
	v_cvt_pk_fp8_f32 v6, v4, v5 op_sel:[0,0,1]
	v_med3_f32 v4, v10, s47, v173
	v_med3_f32 v5, v11, s47, v173
	v_cvt_pk_fp8_f32 v7, v4, v5
	v_med3_f32 v4, v8, s47, v173
	v_med3_f32 v5, v9, s47, v173
	v_pk_mul_f32 v[10:11], v[18:19], s[18:19] op_sel_hi:[1,0]
	v_cvt_pk_fp8_f32 v7, v4, v5 op_sel:[0,0,1]
	v_pk_mul_f32 v[4:5], v[24:25], s[18:19] op_sel_hi:[1,0]
	v_pk_mul_f32 v[8:9], v[20:21], s[18:19] op_sel_hi:[1,0]
	v_med3_f32 v4, v4, s47, v173
	global_store_dwordx2 v[2:3], v[6:7], off
	v_pk_mul_f32 v[6:7], v[22:23], s[18:19] op_sel_hi:[1,0]
	v_med3_f32 v5, v5, s47, v173
	v_med3_f32 v12, v6, s47, v173
	v_med3_f32 v7, v7, s47, v173
	v_mov_b32_e32 v6, 0
	v_cvt_pk_fp8_f32 v6, v12, v7
	v_mov_b32_e32 v7, 0
	v_cvt_pk_fp8_f32 v6, v4, v5 op_sel:[0,0,1]
	v_med3_f32 v4, v10, s47, v173
	v_med3_f32 v5, v11, s47, v173
	v_cvt_pk_fp8_f32 v7, v4, v5
	v_med3_f32 v4, v8, s47, v173
	v_med3_f32 v5, v9, s47, v173
	v_cvt_pk_fp8_f32 v7, v4, v5 op_sel:[0,0,1]
	global_store_dwordx2 v[2:3], v[6:7], off offset:128
	s_cbranch_vccz .LBB0_2101
	s_waitcnt vmcnt(0)
	s_cmpk_gt_u32 s4, 0xff
	s_cbranch_scc1 .LBB0_2112
	s_barrier

.LBB0_2245:
	ds_read_b128 v[150:153], v146
	ds_read_b128 v[154:157], v146 offset:1024
	ds_read_b128 v[158:161], v146 offset:2048
	ds_read_b128 v[162:165], v146 offset:3072
	s_add_u32 s0, s30, 0xfffc0080
	s_addc_u32 s1, s31, -1
	s_cmp_eq_u32 s61, 12
	s_cselect_b32 s37, s55, s1
	s_cselect_b32 s36, s56, s0
	s_cselect_b32 s35, s57, s60
	s_cselect_b32 s34, s58, s59
	s_mov_b32 m0, s46
	v_lshl_add_u64 v[198:199], s[30:31], 0, v[140:141]
	ds_read_b128 v[166:169], v147
	ds_read_b128 v[170:173], v147 offset:1024
	ds_read_b128 v[174:177], v147 offset:2048
	ds_read_b128 v[178:181], v147 offset:3072
	ds_read_b128 v[182:185], v147 offset:4096
	ds_read_b128 v[186:189], v147 offset:5120
	ds_read_b128 v[190:193], v147 offset:6144
	ds_read_b128 v[194:197], v147 offset:7168
	global_load_lds_dwordx4 v[198:199], off
	v_lshl_add_u64 v[198:199], s[30:31], 0, v[138:139]
	s_mov_b32 m0, s47
	s_nop 0
	global_load_lds_dwordx4 v[198:199], off
	s_waitcnt lgkmcnt(8)
	s_waitcnt vmcnt(10)
	s_barrier
	s_waitcnt lgkmcnt(0)
	v_mfma_f32_16x16x32_bf16 v[126:129], v[150:153], v[166:169], v[126:129]
	v_mfma_f32_16x16x32_bf16 v[122:125], v[158:161], v[166:169], v[122:125]
	v_mfma_f32_16x16x32_bf16 v[118:121], v[150:153], v[174:177], v[118:121]
	v_mfma_f32_16x16x32_bf16 v[114:117], v[158:161], v[174:177], v[114:117]
	v_mfma_f32_16x16x32_bf16 v[102:105], v[150:153], v[182:185], v[102:105]
	v_mfma_f32_16x16x32_bf16 v[98:101], v[158:161], v[182:185], v[98:101]
	v_mfma_f32_16x16x32_bf16 v[86:89], v[150:153], v[190:193], v[86:89]
	v_mfma_f32_16x16x32_bf16 v[82:85], v[158:161], v[190:193], v[82:85]
	v_mfma_f32_16x16x32_bf16 v[126:129], v[154:157], v[170:173], v[126:129]
	v_mfma_f32_16x16x32_bf16 v[122:125], v[162:165], v[170:173], v[122:125]
	v_mfma_f32_16x16x32_bf16 v[118:121], v[154:157], v[178:181], v[118:121]
	v_mfma_f32_16x16x32_bf16 v[114:117], v[162:165], v[178:181], v[114:117]
	v_mfma_f32_16x16x32_bf16 v[102:105], v[154:157], v[186:189], v[102:105]
	v_mfma_f32_16x16x32_bf16 v[98:101], v[162:165], v[186:189], v[98:101]
	v_mfma_f32_16x16x32_bf16 v[86:89], v[154:157], v[194:197], v[86:89]
	v_mfma_f32_16x16x32_bf16 v[82:85], v[162:165], v[194:197], v[82:85]
	s_barrier
	s_mov_b32 m0, s48
	v_lshl_add_u64 v[214:215], s[34:35], 0, v[134:135]
	ds_read_b128 v[198:201], v148
	ds_read_b128 v[202:205], v148 offset:1024
	ds_read_b128 v[206:209], v148 offset:2048
	ds_read_b128 v[210:213], v148 offset:3072
	global_load_lds_dwordx4 v[214:215], off
	v_lshl_add_u64 v[216:217], s[34:35], 0, v[130:131]
	s_mov_b32 m0, s49
	s_nop 0
	global_load_lds_dwordx4 v[216:217], off
	s_waitcnt vmcnt(10)
	s_barrier
	s_waitcnt lgkmcnt(0)
	v_mfma_f32_16x16x32_bf16 v[110:113], v[198:201], v[166:169], v[110:113]
	v_mfma_f32_16x16x32_bf16 v[106:109], v[206:209], v[166:169], v[106:109]
	v_mfma_f32_16x16x32_bf16 v[94:97], v[198:201], v[174:177], v[94:97]
	v_mfma_f32_16x16x32_bf16 v[90:93], v[206:209], v[174:177], v[90:93]
	v_mfma_f32_16x16x32_bf16 v[78:81], v[198:201], v[182:185], v[78:81]
	v_mfma_f32_16x16x32_bf16 v[74:77], v[206:209], v[182:185], v[74:77]
	v_mfma_f32_16x16x32_bf16 v[70:73], v[198:201], v[190:193], v[70:73]
	v_mfma_f32_16x16x32_bf16 v[66:69], v[206:209], v[190:193], v[66:69]
	v_mfma_f32_16x16x32_bf16 v[110:113], v[202:205], v[170:173], v[110:113]
	v_mfma_f32_16x16x32_bf16 v[106:109], v[210:213], v[170:173], v[106:109]
	v_mfma_f32_16x16x32_bf16 v[94:97], v[202:205], v[178:181], v[94:97]
	v_mfma_f32_16x16x32_bf16 v[90:93], v[210:213], v[178:181], v[90:93]
	v_mfma_f32_16x16x32_bf16 v[78:81], v[202:205], v[186:189], v[78:81]
	v_mfma_f32_16x16x32_bf16 v[74:77], v[210:213], v[186:189], v[74:77]
	v_mfma_f32_16x16x32_bf16 v[70:73], v[202:205], v[194:197], v[70:73]
	v_mfma_f32_16x16x32_bf16 v[66:69], v[210:213], v[194:197], v[66:69]
	s_mov_b32 m0, s9
	v_lshl_add_u64 v[218:219], s[36:37], 0, v[136:137]
	s_barrier
	ds_read_b128 v[166:169], v147 offset:16384
	ds_read_b128 v[170:173], v147 offset:17408
	ds_read_b128 v[174:177], v147 offset:18432
	ds_read_b128 v[178:181], v147 offset:19456
	ds_read_b128 v[182:185], v147 offset:20480
	ds_read_b128 v[186:189], v147 offset:21504
	ds_read_b128 v[190:193], v147 offset:22528
	ds_read_b128 v[194:197], v147 offset:23552
	global_load_lds_dwordx4 v[218:219], off
	v_lshl_add_u64 v[220:221], s[36:37], 0, v[132:133]
	s_mov_b32 m0, s21
	s_nop 0
	global_load_lds_dwordx4 v[220:221], off
	s_waitcnt vmcnt(10)
	s_barrier
	s_waitcnt lgkmcnt(0)
	v_mfma_f32_16x16x32_bf16 v[62:65], v[150:153], v[166:169], v[62:65]
	v_mfma_f32_16x16x32_bf16 v[58:61], v[158:161], v[166:169], v[58:61]
	v_mfma_f32_16x16x32_bf16 v[54:57], v[150:153], v[174:177], v[54:57]
	v_mfma_f32_16x16x32_bf16 v[50:53], v[158:161], v[174:177], v[50:53]
	v_mfma_f32_16x16x32_bf16 v[38:41], v[150:153], v[182:185], v[38:41]
	v_mfma_f32_16x16x32_bf16 v[34:37], v[158:161], v[182:185], v[34:37]
	v_mfma_f32_16x16x32_bf16 v[22:25], v[150:153], v[190:193], v[22:25]
	v_mfma_f32_16x16x32_bf16 v[18:21], v[158:161], v[190:193], v[18:21]
	v_mfma_f32_16x16x32_bf16 v[62:65], v[154:157], v[170:173], v[62:65]
	v_mfma_f32_16x16x32_bf16 v[58:61], v[162:165], v[170:173], v[58:61]
	v_mfma_f32_16x16x32_bf16 v[54:57], v[154:157], v[178:181], v[54:57]
	v_mfma_f32_16x16x32_bf16 v[50:53], v[162:165], v[178:181], v[50:53]
	v_mfma_f32_16x16x32_bf16 v[38:41], v[154:157], v[186:189], v[38:41]
	v_mfma_f32_16x16x32_bf16 v[34:37], v[162:165], v[186:189], v[34:37]
	v_mfma_f32_16x16x32_bf16 v[22:25], v[154:157], v[194:197], v[22:25]
	v_mfma_f32_16x16x32_bf16 v[18:21], v[162:165], v[194:197], v[18:21]
	s_barrier
	s_add_u32 s0, s34, 0x40000
	s_addc_u32 s1, s35, 0
	s_add_i32 s62, s44, s8
	v_lshl_add_u64 v[150:151], s[0:1], 0, v[134:135]
	s_mov_b32 m0, s62
	s_nop 0
	global_load_lds_dwordx4 v[150:151], off
	v_lshl_add_u64 v[150:151], s[0:1], 0, v[130:131]
	s_add_i32 m0, s62, 0x2000
	s_nop 0
	global_load_lds_dwordx4 v[150:151], off
	s_waitcnt vmcnt(10)
	s_barrier
	v_mfma_f32_16x16x32_bf16 v[46:49], v[198:201], v[166:169], v[46:49]
	v_mfma_f32_16x16x32_bf16 v[42:45], v[206:209], v[166:169], v[42:45]
	v_mfma_f32_16x16x32_bf16 v[30:33], v[198:201], v[174:177], v[30:33]
	v_mfma_f32_16x16x32_bf16 v[26:29], v[206:209], v[174:177], v[26:29]
	v_mfma_f32_16x16x32_bf16 v[14:17], v[198:201], v[182:185], v[14:17]
	v_mfma_f32_16x16x32_bf16 v[10:13], v[206:209], v[182:185], v[10:13]
	v_mfma_f32_16x16x32_bf16 v[6:9], v[198:201], v[190:193], v[6:9]
	v_mfma_f32_16x16x32_bf16 v[2:5], v[206:209], v[190:193], v[2:5]
	v_mfma_f32_16x16x32_bf16 v[46:49], v[202:205], v[170:173], v[46:49]
	v_mfma_f32_16x16x32_bf16 v[42:45], v[210:213], v[170:173], v[42:45]
	v_mfma_f32_16x16x32_bf16 v[30:33], v[202:205], v[178:181], v[30:33]
	v_mfma_f32_16x16x32_bf16 v[26:29], v[210:213], v[178:181], v[26:29]
	v_mfma_f32_16x16x32_bf16 v[14:17], v[202:205], v[186:189], v[14:17]
	v_mfma_f32_16x16x32_bf16 v[10:13], v[210:213], v[186:189], v[10:13]
	v_mfma_f32_16x16x32_bf16 v[6:9], v[202:205], v[194:197], v[6:9]
	v_mfma_f32_16x16x32_bf16 v[2:5], v[210:213], v[194:197], v[2:5]
	s_add_i32 s62, 0, 0x18000
	v_add_u32_e32 v149, s62, v145
	s_barrier
	ds_read_b128 v[150:153], v149
	ds_read_b128 v[154:157], v149 offset:1024
	ds_read_b128 v[158:161], v149 offset:2048
	ds_read_b128 v[162:165], v149 offset:3072
	s_add_u32 s0, s36, 0x40000
	s_addc_u32 s1, s37, 0
	s_mov_b32 m0, s38
	v_lshl_add_u64 v[198:199], s[0:1], 0, v[136:137]
	ds_read_b128 v[166:169], v147 offset:32768
	ds_read_b128 v[170:173], v147 offset:33792
	ds_read_b128 v[174:177], v147 offset:34816
	ds_read_b128 v[178:181], v147 offset:35840
	ds_read_b128 v[182:185], v147 offset:36864
	ds_read_b128 v[186:189], v147 offset:37888
	ds_read_b128 v[190:193], v147 offset:38912
	ds_read_b128 v[194:197], v147 offset:39936
	global_load_lds_dwordx4 v[198:199], off
	v_lshl_add_u64 v[198:199], s[0:1], 0, v[132:133]
	s_mov_b32 m0, s39
	s_nop 0
	global_load_lds_dwordx4 v[198:199], off
	s_waitcnt lgkmcnt(8)
	s_waitcnt vmcnt(10)
	s_barrier
	s_waitcnt lgkmcnt(0)
	v_mfma_f32_16x16x32_bf16 v[126:129], v[150:153], v[166:169], v[126:129]
	v_mfma_f32_16x16x32_bf16 v[122:125], v[158:161], v[166:169], v[122:125]
	v_mfma_f32_16x16x32_bf16 v[118:121], v[150:153], v[174:177], v[118:121]
	v_mfma_f32_16x16x32_bf16 v[114:117], v[158:161], v[174:177], v[114:117]
	v_mfma_f32_16x16x32_bf16 v[102:105], v[150:153], v[182:185], v[102:105]
	v_mfma_f32_16x16x32_bf16 v[98:101], v[158:161], v[182:185], v[98:101]
	v_mfma_f32_16x16x32_bf16 v[86:89], v[150:153], v[190:193], v[86:89]
	v_mfma_f32_16x16x32_bf16 v[82:85], v[158:161], v[190:193], v[82:85]
	v_mfma_f32_16x16x32_bf16 v[126:129], v[154:157], v[170:173], v[126:129]
	v_mfma_f32_16x16x32_bf16 v[122:125], v[162:165], v[170:173], v[122:125]
	v_mfma_f32_16x16x32_bf16 v[118:121], v[154:157], v[178:181], v[118:121]
	v_mfma_f32_16x16x32_bf16 v[114:117], v[162:165], v[178:181], v[114:117]
	v_mfma_f32_16x16x32_bf16 v[102:105], v[154:157], v[186:189], v[102:105]
	v_mfma_f32_16x16x32_bf16 v[98:101], v[162:165], v[186:189], v[98:101]
	v_mfma_f32_16x16x32_bf16 v[86:89], v[154:157], v[194:197], v[86:89]
	v_mfma_f32_16x16x32_bf16 v[82:85], v[162:165], v[194:197], v[82:85]
	s_barrier
	s_add_i32 s36, 0, 0x1c000
	s_add_i32 s0, s62, s8
	v_add_u32_e32 v149, s36, v145
	v_lshl_add_u64 v[214:215], v[214:215], 0, s[24:25]
	s_mov_b32 m0, s0
	ds_read_b128 v[198:201], v149
	ds_read_b128 v[202:205], v149 offset:1024
	ds_read_b128 v[206:209], v149 offset:2048
	ds_read_b128 v[210:213], v149 offset:3072
	global_load_lds_dwordx4 v[214:215], off
	v_lshl_add_u64 v[214:215], v[216:217], 0, s[24:25]
	s_add_i32 m0, s0, 0x2000
	s_nop 0
	global_load_lds_dwordx4 v[214:215], off
	s_waitcnt vmcnt(10)
	s_barrier
	s_waitcnt lgkmcnt(0)
	v_mfma_f32_16x16x32_bf16 v[110:113], v[198:201], v[166:169], v[110:113]
	v_mfma_f32_16x16x32_bf16 v[106:109], v[206:209], v[166:169], v[106:109]
	v_mfma_f32_16x16x32_bf16 v[94:97], v[198:201], v[174:177], v[94:97]
	v_mfma_f32_16x16x32_bf16 v[90:93], v[206:209], v[174:177], v[90:93]
	v_mfma_f32_16x16x32_bf16 v[78:81], v[198:201], v[182:185], v[78:81]
	v_mfma_f32_16x16x32_bf16 v[74:77], v[206:209], v[182:185], v[74:77]
	v_mfma_f32_16x16x32_bf16 v[70:73], v[198:201], v[190:193], v[70:73]
	v_mfma_f32_16x16x32_bf16 v[66:69], v[206:209], v[190:193], v[66:69]
	v_mfma_f32_16x16x32_bf16 v[110:113], v[202:205], v[170:173], v[110:113]
	v_mfma_f32_16x16x32_bf16 v[106:109], v[210:213], v[170:173], v[106:109]
	v_mfma_f32_16x16x32_bf16 v[94:97], v[202:205], v[178:181], v[94:97]
	v_mfma_f32_16x16x32_bf16 v[90:93], v[210:213], v[178:181], v[90:93]
	v_mfma_f32_16x16x32_bf16 v[78:81], v[202:205], v[186:189], v[78:81]
	v_mfma_f32_16x16x32_bf16 v[74:77], v[210:213], v[186:189], v[74:77]
	v_mfma_f32_16x16x32_bf16 v[70:73], v[202:205], v[194:197], v[70:73]
	v_mfma_f32_16x16x32_bf16 v[66:69], v[210:213], v[194:197], v[66:69]
	s_mov_b32 m0, s42
	v_lshl_add_u64 v[214:215], v[218:219], 0, s[24:25]
	s_barrier
	ds_read_b128 v[166:169], v147 offset:49152
	ds_read_b128 v[170:173], v147 offset:50176
	ds_read_b128 v[174:177], v147 offset:51200
	ds_read_b128 v[178:181], v147 offset:52224
	ds_read_b128 v[182:185], v147 offset:53248
	ds_read_b128 v[186:189], v147 offset:54272
	ds_read_b128 v[190:193], v147 offset:55296
	ds_read_b128 v[194:197], v147 offset:56320
	global_load_lds_dwordx4 v[214:215], off
	v_lshl_add_u64 v[214:215], v[220:221], 0, s[24:25]
	s_mov_b32 m0, s43
	s_nop 0
	global_load_lds_dwordx4 v[214:215], off
	s_waitcnt vmcnt(10)
	s_barrier
	s_waitcnt lgkmcnt(0)
	v_mfma_f32_16x16x32_bf16 v[62:65], v[150:153], v[166:169], v[62:65]
	v_mfma_f32_16x16x32_bf16 v[58:61], v[158:161], v[166:169], v[58:61]
	v_mfma_f32_16x16x32_bf16 v[54:57], v[150:153], v[174:177], v[54:57]
	v_mfma_f32_16x16x32_bf16 v[50:53], v[158:161], v[174:177], v[50:53]
	v_mfma_f32_16x16x32_bf16 v[38:41], v[150:153], v[182:185], v[38:41]
	v_mfma_f32_16x16x32_bf16 v[34:37], v[158:161], v[182:185], v[34:37]
	v_mfma_f32_16x16x32_bf16 v[22:25], v[150:153], v[190:193], v[22:25]
	v_mfma_f32_16x16x32_bf16 v[18:21], v[158:161], v[190:193], v[18:21]
	v_mfma_f32_16x16x32_bf16 v[62:65], v[154:157], v[170:173], v[62:65]
	v_mfma_f32_16x16x32_bf16 v[58:61], v[162:165], v[170:173], v[58:61]
	v_mfma_f32_16x16x32_bf16 v[54:57], v[154:157], v[178:181], v[54:57]
	v_mfma_f32_16x16x32_bf16 v[50:53], v[162:165], v[178:181], v[50:53]
	v_mfma_f32_16x16x32_bf16 v[38:41], v[154:157], v[186:189], v[38:41]
	v_mfma_f32_16x16x32_bf16 v[34:37], v[162:165], v[186:189], v[34:37]
	v_mfma_f32_16x16x32_bf16 v[22:25], v[154:157], v[194:197], v[22:25]
	v_mfma_f32_16x16x32_bf16 v[18:21], v[162:165], v[194:197], v[18:21]
	s_barrier
	s_add_u32 s0, s34, 0x40080
	s_addc_u32 s1, s35, 0
	s_add_i32 s34, s36, s8
	v_lshl_add_u64 v[150:151], s[0:1], 0, v[134:135]
	s_mov_b32 m0, s34
	s_nop 0
	global_load_lds_dwordx4 v[150:151], off
	v_lshl_add_u64 v[150:151], s[0:1], 0, v[130:131]
	s_add_i32 m0, s34, 0x2000
	s_nop 0
	global_load_lds_dwordx4 v[150:151], off
	s_waitcnt vmcnt(10)
	s_barrier
	v_mfma_f32_16x16x32_bf16 v[46:49], v[198:201], v[166:169], v[46:49]
	v_mfma_f32_16x16x32_bf16 v[42:45], v[206:209], v[166:169], v[42:45]
	v_mfma_f32_16x16x32_bf16 v[30:33], v[198:201], v[174:177], v[30:33]
	v_mfma_f32_16x16x32_bf16 v[26:29], v[206:209], v[174:177], v[26:29]
	v_mfma_f32_16x16x32_bf16 v[14:17], v[198:201], v[182:185], v[14:17]
	v_mfma_f32_16x16x32_bf16 v[10:13], v[206:209], v[182:185], v[10:13]
	v_mfma_f32_16x16x32_bf16 v[6:9], v[198:201], v[190:193], v[6:9]
	v_mfma_f32_16x16x32_bf16 v[2:5], v[206:209], v[190:193], v[2:5]
	v_mfma_f32_16x16x32_bf16 v[46:49], v[202:205], v[170:173], v[46:49]
	v_mfma_f32_16x16x32_bf16 v[42:45], v[210:213], v[170:173], v[42:45]
	v_mfma_f32_16x16x32_bf16 v[30:33], v[202:205], v[178:181], v[30:33]
	v_mfma_f32_16x16x32_bf16 v[26:29], v[210:213], v[178:181], v[26:29]
	v_mfma_f32_16x16x32_bf16 v[14:17], v[202:205], v[186:189], v[14:17]
	v_mfma_f32_16x16x32_bf16 v[10:13], v[210:213], v[186:189], v[10:13]
	v_mfma_f32_16x16x32_bf16 v[6:9], v[202:205], v[194:197], v[6:9]
	v_mfma_f32_16x16x32_bf16 v[2:5], v[210:213], v[194:197], v[2:5]
	s_add_i32 s61, s61, 2
	s_add_u32 s59, s59, 0x100
	s_addc_u32 s60, s60, 0
	s_add_u32 s30, s30, 0x100
	s_addc_u32 s31, s31, 0
	s_cmp_gt_u32 s61, 13
	s_barrier
	s_cbranch_scc0 .LBB0_2245
	v_mov_b32_e32 v149, v143
	v_mov_b32_e32 v150, v144
	s_lshl_b32 s0, s53, 8
	s_or_b32 s0, s0, s41
	v_lshl_add_u32 v150, v150, 3, s0
	s_lshl_b32 s0, s54, 8
	s_add_i32 s0, s0, s40
	v_add_u32_e32 v149, s0, v149
	v_ashrrev_i32_e32 v151, 31, v150
	v_mov_b32_e32 v152, v149
	v_lshl_add_u64 v[150:151], v[150:151], 1, s[18:19]
	v_cvt_pk_bf16_f32 v126, v126, v127
	v_mad_i64_i32 v[152:153], s[0:1], v152, s45, v[150:151]
	v_cvt_pk_bf16_f32 v127, v128, v129
	v_cvt_pk_bf16_f32 v128, v122, v123
	v_cvt_pk_bf16_f32 v129, v124, v125
	v_cvt_pk_bf16_f32 v110, v110, v111
	v_cvt_pk_bf16_f32 v111, v112, v113
	v_cvt_pk_bf16_f32 v112, v106, v107
	v_cvt_pk_bf16_f32 v113, v108, v109
	v_add_u32_e32 v106, 16, v149
	global_store_dwordx4 v[152:153], v[126:129], off
	global_store_dwordx4 v[152:153], v[110:113], off offset:256
	v_cvt_pk_bf16_f32 v107, v120, v121
	v_cvt_pk_bf16_f32 v108, v114, v115
	v_mad_i64_i32 v[110:111], s[0:1], v106, s45, v[150:151]
	v_cvt_pk_bf16_f32 v106, v118, v119
	v_cvt_pk_bf16_f32 v109, v116, v117
	v_cvt_pk_bf16_f32 v94, v94, v95
	v_cvt_pk_bf16_f32 v95, v96, v97
	v_cvt_pk_bf16_f32 v96, v90, v91
	v_cvt_pk_bf16_f32 v97, v92, v93
	v_add_u32_e32 v90, 32, v149
	global_store_dwordx4 v[110:111], v[106:109], off
	global_store_dwordx4 v[110:111], v[94:97], off offset:256
	v_cvt_pk_bf16_f32 v91, v104, v105
	v_cvt_pk_bf16_f32 v92, v98, v99
	v_mad_i64_i32 v[94:95], s[0:1], v90, s45, v[150:151]
	v_cvt_pk_bf16_f32 v90, v102, v103
	v_cvt_pk_bf16_f32 v93, v100, v101
	v_cvt_pk_bf16_f32 v78, v78, v79
	v_cvt_pk_bf16_f32 v79, v80, v81
	v_cvt_pk_bf16_f32 v80, v74, v75
	v_cvt_pk_bf16_f32 v81, v76, v77
	v_add_u32_e32 v74, 48, v149
	global_store_dwordx4 v[94:95], v[90:93], off
	global_store_dwordx4 v[94:95], v[78:81], off offset:256
	v_cvt_pk_bf16_f32 v75, v88, v89
	v_cvt_pk_bf16_f32 v76, v82, v83
	v_mad_i64_i32 v[78:79], s[0:1], v74, s45, v[150:151]
	v_cvt_pk_bf16_f32 v74, v86, v87
	v_cvt_pk_bf16_f32 v77, v84, v85
	v_cvt_pk_bf16_f32 v70, v70, v71
	v_cvt_pk_bf16_f32 v71, v72, v73
	v_cvt_pk_bf16_f32 v72, v66, v67
	v_cvt_pk_bf16_f32 v73, v68, v69
	v_add_u32_e32 v66, 0x80, v149
	global_store_dwordx4 v[78:79], v[74:77], off
	global_store_dwordx4 v[78:79], v[70:73], off offset:256
	v_cvt_pk_bf16_f32 v62, v62, v63
	v_mad_i64_i32 v[66:67], s[0:1], v66, s45, v[150:151]
	v_cvt_pk_bf16_f32 v63, v64, v65
	v_cvt_pk_bf16_f32 v64, v58, v59
	v_cvt_pk_bf16_f32 v65, v60, v61
	v_cvt_pk_bf16_f32 v46, v46, v47
	v_cvt_pk_bf16_f32 v47, v48, v49
	v_cvt_pk_bf16_f32 v48, v42, v43
	v_cvt_pk_bf16_f32 v49, v44, v45
	v_add_u32_e32 v42, 0x90, v149
	global_store_dwordx4 v[66:67], v[62:65], off
	global_store_dwordx4 v[66:67], v[46:49], off offset:256
	v_cvt_pk_bf16_f32 v43, v56, v57
	v_cvt_pk_bf16_f32 v44, v50, v51
	v_mad_i64_i32 v[46:47], s[0:1], v42, s45, v[150:151]
	v_cvt_pk_bf16_f32 v42, v54, v55
	v_cvt_pk_bf16_f32 v45, v52, v53
	v_cvt_pk_bf16_f32 v30, v30, v31
	v_cvt_pk_bf16_f32 v31, v32, v33
	v_cvt_pk_bf16_f32 v32, v26, v27
	v_cvt_pk_bf16_f32 v33, v28, v29
	v_add_u32_e32 v26, 0xa0, v149
	global_store_dwordx4 v[46:47], v[42:45], off
	global_store_dwordx4 v[46:47], v[30:33], off offset:256
	v_cvt_pk_bf16_f32 v27, v40, v41
	v_cvt_pk_bf16_f32 v28, v34, v35
	v_mad_i64_i32 v[30:31], s[0:1], v26, s45, v[150:151]
	v_cvt_pk_bf16_f32 v26, v38, v39
	v_cvt_pk_bf16_f32 v29, v36, v37
	v_cvt_pk_bf16_f32 v14, v14, v15
	v_cvt_pk_bf16_f32 v15, v16, v17
	v_cvt_pk_bf16_f32 v16, v10, v11
	v_cvt_pk_bf16_f32 v17, v12, v13
	v_add_u32_e32 v10, 0xb0, v149
	global_store_dwordx4 v[30:31], v[26:29], off
	global_store_dwordx4 v[30:31], v[14:17], off offset:256
	v_cvt_pk_bf16_f32 v11, v24, v25
	v_cvt_pk_bf16_f32 v12, v18, v19
	v_mad_i64_i32 v[14:15], s[0:1], v10, s45, v[150:151]
	v_cvt_pk_bf16_f32 v10, v22, v23
	v_cvt_pk_bf16_f32 v13, v20, v21
	v_cvt_pk_bf16_f32 v6, v6, v7
	v_cvt_pk_bf16_f32 v7, v8, v9
	v_cvt_pk_bf16_f32 v8, v2, v3
	v_cvt_pk_bf16_f32 v9, v4, v5
	s_and_b64 vcc, exec, s[26:27]
	s_mov_b32 s53, s52
	s_mov_b32 s54, s51
	global_store_dwordx4 v[14:15], v[10:13], off
	global_store_dwordx4 v[14:15], v[6:9], off offset:256
	s_cbranch_vccz .LBB0_2244
	s_waitcnt vmcnt(0)
	s_cmpk_gt_u32 s5, 0xff
	s_cbranch_scc1 .LBB0_2249
	s_barrier

.LBB0_2325:
	ds_read_b128 v[130:133], v165
	ds_read_b128 v[134:137], v165 offset:1024
	ds_read_b128 v[154:157], v165 offset:2048
	ds_read_b128 v[158:161], v165 offset:3072
	s_add_u32 s36, s34, 0x100
	s_addc_u32 s37, s35, 0
	s_cmp_eq_u32 s59, 2
	s_cselect_b32 s41, s13, s37
	s_cselect_b32 s40, s12, s36
	s_cselect_b32 s39, s15, s58
	s_cselect_b32 s38, s14, s20
	v_lshl_add_u64 v[202:203], s[34:35], 0, v[148:149]
	s_add_i32 m0, s17, 0xc000
	ds_read_b128 v[170:173], v166
	ds_read_b128 v[174:177], v166 offset:1024
	ds_read_b128 v[178:181], v166 offset:2048
	ds_read_b128 v[182:185], v166 offset:3072
	ds_read_b128 v[186:189], v166 offset:4096
	ds_read_b128 v[190:193], v166 offset:5120
	ds_read_b128 v[194:197], v166 offset:6144
	ds_read_b128 v[198:201], v166 offset:7168
	global_load_lds_dwordx4 v[202:203], off
	v_lshl_add_u64 v[202:203], s[34:35], 0, v[146:147]
	s_add_i32 m0, s17, 0xe000
	s_nop 0
	global_load_lds_dwordx4 v[202:203], off
	s_waitcnt lgkmcnt(8)
	s_waitcnt vmcnt(10)
	s_barrier
	s_waitcnt lgkmcnt(0)
	v_mfma_f32_16x16x32_bf16 v[126:129], v[130:133], v[170:173], v[126:129]
	v_mfma_f32_16x16x32_bf16 v[122:125], v[154:157], v[170:173], v[122:125]
	v_mfma_f32_16x16x32_bf16 v[114:117], v[130:133], v[178:181], v[114:117]
	v_mfma_f32_16x16x32_bf16 v[106:109], v[154:157], v[178:181], v[106:109]
	v_mfma_f32_16x16x32_bf16 v[98:101], v[130:133], v[186:189], v[98:101]
	v_mfma_f32_16x16x32_bf16 v[90:93], v[154:157], v[186:189], v[90:93]
	v_mfma_f32_16x16x32_bf16 v[82:85], v[130:133], v[194:197], v[82:85]
	v_mfma_f32_16x16x32_bf16 v[74:77], v[154:157], v[194:197], v[74:77]
	v_mfma_f32_16x16x32_bf16 v[126:129], v[134:137], v[174:177], v[126:129]
	v_mfma_f32_16x16x32_bf16 v[122:125], v[158:161], v[174:177], v[122:125]
	v_mfma_f32_16x16x32_bf16 v[114:117], v[134:137], v[182:185], v[114:117]
	v_mfma_f32_16x16x32_bf16 v[106:109], v[158:161], v[182:185], v[106:109]
	v_mfma_f32_16x16x32_bf16 v[98:101], v[134:137], v[190:193], v[98:101]
	v_mfma_f32_16x16x32_bf16 v[90:93], v[158:161], v[190:193], v[90:93]
	v_mfma_f32_16x16x32_bf16 v[82:85], v[134:137], v[198:201], v[82:85]
	v_mfma_f32_16x16x32_bf16 v[74:77], v[158:161], v[198:201], v[74:77]
	s_barrier
	s_add_i32 s0, s49, s8
	v_lshl_add_u64 v[218:219], s[38:39], 0, v[142:143]
	s_mov_b32 m0, s0
	ds_read_b128 v[202:205], v167
	ds_read_b128 v[206:209], v167 offset:1024
	ds_read_b128 v[210:213], v167 offset:2048
	ds_read_b128 v[214:217], v167 offset:3072
	global_load_lds_dwordx4 v[218:219], off
	v_lshl_add_u64 v[220:221], s[38:39], 0, v[138:139]
	s_add_i32 m0, s0, 0x2000
	s_nop 0
	global_load_lds_dwordx4 v[220:221], off
	s_waitcnt vmcnt(10)
	s_barrier
	s_waitcnt lgkmcnt(0)
	v_mfma_f32_16x16x32_bf16 v[118:121], v[202:205], v[170:173], v[118:121]
	v_mfma_f32_16x16x32_bf16 v[110:113], v[210:213], v[170:173], v[110:113]
	v_mfma_f32_16x16x32_bf16 v[102:105], v[202:205], v[178:181], v[102:105]
	v_mfma_f32_16x16x32_bf16 v[94:97], v[210:213], v[178:181], v[94:97]
	v_mfma_f32_16x16x32_bf16 v[86:89], v[202:205], v[186:189], v[86:89]
	v_mfma_f32_16x16x32_bf16 v[78:81], v[210:213], v[186:189], v[78:81]
	v_mfma_f32_16x16x32_bf16 v[70:73], v[202:205], v[194:197], v[70:73]
	v_mfma_f32_16x16x32_bf16 v[66:69], v[210:213], v[194:197], v[66:69]
	v_mfma_f32_16x16x32_bf16 v[118:121], v[206:209], v[174:177], v[118:121]
	v_mfma_f32_16x16x32_bf16 v[110:113], v[214:217], v[174:177], v[110:113]
	v_mfma_f32_16x16x32_bf16 v[102:105], v[206:209], v[182:185], v[102:105]
	v_mfma_f32_16x16x32_bf16 v[94:97], v[214:217], v[182:185], v[94:97]
	v_mfma_f32_16x16x32_bf16 v[86:89], v[206:209], v[190:193], v[86:89]
	v_mfma_f32_16x16x32_bf16 v[78:81], v[214:217], v[190:193], v[78:81]
	v_mfma_f32_16x16x32_bf16 v[70:73], v[206:209], v[198:201], v[70:73]
	v_mfma_f32_16x16x32_bf16 v[66:69], v[214:217], v[198:201], v[66:69]
	s_mov_b32 m0, s17
	v_lshl_add_u64 v[222:223], s[40:41], 0, v[144:145]
	s_barrier
	ds_read_b128 v[170:173], v166 offset:16384
	ds_read_b128 v[174:177], v166 offset:17408
	ds_read_b128 v[178:181], v166 offset:18432
	ds_read_b128 v[182:185], v166 offset:19456
	ds_read_b128 v[186:189], v166 offset:20480
	ds_read_b128 v[190:193], v166 offset:21504
	ds_read_b128 v[194:197], v166 offset:22528
	ds_read_b128 v[198:201], v166 offset:23552
	global_load_lds_dwordx4 v[222:223], off
	v_lshl_add_u64 v[224:225], s[40:41], 0, v[140:141]
	s_mov_b32 m0, s42
	s_nop 0
	global_load_lds_dwordx4 v[224:225], off
	s_waitcnt vmcnt(10)
	s_barrier
	s_waitcnt lgkmcnt(0)
	v_mfma_f32_16x16x32_bf16 v[62:65], v[130:133], v[170:173], v[62:65]
	v_mfma_f32_16x16x32_bf16 v[58:61], v[154:157], v[170:173], v[58:61]
	v_mfma_f32_16x16x32_bf16 v[50:53], v[130:133], v[178:181], v[50:53]
	v_mfma_f32_16x16x32_bf16 v[42:45], v[154:157], v[178:181], v[42:45]
	v_mfma_f32_16x16x32_bf16 v[34:37], v[130:133], v[186:189], v[34:37]
	v_mfma_f32_16x16x32_bf16 v[26:29], v[154:157], v[186:189], v[26:29]
	v_mfma_f32_16x16x32_bf16 v[18:21], v[130:133], v[194:197], v[18:21]
	v_mfma_f32_16x16x32_bf16 v[10:13], v[154:157], v[194:197], v[10:13]
	v_mfma_f32_16x16x32_bf16 v[62:65], v[134:137], v[174:177], v[62:65]
	v_mfma_f32_16x16x32_bf16 v[58:61], v[158:161], v[174:177], v[58:61]
	v_mfma_f32_16x16x32_bf16 v[50:53], v[134:137], v[182:185], v[50:53]
	v_mfma_f32_16x16x32_bf16 v[42:45], v[158:161], v[182:185], v[42:45]
	v_mfma_f32_16x16x32_bf16 v[34:37], v[134:137], v[190:193], v[34:37]
	v_mfma_f32_16x16x32_bf16 v[26:29], v[158:161], v[190:193], v[26:29]
	v_mfma_f32_16x16x32_bf16 v[18:21], v[134:137], v[198:201], v[18:21]
	v_mfma_f32_16x16x32_bf16 v[10:13], v[158:161], v[198:201], v[10:13]
	s_barrier
	s_add_u32 s0, s38, 0x18000
	s_addc_u32 s1, s39, 0
	s_add_i32 s34, s50, s8
	v_lshl_add_u64 v[130:131], s[0:1], 0, v[142:143]
	s_mov_b32 m0, s34
	s_nop 0
	global_load_lds_dwordx4 v[130:131], off
	v_lshl_add_u64 v[130:131], s[0:1], 0, v[138:139]
	s_add_i32 m0, s34, 0x2000
	s_nop 0
	global_load_lds_dwordx4 v[130:131], off
	s_waitcnt vmcnt(10)
	s_barrier
	v_mfma_f32_16x16x32_bf16 v[54:57], v[202:205], v[170:173], v[54:57]
	v_mfma_f32_16x16x32_bf16 v[46:49], v[210:213], v[170:173], v[46:49]
	v_mfma_f32_16x16x32_bf16 v[38:41], v[202:205], v[178:181], v[38:41]
	v_mfma_f32_16x16x32_bf16 v[30:33], v[210:213], v[178:181], v[30:33]
	v_mfma_f32_16x16x32_bf16 v[22:25], v[202:205], v[186:189], v[22:25]
	v_mfma_f32_16x16x32_bf16 v[14:17], v[210:213], v[186:189], v[14:17]
	v_mfma_f32_16x16x32_bf16 v[6:9], v[202:205], v[194:197], v[6:9]
	v_mfma_f32_16x16x32_bf16 v[2:5], v[210:213], v[194:197], v[2:5]
	v_mfma_f32_16x16x32_bf16 v[54:57], v[206:209], v[174:177], v[54:57]
	v_mfma_f32_16x16x32_bf16 v[46:49], v[214:217], v[174:177], v[46:49]
	v_mfma_f32_16x16x32_bf16 v[38:41], v[206:209], v[182:185], v[38:41]
	v_mfma_f32_16x16x32_bf16 v[30:33], v[214:217], v[182:185], v[30:33]
	v_mfma_f32_16x16x32_bf16 v[22:25], v[206:209], v[190:193], v[22:25]
	v_mfma_f32_16x16x32_bf16 v[14:17], v[214:217], v[190:193], v[14:17]
	v_mfma_f32_16x16x32_bf16 v[6:9], v[206:209], v[198:201], v[6:9]
	v_mfma_f32_16x16x32_bf16 v[2:5], v[214:217], v[198:201], v[2:5]
	s_add_i32 s34, 0, 0x18000
	v_add_u32_e32 v158, s34, v164
	s_barrier
	ds_read_b128 v[130:133], v158
	ds_read_b128 v[134:137], v158 offset:1024
	ds_read_b128 v[154:157], v158 offset:2048
	ds_read_b128 v[158:161], v158 offset:3072
	s_add_u32 s0, s40, 0x18000
	s_addc_u32 s1, s41, 0
	s_mov_b32 m0, s43
	v_lshl_add_u64 v[202:203], s[0:1], 0, v[144:145]
	ds_read_b128 v[170:173], v166 offset:32768
	ds_read_b128 v[174:177], v166 offset:33792
	ds_read_b128 v[178:181], v166 offset:34816
	ds_read_b128 v[182:185], v166 offset:35840
	ds_read_b128 v[186:189], v166 offset:36864
	ds_read_b128 v[190:193], v166 offset:37888
	ds_read_b128 v[194:197], v166 offset:38912
	ds_read_b128 v[198:201], v166 offset:39936
	global_load_lds_dwordx4 v[202:203], off
	v_lshl_add_u64 v[202:203], s[0:1], 0, v[140:141]
	s_mov_b32 m0, s44
	s_nop 0
	global_load_lds_dwordx4 v[202:203], off
	s_waitcnt lgkmcnt(8)
	s_waitcnt vmcnt(10)
	s_barrier
	s_waitcnt lgkmcnt(0)
	v_mfma_f32_16x16x32_bf16 v[126:129], v[130:133], v[170:173], v[126:129]
	v_mfma_f32_16x16x32_bf16 v[122:125], v[154:157], v[170:173], v[122:125]
	v_mfma_f32_16x16x32_bf16 v[114:117], v[130:133], v[178:181], v[114:117]
	v_mfma_f32_16x16x32_bf16 v[106:109], v[154:157], v[178:181], v[106:109]
	v_mfma_f32_16x16x32_bf16 v[98:101], v[130:133], v[186:189], v[98:101]
	v_mfma_f32_16x16x32_bf16 v[90:93], v[154:157], v[186:189], v[90:93]
	v_mfma_f32_16x16x32_bf16 v[82:85], v[130:133], v[194:197], v[82:85]
	v_mfma_f32_16x16x32_bf16 v[74:77], v[154:157], v[194:197], v[74:77]
	v_mfma_f32_16x16x32_bf16 v[126:129], v[134:137], v[174:177], v[126:129]
	v_mfma_f32_16x16x32_bf16 v[122:125], v[158:161], v[174:177], v[122:125]
	v_mfma_f32_16x16x32_bf16 v[114:117], v[134:137], v[182:185], v[114:117]
	v_mfma_f32_16x16x32_bf16 v[106:109], v[158:161], v[182:185], v[106:109]
	v_mfma_f32_16x16x32_bf16 v[98:101], v[134:137], v[190:193], v[98:101]
	v_mfma_f32_16x16x32_bf16 v[90:93], v[158:161], v[190:193], v[90:93]
	v_mfma_f32_16x16x32_bf16 v[82:85], v[134:137], v[198:201], v[82:85]
	v_mfma_f32_16x16x32_bf16 v[74:77], v[158:161], v[198:201], v[74:77]
	s_barrier
	s_add_i32 s35, 0, 0x1c000
	s_add_i32 s0, s34, s8
	v_add_u32_e32 v169, s35, v164
	v_lshl_add_u64 v[218:219], v[218:219], 0, s[30:31]
	s_mov_b32 m0, s0
	ds_read_b128 v[202:205], v169
	ds_read_b128 v[206:209], v169 offset:1024
	ds_read_b128 v[210:213], v169 offset:2048
	ds_read_b128 v[214:217], v169 offset:3072
	global_load_lds_dwordx4 v[218:219], off
	v_lshl_add_u64 v[218:219], v[220:221], 0, s[30:31]
	s_add_i32 m0, s0, 0x2000
	s_nop 0
	global_load_lds_dwordx4 v[218:219], off
	s_waitcnt vmcnt(10)
	s_barrier
	s_waitcnt lgkmcnt(0)
	v_mfma_f32_16x16x32_bf16 v[118:121], v[202:205], v[170:173], v[118:121]
	v_mfma_f32_16x16x32_bf16 v[110:113], v[210:213], v[170:173], v[110:113]
	v_mfma_f32_16x16x32_bf16 v[102:105], v[202:205], v[178:181], v[102:105]
	v_mfma_f32_16x16x32_bf16 v[94:97], v[210:213], v[178:181], v[94:97]
	v_mfma_f32_16x16x32_bf16 v[86:89], v[202:205], v[186:189], v[86:89]
	v_mfma_f32_16x16x32_bf16 v[78:81], v[210:213], v[186:189], v[78:81]
	v_mfma_f32_16x16x32_bf16 v[70:73], v[202:205], v[194:197], v[70:73]
	v_mfma_f32_16x16x32_bf16 v[66:69], v[210:213], v[194:197], v[66:69]
	v_mfma_f32_16x16x32_bf16 v[118:121], v[206:209], v[174:177], v[118:121]
	v_mfma_f32_16x16x32_bf16 v[110:113], v[214:217], v[174:177], v[110:113]
	v_mfma_f32_16x16x32_bf16 v[102:105], v[206:209], v[182:185], v[102:105]
	v_mfma_f32_16x16x32_bf16 v[94:97], v[214:217], v[182:185], v[94:97]
	v_mfma_f32_16x16x32_bf16 v[86:89], v[206:209], v[190:193], v[86:89]
	v_mfma_f32_16x16x32_bf16 v[78:81], v[214:217], v[190:193], v[78:81]
	v_mfma_f32_16x16x32_bf16 v[70:73], v[206:209], v[198:201], v[70:73]
	v_mfma_f32_16x16x32_bf16 v[66:69], v[214:217], v[198:201], v[66:69]
	s_mov_b32 m0, s46
	v_lshl_add_u64 v[218:219], v[222:223], 0, s[30:31]
	s_barrier
	ds_read_b128 v[170:173], v166 offset:49152
	ds_read_b128 v[174:177], v166 offset:50176
	ds_read_b128 v[178:181], v166 offset:51200
	ds_read_b128 v[182:185], v166 offset:52224
	ds_read_b128 v[186:189], v166 offset:53248
	ds_read_b128 v[190:193], v166 offset:54272
	ds_read_b128 v[194:197], v166 offset:55296
	ds_read_b128 v[198:201], v166 offset:56320
	global_load_lds_dwordx4 v[218:219], off
	v_lshl_add_u64 v[218:219], v[224:225], 0, s[30:31]
	s_mov_b32 m0, s47
	s_nop 0
	global_load_lds_dwordx4 v[218:219], off
	s_waitcnt vmcnt(10)
	s_barrier
	s_waitcnt lgkmcnt(0)
	v_mfma_f32_16x16x32_bf16 v[62:65], v[130:133], v[170:173], v[62:65]
	v_mfma_f32_16x16x32_bf16 v[58:61], v[154:157], v[170:173], v[58:61]
	v_mfma_f32_16x16x32_bf16 v[50:53], v[130:133], v[178:181], v[50:53]
	v_mfma_f32_16x16x32_bf16 v[42:45], v[154:157], v[178:181], v[42:45]
	v_mfma_f32_16x16x32_bf16 v[34:37], v[130:133], v[186:189], v[34:37]
	v_mfma_f32_16x16x32_bf16 v[26:29], v[154:157], v[186:189], v[26:29]
	v_mfma_f32_16x16x32_bf16 v[18:21], v[130:133], v[194:197], v[18:21]
	v_mfma_f32_16x16x32_bf16 v[10:13], v[154:157], v[194:197], v[10:13]
	v_mfma_f32_16x16x32_bf16 v[62:65], v[134:137], v[174:177], v[62:65]
	v_mfma_f32_16x16x32_bf16 v[58:61], v[158:161], v[174:177], v[58:61]
	v_mfma_f32_16x16x32_bf16 v[50:53], v[134:137], v[182:185], v[50:53]
	v_mfma_f32_16x16x32_bf16 v[42:45], v[158:161], v[182:185], v[42:45]
	v_mfma_f32_16x16x32_bf16 v[34:37], v[134:137], v[190:193], v[34:37]
	v_mfma_f32_16x16x32_bf16 v[26:29], v[158:161], v[190:193], v[26:29]
	v_mfma_f32_16x16x32_bf16 v[18:21], v[134:137], v[198:201], v[18:21]
	v_mfma_f32_16x16x32_bf16 v[10:13], v[158:161], v[198:201], v[10:13]
	s_barrier
	s_add_u32 s0, s38, 0x18080
	s_addc_u32 s1, s39, 0
	s_add_i32 s34, s35, s8
	v_lshl_add_u64 v[130:131], s[0:1], 0, v[142:143]
	s_mov_b32 m0, s34
	s_nop 0
	global_load_lds_dwordx4 v[130:131], off
	v_lshl_add_u64 v[130:131], s[0:1], 0, v[138:139]
	s_add_i32 m0, s34, 0x2000
	s_nop 0
	global_load_lds_dwordx4 v[130:131], off
	s_waitcnt vmcnt(10)
	s_barrier
	v_mfma_f32_16x16x32_bf16 v[54:57], v[202:205], v[170:173], v[54:57]
	v_mfma_f32_16x16x32_bf16 v[46:49], v[210:213], v[170:173], v[46:49]
	v_mfma_f32_16x16x32_bf16 v[38:41], v[202:205], v[178:181], v[38:41]
	v_mfma_f32_16x16x32_bf16 v[30:33], v[210:213], v[178:181], v[30:33]
	v_mfma_f32_16x16x32_bf16 v[22:25], v[202:205], v[186:189], v[22:25]
	v_mfma_f32_16x16x32_bf16 v[14:17], v[210:213], v[186:189], v[14:17]
	v_mfma_f32_16x16x32_bf16 v[6:9], v[202:205], v[194:197], v[6:9]
	v_mfma_f32_16x16x32_bf16 v[2:5], v[210:213], v[194:197], v[2:5]
	v_mfma_f32_16x16x32_bf16 v[54:57], v[206:209], v[174:177], v[54:57]
	v_mfma_f32_16x16x32_bf16 v[46:49], v[214:217], v[174:177], v[46:49]
	v_mfma_f32_16x16x32_bf16 v[38:41], v[206:209], v[182:185], v[38:41]
	v_mfma_f32_16x16x32_bf16 v[30:33], v[214:217], v[182:185], v[30:33]
	v_mfma_f32_16x16x32_bf16 v[22:25], v[206:209], v[190:193], v[22:25]
	v_mfma_f32_16x16x32_bf16 v[14:17], v[214:217], v[190:193], v[14:17]
	v_mfma_f32_16x16x32_bf16 v[6:9], v[206:209], v[198:201], v[6:9]
	v_mfma_f32_16x16x32_bf16 v[2:5], v[214:217], v[198:201], v[2:5]
	s_add_i32 s59, s59, 2
	s_add_u32 s20, s20, 0x100
	s_addc_u32 s58, s58, 0
	s_cmp_gt_u32 s59, 3
	s_mov_b64 s[34:35], s[36:37]
	s_barrier
	s_cbranch_scc0 .LBB0_2325
	v_mov_b32_e32 v169, v162
	v_mov_b32_e32 v130, v163
	s_mov_b64 s[34:35], -1
	v_lshlrev_b32_e32 v154, 3, v130
	s_cmp_gt_i32 s57, 3
	v_ashrrev_i32_e32 v155, 31, v154
	s_cbranch_scc0 .LBB0_2328
	s_lshl_b32 s0, s56, 8
	s_add_i32 s0, s0, s45
	v_add_u32_e32 v248, s0, v169
	v_mov_b32_e32 v136, v248
	v_lshlrev_b64 v[132:133], 2, v[154:155]
	v_ashrrev_i32_e32 v137, 31, v136
	v_lshl_add_u64 v[130:131], s[26:27], 0, v[132:133]
	v_lshlrev_b64 v[134:135], 7, v[136:137]
	v_lshl_add_u64 v[156:157], v[130:131], 0, v[134:135]
	v_lshl_add_u64 v[132:133], s[24:25], 0, v[132:133]
	global_load_dwordx4 v[170:173], v[156:157], off
	global_load_dwordx4 v[174:177], v[156:157], off offset:16
	v_lshl_add_u64 v[134:135], v[132:133], 0, v[134:135]
	global_load_dwordx4 v[178:181], v[134:135], off
	global_load_dwordx4 v[182:185], v[134:135], off offset:16
	v_add_u32_e32 v160, 16, v136
	v_ashrrev_i32_e32 v161, 31, v160
	v_lshlrev_b64 v[134:135], 7, v[160:161]
	v_lshl_add_u64 v[156:157], v[130:131], 0, v[134:135]
	global_load_dwordx4 v[186:189], v[156:157], off
	global_load_dwordx4 v[194:197], v[156:157], off offset:16
	v_lshl_add_u64 v[134:135], v[132:133], 0, v[134:135]
	global_load_dwordx4 v[190:193], v[134:135], off
	global_load_dwordx4 v[198:201], v[134:135], off offset:16
	v_add_u32_e32 v238, 32, v136
	v_add_u32_e32 v134, 48, v136
	v_ashrrev_i32_e32 v239, 31, v238
	v_ashrrev_i32_e32 v135, 31, v134
	v_lshlrev_b64 v[202:203], 7, v[238:239]
	v_lshlrev_b64 v[204:205], 7, v[134:135]
	v_lshl_add_u64 v[206:207], v[132:133], 0, v[202:203]
	v_lshl_add_u64 v[214:215], v[130:131], 0, v[202:203]
	v_lshl_add_u64 v[222:223], v[132:133], 0, v[204:205]
	v_lshl_add_u64 v[230:231], v[130:131], 0, v[204:205]
	global_load_dwordx4 v[202:205], v[206:207], off
	s_nop 0
	global_load_dwordx4 v[206:209], v[206:207], off offset:16
	s_nop 0
	global_load_dwordx4 v[210:213], v[214:215], off
	s_nop 0
	global_load_dwordx4 v[214:217], v[214:215], off offset:16
	s_nop 0
	global_load_dwordx4 v[218:221], v[222:223], off
	s_nop 0
	global_load_dwordx4 v[222:225], v[222:223], off offset:16
	s_nop 0
	global_load_dwordx4 v[226:229], v[230:231], off
	s_nop 0
	global_load_dwordx4 v[230:233], v[230:231], off offset:16
	v_mov_b32_e32 v234, 0
	v_mov_b32_e32 v235, 0
	v_mov_b32_e32 v236, 0
	v_mov_b32_e32 v237, 0
	s_lshl_b32 s0, s57, 2
	s_add_i32 s0, s48, s0
	v_mov_b64_e32 v[156:157], s[22:23]
	s_mul_i32 s20, s0, 0xc0
	v_lshl_add_u64 v[158:159], s[20:21], 0, v[154:155]
	v_mad_i64_i32 v[136:137], s[0:1], v136, s52, v[156:157]
	v_lshl_add_u64 v[136:137], v[136:137], 0, v[158:159]
	s_mov_b64 s[34:35], 0
	s_waitcnt vmcnt(0) lgkmcnt(0)
	v_pk_mul_f32 v[240:241], v[120:121], v[172:173]
	v_pk_mul_f32 v[242:243], v[118:119], v[170:171]
	v_pk_mul_f32 v[172:173], v[128:129], v[172:173]
	v_pk_mul_f32 v[246:247], v[110:111], v[174:175]
	v_pk_mul_f32 v[170:171], v[126:127], v[170:171]
	v_pk_mul_f32 v[174:175], v[122:123], v[174:175]
	v_pk_fma_f32 v[240:241], v[128:129], v[180:181], v[240:241] neg_lo:[0,0,1] neg_hi:[0,0,1]
	v_pk_fma_f32 v[242:243], v[126:127], v[178:179], v[242:243] neg_lo:[0,0,1] neg_hi:[0,0,1]
	v_pk_fma_f32 v[172:173], v[120:121], v[180:181], v[172:173]
	v_pk_fma_f32 v[180:181], v[122:123], v[182:183], v[246:247] neg_lo:[0,0,1] neg_hi:[0,0,1]
	v_pk_fma_f32 v[170:171], v[118:119], v[178:179], v[170:171]
	v_pk_fma_f32 v[174:175], v[110:111], v[182:183], v[174:175]
	v_med3_f32 v135, v242, s51, v168
	v_med3_f32 v161, v243, s51, v168
	v_med3_f32 v180, v180, s51, v168
	v_med3_f32 v181, v181, s51, v168
	v_med3_f32 v170, v170, s51, v168
	v_med3_f32 v171, v171, s51, v168
	v_med3_f32 v174, v174, s51, v168
	v_med3_f32 v175, v175, s51, v168
	v_cvt_pk_fp8_f32 v234, v135, v161
	v_cvt_pk_fp8_f32 v235, v180, v181
	v_pk_mul_f32 v[244:245], v[112:113], v[176:177]
	v_cvt_pk_fp8_f32 v236, v170, v171
	v_cvt_pk_fp8_f32 v237, v174, v175
	v_pk_mul_f32 v[176:177], v[124:125], v[176:177]
	v_pk_fma_f32 v[178:179], v[124:125], v[184:185], v[244:245] neg_lo:[0,0,1] neg_hi:[0,0,1]
	v_pk_fma_f32 v[176:177], v[112:113], v[184:185], v[176:177]
	v_med3_f32 v184, v240, s51, v168
	v_med3_f32 v185, v241, s51, v168
	v_med3_f32 v178, v178, s51, v168
	v_med3_f32 v179, v179, s51, v168
	v_med3_f32 v172, v172, s51, v168
	v_med3_f32 v173, v173, s51, v168
	v_med3_f32 v176, v176, s51, v168
	v_med3_f32 v177, v177, s51, v168
	v_cvt_pk_fp8_f32 v234, v184, v185 op_sel:[0,0,1]
	v_cvt_pk_fp8_f32 v235, v178, v179 op_sel:[0,0,1]
	v_cvt_pk_fp8_f32 v236, v172, v173 op_sel:[0,0,1]
	v_cvt_pk_fp8_f32 v237, v176, v177 op_sel:[0,0,1]
	v_pk_mul_f32 v[170:171], v[102:103], v[186:187]
	v_pk_mul_f32 v[182:183], v[104:105], v[188:189]
	global_store_dwordx2 v[136:137], v[234:235], off offset:128
	global_store_dwordx2 v[136:137], v[236:237], off offset:160
	v_pk_fma_f32 v[136:137], v[114:115], v[190:191], v[170:171] neg_lo:[0,0,1] neg_hi:[0,0,1]
	v_pk_mul_f32 v[178:179], v[94:95], v[194:195]
	v_pk_fma_f32 v[172:173], v[116:117], v[192:193], v[182:183] neg_lo:[0,0,1] neg_hi:[0,0,1]
	v_pk_fma_f32 v[178:179], v[106:107], v[198:199], v[178:179] neg_lo:[0,0,1] neg_hi:[0,0,1]
	v_med3_f32 v135, v136, s51, v168
	v_med3_f32 v137, v137, s51, v168
	v_mov_b32_e32 v136, 0
	v_cvt_pk_fp8_f32 v136, v135, v137
	v_med3_f32 v135, v172, s51, v168
	v_med3_f32 v161, v173, s51, v168
	v_med3_f32 v172, v178, s51, v168
	v_med3_f32 v173, v179, s51, v168
	v_mov_b32_e32 v137, 0
	v_cvt_pk_fp8_f32 v137, v172, v173
	v_pk_mul_f32 v[176:177], v[96:97], v[196:197]
	v_pk_mul_f32 v[174:175], v[114:115], v[186:187]
	v_pk_fma_f32 v[176:177], v[108:109], v[200:201], v[176:177] neg_lo:[0,0,1] neg_hi:[0,0,1]
	v_pk_mul_f32 v[170:171], v[116:117], v[188:189]
	v_pk_fma_f32 v[174:175], v[102:103], v[190:191], v[174:175]
	v_pk_mul_f32 v[182:183], v[106:107], v[194:195]
	v_cvt_pk_fp8_f32 v136, v135, v161 op_sel:[0,0,1]
	v_med3_f32 v135, v176, s51, v168
	v_med3_f32 v161, v177, s51, v168
	v_pk_fma_f32 v[170:171], v[104:105], v[192:193], v[170:171]
	v_pk_fma_f32 v[182:183], v[94:95], v[198:199], v[182:183]
	v_cvt_pk_fp8_f32 v137, v135, v161 op_sel:[0,0,1]
	v_med3_f32 v135, v174, s51, v168
	v_med3_f32 v161, v175, s51, v168
	v_mov_b32_e32 v172, 0
	v_cvt_pk_fp8_f32 v172, v135, v161
	v_med3_f32 v135, v170, s51, v168
	v_med3_f32 v161, v171, s51, v168
	v_med3_f32 v170, v182, s51, v168
	v_med3_f32 v171, v183, s51, v168
	v_mov_b32_e32 v173, 0
	v_cvt_pk_fp8_f32 v173, v170, v171
	v_pk_mul_f32 v[180:181], v[108:109], v[196:197]
	v_cvt_pk_fp8_f32 v172, v135, v161 op_sel:[0,0,1]
	v_pk_fma_f32 v[180:181], v[96:97], v[200:201], v[180:181]
	v_pk_mul_f32 v[176:177], v[78:79], v[214:215]
	v_med3_f32 v135, v180, s51, v168
	v_med3_f32 v161, v181, s51, v168
	v_cvt_pk_fp8_f32 v173, v135, v161 op_sel:[0,0,1]
	v_mad_i64_i32 v[160:161], s[0:1], v160, s52, v[156:157]
	v_lshl_add_u64 v[160:161], v[160:161], 0, v[158:159]
	global_store_dwordx2 v[160:161], v[136:137], off offset:128
	global_store_dwordx2 v[160:161], v[172:173], off offset:160
	v_pk_mul_f32 v[160:161], v[86:87], v[210:211]
	v_pk_mul_f32 v[136:137], v[88:89], v[212:213]
	v_pk_fma_f32 v[160:161], v[98:99], v[202:203], v[160:161] neg_lo:[0,0,1] neg_hi:[0,0,1]
	v_pk_fma_f32 v[136:137], v[100:101], v[204:205], v[136:137] neg_lo:[0,0,1] neg_hi:[0,0,1]
	v_pk_fma_f32 v[176:177], v[90:91], v[206:207], v[176:177] neg_lo:[0,0,1] neg_hi:[0,0,1]
	v_med3_f32 v135, v160, s51, v168
	v_med3_f32 v161, v161, s51, v168
	v_mov_b32_e32 v160, 0
	v_cvt_pk_fp8_f32 v160, v135, v161
	v_med3_f32 v135, v136, s51, v168
	v_med3_f32 v136, v137, s51, v168
	v_med3_f32 v137, v176, s51, v168
	v_med3_f32 v176, v177, s51, v168
	v_mov_b32_e32 v161, 0
	v_cvt_pk_fp8_f32 v161, v137, v176
	v_pk_mul_f32 v[174:175], v[80:81], v[216:217]
	v_pk_mul_f32 v[172:173], v[98:99], v[210:211]
	v_pk_fma_f32 v[174:175], v[92:93], v[208:209], v[174:175] neg_lo:[0,0,1] neg_hi:[0,0,1]
	v_pk_mul_f32 v[170:171], v[100:101], v[212:213]
	v_pk_fma_f32 v[172:173], v[86:87], v[202:203], v[172:173]
	v_pk_mul_f32 v[180:181], v[90:91], v[214:215]
	v_cvt_pk_fp8_f32 v160, v135, v136 op_sel:[0,0,1]
	v_med3_f32 v135, v174, s51, v168
	v_med3_f32 v136, v175, s51, v168
	v_pk_fma_f32 v[170:171], v[88:89], v[204:205], v[170:171]
	v_pk_fma_f32 v[180:181], v[78:79], v[206:207], v[180:181]
	v_cvt_pk_fp8_f32 v161, v135, v136 op_sel:[0,0,1]
	v_med3_f32 v135, v172, s51, v168
	v_med3_f32 v137, v173, s51, v168
	v_mov_b32_e32 v136, 0
	v_cvt_pk_fp8_f32 v136, v135, v137
	v_med3_f32 v135, v170, s51, v168
	v_med3_f32 v170, v171, s51, v168
	v_med3_f32 v171, v180, s51, v168
	v_med3_f32 v172, v181, s51, v168
	v_mov_b32_e32 v137, 0
	v_cvt_pk_fp8_f32 v137, v171, v172
	v_pk_mul_f32 v[178:179], v[92:93], v[216:217]
	v_cvt_pk_fp8_f32 v136, v135, v170 op_sel:[0,0,1]
	v_pk_fma_f32 v[178:179], v[80:81], v[208:209], v[178:179]
	v_pk_mul_f32 v[176:177], v[66:67], v[230:231]
	v_med3_f32 v135, v178, s51, v168
	v_med3_f32 v170, v179, s51, v168
	v_cvt_pk_fp8_f32 v137, v135, v170 op_sel:[0,0,1]
	v_mad_i64_i32 v[170:171], s[0:1], v238, s52, v[156:157]
	v_lshl_add_u64 v[170:171], v[170:171], 0, v[158:159]
	global_store_dwordx2 v[170:171], v[160:161], off offset:128
	global_store_dwordx2 v[170:171], v[136:137], off offset:160
	v_pk_mul_f32 v[160:161], v[70:71], v[226:227]
	v_pk_mul_f32 v[136:137], v[72:73], v[228:229]
	v_pk_fma_f32 v[160:161], v[82:83], v[218:219], v[160:161] neg_lo:[0,0,1] neg_hi:[0,0,1]
	v_pk_fma_f32 v[136:137], v[84:85], v[220:221], v[136:137] neg_lo:[0,0,1] neg_hi:[0,0,1]
	v_pk_fma_f32 v[176:177], v[74:75], v[222:223], v[176:177] neg_lo:[0,0,1] neg_hi:[0,0,1]
	v_med3_f32 v135, v160, s51, v168
	v_med3_f32 v161, v161, s51, v168
	v_mov_b32_e32 v160, 0
	v_cvt_pk_fp8_f32 v160, v135, v161
	v_med3_f32 v135, v136, s51, v168
	v_med3_f32 v136, v137, s51, v168
	v_med3_f32 v137, v176, s51, v168
	v_med3_f32 v176, v177, s51, v168
	v_mov_b32_e32 v161, 0
	v_cvt_pk_fp8_f32 v161, v137, v176
	v_pk_mul_f32 v[174:175], v[68:69], v[232:233]
	v_pk_mul_f32 v[172:173], v[82:83], v[226:227]
	v_pk_fma_f32 v[174:175], v[76:77], v[224:225], v[174:175] neg_lo:[0,0,1] neg_hi:[0,0,1]
	v_pk_mul_f32 v[170:171], v[84:85], v[228:229]
	v_pk_fma_f32 v[172:173], v[70:71], v[218:219], v[172:173]
	v_pk_mul_f32 v[180:181], v[74:75], v[230:231]
	v_cvt_pk_fp8_f32 v160, v135, v136 op_sel:[0,0,1]
	v_med3_f32 v135, v174, s51, v168
	v_med3_f32 v136, v175, s51, v168
	v_pk_fma_f32 v[170:171], v[72:73], v[220:221], v[170:171]
	v_pk_fma_f32 v[180:181], v[66:67], v[222:223], v[180:181]
	v_cvt_pk_fp8_f32 v161, v135, v136 op_sel:[0,0,1]
	v_med3_f32 v135, v172, s51, v168
	v_med3_f32 v137, v173, s51, v168
	v_mov_b32_e32 v136, 0
	v_cvt_pk_fp8_f32 v136, v135, v137
	v_med3_f32 v135, v170, s51, v168
	v_med3_f32 v170, v171, s51, v168
	v_med3_f32 v171, v180, s51, v168
	v_med3_f32 v172, v181, s51, v168
	v_mov_b32_e32 v137, 0
	v_cvt_pk_fp8_f32 v137, v171, v172
	v_pk_mul_f32 v[178:179], v[76:77], v[232:233]
	v_cvt_pk_fp8_f32 v136, v135, v170 op_sel:[0,0,1]
	v_pk_fma_f32 v[178:179], v[68:69], v[224:225], v[178:179]
	v_add_u32_e32 v226, 0x80, v248
	v_med3_f32 v135, v178, s51, v168
	v_med3_f32 v170, v179, s51, v168
	v_cvt_pk_fp8_f32 v137, v135, v170 op_sel:[0,0,1]
	v_mad_i64_i32 v[134:135], s[0:1], v134, s52, v[156:157]
	v_lshl_add_u64 v[134:135], v[134:135], 0, v[158:159]
	global_store_dwordx2 v[134:135], v[160:161], off offset:128
	global_store_dwordx2 v[134:135], v[136:137], off offset:160
	s_nop 0
	v_ashrrev_i32_e32 v227, 31, v226
	v_lshlrev_b64 v[134:135], 7, v[226:227]
	v_lshl_add_u64 v[136:137], v[130:131], 0, v[134:135]
	global_load_dwordx4 v[170:173], v[136:137], off
	v_lshl_add_u64 v[134:135], v[132:133], 0, v[134:135]
	global_load_dwordx4 v[174:177], v[134:135], off
	global_load_dwordx4 v[178:181], v[136:137], off offset:16
	global_load_dwordx4 v[182:185], v[134:135], off offset:16
	v_add_u32_e32 v228, 16, v226
	v_ashrrev_i32_e32 v229, 31, v228
	v_lshlrev_b64 v[134:135], 7, v[228:229]
	v_lshl_add_u64 v[136:137], v[130:131], 0, v[134:135]
	global_load_dwordx4 v[186:189], v[136:137], off
	v_lshl_add_u64 v[134:135], v[132:133], 0, v[134:135]
	global_load_dwordx4 v[190:193], v[134:135], off
	global_load_dwordx4 v[194:197], v[136:137], off offset:16
	global_load_dwordx4 v[198:201], v[134:135], off offset:16
	v_add_u32_e32 v230, 32, v226
	v_ashrrev_i32_e32 v231, 31, v230
	v_lshlrev_b64 v[134:135], 7, v[230:231]
	v_lshl_add_u64 v[136:137], v[132:133], 0, v[134:135]
	v_lshl_add_u64 v[134:135], v[130:131], 0, v[134:135]
	global_load_dwordx4 v[202:205], v[136:137], off
	global_load_dwordx4 v[206:209], v[136:137], off offset:16
	global_load_dwordx4 v[210:213], v[134:135], off
	global_load_dwordx4 v[214:217], v[134:135], off offset:16
	v_add_u32_e32 v160, 48, v226
	v_ashrrev_i32_e32 v161, 31, v160
	v_lshlrev_b64 v[134:135], 7, v[160:161]
	v_lshl_add_u64 v[132:133], v[132:133], 0, v[134:135]
	v_lshl_add_u64 v[134:135], v[130:131], 0, v[134:135]
	global_load_dwordx4 v[218:221], v[132:133], off
	s_nop 0
	global_load_dwordx4 v[130:133], v[132:133], off offset:16
	s_nop 0
	global_load_dwordx4 v[222:225], v[134:135], off
	s_nop 0
	global_load_dwordx4 v[134:137], v[134:135], off offset:16
	s_waitcnt vmcnt(0) lgkmcnt(0)
	v_pk_mul_f32 v[232:233], v[56:57], v[172:173]
	v_pk_mul_f32 v[234:235], v[54:55], v[170:171]
	v_pk_mul_f32 v[172:173], v[64:65], v[172:173]
	v_pk_fma_f32 v[232:233], v[64:65], v[176:177], v[232:233] neg_lo:[0,0,1] neg_hi:[0,0,1]
	v_pk_fma_f32 v[234:235], v[62:63], v[174:175], v[234:235] neg_lo:[0,0,1] neg_hi:[0,0,1]
	v_pk_fma_f32 v[172:173], v[56:57], v[176:177], v[172:173]
	v_pk_mul_f32 v[176:177], v[46:47], v[178:179]
	v_pk_mul_f32 v[178:179], v[58:59], v[178:179]
	v_pk_fma_f32 v[176:177], v[58:59], v[182:183], v[176:177] neg_lo:[0,0,1] neg_hi:[0,0,1]
	v_pk_fma_f32 v[178:179], v[46:47], v[182:183], v[178:179]
	v_med3_f32 v161, v234, s51, v168
	v_med3_f32 v183, v235, s51, v168
	v_mov_b32_e32 v182, 0
	v_cvt_pk_fp8_f32 v182, v161, v183
	v_med3_f32 v176, v176, s51, v168
	v_med3_f32 v177, v177, s51, v168
	v_mov_b32_e32 v183, 0
	v_pk_mul_f32 v[170:171], v[62:63], v[170:171]
	v_cvt_pk_fp8_f32 v183, v176, v177
	v_pk_fma_f32 v[170:171], v[54:55], v[174:175], v[170:171]
	v_pk_mul_f32 v[174:175], v[48:49], v[180:181]
	v_pk_mul_f32 v[180:181], v[60:61], v[180:181]
	v_pk_fma_f32 v[174:175], v[60:61], v[184:185], v[174:175] neg_lo:[0,0,1] neg_hi:[0,0,1]
	v_pk_fma_f32 v[180:181], v[48:49], v[184:185], v[180:181]
	v_med3_f32 v161, v232, s51, v168
	v_med3_f32 v184, v233, s51, v168
	v_cvt_pk_fp8_f32 v182, v161, v184 op_sel:[0,0,1]
	v_med3_f32 v161, v174, s51, v168
	v_med3_f32 v174, v175, s51, v168
	v_cvt_pk_fp8_f32 v183, v161, v174 op_sel:[0,0,1]
	v_med3_f32 v161, v170, s51, v168
	v_med3_f32 v171, v171, s51, v168
	v_mov_b32_e32 v170, 0
	v_cvt_pk_fp8_f32 v170, v161, v171
	v_med3_f32 v161, v172, s51, v168
	v_med3_f32 v172, v173, s51, v168
	v_med3_f32 v173, v178, s51, v168
	v_med3_f32 v174, v179, s51, v168
	v_mov_b32_e32 v171, 0
	v_cvt_pk_fp8_f32 v171, v173, v174
	v_cvt_pk_fp8_f32 v170, v161, v172 op_sel:[0,0,1]
	v_med3_f32 v161, v180, s51, v168
	v_med3_f32 v172, v181, s51, v168
	v_cvt_pk_fp8_f32 v171, v161, v172 op_sel:[0,0,1]
	v_mad_i64_i32 v[172:173], s[0:1], v226, s52, v[156:157]
	v_lshl_add_u64 v[172:173], v[172:173], 0, v[158:159]
	global_store_dwordx2 v[172:173], v[182:183], off offset:128
	global_store_dwordx2 v[172:173], v[170:171], off offset:160
	v_pk_mul_f32 v[172:173], v[38:39], v[186:187]
	v_pk_mul_f32 v[170:171], v[40:41], v[188:189]
	v_pk_fma_f32 v[172:173], v[50:51], v[190:191], v[172:173] neg_lo:[0,0,1] neg_hi:[0,0,1]
	v_pk_mul_f32 v[180:181], v[30:31], v[194:195]
	v_pk_fma_f32 v[170:171], v[52:53], v[192:193], v[170:171] neg_lo:[0,0,1] neg_hi:[0,0,1]
	v_pk_fma_f32 v[180:181], v[42:43], v[198:199], v[180:181] neg_lo:[0,0,1] neg_hi:[0,0,1]
	v_med3_f32 v161, v172, s51, v168
	v_med3_f32 v173, v173, s51, v168
	v_mov_b32_e32 v172, 0
	v_cvt_pk_fp8_f32 v172, v161, v173
	v_med3_f32 v161, v170, s51, v168
	v_med3_f32 v170, v171, s51, v168
	v_med3_f32 v171, v180, s51, v168
	v_med3_f32 v180, v181, s51, v168
	v_mov_b32_e32 v173, 0
	v_cvt_pk_fp8_f32 v173, v171, v180
	v_pk_mul_f32 v[178:179], v[32:33], v[196:197]
	v_pk_mul_f32 v[176:177], v[50:51], v[186:187]
	v_pk_fma_f32 v[178:179], v[44:45], v[200:201], v[178:179] neg_lo:[0,0,1] neg_hi:[0,0,1]
	v_pk_mul_f32 v[174:175], v[52:53], v[188:189]
	v_pk_fma_f32 v[176:177], v[38:39], v[190:191], v[176:177]
	v_pk_mul_f32 v[184:185], v[42:43], v[194:195]
	v_cvt_pk_fp8_f32 v172, v161, v170 op_sel:[0,0,1]
	v_med3_f32 v161, v178, s51, v168
	v_med3_f32 v170, v179, s51, v168
	v_pk_fma_f32 v[174:175], v[40:41], v[192:193], v[174:175]
	v_pk_fma_f32 v[184:185], v[30:31], v[198:199], v[184:185]
	v_cvt_pk_fp8_f32 v173, v161, v170 op_sel:[0,0,1]
	v_med3_f32 v161, v176, s51, v168
	v_med3_f32 v171, v177, s51, v168
	v_mov_b32_e32 v170, 0
	v_cvt_pk_fp8_f32 v170, v161, v171
	v_med3_f32 v161, v174, s51, v168
	v_med3_f32 v174, v175, s51, v168
	v_med3_f32 v175, v184, s51, v168
	v_med3_f32 v176, v185, s51, v168
	v_mov_b32_e32 v171, 0
	v_cvt_pk_fp8_f32 v171, v175, v176
	v_pk_mul_f32 v[182:183], v[44:45], v[196:197]
	v_cvt_pk_fp8_f32 v170, v161, v174 op_sel:[0,0,1]
	v_pk_fma_f32 v[182:183], v[32:33], v[200:201], v[182:183]
	v_pk_mul_f32 v[180:181], v[14:15], v[214:215]
	v_med3_f32 v161, v182, s51, v168
	v_med3_f32 v174, v183, s51, v168
	v_cvt_pk_fp8_f32 v171, v161, v174 op_sel:[0,0,1]
	v_mad_i64_i32 v[174:175], s[0:1], v228, s52, v[156:157]
	v_lshl_add_u64 v[174:175], v[174:175], 0, v[158:159]
	global_store_dwordx2 v[174:175], v[172:173], off offset:128
	global_store_dwordx2 v[174:175], v[170:171], off offset:160
	v_pk_mul_f32 v[172:173], v[22:23], v[210:211]
	v_pk_mul_f32 v[170:171], v[24:25], v[212:213]
	v_pk_fma_f32 v[172:173], v[34:35], v[202:203], v[172:173] neg_lo:[0,0,1] neg_hi:[0,0,1]
	v_pk_fma_f32 v[170:171], v[36:37], v[204:205], v[170:171] neg_lo:[0,0,1] neg_hi:[0,0,1]
	v_pk_fma_f32 v[180:181], v[26:27], v[206:207], v[180:181] neg_lo:[0,0,1] neg_hi:[0,0,1]
	v_med3_f32 v161, v172, s51, v168
	v_med3_f32 v173, v173, s51, v168
	v_mov_b32_e32 v172, 0
	v_cvt_pk_fp8_f32 v172, v161, v173
	v_med3_f32 v161, v170, s51, v168
	v_med3_f32 v170, v171, s51, v168
	v_med3_f32 v171, v180, s51, v168
	v_med3_f32 v180, v181, s51, v168
	v_mov_b32_e32 v173, 0
	v_cvt_pk_fp8_f32 v173, v171, v180
	v_pk_mul_f32 v[178:179], v[16:17], v[216:217]
	v_pk_mul_f32 v[176:177], v[34:35], v[210:211]
	v_pk_fma_f32 v[178:179], v[28:29], v[208:209], v[178:179] neg_lo:[0,0,1] neg_hi:[0,0,1]
	v_pk_mul_f32 v[174:175], v[36:37], v[212:213]
	v_pk_fma_f32 v[176:177], v[22:23], v[202:203], v[176:177]
	v_pk_mul_f32 v[184:185], v[26:27], v[214:215]
	v_cvt_pk_fp8_f32 v172, v161, v170 op_sel:[0,0,1]
	v_med3_f32 v161, v178, s51, v168
	v_med3_f32 v170, v179, s51, v168
	v_pk_fma_f32 v[174:175], v[24:25], v[204:205], v[174:175]
	v_pk_fma_f32 v[184:185], v[14:15], v[206:207], v[184:185]
	v_cvt_pk_fp8_f32 v173, v161, v170 op_sel:[0,0,1]
	v_med3_f32 v161, v176, s51, v168
	v_med3_f32 v171, v177, s51, v168
	v_mov_b32_e32 v170, 0
	v_cvt_pk_fp8_f32 v170, v161, v171
	v_med3_f32 v161, v174, s51, v168
	v_med3_f32 v174, v175, s51, v168
	v_med3_f32 v175, v184, s51, v168
	v_med3_f32 v176, v185, s51, v168
	v_mov_b32_e32 v171, 0
	v_cvt_pk_fp8_f32 v171, v175, v176
	v_pk_mul_f32 v[182:183], v[28:29], v[216:217]
	v_cvt_pk_fp8_f32 v170, v161, v174 op_sel:[0,0,1]
	v_pk_fma_f32 v[182:183], v[16:17], v[208:209], v[182:183]
	v_pk_mul_f32 v[178:179], v[4:5], v[136:137]
	v_med3_f32 v161, v182, s51, v168
	v_med3_f32 v174, v183, s51, v168
	v_cvt_pk_fp8_f32 v171, v161, v174 op_sel:[0,0,1]
	v_mad_i64_i32 v[174:175], s[0:1], v230, s52, v[156:157]
	v_lshl_add_u64 v[174:175], v[174:175], 0, v[158:159]
	global_store_dwordx2 v[174:175], v[172:173], off offset:128
	global_store_dwordx2 v[174:175], v[170:171], off offset:160
	v_pk_mul_f32 v[172:173], v[6:7], v[222:223]
	v_pk_mul_f32 v[170:171], v[8:9], v[224:225]
	v_pk_fma_f32 v[172:173], v[18:19], v[218:219], v[172:173] neg_lo:[0,0,1] neg_hi:[0,0,1]
	v_pk_mul_f32 v[180:181], v[2:3], v[134:135]
	v_pk_mul_f32 v[136:137], v[12:13], v[136:137]
	v_pk_mul_f32 v[134:135], v[10:11], v[134:135]
	v_pk_fma_f32 v[170:171], v[20:21], v[220:221], v[170:171] neg_lo:[0,0,1] neg_hi:[0,0,1]
	v_pk_fma_f32 v[178:179], v[12:13], v[132:133], v[178:179] neg_lo:[0,0,1] neg_hi:[0,0,1]
	v_pk_fma_f32 v[180:181], v[10:11], v[130:131], v[180:181] neg_lo:[0,0,1] neg_hi:[0,0,1]
	v_pk_fma_f32 v[132:133], v[4:5], v[132:133], v[136:137]
	v_pk_fma_f32 v[130:131], v[2:3], v[130:131], v[134:135]
	v_med3_f32 v135, v172, s51, v168
	v_med3_f32 v136, v173, s51, v168
	v_mov_b32_e32 v134, 0
	v_cvt_pk_fp8_f32 v134, v135, v136
	v_med3_f32 v136, v170, s51, v168
	v_med3_f32 v161, v180, s51, v168
	v_med3_f32 v170, v181, s51, v168
	v_mov_b32_e32 v135, 0
	v_cvt_pk_fp8_f32 v135, v161, v170
	v_pk_mul_f32 v[176:177], v[18:19], v[222:223]
	v_med3_f32 v137, v171, s51, v168
	v_pk_fma_f32 v[176:177], v[6:7], v[218:219], v[176:177]
	v_cvt_pk_fp8_f32 v134, v136, v137 op_sel:[0,0,1]
	v_med3_f32 v136, v178, s51, v168
	v_med3_f32 v137, v179, s51, v168
	v_cvt_pk_fp8_f32 v135, v136, v137 op_sel:[0,0,1]
	v_med3_f32 v137, v176, s51, v168
	v_med3_f32 v161, v177, s51, v168
	v_mov_b32_e32 v136, 0
	v_cvt_pk_fp8_f32 v136, v137, v161
	v_med3_f32 v130, v130, s51, v168
	v_med3_f32 v131, v131, s51, v168
	v_mov_b32_e32 v137, 0
	v_cvt_pk_fp8_f32 v137, v130, v131
	v_pk_mul_f32 v[174:175], v[20:21], v[224:225]
	v_med3_f32 v130, v132, s51, v168
	v_pk_fma_f32 v[174:175], v[8:9], v[220:221], v[174:175]
	v_med3_f32 v131, v133, s51, v168
	v_med3_f32 v161, v174, s51, v168
	v_med3_f32 v170, v175, s51, v168
	v_cvt_pk_fp8_f32 v136, v161, v170 op_sel:[0,0,1]
	v_cvt_pk_fp8_f32 v137, v130, v131 op_sel:[0,0,1]
	v_mad_i64_i32 v[130:131], s[0:1], v160, s52, v[156:157]
	v_lshl_add_u64 v[130:131], v[130:131], 0, v[158:159]
	global_store_dwordx2 v[130:131], v[134:135], off offset:128
	global_store_dwordx2 v[130:131], v[136:137], off offset:160

.LBB0_2344:
	s_add_u32 s39, s30, s38
	s_addc_u32 s40, s31, 0
	s_add_u32 s41, s39, 0x100
	s_addc_u32 s42, s40, 0
	s_and_b64 s[0:1], s[36:37], exec
	s_cselect_b32 s43, s21, s42
	s_cselect_b32 s42, s62, s41
	s_add_u32 s0, s28, s38
	s_addc_u32 s1, s29, 0
	s_add_u32 s38, s0, 0x100
	s_addc_u32 s41, s1, 0
	s_and_b64 s[0:1], s[36:37], exec
	s_cselect_b32 s45, s19, s41
	s_cselect_b32 s44, s63, s38
	s_add_u32 s46, s39, 0x10080
	s_addc_u32 s47, s40, 0
	s_add_i32 s70, s58, s9
	s_add_i32 m0, s27, 0xc000
	s_add_i32 s71, s27, 0xe000
	s_add_i32 s0, s70, 0x2000
	s_add_u32 s40, s44, 0x10000
	s_addc_u32 s41, s45, 0
	s_add_i32 s77, s59, s9
	ds_read_b128 v[152:155], v147
	ds_read_b128 v[156:159], v147 offset:1024
	ds_read_b128 v[160:163], v147 offset:2048
	ds_read_b128 v[164:167], v147 offset:3072
	s_add_i32 s1, s77, 0x2000
	s_add_i32 s73, 0, 0x18000
	s_add_u32 s38, s42, 0x10000
	s_addc_u32 s39, s43, 0
	s_add_i32 s72, s73, s9
	s_add_i32 s69, 0, 0x1c000
	s_add_i32 s67, s72, 0x2000
	s_add_u32 s36, s44, 0x10080
	s_addc_u32 s37, s45, 0
	s_add_i32 s65, s69, s9
	s_add_i32 s64, s65, 0x2000
	v_lshl_add_u64 v[142:143], s[46:47], 0, v[136:137]
	ds_read_b128 v[168:171], v148
	ds_read_b128 v[172:175], v148 offset:1024
	ds_read_b128 v[176:179], v148 offset:2048
	ds_read_b128 v[180:183], v148 offset:3072
	ds_read_b128 v[184:187], v148 offset:4096
	ds_read_b128 v[188:191], v148 offset:5120
	ds_read_b128 v[192:195], v148 offset:6144
	ds_read_b128 v[196:199], v148 offset:7168
	global_load_lds_dwordx4 v[142:143], off
	v_lshl_add_u64 v[142:143], s[46:47], 0, v[132:133]
	s_mov_b32 m0, s71
	s_nop 0
	global_load_lds_dwordx4 v[142:143], off
	s_waitcnt lgkmcnt(8)
	s_waitcnt vmcnt(10)
	s_barrier
	s_waitcnt lgkmcnt(0)
	v_mfma_f32_16x16x32_bf16 v[126:129], v[152:155], v[168:171], v[126:129]
	v_mfma_f32_16x16x32_bf16 v[122:125], v[160:163], v[168:171], v[122:125]
	v_mfma_f32_16x16x32_bf16 v[110:113], v[152:155], v[176:179], v[110:113]
	v_mfma_f32_16x16x32_bf16 v[106:109], v[160:163], v[176:179], v[106:109]
	v_mfma_f32_16x16x32_bf16 v[94:97], v[152:155], v[184:187], v[94:97]
	v_mfma_f32_16x16x32_bf16 v[90:93], v[160:163], v[184:187], v[90:93]
	v_mfma_f32_16x16x32_bf16 v[78:81], v[152:155], v[192:195], v[78:81]
	v_mfma_f32_16x16x32_bf16 v[74:77], v[160:163], v[192:195], v[74:77]
	v_mfma_f32_16x16x32_bf16 v[126:129], v[156:159], v[172:175], v[126:129]
	v_mfma_f32_16x16x32_bf16 v[122:125], v[164:167], v[172:175], v[122:125]
	v_mfma_f32_16x16x32_bf16 v[110:113], v[156:159], v[180:183], v[110:113]
	v_mfma_f32_16x16x32_bf16 v[106:109], v[164:167], v[180:183], v[106:109]
	v_mfma_f32_16x16x32_bf16 v[94:97], v[156:159], v[188:191], v[94:97]
	v_mfma_f32_16x16x32_bf16 v[90:93], v[164:167], v[188:191], v[90:93]
	v_mfma_f32_16x16x32_bf16 v[78:81], v[156:159], v[196:199], v[78:81]
	v_mfma_f32_16x16x32_bf16 v[74:77], v[164:167], v[196:199], v[74:77]
	s_barrier
	s_mov_b32 m0, s70
	v_lshl_add_u64 v[142:143], s[44:45], 0, v[134:135]
	ds_read_b128 v[200:203], v149
	ds_read_b128 v[204:207], v149 offset:1024
	ds_read_b128 v[208:211], v149 offset:2048
	ds_read_b128 v[212:215], v149 offset:3072
	global_load_lds_dwordx4 v[142:143], off
	v_lshl_add_u64 v[216:217], s[44:45], 0, v[130:131]
	s_mov_b32 m0, s0
	s_nop 0
	global_load_lds_dwordx4 v[216:217], off
	s_waitcnt vmcnt(10)
	s_barrier
	s_waitcnt lgkmcnt(0)
	v_mfma_f32_16x16x32_bf16 v[118:121], v[200:203], v[168:171], v[118:121]
	v_mfma_f32_16x16x32_bf16 v[114:117], v[208:211], v[168:171], v[114:117]
	v_mfma_f32_16x16x32_bf16 v[102:105], v[200:203], v[176:179], v[102:105]
	v_mfma_f32_16x16x32_bf16 v[98:101], v[208:211], v[176:179], v[98:101]
	v_mfma_f32_16x16x32_bf16 v[86:89], v[200:203], v[184:187], v[86:89]
	v_mfma_f32_16x16x32_bf16 v[82:85], v[208:211], v[184:187], v[82:85]
	v_mfma_f32_16x16x32_bf16 v[70:73], v[200:203], v[192:195], v[70:73]
	v_mfma_f32_16x16x32_bf16 v[66:69], v[208:211], v[192:195], v[66:69]
	v_mfma_f32_16x16x32_bf16 v[118:121], v[204:207], v[172:175], v[118:121]
	v_mfma_f32_16x16x32_bf16 v[114:117], v[212:215], v[172:175], v[114:117]
	v_mfma_f32_16x16x32_bf16 v[102:105], v[204:207], v[180:183], v[102:105]
	v_mfma_f32_16x16x32_bf16 v[98:101], v[212:215], v[180:183], v[98:101]
	v_mfma_f32_16x16x32_bf16 v[86:89], v[204:207], v[188:191], v[86:89]
	v_mfma_f32_16x16x32_bf16 v[82:85], v[212:215], v[188:191], v[82:85]
	v_mfma_f32_16x16x32_bf16 v[70:73], v[204:207], v[196:199], v[70:73]
	v_mfma_f32_16x16x32_bf16 v[66:69], v[212:215], v[196:199], v[66:69]
	s_mov_b32 m0, s27
	v_lshl_add_u64 v[218:219], s[42:43], 0, v[136:137]
	s_barrier
	ds_read_b128 v[168:171], v148 offset:16384
	ds_read_b128 v[172:175], v148 offset:17408
	ds_read_b128 v[176:179], v148 offset:18432
	ds_read_b128 v[180:183], v148 offset:19456
	ds_read_b128 v[184:187], v148 offset:20480
	ds_read_b128 v[188:191], v148 offset:21504
	ds_read_b128 v[192:195], v148 offset:22528
	ds_read_b128 v[196:199], v148 offset:23552
	global_load_lds_dwordx4 v[218:219], off
	v_lshl_add_u64 v[220:221], s[42:43], 0, v[132:133]
	s_mov_b32 m0, s48
	s_nop 0
	global_load_lds_dwordx4 v[220:221], off
	s_waitcnt vmcnt(10)
	s_barrier
	s_waitcnt lgkmcnt(0)
	v_mfma_f32_16x16x32_bf16 v[62:65], v[152:155], v[168:171], v[62:65]
	v_mfma_f32_16x16x32_bf16 v[58:61], v[160:163], v[168:171], v[58:61]
	v_mfma_f32_16x16x32_bf16 v[46:49], v[152:155], v[176:179], v[46:49]
	v_mfma_f32_16x16x32_bf16 v[42:45], v[160:163], v[176:179], v[42:45]
	v_mfma_f32_16x16x32_bf16 v[30:33], v[152:155], v[184:187], v[30:33]
	v_mfma_f32_16x16x32_bf16 v[26:29], v[160:163], v[184:187], v[26:29]
	v_mfma_f32_16x16x32_bf16 v[14:17], v[152:155], v[192:195], v[14:17]
	v_mfma_f32_16x16x32_bf16 v[10:13], v[160:163], v[192:195], v[10:13]
	v_mfma_f32_16x16x32_bf16 v[62:65], v[156:159], v[172:175], v[62:65]
	v_mfma_f32_16x16x32_bf16 v[58:61], v[164:167], v[172:175], v[58:61]
	v_mfma_f32_16x16x32_bf16 v[46:49], v[156:159], v[180:183], v[46:49]
	v_mfma_f32_16x16x32_bf16 v[42:45], v[164:167], v[180:183], v[42:45]
	v_mfma_f32_16x16x32_bf16 v[30:33], v[156:159], v[188:191], v[30:33]
	v_mfma_f32_16x16x32_bf16 v[26:29], v[164:167], v[188:191], v[26:29]
	v_mfma_f32_16x16x32_bf16 v[14:17], v[156:159], v[196:199], v[14:17]
	v_mfma_f32_16x16x32_bf16 v[10:13], v[164:167], v[196:199], v[10:13]
	s_barrier
	s_mov_b32 m0, s77
	v_lshl_add_u64 v[152:153], s[40:41], 0, v[134:135]
	global_load_lds_dwordx4 v[152:153], off
	v_lshl_add_u64 v[152:153], s[40:41], 0, v[130:131]
	s_mov_b32 m0, s1
	s_nop 0
	global_load_lds_dwordx4 v[152:153], off
	s_waitcnt vmcnt(10)
	s_barrier
	v_mfma_f32_16x16x32_bf16 v[54:57], v[200:203], v[168:171], v[54:57]
	v_mfma_f32_16x16x32_bf16 v[50:53], v[208:211], v[168:171], v[50:53]
	v_mfma_f32_16x16x32_bf16 v[38:41], v[200:203], v[176:179], v[38:41]
	v_mfma_f32_16x16x32_bf16 v[34:37], v[208:211], v[176:179], v[34:37]
	v_mfma_f32_16x16x32_bf16 v[22:25], v[200:203], v[184:187], v[22:25]
	v_mfma_f32_16x16x32_bf16 v[18:21], v[208:211], v[184:187], v[18:21]
	v_mfma_f32_16x16x32_bf16 v[6:9], v[200:203], v[192:195], v[6:9]
	v_mfma_f32_16x16x32_bf16 v[2:5], v[208:211], v[192:195], v[2:5]
	v_mfma_f32_16x16x32_bf16 v[54:57], v[204:207], v[172:175], v[54:57]
	v_mfma_f32_16x16x32_bf16 v[50:53], v[212:215], v[172:175], v[50:53]
	v_mfma_f32_16x16x32_bf16 v[38:41], v[204:207], v[180:183], v[38:41]
	v_mfma_f32_16x16x32_bf16 v[34:37], v[212:215], v[180:183], v[34:37]
	v_mfma_f32_16x16x32_bf16 v[22:25], v[204:207], v[188:191], v[22:25]
	v_mfma_f32_16x16x32_bf16 v[18:21], v[212:215], v[188:191], v[18:21]
	v_mfma_f32_16x16x32_bf16 v[6:9], v[204:207], v[196:199], v[6:9]
	v_mfma_f32_16x16x32_bf16 v[2:5], v[212:215], v[196:199], v[2:5]
	v_add_u32_e32 v151, s73, v146
	s_barrier
	ds_read_b128 v[152:155], v151
	ds_read_b128 v[156:159], v151 offset:1024
	ds_read_b128 v[160:163], v151 offset:2048
	ds_read_b128 v[164:167], v151 offset:3072
	s_mov_b32 m0, s49
	v_lshl_add_u64 v[200:201], s[38:39], 0, v[136:137]
	ds_read_b128 v[168:171], v148 offset:32768
	ds_read_b128 v[172:175], v148 offset:33792
	ds_read_b128 v[176:179], v148 offset:34816
	ds_read_b128 v[180:183], v148 offset:35840
	ds_read_b128 v[184:187], v148 offset:36864
	ds_read_b128 v[188:191], v148 offset:37888
	ds_read_b128 v[192:195], v148 offset:38912
	ds_read_b128 v[196:199], v148 offset:39936
	global_load_lds_dwordx4 v[200:201], off
	v_lshl_add_u64 v[200:201], s[38:39], 0, v[132:133]
	s_mov_b32 m0, s50
	s_nop 0
	global_load_lds_dwordx4 v[200:201], off
	s_waitcnt lgkmcnt(8)
	s_waitcnt vmcnt(10)
	s_barrier
	s_waitcnt lgkmcnt(0)
	v_mfma_f32_16x16x32_bf16 v[126:129], v[152:155], v[168:171], v[126:129]
	v_mfma_f32_16x16x32_bf16 v[122:125], v[160:163], v[168:171], v[122:125]
	v_mfma_f32_16x16x32_bf16 v[110:113], v[152:155], v[176:179], v[110:113]
	v_mfma_f32_16x16x32_bf16 v[106:109], v[160:163], v[176:179], v[106:109]
	v_mfma_f32_16x16x32_bf16 v[94:97], v[152:155], v[184:187], v[94:97]
	v_mfma_f32_16x16x32_bf16 v[90:93], v[160:163], v[184:187], v[90:93]
	v_mfma_f32_16x16x32_bf16 v[78:81], v[152:155], v[192:195], v[78:81]
	v_mfma_f32_16x16x32_bf16 v[74:77], v[160:163], v[192:195], v[74:77]
	v_mfma_f32_16x16x32_bf16 v[126:129], v[156:159], v[172:175], v[126:129]
	v_mfma_f32_16x16x32_bf16 v[122:125], v[164:167], v[172:175], v[122:125]
	v_mfma_f32_16x16x32_bf16 v[110:113], v[156:159], v[180:183], v[110:113]
	v_mfma_f32_16x16x32_bf16 v[106:109], v[164:167], v[180:183], v[106:109]
	v_mfma_f32_16x16x32_bf16 v[94:97], v[156:159], v[188:191], v[94:97]
	v_mfma_f32_16x16x32_bf16 v[90:93], v[164:167], v[188:191], v[90:93]
	v_mfma_f32_16x16x32_bf16 v[78:81], v[156:159], v[196:199], v[78:81]
	v_mfma_f32_16x16x32_bf16 v[74:77], v[164:167], v[196:199], v[74:77]
	s_barrier
	s_mov_b32 m0, s72
	v_add_u32_e32 v151, s69, v146
	v_lshl_add_u64 v[142:143], v[142:143], 0, s[16:17]
	ds_read_b128 v[200:203], v151
	ds_read_b128 v[204:207], v151 offset:1024
	ds_read_b128 v[208:211], v151 offset:2048
	ds_read_b128 v[212:215], v151 offset:3072
	global_load_lds_dwordx4 v[142:143], off
	v_lshl_add_u64 v[142:143], v[216:217], 0, s[16:17]
	s_mov_b32 m0, s67
	s_nop 0
	global_load_lds_dwordx4 v[142:143], off
	s_waitcnt vmcnt(10)
	s_barrier
	s_waitcnt lgkmcnt(0)
	v_mfma_f32_16x16x32_bf16 v[118:121], v[200:203], v[168:171], v[118:121]
	v_mfma_f32_16x16x32_bf16 v[114:117], v[208:211], v[168:171], v[114:117]
	v_mfma_f32_16x16x32_bf16 v[102:105], v[200:203], v[176:179], v[102:105]
	v_mfma_f32_16x16x32_bf16 v[98:101], v[208:211], v[176:179], v[98:101]
	v_mfma_f32_16x16x32_bf16 v[86:89], v[200:203], v[184:187], v[86:89]
	v_mfma_f32_16x16x32_bf16 v[82:85], v[208:211], v[184:187], v[82:85]
	v_mfma_f32_16x16x32_bf16 v[70:73], v[200:203], v[192:195], v[70:73]
	v_mfma_f32_16x16x32_bf16 v[66:69], v[208:211], v[192:195], v[66:69]
	v_mfma_f32_16x16x32_bf16 v[118:121], v[204:207], v[172:175], v[118:121]
	v_mfma_f32_16x16x32_bf16 v[114:117], v[212:215], v[172:175], v[114:117]
	v_mfma_f32_16x16x32_bf16 v[102:105], v[204:207], v[180:183], v[102:105]
	v_mfma_f32_16x16x32_bf16 v[98:101], v[212:215], v[180:183], v[98:101]
	v_mfma_f32_16x16x32_bf16 v[86:89], v[204:207], v[188:191], v[86:89]
	v_mfma_f32_16x16x32_bf16 v[82:85], v[212:215], v[188:191], v[82:85]
	v_mfma_f32_16x16x32_bf16 v[70:73], v[204:207], v[196:199], v[70:73]
	v_mfma_f32_16x16x32_bf16 v[66:69], v[212:215], v[196:199], v[66:69]
	s_mov_b32 m0, s56
	v_lshl_add_u64 v[142:143], v[218:219], 0, s[16:17]
	s_barrier
	ds_read_b128 v[168:171], v148 offset:49152
	ds_read_b128 v[172:175], v148 offset:50176
	ds_read_b128 v[176:179], v148 offset:51200
	ds_read_b128 v[180:183], v148 offset:52224
	ds_read_b128 v[184:187], v148 offset:53248
	ds_read_b128 v[188:191], v148 offset:54272
	ds_read_b128 v[192:195], v148 offset:55296
	ds_read_b128 v[196:199], v148 offset:56320
	global_load_lds_dwordx4 v[142:143], off
	v_lshl_add_u64 v[142:143], v[220:221], 0, s[16:17]
	s_mov_b32 m0, s57
	s_nop 0
	global_load_lds_dwordx4 v[142:143], off
	s_waitcnt vmcnt(10)
	s_barrier
	s_waitcnt lgkmcnt(0)
	v_mfma_f32_16x16x32_bf16 v[62:65], v[152:155], v[168:171], v[62:65]
	v_mfma_f32_16x16x32_bf16 v[58:61], v[160:163], v[168:171], v[58:61]
	v_mfma_f32_16x16x32_bf16 v[46:49], v[152:155], v[176:179], v[46:49]
	v_mfma_f32_16x16x32_bf16 v[42:45], v[160:163], v[176:179], v[42:45]
	v_mfma_f32_16x16x32_bf16 v[30:33], v[152:155], v[184:187], v[30:33]
	v_mfma_f32_16x16x32_bf16 v[26:29], v[160:163], v[184:187], v[26:29]
	v_mfma_f32_16x16x32_bf16 v[14:17], v[152:155], v[192:195], v[14:17]
	v_mfma_f32_16x16x32_bf16 v[10:13], v[160:163], v[192:195], v[10:13]
	v_mfma_f32_16x16x32_bf16 v[62:65], v[156:159], v[172:175], v[62:65]
	v_mfma_f32_16x16x32_bf16 v[58:61], v[164:167], v[172:175], v[58:61]
	v_mfma_f32_16x16x32_bf16 v[46:49], v[156:159], v[180:183], v[46:49]
	v_mfma_f32_16x16x32_bf16 v[42:45], v[164:167], v[180:183], v[42:45]
	v_mfma_f32_16x16x32_bf16 v[30:33], v[156:159], v[188:191], v[30:33]
	v_mfma_f32_16x16x32_bf16 v[26:29], v[164:167], v[188:191], v[26:29]
	v_mfma_f32_16x16x32_bf16 v[14:17], v[156:159], v[196:199], v[14:17]
	v_mfma_f32_16x16x32_bf16 v[10:13], v[164:167], v[196:199], v[10:13]
	s_barrier
	s_mov_b32 m0, s65
	v_lshl_add_u64 v[142:143], s[36:37], 0, v[134:135]
	global_load_lds_dwordx4 v[142:143], off
	v_lshl_add_u64 v[142:143], s[36:37], 0, v[130:131]
	s_mov_b32 m0, s64
	s_nop 0
	global_load_lds_dwordx4 v[142:143], off
	s_waitcnt vmcnt(10)
	s_barrier
	v_mfma_f32_16x16x32_bf16 v[54:57], v[200:203], v[168:171], v[54:57]
	v_mfma_f32_16x16x32_bf16 v[50:53], v[208:211], v[168:171], v[50:53]
	v_mfma_f32_16x16x32_bf16 v[38:41], v[200:203], v[176:179], v[38:41]
	v_mfma_f32_16x16x32_bf16 v[34:37], v[208:211], v[176:179], v[34:37]
	v_mfma_f32_16x16x32_bf16 v[22:25], v[200:203], v[184:187], v[22:25]
	v_mfma_f32_16x16x32_bf16 v[18:21], v[208:211], v[184:187], v[18:21]
	v_mfma_f32_16x16x32_bf16 v[6:9], v[200:203], v[192:195], v[6:9]
	v_mfma_f32_16x16x32_bf16 v[2:5], v[208:211], v[192:195], v[2:5]
	v_mfma_f32_16x16x32_bf16 v[54:57], v[204:207], v[172:175], v[54:57]
	v_mfma_f32_16x16x32_bf16 v[50:53], v[212:215], v[172:175], v[50:53]
	v_mfma_f32_16x16x32_bf16 v[38:41], v[204:207], v[180:183], v[38:41]
	v_mfma_f32_16x16x32_bf16 v[34:37], v[212:215], v[180:183], v[34:37]
	v_mfma_f32_16x16x32_bf16 v[22:25], v[204:207], v[188:191], v[22:25]
	v_mfma_f32_16x16x32_bf16 v[18:21], v[212:215], v[188:191], v[18:21]
	v_mfma_f32_16x16x32_bf16 v[6:9], v[204:207], v[196:199], v[6:9]
	v_mfma_f32_16x16x32_bf16 v[2:5], v[212:215], v[196:199], v[2:5]
	s_movk_i32 s38, 0x100
	s_andn2_b64 vcc, exec, s[34:35]
	s_mov_b64 s[36:37], -1
	s_mov_b64 s[34:35], 0
	s_barrier
	s_cbranch_vccz .LBB0_2344
	s_lshl_b32 s0, s26, 8
	v_mov_b32_e32 v143, v144
	s_add_i32 s0, s0, s53
	v_mov_b32_e32 v142, v145
	v_add_u32_e32 v151, s0, v143
	v_mov_b32_e32 v154, v151
	v_max_f32_e32 v126, v126, v126
	v_ashrrev_i32_e32 v152, 8, v154
	v_and_b32_e32 v152, -8, v152
	v_add_u32_e32 v152, s55, v152
	v_ashrrev_i32_e32 v153, 31, v152
	v_lshlrev_b64 v[152:153], 11, v[152:153]
	v_and_or_b32 v152, v154, s60, v152
	v_med3_f32 v154, v126, s61, v150
	v_max_f32_e32 v126, v127, v127
	v_med3_f32 v127, v126, s61, v150
	v_mov_b32_e32 v126, 0
	v_cvt_pk_fp8_f32 v126, v154, v127
	v_max_f32_e32 v127, v128, v128
	v_max_f32_e32 v128, v129, v129
	v_med3_f32 v127, v127, s61, v150
	v_med3_f32 v128, v128, s61, v150
	v_max_f32_e32 v122, v122, v122
	v_max_f32_e32 v123, v123, v123
	v_cvt_pk_fp8_f32 v126, v127, v128 op_sel:[0,0,1]
	v_med3_f32 v122, v122, s61, v150
	v_med3_f32 v123, v123, s61, v150
	v_mov_b32_e32 v127, 0
	v_cvt_pk_fp8_f32 v127, v122, v123
	v_max_f32_e32 v122, v124, v124
	v_max_f32_e32 v123, v125, v125
	v_med3_f32 v122, v122, s61, v150
	v_med3_f32 v123, v123, s61, v150
	v_lshl_add_u32 v142, v142, 3, s54
	v_cvt_pk_fp8_f32 v127, v122, v123 op_sel:[0,0,1]
	v_mov_b64_e32 v[122:123], s[12:13]
	v_ashrrev_i32_e32 v143, 31, v142
	v_mad_u64_u32 v[124:125], s[0:1], v152, s51, v[122:123]
	v_cvt_pk_bf16_f32 v118, v118, v119
	v_cvt_pk_bf16_f32 v119, v120, v121
	v_cvt_pk_bf16_f32 v120, v114, v115
	v_lshlrev_b64 v[114:115], 8, v[152:153]
	v_mad_i32_i24 v125, v153, s51, v125
	v_cvt_pk_bf16_f32 v121, v116, v117
	v_lshl_add_u64 v[116:117], s[14:15], 0, v[114:115]
	v_lshlrev_b64 v[114:115], 1, v[142:143]
	v_lshl_add_u64 v[124:125], v[124:125], 0, v[142:143]
	v_lshl_add_u64 v[116:117], v[116:117], 0, v[114:115]
	global_store_dwordx2 v[124:125], v[126:127], off
	global_store_dwordx4 v[116:117], v[118:121], off
	v_max_f32_e32 v110, v110, v110
	v_max_f32_e32 v106, v106, v106
	v_add_u32_e32 v118, 16, v151
	v_max_f32_e32 v107, v107, v107
	v_ashrrev_i32_e32 v116, 8, v118
	v_and_b32_e32 v116, -8, v116
	v_add_u32_e32 v116, s55, v116
	v_ashrrev_i32_e32 v117, 31, v116
	v_lshlrev_b64 v[116:117], 11, v[116:117]
	v_and_or_b32 v116, v118, s60, v116
	v_med3_f32 v118, v110, s61, v150
	v_max_f32_e32 v110, v111, v111
	v_med3_f32 v111, v110, s61, v150
	v_mov_b32_e32 v110, 0
	v_cvt_pk_fp8_f32 v110, v118, v111
	v_max_f32_e32 v111, v112, v112
	v_max_f32_e32 v112, v113, v113
	v_med3_f32 v111, v111, s61, v150
	v_med3_f32 v112, v112, s61, v150
	v_cvt_pk_fp8_f32 v110, v111, v112 op_sel:[0,0,1]
	v_med3_f32 v106, v106, s61, v150
	v_med3_f32 v107, v107, s61, v150
	v_mov_b32_e32 v111, 0
	v_cvt_pk_fp8_f32 v111, v106, v107
	v_max_f32_e32 v106, v108, v108
	v_max_f32_e32 v107, v109, v109
	v_med3_f32 v106, v106, s61, v150
	v_med3_f32 v107, v107, s61, v150
	v_cvt_pk_fp8_f32 v111, v106, v107 op_sel:[0,0,1]
	v_mad_u64_u32 v[106:107], s[0:1], v116, s51, v[122:123]
	v_cvt_pk_bf16_f32 v102, v102, v103
	v_cvt_pk_bf16_f32 v103, v104, v105
	v_cvt_pk_bf16_f32 v104, v98, v99
	v_lshlrev_b64 v[98:99], 8, v[116:117]
	v_mad_i32_i24 v107, v117, s51, v107
	v_lshl_add_u64 v[98:99], s[14:15], 0, v[98:99]
	v_lshl_add_u64 v[106:107], v[106:107], 0, v[142:143]
	v_cvt_pk_bf16_f32 v105, v100, v101
	v_lshl_add_u64 v[98:99], v[98:99], 0, v[114:115]
	v_add_u32_e32 v100, 32, v151
	global_store_dwordx2 v[106:107], v[110:111], off
	global_store_dwordx4 v[98:99], v[102:105], off
	v_max_f32_e32 v94, v94, v94
	v_ashrrev_i32_e32 v98, 8, v100
	v_and_b32_e32 v98, -8, v98
	v_add_u32_e32 v98, s55, v98
	v_ashrrev_i32_e32 v99, 31, v98
	v_lshlrev_b64 v[98:99], 11, v[98:99]
	v_and_or_b32 v98, v100, s60, v98
	v_med3_f32 v100, v94, s61, v150
	v_max_f32_e32 v94, v95, v95
	v_med3_f32 v95, v94, s61, v150
	v_mov_b32_e32 v94, 0
	v_cvt_pk_fp8_f32 v94, v100, v95
	v_max_f32_e32 v95, v96, v96
	v_max_f32_e32 v96, v97, v97
	v_med3_f32 v95, v95, s61, v150
	v_med3_f32 v96, v96, s61, v150
	v_max_f32_e32 v90, v90, v90
	v_max_f32_e32 v91, v91, v91
	v_cvt_pk_fp8_f32 v94, v95, v96 op_sel:[0,0,1]
	v_med3_f32 v90, v90, s61, v150
	v_med3_f32 v91, v91, s61, v150
	v_mov_b32_e32 v95, 0
	v_cvt_pk_fp8_f32 v95, v90, v91
	v_max_f32_e32 v90, v92, v92
	v_max_f32_e32 v91, v93, v93
	v_med3_f32 v90, v90, s61, v150
	v_med3_f32 v91, v91, s61, v150
	v_cvt_pk_fp8_f32 v95, v90, v91 op_sel:[0,0,1]
	v_mad_u64_u32 v[90:91], s[0:1], v98, s51, v[122:123]
	v_cvt_pk_bf16_f32 v86, v86, v87
	v_cvt_pk_bf16_f32 v87, v88, v89
	v_cvt_pk_bf16_f32 v88, v82, v83
	v_lshlrev_b64 v[82:83], 8, v[98:99]
	v_mad_i32_i24 v91, v99, s51, v91
	v_lshl_add_u64 v[82:83], s[14:15], 0, v[82:83]
	v_lshl_add_u64 v[90:91], v[90:91], 0, v[142:143]
	v_cvt_pk_bf16_f32 v89, v84, v85
	v_lshl_add_u64 v[82:83], v[82:83], 0, v[114:115]
	v_add_u32_e32 v84, 48, v151
	global_store_dwordx2 v[90:91], v[94:95], off
	global_store_dwordx4 v[82:83], v[86:89], off
	v_max_f32_e32 v78, v78, v78
	v_ashrrev_i32_e32 v82, 8, v84
	v_and_b32_e32 v82, -8, v82
	v_add_u32_e32 v82, s55, v82
	v_ashrrev_i32_e32 v83, 31, v82
	v_lshlrev_b64 v[82:83], 11, v[82:83]
	v_and_or_b32 v82, v84, s60, v82
	v_med3_f32 v84, v78, s61, v150
	v_max_f32_e32 v78, v79, v79
	v_med3_f32 v79, v78, s61, v150
	v_mov_b32_e32 v78, 0
	v_cvt_pk_fp8_f32 v78, v84, v79
	v_max_f32_e32 v79, v80, v80
	v_max_f32_e32 v80, v81, v81
	v_med3_f32 v79, v79, s61, v150
	v_med3_f32 v80, v80, s61, v150
	v_max_f32_e32 v74, v74, v74
	v_max_f32_e32 v75, v75, v75
	v_cvt_pk_fp8_f32 v78, v79, v80 op_sel:[0,0,1]
	v_med3_f32 v74, v74, s61, v150
	v_med3_f32 v75, v75, s61, v150
	v_mov_b32_e32 v79, 0
	v_cvt_pk_fp8_f32 v79, v74, v75
	v_max_f32_e32 v74, v76, v76
	v_max_f32_e32 v75, v77, v77
	v_med3_f32 v74, v74, s61, v150
	v_med3_f32 v75, v75, s61, v150
	v_cvt_pk_fp8_f32 v79, v74, v75 op_sel:[0,0,1]
	v_mad_u64_u32 v[74:75], s[0:1], v82, s51, v[122:123]
	v_cvt_pk_bf16_f32 v70, v70, v71
	v_cvt_pk_bf16_f32 v71, v72, v73
	v_cvt_pk_bf16_f32 v72, v66, v67
	v_lshlrev_b64 v[66:67], 8, v[82:83]
	v_mad_i32_i24 v75, v83, s51, v75
	v_lshl_add_u64 v[66:67], s[14:15], 0, v[66:67]
	v_lshl_add_u64 v[74:75], v[74:75], 0, v[142:143]
	v_cvt_pk_bf16_f32 v73, v68, v69
	v_lshl_add_u64 v[66:67], v[66:67], 0, v[114:115]
	v_add_u32_e32 v68, 0x80, v151
	global_store_dwordx2 v[74:75], v[78:79], off
	global_store_dwordx4 v[66:67], v[70:73], off
	v_max_f32_e32 v62, v62, v62
	v_ashrrev_i32_e32 v66, 8, v68
	v_and_b32_e32 v66, -8, v66
	v_add_u32_e32 v66, s55, v66
	v_ashrrev_i32_e32 v67, 31, v66
	v_lshlrev_b64 v[66:67], 11, v[66:67]
	v_and_or_b32 v66, v68, s60, v66
	v_med3_f32 v68, v62, s61, v150
	v_max_f32_e32 v62, v63, v63
	v_med3_f32 v63, v62, s61, v150
	v_mov_b32_e32 v62, 0
	v_cvt_pk_fp8_f32 v62, v68, v63
	v_max_f32_e32 v63, v64, v64
	v_max_f32_e32 v64, v65, v65
	v_med3_f32 v63, v63, s61, v150
	v_med3_f32 v64, v64, s61, v150
	v_max_f32_e32 v58, v58, v58
	v_max_f32_e32 v59, v59, v59
	v_cvt_pk_fp8_f32 v62, v63, v64 op_sel:[0,0,1]
	v_med3_f32 v58, v58, s61, v150
	v_med3_f32 v59, v59, s61, v150
	v_mov_b32_e32 v63, 0
	v_cvt_pk_fp8_f32 v63, v58, v59
	v_max_f32_e32 v58, v60, v60
	v_max_f32_e32 v59, v61, v61
	v_med3_f32 v58, v58, s61, v150
	v_med3_f32 v59, v59, s61, v150
	v_cvt_pk_fp8_f32 v63, v58, v59 op_sel:[0,0,1]
	v_mad_u64_u32 v[58:59], s[0:1], v66, s51, v[122:123]
	v_cvt_pk_bf16_f32 v54, v54, v55
	v_cvt_pk_bf16_f32 v55, v56, v57
	v_cvt_pk_bf16_f32 v56, v50, v51
	v_lshlrev_b64 v[50:51], 8, v[66:67]
	v_mad_i32_i24 v59, v67, s51, v59
	v_lshl_add_u64 v[50:51], s[14:15], 0, v[50:51]
	v_lshl_add_u64 v[58:59], v[58:59], 0, v[142:143]
	v_cvt_pk_bf16_f32 v57, v52, v53
	v_lshl_add_u64 v[50:51], v[50:51], 0, v[114:115]
	v_add_u32_e32 v52, 0x90, v151
	global_store_dwordx2 v[58:59], v[62:63], off
	global_store_dwordx4 v[50:51], v[54:57], off
	v_max_f32_e32 v46, v46, v46
	v_ashrrev_i32_e32 v50, 8, v52
	v_and_b32_e32 v50, -8, v50
	v_add_u32_e32 v50, s55, v50
	v_ashrrev_i32_e32 v51, 31, v50
	v_lshlrev_b64 v[50:51], 11, v[50:51]
	v_and_or_b32 v50, v52, s60, v50
	v_med3_f32 v52, v46, s61, v150
	v_max_f32_e32 v46, v47, v47
	v_med3_f32 v47, v46, s61, v150
	v_mov_b32_e32 v46, 0
	v_cvt_pk_fp8_f32 v46, v52, v47
	v_max_f32_e32 v47, v48, v48
	v_max_f32_e32 v48, v49, v49
	v_med3_f32 v47, v47, s61, v150
	v_med3_f32 v48, v48, s61, v150
	v_max_f32_e32 v42, v42, v42
	v_max_f32_e32 v43, v43, v43
	v_cvt_pk_fp8_f32 v46, v47, v48 op_sel:[0,0,1]
	v_med3_f32 v42, v42, s61, v150
	v_med3_f32 v43, v43, s61, v150
	v_mov_b32_e32 v47, 0
	v_cvt_pk_fp8_f32 v47, v42, v43
	v_max_f32_e32 v42, v44, v44
	v_max_f32_e32 v43, v45, v45
	v_med3_f32 v42, v42, s61, v150
	v_med3_f32 v43, v43, s61, v150
	v_cvt_pk_fp8_f32 v47, v42, v43 op_sel:[0,0,1]
	v_mad_u64_u32 v[42:43], s[0:1], v50, s51, v[122:123]
	v_cvt_pk_bf16_f32 v38, v38, v39
	v_cvt_pk_bf16_f32 v39, v40, v41
	v_cvt_pk_bf16_f32 v40, v34, v35
	v_lshlrev_b64 v[34:35], 8, v[50:51]
	v_mad_i32_i24 v43, v51, s51, v43
	v_lshl_add_u64 v[34:35], s[14:15], 0, v[34:35]
	v_lshl_add_u64 v[42:43], v[42:43], 0, v[142:143]
	v_cvt_pk_bf16_f32 v41, v36, v37
	v_lshl_add_u64 v[34:35], v[34:35], 0, v[114:115]
	v_add_u32_e32 v36, 0xa0, v151
	global_store_dwordx2 v[42:43], v[46:47], off
	global_store_dwordx4 v[34:35], v[38:41], off
	v_max_f32_e32 v30, v30, v30
	v_ashrrev_i32_e32 v34, 8, v36
	v_and_b32_e32 v34, -8, v34
	v_add_u32_e32 v34, s55, v34
	v_ashrrev_i32_e32 v35, 31, v34
	v_lshlrev_b64 v[34:35], 11, v[34:35]
	v_and_or_b32 v34, v36, s60, v34
	v_med3_f32 v36, v30, s61, v150
	v_max_f32_e32 v30, v31, v31
	v_med3_f32 v31, v30, s61, v150
	v_mov_b32_e32 v30, 0
	v_cvt_pk_fp8_f32 v30, v36, v31
	v_max_f32_e32 v31, v32, v32
	v_max_f32_e32 v32, v33, v33
	v_med3_f32 v31, v31, s61, v150
	v_med3_f32 v32, v32, s61, v150
	v_max_f32_e32 v26, v26, v26
	v_max_f32_e32 v27, v27, v27
	v_cvt_pk_fp8_f32 v30, v31, v32 op_sel:[0,0,1]
	v_med3_f32 v26, v26, s61, v150
	v_med3_f32 v27, v27, s61, v150
	v_mov_b32_e32 v31, 0
	v_cvt_pk_fp8_f32 v31, v26, v27
	v_max_f32_e32 v26, v28, v28
	v_max_f32_e32 v27, v29, v29
	v_med3_f32 v26, v26, s61, v150
	v_med3_f32 v27, v27, s61, v150
	v_cvt_pk_fp8_f32 v31, v26, v27 op_sel:[0,0,1]
	v_mad_u64_u32 v[26:27], s[0:1], v34, s51, v[122:123]
	v_cvt_pk_bf16_f32 v22, v22, v23
	v_cvt_pk_bf16_f32 v23, v24, v25
	v_cvt_pk_bf16_f32 v24, v18, v19
	v_lshlrev_b64 v[18:19], 8, v[34:35]
	v_mad_i32_i24 v27, v35, s51, v27
	v_lshl_add_u64 v[18:19], s[14:15], 0, v[18:19]
	v_lshl_add_u64 v[26:27], v[26:27], 0, v[142:143]
	v_cvt_pk_bf16_f32 v25, v20, v21
	v_lshl_add_u64 v[18:19], v[18:19], 0, v[114:115]
	v_add_u32_e32 v20, 0xb0, v151
	global_store_dwordx2 v[26:27], v[30:31], off
	global_store_dwordx4 v[18:19], v[22:25], off
	v_max_f32_e32 v14, v14, v14
	v_ashrrev_i32_e32 v18, 8, v20
	v_and_b32_e32 v18, -8, v18
	v_add_u32_e32 v18, s55, v18
	v_ashrrev_i32_e32 v19, 31, v18
	v_lshlrev_b64 v[18:19], 11, v[18:19]
	v_and_or_b32 v18, v20, s60, v18
	v_med3_f32 v20, v14, s61, v150
	v_max_f32_e32 v14, v15, v15
	v_med3_f32 v15, v14, s61, v150
	v_mov_b32_e32 v14, 0
	v_cvt_pk_fp8_f32 v14, v20, v15
	v_max_f32_e32 v15, v16, v16
	v_max_f32_e32 v16, v17, v17
	v_med3_f32 v15, v15, s61, v150
	v_med3_f32 v16, v16, s61, v150
	v_max_f32_e32 v10, v10, v10
	v_max_f32_e32 v11, v11, v11
	v_cvt_pk_fp8_f32 v14, v15, v16 op_sel:[0,0,1]
	v_med3_f32 v10, v10, s61, v150
	v_med3_f32 v11, v11, s61, v150
	v_mov_b32_e32 v15, 0
	v_cvt_pk_fp8_f32 v15, v10, v11
	v_max_f32_e32 v10, v12, v12
	v_max_f32_e32 v11, v13, v13
	v_med3_f32 v10, v10, s61, v150
	v_med3_f32 v11, v11, s61, v150
	v_cvt_pk_fp8_f32 v15, v10, v11 op_sel:[0,0,1]
	v_mad_u64_u32 v[10:11], s[0:1], v18, s51, v[122:123]
	v_cvt_pk_bf16_f32 v6, v6, v7
	v_cvt_pk_bf16_f32 v7, v8, v9
	v_cvt_pk_bf16_f32 v8, v2, v3
	v_lshlrev_b64 v[2:3], 8, v[18:19]
	v_mad_i32_i24 v11, v19, s51, v11
	v_lshl_add_u64 v[2:3], s[14:15], 0, v[2:3]
	v_readlane_b32 s72, v254, 2
	v_lshl_add_u64 v[10:11], v[10:11], 0, v[142:143]
	v_cvt_pk_bf16_f32 v9, v4, v5
	v_lshl_add_u64 v[2:3], v[2:3], 0, v[114:115]
	s_and_b64 vcc, exec, s[10:11]
	s_mov_b32 s55, s18
	s_mov_b32 s26, s20
	s_mov_b64 s[28:29], s[24:25]
	s_mov_b64 s[30:31], s[22:23]
	v_readlane_b32 s73, v254, 3
	global_store_dwordx2 v[10:11], v[14:15], off
	global_store_dwordx4 v[2:3], v[6:9], off
	s_cbranch_vccz .LBB0_2337
	s_waitcnt vmcnt(0)
	s_cmpk_gt_u32 s5, 0xff
	s_cbranch_scc1 .LBB0_2348
	s_barrier

.LBB0_2495:
	ds_read_b128 v[130:133], v168
	ds_read_b128 v[134:137], v168 offset:1024
	ds_read_b128 v[138:141], v168 offset:2048
	ds_read_b128 v[142:145], v168 offset:3072
	s_add_u32 s0, s36, 0xfffc0080
	s_addc_u32 s1, s37, -1
	s_cmp_eq_u32 s69, 12
	s_cselect_b32 s41, s61, s1
	s_cselect_b32 s40, s62, s0
	s_cselect_b32 s39, s63, s67
	s_cselect_b32 s38, s64, s65
	s_mov_b32 m0, s51
	v_lshl_add_u64 v[164:165], s[36:37], 0, v[162:163]
	ds_read_b128 v[146:149], v169
	ds_read_b128 v[172:175], v169 offset:1024
	ds_read_b128 v[176:179], v169 offset:2048
	ds_read_b128 v[180:183], v169 offset:3072
	ds_read_b128 v[184:187], v169 offset:4096
	ds_read_b128 v[188:191], v169 offset:5120
	ds_read_b128 v[192:195], v169 offset:6144
	ds_read_b128 v[196:199], v169 offset:7168
	global_load_lds_dwordx4 v[164:165], off
	v_lshl_add_u64 v[164:165], s[36:37], 0, v[160:161]
	s_mov_b32 m0, s52
	s_nop 0
	global_load_lds_dwordx4 v[164:165], off
	s_waitcnt lgkmcnt(8)
	s_waitcnt vmcnt(10)
	s_barrier
	s_waitcnt lgkmcnt(0)
	v_mfma_f32_16x16x32_bf16 v[126:129], v[130:133], v[146:149], v[126:129]
	v_mfma_f32_16x16x32_bf16 v[122:125], v[138:141], v[146:149], v[122:125]
	v_mfma_f32_16x16x32_bf16 v[118:121], v[130:133], v[176:179], v[118:121]
	v_mfma_f32_16x16x32_bf16 v[110:113], v[138:141], v[176:179], v[110:113]
	v_mfma_f32_16x16x32_bf16 v[98:101], v[130:133], v[184:187], v[98:101]
	v_mfma_f32_16x16x32_bf16 v[90:93], v[138:141], v[184:187], v[90:93]
	v_mfma_f32_16x16x32_bf16 v[82:85], v[130:133], v[192:195], v[82:85]
	v_mfma_f32_16x16x32_bf16 v[74:77], v[138:141], v[192:195], v[74:77]
	v_mfma_f32_16x16x32_bf16 v[126:129], v[134:137], v[172:175], v[126:129]
	v_mfma_f32_16x16x32_bf16 v[122:125], v[142:145], v[172:175], v[122:125]
	v_mfma_f32_16x16x32_bf16 v[118:121], v[134:137], v[180:183], v[118:121]
	v_mfma_f32_16x16x32_bf16 v[110:113], v[142:145], v[180:183], v[110:113]
	v_mfma_f32_16x16x32_bf16 v[98:101], v[134:137], v[188:191], v[98:101]
	v_mfma_f32_16x16x32_bf16 v[90:93], v[142:145], v[188:191], v[90:93]
	v_mfma_f32_16x16x32_bf16 v[82:85], v[134:137], v[196:199], v[82:85]
	v_mfma_f32_16x16x32_bf16 v[74:77], v[142:145], v[196:199], v[74:77]
	s_barrier
	s_mov_b32 m0, s53
	v_lshl_add_u64 v[164:165], s[38:39], 0, v[156:157]
	ds_read_b128 v[200:203], v170
	ds_read_b128 v[204:207], v170 offset:1024
	ds_read_b128 v[208:211], v170 offset:2048
	ds_read_b128 v[212:215], v170 offset:3072
	global_load_lds_dwordx4 v[164:165], off
	v_lshl_add_u64 v[216:217], s[38:39], 0, v[152:153]
	s_mov_b32 m0, s54
	s_nop 0
	global_load_lds_dwordx4 v[216:217], off
	s_waitcnt vmcnt(10)
	s_barrier
	s_waitcnt lgkmcnt(0)
	v_mfma_f32_16x16x32_bf16 v[114:117], v[200:203], v[146:149], v[114:117]
	v_mfma_f32_16x16x32_bf16 v[106:109], v[208:211], v[146:149], v[106:109]
	v_mfma_f32_16x16x32_bf16 v[102:105], v[200:203], v[176:179], v[102:105]
	v_mfma_f32_16x16x32_bf16 v[94:97], v[208:211], v[176:179], v[94:97]
	v_mfma_f32_16x16x32_bf16 v[86:89], v[200:203], v[184:187], v[86:89]
	v_mfma_f32_16x16x32_bf16 v[78:81], v[208:211], v[184:187], v[78:81]
	v_mfma_f32_16x16x32_bf16 v[70:73], v[200:203], v[192:195], v[70:73]
	v_mfma_f32_16x16x32_bf16 v[66:69], v[208:211], v[192:195], v[66:69]
	v_mfma_f32_16x16x32_bf16 v[114:117], v[204:207], v[172:175], v[114:117]
	v_mfma_f32_16x16x32_bf16 v[106:109], v[212:215], v[172:175], v[106:109]
	v_mfma_f32_16x16x32_bf16 v[102:105], v[204:207], v[180:183], v[102:105]
	v_mfma_f32_16x16x32_bf16 v[94:97], v[212:215], v[180:183], v[94:97]
	v_mfma_f32_16x16x32_bf16 v[86:89], v[204:207], v[188:191], v[86:89]
	v_mfma_f32_16x16x32_bf16 v[78:81], v[212:215], v[188:191], v[78:81]
	v_mfma_f32_16x16x32_bf16 v[70:73], v[204:207], v[196:199], v[70:73]
	v_mfma_f32_16x16x32_bf16 v[66:69], v[212:215], v[196:199], v[66:69]
	s_mov_b32 m0, s9
	v_lshl_add_u64 v[218:219], s[40:41], 0, v[158:159]
	s_barrier
	ds_read_b128 v[146:149], v169 offset:16384
	ds_read_b128 v[172:175], v169 offset:17408
	ds_read_b128 v[176:179], v169 offset:18432
	ds_read_b128 v[180:183], v169 offset:19456
	ds_read_b128 v[184:187], v169 offset:20480
	ds_read_b128 v[188:191], v169 offset:21504
	ds_read_b128 v[192:195], v169 offset:22528
	ds_read_b128 v[196:199], v169 offset:23552
	global_load_lds_dwordx4 v[218:219], off
	v_lshl_add_u64 v[220:221], s[40:41], 0, v[154:155]
	s_mov_b32 m0, s29
	s_nop 0
	global_load_lds_dwordx4 v[220:221], off
	s_waitcnt vmcnt(10)
	s_barrier
	s_waitcnt lgkmcnt(0)
	v_mfma_f32_16x16x32_bf16 v[62:65], v[130:133], v[146:149], v[62:65]
	v_mfma_f32_16x16x32_bf16 v[58:61], v[138:141], v[146:149], v[58:61]
	v_mfma_f32_16x16x32_bf16 v[50:53], v[130:133], v[176:179], v[50:53]
	v_mfma_f32_16x16x32_bf16 v[42:45], v[138:141], v[176:179], v[42:45]
	v_mfma_f32_16x16x32_bf16 v[34:37], v[130:133], v[184:187], v[34:37]
	v_mfma_f32_16x16x32_bf16 v[26:29], v[138:141], v[184:187], v[26:29]
	v_mfma_f32_16x16x32_bf16 v[18:21], v[130:133], v[192:195], v[18:21]
	v_mfma_f32_16x16x32_bf16 v[10:13], v[138:141], v[192:195], v[10:13]
	v_mfma_f32_16x16x32_bf16 v[62:65], v[134:137], v[172:175], v[62:65]
	v_mfma_f32_16x16x32_bf16 v[58:61], v[142:145], v[172:175], v[58:61]
	v_mfma_f32_16x16x32_bf16 v[50:53], v[134:137], v[180:183], v[50:53]
	v_mfma_f32_16x16x32_bf16 v[42:45], v[142:145], v[180:183], v[42:45]
	v_mfma_f32_16x16x32_bf16 v[34:37], v[134:137], v[188:191], v[34:37]
	v_mfma_f32_16x16x32_bf16 v[26:29], v[142:145], v[188:191], v[26:29]
	v_mfma_f32_16x16x32_bf16 v[18:21], v[134:137], v[196:199], v[18:21]
	v_mfma_f32_16x16x32_bf16 v[10:13], v[142:145], v[196:199], v[10:13]
	s_barrier
	s_add_u32 s0, s38, 0x40000
	s_addc_u32 s1, s39, 0
	s_mov_b32 m0, s55
	v_lshl_add_u64 v[130:131], s[0:1], 0, v[156:157]
	global_load_lds_dwordx4 v[130:131], off
	v_lshl_add_u64 v[130:131], s[0:1], 0, v[152:153]
	s_add_i32 m0, s55, 0x2000
	s_nop 0
	global_load_lds_dwordx4 v[130:131], off
	s_waitcnt vmcnt(10)
	s_barrier
	v_mfma_f32_16x16x32_bf16 v[54:57], v[200:203], v[146:149], v[54:57]
	v_mfma_f32_16x16x32_bf16 v[46:49], v[208:211], v[146:149], v[46:49]
	v_mfma_f32_16x16x32_bf16 v[38:41], v[200:203], v[176:179], v[38:41]
	v_mfma_f32_16x16x32_bf16 v[30:33], v[208:211], v[176:179], v[30:33]
	v_mfma_f32_16x16x32_bf16 v[22:25], v[200:203], v[184:187], v[22:25]
	v_mfma_f32_16x16x32_bf16 v[14:17], v[208:211], v[184:187], v[14:17]
	v_mfma_f32_16x16x32_bf16 v[6:9], v[200:203], v[192:195], v[6:9]
	v_mfma_f32_16x16x32_bf16 v[2:5], v[208:211], v[192:195], v[2:5]
	v_mfma_f32_16x16x32_bf16 v[54:57], v[204:207], v[172:175], v[54:57]
	v_mfma_f32_16x16x32_bf16 v[46:49], v[212:215], v[172:175], v[46:49]
	v_mfma_f32_16x16x32_bf16 v[38:41], v[204:207], v[180:183], v[38:41]
	v_mfma_f32_16x16x32_bf16 v[30:33], v[212:215], v[180:183], v[30:33]
	v_mfma_f32_16x16x32_bf16 v[22:25], v[204:207], v[188:191], v[22:25]
	v_mfma_f32_16x16x32_bf16 v[14:17], v[212:215], v[188:191], v[14:17]
	v_mfma_f32_16x16x32_bf16 v[6:9], v[204:207], v[196:199], v[6:9]
	v_mfma_f32_16x16x32_bf16 v[2:5], v[212:215], v[196:199], v[2:5]
	s_add_i32 s70, 0, 0x18000
	v_add_u32_e32 v142, s70, v167
	s_barrier
	ds_read_b128 v[130:133], v142
	ds_read_b128 v[134:137], v142 offset:1024
	ds_read_b128 v[138:141], v142 offset:2048
	ds_read_b128 v[142:145], v142 offset:3072
	s_add_u32 s0, s40, 0x40000
	s_addc_u32 s1, s41, 0
	s_mov_b32 m0, s42
	v_lshl_add_u64 v[200:201], s[0:1], 0, v[158:159]
	ds_read_b128 v[146:149], v169 offset:32768
	ds_read_b128 v[172:175], v169 offset:33792
	ds_read_b128 v[176:179], v169 offset:34816
	ds_read_b128 v[180:183], v169 offset:35840
	ds_read_b128 v[184:187], v169 offset:36864
	ds_read_b128 v[188:191], v169 offset:37888
	ds_read_b128 v[192:195], v169 offset:38912
	ds_read_b128 v[196:199], v169 offset:39936
	global_load_lds_dwordx4 v[200:201], off
	v_lshl_add_u64 v[200:201], s[0:1], 0, v[154:155]
	s_mov_b32 m0, s43
	s_nop 0
	global_load_lds_dwordx4 v[200:201], off
	s_waitcnt lgkmcnt(8)
	s_waitcnt vmcnt(10)
	s_barrier
	s_waitcnt lgkmcnt(0)
	v_mfma_f32_16x16x32_bf16 v[126:129], v[130:133], v[146:149], v[126:129]
	v_mfma_f32_16x16x32_bf16 v[122:125], v[138:141], v[146:149], v[122:125]
	v_mfma_f32_16x16x32_bf16 v[118:121], v[130:133], v[176:179], v[118:121]
	v_mfma_f32_16x16x32_bf16 v[110:113], v[138:141], v[176:179], v[110:113]
	v_mfma_f32_16x16x32_bf16 v[98:101], v[130:133], v[184:187], v[98:101]
	v_mfma_f32_16x16x32_bf16 v[90:93], v[138:141], v[184:187], v[90:93]
	v_mfma_f32_16x16x32_bf16 v[82:85], v[130:133], v[192:195], v[82:85]
	v_mfma_f32_16x16x32_bf16 v[74:77], v[138:141], v[192:195], v[74:77]
	v_mfma_f32_16x16x32_bf16 v[126:129], v[134:137], v[172:175], v[126:129]
	v_mfma_f32_16x16x32_bf16 v[122:125], v[142:145], v[172:175], v[122:125]
	v_mfma_f32_16x16x32_bf16 v[118:121], v[134:137], v[180:183], v[118:121]
	v_mfma_f32_16x16x32_bf16 v[110:113], v[142:145], v[180:183], v[110:113]
	v_mfma_f32_16x16x32_bf16 v[98:101], v[134:137], v[188:191], v[98:101]
	v_mfma_f32_16x16x32_bf16 v[90:93], v[142:145], v[188:191], v[90:93]
	v_mfma_f32_16x16x32_bf16 v[82:85], v[134:137], v[196:199], v[82:85]
	v_mfma_f32_16x16x32_bf16 v[74:77], v[142:145], v[196:199], v[74:77]
	s_barrier
	s_add_i32 s40, 0, 0x1c000
	s_add_i32 s0, s70, s8
	v_add_u32_e32 v171, s40, v167
	v_lshl_add_u64 v[164:165], v[164:165], 0, s[26:27]
	s_mov_b32 m0, s0
	ds_read_b128 v[200:203], v171
	ds_read_b128 v[204:207], v171 offset:1024
	ds_read_b128 v[208:211], v171 offset:2048
	ds_read_b128 v[212:215], v171 offset:3072
	global_load_lds_dwordx4 v[164:165], off
	v_lshl_add_u64 v[164:165], v[216:217], 0, s[26:27]
	s_add_i32 m0, s0, 0x2000
	s_nop 0
	global_load_lds_dwordx4 v[164:165], off
	s_waitcnt vmcnt(10)
	s_barrier
	s_waitcnt lgkmcnt(0)
	v_mfma_f32_16x16x32_bf16 v[114:117], v[200:203], v[146:149], v[114:117]
	v_mfma_f32_16x16x32_bf16 v[106:109], v[208:211], v[146:149], v[106:109]
	v_mfma_f32_16x16x32_bf16 v[102:105], v[200:203], v[176:179], v[102:105]
	v_mfma_f32_16x16x32_bf16 v[94:97], v[208:211], v[176:179], v[94:97]
	v_mfma_f32_16x16x32_bf16 v[86:89], v[200:203], v[184:187], v[86:89]
	v_mfma_f32_16x16x32_bf16 v[78:81], v[208:211], v[184:187], v[78:81]
	v_mfma_f32_16x16x32_bf16 v[70:73], v[200:203], v[192:195], v[70:73]
	v_mfma_f32_16x16x32_bf16 v[66:69], v[208:211], v[192:195], v[66:69]
	v_mfma_f32_16x16x32_bf16 v[114:117], v[204:207], v[172:175], v[114:117]
	v_mfma_f32_16x16x32_bf16 v[106:109], v[212:215], v[172:175], v[106:109]
	v_mfma_f32_16x16x32_bf16 v[102:105], v[204:207], v[180:183], v[102:105]
	v_mfma_f32_16x16x32_bf16 v[94:97], v[212:215], v[180:183], v[94:97]
	v_mfma_f32_16x16x32_bf16 v[86:89], v[204:207], v[188:191], v[86:89]
	v_mfma_f32_16x16x32_bf16 v[78:81], v[212:215], v[188:191], v[78:81]
	v_mfma_f32_16x16x32_bf16 v[70:73], v[204:207], v[196:199], v[70:73]
	v_mfma_f32_16x16x32_bf16 v[66:69], v[212:215], v[196:199], v[66:69]
	s_mov_b32 m0, s49
	v_lshl_add_u64 v[164:165], v[218:219], 0, s[26:27]
	s_barrier
	ds_read_b128 v[146:149], v169 offset:49152
	ds_read_b128 v[172:175], v169 offset:50176
	ds_read_b128 v[176:179], v169 offset:51200
	ds_read_b128 v[180:183], v169 offset:52224
	ds_read_b128 v[184:187], v169 offset:53248
	ds_read_b128 v[188:191], v169 offset:54272
	ds_read_b128 v[192:195], v169 offset:55296
	ds_read_b128 v[196:199], v169 offset:56320
	global_load_lds_dwordx4 v[164:165], off
	v_lshl_add_u64 v[164:165], v[220:221], 0, s[26:27]
	s_mov_b32 m0, s50
	s_nop 0
	global_load_lds_dwordx4 v[164:165], off
	s_waitcnt vmcnt(10)
	s_barrier
	s_waitcnt lgkmcnt(0)
	v_mfma_f32_16x16x32_bf16 v[62:65], v[130:133], v[146:149], v[62:65]
	v_mfma_f32_16x16x32_bf16 v[58:61], v[138:141], v[146:149], v[58:61]
	v_mfma_f32_16x16x32_bf16 v[50:53], v[130:133], v[176:179], v[50:53]
	v_mfma_f32_16x16x32_bf16 v[42:45], v[138:141], v[176:179], v[42:45]
	v_mfma_f32_16x16x32_bf16 v[34:37], v[130:133], v[184:187], v[34:37]
	v_mfma_f32_16x16x32_bf16 v[26:29], v[138:141], v[184:187], v[26:29]
	v_mfma_f32_16x16x32_bf16 v[18:21], v[130:133], v[192:195], v[18:21]
	v_mfma_f32_16x16x32_bf16 v[10:13], v[138:141], v[192:195], v[10:13]
	v_mfma_f32_16x16x32_bf16 v[62:65], v[134:137], v[172:175], v[62:65]
	v_mfma_f32_16x16x32_bf16 v[58:61], v[142:145], v[172:175], v[58:61]
	v_mfma_f32_16x16x32_bf16 v[50:53], v[134:137], v[180:183], v[50:53]
	v_mfma_f32_16x16x32_bf16 v[42:45], v[142:145], v[180:183], v[42:45]
	v_mfma_f32_16x16x32_bf16 v[34:37], v[134:137], v[188:191], v[34:37]
	v_mfma_f32_16x16x32_bf16 v[26:29], v[142:145], v[188:191], v[26:29]
	v_mfma_f32_16x16x32_bf16 v[18:21], v[134:137], v[196:199], v[18:21]
	v_mfma_f32_16x16x32_bf16 v[10:13], v[142:145], v[196:199], v[10:13]
	s_barrier
	s_add_u32 s0, s38, 0x40080
	s_addc_u32 s1, s39, 0
	s_add_i32 s38, s40, s8
	v_lshl_add_u64 v[130:131], s[0:1], 0, v[156:157]
	s_mov_b32 m0, s38
	s_nop 0
	global_load_lds_dwordx4 v[130:131], off
	v_lshl_add_u64 v[130:131], s[0:1], 0, v[152:153]
	s_add_i32 m0, s38, 0x2000
	s_nop 0
	global_load_lds_dwordx4 v[130:131], off
	s_waitcnt vmcnt(10)
	s_barrier
	v_mfma_f32_16x16x32_bf16 v[54:57], v[200:203], v[146:149], v[54:57]
	v_mfma_f32_16x16x32_bf16 v[46:49], v[208:211], v[146:149], v[46:49]
	v_mfma_f32_16x16x32_bf16 v[38:41], v[200:203], v[176:179], v[38:41]
	v_mfma_f32_16x16x32_bf16 v[30:33], v[208:211], v[176:179], v[30:33]
	v_mfma_f32_16x16x32_bf16 v[22:25], v[200:203], v[184:187], v[22:25]
	v_mfma_f32_16x16x32_bf16 v[14:17], v[208:211], v[184:187], v[14:17]
	v_mfma_f32_16x16x32_bf16 v[6:9], v[200:203], v[192:195], v[6:9]
	v_mfma_f32_16x16x32_bf16 v[2:5], v[208:211], v[192:195], v[2:5]
	v_mfma_f32_16x16x32_bf16 v[54:57], v[204:207], v[172:175], v[54:57]
	v_mfma_f32_16x16x32_bf16 v[46:49], v[212:215], v[172:175], v[46:49]
	v_mfma_f32_16x16x32_bf16 v[38:41], v[204:207], v[180:183], v[38:41]
	v_mfma_f32_16x16x32_bf16 v[30:33], v[212:215], v[180:183], v[30:33]
	v_mfma_f32_16x16x32_bf16 v[22:25], v[204:207], v[188:191], v[22:25]
	v_mfma_f32_16x16x32_bf16 v[14:17], v[212:215], v[188:191], v[14:17]
	v_mfma_f32_16x16x32_bf16 v[6:9], v[204:207], v[196:199], v[6:9]
	v_mfma_f32_16x16x32_bf16 v[2:5], v[212:215], v[196:199], v[2:5]
	s_add_i32 s69, s69, 2
	s_add_u32 s65, s65, 0x100
	s_addc_u32 s67, s67, 0
	s_add_u32 s36, s36, 0x100
	s_addc_u32 s37, s37, 0
	s_cmp_gt_u32 s69, 13
	s_barrier
	s_cbranch_scc0 .LBB0_2495
	s_lshl_b32 s0, s59, 8
	v_mov_b32_e32 v130, v151
	v_mov_b32_e32 v131, v166
	s_or_b32 s0, s0, s46
	s_mov_b32 s59, s58
	v_lshl_add_u32 v164, v131, 3, s0
	s_lshl_b32 s0, s60, 8
	s_add_i32 s0, s0, s45
	v_add_u32_e32 v171, s0, v130
	v_mov_b32_e32 v130, v171
	v_ashrrev_i32_e32 v165, 31, v164
	v_ashrrev_i32_e32 v131, 31, v130
	v_lshlrev_b64 v[130:131], 10, v[130:131]
	v_lshl_add_u64 v[130:131], v[130:131], 0, v[164:165]
	v_lshlrev_b64 v[184:185], 1, v[130:131]
	v_lshl_add_u64 v[130:131], s[10:11], 0, v[184:185]
	global_load_dwordx4 v[172:175], v[130:131], off
	global_load_dwordx4 v[176:179], v[130:131], off offset:256
	v_add_co_u32_e32 v132, vcc, s48, v130
	s_mov_b32 s60, s57
	s_nop 0
	v_addc_co_u32_e32 v133, vcc, 0, v131, vcc
	global_load_dwordx4 v[180:183], v[132:133], off
	global_load_dwordx4 v[146:149], v[132:133], off offset:256
	v_add_co_u32_e32 v132, vcc, s44, v130
	s_waitcnt vmcnt(0) lgkmcnt(0)
	v_lshlrev_b32_e32 v186, 16, v172
	v_addc_co_u32_e32 v133, vcc, 0, v131, vcc
	global_load_dwordx4 v[142:145], v[132:133], off
	global_load_dwordx4 v[138:141], v[132:133], off offset:256
	v_add_co_u32_e32 v130, vcc, s47, v130
	v_and_b32_e32 v187, 0xffff0000, v172
	s_nop 0
	v_addc_co_u32_e32 v131, vcc, 0, v131, vcc
	global_load_dwordx4 v[134:137], v[130:131], off
	s_nop 0
	global_load_dwordx4 v[130:133], v[130:131], off offset:256
	v_lshlrev_b32_e32 v172, 16, v173
	v_and_b32_e32 v173, 0xffff0000, v173
	v_lshlrev_b32_e32 v188, 16, v174
	v_and_b32_e32 v189, 0xffff0000, v174
	v_lshlrev_b32_e32 v174, 16, v175
	v_and_b32_e32 v175, 0xffff0000, v175
	v_pk_fma_f32 v[128:129], v[172:173], s[28:29], v[128:129] op_sel_hi:[1,0,1]
	v_pk_fma_f32 v[126:127], v[186:187], s[28:29], v[126:127] op_sel_hi:[1,0,1]
	v_pk_fma_f32 v[172:173], v[174:175], s[28:29], v[124:125] op_sel_hi:[1,0,1]
	v_pk_fma_f32 v[122:123], v[188:189], s[28:29], v[122:123] op_sel_hi:[1,0,1]
	v_cvt_pk_bf16_f32 v124, v126, v127
	v_cvt_pk_bf16_f32 v125, v128, v129
	v_cvt_pk_bf16_f32 v126, v122, v123
	v_cvt_pk_bf16_f32 v127, v172, v173
	v_lshl_add_u64 v[122:123], s[16:17], 0, v[184:185]
	global_store_dwordx4 v[122:123], v[124:127], off
	v_lshlrev_b32_e32 v128, 16, v178
	v_and_b32_e32 v129, 0xffff0000, v178
	v_lshlrev_b32_e32 v124, 16, v176
	v_and_b32_e32 v125, 0xffff0000, v176
	v_lshlrev_b32_e32 v126, 16, v177
	v_and_b32_e32 v127, 0xffff0000, v177
	v_lshlrev_b32_e32 v172, 16, v179
	v_and_b32_e32 v173, 0xffff0000, v179
	v_pk_fma_f32 v[116:117], v[126:127], s[28:29], v[116:117] op_sel_hi:[1,0,1]
	v_pk_fma_f32 v[114:115], v[124:125], s[28:29], v[114:115] op_sel_hi:[1,0,1]
	v_pk_fma_f32 v[124:125], v[172:173], s[28:29], v[108:109] op_sel_hi:[1,0,1]
	v_pk_fma_f32 v[108:109], v[128:129], s[28:29], v[106:107] op_sel_hi:[1,0,1]
	v_cvt_pk_bf16_f32 v106, v114, v115
	v_cvt_pk_bf16_f32 v107, v116, v117
	v_cvt_pk_bf16_f32 v108, v108, v109
	v_cvt_pk_bf16_f32 v109, v124, v125
	global_store_dwordx4 v[122:123], v[106:109], off offset:256
	v_lshlrev_b32_e32 v114, 16, v182
	v_and_b32_e32 v115, 0xffff0000, v182
	v_lshlrev_b32_e32 v106, 16, v180
	v_and_b32_e32 v107, 0xffff0000, v180
	v_lshlrev_b32_e32 v108, 16, v181
	v_and_b32_e32 v109, 0xffff0000, v181
	v_lshlrev_b32_e32 v116, 16, v183
	v_and_b32_e32 v117, 0xffff0000, v183
	v_pk_fma_f32 v[108:109], v[108:109], s[28:29], v[120:121] op_sel_hi:[1,0,1]
	v_pk_fma_f32 v[106:107], v[106:107], s[28:29], v[118:119] op_sel_hi:[1,0,1]
	v_pk_fma_f32 v[110:111], v[114:115], s[28:29], v[110:111] op_sel_hi:[1,0,1]
	v_pk_fma_f32 v[112:113], v[116:117], s[28:29], v[112:113] op_sel_hi:[1,0,1]
	v_cvt_pk_bf16_f32 v106, v106, v107
	v_cvt_pk_bf16_f32 v107, v108, v109
	v_cvt_pk_bf16_f32 v108, v110, v111
	v_add_co_u32_e32 v110, vcc, s48, v122
	v_cvt_pk_bf16_f32 v109, v112, v113
	s_nop 0
	v_addc_co_u32_e32 v111, vcc, 0, v123, vcc
	global_store_dwordx4 v[110:111], v[106:109], off
	v_lshlrev_b32_e32 v112, 16, v148
	v_and_b32_e32 v113, 0xffff0000, v148
	v_lshlrev_b32_e32 v106, 16, v146
	v_and_b32_e32 v107, 0xffff0000, v146
	v_lshlrev_b32_e32 v108, 16, v147
	v_and_b32_e32 v109, 0xffff0000, v147
	v_lshlrev_b32_e32 v114, 16, v149
	v_and_b32_e32 v115, 0xffff0000, v149
	v_pk_fma_f32 v[104:105], v[108:109], s[28:29], v[104:105] op_sel_hi:[1,0,1]
	v_pk_fma_f32 v[102:103], v[106:107], s[28:29], v[102:103] op_sel_hi:[1,0,1]
	v_pk_fma_f32 v[106:107], v[114:115], s[28:29], v[96:97] op_sel_hi:[1,0,1]
	v_pk_fma_f32 v[96:97], v[112:113], s[28:29], v[94:95] op_sel_hi:[1,0,1]
	v_cvt_pk_bf16_f32 v94, v102, v103
	v_cvt_pk_bf16_f32 v95, v104, v105
	v_cvt_pk_bf16_f32 v96, v96, v97
	v_cvt_pk_bf16_f32 v97, v106, v107
	global_store_dwordx4 v[110:111], v[94:97], off offset:256
	s_waitcnt vmcnt(0) lgkmcnt(0)
	v_lshlrev_b32_e32 v102, 16, v144
	v_lshlrev_b32_e32 v94, 16, v142
	v_and_b32_e32 v95, 0xffff0000, v142
	v_lshlrev_b32_e32 v96, 16, v143
	v_and_b32_e32 v97, 0xffff0000, v143
	v_and_b32_e32 v103, 0xffff0000, v144
	v_lshlrev_b32_e32 v104, 16, v145
	v_and_b32_e32 v105, 0xffff0000, v145
	v_pk_fma_f32 v[94:95], v[94:95], s[28:29], v[98:99] op_sel_hi:[1,0,1]
	v_pk_fma_f32 v[96:97], v[96:97], s[28:29], v[100:101] op_sel_hi:[1,0,1]
	v_pk_fma_f32 v[98:99], v[104:105], s[28:29], v[92:93] op_sel_hi:[1,0,1]
	v_pk_fma_f32 v[92:93], v[102:103], s[28:29], v[90:91] op_sel_hi:[1,0,1]
	v_cvt_pk_bf16_f32 v90, v94, v95
	v_add_co_u32_e32 v94, vcc, s44, v122
	v_cvt_pk_bf16_f32 v91, v96, v97
	v_cvt_pk_bf16_f32 v92, v92, v93
	v_cvt_pk_bf16_f32 v93, v98, v99
	v_addc_co_u32_e32 v95, vcc, 0, v123, vcc
	global_store_dwordx4 v[94:95], v[90:93], off
	v_lshlrev_b32_e32 v96, 16, v140
	v_and_b32_e32 v97, 0xffff0000, v140
	v_lshlrev_b32_e32 v90, 16, v138
	v_and_b32_e32 v91, 0xffff0000, v138
	v_lshlrev_b32_e32 v92, 16, v139
	v_and_b32_e32 v93, 0xffff0000, v139
	v_lshlrev_b32_e32 v98, 16, v141
	v_and_b32_e32 v99, 0xffff0000, v141
	v_pk_fma_f32 v[88:89], v[92:93], s[28:29], v[88:89] op_sel_hi:[1,0,1]
	v_pk_fma_f32 v[86:87], v[90:91], s[28:29], v[86:87] op_sel_hi:[1,0,1]
	v_pk_fma_f32 v[90:91], v[98:99], s[28:29], v[80:81] op_sel_hi:[1,0,1]
	v_pk_fma_f32 v[80:81], v[96:97], s[28:29], v[78:79] op_sel_hi:[1,0,1]
	v_cvt_pk_bf16_f32 v78, v86, v87
	v_cvt_pk_bf16_f32 v79, v88, v89
	v_cvt_pk_bf16_f32 v80, v80, v81
	v_cvt_pk_bf16_f32 v81, v90, v91
	global_store_dwordx4 v[94:95], v[78:81], off offset:256
	v_lshlrev_b32_e32 v86, 16, v136
	v_and_b32_e32 v87, 0xffff0000, v136
	v_lshlrev_b32_e32 v78, 16, v134
	v_and_b32_e32 v79, 0xffff0000, v134
	v_lshlrev_b32_e32 v80, 16, v135
	v_and_b32_e32 v81, 0xffff0000, v135
	v_lshlrev_b32_e32 v88, 16, v137
	v_and_b32_e32 v89, 0xffff0000, v137
	v_pk_fma_f32 v[78:79], v[78:79], s[28:29], v[82:83] op_sel_hi:[1,0,1]
	v_pk_fma_f32 v[80:81], v[80:81], s[28:29], v[84:85] op_sel_hi:[1,0,1]
	v_pk_fma_f32 v[82:83], v[88:89], s[28:29], v[76:77] op_sel_hi:[1,0,1]
	v_pk_fma_f32 v[76:77], v[86:87], s[28:29], v[74:75] op_sel_hi:[1,0,1]
	v_cvt_pk_bf16_f32 v74, v78, v79
	v_add_co_u32_e32 v78, vcc, s47, v122
	v_cvt_pk_bf16_f32 v75, v80, v81
	v_cvt_pk_bf16_f32 v76, v76, v77
	v_cvt_pk_bf16_f32 v77, v82, v83
	v_addc_co_u32_e32 v79, vcc, 0, v123, vcc
	global_store_dwordx4 v[78:79], v[74:77], off
	v_lshlrev_b32_e32 v80, 16, v132
	v_and_b32_e32 v81, 0xffff0000, v132
	v_lshlrev_b32_e32 v74, 16, v130
	v_and_b32_e32 v75, 0xffff0000, v130
	v_lshlrev_b32_e32 v76, 16, v131
	v_and_b32_e32 v77, 0xffff0000, v131
	v_lshlrev_b32_e32 v82, 16, v133
	v_and_b32_e32 v83, 0xffff0000, v133
	v_pk_fma_f32 v[72:73], v[76:77], s[28:29], v[72:73] op_sel_hi:[1,0,1]
	v_pk_fma_f32 v[70:71], v[74:75], s[28:29], v[70:71] op_sel_hi:[1,0,1]
	v_pk_fma_f32 v[74:75], v[82:83], s[28:29], v[68:69] op_sel_hi:[1,0,1]
	v_pk_fma_f32 v[68:69], v[80:81], s[28:29], v[66:67] op_sel_hi:[1,0,1]
	v_cvt_pk_bf16_f32 v66, v70, v71
	v_cvt_pk_bf16_f32 v67, v72, v73
	v_cvt_pk_bf16_f32 v68, v68, v69
	v_cvt_pk_bf16_f32 v69, v74, v75
	global_store_dwordx4 v[78:79], v[66:69], off offset:256
	s_nop 1
	v_add_u32_e32 v66, 0x80, v171
	s_nop 0
	v_ashrrev_i32_e32 v67, 31, v66
	v_lshlrev_b64 v[66:67], 10, v[66:67]
	v_lshl_add_u64 v[66:67], v[66:67], 0, v[164:165]
	v_lshlrev_b64 v[98:99], 1, v[66:67]
	v_lshl_add_u64 v[90:91], s[10:11], 0, v[98:99]
	global_load_dwordx4 v[66:69], v[90:91], off
	global_load_dwordx4 v[70:73], v[90:91], off offset:256
	v_add_co_u32_e32 v78, vcc, s48, v90
	s_waitcnt vmcnt(0) lgkmcnt(0)
	v_lshlrev_b32_e32 v100, 16, v66
	v_addc_co_u32_e32 v79, vcc, 0, v91, vcc
	global_load_dwordx4 v[74:77], v[78:79], off
	s_nop 0
	global_load_dwordx4 v[78:81], v[78:79], off offset:256
	v_add_co_u32_e32 v86, vcc, s44, v90
	v_and_b32_e32 v101, 0xffff0000, v66
	s_nop 0
	v_addc_co_u32_e32 v87, vcc, 0, v91, vcc
	global_load_dwordx4 v[82:85], v[86:87], off
	s_nop 0
	global_load_dwordx4 v[86:89], v[86:87], off offset:256
	v_add_co_u32_e32 v94, vcc, s47, v90
	v_lshlrev_b32_e32 v66, 16, v67
	s_nop 0
	v_addc_co_u32_e32 v95, vcc, 0, v91, vcc
	global_load_dwordx4 v[90:93], v[94:95], off
	s_nop 0
	global_load_dwordx4 v[94:97], v[94:95], off offset:256
	v_and_b32_e32 v67, 0xffff0000, v67
	v_lshlrev_b32_e32 v102, 16, v68
	v_and_b32_e32 v103, 0xffff0000, v68
	v_lshlrev_b32_e32 v68, 16, v69
	v_and_b32_e32 v69, 0xffff0000, v69
	v_pk_fma_f32 v[64:65], v[66:67], s[28:29], v[64:65] op_sel_hi:[1,0,1]
	v_pk_fma_f32 v[62:63], v[100:101], s[28:29], v[62:63] op_sel_hi:[1,0,1]
	v_pk_fma_f32 v[66:67], v[68:69], s[28:29], v[60:61] op_sel_hi:[1,0,1]
	v_pk_fma_f32 v[60:61], v[102:103], s[28:29], v[58:59] op_sel_hi:[1,0,1]
	v_cvt_pk_bf16_f32 v58, v62, v63
	v_cvt_pk_bf16_f32 v59, v64, v65
	v_cvt_pk_bf16_f32 v60, v60, v61
	v_cvt_pk_bf16_f32 v61, v66, v67
	v_lshl_add_u64 v[62:63], s[16:17], 0, v[98:99]
	global_store_dwordx4 v[62:63], v[58:61], off
	v_lshlrev_b32_e32 v64, 16, v72
	v_and_b32_e32 v65, 0xffff0000, v72
	v_lshlrev_b32_e32 v58, 16, v70
	v_and_b32_e32 v59, 0xffff0000, v70
	v_lshlrev_b32_e32 v60, 16, v71
	v_and_b32_e32 v61, 0xffff0000, v71
	v_lshlrev_b32_e32 v66, 16, v73
	v_and_b32_e32 v67, 0xffff0000, v73
	v_pk_fma_f32 v[56:57], v[60:61], s[28:29], v[56:57] op_sel_hi:[1,0,1]
	v_pk_fma_f32 v[54:55], v[58:59], s[28:29], v[54:55] op_sel_hi:[1,0,1]
	v_pk_fma_f32 v[58:59], v[66:67], s[28:29], v[48:49] op_sel_hi:[1,0,1]
	v_pk_fma_f32 v[48:49], v[64:65], s[28:29], v[46:47] op_sel_hi:[1,0,1]
	v_cvt_pk_bf16_f32 v46, v54, v55
	v_cvt_pk_bf16_f32 v47, v56, v57
	v_cvt_pk_bf16_f32 v48, v48, v49
	v_cvt_pk_bf16_f32 v49, v58, v59
	global_store_dwordx4 v[62:63], v[46:49], off offset:256
	s_waitcnt vmcnt(0) lgkmcnt(0)
	v_lshlrev_b32_e32 v54, 16, v76
	v_lshlrev_b32_e32 v46, 16, v74
	v_and_b32_e32 v47, 0xffff0000, v74
	v_lshlrev_b32_e32 v48, 16, v75
	v_and_b32_e32 v49, 0xffff0000, v75
	v_and_b32_e32 v55, 0xffff0000, v76
	v_lshlrev_b32_e32 v56, 16, v77
	v_and_b32_e32 v57, 0xffff0000, v77
	v_pk_fma_f32 v[46:47], v[46:47], s[28:29], v[50:51] op_sel_hi:[1,0,1]
	v_pk_fma_f32 v[48:49], v[48:49], s[28:29], v[52:53] op_sel_hi:[1,0,1]
	v_pk_fma_f32 v[50:51], v[56:57], s[28:29], v[44:45] op_sel_hi:[1,0,1]
	v_pk_fma_f32 v[44:45], v[54:55], s[28:29], v[42:43] op_sel_hi:[1,0,1]
	v_cvt_pk_bf16_f32 v42, v46, v47
	v_add_co_u32_e32 v46, vcc, s48, v62
	v_cvt_pk_bf16_f32 v43, v48, v49
	v_cvt_pk_bf16_f32 v44, v44, v45
	v_cvt_pk_bf16_f32 v45, v50, v51
	v_addc_co_u32_e32 v47, vcc, 0, v63, vcc
	global_store_dwordx4 v[46:47], v[42:45], off
	v_lshlrev_b32_e32 v48, 16, v80
	v_and_b32_e32 v49, 0xffff0000, v80
	v_lshlrev_b32_e32 v42, 16, v78
	v_and_b32_e32 v43, 0xffff0000, v78
	v_lshlrev_b32_e32 v44, 16, v79
	v_and_b32_e32 v45, 0xffff0000, v79
	v_lshlrev_b32_e32 v50, 16, v81
	v_and_b32_e32 v51, 0xffff0000, v81
	v_pk_fma_f32 v[40:41], v[44:45], s[28:29], v[40:41] op_sel_hi:[1,0,1]
	v_pk_fma_f32 v[38:39], v[42:43], s[28:29], v[38:39] op_sel_hi:[1,0,1]
	v_pk_fma_f32 v[42:43], v[50:51], s[28:29], v[32:33] op_sel_hi:[1,0,1]
	v_pk_fma_f32 v[32:33], v[48:49], s[28:29], v[30:31] op_sel_hi:[1,0,1]
	v_cvt_pk_bf16_f32 v30, v38, v39
	v_cvt_pk_bf16_f32 v31, v40, v41
	v_cvt_pk_bf16_f32 v32, v32, v33
	v_cvt_pk_bf16_f32 v33, v42, v43
	global_store_dwordx4 v[46:47], v[30:33], off offset:256
	v_lshlrev_b32_e32 v38, 16, v84
	v_and_b32_e32 v39, 0xffff0000, v84
	v_lshlrev_b32_e32 v30, 16, v82
	v_and_b32_e32 v31, 0xffff0000, v82
	v_lshlrev_b32_e32 v32, 16, v83
	v_and_b32_e32 v33, 0xffff0000, v83
	v_lshlrev_b32_e32 v40, 16, v85
	v_and_b32_e32 v41, 0xffff0000, v85
	v_pk_fma_f32 v[30:31], v[30:31], s[28:29], v[34:35] op_sel_hi:[1,0,1]
	v_pk_fma_f32 v[32:33], v[32:33], s[28:29], v[36:37] op_sel_hi:[1,0,1]
	v_pk_fma_f32 v[34:35], v[40:41], s[28:29], v[28:29] op_sel_hi:[1,0,1]
	v_pk_fma_f32 v[28:29], v[38:39], s[28:29], v[26:27] op_sel_hi:[1,0,1]
	v_cvt_pk_bf16_f32 v26, v30, v31
	v_add_co_u32_e32 v30, vcc, s44, v62
	v_cvt_pk_bf16_f32 v27, v32, v33
	v_cvt_pk_bf16_f32 v28, v28, v29
	v_cvt_pk_bf16_f32 v29, v34, v35
	v_addc_co_u32_e32 v31, vcc, 0, v63, vcc
	global_store_dwordx4 v[30:31], v[26:29], off
	v_lshlrev_b32_e32 v32, 16, v88
	v_and_b32_e32 v33, 0xffff0000, v88
	v_lshlrev_b32_e32 v26, 16, v86
	v_and_b32_e32 v27, 0xffff0000, v86
	v_lshlrev_b32_e32 v28, 16, v87
	v_and_b32_e32 v29, 0xffff0000, v87
	v_lshlrev_b32_e32 v34, 16, v89
	v_and_b32_e32 v35, 0xffff0000, v89
	v_pk_fma_f32 v[24:25], v[28:29], s[28:29], v[24:25] op_sel_hi:[1,0,1]
	v_pk_fma_f32 v[22:23], v[26:27], s[28:29], v[22:23] op_sel_hi:[1,0,1]
	v_pk_fma_f32 v[26:27], v[34:35], s[28:29], v[16:17] op_sel_hi:[1,0,1]
	v_pk_fma_f32 v[16:17], v[32:33], s[28:29], v[14:15] op_sel_hi:[1,0,1]
	v_cvt_pk_bf16_f32 v14, v22, v23
	v_cvt_pk_bf16_f32 v15, v24, v25
	v_cvt_pk_bf16_f32 v16, v16, v17
	v_cvt_pk_bf16_f32 v17, v26, v27
	global_store_dwordx4 v[30:31], v[14:17], off offset:256
	v_lshlrev_b32_e32 v22, 16, v92
	v_and_b32_e32 v23, 0xffff0000, v92
	v_lshlrev_b32_e32 v14, 16, v90
	v_and_b32_e32 v15, 0xffff0000, v90
	v_lshlrev_b32_e32 v16, 16, v91
	v_and_b32_e32 v17, 0xffff0000, v91
	v_lshlrev_b32_e32 v24, 16, v93
	v_and_b32_e32 v25, 0xffff0000, v93
	v_pk_fma_f32 v[14:15], v[14:15], s[28:29], v[18:19] op_sel_hi:[1,0,1]
	v_pk_fma_f32 v[16:17], v[16:17], s[28:29], v[20:21] op_sel_hi:[1,0,1]
	v_pk_fma_f32 v[18:19], v[24:25], s[28:29], v[12:13] op_sel_hi:[1,0,1]
	v_pk_fma_f32 v[12:13], v[22:23], s[28:29], v[10:11] op_sel_hi:[1,0,1]
	v_cvt_pk_bf16_f32 v10, v14, v15
	v_add_co_u32_e32 v14, vcc, s47, v62
	v_cvt_pk_bf16_f32 v11, v16, v17
	v_cvt_pk_bf16_f32 v12, v12, v13
	v_cvt_pk_bf16_f32 v13, v18, v19
	v_addc_co_u32_e32 v15, vcc, 0, v63, vcc
	global_store_dwordx4 v[14:15], v[10:13], off
	v_lshlrev_b32_e32 v16, 16, v96
	v_and_b32_e32 v17, 0xffff0000, v96
	v_lshlrev_b32_e32 v10, 16, v94
	v_and_b32_e32 v11, 0xffff0000, v94
	v_lshlrev_b32_e32 v12, 16, v95
	v_and_b32_e32 v13, 0xffff0000, v95
	v_lshlrev_b32_e32 v18, 16, v97
	v_and_b32_e32 v19, 0xffff0000, v97
	v_pk_fma_f32 v[8:9], v[12:13], s[28:29], v[8:9] op_sel_hi:[1,0,1]
	v_pk_fma_f32 v[6:7], v[10:11], s[28:29], v[6:7] op_sel_hi:[1,0,1]
	v_pk_fma_f32 v[10:11], v[18:19], s[28:29], v[4:5] op_sel_hi:[1,0,1]
	v_pk_fma_f32 v[4:5], v[16:17], s[28:29], v[2:3] op_sel_hi:[1,0,1]
	v_cvt_pk_bf16_f32 v2, v6, v7
	v_cvt_pk_bf16_f32 v3, v8, v9
	v_cvt_pk_bf16_f32 v4, v4, v5
	v_cvt_pk_bf16_f32 v5, v10, v11
	s_and_b64 vcc, exec, s[30:31]
	global_store_dwordx4 v[14:15], v[2:5], off offset:256
	s_cbranch_vccz .LBB0_2494
	s_waitcnt vmcnt(0)
	s_cmpk_gt_u32 s5, 0xff
	s_cbranch_scc1 .LBB0_2499
	s_barrier

.LBB0_2749:
	s_add_u32 s10, s34, 0x100
	s_addc_u32 s11, s35, 0
	s_add_u32 s30, s29, s34
	s_addc_u32 s31, s55, s35
	s_cmpk_eq_i32 s34, 0x300
	s_cselect_b64 vcc, -1, 0
	s_and_b64 s[0:1], vcc, exec
	s_cselect_b32 s1, 0, s10
	s_cselect_b32 s0, 0, s11
	s_cselect_b32 s30, s27, s30
	s_cselect_b32 s31, s25, s31
	s_add_u32 s36, s14, s1
	s_addc_u32 s37, s15, s0
	s_add_i32 s1, 0, 0x10000
	v_add_u32_e32 v14, s1, v196
	ds_read_b128 v[2:5], v14
	ds_read_b128 v[6:9], v14 offset:1024
	ds_read_b128 v[10:13], v14 offset:2048
	ds_read_b128 v[14:17], v14 offset:3072
	v_cndmask_b32_e32 v162, v168, v171, vcc
	v_cndmask_b32_e32 v184, v170, v197, vcc
	v_cndmask_b32_e32 v175, v172, v198, vcc
	v_cndmask_b32_e32 v173, v174, v199, vcc
	v_lshl_add_u64 v[18:19], v[178:179], 0, s[34:35]
	s_add_i32 m0, s45, 0xc000
	ds_read_b128 v[200:203], v169
	ds_read_b128 v[204:207], v169 offset:1024
	ds_read_b128 v[208:211], v169 offset:2048
	ds_read_b128 v[212:215], v169 offset:3072
	ds_read_b128 v[216:219], v169 offset:4096
	ds_read_b128 v[220:223], v169 offset:5120
	ds_read_b128 v[224:227], v169 offset:6144
	ds_read_b128 v[228:231], v169 offset:7168
	global_load_lds_dwordx4 v[18:19], off
	v_lshl_add_u64 v[18:19], v[176:177], 0, s[34:35]
	s_add_i32 m0, s45, 0xe000
	s_nop 0
	global_load_lds_dwordx4 v[18:19], off
	s_waitcnt lgkmcnt(8)
	s_waitcnt vmcnt(10)
	s_barrier
	s_waitcnt lgkmcnt(0)
	v_mfma_scale_f32_16x16x128_f8f6f4 v[158:161], v[2:9], v[200:207], v[158:161], v1, v1 op_sel_hi:[0,0,0]
	v_mfma_scale_f32_16x16x128_f8f6f4 v[150:153], v[10:17], v[200:207], v[150:153], v1, v1 op_sel_hi:[0,0,0]
	v_mfma_scale_f32_16x16x128_f8f6f4 v[142:145], v[2:9], v[208:215], v[142:145], v1, v1 op_sel_hi:[0,0,0]
	v_mfma_scale_f32_16x16x128_f8f6f4 v[134:137], v[10:17], v[208:215], v[134:137], v1, v1 op_sel_hi:[0,0,0]
	v_mfma_scale_f32_16x16x128_f8f6f4 v[126:129], v[2:9], v[216:223], v[126:129], v1, v1 op_sel_hi:[0,0,0]
	v_mfma_scale_f32_16x16x128_f8f6f4 v[118:121], v[10:17], v[216:223], v[118:121], v1, v1 op_sel_hi:[0,0,0]
	v_mfma_scale_f32_16x16x128_f8f6f4 v[110:113], v[2:9], v[224:231], v[110:113], v1, v1 op_sel_hi:[0,0,0]
	v_mfma_scale_f32_16x16x128_f8f6f4 v[102:105], v[10:17], v[224:231], v[102:105], v1, v1 op_sel_hi:[0,0,0]
	s_barrier
	s_add_i32 s0, 0, 0x14000
	s_add_i32 s1, s1, s43
	v_add_u32_e32 v30, s0, v196
	v_lshl_add_u64 v[180:181], s[30:31], 0, v[164:165]
	s_mov_b32 m0, s1
	ds_read_b128 v[18:21], v30
	ds_read_b128 v[22:25], v30 offset:1024
	ds_read_b128 v[26:29], v30 offset:2048
	ds_read_b128 v[30:33], v30 offset:3072
	global_load_lds_dwordx4 v[180:181], off
	v_lshl_add_u64 v[182:183], s[30:31], 0, v[166:167]
	s_add_i32 m0, s1, 0x2000
	s_nop 0
	global_load_lds_dwordx4 v[182:183], off
	s_waitcnt vmcnt(10)
	s_barrier
	s_waitcnt lgkmcnt(0)
	v_mfma_scale_f32_16x16x128_f8f6f4 v[154:157], v[18:25], v[200:207], v[154:157], v1, v1 op_sel_hi:[0,0,0]
	v_mfma_scale_f32_16x16x128_f8f6f4 v[146:149], v[26:33], v[200:207], v[146:149], v1, v1 op_sel_hi:[0,0,0]
	v_mfma_scale_f32_16x16x128_f8f6f4 v[138:141], v[18:25], v[208:215], v[138:141], v1, v1 op_sel_hi:[0,0,0]
	v_mfma_scale_f32_16x16x128_f8f6f4 v[130:133], v[26:33], v[208:215], v[130:133], v1, v1 op_sel_hi:[0,0,0]
	v_mfma_scale_f32_16x16x128_f8f6f4 v[122:125], v[18:25], v[216:223], v[122:125], v1, v1 op_sel_hi:[0,0,0]
	v_mfma_scale_f32_16x16x128_f8f6f4 v[114:117], v[26:33], v[216:223], v[114:117], v1, v1 op_sel_hi:[0,0,0]
	v_mfma_scale_f32_16x16x128_f8f6f4 v[106:109], v[18:25], v[224:231], v[106:109], v1, v1 op_sel_hi:[0,0,0]
	v_mfma_scale_f32_16x16x128_f8f6f4 v[98:101], v[26:33], v[224:231], v[98:101], v1, v1 op_sel_hi:[0,0,0]
	s_mov_b32 m0, s45
	s_barrier
	ds_read_b128 v[200:203], v169 offset:16384
	ds_read_b128 v[204:207], v169 offset:17408
	ds_read_b128 v[208:211], v169 offset:18432
	ds_read_b128 v[212:215], v169 offset:19456
	ds_read_b128 v[216:219], v169 offset:20480
	ds_read_b128 v[220:223], v169 offset:21504
	ds_read_b128 v[224:227], v169 offset:22528
	ds_read_b128 v[228:231], v169 offset:23552
	global_load_lds_dwordx4 v162, s[36:37]
	s_mov_b32 m0, s46
	v_mov_b32_e32 v185, v163
	global_load_lds_dwordx4 v184, s[36:37]
	s_waitcnt vmcnt(10)
	s_barrier
	s_waitcnt lgkmcnt(0)
	v_lshl_add_u64 v[186:187], s[36:37], 0, v[162:163]
	v_lshl_add_u64 v[184:185], s[36:37], 0, v[184:185]
	s_waitcnt lgkmcnt(0)
	v_mfma_scale_f32_16x16x128_f8f6f4 v[94:97], v[2:9], v[200:207], v[94:97], v1, v1 op_sel_hi:[0,0,0]
	v_mfma_scale_f32_16x16x128_f8f6f4 v[86:89], v[10:17], v[200:207], v[86:89], v1, v1 op_sel_hi:[0,0,0]
	v_mfma_scale_f32_16x16x128_f8f6f4 v[78:81], v[2:9], v[208:215], v[78:81], v1, v1 op_sel_hi:[0,0,0]
	v_mfma_scale_f32_16x16x128_f8f6f4 v[70:73], v[10:17], v[208:215], v[70:73], v1, v1 op_sel_hi:[0,0,0]
	v_mfma_scale_f32_16x16x128_f8f6f4 v[62:65], v[2:9], v[216:223], v[62:65], v1, v1 op_sel_hi:[0,0,0]
	v_mfma_scale_f32_16x16x128_f8f6f4 v[54:57], v[10:17], v[216:223], v[54:57], v1, v1 op_sel_hi:[0,0,0]
	v_mfma_scale_f32_16x16x128_f8f6f4 v[46:49], v[2:9], v[224:231], v[46:49], v1, v1 op_sel_hi:[0,0,0]
	v_mfma_scale_f32_16x16x128_f8f6f4 v[38:41], v[10:17], v[224:231], v[38:41], v1, v1 op_sel_hi:[0,0,0]
	s_barrier
	s_add_u32 s34, s30, 0x20000
	s_addc_u32 s35, s31, 0
	s_add_i32 s0, s0, s43
	v_lshl_add_u64 v[2:3], s[34:35], 0, v[164:165]
	s_mov_b32 m0, s0
	s_nop 0
	global_load_lds_dwordx4 v[2:3], off
	v_lshl_add_u64 v[2:3], s[34:35], 0, v[166:167]
	s_add_i32 m0, s0, 0x2000
	s_nop 0
	global_load_lds_dwordx4 v[2:3], off
	s_waitcnt vmcnt(10)
	s_barrier
	v_mfma_scale_f32_16x16x128_f8f6f4 v[90:93], v[18:25], v[200:207], v[90:93], v1, v1 op_sel_hi:[0,0,0]
	v_mfma_scale_f32_16x16x128_f8f6f4 v[82:85], v[26:33], v[200:207], v[82:85], v1, v1 op_sel_hi:[0,0,0]
	v_mfma_scale_f32_16x16x128_f8f6f4 v[74:77], v[18:25], v[208:215], v[74:77], v1, v1 op_sel_hi:[0,0,0]
	v_mfma_scale_f32_16x16x128_f8f6f4 v[66:69], v[26:33], v[208:215], v[66:69], v1, v1 op_sel_hi:[0,0,0]
	v_mfma_scale_f32_16x16x128_f8f6f4 v[58:61], v[18:25], v[216:223], v[58:61], v1, v1 op_sel_hi:[0,0,0]
	v_mfma_scale_f32_16x16x128_f8f6f4 v[50:53], v[26:33], v[216:223], v[50:53], v1, v1 op_sel_hi:[0,0,0]
	v_mfma_scale_f32_16x16x128_f8f6f4 v[42:45], v[18:25], v[224:231], v[42:45], v1, v1 op_sel_hi:[0,0,0]
	v_mfma_scale_f32_16x16x128_f8f6f4 v[34:37], v[26:33], v[224:231], v[34:37], v1, v1 op_sel_hi:[0,0,0]
	s_add_i32 s0, 0, 0x18000
	v_add_u32_e32 v14, s0, v196
	s_barrier
	ds_read_b128 v[2:5], v14
	ds_read_b128 v[6:9], v14 offset:1024
	ds_read_b128 v[10:13], v14 offset:2048
	ds_read_b128 v[14:17], v14 offset:3072
	s_mov_b32 m0, s47
	ds_read_b128 v[18:21], v169 offset:32768
	ds_read_b128 v[22:25], v169 offset:33792
	ds_read_b128 v[26:29], v169 offset:34816
	ds_read_b128 v[30:33], v169 offset:35840
	ds_read_b128 v[200:203], v169 offset:36864
	ds_read_b128 v[204:207], v169 offset:37888
	ds_read_b128 v[208:211], v169 offset:38912
	ds_read_b128 v[212:215], v169 offset:39936
	global_load_lds_dwordx4 v175, s[36:37]
	s_mov_b32 m0, s48
	s_nop 0
	global_load_lds_dwordx4 v173, s[36:37]
	s_waitcnt lgkmcnt(8)
	s_waitcnt vmcnt(10)
	s_barrier
	s_waitcnt lgkmcnt(0)
	v_mfma_scale_f32_16x16x128_f8f6f4 v[158:161], v[2:9], v[18:25], v[158:161], v1, v1 op_sel_hi:[0,0,0]
	v_mfma_scale_f32_16x16x128_f8f6f4 v[150:153], v[10:17], v[18:25], v[150:153], v1, v1 op_sel_hi:[0,0,0]
	v_mfma_scale_f32_16x16x128_f8f6f4 v[142:145], v[2:9], v[26:33], v[142:145], v1, v1 op_sel_hi:[0,0,0]
	v_mfma_scale_f32_16x16x128_f8f6f4 v[134:137], v[10:17], v[26:33], v[134:137], v1, v1 op_sel_hi:[0,0,0]
	v_mfma_scale_f32_16x16x128_f8f6f4 v[126:129], v[2:9], v[200:207], v[126:129], v1, v1 op_sel_hi:[0,0,0]
	v_mfma_scale_f32_16x16x128_f8f6f4 v[118:121], v[10:17], v[200:207], v[118:121], v1, v1 op_sel_hi:[0,0,0]
	v_mfma_scale_f32_16x16x128_f8f6f4 v[110:113], v[2:9], v[208:215], v[110:113], v1, v1 op_sel_hi:[0,0,0]
	v_mfma_scale_f32_16x16x128_f8f6f4 v[102:105], v[10:17], v[208:215], v[102:105], v1, v1 op_sel_hi:[0,0,0]
	s_barrier
	s_add_i32 s34, 0, 0x1c000
	s_add_i32 s0, s0, s43
	v_add_u32_e32 v162, s34, v196
	v_lshl_add_u64 v[180:181], v[180:181], 0, s[20:21]
	s_mov_b32 m0, s0
	ds_read_b128 v[216:219], v162
	ds_read_b128 v[220:223], v162 offset:1024
	ds_read_b128 v[224:227], v162 offset:2048
	ds_read_b128 v[228:231], v162 offset:3072
	global_load_lds_dwordx4 v[180:181], off
	v_lshl_add_u64 v[180:181], v[182:183], 0, s[20:21]
	s_add_i32 m0, s0, 0x2000
	s_nop 0
	global_load_lds_dwordx4 v[180:181], off
	s_waitcnt vmcnt(10)
	s_barrier
	s_waitcnt lgkmcnt(0)
	v_mfma_scale_f32_16x16x128_f8f6f4 v[154:157], v[216:223], v[18:25], v[154:157], v1, v1 op_sel_hi:[0,0,0]
	v_mfma_scale_f32_16x16x128_f8f6f4 v[146:149], v[224:231], v[18:25], v[146:149], v1, v1 op_sel_hi:[0,0,0]
	v_mfma_scale_f32_16x16x128_f8f6f4 v[138:141], v[216:223], v[26:33], v[138:141], v1, v1 op_sel_hi:[0,0,0]
	v_mfma_scale_f32_16x16x128_f8f6f4 v[130:133], v[224:231], v[26:33], v[130:133], v1, v1 op_sel_hi:[0,0,0]
	v_mfma_scale_f32_16x16x128_f8f6f4 v[122:125], v[216:223], v[200:207], v[122:125], v1, v1 op_sel_hi:[0,0,0]
	v_mfma_scale_f32_16x16x128_f8f6f4 v[114:117], v[224:231], v[200:207], v[114:117], v1, v1 op_sel_hi:[0,0,0]
	v_mfma_scale_f32_16x16x128_f8f6f4 v[106:109], v[216:223], v[208:215], v[106:109], v1, v1 op_sel_hi:[0,0,0]
	v_mfma_scale_f32_16x16x128_f8f6f4 v[98:101], v[224:231], v[208:215], v[98:101], v1, v1 op_sel_hi:[0,0,0]
	s_mov_b32 m0, s51
	v_lshl_add_u64 v[180:181], v[186:187], 0, s[20:21]
	s_barrier
	ds_read_b128 v[18:21], v169 offset:49152
	ds_read_b128 v[22:25], v169 offset:50176
	ds_read_b128 v[26:29], v169 offset:51200
	ds_read_b128 v[30:33], v169 offset:52224
	ds_read_b128 v[200:203], v169 offset:53248
	ds_read_b128 v[204:207], v169 offset:54272
	ds_read_b128 v[208:211], v169 offset:55296
	ds_read_b128 v[212:215], v169 offset:56320
	global_load_lds_dwordx4 v[180:181], off
	v_lshl_add_u64 v[180:181], v[184:185], 0, s[20:21]
	s_mov_b32 m0, s52
	s_nop 0
	global_load_lds_dwordx4 v[180:181], off
	s_waitcnt vmcnt(10)
	s_barrier
	s_waitcnt lgkmcnt(0)
	v_mfma_scale_f32_16x16x128_f8f6f4 v[94:97], v[2:9], v[18:25], v[94:97], v1, v1 op_sel_hi:[0,0,0]
	v_mfma_scale_f32_16x16x128_f8f6f4 v[86:89], v[10:17], v[18:25], v[86:89], v1, v1 op_sel_hi:[0,0,0]
	v_mfma_scale_f32_16x16x128_f8f6f4 v[78:81], v[2:9], v[26:33], v[78:81], v1, v1 op_sel_hi:[0,0,0]
	v_mfma_scale_f32_16x16x128_f8f6f4 v[70:73], v[10:17], v[26:33], v[70:73], v1, v1 op_sel_hi:[0,0,0]
	v_mfma_scale_f32_16x16x128_f8f6f4 v[62:65], v[2:9], v[200:207], v[62:65], v1, v1 op_sel_hi:[0,0,0]
	v_mfma_scale_f32_16x16x128_f8f6f4 v[54:57], v[10:17], v[200:207], v[54:57], v1, v1 op_sel_hi:[0,0,0]
	v_mfma_scale_f32_16x16x128_f8f6f4 v[46:49], v[2:9], v[208:215], v[46:49], v1, v1 op_sel_hi:[0,0,0]
	v_mfma_scale_f32_16x16x128_f8f6f4 v[38:41], v[10:17], v[208:215], v[38:41], v1, v1 op_sel_hi:[0,0,0]
	s_barrier
	s_add_u32 s0, s30, 0x20080
	s_addc_u32 s1, s31, 0
	s_add_i32 s30, s34, s43
	v_lshl_add_u64 v[2:3], s[0:1], 0, v[164:165]
	s_mov_b32 m0, s30
	s_nop 0
	global_load_lds_dwordx4 v[2:3], off
	v_lshl_add_u64 v[2:3], s[0:1], 0, v[166:167]
	s_add_i32 m0, s30, 0x2000
	s_nop 0
	global_load_lds_dwordx4 v[2:3], off
	s_waitcnt vmcnt(10)
	s_barrier
	v_mfma_scale_f32_16x16x128_f8f6f4 v[90:93], v[216:223], v[18:25], v[90:93], v1, v1 op_sel_hi:[0,0,0]
	v_mfma_scale_f32_16x16x128_f8f6f4 v[82:85], v[224:231], v[18:25], v[82:85], v1, v1 op_sel_hi:[0,0,0]
	v_mfma_scale_f32_16x16x128_f8f6f4 v[74:77], v[216:223], v[26:33], v[74:77], v1, v1 op_sel_hi:[0,0,0]
	v_mfma_scale_f32_16x16x128_f8f6f4 v[66:69], v[224:231], v[26:33], v[66:69], v1, v1 op_sel_hi:[0,0,0]
	v_mfma_scale_f32_16x16x128_f8f6f4 v[58:61], v[216:223], v[200:207], v[58:61], v1, v1 op_sel_hi:[0,0,0]
	v_mfma_scale_f32_16x16x128_f8f6f4 v[50:53], v[224:231], v[200:207], v[50:53], v1, v1 op_sel_hi:[0,0,0]
	v_mfma_scale_f32_16x16x128_f8f6f4 v[42:45], v[216:223], v[208:215], v[42:45], v1, v1 op_sel_hi:[0,0,0]
	v_mfma_scale_f32_16x16x128_f8f6f4 v[34:37], v[224:231], v[208:215], v[34:37], v1, v1 op_sel_hi:[0,0,0]
	s_add_i32 s56, s56, 2
	s_cmp_gt_u32 s56, 5
	s_mov_b64 s[34:35], s[10:11]
	s_barrier
	s_cbranch_scc0 .LBB0_2749
	v_mul_f32_e32 v5, 0x3c800000, v158
	v_mul_f32_e32 v6, 0xbfb8aa3b, v5
	v_exp_f32_e32 v6, v6
	s_ashr_i32 s29, s28, 31
	s_ashr_i32 s27, s26, 31
	s_lshl_b64 s[10:11], s[28:29], 18
	v_add_f32_e32 v6, 1.0, v6
	v_rcp_f32_e32 v6, v6
	s_lshl_b64 s[26:27], s[26:27], 15
	v_mov_b32_e32 v3, v194
	s_add_u32 s0, s8, s10
	v_mul_f32_e32 v5, v5, v6
	v_mul_f32_e32 v6, 0x3c800000, v159
	v_mul_f32_e32 v7, 0xbfb8aa3b, v6
	v_exp_f32_e32 v7, v7
	v_mul_f32_e32 v5, v5, v154
	v_mul_f32_e32 v5, 0x3e000000, v5
	v_med3_f32 v5, v5, s40, v189
	v_add_f32_e32 v7, 1.0, v7
	v_rcp_f32_e32 v7, v7
	s_nop 15
	s_nop 15
	v_mov_b32_e32 v2, v195
	v_mul_f32_e32 v6, v6, v7
	v_mul_f32_e32 v7, 0x3c800000, v160
	v_mul_f32_e32 v8, 0xbfb8aa3b, v7
	v_exp_f32_e32 v8, v8
	v_mul_f32_e32 v6, v6, v155
	v_mul_f32_e32 v6, 0x3e000000, v6
	v_add_u32_e32 v4, s49, v3
	v_add_f32_e32 v8, 1.0, v8
	v_rcp_f32_e32 v8, v8
	s_addc_u32 s1, s9, s11
	s_add_u32 s10, s0, s26
	v_mul_f32_e32 v7, v7, v8
	v_mul_f32_e32 v8, 0x3c800000, v161
	v_mul_f32_e32 v9, 0xbfb8aa3b, v8
	v_exp_f32_e32 v9, v9
	v_mul_f32_e32 v7, v7, v156
	v_mul_f32_e32 v7, 0x3e000000, v7
	v_lshl_add_u32 v2, v2, 3, s50
	v_add_f32_e32 v9, 1.0, v9
	v_rcp_f32_e32 v9, v9
	s_addc_u32 s11, s1, s27
	v_ashrrev_i32_e32 v3, 31, v2
	s_and_b64 vcc, exec, s[6:7]
	v_mul_f32_e32 v8, v8, v9
	v_mul_f32_e32 v9, 0x3c800000, v150
	v_mul_f32_e32 v10, 0xbfb8aa3b, v9
	v_exp_f32_e32 v10, v10
	v_mul_f32_e32 v8, v8, v157
	v_mul_f32_e32 v8, 0x3e000000, v8
	v_mov_b32_e32 v174, v199
	v_add_f32_e32 v10, 1.0, v10
	v_rcp_f32_e32 v10, v10
	v_mov_b32_e32 v172, v198
	v_mov_b32_e32 v170, v197
	v_mov_b32_e32 v168, v171
	v_mul_f32_e32 v9, v9, v10
	v_mul_f32_e32 v10, 0x3c800000, v151
	v_mul_f32_e32 v11, 0xbfb8aa3b, v10
	v_exp_f32_e32 v11, v11
	v_mul_f32_e32 v9, v9, v146
	v_mul_f32_e32 v9, 0x3e000000, v9
	s_mov_b32 s26, s24
	v_add_f32_e32 v11, 1.0, v11
	v_rcp_f32_e32 v11, v11
	s_mov_b32 s28, s54
	s_mov_b64 s[30:31], s[12:13]
	v_mul_f32_e32 v10, v10, v11
	v_mul_f32_e32 v11, 0x3c800000, v152
	v_mul_f32_e32 v12, 0xbfb8aa3b, v11
	v_exp_f32_e32 v12, v12
	v_mul_f32_e32 v10, v10, v147
	v_mul_f32_e32 v10, 0x3e000000, v10
	v_add_f32_e32 v12, 1.0, v12
	v_rcp_f32_e32 v12, v12
	s_nop 0
	v_mul_f32_e32 v11, v11, v12
	v_mul_f32_e32 v12, 0x3c800000, v153
	v_mul_f32_e32 v13, 0xbfb8aa3b, v12
	v_exp_f32_e32 v13, v13
	v_mul_f32_e32 v11, v11, v148
	v_mul_f32_e32 v11, 0x3e000000, v11
	v_add_f32_e32 v13, 1.0, v13
	v_rcp_f32_e32 v13, v13
	s_nop 0
	v_mul_f32_e32 v12, v12, v13
	v_med3_f32 v13, v6, s40, v189
	v_mov_b32_e32 v6, v163
	v_cvt_pk_fp8_f32 v6, v5, v13
	v_med3_f32 v5, v7, s40, v189
	v_med3_f32 v7, v8, s40, v189
	v_med3_f32 v8, v10, s40, v189
	v_cvt_pk_fp8_f32 v6, v5, v7 op_sel:[0,0,1]
	v_med3_f32 v5, v9, s40, v189
	v_mov_b32_e32 v7, v163
	v_cvt_pk_fp8_f32 v7, v5, v8
	v_mul_f32_e32 v12, v12, v149
	v_mul_f32_e32 v12, 0x3e000000, v12
	v_med3_f32 v5, v11, s40, v189
	v_med3_f32 v8, v12, s40, v189
	v_cvt_pk_fp8_f32 v7, v5, v8 op_sel:[0,0,1]
	v_ashrrev_i32_e32 v5, 31, v4
	v_lshlrev_b64 v[8:9], 7, v[4:5]
	v_lshl_add_u64 v[8:9], s[10:11], 0, v[8:9]
	v_lshl_add_u64 v[8:9], v[8:9], 0, v[2:3]
	v_mul_f32_e32 v5, 0x3c800000, v142
	global_store_dwordx2 v[8:9], v[6:7], off
	v_mul_f32_e32 v6, 0xbfb8aa3b, v5
	v_exp_f32_e32 v6, v6
	s_nop 0
	v_add_f32_e32 v6, 1.0, v6
	v_rcp_f32_e32 v6, v6
	s_nop 0
	v_mul_f32_e32 v5, v5, v6
	v_mul_f32_e32 v6, 0x3c800000, v143
	v_mul_f32_e32 v7, 0xbfb8aa3b, v6
	v_exp_f32_e32 v7, v7
	v_mul_f32_e32 v5, v5, v138
	v_mul_f32_e32 v5, 0x3e000000, v5
	v_med3_f32 v5, v5, s40, v189
	v_add_f32_e32 v7, 1.0, v7
	v_rcp_f32_e32 v7, v7
	s_nop 0
	v_mul_f32_e32 v6, v6, v7
	v_mul_f32_e32 v6, v6, v139
	v_mul_f32_e32 v7, 0x3e000000, v6
	v_mul_f32_e32 v6, 0x3c800000, v144
	v_mul_f32_e32 v8, 0xbfb8aa3b, v6
	v_exp_f32_e32 v8, v8
	v_med3_f32 v7, v7, s40, v189
	v_add_f32_e32 v8, 1.0, v8
	v_rcp_f32_e32 v8, v8
	s_nop 0
	v_mul_f32_e32 v6, v6, v8
	v_mul_f32_e32 v6, v6, v140
	v_mul_f32_e32 v9, 0x3e000000, v6
	v_mul_f32_e32 v6, 0x3c800000, v145
	v_mul_f32_e32 v8, 0xbfb8aa3b, v6
	v_exp_f32_e32 v8, v8
	s_nop 0
	v_add_f32_e32 v8, 1.0, v8
	v_rcp_f32_e32 v8, v8
	s_nop 0
	v_mul_f32_e32 v6, v6, v8
	v_mul_f32_e32 v6, v6, v141
	v_mul_f32_e32 v10, 0x3e000000, v6
	v_mul_f32_e32 v6, 0x3c800000, v134
	v_mul_f32_e32 v8, 0xbfb8aa3b, v6
	v_exp_f32_e32 v8, v8
	s_nop 0
	v_add_f32_e32 v8, 1.0, v8
	v_rcp_f32_e32 v8, v8
	s_nop 0
	v_mul_f32_e32 v6, v6, v8
	v_mul_f32_e32 v6, v6, v130
	v_mul_f32_e32 v11, 0x3e000000, v6
	v_mul_f32_e32 v6, 0x3c800000, v135
	v_mul_f32_e32 v8, 0xbfb8aa3b, v6
	v_exp_f32_e32 v8, v8
	s_nop 0
	v_add_f32_e32 v8, 1.0, v8
	v_rcp_f32_e32 v8, v8
	s_nop 0
	v_mul_f32_e32 v6, v6, v8
	v_mul_f32_e32 v6, v6, v131
	v_mul_f32_e32 v12, 0x3e000000, v6
	v_mul_f32_e32 v6, 0x3c800000, v136
	v_mul_f32_e32 v8, 0xbfb8aa3b, v6
	v_exp_f32_e32 v8, v8
	s_nop 0
	v_add_f32_e32 v8, 1.0, v8
	v_rcp_f32_e32 v8, v8
	s_nop 0
	v_mul_f32_e32 v6, v6, v8
	v_mul_f32_e32 v6, v6, v132
	v_mul_f32_e32 v13, 0x3e000000, v6
	v_mul_f32_e32 v6, 0x3c800000, v137
	v_mul_f32_e32 v8, 0xbfb8aa3b, v6
	v_exp_f32_e32 v8, v8
	s_nop 0
	v_add_f32_e32 v8, 1.0, v8
	v_rcp_f32_e32 v8, v8
	s_nop 0
	v_mul_f32_e32 v6, v6, v8
	v_mov_b32_e32 v8, v163
	v_cvt_pk_fp8_f32 v8, v5, v7
	v_med3_f32 v5, v9, s40, v189
	v_med3_f32 v7, v10, s40, v189
	v_mov_b32_e32 v9, v163
	v_cvt_pk_fp8_f32 v8, v5, v7 op_sel:[0,0,1]
	v_med3_f32 v5, v11, s40, v189
	v_med3_f32 v7, v12, s40, v189
	v_cvt_pk_fp8_f32 v9, v5, v7
	v_mul_f32_e32 v6, v6, v133
	v_mul_f32_e32 v14, 0x3e000000, v6
	v_add_u32_e32 v6, 16, v4
	v_med3_f32 v5, v13, s40, v189
	v_med3_f32 v7, v14, s40, v189
	v_cvt_pk_fp8_f32 v9, v5, v7 op_sel:[0,0,1]
	v_ashrrev_i32_e32 v7, 31, v6
	v_lshlrev_b64 v[6:7], 7, v[6:7]
	v_lshl_add_u64 v[6:7], s[10:11], 0, v[6:7]
	v_lshl_add_u64 v[6:7], v[6:7], 0, v[2:3]
	v_mul_f32_e32 v5, 0x3c800000, v126
	global_store_dwordx2 v[6:7], v[8:9], off
	v_mul_f32_e32 v6, 0xbfb8aa3b, v5
	v_exp_f32_e32 v6, v6
	s_nop 0
	v_add_f32_e32 v6, 1.0, v6
	v_rcp_f32_e32 v6, v6
	s_nop 0
	v_mul_f32_e32 v5, v5, v6
	v_mul_f32_e32 v6, 0x3c800000, v127
	v_mul_f32_e32 v7, 0xbfb8aa3b, v6
	v_exp_f32_e32 v7, v7
	v_mul_f32_e32 v5, v5, v122
	v_mul_f32_e32 v5, 0x3e000000, v5
	v_med3_f32 v5, v5, s40, v189
	v_add_f32_e32 v7, 1.0, v7
	v_rcp_f32_e32 v7, v7
	s_nop 0
	v_mul_f32_e32 v6, v6, v7
	v_mul_f32_e32 v6, v6, v123
	v_mul_f32_e32 v7, 0x3e000000, v6
	v_mul_f32_e32 v6, 0x3c800000, v128
	v_mul_f32_e32 v8, 0xbfb8aa3b, v6
	v_exp_f32_e32 v8, v8
	v_med3_f32 v7, v7, s40, v189
	v_add_f32_e32 v8, 1.0, v8
	v_rcp_f32_e32 v8, v8
	s_nop 0
	v_mul_f32_e32 v6, v6, v8
	v_mul_f32_e32 v6, v6, v124
	v_mul_f32_e32 v9, 0x3e000000, v6
	v_mul_f32_e32 v6, 0x3c800000, v129
	v_mul_f32_e32 v8, 0xbfb8aa3b, v6
	v_exp_f32_e32 v8, v8
	s_nop 0
	v_add_f32_e32 v8, 1.0, v8
	v_rcp_f32_e32 v8, v8
	s_nop 0
	v_mul_f32_e32 v6, v6, v8
	v_mul_f32_e32 v6, v6, v125
	v_mul_f32_e32 v10, 0x3e000000, v6
	v_mul_f32_e32 v6, 0x3c800000, v118
	v_mul_f32_e32 v8, 0xbfb8aa3b, v6
	v_exp_f32_e32 v8, v8
	s_nop 0
	v_add_f32_e32 v8, 1.0, v8
	v_rcp_f32_e32 v8, v8
	s_nop 0
	v_mul_f32_e32 v6, v6, v8
	v_mul_f32_e32 v6, v6, v114
	v_mul_f32_e32 v11, 0x3e000000, v6
	v_mul_f32_e32 v6, 0x3c800000, v119
	v_mul_f32_e32 v8, 0xbfb8aa3b, v6
	v_exp_f32_e32 v8, v8
	s_nop 0
	v_add_f32_e32 v8, 1.0, v8
	v_rcp_f32_e32 v8, v8
	s_nop 0
	v_mul_f32_e32 v6, v6, v8
	v_mul_f32_e32 v6, v6, v115
	v_mul_f32_e32 v12, 0x3e000000, v6
	v_mul_f32_e32 v6, 0x3c800000, v120
	v_mul_f32_e32 v8, 0xbfb8aa3b, v6
	v_exp_f32_e32 v8, v8
	s_nop 0
	v_add_f32_e32 v8, 1.0, v8
	v_rcp_f32_e32 v8, v8
	s_nop 0
	v_mul_f32_e32 v6, v6, v8
	v_mul_f32_e32 v6, v6, v116
	v_mul_f32_e32 v13, 0x3e000000, v6
	v_mul_f32_e32 v6, 0x3c800000, v121
	v_mul_f32_e32 v8, 0xbfb8aa3b, v6
	v_exp_f32_e32 v8, v8
	s_nop 0
	v_add_f32_e32 v8, 1.0, v8
	v_rcp_f32_e32 v8, v8
	s_nop 0
	v_mul_f32_e32 v6, v6, v8
	v_mov_b32_e32 v8, v163
	v_cvt_pk_fp8_f32 v8, v5, v7
	v_med3_f32 v5, v9, s40, v189
	v_med3_f32 v7, v10, s40, v189
	v_mov_b32_e32 v9, v163
	v_cvt_pk_fp8_f32 v8, v5, v7 op_sel:[0,0,1]
	v_med3_f32 v5, v11, s40, v189
	v_med3_f32 v7, v12, s40, v189
	v_cvt_pk_fp8_f32 v9, v5, v7
	v_mul_f32_e32 v6, v6, v117
	v_mul_f32_e32 v14, 0x3e000000, v6
	v_add_u32_e32 v6, 32, v4
	v_med3_f32 v5, v13, s40, v189
	v_med3_f32 v7, v14, s40, v189
	v_cvt_pk_fp8_f32 v9, v5, v7 op_sel:[0,0,1]
	v_ashrrev_i32_e32 v7, 31, v6
	v_lshlrev_b64 v[6:7], 7, v[6:7]
	v_lshl_add_u64 v[6:7], s[10:11], 0, v[6:7]
	v_lshl_add_u64 v[6:7], v[6:7], 0, v[2:3]
	v_mul_f32_e32 v5, 0x3c800000, v110
	global_store_dwordx2 v[6:7], v[8:9], off
	v_mul_f32_e32 v6, 0xbfb8aa3b, v5
	v_exp_f32_e32 v6, v6
	s_nop 0
	v_add_f32_e32 v6, 1.0, v6
	v_rcp_f32_e32 v6, v6
	s_nop 0
	v_mul_f32_e32 v5, v5, v6
	v_mul_f32_e32 v6, 0x3c800000, v111
	v_mul_f32_e32 v7, 0xbfb8aa3b, v6
	v_exp_f32_e32 v7, v7
	v_mul_f32_e32 v5, v5, v106
	v_mul_f32_e32 v5, 0x3e000000, v5
	v_med3_f32 v5, v5, s40, v189
	v_add_f32_e32 v7, 1.0, v7
	v_rcp_f32_e32 v7, v7
	s_nop 0
	v_mul_f32_e32 v6, v6, v7
	v_mul_f32_e32 v6, v6, v107
	v_mul_f32_e32 v7, 0x3e000000, v6
	v_mul_f32_e32 v6, 0x3c800000, v112
	v_mul_f32_e32 v8, 0xbfb8aa3b, v6
	v_exp_f32_e32 v8, v8
	v_med3_f32 v7, v7, s40, v189
	v_add_f32_e32 v8, 1.0, v8
	v_rcp_f32_e32 v8, v8
	s_nop 0
	v_mul_f32_e32 v6, v6, v8
	v_mul_f32_e32 v6, v6, v108
	v_mul_f32_e32 v9, 0x3e000000, v6
	v_mul_f32_e32 v6, 0x3c800000, v113
	v_mul_f32_e32 v8, 0xbfb8aa3b, v6
	v_exp_f32_e32 v8, v8
	s_nop 0
	v_add_f32_e32 v8, 1.0, v8
	v_rcp_f32_e32 v8, v8
	s_nop 0
	v_mul_f32_e32 v6, v6, v8
	v_mul_f32_e32 v6, v6, v109
	v_mul_f32_e32 v10, 0x3e000000, v6
	v_mul_f32_e32 v6, 0x3c800000, v102
	v_mul_f32_e32 v8, 0xbfb8aa3b, v6
	v_exp_f32_e32 v8, v8
	s_nop 0
	v_add_f32_e32 v8, 1.0, v8
	v_rcp_f32_e32 v8, v8
	s_nop 0
	v_mul_f32_e32 v6, v6, v8
	v_mul_f32_e32 v6, v6, v98
	v_mul_f32_e32 v11, 0x3e000000, v6
	v_mul_f32_e32 v6, 0x3c800000, v103
	v_mul_f32_e32 v8, 0xbfb8aa3b, v6
	v_exp_f32_e32 v8, v8
	s_nop 0
	v_add_f32_e32 v8, 1.0, v8
	v_rcp_f32_e32 v8, v8
	s_nop 0
	v_mul_f32_e32 v6, v6, v8
	v_mul_f32_e32 v6, v6, v99
	v_mul_f32_e32 v12, 0x3e000000, v6
	v_mul_f32_e32 v6, 0x3c800000, v104
	v_mul_f32_e32 v8, 0xbfb8aa3b, v6
	v_exp_f32_e32 v8, v8
	s_nop 0
	v_add_f32_e32 v8, 1.0, v8
	v_rcp_f32_e32 v8, v8
	s_nop 0
	v_mul_f32_e32 v6, v6, v8
	v_mul_f32_e32 v6, v6, v100
	v_mul_f32_e32 v13, 0x3e000000, v6
	v_mul_f32_e32 v6, 0x3c800000, v105
	v_mul_f32_e32 v8, 0xbfb8aa3b, v6
	v_exp_f32_e32 v8, v8
	s_nop 0
	v_add_f32_e32 v8, 1.0, v8
	v_rcp_f32_e32 v8, v8
	s_nop 0
	v_mul_f32_e32 v6, v6, v8
	v_mov_b32_e32 v8, v163
	v_cvt_pk_fp8_f32 v8, v5, v7
	v_med3_f32 v5, v9, s40, v189
	v_med3_f32 v7, v10, s40, v189
	v_mov_b32_e32 v9, v163
	v_cvt_pk_fp8_f32 v8, v5, v7 op_sel:[0,0,1]
	v_med3_f32 v5, v11, s40, v189
	v_med3_f32 v7, v12, s40, v189
	v_cvt_pk_fp8_f32 v9, v5, v7
	v_mul_f32_e32 v6, v6, v101
	v_mul_f32_e32 v14, 0x3e000000, v6
	v_add_u32_e32 v6, 48, v4
	v_med3_f32 v5, v13, s40, v189
	v_med3_f32 v7, v14, s40, v189
	v_cvt_pk_fp8_f32 v9, v5, v7 op_sel:[0,0,1]
	v_ashrrev_i32_e32 v7, 31, v6
	v_lshlrev_b64 v[6:7], 7, v[6:7]
	v_lshl_add_u64 v[6:7], s[10:11], 0, v[6:7]
	v_lshl_add_u64 v[6:7], v[6:7], 0, v[2:3]
	v_mul_f32_e32 v5, 0x3c800000, v94
	global_store_dwordx2 v[6:7], v[8:9], off
	v_mul_f32_e32 v7, 0xbfb8aa3b, v5
	v_exp_f32_e32 v7, v7
	v_add_u32_e32 v6, 0x80, v4
	v_add_f32_e32 v7, 1.0, v7
	v_rcp_f32_e32 v7, v7
	s_nop 0
	v_mul_f32_e32 v5, v5, v7
	v_mul_f32_e32 v7, 0x3c800000, v95
	v_mul_f32_e32 v8, 0xbfb8aa3b, v7
	v_exp_f32_e32 v8, v8
	v_mul_f32_e32 v5, v5, v90
	v_mul_f32_e32 v5, 0x3e000000, v5
	v_med3_f32 v5, v5, s40, v189
	v_add_f32_e32 v8, 1.0, v8
	v_rcp_f32_e32 v8, v8
	s_nop 0
	v_mul_f32_e32 v7, v7, v8
	v_mul_f32_e32 v8, 0x3c800000, v96
	v_mul_f32_e32 v9, 0xbfb8aa3b, v8
	v_exp_f32_e32 v9, v9
	v_mul_f32_e32 v7, v7, v91
	v_mul_f32_e32 v7, 0x3e000000, v7
	v_med3_f32 v7, v7, s40, v189
	v_add_f32_e32 v9, 1.0, v9
	v_rcp_f32_e32 v9, v9
	s_nop 0
	v_mul_f32_e32 v8, v8, v9
	v_mul_f32_e32 v8, v8, v92
	v_mul_f32_e32 v9, 0x3e000000, v8
	v_mul_f32_e32 v8, 0x3c800000, v97
	v_mul_f32_e32 v10, 0xbfb8aa3b, v8
	v_exp_f32_e32 v10, v10
	s_nop 0
	v_add_f32_e32 v10, 1.0, v10
	v_rcp_f32_e32 v10, v10
	s_nop 0
	v_mul_f32_e32 v8, v8, v10
	v_mul_f32_e32 v8, v8, v93
	v_mul_f32_e32 v10, 0x3e000000, v8
	v_mul_f32_e32 v8, 0x3c800000, v86
	v_mul_f32_e32 v11, 0xbfb8aa3b, v8
	v_exp_f32_e32 v11, v11
	s_nop 0
	v_add_f32_e32 v11, 1.0, v11
	v_rcp_f32_e32 v11, v11
	s_nop 0
	v_mul_f32_e32 v8, v8, v11
	v_mul_f32_e32 v8, v8, v82
	v_mul_f32_e32 v11, 0x3e000000, v8
	v_mul_f32_e32 v8, 0x3c800000, v87
	v_mul_f32_e32 v12, 0xbfb8aa3b, v8
	v_exp_f32_e32 v12, v12
	s_nop 0
	v_add_f32_e32 v12, 1.0, v12
	v_rcp_f32_e32 v12, v12
	s_nop 0
	v_mul_f32_e32 v8, v8, v12
	v_mul_f32_e32 v8, v8, v83
	v_mul_f32_e32 v12, 0x3e000000, v8
	v_mul_f32_e32 v8, 0x3c800000, v88
	v_mul_f32_e32 v13, 0xbfb8aa3b, v8
	v_exp_f32_e32 v13, v13
	s_nop 0
	v_add_f32_e32 v13, 1.0, v13
	v_rcp_f32_e32 v13, v13
	s_nop 0
	v_mul_f32_e32 v8, v8, v13
	v_mul_f32_e32 v8, v8, v84
	v_mul_f32_e32 v13, 0x3e000000, v8
	v_mul_f32_e32 v8, 0x3c800000, v89
	v_mul_f32_e32 v14, 0xbfb8aa3b, v8
	v_exp_f32_e32 v14, v14
	s_nop 0
	v_add_f32_e32 v14, 1.0, v14
	v_rcp_f32_e32 v14, v14
	s_nop 0
	v_mul_f32_e32 v8, v8, v14
	v_mul_f32_e32 v8, v8, v85
	v_mul_f32_e32 v14, 0x3e000000, v8
	v_mov_b32_e32 v8, v163
	v_cvt_pk_fp8_f32 v8, v5, v7
	v_med3_f32 v5, v9, s40, v189
	v_med3_f32 v7, v10, s40, v189
	v_mov_b32_e32 v9, v163
	v_cvt_pk_fp8_f32 v8, v5, v7 op_sel:[0,0,1]
	v_med3_f32 v5, v11, s40, v189
	v_med3_f32 v7, v12, s40, v189
	v_cvt_pk_fp8_f32 v9, v5, v7
	v_med3_f32 v5, v13, s40, v189
	v_med3_f32 v7, v14, s40, v189
	v_cvt_pk_fp8_f32 v9, v5, v7 op_sel:[0,0,1]
	v_ashrrev_i32_e32 v7, 31, v6
	v_lshlrev_b64 v[6:7], 7, v[6:7]
	v_lshl_add_u64 v[6:7], s[10:11], 0, v[6:7]
	v_lshl_add_u64 v[6:7], v[6:7], 0, v[2:3]
	v_mul_f32_e32 v5, 0x3c800000, v78
	global_store_dwordx2 v[6:7], v[8:9], off
	v_mul_f32_e32 v6, 0xbfb8aa3b, v5
	v_exp_f32_e32 v6, v6
	s_nop 0
	v_add_f32_e32 v6, 1.0, v6
	v_rcp_f32_e32 v6, v6
	s_nop 0
	v_mul_f32_e32 v5, v5, v6
	v_mul_f32_e32 v6, 0x3c800000, v79
	v_mul_f32_e32 v7, 0xbfb8aa3b, v6
	v_exp_f32_e32 v7, v7
	v_mul_f32_e32 v5, v5, v74
	v_mul_f32_e32 v5, 0x3e000000, v5
	v_med3_f32 v5, v5, s40, v189
	v_add_f32_e32 v7, 1.0, v7
	v_rcp_f32_e32 v7, v7
	s_nop 0
	v_mul_f32_e32 v6, v6, v7
	v_mul_f32_e32 v6, v6, v75
	v_mul_f32_e32 v7, 0x3e000000, v6
	v_mul_f32_e32 v6, 0x3c800000, v80
	v_mul_f32_e32 v8, 0xbfb8aa3b, v6
	v_exp_f32_e32 v8, v8
	v_med3_f32 v7, v7, s40, v189
	v_add_f32_e32 v8, 1.0, v8
	v_rcp_f32_e32 v8, v8
	s_nop 0
	v_mul_f32_e32 v6, v6, v8
	v_mul_f32_e32 v6, v6, v76
	v_mul_f32_e32 v9, 0x3e000000, v6
	v_mul_f32_e32 v6, 0x3c800000, v81
	v_mul_f32_e32 v8, 0xbfb8aa3b, v6
	v_exp_f32_e32 v8, v8
	s_nop 0
	v_add_f32_e32 v8, 1.0, v8
	v_rcp_f32_e32 v8, v8
	s_nop 0
	v_mul_f32_e32 v6, v6, v8
	v_mul_f32_e32 v6, v6, v77
	v_mul_f32_e32 v10, 0x3e000000, v6
	v_mul_f32_e32 v6, 0x3c800000, v70
	v_mul_f32_e32 v8, 0xbfb8aa3b, v6
	v_exp_f32_e32 v8, v8
	s_nop 0
	v_add_f32_e32 v8, 1.0, v8
	v_rcp_f32_e32 v8, v8
	s_nop 0
	v_mul_f32_e32 v6, v6, v8
	v_mul_f32_e32 v6, v6, v66
	v_mul_f32_e32 v11, 0x3e000000, v6
	v_mul_f32_e32 v6, 0x3c800000, v71
	v_mul_f32_e32 v8, 0xbfb8aa3b, v6
	v_exp_f32_e32 v8, v8
	s_nop 0
	v_add_f32_e32 v8, 1.0, v8
	v_rcp_f32_e32 v8, v8
	s_nop 0
	v_mul_f32_e32 v6, v6, v8
	v_mul_f32_e32 v6, v6, v67
	v_mul_f32_e32 v12, 0x3e000000, v6
	v_mul_f32_e32 v6, 0x3c800000, v72
	v_mul_f32_e32 v8, 0xbfb8aa3b, v6
	v_exp_f32_e32 v8, v8
	s_nop 0
	v_add_f32_e32 v8, 1.0, v8
	v_rcp_f32_e32 v8, v8
	s_nop 0
	v_mul_f32_e32 v6, v6, v8
	v_mul_f32_e32 v6, v6, v68
	v_mul_f32_e32 v13, 0x3e000000, v6
	v_mul_f32_e32 v6, 0x3c800000, v73
	v_mul_f32_e32 v8, 0xbfb8aa3b, v6
	v_exp_f32_e32 v8, v8
	s_nop 0
	v_add_f32_e32 v8, 1.0, v8
	v_rcp_f32_e32 v8, v8
	s_nop 0
	v_mul_f32_e32 v6, v6, v8
	v_mov_b32_e32 v8, v163
	v_cvt_pk_fp8_f32 v8, v5, v7
	v_med3_f32 v5, v9, s40, v189
	v_med3_f32 v7, v10, s40, v189
	v_mov_b32_e32 v9, v163
	v_cvt_pk_fp8_f32 v8, v5, v7 op_sel:[0,0,1]
	v_med3_f32 v5, v11, s40, v189
	v_med3_f32 v7, v12, s40, v189
	v_cvt_pk_fp8_f32 v9, v5, v7
	v_mul_f32_e32 v6, v6, v69
	v_mul_f32_e32 v14, 0x3e000000, v6
	v_add_u32_e32 v6, 0x90, v4
	v_med3_f32 v5, v13, s40, v189
	v_med3_f32 v7, v14, s40, v189
	v_cvt_pk_fp8_f32 v9, v5, v7 op_sel:[0,0,1]
	v_ashrrev_i32_e32 v7, 31, v6
	v_lshlrev_b64 v[6:7], 7, v[6:7]
	v_lshl_add_u64 v[6:7], s[10:11], 0, v[6:7]
	v_lshl_add_u64 v[6:7], v[6:7], 0, v[2:3]
	v_mul_f32_e32 v5, 0x3c800000, v62
	global_store_dwordx2 v[6:7], v[8:9], off
	v_mul_f32_e32 v6, 0xbfb8aa3b, v5
	v_exp_f32_e32 v6, v6
	s_nop 0
	v_add_f32_e32 v6, 1.0, v6
	v_rcp_f32_e32 v6, v6
	s_nop 0
	v_mul_f32_e32 v5, v5, v6
	v_mul_f32_e32 v6, 0x3c800000, v63
	v_mul_f32_e32 v7, 0xbfb8aa3b, v6
	v_exp_f32_e32 v7, v7
	v_mul_f32_e32 v5, v5, v58
	v_mul_f32_e32 v5, 0x3e000000, v5
	v_med3_f32 v5, v5, s40, v189
	v_add_f32_e32 v7, 1.0, v7
	v_rcp_f32_e32 v7, v7
	s_nop 0
	v_mul_f32_e32 v6, v6, v7
	v_mul_f32_e32 v6, v6, v59
	v_mul_f32_e32 v7, 0x3e000000, v6
	v_mul_f32_e32 v6, 0x3c800000, v64
	v_mul_f32_e32 v8, 0xbfb8aa3b, v6
	v_exp_f32_e32 v8, v8
	v_med3_f32 v7, v7, s40, v189
	v_add_f32_e32 v8, 1.0, v8
	v_rcp_f32_e32 v8, v8
	s_nop 0
	v_mul_f32_e32 v6, v6, v8
	v_mul_f32_e32 v6, v6, v60
	v_mul_f32_e32 v9, 0x3e000000, v6
	v_mul_f32_e32 v6, 0x3c800000, v65
	v_mul_f32_e32 v8, 0xbfb8aa3b, v6
	v_exp_f32_e32 v8, v8
	s_nop 0
	v_add_f32_e32 v8, 1.0, v8
	v_rcp_f32_e32 v8, v8
	s_nop 0
	v_mul_f32_e32 v6, v6, v8
	v_mul_f32_e32 v6, v6, v61
	v_mul_f32_e32 v10, 0x3e000000, v6
	v_mul_f32_e32 v6, 0x3c800000, v54
	v_mul_f32_e32 v8, 0xbfb8aa3b, v6
	v_exp_f32_e32 v8, v8
	s_nop 0
	v_add_f32_e32 v8, 1.0, v8
	v_rcp_f32_e32 v8, v8
	s_nop 0
	v_mul_f32_e32 v6, v6, v8
	v_mul_f32_e32 v6, v6, v50
	v_mul_f32_e32 v11, 0x3e000000, v6
	v_mul_f32_e32 v6, 0x3c800000, v55
	v_mul_f32_e32 v8, 0xbfb8aa3b, v6
	v_exp_f32_e32 v8, v8
	s_nop 0
	v_add_f32_e32 v8, 1.0, v8
	v_rcp_f32_e32 v8, v8
	s_nop 0
	v_mul_f32_e32 v6, v6, v8
	v_mul_f32_e32 v6, v6, v51
	v_mul_f32_e32 v12, 0x3e000000, v6
	v_mul_f32_e32 v6, 0x3c800000, v56
	v_mul_f32_e32 v8, 0xbfb8aa3b, v6
	v_exp_f32_e32 v8, v8
	s_nop 0
	v_add_f32_e32 v8, 1.0, v8
	v_rcp_f32_e32 v8, v8
	s_nop 0
	v_mul_f32_e32 v6, v6, v8
	v_mul_f32_e32 v6, v6, v52
	v_mul_f32_e32 v13, 0x3e000000, v6
	v_mul_f32_e32 v6, 0x3c800000, v57
	v_mul_f32_e32 v8, 0xbfb8aa3b, v6
	v_exp_f32_e32 v8, v8
	s_nop 0
	v_add_f32_e32 v8, 1.0, v8
	v_rcp_f32_e32 v8, v8
	s_nop 0
	v_mul_f32_e32 v6, v6, v8
	v_mov_b32_e32 v8, v163
	v_cvt_pk_fp8_f32 v8, v5, v7
	v_med3_f32 v5, v9, s40, v189
	v_med3_f32 v7, v10, s40, v189
	v_mov_b32_e32 v9, v163
	v_cvt_pk_fp8_f32 v8, v5, v7 op_sel:[0,0,1]
	v_med3_f32 v5, v11, s40, v189
	v_med3_f32 v7, v12, s40, v189
	v_cvt_pk_fp8_f32 v9, v5, v7
	v_mul_f32_e32 v6, v6, v53
	v_mul_f32_e32 v14, 0x3e000000, v6
	v_add_u32_e32 v6, 0xa0, v4
	v_med3_f32 v5, v13, s40, v189
	v_med3_f32 v7, v14, s40, v189
	v_cvt_pk_fp8_f32 v9, v5, v7 op_sel:[0,0,1]
	v_ashrrev_i32_e32 v7, 31, v6
	v_lshlrev_b64 v[6:7], 7, v[6:7]
	v_lshl_add_u64 v[6:7], s[10:11], 0, v[6:7]
	v_lshl_add_u64 v[6:7], v[6:7], 0, v[2:3]
	v_mul_f32_e32 v5, 0x3c800000, v46
	global_store_dwordx2 v[6:7], v[8:9], off
	v_mul_f32_e32 v6, 0xbfb8aa3b, v5
	v_exp_f32_e32 v6, v6
	v_add_u32_e32 v4, 0xb0, v4
	v_add_f32_e32 v6, 1.0, v6
	v_rcp_f32_e32 v6, v6
	s_nop 0
	v_mul_f32_e32 v5, v5, v6
	v_mul_f32_e32 v6, 0x3c800000, v47
	v_mul_f32_e32 v7, 0xbfb8aa3b, v6
	v_exp_f32_e32 v7, v7
	v_mul_f32_e32 v5, v5, v42
	v_mul_f32_e32 v5, 0x3e000000, v5
	v_med3_f32 v5, v5, s40, v189
	v_add_f32_e32 v7, 1.0, v7
	v_rcp_f32_e32 v7, v7
	s_nop 0
	v_mul_f32_e32 v6, v6, v7
	v_mul_f32_e32 v7, 0x3c800000, v48
	v_mul_f32_e32 v8, 0xbfb8aa3b, v7
	v_exp_f32_e32 v8, v8
	v_mul_f32_e32 v6, v6, v43
	v_mul_f32_e32 v6, 0x3e000000, v6
	v_add_f32_e32 v8, 1.0, v8
	v_rcp_f32_e32 v8, v8
	s_nop 0
	v_mul_f32_e32 v7, v7, v8
	v_mul_f32_e32 v8, 0x3c800000, v49
	v_mul_f32_e32 v9, 0xbfb8aa3b, v8
	v_exp_f32_e32 v9, v9
	v_mul_f32_e32 v7, v7, v44
	v_mul_f32_e32 v7, 0x3e000000, v7
	v_add_f32_e32 v9, 1.0, v9
	v_rcp_f32_e32 v9, v9
	s_nop 0
	v_mul_f32_e32 v8, v8, v9
	v_mul_f32_e32 v9, 0x3c800000, v38
	v_mul_f32_e32 v10, 0xbfb8aa3b, v9
	v_exp_f32_e32 v10, v10
	v_mul_f32_e32 v8, v8, v45
	v_mul_f32_e32 v8, 0x3e000000, v8
	v_add_f32_e32 v10, 1.0, v10
	v_rcp_f32_e32 v10, v10
	s_nop 0
	v_mul_f32_e32 v9, v9, v10
	v_mul_f32_e32 v10, 0x3c800000, v39
	v_mul_f32_e32 v11, 0xbfb8aa3b, v10
	v_exp_f32_e32 v11, v11
	v_mul_f32_e32 v9, v9, v34
	v_mul_f32_e32 v9, 0x3e000000, v9
	v_add_f32_e32 v11, 1.0, v11
	v_rcp_f32_e32 v11, v11
	s_nop 0
	v_mul_f32_e32 v10, v10, v11
	v_mul_f32_e32 v11, 0x3c800000, v40
	v_mul_f32_e32 v12, 0xbfb8aa3b, v11
	v_exp_f32_e32 v12, v12
	v_mul_f32_e32 v10, v10, v35
	v_mul_f32_e32 v10, 0x3e000000, v10
	v_add_f32_e32 v12, 1.0, v12
	v_rcp_f32_e32 v12, v12
	s_nop 0
	v_mul_f32_e32 v11, v11, v12
	v_mul_f32_e32 v12, 0x3c800000, v41
	v_mul_f32_e32 v13, 0xbfb8aa3b, v12
	v_exp_f32_e32 v13, v13
	v_mul_f32_e32 v11, v11, v36
	v_mul_f32_e32 v11, 0x3e000000, v11
	v_add_f32_e32 v13, 1.0, v13
	v_rcp_f32_e32 v13, v13
	s_nop 0
	v_mul_f32_e32 v12, v12, v13
	v_med3_f32 v13, v6, s40, v189
	v_mov_b32_e32 v6, v163
	v_cvt_pk_fp8_f32 v6, v5, v13
	v_med3_f32 v5, v7, s40, v189
	v_med3_f32 v7, v8, s40, v189
	v_med3_f32 v8, v10, s40, v189
	v_cvt_pk_fp8_f32 v6, v5, v7 op_sel:[0,0,1]
	v_med3_f32 v5, v9, s40, v189
	v_mov_b32_e32 v7, v163
	v_cvt_pk_fp8_f32 v7, v5, v8
	v_mul_f32_e32 v12, v12, v37
	v_mul_f32_e32 v12, 0x3e000000, v12
	v_med3_f32 v5, v11, s40, v189
	v_med3_f32 v8, v12, s40, v189
	v_cvt_pk_fp8_f32 v7, v5, v8 op_sel:[0,0,1]
	v_ashrrev_i32_e32 v5, 31, v4
	v_lshlrev_b64 v[4:5], 7, v[4:5]
	v_lshl_add_u64 v[4:5], s[10:11], 0, v[4:5]
	v_lshl_add_u64 v[2:3], v[4:5], 0, v[2:3]
	global_store_dwordx2 v[2:3], v[6:7], off
	s_cbranch_vccz .LBB0_2738
	s_waitcnt vmcnt(0)
	s_cmpk_gt_u32 s42, 0xff
	s_cbranch_scc1 .LBB0_2684
	s_barrier
	s_branch .LBB0_2684

.LBB0_2816:
	ds_read_b128 v[2:5], v168
	ds_read_b128 v[6:9], v168 offset:1024
	ds_read_b128 v[10:13], v168 offset:2048
	ds_read_b128 v[14:17], v168 offset:3072
	s_add_u32 s0, s26, 0x4000
	s_addc_u32 s1, s27, 0
	s_cmp_eq_u32 s53, 4
	s_cselect_b32 s34, s49, s0
	s_cselect_b32 s35, s19, s1
	s_cselect_b32 s28, s50, s51
	s_cselect_b32 s29, s17, s52
	s_add_u32 s30, s34, 0x8000
	s_addc_u32 s31, s35, 0
	v_lshl_add_u64 v[162:163], s[26:27], 0, v[156:157]
	s_add_i32 m0, s25, 0xc000
	ds_read_b128 v[174:177], v169
	ds_read_b128 v[178:181], v169 offset:1024
	ds_read_b128 v[182:185], v169 offset:2048
	ds_read_b128 v[186:189], v169 offset:3072
	ds_read_b128 v[190:193], v169 offset:4096
	ds_read_b128 v[194:197], v169 offset:5120
	ds_read_b128 v[198:201], v169 offset:6144
	ds_read_b128 v[202:205], v169 offset:7168
	global_load_lds_dwordx4 v[162:163], off
	v_lshl_add_u64 v[162:163], s[26:27], 0, v[154:155]
	s_add_i32 m0, s25, 0xe000
	s_nop 0
	global_load_lds_dwordx4 v[162:163], off
	s_waitcnt lgkmcnt(8)
	s_waitcnt vmcnt(10)
	s_barrier
	s_waitcnt lgkmcnt(0)
	v_mfma_scale_f32_16x16x128_f8f6f4 v[142:145], v[2:9], v[174:181], v[142:145], v170, v170 op_sel_hi:[0,0,0]
	v_mfma_scale_f32_16x16x128_f8f6f4 v[138:141], v[10:17], v[174:181], v[138:141], v170, v170 op_sel_hi:[0,0,0]
	v_mfma_scale_f32_16x16x128_f8f6f4 v[126:129], v[2:9], v[182:189], v[126:129], v170, v170 op_sel_hi:[0,0,0]
	v_mfma_scale_f32_16x16x128_f8f6f4 v[122:125], v[10:17], v[182:189], v[122:125], v170, v170 op_sel_hi:[0,0,0]
	v_mfma_scale_f32_16x16x128_f8f6f4 v[110:113], v[2:9], v[190:197], v[110:113], v170, v170 op_sel_hi:[0,0,0]
	v_mfma_scale_f32_16x16x128_f8f6f4 v[106:109], v[10:17], v[190:197], v[106:109], v170, v170 op_sel_hi:[0,0,0]
	v_mfma_scale_f32_16x16x128_f8f6f4 v[94:97], v[2:9], v[198:205], v[94:97], v170, v170 op_sel_hi:[0,0,0]
	v_mfma_scale_f32_16x16x128_f8f6f4 v[90:93], v[10:17], v[198:205], v[90:93], v170, v170 op_sel_hi:[0,0,0]
	s_barrier
	s_add_i32 s0, s45, s37
	v_lshl_add_u64 v[162:163], s[28:29], 0, v[150:151]
	s_mov_b32 m0, s0
	ds_read_b128 v[206:209], v171
	ds_read_b128 v[210:213], v171 offset:1024
	ds_read_b128 v[214:217], v171 offset:2048
	ds_read_b128 v[218:221], v171 offset:3072
	global_load_lds_dwordx4 v[162:163], off
	v_lshl_add_u64 v[164:165], s[28:29], 0, v[146:147]
	s_add_i32 m0, s0, 0x2000
	s_nop 0
	global_load_lds_dwordx4 v[164:165], off
	s_waitcnt vmcnt(10)
	s_barrier
	s_waitcnt lgkmcnt(0)
	v_mfma_scale_f32_16x16x128_f8f6f4 v[134:137], v[206:213], v[174:181], v[134:137], v170, v170 op_sel_hi:[0,0,0]
	v_mfma_scale_f32_16x16x128_f8f6f4 v[130:133], v[214:221], v[174:181], v[130:133], v170, v170 op_sel_hi:[0,0,0]
	v_mfma_scale_f32_16x16x128_f8f6f4 v[118:121], v[206:213], v[182:189], v[118:121], v170, v170 op_sel_hi:[0,0,0]
	v_mfma_scale_f32_16x16x128_f8f6f4 v[114:117], v[214:221], v[182:189], v[114:117], v170, v170 op_sel_hi:[0,0,0]
	v_mfma_scale_f32_16x16x128_f8f6f4 v[102:105], v[206:213], v[190:197], v[102:105], v170, v170 op_sel_hi:[0,0,0]
	v_mfma_scale_f32_16x16x128_f8f6f4 v[98:101], v[214:221], v[190:197], v[98:101], v170, v170 op_sel_hi:[0,0,0]
	v_mfma_scale_f32_16x16x128_f8f6f4 v[86:89], v[206:213], v[198:205], v[86:89], v170, v170 op_sel_hi:[0,0,0]
	v_mfma_scale_f32_16x16x128_f8f6f4 v[82:85], v[214:221], v[198:205], v[82:85], v170, v170 op_sel_hi:[0,0,0]
	s_mov_b32 m0, s25
	v_lshl_add_u64 v[222:223], s[34:35], 0, v[152:153]
	s_barrier
	ds_read_b128 v[174:177], v169 offset:16384
	ds_read_b128 v[178:181], v169 offset:17408
	ds_read_b128 v[182:185], v169 offset:18432
	ds_read_b128 v[186:189], v169 offset:19456
	ds_read_b128 v[190:193], v169 offset:20480
	ds_read_b128 v[194:197], v169 offset:21504
	ds_read_b128 v[198:201], v169 offset:22528
	ds_read_b128 v[202:205], v169 offset:23552
	global_load_lds_dwordx4 v[222:223], off
	v_lshl_add_u64 v[222:223], s[34:35], 0, v[148:149]
	s_mov_b32 m0, s38
	s_nop 0
	global_load_lds_dwordx4 v[222:223], off
	s_waitcnt vmcnt(10)
	s_barrier
	s_waitcnt lgkmcnt(0)
	v_mfma_scale_f32_16x16x128_f8f6f4 v[78:81], v[2:9], v[174:181], v[78:81], v170, v170 op_sel_hi:[0,0,0]
	v_mfma_scale_f32_16x16x128_f8f6f4 v[74:77], v[10:17], v[174:181], v[74:77], v170, v170 op_sel_hi:[0,0,0]
	v_mfma_scale_f32_16x16x128_f8f6f4 v[62:65], v[2:9], v[182:189], v[62:65], v170, v170 op_sel_hi:[0,0,0]
	v_mfma_scale_f32_16x16x128_f8f6f4 v[58:61], v[10:17], v[182:189], v[58:61], v170, v170 op_sel_hi:[0,0,0]
	v_mfma_scale_f32_16x16x128_f8f6f4 v[46:49], v[2:9], v[190:197], v[46:49], v170, v170 op_sel_hi:[0,0,0]
	v_mfma_scale_f32_16x16x128_f8f6f4 v[42:45], v[10:17], v[190:197], v[42:45], v170, v170 op_sel_hi:[0,0,0]
	v_mfma_scale_f32_16x16x128_f8f6f4 v[30:33], v[2:9], v[198:205], v[30:33], v170, v170 op_sel_hi:[0,0,0]
	v_mfma_scale_f32_16x16x128_f8f6f4 v[26:29], v[10:17], v[198:205], v[26:29], v170, v170 op_sel_hi:[0,0,0]
	s_barrier
	s_add_u32 s0, s28, 0x20000
	s_addc_u32 s1, s29, 0
	s_add_i32 s54, s46, s37
	v_lshl_add_u64 v[2:3], s[0:1], 0, v[150:151]
	s_mov_b32 m0, s54
	s_nop 0
	global_load_lds_dwordx4 v[2:3], off
	v_lshl_add_u64 v[2:3], s[0:1], 0, v[146:147]
	s_add_i32 m0, s54, 0x2000
	s_nop 0
	global_load_lds_dwordx4 v[2:3], off
	s_waitcnt vmcnt(10)
	s_barrier
	v_mfma_scale_f32_16x16x128_f8f6f4 v[70:73], v[206:213], v[174:181], v[70:73], v170, v170 op_sel_hi:[0,0,0]
	v_mfma_scale_f32_16x16x128_f8f6f4 v[66:69], v[214:221], v[174:181], v[66:69], v170, v170 op_sel_hi:[0,0,0]
	v_mfma_scale_f32_16x16x128_f8f6f4 v[54:57], v[206:213], v[182:189], v[54:57], v170, v170 op_sel_hi:[0,0,0]
	v_mfma_scale_f32_16x16x128_f8f6f4 v[50:53], v[214:221], v[182:189], v[50:53], v170, v170 op_sel_hi:[0,0,0]
	v_mfma_scale_f32_16x16x128_f8f6f4 v[38:41], v[206:213], v[190:197], v[38:41], v170, v170 op_sel_hi:[0,0,0]
	v_mfma_scale_f32_16x16x128_f8f6f4 v[34:37], v[214:221], v[190:197], v[34:37], v170, v170 op_sel_hi:[0,0,0]
	v_mfma_scale_f32_16x16x128_f8f6f4 v[22:25], v[206:213], v[198:205], v[22:25], v170, v170 op_sel_hi:[0,0,0]
	v_mfma_scale_f32_16x16x128_f8f6f4 v[18:21], v[214:221], v[198:205], v[18:21], v170, v170 op_sel_hi:[0,0,0]
	s_add_i32 s54, 0, 0x18000
	v_add_u32_e32 v14, s54, v167
	s_barrier
	ds_read_b128 v[2:5], v14
	ds_read_b128 v[6:9], v14 offset:1024
	ds_read_b128 v[10:13], v14 offset:2048
	ds_read_b128 v[14:17], v14 offset:3072
	s_add_u32 s0, s34, 0x4000
	s_addc_u32 s1, s35, 0
	s_mov_b32 m0, s39
	v_lshl_add_u64 v[206:207], s[0:1], 0, v[152:153]
	ds_read_b128 v[174:177], v169 offset:32768
	ds_read_b128 v[178:181], v169 offset:33792
	ds_read_b128 v[182:185], v169 offset:34816
	ds_read_b128 v[186:189], v169 offset:35840
	ds_read_b128 v[190:193], v169 offset:36864
	ds_read_b128 v[194:197], v169 offset:37888
	ds_read_b128 v[198:201], v169 offset:38912
	ds_read_b128 v[202:205], v169 offset:39936
	global_load_lds_dwordx4 v[206:207], off
	v_lshl_add_u64 v[206:207], s[0:1], 0, v[148:149]
	s_mov_b32 m0, s40
	s_nop 0
	global_load_lds_dwordx4 v[206:207], off
	s_waitcnt lgkmcnt(8)
	s_waitcnt vmcnt(10)
	s_barrier
	s_waitcnt lgkmcnt(0)
	v_mfma_scale_f32_16x16x128_f8f6f4 v[142:145], v[2:9], v[174:181], v[142:145], v170, v170 op_sel_hi:[0,0,0]
	v_mfma_scale_f32_16x16x128_f8f6f4 v[138:141], v[10:17], v[174:181], v[138:141], v170, v170 op_sel_hi:[0,0,0]
	v_mfma_scale_f32_16x16x128_f8f6f4 v[126:129], v[2:9], v[182:189], v[126:129], v170, v170 op_sel_hi:[0,0,0]
	v_mfma_scale_f32_16x16x128_f8f6f4 v[122:125], v[10:17], v[182:189], v[122:125], v170, v170 op_sel_hi:[0,0,0]
	v_mfma_scale_f32_16x16x128_f8f6f4 v[110:113], v[2:9], v[190:197], v[110:113], v170, v170 op_sel_hi:[0,0,0]
	v_mfma_scale_f32_16x16x128_f8f6f4 v[106:109], v[10:17], v[190:197], v[106:109], v170, v170 op_sel_hi:[0,0,0]
	v_mfma_scale_f32_16x16x128_f8f6f4 v[94:97], v[2:9], v[198:205], v[94:97], v170, v170 op_sel_hi:[0,0,0]
	v_mfma_scale_f32_16x16x128_f8f6f4 v[90:93], v[10:17], v[198:205], v[90:93], v170, v170 op_sel_hi:[0,0,0]
	s_barrier
	s_add_i32 s34, 0, 0x1c000
	s_add_i32 s0, s54, s37
	v_add_u32_e32 v173, s34, v167
	v_lshl_add_u64 v[162:163], v[162:163], 0, s[12:13]
	s_mov_b32 m0, s0
	ds_read_b128 v[206:209], v173
	ds_read_b128 v[210:213], v173 offset:1024
	ds_read_b128 v[214:217], v173 offset:2048
	ds_read_b128 v[218:221], v173 offset:3072
	global_load_lds_dwordx4 v[162:163], off
	v_lshl_add_u64 v[162:163], v[164:165], 0, s[12:13]
	s_add_i32 m0, s0, 0x2000
	s_nop 0
	global_load_lds_dwordx4 v[162:163], off
	s_waitcnt vmcnt(10)
	s_barrier
	s_waitcnt lgkmcnt(0)
	v_mfma_scale_f32_16x16x128_f8f6f4 v[134:137], v[206:213], v[174:181], v[134:137], v170, v170 op_sel_hi:[0,0,0]
	v_mfma_scale_f32_16x16x128_f8f6f4 v[130:133], v[214:221], v[174:181], v[130:133], v170, v170 op_sel_hi:[0,0,0]
	v_mfma_scale_f32_16x16x128_f8f6f4 v[118:121], v[206:213], v[182:189], v[118:121], v170, v170 op_sel_hi:[0,0,0]
	v_mfma_scale_f32_16x16x128_f8f6f4 v[114:117], v[214:221], v[182:189], v[114:117], v170, v170 op_sel_hi:[0,0,0]
	v_mfma_scale_f32_16x16x128_f8f6f4 v[102:105], v[206:213], v[190:197], v[102:105], v170, v170 op_sel_hi:[0,0,0]
	v_mfma_scale_f32_16x16x128_f8f6f4 v[98:101], v[214:221], v[190:197], v[98:101], v170, v170 op_sel_hi:[0,0,0]
	v_mfma_scale_f32_16x16x128_f8f6f4 v[86:89], v[206:213], v[198:205], v[86:89], v170, v170 op_sel_hi:[0,0,0]
	v_mfma_scale_f32_16x16x128_f8f6f4 v[82:85], v[214:221], v[198:205], v[82:85], v170, v170 op_sel_hi:[0,0,0]
	s_mov_b32 m0, s43
	v_lshl_add_u64 v[162:163], s[30:31], 0, v[152:153]
	s_barrier
	ds_read_b128 v[174:177], v169 offset:49152
	ds_read_b128 v[178:181], v169 offset:50176
	ds_read_b128 v[182:185], v169 offset:51200
	ds_read_b128 v[186:189], v169 offset:52224
	ds_read_b128 v[190:193], v169 offset:53248
	ds_read_b128 v[194:197], v169 offset:54272
	ds_read_b128 v[198:201], v169 offset:55296
	ds_read_b128 v[202:205], v169 offset:56320
	global_load_lds_dwordx4 v[162:163], off
	v_lshl_add_u64 v[162:163], s[30:31], 0, v[148:149]
	s_mov_b32 m0, s44
	s_nop 0
	global_load_lds_dwordx4 v[162:163], off
	s_waitcnt vmcnt(10)
	s_barrier
	s_waitcnt lgkmcnt(0)
	v_mfma_scale_f32_16x16x128_f8f6f4 v[78:81], v[2:9], v[174:181], v[78:81], v170, v170 op_sel_hi:[0,0,0]
	v_mfma_scale_f32_16x16x128_f8f6f4 v[74:77], v[10:17], v[174:181], v[74:77], v170, v170 op_sel_hi:[0,0,0]
	v_mfma_scale_f32_16x16x128_f8f6f4 v[62:65], v[2:9], v[182:189], v[62:65], v170, v170 op_sel_hi:[0,0,0]
	v_mfma_scale_f32_16x16x128_f8f6f4 v[58:61], v[10:17], v[182:189], v[58:61], v170, v170 op_sel_hi:[0,0,0]
	v_mfma_scale_f32_16x16x128_f8f6f4 v[46:49], v[2:9], v[190:197], v[46:49], v170, v170 op_sel_hi:[0,0,0]
	v_mfma_scale_f32_16x16x128_f8f6f4 v[42:45], v[10:17], v[190:197], v[42:45], v170, v170 op_sel_hi:[0,0,0]
	v_mfma_scale_f32_16x16x128_f8f6f4 v[30:33], v[2:9], v[198:205], v[30:33], v170, v170 op_sel_hi:[0,0,0]
	v_mfma_scale_f32_16x16x128_f8f6f4 v[26:29], v[10:17], v[198:205], v[26:29], v170, v170 op_sel_hi:[0,0,0]
	s_barrier
	s_add_u32 s0, s28, 0x20080
	s_addc_u32 s1, s29, 0
	s_add_i32 s28, s34, s37
	v_lshl_add_u64 v[2:3], s[0:1], 0, v[150:151]
	s_mov_b32 m0, s28
	s_nop 0
	global_load_lds_dwordx4 v[2:3], off
	v_lshl_add_u64 v[2:3], s[0:1], 0, v[146:147]
	s_add_i32 m0, s28, 0x2000
	s_nop 0
	global_load_lds_dwordx4 v[2:3], off
	s_waitcnt vmcnt(10)
	s_barrier
	v_mfma_scale_f32_16x16x128_f8f6f4 v[70:73], v[206:213], v[174:181], v[70:73], v170, v170 op_sel_hi:[0,0,0]
	v_mfma_scale_f32_16x16x128_f8f6f4 v[66:69], v[214:221], v[174:181], v[66:69], v170, v170 op_sel_hi:[0,0,0]
	v_mfma_scale_f32_16x16x128_f8f6f4 v[54:57], v[206:213], v[182:189], v[54:57], v170, v170 op_sel_hi:[0,0,0]
	v_mfma_scale_f32_16x16x128_f8f6f4 v[50:53], v[214:221], v[182:189], v[50:53], v170, v170 op_sel_hi:[0,0,0]
	v_mfma_scale_f32_16x16x128_f8f6f4 v[38:41], v[206:213], v[190:197], v[38:41], v170, v170 op_sel_hi:[0,0,0]
	v_mfma_scale_f32_16x16x128_f8f6f4 v[34:37], v[214:221], v[190:197], v[34:37], v170, v170 op_sel_hi:[0,0,0]
	v_mfma_scale_f32_16x16x128_f8f6f4 v[22:25], v[206:213], v[198:205], v[22:25], v170, v170 op_sel_hi:[0,0,0]
	v_mfma_scale_f32_16x16x128_f8f6f4 v[18:21], v[214:221], v[198:205], v[18:21], v170, v170 op_sel_hi:[0,0,0]
	s_add_i32 s53, s53, 2
	s_add_u32 s51, s51, 0x100
	s_addc_u32 s52, s52, 0
	s_add_u32 s26, s26, 0x10000
	s_addc_u32 s27, s27, 0
	s_cmp_gt_u32 s53, 5
	s_barrier
	s_cbranch_scc0 .LBB0_2816
	v_pk_mul_f32 v[8:9], v[142:143], s[14:15] op_sel_hi:[1,0]
	v_pk_mul_f32 v[6:7], v[144:145], s[14:15] op_sel_hi:[1,0]
	v_med3_f32 v14, v8, s47, v172
	v_med3_f32 v9, v9, s47, v172
	v_mov_b32_e32 v8, 0
	v_cvt_pk_fp8_f32 v8, v14, v9
	v_pk_mul_f32 v[12:13], v[138:139], s[14:15] op_sel_hi:[1,0]
	v_pk_mul_f32 v[10:11], v[140:141], s[14:15] op_sel_hi:[1,0]
	v_med3_f32 v6, v6, s47, v172
	v_med3_f32 v7, v7, s47, v172
	v_med3_f32 v12, v12, s47, v172
	v_med3_f32 v13, v13, s47, v172
	v_mov_b32_e32 v9, 0
	v_mov_b32_e32 v3, v1
	v_mov_b32_e32 v2, v166
	s_lshl_b32 s0, s48, 8
	v_cvt_pk_fp8_f32 v9, v12, v13
	v_cvt_pk_fp8_f32 v8, v6, v7 op_sel:[0,0,1]
	v_med3_f32 v6, v10, s47, v172
	v_med3_f32 v7, v11, s47, v172
	v_pk_mul_f32 v[10:11], v[134:135], s[14:15] op_sel_hi:[1,0]
	s_nop 15
	s_nop 15
	s_or_b32 s0, s0, s42
	v_pk_mul_f32 v[14:15], v[130:131], s[14:15] op_sel_hi:[1,0]
	v_med3_f32 v17, v10, s47, v172
	v_med3_f32 v11, v11, s47, v172
	v_mov_b32_e32 v10, 0
	v_lshl_add_u32 v2, v2, 3, s0
	s_lshl_b32 s0, s24, 8
	v_cvt_pk_fp8_f32 v10, v17, v11
	v_med3_f32 v14, v14, s47, v172
	v_med3_f32 v15, v15, s47, v172
	v_mov_b32_e32 v11, 0
	s_add_i32 s0, s0, s15
	v_cvt_pk_fp8_f32 v11, v14, v15
	v_add_u32_e32 v16, s0, v3
	v_cvt_pk_fp8_f32 v9, v6, v7 op_sel:[0,0,1]
	v_pk_mul_f32 v[6:7], v[136:137], s[14:15] op_sel_hi:[1,0]
	v_mov_b32_e32 v4, v16
	v_pk_mul_f32 v[12:13], v[132:133], s[14:15] op_sel_hi:[1,0]
	v_med3_f32 v6, v6, s47, v172
	v_med3_f32 v7, v7, s47, v172
	v_cvt_pk_fp8_f32 v10, v6, v7 op_sel:[0,0,1]
	v_ashrrev_i32_e32 v5, 31, v4
	v_med3_f32 v6, v12, s47, v172
	v_med3_f32 v7, v13, s47, v172
	v_lshlrev_b64 v[4:5], 10, v[4:5]
	v_cvt_pk_fp8_f32 v11, v6, v7 op_sel:[0,0,1]
	v_ashrrev_i32_e32 v3, 31, v2
	v_lshl_add_u64 v[4:5], s[10:11], 0, v[4:5]
	v_lshl_add_u64 v[4:5], v[4:5], 0, v[2:3]
	global_store_dwordx2 v[4:5], v[8:9], off
	global_store_dwordx2 v[4:5], v[10:11], off offset:128
	v_pk_mul_f32 v[8:9], v[126:127], s[14:15] op_sel_hi:[1,0]
	v_pk_mul_f32 v[6:7], v[128:129], s[14:15] op_sel_hi:[1,0]
	v_med3_f32 v14, v8, s47, v172
	v_med3_f32 v9, v9, s47, v172
	v_mov_b32_e32 v8, 0
	v_cvt_pk_fp8_f32 v8, v14, v9
	v_pk_mul_f32 v[12:13], v[122:123], s[14:15] op_sel_hi:[1,0]
	v_pk_mul_f32 v[10:11], v[124:125], s[14:15] op_sel_hi:[1,0]
	v_med3_f32 v6, v6, s47, v172
	v_med3_f32 v7, v7, s47, v172
	v_med3_f32 v12, v12, s47, v172
	v_med3_f32 v13, v13, s47, v172
	v_mov_b32_e32 v9, 0
	v_cvt_pk_fp8_f32 v9, v12, v13
	v_cvt_pk_fp8_f32 v8, v6, v7 op_sel:[0,0,1]
	v_med3_f32 v6, v10, s47, v172
	v_med3_f32 v7, v11, s47, v172
	v_pk_mul_f32 v[10:11], v[118:119], s[14:15] op_sel_hi:[1,0]
	v_pk_mul_f32 v[14:15], v[114:115], s[14:15] op_sel_hi:[1,0]
	v_med3_f32 v17, v10, s47, v172
	v_med3_f32 v11, v11, s47, v172
	v_mov_b32_e32 v10, 0
	v_cvt_pk_fp8_f32 v10, v17, v11
	v_med3_f32 v14, v14, s47, v172
	v_med3_f32 v15, v15, s47, v172
	v_mov_b32_e32 v11, 0
	v_cvt_pk_fp8_f32 v11, v14, v15
	v_cvt_pk_fp8_f32 v9, v6, v7 op_sel:[0,0,1]
	v_pk_mul_f32 v[6:7], v[120:121], s[14:15] op_sel_hi:[1,0]
	v_add_u32_e32 v4, 16, v16
	v_pk_mul_f32 v[12:13], v[116:117], s[14:15] op_sel_hi:[1,0]
	v_med3_f32 v6, v6, s47, v172
	v_med3_f32 v7, v7, s47, v172
	v_cvt_pk_fp8_f32 v10, v6, v7 op_sel:[0,0,1]
	v_ashrrev_i32_e32 v5, 31, v4
	v_med3_f32 v6, v12, s47, v172
	v_med3_f32 v7, v13, s47, v172
	v_lshlrev_b64 v[4:5], 10, v[4:5]
	v_cvt_pk_fp8_f32 v11, v6, v7 op_sel:[0,0,1]
	v_lshl_add_u64 v[4:5], s[10:11], 0, v[4:5]
	v_lshl_add_u64 v[4:5], v[4:5], 0, v[2:3]
	global_store_dwordx2 v[4:5], v[8:9], off
	global_store_dwordx2 v[4:5], v[10:11], off offset:128
	v_pk_mul_f32 v[8:9], v[110:111], s[14:15] op_sel_hi:[1,0]
	v_pk_mul_f32 v[6:7], v[112:113], s[14:15] op_sel_hi:[1,0]
	v_med3_f32 v14, v8, s47, v172
	v_med3_f32 v9, v9, s47, v172
	v_mov_b32_e32 v8, 0
	v_cvt_pk_fp8_f32 v8, v14, v9
	v_pk_mul_f32 v[12:13], v[106:107], s[14:15] op_sel_hi:[1,0]
	v_pk_mul_f32 v[10:11], v[108:109], s[14:15] op_sel_hi:[1,0]
	v_med3_f32 v6, v6, s47, v172
	v_med3_f32 v7, v7, s47, v172
	v_med3_f32 v12, v12, s47, v172
	v_med3_f32 v13, v13, s47, v172
	v_mov_b32_e32 v9, 0
	v_cvt_pk_fp8_f32 v9, v12, v13
	v_cvt_pk_fp8_f32 v8, v6, v7 op_sel:[0,0,1]
	v_med3_f32 v6, v10, s47, v172
	v_med3_f32 v7, v11, s47, v172
	v_pk_mul_f32 v[10:11], v[102:103], s[14:15] op_sel_hi:[1,0]
	v_pk_mul_f32 v[14:15], v[98:99], s[14:15] op_sel_hi:[1,0]
	v_med3_f32 v17, v10, s47, v172
	v_med3_f32 v11, v11, s47, v172
	v_mov_b32_e32 v10, 0
	v_cvt_pk_fp8_f32 v10, v17, v11
	v_med3_f32 v14, v14, s47, v172
	v_med3_f32 v15, v15, s47, v172
	v_mov_b32_e32 v11, 0
	v_cvt_pk_fp8_f32 v11, v14, v15
	v_cvt_pk_fp8_f32 v9, v6, v7 op_sel:[0,0,1]
	v_pk_mul_f32 v[6:7], v[104:105], s[14:15] op_sel_hi:[1,0]
	v_add_u32_e32 v4, 32, v16
	v_pk_mul_f32 v[12:13], v[100:101], s[14:15] op_sel_hi:[1,0]
	v_med3_f32 v6, v6, s47, v172
	v_med3_f32 v7, v7, s47, v172
	v_cvt_pk_fp8_f32 v10, v6, v7 op_sel:[0,0,1]
	v_ashrrev_i32_e32 v5, 31, v4
	v_med3_f32 v6, v12, s47, v172
	v_med3_f32 v7, v13, s47, v172
	v_lshlrev_b64 v[4:5], 10, v[4:5]
	v_cvt_pk_fp8_f32 v11, v6, v7 op_sel:[0,0,1]
	v_lshl_add_u64 v[4:5], s[10:11], 0, v[4:5]
	v_lshl_add_u64 v[4:5], v[4:5], 0, v[2:3]
	global_store_dwordx2 v[4:5], v[8:9], off
	global_store_dwordx2 v[4:5], v[10:11], off offset:128
	v_pk_mul_f32 v[8:9], v[94:95], s[14:15] op_sel_hi:[1,0]
	v_pk_mul_f32 v[6:7], v[96:97], s[14:15] op_sel_hi:[1,0]
	v_med3_f32 v14, v8, s47, v172
	v_med3_f32 v9, v9, s47, v172
	v_mov_b32_e32 v8, 0
	v_cvt_pk_fp8_f32 v8, v14, v9
	v_pk_mul_f32 v[12:13], v[90:91], s[14:15] op_sel_hi:[1,0]
	v_pk_mul_f32 v[10:11], v[92:93], s[14:15] op_sel_hi:[1,0]
	v_med3_f32 v6, v6, s47, v172
	v_med3_f32 v7, v7, s47, v172
	v_med3_f32 v12, v12, s47, v172
	v_med3_f32 v13, v13, s47, v172
	v_mov_b32_e32 v9, 0
	v_cvt_pk_fp8_f32 v9, v12, v13
	v_cvt_pk_fp8_f32 v8, v6, v7 op_sel:[0,0,1]
	v_med3_f32 v6, v10, s47, v172
	v_med3_f32 v7, v11, s47, v172
	v_pk_mul_f32 v[10:11], v[86:87], s[14:15] op_sel_hi:[1,0]
	v_pk_mul_f32 v[14:15], v[82:83], s[14:15] op_sel_hi:[1,0]
	v_med3_f32 v17, v10, s47, v172
	v_med3_f32 v11, v11, s47, v172
	v_mov_b32_e32 v10, 0
	v_cvt_pk_fp8_f32 v10, v17, v11
	v_med3_f32 v14, v14, s47, v172
	v_med3_f32 v15, v15, s47, v172
	v_mov_b32_e32 v11, 0
	v_cvt_pk_fp8_f32 v11, v14, v15
	v_cvt_pk_fp8_f32 v9, v6, v7 op_sel:[0,0,1]
	v_pk_mul_f32 v[6:7], v[88:89], s[14:15] op_sel_hi:[1,0]
	v_add_u32_e32 v4, 48, v16
	v_pk_mul_f32 v[12:13], v[84:85], s[14:15] op_sel_hi:[1,0]
	v_med3_f32 v6, v6, s47, v172
	v_med3_f32 v7, v7, s47, v172
	v_cvt_pk_fp8_f32 v10, v6, v7 op_sel:[0,0,1]
	v_ashrrev_i32_e32 v5, 31, v4
	v_med3_f32 v6, v12, s47, v172
	v_med3_f32 v7, v13, s47, v172
	v_lshlrev_b64 v[4:5], 10, v[4:5]
	v_cvt_pk_fp8_f32 v11, v6, v7 op_sel:[0,0,1]
	v_lshl_add_u64 v[4:5], s[10:11], 0, v[4:5]
	v_lshl_add_u64 v[4:5], v[4:5], 0, v[2:3]
	global_store_dwordx2 v[4:5], v[8:9], off
	global_store_dwordx2 v[4:5], v[10:11], off offset:128
	v_pk_mul_f32 v[8:9], v[78:79], s[14:15] op_sel_hi:[1,0]
	v_pk_mul_f32 v[6:7], v[80:81], s[14:15] op_sel_hi:[1,0]
	v_med3_f32 v14, v8, s47, v172
	v_med3_f32 v9, v9, s47, v172
	v_mov_b32_e32 v8, 0
	v_cvt_pk_fp8_f32 v8, v14, v9
	v_pk_mul_f32 v[12:13], v[74:75], s[14:15] op_sel_hi:[1,0]
	v_pk_mul_f32 v[10:11], v[76:77], s[14:15] op_sel_hi:[1,0]
	v_med3_f32 v6, v6, s47, v172
	v_med3_f32 v7, v7, s47, v172
	v_med3_f32 v12, v12, s47, v172
	v_med3_f32 v13, v13, s47, v172
	v_mov_b32_e32 v9, 0
	v_cvt_pk_fp8_f32 v9, v12, v13
	v_cvt_pk_fp8_f32 v8, v6, v7 op_sel:[0,0,1]
	v_med3_f32 v6, v10, s47, v172
	v_med3_f32 v7, v11, s47, v172
	v_pk_mul_f32 v[10:11], v[70:71], s[14:15] op_sel_hi:[1,0]
	v_pk_mul_f32 v[14:15], v[66:67], s[14:15] op_sel_hi:[1,0]
	v_med3_f32 v17, v10, s47, v172
	v_med3_f32 v11, v11, s47, v172
	v_mov_b32_e32 v10, 0
	v_cvt_pk_fp8_f32 v10, v17, v11
	v_med3_f32 v14, v14, s47, v172
	v_med3_f32 v15, v15, s47, v172
	v_mov_b32_e32 v11, 0
	v_cvt_pk_fp8_f32 v11, v14, v15
	v_cvt_pk_fp8_f32 v9, v6, v7 op_sel:[0,0,1]
	v_pk_mul_f32 v[6:7], v[72:73], s[14:15] op_sel_hi:[1,0]
	v_add_u32_e32 v4, 0x80, v16
	v_pk_mul_f32 v[12:13], v[68:69], s[14:15] op_sel_hi:[1,0]
	v_med3_f32 v6, v6, s47, v172
	v_med3_f32 v7, v7, s47, v172
	v_cvt_pk_fp8_f32 v10, v6, v7 op_sel:[0,0,1]
	v_ashrrev_i32_e32 v5, 31, v4
	v_med3_f32 v6, v12, s47, v172
	v_med3_f32 v7, v13, s47, v172
	v_lshlrev_b64 v[4:5], 10, v[4:5]
	v_cvt_pk_fp8_f32 v11, v6, v7 op_sel:[0,0,1]
	v_lshl_add_u64 v[4:5], s[10:11], 0, v[4:5]
	v_lshl_add_u64 v[4:5], v[4:5], 0, v[2:3]
	global_store_dwordx2 v[4:5], v[8:9], off
	global_store_dwordx2 v[4:5], v[10:11], off offset:128
	v_pk_mul_f32 v[8:9], v[62:63], s[14:15] op_sel_hi:[1,0]
	v_pk_mul_f32 v[6:7], v[64:65], s[14:15] op_sel_hi:[1,0]
	v_med3_f32 v14, v8, s47, v172
	v_med3_f32 v9, v9, s47, v172
	v_mov_b32_e32 v8, 0
	v_cvt_pk_fp8_f32 v8, v14, v9
	v_pk_mul_f32 v[12:13], v[58:59], s[14:15] op_sel_hi:[1,0]
	v_pk_mul_f32 v[10:11], v[60:61], s[14:15] op_sel_hi:[1,0]
	v_med3_f32 v6, v6, s47, v172
	v_med3_f32 v7, v7, s47, v172
	v_med3_f32 v12, v12, s47, v172
	v_med3_f32 v13, v13, s47, v172
	v_mov_b32_e32 v9, 0
	v_cvt_pk_fp8_f32 v9, v12, v13
	v_cvt_pk_fp8_f32 v8, v6, v7 op_sel:[0,0,1]
	v_med3_f32 v6, v10, s47, v172
	v_med3_f32 v7, v11, s47, v172
	v_pk_mul_f32 v[10:11], v[54:55], s[14:15] op_sel_hi:[1,0]
	v_pk_mul_f32 v[14:15], v[50:51], s[14:15] op_sel_hi:[1,0]
	v_med3_f32 v17, v10, s47, v172
	v_med3_f32 v11, v11, s47, v172
	v_mov_b32_e32 v10, 0
	v_cvt_pk_fp8_f32 v10, v17, v11
	v_med3_f32 v14, v14, s47, v172
	v_med3_f32 v15, v15, s47, v172
	v_mov_b32_e32 v11, 0
	v_cvt_pk_fp8_f32 v11, v14, v15
	v_cvt_pk_fp8_f32 v9, v6, v7 op_sel:[0,0,1]
	v_pk_mul_f32 v[6:7], v[56:57], s[14:15] op_sel_hi:[1,0]
	v_add_u32_e32 v4, 0x90, v16
	v_pk_mul_f32 v[12:13], v[52:53], s[14:15] op_sel_hi:[1,0]
	v_med3_f32 v6, v6, s47, v172
	v_med3_f32 v7, v7, s47, v172
	v_cvt_pk_fp8_f32 v10, v6, v7 op_sel:[0,0,1]
	v_ashrrev_i32_e32 v5, 31, v4
	v_med3_f32 v6, v12, s47, v172
	v_med3_f32 v7, v13, s47, v172
	v_lshlrev_b64 v[4:5], 10, v[4:5]
	v_cvt_pk_fp8_f32 v11, v6, v7 op_sel:[0,0,1]
	v_lshl_add_u64 v[4:5], s[10:11], 0, v[4:5]
	v_lshl_add_u64 v[4:5], v[4:5], 0, v[2:3]
	global_store_dwordx2 v[4:5], v[8:9], off
	global_store_dwordx2 v[4:5], v[10:11], off offset:128
	v_pk_mul_f32 v[8:9], v[46:47], s[14:15] op_sel_hi:[1,0]
	v_pk_mul_f32 v[6:7], v[48:49], s[14:15] op_sel_hi:[1,0]
	v_med3_f32 v14, v8, s47, v172
	v_med3_f32 v9, v9, s47, v172
	v_mov_b32_e32 v8, 0
	v_cvt_pk_fp8_f32 v8, v14, v9
	v_pk_mul_f32 v[12:13], v[42:43], s[14:15] op_sel_hi:[1,0]
	v_pk_mul_f32 v[10:11], v[44:45], s[14:15] op_sel_hi:[1,0]
	v_med3_f32 v6, v6, s47, v172
	v_med3_f32 v7, v7, s47, v172
	v_med3_f32 v12, v12, s47, v172
	v_med3_f32 v13, v13, s47, v172
	v_mov_b32_e32 v9, 0
	v_cvt_pk_fp8_f32 v9, v12, v13
	v_cvt_pk_fp8_f32 v8, v6, v7 op_sel:[0,0,1]
	v_med3_f32 v6, v10, s47, v172
	v_med3_f32 v7, v11, s47, v172
	v_pk_mul_f32 v[10:11], v[38:39], s[14:15] op_sel_hi:[1,0]
	v_pk_mul_f32 v[14:15], v[34:35], s[14:15] op_sel_hi:[1,0]
	v_med3_f32 v17, v10, s47, v172
	v_med3_f32 v11, v11, s47, v172
	v_mov_b32_e32 v10, 0
	v_cvt_pk_fp8_f32 v10, v17, v11
	v_med3_f32 v14, v14, s47, v172
	v_med3_f32 v15, v15, s47, v172
	v_mov_b32_e32 v11, 0
	v_cvt_pk_fp8_f32 v11, v14, v15
	v_cvt_pk_fp8_f32 v9, v6, v7 op_sel:[0,0,1]
	v_pk_mul_f32 v[6:7], v[40:41], s[14:15] op_sel_hi:[1,0]
	v_add_u32_e32 v4, 0xa0, v16
	v_pk_mul_f32 v[12:13], v[36:37], s[14:15] op_sel_hi:[1,0]
	v_med3_f32 v6, v6, s47, v172
	v_med3_f32 v7, v7, s47, v172
	v_cvt_pk_fp8_f32 v10, v6, v7 op_sel:[0,0,1]
	v_ashrrev_i32_e32 v5, 31, v4
	v_med3_f32 v6, v12, s47, v172
	v_med3_f32 v7, v13, s47, v172
	v_lshlrev_b64 v[4:5], 10, v[4:5]
	v_cvt_pk_fp8_f32 v11, v6, v7 op_sel:[0,0,1]
	v_lshl_add_u64 v[4:5], s[10:11], 0, v[4:5]
	v_lshl_add_u64 v[4:5], v[4:5], 0, v[2:3]
	global_store_dwordx2 v[4:5], v[8:9], off
	global_store_dwordx2 v[4:5], v[10:11], off offset:128
	v_pk_mul_f32 v[8:9], v[30:31], s[14:15] op_sel_hi:[1,0]
	v_pk_mul_f32 v[6:7], v[32:33], s[14:15] op_sel_hi:[1,0]
	v_med3_f32 v14, v8, s47, v172
	v_med3_f32 v9, v9, s47, v172
	v_mov_b32_e32 v8, 0
	v_cvt_pk_fp8_f32 v8, v14, v9
	v_pk_mul_f32 v[12:13], v[26:27], s[14:15] op_sel_hi:[1,0]
	v_pk_mul_f32 v[10:11], v[28:29], s[14:15] op_sel_hi:[1,0]
	v_med3_f32 v6, v6, s47, v172
	v_med3_f32 v7, v7, s47, v172
	v_med3_f32 v12, v12, s47, v172
	v_med3_f32 v13, v13, s47, v172
	v_mov_b32_e32 v9, 0
	v_cvt_pk_fp8_f32 v9, v12, v13
	v_cvt_pk_fp8_f32 v8, v6, v7 op_sel:[0,0,1]
	v_med3_f32 v6, v10, s47, v172
	v_med3_f32 v7, v11, s47, v172
	v_pk_mul_f32 v[10:11], v[22:23], s[14:15] op_sel_hi:[1,0]
	v_add_u32_e32 v4, 0xb0, v16
	v_pk_mul_f32 v[14:15], v[18:19], s[14:15] op_sel_hi:[1,0]
	v_med3_f32 v16, v10, s47, v172
	v_med3_f32 v11, v11, s47, v172
	v_mov_b32_e32 v10, 0
	v_cvt_pk_fp8_f32 v10, v16, v11
	v_med3_f32 v14, v14, s47, v172
	v_med3_f32 v15, v15, s47, v172
	v_mov_b32_e32 v11, 0
	v_cvt_pk_fp8_f32 v11, v14, v15
	v_cvt_pk_fp8_f32 v9, v6, v7 op_sel:[0,0,1]
	v_pk_mul_f32 v[6:7], v[24:25], s[14:15] op_sel_hi:[1,0]
	v_pk_mul_f32 v[12:13], v[20:21], s[14:15] op_sel_hi:[1,0]
	v_med3_f32 v6, v6, s47, v172
	v_med3_f32 v7, v7, s47, v172
	v_cvt_pk_fp8_f32 v10, v6, v7 op_sel:[0,0,1]
	v_ashrrev_i32_e32 v5, 31, v4
	v_med3_f32 v6, v12, s47, v172
	v_med3_f32 v7, v13, s47, v172
	v_lshlrev_b64 v[4:5], 10, v[4:5]
	v_cvt_pk_fp8_f32 v11, v6, v7 op_sel:[0,0,1]
	v_lshl_add_u64 v[4:5], s[10:11], 0, v[4:5]
	v_lshl_add_u64 v[2:3], v[4:5], 0, v[2:3]
	s_and_b64 vcc, exec, s[6:7]
	s_mov_b32 s48, s16
	s_mov_b32 s24, s18
	s_mov_b64 s[26:27], s[22:23]
	s_mov_b64 s[28:29], s[20:21]
	global_store_dwordx2 v[2:3], v[8:9], off
	global_store_dwordx2 v[2:3], v[10:11], off offset:128
	s_cbranch_vccz .LBB0_2809
	s_waitcnt vmcnt(0)
	s_cmpk_gt_u32 s4, 0xff
	s_cbranch_scc1 .LBB0_2820
	s_barrier
